# non-temporal (nt) cache policy on the 192 GEMM epilogue dwordx4 stores
# baseline (speedup 1.0000x reference)
; #define G_STAGE(bufoff, gbase, voff) do { _Pragma("unroll") for (int _i = 0; _i < 2; ++_i) { unsigned _vo = (voff)[_i]; asm volatile("" : "+v"(_vo));   \
;     __builtin_amdgcn_global_load_lds((const unsigned*)((const char*)(gbase) + _vo), (LAS unsigned*)(lds + (bufoff) + ldsw + _i * 8192), 16, 0, 0); } } while (0)
; #define G_LDA(dst, b, h) do { _Pragma("unroll") for (int m = 0; m < 4; ++m) _Pragma("unroll") for (int k = 0; k < 2; ++k) dst[m][k] = *(const LAS bf16x8*)(lds + G_SA(b, h) + aoff + m * 2048 + k * 1024); } while (0)
; #define G_LDB(dst, b, h) do { _Pragma("unroll") for (int n = 0; n < 2; ++n) _Pragma("unroll") for (int k = 0; k < 2; ++k) dst[n][k] = *(const LAS bf16x8*)(lds + G_SB(b, h) + boff + n * 2048 + k * 1024); } while (0)
; #define G_MMA(ai, bj, At, Bt) do { __builtin_amdgcn_s_setprio(1); _Pragma("unroll") for (int m = 0; m < 4; ++m) _Pragma("unroll") for (int n = 0; n < 2; ++n) _Pragma("unroll") for (int k = 0; k < 2; ++k) \
;     acc[ai][bj][m][n] = __builtin_amdgcn_mfma_f32_16x16x32_bf16(Bt[n][k], At[m][k], acc[ai][bj][m][n], 0, 0, 0); __builtin_amdgcn_s_setprio(0); } while (0)
; #define G_WAIT_L(n) asm volatile("s_waitcnt lgkmcnt(" #n ")" ::: "memory")
; #define G_BAR __builtin_amdgcn_s_barrier()
; #define G_SCHED __builtin_amdgcn_sched_barrier(0)
; template <class Epi>
; __device__ __forceinline__ void gemm_phase(LAS unsigned char* lds, const int K, const unsigned lda_b, const unsigned ldb_b, const Map& M, const Epi& E) {
;     ...
;       G_LDB(B0, 0, 0); G_SCHED; G_LDA(At, 0, 0); G_STAGE(G_SA(1, 1), a1h1, voffA);
;       G_WAIT_L(8); G_BAR; G_WAIT_L(0); G_MMA(0, 0, At, B0); G_BAR; G_SCHED;
;       G_LDB(B1, 0, 1); G_STAGE(G_SB(0, 0), b2h0, voffB);
;       G_BAR; G_WAIT_L(0); G_MMA(0, 1, At, B1); G_BAR;
;       G_LDA(At, 0, 1); G_STAGE(G_SA(0, 0), a2h0, voffA);
;       G_BAR; G_WAIT_L(0); G_MMA(1, 0, At, B0); G_BAR; G_SCHED;
.LBB0_235:
	s_add_u32 s22, s2, 0xfff80080
	s_addc_u32 s34, s3, -1
	s_add_u32 s35, s29, 0xfffe0000
	s_addc_u32 s38, s30, -1
	s_add_i32 s81, 0, 0x10000
	v_add_u32_e32 v80, s81, v160
	ds_read_b128 v[138:141], v80
	ds_read_b128 v[142:145], v80 offset:1024
	ds_read_b128 v[146:149], v80 offset:2048
	ds_read_b128 v[150:153], v80 offset:3072
	s_cmp_eq_u32 s31, 28
	s_cselect_b32 s43, s7, s34
	s_cselect_b32 s42, s6, s22
	s_cselect_b32 s45, s9, s38
	s_cselect_b32 s44, s8, s35
	v_mov_b32_e32 v80, v154
	s_cselect_b32 s39, s28, s30
	s_cselect_b32 s38, s0, s29
	s_add_u32 s68, s42, 0x80000
	ds_read_b128 v[166:169], v165
	ds_read_b128 v[170:173], v165 offset:1024
	ds_read_b128 v[174:177], v165 offset:2048
	ds_read_b128 v[184:187], v165 offset:3072
	ds_read_b128 v[190:193], v165 offset:4096
	ds_read_b128 v[194:197], v165 offset:5120
	ds_read_b128 v[198:201], v165 offset:6144
	ds_read_b128 v[202:205], v165 offset:7168
	s_addc_u32 s69, s43, 0
	s_add_i32 m0, s19, 0xc000
	s_nop 0
	global_load_lds_dwordx4 v80, s[2:3]
	v_mov_b32_e32 v80, v156
	s_add_i32 m0, s19, 0xe000
	s_nop 0
	global_load_lds_dwordx4 v80, s[2:3]
	s_waitcnt lgkmcnt(8)
	s_barrier
	s_waitcnt lgkmcnt(0)
	s_setprio 1
	s_waitcnt lgkmcnt(0)
	v_mfma_f32_16x16x32_bf16 v[126:129], v[138:141], v[166:169], v[126:129]
	v_mfma_f32_16x16x32_bf16 v[122:125], v[146:149], v[166:169], v[122:125]
	v_mfma_f32_16x16x32_bf16 v[110:113], v[138:141], v[174:177], v[110:113]
	v_mfma_f32_16x16x32_bf16 v[106:109], v[146:149], v[174:177], v[106:109]
	v_mfma_f32_16x16x32_bf16 v[94:97], v[138:141], v[190:193], v[94:97]
	v_mfma_f32_16x16x32_bf16 v[90:93], v[146:149], v[190:193], v[90:93]
	v_mfma_f32_16x16x32_bf16 v[76:79], v[138:141], v[198:201], v[76:79]
	v_mfma_f32_16x16x32_bf16 v[72:75], v[146:149], v[198:201], v[72:75]
	v_mfma_f32_16x16x32_bf16 v[126:129], v[142:145], v[170:173], v[126:129]
	v_mfma_f32_16x16x32_bf16 v[122:125], v[150:153], v[170:173], v[122:125]
	v_mfma_f32_16x16x32_bf16 v[110:113], v[142:145], v[184:187], v[110:113]
	v_mfma_f32_16x16x32_bf16 v[106:109], v[150:153], v[184:187], v[106:109]
	v_mfma_f32_16x16x32_bf16 v[94:97], v[142:145], v[194:197], v[94:97]
	v_mfma_f32_16x16x32_bf16 v[90:93], v[150:153], v[194:197], v[90:93]
	v_mfma_f32_16x16x32_bf16 v[76:79], v[142:145], v[202:205], v[76:79]
	v_mfma_f32_16x16x32_bf16 v[72:75], v[150:153], v[202:205], v[72:75]
	s_setprio 0
	s_barrier
	s_add_i32 s22, 0, 0x14000
	v_add_u32_e32 v80, s22, v160
	ds_read_b128 v[206:209], v80
	ds_read_b128 v[210:213], v80 offset:1024
	ds_read_b128 v[214:217], v80 offset:2048
	ds_read_b128 v[218:221], v80 offset:3072
	v_mov_b32_e32 v80, v155
	s_add_i32 s34, s81, s18
	s_mov_b32 m0, s34
	s_nop 0
	global_load_lds_dwordx4 v80, s[44:45]
	v_mov_b32_e32 v80, v157
	s_add_i32 m0, s34, 0x2000
	s_nop 0
	global_load_lds_dwordx4 v80, s[44:45]
	s_barrier
	s_waitcnt lgkmcnt(0)
	s_setprio 1
	s_waitcnt lgkmcnt(0)
	v_mfma_f32_16x16x32_bf16 v[118:121], v[206:209], v[166:169], v[118:121]
	v_mfma_f32_16x16x32_bf16 v[114:117], v[214:217], v[166:169], v[114:117]
	v_mfma_f32_16x16x32_bf16 v[102:105], v[206:209], v[174:177], v[102:105]
	v_mfma_f32_16x16x32_bf16 v[98:101], v[214:217], v[174:177], v[98:101]
	v_mfma_f32_16x16x32_bf16 v[86:89], v[206:209], v[190:193], v[86:89]
	v_mfma_f32_16x16x32_bf16 v[82:85], v[214:217], v[190:193], v[82:85]
	v_mfma_f32_16x16x32_bf16 v[68:71], v[206:209], v[198:201], v[68:71]
	v_mfma_f32_16x16x32_bf16 v[64:67], v[214:217], v[198:201], v[64:67]
	v_mfma_f32_16x16x32_bf16 v[118:121], v[210:213], v[170:173], v[118:121]
	v_mfma_f32_16x16x32_bf16 v[114:117], v[218:221], v[170:173], v[114:117]
	v_mfma_f32_16x16x32_bf16 v[102:105], v[210:213], v[184:187], v[102:105]
	v_mfma_f32_16x16x32_bf16 v[98:101], v[218:221], v[184:187], v[98:101]
	v_mfma_f32_16x16x32_bf16 v[86:89], v[210:213], v[194:197], v[86:89]
	v_mfma_f32_16x16x32_bf16 v[82:85], v[218:221], v[194:197], v[82:85]
	v_mfma_f32_16x16x32_bf16 v[68:71], v[210:213], v[202:205], v[68:71]
	v_mfma_f32_16x16x32_bf16 v[64:67], v[218:221], v[202:205], v[64:67]
	s_setprio 0
	v_mov_b32_e32 v80, v154
	s_mov_b32 m0, s19
	s_barrier
	ds_read_b128 v[166:169], v165 offset:16384
	ds_read_b128 v[170:173], v165 offset:17408
	ds_read_b128 v[174:177], v165 offset:18432
	ds_read_b128 v[184:187], v165 offset:19456
	ds_read_b128 v[190:193], v165 offset:20480
	ds_read_b128 v[194:197], v165 offset:21504
	ds_read_b128 v[198:201], v165 offset:22528
	ds_read_b128 v[202:205], v165 offset:23552
	s_nop 0
	global_load_lds_dwordx4 v80, s[42:43]
	v_mov_b32_e32 v80, v156
	s_mov_b32 m0, s46
	s_nop 0
	global_load_lds_dwordx4 v80, s[42:43]
	s_barrier
	s_waitcnt lgkmcnt(0)
	s_setprio 1
	s_waitcnt lgkmcnt(0)
	v_mfma_f32_16x16x32_bf16 v[60:63], v[138:141], v[166:169], v[60:63]
	v_mfma_f32_16x16x32_bf16 v[56:59], v[146:149], v[166:169], v[56:59]
	v_mfma_f32_16x16x32_bf16 v[44:47], v[138:141], v[174:177], v[44:47]
	v_mfma_f32_16x16x32_bf16 v[40:43], v[146:149], v[174:177], v[40:43]
	v_mfma_f32_16x16x32_bf16 v[28:31], v[138:141], v[190:193], v[28:31]
	v_mfma_f32_16x16x32_bf16 v[24:27], v[146:149], v[190:193], v[24:27]
	v_mfma_f32_16x16x32_bf16 v[12:15], v[138:141], v[198:201], v[12:15]
	v_mfma_f32_16x16x32_bf16 v[8:11], v[146:149], v[198:201], v[8:11]
	v_mfma_f32_16x16x32_bf16 v[60:63], v[142:145], v[170:173], v[60:63]
	v_mfma_f32_16x16x32_bf16 v[56:59], v[150:153], v[170:173], v[56:59]
	v_mfma_f32_16x16x32_bf16 v[44:47], v[142:145], v[184:187], v[44:47]
	v_mfma_f32_16x16x32_bf16 v[40:43], v[150:153], v[184:187], v[40:43]
	v_mfma_f32_16x16x32_bf16 v[28:31], v[142:145], v[194:197], v[28:31]
	v_mfma_f32_16x16x32_bf16 v[24:27], v[150:153], v[194:197], v[24:27]
	v_mfma_f32_16x16x32_bf16 v[12:15], v[142:145], v[202:205], v[12:15]
	v_mfma_f32_16x16x32_bf16 v[8:11], v[150:153], v[202:205], v[8:11]
	s_setprio 0
	s_barrier
; #define G_STAGE(bufoff, gbase, voff) do { _Pragma("unroll") for (int _i = 0; _i < 2; ++_i) { unsigned _vo = (voff)[_i]; asm volatile("" : "+v"(_vo));   \
;     __builtin_amdgcn_global_load_lds((const unsigned*)((const char*)(gbase) + _vo), (LAS unsigned*)(lds + (bufoff) + ldsw + _i * 8192), 16, 0, 0); } } while (0)
; #define G_LDA(dst, b, h) do { _Pragma("unroll") for (int m = 0; m < 4; ++m) _Pragma("unroll") for (int k = 0; k < 2; ++k) dst[m][k] = *(const LAS bf16x8*)(lds + G_SA(b, h) + aoff + m * 2048 + k * 1024); } while (0)
; #define G_LDB(dst, b, h) do { _Pragma("unroll") for (int n = 0; n < 2; ++n) _Pragma("unroll") for (int k = 0; k < 2; ++k) dst[n][k] = *(const LAS bf16x8*)(lds + G_SB(b, h) + boff + n * 2048 + k * 1024); } while (0)
; #define G_MMA(ai, bj, At, Bt) do { __builtin_amdgcn_s_setprio(1); _Pragma("unroll") for (int m = 0; m < 4; ++m) _Pragma("unroll") for (int n = 0; n < 2; ++n) _Pragma("unroll") for (int k = 0; k < 2; ++k) \
;     acc[ai][bj][m][n] = __builtin_amdgcn_mfma_f32_16x16x32_bf16(Bt[n][k], At[m][k], acc[ai][bj][m][n], 0, 0, 0); __builtin_amdgcn_s_setprio(0); } while (0)
; #define G_WAIT_V(n) asm volatile("s_waitcnt vmcnt(" #n ")" ::: "memory")
; #define G_WAIT_L(n) asm volatile("s_waitcnt lgkmcnt(" #n ")" ::: "memory")
; #define G_BAR __builtin_amdgcn_s_barrier()
; #define G_SCHED __builtin_amdgcn_sched_barrier(0)
; template <class Epi>
; __device__ __forceinline__ void gemm_phase(LAS unsigned char* lds, const int K, const unsigned lda_b, const unsigned ldb_b, const Map& M, const Epi& E) {
;     ...
;       G_STAGE(G_SB(0, 1), b2h1, voffB);
;       G_WAIT_V(6); G_BAR; G_MMA(1, 1, At, B1); G_BAR;
;       G_LDB(B0, 1, 0); G_SCHED; G_LDA(At, 1, 0); G_STAGE(G_SA(0, 1), a2h1, voffA);
;       G_WAIT_L(8); G_BAR; G_WAIT_L(0); G_MMA(0, 0, At, B0); G_BAR; G_SCHED;
;       G_LDB(B1, 1, 1); G_STAGE(G_SB(1, 0), b2h0 + kstep, voffB);
;       G_BAR; G_WAIT_L(0); G_MMA(0, 1, At, B1); G_BAR;
;       G_LDA(At, 1, 1); G_STAGE(G_SA(1, 0), a2h0 + kstep, voffA);
;       G_BAR; G_WAIT_L(0); G_MMA(1, 0, At, B0); G_BAR; G_SCHED;
	v_mov_b32_e32 v80, v155
	s_add_i32 s22, s22, s18
	s_mov_b32 m0, s22
	s_nop 0
	global_load_lds_dwordx4 v80, s[38:39]
	v_mov_b32_e32 v80, v157
	s_add_i32 m0, s22, 0x2000
	s_nop 0
	global_load_lds_dwordx4 v80, s[38:39]
	s_waitcnt vmcnt(6)
	s_barrier
	s_setprio 1
	v_mfma_f32_16x16x32_bf16 v[52:55], v[206:209], v[166:169], v[52:55]
	v_mfma_f32_16x16x32_bf16 v[48:51], v[214:217], v[166:169], v[48:51]
	v_mfma_f32_16x16x32_bf16 v[36:39], v[206:209], v[174:177], v[36:39]
	v_mfma_f32_16x16x32_bf16 v[32:35], v[214:217], v[174:177], v[32:35]
	v_mfma_f32_16x16x32_bf16 v[20:23], v[206:209], v[190:193], v[20:23]
	v_mfma_f32_16x16x32_bf16 v[16:19], v[214:217], v[190:193], v[16:19]
	v_mfma_f32_16x16x32_bf16 v[4:7], v[206:209], v[198:201], v[4:7]
	v_mfma_f32_16x16x32_bf16 v[0:3], v[214:217], v[198:201], v[0:3]
	v_mfma_f32_16x16x32_bf16 v[52:55], v[210:213], v[170:173], v[52:55]
	v_mfma_f32_16x16x32_bf16 v[48:51], v[218:221], v[170:173], v[48:51]
	v_mfma_f32_16x16x32_bf16 v[36:39], v[210:213], v[184:187], v[36:39]
	v_mfma_f32_16x16x32_bf16 v[32:35], v[218:221], v[184:187], v[32:35]
	v_mfma_f32_16x16x32_bf16 v[20:23], v[210:213], v[194:197], v[20:23]
	v_mfma_f32_16x16x32_bf16 v[16:19], v[218:221], v[194:197], v[16:19]
	v_mfma_f32_16x16x32_bf16 v[4:7], v[210:213], v[202:205], v[4:7]
	v_mfma_f32_16x16x32_bf16 v[0:3], v[218:221], v[202:205], v[0:3]
	s_setprio 0
	s_add_i32 s22, 0, 0x18000
	v_add_u32_e32 v80, s22, v160
	s_barrier
	ds_read_b128 v[138:141], v80
	ds_read_b128 v[142:145], v80 offset:1024
	ds_read_b128 v[146:149], v80 offset:2048
	ds_read_b128 v[150:153], v80 offset:3072
	v_mov_b32_e32 v80, v154
	s_mov_b32 m0, s47
	ds_read_b128 v[166:169], v165 offset:32768
	ds_read_b128 v[170:173], v165 offset:33792
	ds_read_b128 v[174:177], v165 offset:34816
	ds_read_b128 v[184:187], v165 offset:35840
	ds_read_b128 v[190:193], v165 offset:36864
	ds_read_b128 v[194:197], v165 offset:37888
	ds_read_b128 v[198:201], v165 offset:38912
	ds_read_b128 v[202:205], v165 offset:39936
	s_nop 0
	global_load_lds_dwordx4 v80, s[68:69]
	v_mov_b32_e32 v80, v156
	s_mov_b32 m0, s48
	s_nop 0
	global_load_lds_dwordx4 v80, s[68:69]
	s_waitcnt lgkmcnt(8)
	s_barrier
	s_waitcnt lgkmcnt(0)
	s_setprio 1
	s_waitcnt lgkmcnt(0)
	v_mfma_f32_16x16x32_bf16 v[126:129], v[138:141], v[166:169], v[126:129]
	v_mfma_f32_16x16x32_bf16 v[122:125], v[146:149], v[166:169], v[122:125]
	v_mfma_f32_16x16x32_bf16 v[110:113], v[138:141], v[174:177], v[110:113]
	v_mfma_f32_16x16x32_bf16 v[106:109], v[146:149], v[174:177], v[106:109]
	v_mfma_f32_16x16x32_bf16 v[94:97], v[138:141], v[190:193], v[94:97]
	v_mfma_f32_16x16x32_bf16 v[90:93], v[146:149], v[190:193], v[90:93]
	v_mfma_f32_16x16x32_bf16 v[76:79], v[138:141], v[198:201], v[76:79]
	v_mfma_f32_16x16x32_bf16 v[72:75], v[146:149], v[198:201], v[72:75]
	v_mfma_f32_16x16x32_bf16 v[126:129], v[142:145], v[170:173], v[126:129]
	v_mfma_f32_16x16x32_bf16 v[122:125], v[150:153], v[170:173], v[122:125]
	v_mfma_f32_16x16x32_bf16 v[110:113], v[142:145], v[184:187], v[110:113]
	v_mfma_f32_16x16x32_bf16 v[106:109], v[150:153], v[184:187], v[106:109]
	v_mfma_f32_16x16x32_bf16 v[94:97], v[142:145], v[194:197], v[94:97]
	v_mfma_f32_16x16x32_bf16 v[90:93], v[150:153], v[194:197], v[90:93]
	v_mfma_f32_16x16x32_bf16 v[76:79], v[142:145], v[202:205], v[76:79]
	v_mfma_f32_16x16x32_bf16 v[72:75], v[150:153], v[202:205], v[72:75]
	s_setprio 0
	s_barrier
	s_add_i32 s34, 0, 0x1c000
	v_add_u32_e32 v80, s34, v160
	ds_read_b128 v[206:209], v80
	ds_read_b128 v[210:213], v80 offset:1024
	ds_read_b128 v[214:217], v80 offset:2048
	ds_read_b128 v[218:221], v80 offset:3072
	v_mov_b32_e32 v80, v155
	s_add_i32 s22, s22, s18
	s_add_i32 m0, s22, 0xffffff80
	v_mov_b32_e32 v80, v157
	global_load_lds_dwordx4 v155, s[44:45] offset:128
	s_add_i32 m0, s22, 0x1f80
	s_nop 0
	global_load_lds_dwordx4 v157, s[44:45] offset:128
	s_barrier
	s_waitcnt lgkmcnt(0)
	s_setprio 1
	s_waitcnt lgkmcnt(0)
	v_mfma_f32_16x16x32_bf16 v[118:121], v[206:209], v[166:169], v[118:121]
	v_mfma_f32_16x16x32_bf16 v[114:117], v[214:217], v[166:169], v[114:117]
	v_mfma_f32_16x16x32_bf16 v[102:105], v[206:209], v[174:177], v[102:105]
	v_mfma_f32_16x16x32_bf16 v[98:101], v[214:217], v[174:177], v[98:101]
	v_mfma_f32_16x16x32_bf16 v[86:89], v[206:209], v[190:193], v[86:89]
	v_mfma_f32_16x16x32_bf16 v[82:85], v[214:217], v[190:193], v[82:85]
	v_mfma_f32_16x16x32_bf16 v[68:71], v[206:209], v[198:201], v[68:71]
	v_mfma_f32_16x16x32_bf16 v[64:67], v[214:217], v[198:201], v[64:67]
	v_mfma_f32_16x16x32_bf16 v[118:121], v[210:213], v[170:173], v[118:121]
	v_mfma_f32_16x16x32_bf16 v[114:117], v[218:221], v[170:173], v[114:117]
	v_mfma_f32_16x16x32_bf16 v[102:105], v[210:213], v[184:187], v[102:105]
	v_mfma_f32_16x16x32_bf16 v[98:101], v[218:221], v[184:187], v[98:101]
	v_mfma_f32_16x16x32_bf16 v[86:89], v[210:213], v[194:197], v[86:89]
	v_mfma_f32_16x16x32_bf16 v[82:85], v[218:221], v[194:197], v[82:85]
	v_mfma_f32_16x16x32_bf16 v[68:71], v[210:213], v[202:205], v[68:71]
	v_mfma_f32_16x16x32_bf16 v[64:67], v[218:221], v[202:205], v[64:67]
	s_setprio 0
	v_mov_b32_e32 v80, v154
	s_barrier
	ds_read_b128 v[166:169], v165 offset:49152
	ds_read_b128 v[170:173], v165 offset:50176
	ds_read_b128 v[174:177], v165 offset:51200
	ds_read_b128 v[184:187], v165 offset:52224
	ds_read_b128 v[190:193], v165 offset:53248
	ds_read_b128 v[194:197], v165 offset:54272
	ds_read_b128 v[198:201], v165 offset:55296
	ds_read_b128 v[202:205], v165 offset:56320
	s_add_i32 m0, s49, 0xffffff80
	v_mov_b32_e32 v80, v156
	global_load_lds_dwordx4 v154, s[42:43] offset:128
	s_add_i32 m0, s61, 0xffffff80
	s_nop 0
	global_load_lds_dwordx4 v156, s[42:43] offset:128
	s_barrier
; __device__ __forceinline__ float rinv_of(unsigned long long ss) { return rsqrtf((float)ss * (1.f / 16777216.f) * (1.f / DM) + 1e-6f); }
; #define G_STAGE(bufoff, gbase, voff) do { _Pragma("unroll") for (int _i = 0; _i < 2; ++_i) { unsigned _vo = (voff)[_i]; asm volatile("" : "+v"(_vo));   \
;     __builtin_amdgcn_global_load_lds((const unsigned*)((const char*)(gbase) + _vo), (LAS unsigned*)(lds + (bufoff) + ldsw + _i * 8192), 16, 0, 0); } } while (0)
; #define G_LDA(dst, b, h) do { _Pragma("unroll") for (int m = 0; m < 4; ++m) _Pragma("unroll") for (int k = 0; k < 2; ++k) dst[m][k] = *(const LAS bf16x8*)(lds + G_SA(b, h) + aoff + m * 2048 + k * 1024); } while (0)
; #define G_LDB(dst, b, h) do { _Pragma("unroll") for (int n = 0; n < 2; ++n) _Pragma("unroll") for (int k = 0; k < 2; ++k) dst[n][k] = *(const LAS bf16x8*)(lds + G_SB(b, h) + boff + n * 2048 + k * 1024); } while (0)
; #define G_WAIT_V(n) asm volatile("s_waitcnt vmcnt(" #n ")" ::: "memory")
; #define G_BAR __builtin_amdgcn_s_barrier()
;   __device__ __forceinline__ void operator()(const f32x4 (&acc)[2][2][4][2], const Unit& u, const EpiCtx& x_, int wr, int wc, int fr, int fq) const {
;     ...
;     if (SCALE == 2) {
; #pragma unroll
;       for (int bj = 0; bj < 2; ++bj) {
;         const unsigned long long* sp = x_.ss + u.c0 + (PERM ? wc * 64 + bj * 32 + 8 * fq : bj * 128 + wc * 32 + 4 * fq);
; #pragma unroll
;         for (int i = 0; i < 4; ++i) { cs[bj][0][i] = rinv_of(sp[i]); cs[bj][1][i] = rinv_of(sp[(PERM ? 4 : 16) + i]); }
;       }
; template <class Epi>
; __device__ __forceinline__ void gemm_phase(LAS unsigned char* lds, const int K, const unsigned lda_b, const unsigned ldb_b, const Map& M, const Epi& E) {
;     ...
;       G_BAR; G_WAIT_L(0); G_MMA(1, 0, At, B0); G_BAR; G_SCHED;
;       G_STAGE(G_SB(0, 1), b2h1, voffB);
;       G_WAIT_V(6); G_BAR; G_MMA(1, 1, At, B1); G_BAR;
;       G_LDB(B0, 1, 0); G_SCHED; G_LDA(At, 1, 0); G_STAGE(G_SA(0, 1), a2h1, voffA);
;       G_WAIT_L(8); G_BAR; G_WAIT_L(0); G_MMA(0, 0, At, B0); G_BAR; G_SCHED;
;       G_LDB(B1, 1, 1); G_STAGE(G_SB(1, 0), b2h0 + kstep, voffB);
;       G_BAR; G_WAIT_L(0); G_MMA(0, 1, At, B1); G_BAR;
;       G_LDA(At, 1, 1); G_STAGE(G_SA(1, 0), a2h0 + kstep, voffA);
;       G_BAR; G_WAIT_L(0); G_MMA(1, 0, At, B0); G_BAR; G_SCHED;
;       G_STAGE(G_SB(1, 1), b2h1 + kstep, voffB);
;       G_WAIT_V(6); G_BAR; G_MMA(1, 1, At, B1); G_BAR;
	s_waitcnt lgkmcnt(0)
	s_setprio 1
	s_waitcnt lgkmcnt(0)
	v_mfma_f32_16x16x32_bf16 v[60:63], v[138:141], v[166:169], v[60:63]
	v_mfma_f32_16x16x32_bf16 v[56:59], v[146:149], v[166:169], v[56:59]
	v_mfma_f32_16x16x32_bf16 v[44:47], v[138:141], v[174:177], v[44:47]
	v_mfma_f32_16x16x32_bf16 v[40:43], v[146:149], v[174:177], v[40:43]
	v_mfma_f32_16x16x32_bf16 v[28:31], v[138:141], v[190:193], v[28:31]
	v_mfma_f32_16x16x32_bf16 v[24:27], v[146:149], v[190:193], v[24:27]
	v_mfma_f32_16x16x32_bf16 v[12:15], v[138:141], v[198:201], v[12:15]
	v_mfma_f32_16x16x32_bf16 v[8:11], v[146:149], v[198:201], v[8:11]
	v_mfma_f32_16x16x32_bf16 v[60:63], v[142:145], v[170:173], v[60:63]
	v_mfma_f32_16x16x32_bf16 v[56:59], v[150:153], v[170:173], v[56:59]
	v_mfma_f32_16x16x32_bf16 v[44:47], v[142:145], v[184:187], v[44:47]
	v_mfma_f32_16x16x32_bf16 v[40:43], v[150:153], v[184:187], v[40:43]
	v_mfma_f32_16x16x32_bf16 v[28:31], v[142:145], v[194:197], v[28:31]
	v_mfma_f32_16x16x32_bf16 v[24:27], v[150:153], v[194:197], v[24:27]
	v_mfma_f32_16x16x32_bf16 v[12:15], v[142:145], v[202:205], v[12:15]
	v_mfma_f32_16x16x32_bf16 v[8:11], v[150:153], v[202:205], v[8:11]
	s_setprio 0
	s_barrier
	v_mov_b32_e32 v80, v155
	s_add_i32 s22, s34, s18
	s_add_i32 m0, s22, 0xffffff80
	v_mov_b32_e32 v80, v157
	global_load_lds_dwordx4 v155, s[38:39] offset:128
	s_add_i32 m0, s22, 0x1f80
	s_nop 0
	global_load_lds_dwordx4 v157, s[38:39] offset:128
	s_waitcnt vmcnt(6)
	s_barrier
	s_setprio 1
	v_mfma_f32_16x16x32_bf16 v[52:55], v[206:209], v[166:169], v[52:55]
	v_mfma_f32_16x16x32_bf16 v[48:51], v[214:217], v[166:169], v[48:51]
	v_mfma_f32_16x16x32_bf16 v[36:39], v[206:209], v[174:177], v[36:39]
	v_mfma_f32_16x16x32_bf16 v[32:35], v[214:217], v[174:177], v[32:35]
	v_mfma_f32_16x16x32_bf16 v[20:23], v[206:209], v[190:193], v[20:23]
	v_mfma_f32_16x16x32_bf16 v[16:19], v[214:217], v[190:193], v[16:19]
	v_mfma_f32_16x16x32_bf16 v[4:7], v[206:209], v[198:201], v[4:7]
	v_mfma_f32_16x16x32_bf16 v[0:3], v[214:217], v[198:201], v[0:3]
	v_mfma_f32_16x16x32_bf16 v[52:55], v[210:213], v[170:173], v[52:55]
	v_mfma_f32_16x16x32_bf16 v[48:51], v[218:221], v[170:173], v[48:51]
	v_mfma_f32_16x16x32_bf16 v[36:39], v[210:213], v[184:187], v[36:39]
	v_mfma_f32_16x16x32_bf16 v[32:35], v[218:221], v[184:187], v[32:35]
	v_mfma_f32_16x16x32_bf16 v[20:23], v[210:213], v[194:197], v[20:23]
	v_mfma_f32_16x16x32_bf16 v[16:19], v[218:221], v[194:197], v[16:19]
	v_mfma_f32_16x16x32_bf16 v[4:7], v[210:213], v[202:205], v[4:7]
	v_mfma_f32_16x16x32_bf16 v[0:3], v[218:221], v[202:205], v[0:3]
	s_setprio 0
	s_add_i32 s31, s31, 2
	s_add_u32 s29, s29, 0x100
	s_addc_u32 s30, s30, 0
	s_add_u32 s2, s2, 0x100
	s_addc_u32 s3, s3, 0
	s_cmp_gt_u32 s31, 29
	s_barrier
	s_cbranch_scc0 .LBB0_235
	s_ashr_i32 s95, s94, 31
	v_readfirstlane_b32 s0, v130
	v_readfirstlane_b32 s42, v131
	v_lshl_add_u64 v[130:131], s[94:95], 3, v[134:135]
	s_nop 1
	global_load_dwordx4 v[170:173], v[130:131], off
	global_load_dwordx4 v[174:177], v[130:131], off offset:48
	global_load_dwordx4 v[184:187], v[130:131], off offset:272
	global_load_dwordx4 v[190:193], v[130:131], off offset:32
	global_load_dwordx4 v[194:197], v[130:131], off offset:16
	global_load_dwordx4 v[198:201], v[130:131], off offset:256
	global_load_dwordx4 v[202:205], v[130:131], off offset:288
	global_load_dwordx4 v[206:209], v[130:131], off offset:304
	s_nop 0
	s_nop 0
	v_mov_b64_e32 v[146:147], s[62:63]
	v_mov_b32_e32 v137, v81
	s_add_i32 s28, s67, s94
	s_ashr_i32 s29, s28, 31
	s_lshl_b64 s[38:39], s[28:29], 1
	s_nop 0
	s_waitcnt lgkmcnt(0)
	s_waitcnt vmcnt(7)
	v_ffbh_u32_e32 v80, v173
	v_min_u32_e32 v80, 32, v80
	v_lshlrev_b64 v[132:133], v80, v[172:173]
	s_nop 0
	v_min_u32_e32 v132, 1, v132
	v_or_b32_e32 v132, v133, v132
	v_cvt_f32_u32_e32 v132, v132
	v_sub_u32_e32 v80, 32, v80
	v_ldexp_f32 v133, v132, v80
	v_ffbh_u32_e32 v80, v171
	v_min_u32_e32 v80, 32, v80
	v_lshlrev_b64 v[138:139], v80, v[170:171]
	v_min_u32_e32 v132, 1, v138
	v_or_b32_e32 v132, v139, v132
	v_cvt_f32_u32_e32 v132, v132
	v_sub_u32_e32 v80, 32, v80
	v_ldexp_f32 v132, v132, v80
	v_pk_mul_f32 v[132:133], v[132:133], s[60:61] op_sel_hi:[1,0]
	s_nop 0
	v_pk_fma_f32 v[132:133], v[132:133], s[26:27], v[146:147] op_sel_hi:[1,0,0]
	s_nop 0
	v_mul_f32_e32 v80, 0x4b800000, v132
	v_cmp_gt_f32_e64 s[2:3], s50, v132
	v_cmp_gt_f32_e32 vcc, s50, v133
	s_nop 0
	v_cndmask_b32_e64 v80, v132, v80, s[2:3]
	v_rsq_f32_e32 v132, v80
	v_mul_f32_e32 v80, 0x4b800000, v133
	v_cndmask_b32_e32 v80, v133, v80, vcc
	v_rsq_f32_e32 v133, v80
	s_waitcnt lgkmcnt(0)
	s_waitcnt vmcnt(4)
	v_ffbh_u32_e32 v80, v193
	v_pk_mul_f32 v[138:139], v[132:133], s[64:65] op_sel_hi:[1,0]
	v_min_u32_e32 v80, 32, v80
	v_cndmask_b32_e32 v139, v133, v139, vcc
	v_cndmask_b32_e64 v138, v132, v138, s[2:3]
	v_lshlrev_b64 v[132:133], v80, v[192:193]
	s_nop 0
	v_min_u32_e32 v132, 1, v132
	v_or_b32_e32 v132, v133, v132
	v_cvt_f32_u32_e32 v132, v132
	v_sub_u32_e32 v80, 32, v80
	v_pk_mul_f32 v[126:127], v[126:127], v[138:139]
	v_pk_mul_f32 v[110:111], v[110:111], v[138:139]
	v_ldexp_f32 v133, v132, v80
	v_ffbh_u32_e32 v80, v191
	v_min_u32_e32 v80, 32, v80
	v_lshlrev_b64 v[140:141], v80, v[190:191]
	v_min_u32_e32 v132, 1, v140
	v_or_b32_e32 v132, v141, v132
	v_cvt_f32_u32_e32 v132, v132
	v_sub_u32_e32 v80, 32, v80
	v_pk_mul_f32 v[94:95], v[94:95], v[138:139]
	v_pk_mul_f32 v[76:77], v[76:77], v[138:139]
	v_ldexp_f32 v132, v132, v80
	v_pk_mul_f32 v[132:133], v[132:133], s[60:61] op_sel_hi:[1,0]
	v_pk_mul_f32 v[60:61], v[60:61], v[138:139]
	v_pk_fma_f32 v[132:133], v[132:133], s[26:27], v[146:147] op_sel_hi:[1,0,0]
	v_pk_mul_f32 v[44:45], v[44:45], v[138:139]
	v_mul_f32_e32 v80, 0x4b800000, v132
	v_cmp_gt_f32_e64 s[2:3], s50, v132
	v_cmp_gt_f32_e32 vcc, s50, v133
	v_pk_mul_f32 v[28:29], v[28:29], v[138:139]
	v_cndmask_b32_e64 v80, v132, v80, s[2:3]
	v_rsq_f32_e32 v132, v80
	v_mul_f32_e32 v80, 0x4b800000, v133
	v_cndmask_b32_e32 v80, v133, v80, vcc
	v_rsq_f32_e32 v133, v80
	v_pk_mul_f32 v[12:13], v[12:13], v[138:139]
	v_pk_mul_f32 v[140:141], v[132:133], s[64:65] op_sel_hi:[1,0]
	s_nop 0
	v_cndmask_b32_e32 v141, v133, v141, vcc
	v_cndmask_b32_e64 v140, v132, v140, s[2:3]
	s_waitcnt lgkmcnt(0)
; __device__ __forceinline__ float rinv_of(unsigned long long ss) { return rsqrtf((float)ss * (1.f / 16777216.f) * (1.f / DM) + 1e-6f); }
;   __device__ __forceinline__ void operator()(const f32x4 (&acc)[2][2][4][2], const Unit& u, const EpiCtx& x_, int wr, int wc, int fr, int fq) const {
;     ...
;     if (SCALE == 2) {
; #pragma unroll
;       for (int bj = 0; bj < 2; ++bj) {
;         const unsigned long long* sp = x_.ss + u.c0 + (PERM ? wc * 64 + bj * 32 + 8 * fq : bj * 128 + wc * 32 + 4 * fq);
; #pragma unroll
;         for (int i = 0; i < 4; ++i) { cs[bj][0][i] = rinv_of(sp[i]); cs[bj][1][i] = rinv_of(sp[(PERM ? 4 : 16) + i]); }
;       }
;     }
; #pragma unroll
;     for (int ai = 0; ai < 2; ++ai)
; #pragma unroll
;       for (int m = 0; m < 4; ++m) {
;         const int row = (u.r0 + (ai ? x_.rdelta : 0)) + wr * 64 + m * 16 + fr;
;         bf16_t* rowp = (bf16_t*)u.C + (size_t)row * x_.ldc;
;         const float rs = (SCALE == 1) ? rinv_of(x_.ss[row]) : 1.f;
; #pragma unroll
;         for (int bj = 0; bj < 2; ++bj) {
;           const int cb = PERM ? (u.c0 + wc * 64 + bj * 32) : (u.c0 + bj * 128) + wc * 32;
;           f32x4 v0 = acc[ai][bj][m][0], v1 = acc[ai][bj][m][1];
;           if (SCALE == 1) { v0 *= rs; v1 *= rs; }
;           if (SCALE == 2) { v0 *= cs[bj][0]; v1 *= cs[bj][1]; }
	s_waitcnt vmcnt(3)
	v_ffbh_u32_e32 v80, v197
	v_min_u32_e32 v80, 32, v80
	v_lshlrev_b64 v[132:133], v80, v[196:197]
	v_min_u32_e32 v132, 1, v132
	v_or_b32_e32 v132, v133, v132
	v_cvt_f32_u32_e32 v132, v132
	v_sub_u32_e32 v80, 32, v80
	v_ldexp_f32 v133, v132, v80
	v_ffbh_u32_e32 v80, v195
	v_min_u32_e32 v80, 32, v80
	v_lshlrev_b64 v[142:143], v80, v[194:195]
	v_min_u32_e32 v132, 1, v142
	v_or_b32_e32 v132, v143, v132
	v_cvt_f32_u32_e32 v132, v132
	v_sub_u32_e32 v80, 32, v80
	v_ldexp_f32 v132, v132, v80
	v_pk_mul_f32 v[132:133], v[132:133], s[60:61] op_sel_hi:[1,0]
	s_nop 0
	v_pk_fma_f32 v[132:133], v[132:133], s[26:27], v[146:147] op_sel_hi:[1,0,0]
	s_nop 0
	v_mul_f32_e32 v80, 0x4b800000, v132
	v_cmp_gt_f32_e64 s[2:3], s50, v132
	v_cmp_gt_f32_e32 vcc, s50, v133
	s_nop 0
	v_cndmask_b32_e64 v80, v132, v80, s[2:3]
	v_rsq_f32_e32 v132, v80
	v_mul_f32_e32 v80, 0x4b800000, v133
	v_cndmask_b32_e32 v80, v133, v80, vcc
	v_rsq_f32_e32 v133, v80
	v_ffbh_u32_e32 v80, v177
	v_min_u32_e32 v80, 32, v80
	v_pk_mul_f32 v[142:143], v[132:133], s[64:65] op_sel_hi:[1,0]
	s_nop 0
	v_cndmask_b32_e32 v143, v133, v143, vcc
	v_cndmask_b32_e64 v142, v132, v142, s[2:3]
	v_lshlrev_b64 v[132:133], v80, v[176:177]
	v_min_u32_e32 v132, 1, v132
	v_or_b32_e32 v132, v133, v132
	v_cvt_f32_u32_e32 v132, v132
	v_sub_u32_e32 v80, 32, v80
	v_pk_mul_f32 v[128:129], v[128:129], v[142:143]
	v_pk_mul_f32 v[112:113], v[112:113], v[142:143]
	v_ldexp_f32 v133, v132, v80
	v_ffbh_u32_e32 v80, v175
	v_min_u32_e32 v80, 32, v80
	v_lshlrev_b64 v[144:145], v80, v[174:175]
	s_nop 0
	v_min_u32_e32 v132, 1, v144
	v_or_b32_e32 v132, v145, v132
	v_cvt_f32_u32_e32 v132, v132
	v_sub_u32_e32 v80, 32, v80
	v_pk_mul_f32 v[96:97], v[96:97], v[142:143]
	v_pk_mul_f32 v[78:79], v[78:79], v[142:143]
	v_ldexp_f32 v132, v132, v80
	v_pk_mul_f32 v[132:133], v[132:133], s[60:61] op_sel_hi:[1,0]
	v_pk_mul_f32 v[62:63], v[62:63], v[142:143]
	v_pk_fma_f32 v[132:133], v[132:133], s[26:27], v[146:147] op_sel_hi:[1,0,0]
	v_pk_mul_f32 v[46:47], v[46:47], v[142:143]
	v_mul_f32_e32 v80, 0x4b800000, v132
	v_cmp_gt_f32_e64 s[2:3], s50, v132
	v_cmp_gt_f32_e32 vcc, s50, v133
	v_pk_mul_f32 v[30:31], v[30:31], v[142:143]
	v_cndmask_b32_e64 v80, v132, v80, s[2:3]
	v_rsq_f32_e32 v132, v80
	v_mul_f32_e32 v80, 0x4b800000, v133
	v_cndmask_b32_e32 v80, v133, v80, vcc
	v_rsq_f32_e32 v133, v80
	v_pk_mul_f32 v[14:15], v[14:15], v[142:143]
	v_pk_mul_f32 v[144:145], v[132:133], s[64:65] op_sel_hi:[1,0]
	s_nop 0
	v_cndmask_b32_e32 v145, v133, v145, vcc
	v_cndmask_b32_e64 v144, v132, v144, s[2:3]
	s_waitcnt lgkmcnt(0)
	s_waitcnt vmcnt(2)
	v_ffbh_u32_e32 v80, v201
	v_min_u32_e32 v80, 32, v80
	v_lshlrev_b64 v[132:133], v80, v[200:201]
	s_nop 0
	v_min_u32_e32 v132, 1, v132
	v_or_b32_e32 v132, v133, v132
	v_cvt_f32_u32_e32 v132, v132
	v_sub_u32_e32 v80, 32, v80
	v_ldexp_f32 v133, v132, v80
	v_ffbh_u32_e32 v80, v199
	v_min_u32_e32 v80, 32, v80
	v_lshlrev_b64 v[148:149], v80, v[198:199]
	v_min_u32_e32 v132, 1, v148
	v_or_b32_e32 v132, v149, v132
	v_cvt_f32_u32_e32 v132, v132
	v_sub_u32_e32 v80, 32, v80
	v_ldexp_f32 v132, v132, v80
	v_pk_mul_f32 v[132:133], v[132:133], s[60:61] op_sel_hi:[1,0]
	s_nop 0
	v_pk_fma_f32 v[132:133], v[132:133], s[26:27], v[146:147] op_sel_hi:[1,0,0]
	s_nop 0
	v_mul_f32_e32 v80, 0x4b800000, v132
	v_cmp_gt_f32_e64 s[2:3], s50, v132
	v_cmp_gt_f32_e32 vcc, s50, v133
	s_nop 0
	v_cndmask_b32_e64 v80, v132, v80, s[2:3]
	v_rsq_f32_e32 v132, v80
	v_mul_f32_e32 v80, 0x4b800000, v133
	v_cndmask_b32_e32 v80, v133, v80, vcc
	v_rsq_f32_e32 v133, v80
	s_waitcnt lgkmcnt(0)
	s_waitcnt vmcnt(1)
	v_ffbh_u32_e32 v80, v205
	v_pk_mul_f32 v[148:149], v[132:133], s[64:65] op_sel_hi:[1,0]
	v_min_u32_e32 v80, 32, v80
	v_cndmask_b32_e32 v149, v133, v149, vcc
	v_cndmask_b32_e64 v148, v132, v148, s[2:3]
	v_lshlrev_b64 v[132:133], v80, v[204:205]
	v_min_u32_e32 v132, 1, v132
	v_or_b32_e32 v132, v133, v132
	v_cvt_f32_u32_e32 v132, v132
	v_sub_u32_e32 v80, 32, v80
	v_pk_mul_f32 v[118:119], v[118:119], v[148:149]
	v_pk_mul_f32 v[102:103], v[102:103], v[148:149]
	v_ldexp_f32 v133, v132, v80
	v_ffbh_u32_e32 v80, v203
	v_min_u32_e32 v80, 32, v80
	v_lshlrev_b64 v[150:151], v80, v[202:203]
	v_min_u32_e32 v132, 1, v150
	v_or_b32_e32 v132, v151, v132
	v_cvt_f32_u32_e32 v132, v132
	v_sub_u32_e32 v80, 32, v80
	v_pk_mul_f32 v[86:87], v[86:87], v[148:149]
	v_pk_mul_f32 v[68:69], v[68:69], v[148:149]
	v_ldexp_f32 v132, v132, v80
	v_pk_mul_f32 v[132:133], v[132:133], s[60:61] op_sel_hi:[1,0]
	v_pk_mul_f32 v[52:53], v[52:53], v[148:149]
	v_pk_fma_f32 v[132:133], v[132:133], s[26:27], v[146:147] op_sel_hi:[1,0,0]
	v_pk_mul_f32 v[36:37], v[36:37], v[148:149]
	v_mul_f32_e32 v80, 0x4b800000, v132
	v_cmp_gt_f32_e64 s[2:3], s50, v132
	v_cmp_gt_f32_e32 vcc, s50, v133
	v_pk_mul_f32 v[20:21], v[20:21], v[148:149]
	v_cndmask_b32_e64 v80, v132, v80, s[2:3]
	v_rsq_f32_e32 v132, v80
	v_mul_f32_e32 v80, 0x4b800000, v133
	v_cndmask_b32_e32 v80, v133, v80, vcc
	v_rsq_f32_e32 v133, v80
	v_ffbh_u32_e32 v80, v187
	v_min_u32_e32 v80, 32, v80
	v_pk_mul_f32 v[4:5], v[4:5], v[148:149]
	v_pk_mul_f32 v[150:151], v[132:133], s[64:65] op_sel_hi:[1,0]
	s_nop 0
	v_cndmask_b32_e32 v151, v133, v151, vcc
	v_cndmask_b32_e64 v150, v132, v150, s[2:3]
	v_lshlrev_b64 v[132:133], v80, v[186:187]
	v_min_u32_e32 v132, 1, v132
	v_or_b32_e32 v132, v133, v132
	v_cvt_f32_u32_e32 v132, v132
	v_sub_u32_e32 v80, 32, v80
	v_ldexp_f32 v133, v132, v80
	v_ffbh_u32_e32 v80, v185
	v_min_u32_e32 v80, 32, v80
	v_lshlrev_b64 v[152:153], v80, v[184:185]
	v_min_u32_e32 v132, 1, v152
	v_or_b32_e32 v132, v153, v132
	v_cvt_f32_u32_e32 v132, v132
	v_sub_u32_e32 v80, 32, v80
	v_pk_mul_f32 v[166:167], v[124:125], v[144:145]
	v_pk_mul_f32 v[124:125], v[122:123], v[140:141]
	v_ldexp_f32 v132, v132, v80
	v_pk_mul_f32 v[132:133], v[132:133], s[60:61] op_sel_hi:[1,0]
	v_cvt_pk_bf16_f32 v122, v126, v127
	v_cvt_pk_bf16_f32 v123, v128, v129
	v_cvt_pk_bf16_f32 v124, v124, v125
	v_cvt_pk_bf16_f32 v125, v166, v167
	s_nop 0
	v_pk_fma_f32 v[132:133], v[132:133], s[26:27], v[146:147] op_sel_hi:[1,0,0]
	s_nop 0
	v_mul_f32_e32 v80, 0x4b800000, v132
	v_cmp_gt_f32_e64 s[2:3], s50, v132
	v_cmp_gt_f32_e32 vcc, s50, v133
	s_nop 0
	v_cndmask_b32_e64 v80, v132, v80, s[2:3]
	v_rsq_f32_e32 v132, v80
	v_mul_f32_e32 v80, 0x4b800000, v133
	v_cndmask_b32_e32 v80, v133, v80, vcc
	v_rsq_f32_e32 v133, v80
	s_nop 0
	v_pk_mul_f32 v[152:153], v[132:133], s[64:65] op_sel_hi:[1,0]
	s_nop 0
	v_cndmask_b32_e32 v153, v133, v153, vcc
	v_cndmask_b32_e64 v152, v132, v152, s[2:3]
	s_nop 0
	v_pk_mul_f32 v[120:121], v[120:121], v[152:153]
	v_pk_mul_f32 v[104:105], v[104:105], v[152:153]
	v_pk_mul_f32 v[88:89], v[88:89], v[152:153]
	v_pk_mul_f32 v[70:71], v[70:71], v[152:153]
	v_pk_mul_f32 v[54:55], v[54:55], v[152:153]
	v_pk_mul_f32 v[38:39], v[38:39], v[152:153]
	v_pk_mul_f32 v[22:23], v[22:23], v[152:153]
	v_pk_mul_f32 v[6:7], v[6:7], v[152:153]
	s_waitcnt lgkmcnt(0)
; __device__ __forceinline__ unsigned cvt_pk_bf16(float lo, float hi) { unsigned r; asm("v_cvt_pk_bf16_f32 %0, %1, %2" : "=v"(r) : "v"(lo), "v"(hi)); return r; }
; __device__ __forceinline__ float rinv_of(unsigned long long ss) { return rsqrtf((float)ss * (1.f / 16777216.f) * (1.f / DM) + 1e-6f); }
;   __device__ __forceinline__ void operator()(const f32x4 (&acc)[2][2][4][2], const Unit& u, const EpiCtx& x_, int wr, int wc, int fr, int fq) const {
;     ...
; #pragma unroll
;     for (int ai = 0; ai < 2; ++ai)
; #pragma unroll
;       for (int m = 0; m < 4; ++m) {
;         const int row = (u.r0 + (ai ? x_.rdelta : 0)) + wr * 64 + m * 16 + fr;
;         bf16_t* rowp = (bf16_t*)u.C + (size_t)row * x_.ldc;
;         const float rs = (SCALE == 1) ? rinv_of(x_.ss[row]) : 1.f;
; #pragma unroll
;         for (int bj = 0; bj < 2; ++bj) {
;           const int cb = PERM ? (u.c0 + wc * 64 + bj * 32) : (u.c0 + bj * 128) + wc * 32;
;           f32x4 v0 = acc[ai][bj][m][0], v1 = acc[ai][bj][m][1];
;           if (SCALE == 1) { v0 *= rs; v1 *= rs; }
;           if (SCALE == 2) { v0 *= cs[bj][0]; v1 *= cs[bj][1]; }
;           if (PERM) {
;             uint4 o; o.x = cvt_pk_bf16(v0[0], v0[1]); o.y = cvt_pk_bf16(v0[2], v0[3]); o.z = cvt_pk_bf16(v1[0], v1[1]); o.w = cvt_pk_bf16(v1[2], v1[3]);
;             *(uint4*)(rowp + cb + 8 * fq) = o;
;           } else {
;             uint2 o0, o1; o0.x = cvt_pk_bf16(v0[0], v0[1]); o0.y = cvt_pk_bf16(v0[2], v0[3]); o1.x = cvt_pk_bf16(v1[0], v1[1]); o1.y = cvt_pk_bf16(v1[2], v1[3]);
;             *(uint2*)(rowp + cb + 4 * fq) = o0; *(uint2*)(rowp + cb + 16 + 4 * fq) = o1;
;           }
;         }
	s_waitcnt vmcnt(0)
	v_ffbh_u32_e32 v80, v209
	v_min_u32_e32 v80, 32, v80
	v_lshlrev_b64 v[132:133], v80, v[208:209]
	v_min_u32_e32 v132, 1, v132
	v_or_b32_e32 v132, v133, v132
	v_cvt_f32_u32_e32 v132, v132
	v_sub_u32_e32 v80, 32, v80
	v_ldexp_f32 v133, v132, v80
	v_ffbh_u32_e32 v80, v207
	v_min_u32_e32 v80, 32, v80
	v_lshlrev_b64 v[130:131], v80, v[206:207]
	v_min_u32_e32 v130, 1, v130
	v_or_b32_e32 v130, v131, v130
	v_cvt_f32_u32_e32 v130, v130
	v_sub_u32_e32 v80, 32, v80
	v_ldexp_f32 v132, v130, v80
	v_pk_mul_f32 v[130:131], v[132:133], s[60:61] op_sel_hi:[1,0]
	s_nop 0
	v_pk_fma_f32 v[130:131], v[130:131], s[26:27], v[146:147] op_sel_hi:[1,0,0]
	s_nop 0
	v_mul_f32_e32 v80, 0x4b800000, v130
	v_cmp_gt_f32_e64 s[2:3], s50, v130
	v_cmp_gt_f32_e32 vcc, s50, v131
	s_nop 0
	v_cndmask_b32_e64 v80, v130, v80, s[2:3]
	v_rsq_f32_e32 v130, v80
	v_mul_f32_e32 v80, 0x4b800000, v131
	v_cndmask_b32_e32 v80, v131, v80, vcc
	v_rsq_f32_e32 v131, v80
	s_nop 0
	v_pk_mul_f32 v[132:133], v[130:131], s[64:65] op_sel_hi:[1,0]
	s_nop 0
	v_cndmask_b32_e64 v130, v130, v132, s[2:3]
	v_add_u32_e32 v132, s79, v159
	v_cndmask_b32_e32 v131, v131, v133, vcc
	v_ashrrev_i32_e32 v133, 31, v132
	v_lshlrev_b64 v[146:147], 15, v[132:133]
	s_add_i32 s2, s94, s66
	v_lshl_add_u64 v[146:147], s[4:5], 0, v[146:147]
	s_ashr_i32 s3, s2, 31
	v_lshl_add_u64 v[146:147], v[146:147], 0, v[136:137]
	s_lshl_b64 s[2:3], s[2:3], 1
	v_lshl_add_u64 v[126:127], v[146:147], 0, s[2:3]
	global_store_dwordx4 v[126:127], v[122:125], off nt
	s_cmp_eq_u32 s76, s75
	s_mov_b32 s94, s42
	v_pk_mul_f32 v[122:123], v[116:117], v[130:131]
	v_pk_mul_f32 v[116:117], v[114:115], v[150:151]
	v_cvt_pk_bf16_f32 v114, v118, v119
	v_lshl_add_u64 v[118:119], v[146:147], 0, s[38:39]
	v_cvt_pk_bf16_f32 v115, v120, v121
	v_cvt_pk_bf16_f32 v116, v116, v117
	v_cvt_pk_bf16_f32 v117, v122, v123
	global_store_dwordx4 v[118:119], v[114:117], off nt
	v_pk_mul_f32 v[118:119], v[108:109], v[144:145]
	v_pk_mul_f32 v[108:109], v[106:107], v[140:141]
	v_add_u32_e32 v114, s79, v161
	v_ashrrev_i32_e32 v115, 31, v114
	v_lshlrev_b64 v[116:117], 15, v[114:115]
	v_lshl_add_u64 v[116:117], s[4:5], 0, v[116:117]
	v_lshl_add_u64 v[116:117], v[116:117], 0, v[136:137]
	v_cvt_pk_bf16_f32 v106, v110, v111
	v_cvt_pk_bf16_f32 v107, v112, v113
	v_lshl_add_u64 v[110:111], v[116:117], 0, s[2:3]
	v_cvt_pk_bf16_f32 v108, v108, v109
	v_cvt_pk_bf16_f32 v109, v118, v119
	global_store_dwordx4 v[110:111], v[106:109], off nt
	s_nop 1
	v_pk_mul_f32 v[106:107], v[100:101], v[130:131]
	v_pk_mul_f32 v[100:101], v[98:99], v[150:151]
	v_cvt_pk_bf16_f32 v98, v102, v103
	v_lshl_add_u64 v[102:103], v[116:117], 0, s[38:39]
	v_cvt_pk_bf16_f32 v99, v104, v105
	v_cvt_pk_bf16_f32 v100, v100, v101
	v_cvt_pk_bf16_f32 v101, v106, v107
	global_store_dwordx4 v[102:103], v[98:101], off nt
	v_pk_mul_f32 v[102:103], v[92:93], v[144:145]
	v_pk_mul_f32 v[92:93], v[90:91], v[140:141]
	v_add_u32_e32 v98, s79, v163
	v_ashrrev_i32_e32 v99, 31, v98
	v_lshlrev_b64 v[100:101], 15, v[98:99]
	v_lshl_add_u64 v[100:101], s[4:5], 0, v[100:101]
	v_lshl_add_u64 v[100:101], v[100:101], 0, v[136:137]
	v_cvt_pk_bf16_f32 v90, v94, v95
	v_cvt_pk_bf16_f32 v91, v96, v97
	v_lshl_add_u64 v[94:95], v[100:101], 0, s[2:3]
	v_cvt_pk_bf16_f32 v92, v92, v93
	v_cvt_pk_bf16_f32 v93, v102, v103
	global_store_dwordx4 v[94:95], v[90:93], off nt
	s_nop 1
	v_pk_mul_f32 v[90:91], v[84:85], v[130:131]
	v_pk_mul_f32 v[84:85], v[82:83], v[150:151]
	v_cvt_pk_bf16_f32 v82, v86, v87
	v_lshl_add_u64 v[86:87], v[100:101], 0, s[38:39]
	v_cvt_pk_bf16_f32 v83, v88, v89
	v_cvt_pk_bf16_f32 v84, v84, v85
	v_cvt_pk_bf16_f32 v85, v90, v91
	global_store_dwordx4 v[86:87], v[82:85], off nt
	v_pk_mul_f32 v[86:87], v[74:75], v[144:145]
	v_pk_mul_f32 v[74:75], v[72:73], v[140:141]
	v_add_u32_e32 v82, s79, v164
	v_ashrrev_i32_e32 v83, 31, v82
	v_lshlrev_b64 v[84:85], 15, v[82:83]
	v_lshl_add_u64 v[84:85], s[4:5], 0, v[84:85]
	v_lshl_add_u64 v[84:85], v[84:85], 0, v[136:137]
	v_cvt_pk_bf16_f32 v72, v76, v77
	v_cvt_pk_bf16_f32 v73, v78, v79
; __device__ __forceinline__ unsigned cvt_pk_bf16(float lo, float hi) { unsigned r; asm("v_cvt_pk_bf16_f32 %0, %1, %2" : "=v"(r) : "v"(lo), "v"(hi)); return r; }
; #define G_WAIT_V(n) asm volatile("s_waitcnt vmcnt(" #n ")" ::: "memory")
; #define G_BAR __builtin_amdgcn_s_barrier()
;   __device__ __forceinline__ void operator()(const f32x4 (&acc)[2][2][4][2], const Unit& u, const EpiCtx& x_, int wr, int wc, int fr, int fq) const {
;     ...
;         for (int bj = 0; bj < 2; ++bj) {
;           const int cb = PERM ? (u.c0 + wc * 64 + bj * 32) : (u.c0 + bj * 128) + wc * 32;
;           f32x4 v0 = acc[ai][bj][m][0], v1 = acc[ai][bj][m][1];
;           if (SCALE == 1) { v0 *= rs; v1 *= rs; }
;           if (SCALE == 2) { v0 *= cs[bj][0]; v1 *= cs[bj][1]; }
;           if (PERM) {
;             uint4 o; o.x = cvt_pk_bf16(v0[0], v0[1]); o.y = cvt_pk_bf16(v0[2], v0[3]); o.z = cvt_pk_bf16(v1[0], v1[1]); o.w = cvt_pk_bf16(v1[2], v1[3]);
;             *(uint4*)(rowp + cb + 8 * fq) = o;
;           } else {
;             uint2 o0, o1; o0.x = cvt_pk_bf16(v0[0], v0[1]); o0.y = cvt_pk_bf16(v0[2], v0[3]); o1.x = cvt_pk_bf16(v1[0], v1[1]); o1.y = cvt_pk_bf16(v1[2], v1[3]);
;             *(uint2*)(rowp + cb + 4 * fq) = o0; *(uint2*)(rowp + cb + 16 + 4 * fq) = o1;
;           }
;         }
; template <class Epi>
; __device__ __forceinline__ void gemm_phase(LAS unsigned char* lds, const int K, const unsigned lda_b, const unsigned ldb_b, const Map& M, const Epi& E) {
;     ...
;     if (!has_next) break;
; #pragma unroll
;     for (int a = 0; a < 2; ++a)
; #pragma unroll
;       for (int b = 0; b < 2; ++b)
; #pragma unroll
;         for (int m = 0; m < 4; ++m)
; #pragma unroll
;           for (int n = 0; n < 2; ++n) acc[a][b][m][n] = (f32x4){0.f, 0.f, 0.f, 0.f};
;     cur = nxt; ++ui;
;   }
;   G_WAIT_V(0);
;   if (wr == 0) G_BAR;
	v_lshl_add_u64 v[76:77], v[84:85], 0, s[2:3]
	v_cvt_pk_bf16_f32 v74, v74, v75
	v_cvt_pk_bf16_f32 v75, v86, v87
	global_store_dwordx4 v[76:77], v[72:75], off nt
	s_mov_b32 s79, s0
	s_nop 0
	v_pk_mul_f32 v[72:73], v[66:67], v[130:131]
	v_pk_mul_f32 v[66:67], v[64:65], v[150:151]
	v_cvt_pk_bf16_f32 v64, v68, v69
	v_lshl_add_u64 v[68:69], v[84:85], 0, s[38:39]
	v_cvt_pk_bf16_f32 v65, v70, v71
	v_cvt_pk_bf16_f32 v66, v66, v67
	v_cvt_pk_bf16_f32 v67, v72, v73
	global_store_dwordx4 v[68:69], v[64:67], off nt
	s_nop 1
	v_add_u32_e32 v64, 0x80, v132
	v_ashrrev_i32_e32 v65, 31, v64
	v_lshlrev_b64 v[64:65], 15, v[64:65]
	v_lshl_add_u64 v[64:65], s[4:5], 0, v[64:65]
	v_lshl_add_u64 v[64:65], v[64:65], 0, v[136:137]
	v_pk_mul_f32 v[66:67], v[58:59], v[144:145]
	v_pk_mul_f32 v[58:59], v[56:57], v[140:141]
	v_cvt_pk_bf16_f32 v56, v60, v61
	v_cvt_pk_bf16_f32 v57, v62, v63
	v_lshl_add_u64 v[60:61], v[64:65], 0, s[2:3]
	v_cvt_pk_bf16_f32 v58, v58, v59
	v_cvt_pk_bf16_f32 v59, v66, v67
	global_store_dwordx4 v[60:61], v[56:59], off nt
	s_nop 1
	v_pk_mul_f32 v[56:57], v[50:51], v[130:131]
	v_pk_mul_f32 v[50:51], v[48:49], v[150:151]
	v_cvt_pk_bf16_f32 v48, v52, v53
	v_lshl_add_u64 v[52:53], v[64:65], 0, s[38:39]
	v_cvt_pk_bf16_f32 v49, v54, v55
	v_cvt_pk_bf16_f32 v50, v50, v51
	v_cvt_pk_bf16_f32 v51, v56, v57
	global_store_dwordx4 v[52:53], v[48:51], off nt
	s_nop 1
	v_add_u32_e32 v48, 0x80, v114
	v_ashrrev_i32_e32 v49, 31, v48
	v_lshlrev_b64 v[48:49], 15, v[48:49]
	v_lshl_add_u64 v[48:49], s[4:5], 0, v[48:49]
	v_lshl_add_u64 v[48:49], v[48:49], 0, v[136:137]
	v_pk_mul_f32 v[50:51], v[42:43], v[144:145]
	v_pk_mul_f32 v[42:43], v[40:41], v[140:141]
	v_cvt_pk_bf16_f32 v40, v44, v45
	v_cvt_pk_bf16_f32 v41, v46, v47
	v_lshl_add_u64 v[44:45], v[48:49], 0, s[2:3]
	v_cvt_pk_bf16_f32 v42, v42, v43
	v_cvt_pk_bf16_f32 v43, v50, v51
	global_store_dwordx4 v[44:45], v[40:43], off nt
	s_nop 1
	v_pk_mul_f32 v[40:41], v[34:35], v[130:131]
	v_pk_mul_f32 v[34:35], v[32:33], v[150:151]
	v_cvt_pk_bf16_f32 v32, v36, v37
	v_lshl_add_u64 v[36:37], v[48:49], 0, s[38:39]
	v_cvt_pk_bf16_f32 v33, v38, v39
	v_cvt_pk_bf16_f32 v34, v34, v35
	v_cvt_pk_bf16_f32 v35, v40, v41
	global_store_dwordx4 v[36:37], v[32:35], off nt
	s_nop 1
	v_add_u32_e32 v32, 0x80, v98
	v_ashrrev_i32_e32 v33, 31, v32
	v_lshlrev_b64 v[32:33], 15, v[32:33]
	v_lshl_add_u64 v[32:33], s[4:5], 0, v[32:33]
	v_lshl_add_u64 v[32:33], v[32:33], 0, v[136:137]
	v_pk_mul_f32 v[34:35], v[26:27], v[144:145]
	v_pk_mul_f32 v[26:27], v[24:25], v[140:141]
	v_cvt_pk_bf16_f32 v24, v28, v29
	v_cvt_pk_bf16_f32 v25, v30, v31
	v_lshl_add_u64 v[28:29], v[32:33], 0, s[2:3]
	v_cvt_pk_bf16_f32 v26, v26, v27
	v_cvt_pk_bf16_f32 v27, v34, v35
	global_store_dwordx4 v[28:29], v[24:27], off nt
	s_nop 1
	v_pk_mul_f32 v[24:25], v[18:19], v[130:131]
	v_pk_mul_f32 v[18:19], v[16:17], v[150:151]
	v_cvt_pk_bf16_f32 v16, v20, v21
	v_lshl_add_u64 v[20:21], v[32:33], 0, s[38:39]
	v_cvt_pk_bf16_f32 v17, v22, v23
	v_cvt_pk_bf16_f32 v18, v18, v19
	v_cvt_pk_bf16_f32 v19, v24, v25
	global_store_dwordx4 v[20:21], v[16:19], off nt
	s_nop 1
	v_add_u32_e32 v16, 0x80, v82
	v_ashrrev_i32_e32 v17, 31, v16
	v_lshlrev_b64 v[16:17], 15, v[16:17]
	v_lshl_add_u64 v[16:17], s[4:5], 0, v[16:17]
	v_lshl_add_u64 v[16:17], v[16:17], 0, v[136:137]
	v_pk_mul_f32 v[18:19], v[10:11], v[144:145]
	v_pk_mul_f32 v[10:11], v[8:9], v[140:141]
	v_cvt_pk_bf16_f32 v8, v12, v13
	v_cvt_pk_bf16_f32 v9, v14, v15
	v_lshl_add_u64 v[12:13], v[16:17], 0, s[2:3]
	v_cvt_pk_bf16_f32 v10, v10, v11
	v_cvt_pk_bf16_f32 v11, v18, v19
	global_store_dwordx4 v[12:13], v[8:11], off nt
	s_mov_b64 s[2:3], s[6:7]
	s_mov_b64 s[4:5], s[40:41]
	v_pk_mul_f32 v[8:9], v[2:3], v[130:131]
	v_pk_mul_f32 v[2:3], v[0:1], v[150:151]
	v_cvt_pk_bf16_f32 v0, v4, v5
	v_lshl_add_u64 v[4:5], v[16:17], 0, s[38:39]
	s_mov_b64 s[38:39], s[8:9]
	v_cvt_pk_bf16_f32 v1, v6, v7
	v_cvt_pk_bf16_f32 v2, v2, v3
	v_cvt_pk_bf16_f32 v3, v8, v9
	global_store_dwordx4 v[4:5], v[0:3], off nt
	s_cbranch_scc0 .LBB0_234
	s_waitcnt vmcnt(0)
	s_cmpk_gt_u32 s13, 0xff
	s_cbranch_scc1 .LBB0_239
	s_barrier

; #define G_STAGE(bufoff, gbase, voff) do { _Pragma("unroll") for (int _i = 0; _i < 2; ++_i) { unsigned _vo = (voff)[_i]; asm volatile("" : "+v"(_vo));   \
;     __builtin_amdgcn_global_load_lds((const unsigned*)((const char*)(gbase) + _vo), (LAS unsigned*)(lds + (bufoff) + ldsw + _i * 8192), 16, 0, 0); } } while (0)
; #define G_LDA(dst, b, h) do { _Pragma("unroll") for (int m = 0; m < 4; ++m) _Pragma("unroll") for (int k = 0; k < 2; ++k) dst[m][k] = *(const LAS bf16x8*)(lds + G_SA(b, h) + aoff + m * 2048 + k * 1024); } while (0)
; #define G_LDB(dst, b, h) do { _Pragma("unroll") for (int n = 0; n < 2; ++n) _Pragma("unroll") for (int k = 0; k < 2; ++k) dst[n][k] = *(const LAS bf16x8*)(lds + G_SB(b, h) + boff + n * 2048 + k * 1024); } while (0)
; template <class Epi>
; __device__ __forceinline__ void gemm_phase(LAS unsigned char* lds, const int K, const unsigned lda_b, const unsigned ldb_b, const Map& M, const Epi& E) {
;     ...
;     for (int t = 0; t < nt; t += 2) {
;       const bool last = (t == nt - 2);
;       const char* a1h1 = cur.a0 + a_h + (size_t)(t + 1) * kstep;
;       const char* a2h0 = last ? nxt.a0 : cur.a0 + (size_t)(t + 2) * kstep; const char* a2h1 = a2h0 + a_h;
;       const char* b2h0 = last ? nxt.b0 : cur.b0 + (size_t)(t + 2) * kstep; const char* b2h1 = last ? nxt.b1 : cur.b1 + (size_t)(t + 2) * kstep;
;       G_LDB(B0, 0, 0); G_SCHED; G_LDA(At, 0, 0); G_STAGE(G_SA(1, 1), a1h1, voffA);
;       G_WAIT_L(8); G_BAR; G_WAIT_L(0); G_MMA(0, 0, At, B0); G_BAR; G_SCHED;
;       G_LDB(B1, 0, 1); G_STAGE(G_SB(0, 0), b2h0, voffB);
;       G_BAR; G_WAIT_L(0); G_MMA(0, 1, At, B1); G_BAR;
;       G_LDA(At, 0, 1); G_STAGE(G_SA(0, 0), a2h0, voffA);
;       G_BAR; G_WAIT_L(0); G_MMA(1, 0, At, B0); G_BAR; G_SCHED;
;       G_STAGE(G_SB(0, 1), b2h1, voffB);
;       G_WAIT_V(6); G_BAR; G_MMA(1, 1, At, B1); G_BAR;
;       G_LDB(B0, 1, 0); G_SCHED; G_LDA(At, 1, 0); G_STAGE(G_SA(0, 1), a2h1, voffA);
;       G_WAIT_L(8); G_BAR; G_WAIT_L(0); G_MMA(0, 0, At, B0); G_BAR; G_SCHED;
;       G_LDB(B1, 1, 1); G_STAGE(G_SB(1, 0), b2h0 + kstep, voffB);
;       G_BAR; G_WAIT_L(0); G_MMA(0, 1, At, B1); G_BAR;
;       G_LDA(At, 1, 1); G_STAGE(G_SA(1, 0), a2h0 + kstep, voffA);
;       G_BAR; G_WAIT_L(0); G_MMA(1, 0, At, B0); G_BAR; G_SCHED;
;       G_STAGE(G_SB(1, 1), b2h1 + kstep, voffB);
;       G_WAIT_V(6); G_BAR; G_MMA(1, 1, At, B1); G_BAR;
.LBB0_257:
	s_add_u32 s22, s38, 0xfff80080
	s_addc_u32 s35, s39, -1
	s_add_u32 s42, s30, 0xfffe0000
	s_addc_u32 s43, s31, -1
	s_add_i32 s81, 0, 0x10000
	v_add_u32_e32 v0, s81, v149
	ds_read_b128 v[136:139], v0
	ds_read_b128 v[140:143], v0 offset:1024
	ds_read_b128 v[154:157], v0 offset:2048
	ds_read_b128 v[164:167], v0 offset:3072
	s_cmp_eq_u32 s34, 28
	s_cselect_b32 s45, s9, s35
	s_cselect_b32 s44, s8, s22
	s_cselect_b32 s69, s41, s43
	s_cselect_b32 s68, s40, s42
	v_mov_b32_e32 v0, v144
	s_cselect_b32 s43, s29, s31
	s_cselect_b32 s42, s28, s30
	s_add_u32 s94, s44, 0x80000
	ds_read_b128 v[168:171], v153
	ds_read_b128 v[172:175], v153 offset:1024
	ds_read_b128 v[176:179], v153 offset:2048
	ds_read_b128 v[184:187], v153 offset:3072
	ds_read_b128 v[190:193], v153 offset:4096
	ds_read_b128 v[194:197], v153 offset:5120
	ds_read_b128 v[198:201], v153 offset:6144
	ds_read_b128 v[202:205], v153 offset:7168
	s_addc_u32 s95, s45, 0
	s_add_i32 m0, s18, 0xc000
	s_nop 0
	global_load_lds_dwordx4 v0, s[38:39]
	v_mov_b32_e32 v0, v146
	s_add_i32 m0, s18, 0xe000
	s_nop 0
	global_load_lds_dwordx4 v0, s[38:39]
	s_waitcnt lgkmcnt(8)
	s_barrier
	s_waitcnt lgkmcnt(0)
	s_setprio 1
	s_waitcnt lgkmcnt(0)
	v_mfma_f32_16x16x32_bf16 v[130:133], v[136:139], v[168:171], v[130:133]
	v_mfma_f32_16x16x32_bf16 v[126:129], v[154:157], v[168:171], v[126:129]
	v_mfma_f32_16x16x32_bf16 v[114:117], v[136:139], v[176:179], v[114:117]
	v_mfma_f32_16x16x32_bf16 v[110:113], v[154:157], v[176:179], v[110:113]
	v_mfma_f32_16x16x32_bf16 v[98:101], v[136:139], v[190:193], v[98:101]
	v_mfma_f32_16x16x32_bf16 v[94:97], v[154:157], v[190:193], v[94:97]
	v_mfma_f32_16x16x32_bf16 v[82:85], v[136:139], v[198:201], v[82:85]
	v_mfma_f32_16x16x32_bf16 v[76:79], v[154:157], v[198:201], v[76:79]
	v_mfma_f32_16x16x32_bf16 v[130:133], v[140:143], v[172:175], v[130:133]
	v_mfma_f32_16x16x32_bf16 v[126:129], v[164:167], v[172:175], v[126:129]
	v_mfma_f32_16x16x32_bf16 v[114:117], v[140:143], v[184:187], v[114:117]
	v_mfma_f32_16x16x32_bf16 v[110:113], v[164:167], v[184:187], v[110:113]
	v_mfma_f32_16x16x32_bf16 v[98:101], v[140:143], v[194:197], v[98:101]
	v_mfma_f32_16x16x32_bf16 v[94:97], v[164:167], v[194:197], v[94:97]
	v_mfma_f32_16x16x32_bf16 v[82:85], v[140:143], v[202:205], v[82:85]
	v_mfma_f32_16x16x32_bf16 v[76:79], v[164:167], v[202:205], v[76:79]
	s_setprio 0
	s_barrier
	s_add_i32 s22, 0, 0x14000
	v_add_u32_e32 v0, s22, v149
	ds_read_b128 v[206:209], v0
	ds_read_b128 v[210:213], v0 offset:1024
	ds_read_b128 v[214:217], v0 offset:2048
	ds_read_b128 v[218:221], v0 offset:3072
	v_mov_b32_e32 v0, v145
	s_add_i32 s35, s81, s13
	s_mov_b32 m0, s35
	s_nop 0
	global_load_lds_dwordx4 v0, s[68:69]
	v_mov_b32_e32 v0, v147
	s_add_i32 m0, s35, 0x2000
	s_nop 0
	global_load_lds_dwordx4 v0, s[68:69]
	s_barrier
	s_waitcnt lgkmcnt(0)
	s_setprio 1
	s_waitcnt lgkmcnt(0)
	v_mfma_f32_16x16x32_bf16 v[122:125], v[206:209], v[168:171], v[122:125]
	v_mfma_f32_16x16x32_bf16 v[118:121], v[214:217], v[168:171], v[118:121]
	v_mfma_f32_16x16x32_bf16 v[106:109], v[206:209], v[176:179], v[106:109]
	v_mfma_f32_16x16x32_bf16 v[102:105], v[214:217], v[176:179], v[102:105]
	v_mfma_f32_16x16x32_bf16 v[90:93], v[206:209], v[190:193], v[90:93]
	v_mfma_f32_16x16x32_bf16 v[86:89], v[214:217], v[190:193], v[86:89]
	v_mfma_f32_16x16x32_bf16 v[72:75], v[206:209], v[198:201], v[72:75]
	v_mfma_f32_16x16x32_bf16 v[68:71], v[214:217], v[198:201], v[68:71]
	v_mfma_f32_16x16x32_bf16 v[122:125], v[210:213], v[172:175], v[122:125]
	v_mfma_f32_16x16x32_bf16 v[118:121], v[218:221], v[172:175], v[118:121]
	v_mfma_f32_16x16x32_bf16 v[106:109], v[210:213], v[184:187], v[106:109]
	v_mfma_f32_16x16x32_bf16 v[102:105], v[218:221], v[184:187], v[102:105]
	v_mfma_f32_16x16x32_bf16 v[90:93], v[210:213], v[194:197], v[90:93]
	v_mfma_f32_16x16x32_bf16 v[86:89], v[218:221], v[194:197], v[86:89]
	v_mfma_f32_16x16x32_bf16 v[72:75], v[210:213], v[202:205], v[72:75]
	v_mfma_f32_16x16x32_bf16 v[68:71], v[218:221], v[202:205], v[68:71]
	s_setprio 0
	v_mov_b32_e32 v0, v144
	s_mov_b32 m0, s18
	s_barrier
	ds_read_b128 v[168:171], v153 offset:16384
	ds_read_b128 v[172:175], v153 offset:17408
	ds_read_b128 v[176:179], v153 offset:18432
	ds_read_b128 v[184:187], v153 offset:19456
	ds_read_b128 v[190:193], v153 offset:20480
	ds_read_b128 v[194:197], v153 offset:21504
	ds_read_b128 v[198:201], v153 offset:22528
	ds_read_b128 v[202:205], v153 offset:23552
	s_nop 0
	global_load_lds_dwordx4 v0, s[44:45]
	v_mov_b32_e32 v0, v146
	s_mov_b32 m0, s19
	s_nop 0
	global_load_lds_dwordx4 v0, s[44:45]
	s_barrier
	s_waitcnt lgkmcnt(0)
	s_setprio 1
	s_waitcnt lgkmcnt(0)
	v_mfma_f32_16x16x32_bf16 v[64:67], v[136:139], v[168:171], v[64:67]
	v_mfma_f32_16x16x32_bf16 v[60:63], v[154:157], v[168:171], v[60:63]
	v_mfma_f32_16x16x32_bf16 v[48:51], v[136:139], v[176:179], v[48:51]
	v_mfma_f32_16x16x32_bf16 v[44:47], v[154:157], v[176:179], v[44:47]
	v_mfma_f32_16x16x32_bf16 v[32:35], v[136:139], v[190:193], v[32:35]
	v_mfma_f32_16x16x32_bf16 v[28:31], v[154:157], v[190:193], v[28:31]
	v_mfma_f32_16x16x32_bf16 v[16:19], v[136:139], v[198:201], v[16:19]
	v_mfma_f32_16x16x32_bf16 v[12:15], v[154:157], v[198:201], v[12:15]
	v_mfma_f32_16x16x32_bf16 v[64:67], v[140:143], v[172:175], v[64:67]
	v_mfma_f32_16x16x32_bf16 v[60:63], v[164:167], v[172:175], v[60:63]
	v_mfma_f32_16x16x32_bf16 v[48:51], v[140:143], v[184:187], v[48:51]
	v_mfma_f32_16x16x32_bf16 v[44:47], v[164:167], v[184:187], v[44:47]
	v_mfma_f32_16x16x32_bf16 v[32:35], v[140:143], v[194:197], v[32:35]
	v_mfma_f32_16x16x32_bf16 v[28:31], v[164:167], v[194:197], v[28:31]
	v_mfma_f32_16x16x32_bf16 v[16:19], v[140:143], v[202:205], v[16:19]
	v_mfma_f32_16x16x32_bf16 v[12:15], v[164:167], v[202:205], v[12:15]
	s_setprio 0
	s_barrier
; #define G_STAGE(bufoff, gbase, voff) do { _Pragma("unroll") for (int _i = 0; _i < 2; ++_i) { unsigned _vo = (voff)[_i]; asm volatile("" : "+v"(_vo));   \
;     __builtin_amdgcn_global_load_lds((const unsigned*)((const char*)(gbase) + _vo), (LAS unsigned*)(lds + (bufoff) + ldsw + _i * 8192), 16, 0, 0); } } while (0)
; #define G_LDA(dst, b, h) do { _Pragma("unroll") for (int m = 0; m < 4; ++m) _Pragma("unroll") for (int k = 0; k < 2; ++k) dst[m][k] = *(const LAS bf16x8*)(lds + G_SA(b, h) + aoff + m * 2048 + k * 1024); } while (0)
; #define G_LDB(dst, b, h) do { _Pragma("unroll") for (int n = 0; n < 2; ++n) _Pragma("unroll") for (int k = 0; k < 2; ++k) dst[n][k] = *(const LAS bf16x8*)(lds + G_SB(b, h) + boff + n * 2048 + k * 1024); } while (0)
; #define G_MMA(ai, bj, At, Bt) do { __builtin_amdgcn_s_setprio(1); _Pragma("unroll") for (int m = 0; m < 4; ++m) _Pragma("unroll") for (int n = 0; n < 2; ++n) _Pragma("unroll") for (int k = 0; k < 2; ++k) \
;     acc[ai][bj][m][n] = __builtin_amdgcn_mfma_f32_16x16x32_bf16(Bt[n][k], At[m][k], acc[ai][bj][m][n], 0, 0, 0); __builtin_amdgcn_s_setprio(0); } while (0)
; #define G_WAIT_V(n) asm volatile("s_waitcnt vmcnt(" #n ")" ::: "memory")
; template <class Epi>
; __device__ __forceinline__ void gemm_phase(LAS unsigned char* lds, const int K, const unsigned lda_b, const unsigned ldb_b, const Map& M, const Epi& E) {
;     ...
;       G_LDB(B0, 0, 0); G_SCHED; G_LDA(At, 0, 0); G_STAGE(G_SA(1, 1), a1h1, voffA);
;       G_WAIT_L(8); G_BAR; G_WAIT_L(0); G_MMA(0, 0, At, B0); G_BAR; G_SCHED;
;       G_LDB(B1, 0, 1); G_STAGE(G_SB(0, 0), b2h0, voffB);
;       G_BAR; G_WAIT_L(0); G_MMA(0, 1, At, B1); G_BAR;
;       G_LDA(At, 0, 1); G_STAGE(G_SA(0, 0), a2h0, voffA);
;       G_BAR; G_WAIT_L(0); G_MMA(1, 0, At, B0); G_BAR; G_SCHED;
;       G_STAGE(G_SB(0, 1), b2h1, voffB);
;       G_WAIT_V(6); G_BAR; G_MMA(1, 1, At, B1); G_BAR;
;       G_LDB(B0, 1, 0); G_SCHED; G_LDA(At, 1, 0); G_STAGE(G_SA(0, 1), a2h1, voffA);
;       G_WAIT_L(8); G_BAR; G_WAIT_L(0); G_MMA(0, 0, At, B0); G_BAR; G_SCHED;
;       G_LDB(B1, 1, 1); G_STAGE(G_SB(1, 0), b2h0 + kstep, voffB);
;       G_BAR; G_WAIT_L(0); G_MMA(0, 1, At, B1); G_BAR;
;       G_LDA(At, 1, 1); G_STAGE(G_SA(1, 0), a2h0 + kstep, voffA);
;       G_BAR; G_WAIT_L(0); G_MMA(1, 0, At, B0); G_BAR; G_SCHED;
;       G_STAGE(G_SB(1, 1), b2h1 + kstep, voffB);
;       G_WAIT_V(6); G_BAR; G_MMA(1, 1, At, B1); G_BAR;
	v_mov_b32_e32 v0, v145
	s_add_i32 s22, s22, s13
	s_mov_b32 m0, s22
	s_nop 0
	global_load_lds_dwordx4 v0, s[42:43]
	v_mov_b32_e32 v0, v147
	s_add_i32 m0, s22, 0x2000
	s_nop 0
	global_load_lds_dwordx4 v0, s[42:43]
	s_waitcnt vmcnt(6)
	s_barrier
	s_setprio 1
	v_mfma_f32_16x16x32_bf16 v[56:59], v[206:209], v[168:171], v[56:59]
	v_mfma_f32_16x16x32_bf16 v[52:55], v[214:217], v[168:171], v[52:55]
	v_mfma_f32_16x16x32_bf16 v[40:43], v[206:209], v[176:179], v[40:43]
	v_mfma_f32_16x16x32_bf16 v[36:39], v[214:217], v[176:179], v[36:39]
	v_mfma_f32_16x16x32_bf16 v[24:27], v[206:209], v[190:193], v[24:27]
	v_mfma_f32_16x16x32_bf16 v[20:23], v[214:217], v[190:193], v[20:23]
	v_mfma_f32_16x16x32_bf16 v[8:11], v[206:209], v[198:201], v[8:11]
	v_mfma_f32_16x16x32_bf16 v[4:7], v[214:217], v[198:201], v[4:7]
	v_mfma_f32_16x16x32_bf16 v[56:59], v[210:213], v[172:175], v[56:59]
	v_mfma_f32_16x16x32_bf16 v[52:55], v[218:221], v[172:175], v[52:55]
	v_mfma_f32_16x16x32_bf16 v[40:43], v[210:213], v[184:187], v[40:43]
	v_mfma_f32_16x16x32_bf16 v[36:39], v[218:221], v[184:187], v[36:39]
	v_mfma_f32_16x16x32_bf16 v[24:27], v[210:213], v[194:197], v[24:27]
	v_mfma_f32_16x16x32_bf16 v[20:23], v[218:221], v[194:197], v[20:23]
	v_mfma_f32_16x16x32_bf16 v[8:11], v[210:213], v[202:205], v[8:11]
	v_mfma_f32_16x16x32_bf16 v[4:7], v[218:221], v[202:205], v[4:7]
	s_setprio 0
	s_add_i32 s22, 0, 0x18000
	v_add_u32_e32 v0, s22, v149
	s_barrier
	ds_read_b128 v[136:139], v0
	ds_read_b128 v[140:143], v0 offset:1024
	ds_read_b128 v[154:157], v0 offset:2048
	ds_read_b128 v[164:167], v0 offset:3072
	v_mov_b32_e32 v0, v144
	s_mov_b32 m0, s46
	ds_read_b128 v[168:171], v153 offset:32768
	ds_read_b128 v[172:175], v153 offset:33792
	ds_read_b128 v[176:179], v153 offset:34816
	ds_read_b128 v[184:187], v153 offset:35840
	ds_read_b128 v[190:193], v153 offset:36864
	ds_read_b128 v[194:197], v153 offset:37888
	ds_read_b128 v[198:201], v153 offset:38912
	ds_read_b128 v[202:205], v153 offset:39936
	s_nop 0
	global_load_lds_dwordx4 v0, s[94:95]
	v_mov_b32_e32 v0, v146
	s_mov_b32 m0, s47
	s_nop 0
	global_load_lds_dwordx4 v0, s[94:95]
	s_waitcnt lgkmcnt(8)
	s_barrier
	s_waitcnt lgkmcnt(0)
	s_setprio 1
	s_waitcnt lgkmcnt(0)
	v_mfma_f32_16x16x32_bf16 v[130:133], v[136:139], v[168:171], v[130:133]
	v_mfma_f32_16x16x32_bf16 v[126:129], v[154:157], v[168:171], v[126:129]
	v_mfma_f32_16x16x32_bf16 v[114:117], v[136:139], v[176:179], v[114:117]
	v_mfma_f32_16x16x32_bf16 v[110:113], v[154:157], v[176:179], v[110:113]
	v_mfma_f32_16x16x32_bf16 v[98:101], v[136:139], v[190:193], v[98:101]
	v_mfma_f32_16x16x32_bf16 v[94:97], v[154:157], v[190:193], v[94:97]
	v_mfma_f32_16x16x32_bf16 v[82:85], v[136:139], v[198:201], v[82:85]
	v_mfma_f32_16x16x32_bf16 v[76:79], v[154:157], v[198:201], v[76:79]
	v_mfma_f32_16x16x32_bf16 v[130:133], v[140:143], v[172:175], v[130:133]
	v_mfma_f32_16x16x32_bf16 v[126:129], v[164:167], v[172:175], v[126:129]
	v_mfma_f32_16x16x32_bf16 v[114:117], v[140:143], v[184:187], v[114:117]
	v_mfma_f32_16x16x32_bf16 v[110:113], v[164:167], v[184:187], v[110:113]
	v_mfma_f32_16x16x32_bf16 v[98:101], v[140:143], v[194:197], v[98:101]
	v_mfma_f32_16x16x32_bf16 v[94:97], v[164:167], v[194:197], v[94:97]
	v_mfma_f32_16x16x32_bf16 v[82:85], v[140:143], v[202:205], v[82:85]
	v_mfma_f32_16x16x32_bf16 v[76:79], v[164:167], v[202:205], v[76:79]
	s_setprio 0
	s_barrier
	s_add_i32 s35, 0, 0x1c000
	v_add_u32_e32 v0, s35, v149
	v_mov_b32_e32 v80, v145
	ds_read_b128 v[206:209], v0
	ds_read_b128 v[210:213], v0 offset:1024
	ds_read_b128 v[214:217], v0 offset:2048
	ds_read_b128 v[218:221], v0 offset:3072
	s_add_i32 s22, s22, s13
	s_add_i32 m0, s22, 0xffffff80
	v_mov_b32_e32 v80, v147
	global_load_lds_dwordx4 v145, s[68:69] offset:128
	s_add_i32 m0, s22, 0x1f80
	s_nop 0
	global_load_lds_dwordx4 v147, s[68:69] offset:128
	s_barrier
	s_waitcnt lgkmcnt(0)
	s_setprio 1
	s_waitcnt lgkmcnt(0)
	v_mfma_f32_16x16x32_bf16 v[122:125], v[206:209], v[168:171], v[122:125]
	v_mfma_f32_16x16x32_bf16 v[118:121], v[214:217], v[168:171], v[118:121]
	v_mfma_f32_16x16x32_bf16 v[106:109], v[206:209], v[176:179], v[106:109]
	v_mfma_f32_16x16x32_bf16 v[102:105], v[214:217], v[176:179], v[102:105]
	v_mfma_f32_16x16x32_bf16 v[90:93], v[206:209], v[190:193], v[90:93]
	v_mfma_f32_16x16x32_bf16 v[86:89], v[214:217], v[190:193], v[86:89]
	v_mfma_f32_16x16x32_bf16 v[72:75], v[206:209], v[198:201], v[72:75]
	v_mfma_f32_16x16x32_bf16 v[68:71], v[214:217], v[198:201], v[68:71]
	v_mfma_f32_16x16x32_bf16 v[122:125], v[210:213], v[172:175], v[122:125]
	v_mfma_f32_16x16x32_bf16 v[118:121], v[218:221], v[172:175], v[118:121]
	v_mfma_f32_16x16x32_bf16 v[106:109], v[210:213], v[184:187], v[106:109]
	v_mfma_f32_16x16x32_bf16 v[102:105], v[218:221], v[184:187], v[102:105]
	v_mfma_f32_16x16x32_bf16 v[90:93], v[210:213], v[194:197], v[90:93]
	v_mfma_f32_16x16x32_bf16 v[86:89], v[218:221], v[194:197], v[86:89]
	v_mfma_f32_16x16x32_bf16 v[72:75], v[210:213], v[202:205], v[72:75]
	v_mfma_f32_16x16x32_bf16 v[68:71], v[218:221], v[202:205], v[68:71]
	s_setprio 0
	v_mov_b32_e32 v80, v144
	s_barrier
	ds_read_b128 v[168:171], v153 offset:49152
	ds_read_b128 v[172:175], v153 offset:50176
	ds_read_b128 v[176:179], v153 offset:51200
	ds_read_b128 v[184:187], v153 offset:52224
	ds_read_b128 v[190:193], v153 offset:53248
	ds_read_b128 v[194:197], v153 offset:54272
	ds_read_b128 v[198:201], v153 offset:55296
	ds_read_b128 v[202:205], v153 offset:56320
	s_add_i32 m0, s48, 0xffffff80
	v_mov_b32_e32 v80, v146
	global_load_lds_dwordx4 v144, s[44:45] offset:128
	s_add_i32 m0, s49, 0xffffff80
	s_nop 0
	global_load_lds_dwordx4 v146, s[44:45] offset:128
	s_barrier
; __device__ __forceinline__ unsigned cvt_pk_bf16(float lo, float hi) { unsigned r; asm("v_cvt_pk_bf16_f32 %0, %1, %2" : "=v"(r) : "v"(lo), "v"(hi)); return r; }
; __device__ __forceinline__ float rinv_of(unsigned long long ss) { return rsqrtf((float)ss * (1.f / 16777216.f) * (1.f / DM) + 1e-6f); }
; #define G_BAR __builtin_amdgcn_s_barrier()
;   __device__ __forceinline__ void operator()(const f32x4 (&acc)[2][2][4][2], const Unit& u, const EpiCtx& x_, int wr, int wc, int fr, int fq) const {
;     ...
;     for (int ai = 0; ai < 2; ++ai)
; #pragma unroll
;       for (int m = 0; m < 4; ++m) {
;         const int row = (u.r0 + (ai ? x_.rdelta : 0)) + wr * 64 + m * 16 + fr;
;         bf16_t* rowp = (bf16_t*)u.C + (size_t)row * x_.ldc;
;         const float rs = (SCALE == 1) ? rinv_of(x_.ss[row]) : 1.f;
; #pragma unroll
;         for (int bj = 0; bj < 2; ++bj) {
;           const int cb = PERM ? (u.c0 + wc * 64 + bj * 32) : (u.c0 + bj * 128) + wc * 32;
;           f32x4 v0 = acc[ai][bj][m][0], v1 = acc[ai][bj][m][1];
;           if (SCALE == 1) { v0 *= rs; v1 *= rs; }
;           if (SCALE == 2) { v0 *= cs[bj][0]; v1 *= cs[bj][1]; }
;           if (PERM) {
;             uint4 o; o.x = cvt_pk_bf16(v0[0], v0[1]); o.y = cvt_pk_bf16(v0[2], v0[3]); o.z = cvt_pk_bf16(v1[0], v1[1]); o.w = cvt_pk_bf16(v1[2], v1[3]);
;             *(uint4*)(rowp + cb + 8 * fq) = o;
;           } else {
;             uint2 o0, o1; o0.x = cvt_pk_bf16(v0[0], v0[1]); o0.y = cvt_pk_bf16(v0[2], v0[3]); o1.x = cvt_pk_bf16(v1[0], v1[1]); o1.y = cvt_pk_bf16(v1[2], v1[3]);
;             *(uint2*)(rowp + cb + 4 * fq) = o0; *(uint2*)(rowp + cb + 16 + 4 * fq) = o1;
; template <class Epi>
; __device__ __forceinline__ void gemm_phase(LAS unsigned char* lds, const int K, const unsigned lda_b, const unsigned ldb_b, const Map& M, const Epi& E) {
;     ...
;       G_WAIT_V(6); G_BAR; G_MMA(1, 1, At, B1); G_BAR;
;       G_LDB(B0, 1, 0); G_SCHED; G_LDA(At, 1, 0); G_STAGE(G_SA(0, 1), a2h1, voffA);
;       G_WAIT_L(8); G_BAR; G_WAIT_L(0); G_MMA(0, 0, At, B0); G_BAR; G_SCHED;
;       G_LDB(B1, 1, 1); G_STAGE(G_SB(1, 0), b2h0 + kstep, voffB);
;       G_BAR; G_WAIT_L(0); G_MMA(0, 1, At, B1); G_BAR;
;       G_LDA(At, 1, 1); G_STAGE(G_SA(1, 0), a2h0 + kstep, voffA);
;       G_BAR; G_WAIT_L(0); G_MMA(1, 0, At, B0); G_BAR; G_SCHED;
;       G_STAGE(G_SB(1, 1), b2h1 + kstep, voffB);
;       G_WAIT_V(6); G_BAR; G_MMA(1, 1, At, B1); G_BAR;
	s_waitcnt lgkmcnt(0)
	s_setprio 1
	s_waitcnt lgkmcnt(0)
	v_mfma_f32_16x16x32_bf16 v[64:67], v[136:139], v[168:171], v[64:67]
	v_mfma_f32_16x16x32_bf16 v[60:63], v[154:157], v[168:171], v[60:63]
	v_mfma_f32_16x16x32_bf16 v[48:51], v[136:139], v[176:179], v[48:51]
	v_mfma_f32_16x16x32_bf16 v[44:47], v[154:157], v[176:179], v[44:47]
	v_mfma_f32_16x16x32_bf16 v[32:35], v[136:139], v[190:193], v[32:35]
	v_mfma_f32_16x16x32_bf16 v[28:31], v[154:157], v[190:193], v[28:31]
	v_mfma_f32_16x16x32_bf16 v[16:19], v[136:139], v[198:201], v[16:19]
	v_mfma_f32_16x16x32_bf16 v[12:15], v[154:157], v[198:201], v[12:15]
	v_mfma_f32_16x16x32_bf16 v[64:67], v[140:143], v[172:175], v[64:67]
	v_mfma_f32_16x16x32_bf16 v[60:63], v[164:167], v[172:175], v[60:63]
	v_mfma_f32_16x16x32_bf16 v[48:51], v[140:143], v[184:187], v[48:51]
	v_mfma_f32_16x16x32_bf16 v[44:47], v[164:167], v[184:187], v[44:47]
	v_mfma_f32_16x16x32_bf16 v[32:35], v[140:143], v[194:197], v[32:35]
	v_mfma_f32_16x16x32_bf16 v[28:31], v[164:167], v[194:197], v[28:31]
	v_mfma_f32_16x16x32_bf16 v[16:19], v[140:143], v[202:205], v[16:19]
	v_mfma_f32_16x16x32_bf16 v[12:15], v[164:167], v[202:205], v[12:15]
	s_setprio 0
	s_barrier
	v_mov_b32_e32 v80, v145
	s_add_i32 s22, s35, s13
	s_add_i32 m0, s22, 0xffffff80
	v_mov_b32_e32 v80, v147
	global_load_lds_dwordx4 v145, s[42:43] offset:128
	s_add_i32 m0, s22, 0x1f80
	s_nop 0
	global_load_lds_dwordx4 v147, s[42:43] offset:128
	s_waitcnt vmcnt(6)
	s_barrier
	s_setprio 1
	v_mfma_f32_16x16x32_bf16 v[56:59], v[206:209], v[168:171], v[56:59]
	v_mfma_f32_16x16x32_bf16 v[52:55], v[214:217], v[168:171], v[52:55]
	v_mfma_f32_16x16x32_bf16 v[40:43], v[206:209], v[176:179], v[40:43]
	v_mfma_f32_16x16x32_bf16 v[36:39], v[214:217], v[176:179], v[36:39]
	v_mfma_f32_16x16x32_bf16 v[24:27], v[206:209], v[190:193], v[24:27]
	v_mfma_f32_16x16x32_bf16 v[20:23], v[214:217], v[190:193], v[20:23]
	v_mfma_f32_16x16x32_bf16 v[8:11], v[206:209], v[198:201], v[8:11]
	v_mfma_f32_16x16x32_bf16 v[4:7], v[214:217], v[198:201], v[4:7]
	v_mfma_f32_16x16x32_bf16 v[56:59], v[210:213], v[172:175], v[56:59]
	v_mfma_f32_16x16x32_bf16 v[52:55], v[218:221], v[172:175], v[52:55]
	v_mfma_f32_16x16x32_bf16 v[40:43], v[210:213], v[184:187], v[40:43]
	v_mfma_f32_16x16x32_bf16 v[36:39], v[218:221], v[184:187], v[36:39]
	v_mfma_f32_16x16x32_bf16 v[24:27], v[210:213], v[194:197], v[24:27]
	v_mfma_f32_16x16x32_bf16 v[20:23], v[218:221], v[194:197], v[20:23]
	v_mfma_f32_16x16x32_bf16 v[8:11], v[210:213], v[202:205], v[8:11]
	v_mfma_f32_16x16x32_bf16 v[4:7], v[218:221], v[202:205], v[4:7]
	s_setprio 0
	s_add_i32 s34, s34, 2
	s_add_u32 s30, s30, 0x100
	s_addc_u32 s31, s31, 0
	s_add_u32 s38, s38, 0x100
	s_addc_u32 s39, s39, 0
	s_cmp_gt_u32 s34, 29
	s_barrier
	s_cbranch_scc0 .LBB0_257
	s_nop 1
	v_add_u32_e32 v184, s76, v148
	v_ashrrev_i32_e32 v185, 31, v184
	v_lshl_add_u64 v[186:187], v[184:185], 3, s[4:5]
	global_load_dwordx2 v[164:165], v[186:187], off
	v_add_u32_e32 v190, s76, v150
	v_ashrrev_i32_e32 v191, 31, v190
	v_lshl_add_u64 v[192:193], v[190:191], 3, s[4:5]
	global_load_dwordx2 v[166:167], v[192:193], off
	v_add_u32_e32 v194, s76, v151
	v_ashrrev_i32_e32 v195, 31, v194
	v_lshl_add_u64 v[196:197], v[194:195], 3, s[4:5]
	global_load_dwordx2 v[168:169], v[196:197], off
	v_add_u32_e32 v198, s76, v152
	v_ashrrev_i32_e32 v199, 31, v198
	v_lshl_add_u64 v[200:201], v[198:199], 3, s[4:5]
	global_load_dwordx2 v[170:171], v[200:201], off
	global_load_dwordx2 v[172:173], v[186:187], off offset:1024
	global_load_dwordx2 v[174:175], v[192:193], off offset:1024
	global_load_dwordx2 v[176:177], v[196:197], off offset:1024
	global_load_dwordx2 v[178:179], v[200:201], off offset:1024
	v_add_u32_e32 v138, s76, v148
	v_ashrrev_i32_e32 v139, 31, v138
	v_lshl_add_u64 v[140:141], v[138:139], 3, s[4:5]
	s_nop 0
	v_lshlrev_b64 v[154:155], 13, v[138:139]
	s_add_i32 s28, s79, s61
	v_mov_b32_e32 v135, v81
	s_add_i32 s30, s66, s79
	s_ashr_i32 s29, s28, 31
	v_add_u32_e32 v136, s76, v150
	s_ashr_i32 s31, s30, 31
	s_lshl_b64 s[38:39], s[28:29], 1
	v_ashrrev_i32_e32 v137, 31, v136
	s_lshl_b64 s[42:43], s[30:31], 1
	v_lshl_add_u64 v[142:143], v[136:137], 3, s[4:5]
	v_readfirstlane_b32 s79, v3
	s_mov_b64 s[44:45], s[8:9]
	s_mov_b64 s[68:69], s[40:41]
	s_cmp_eq_u32 s75, s67
	s_waitcnt lgkmcnt(0)
	s_waitcnt vmcnt(7)
	v_ffbh_u32_e32 v80, v165
	v_min_u32_e32 v80, 32, v80
	v_lshlrev_b64 v[0:1], v80, v[164:165]
	v_min_u32_e32 v0, 1, v0
	v_or_b32_e32 v0, v1, v0
	v_cvt_f32_u32_e32 v139, v0
	v_sub_u32_e32 v80, 32, v80
	v_lshl_add_u64 v[0:1], s[2:3], 0, v[154:155]
	v_lshl_add_u64 v[0:1], v[0:1], 0, v[134:135]
	v_ldexp_f32 v80, v139, v80
	v_mul_f32_e32 v80, 0x33800000, v80
	v_fmamk_f32 v80, v80, 0x3a000000, v234
	v_mul_f32_e32 v139, 0x4b800000, v80
	v_cmp_gt_f32_e32 vcc, s50, v80
	v_lshl_add_u64 v[154:155], v[0:1], 0, s[38:39]
	v_lshl_add_u64 v[0:1], v[0:1], 0, s[42:43]
	v_cndmask_b32_e32 v80, v80, v139, vcc
	v_rsq_f32_e32 v80, v80
	s_nop 0
	v_mul_f32_e32 v139, 0x45800000, v80
	v_cndmask_b32_e32 v80, v80, v139, vcc
	v_pk_mul_f32 v[132:133], v[132:133], v[80:81] op_sel_hi:[1,0]
	v_pk_mul_f32 v[130:131], v[130:131], v[80:81] op_sel_hi:[1,0]
	v_pk_mul_f32 v[128:129], v[128:129], v[80:81] op_sel_hi:[1,0]
	v_pk_mul_f32 v[126:127], v[126:127], v[80:81] op_sel_hi:[1,0]
	v_pk_mul_f32 v[124:125], v[124:125], v[80:81] op_sel_hi:[1,0]
	v_pk_mul_f32 v[122:123], v[122:123], v[80:81] op_sel_hi:[1,0]
	v_pk_mul_f32 v[156:157], v[120:121], v[80:81] op_sel_hi:[1,0]
	v_pk_mul_f32 v[160:161], v[118:119], v[80:81] op_sel_hi:[1,0]
	v_cvt_pk_bf16_f32 v118, v130, v131
	v_cvt_pk_bf16_f32 v119, v132, v133
	v_cvt_pk_bf16_f32 v120, v126, v127
	v_cvt_pk_bf16_f32 v121, v128, v129
	v_cvt_pk_bf16_f32 v122, v122, v123
	v_cvt_pk_bf16_f32 v123, v124, v125
	s_nop 0
	v_cvt_pk_bf16_f32 v124, v160, v161
	v_cvt_pk_bf16_f32 v125, v156, v157
	global_store_dwordx4 v[154:155], v[118:121], off nt
	global_store_dwordx4 v[0:1], v[122:125], off nt
	s_nop 0
	v_add_u32_e32 v118, s76, v151
	v_lshlrev_b64 v[122:123], 13, v[136:137]
	v_ashrrev_i32_e32 v119, 31, v118
	v_lshl_add_u64 v[120:121], v[118:119], 3, s[4:5]
	s_waitcnt lgkmcnt(0)
; __device__ __forceinline__ unsigned cvt_pk_bf16(float lo, float hi) { unsigned r; asm("v_cvt_pk_bf16_f32 %0, %1, %2" : "=v"(r) : "v"(lo), "v"(hi)); return r; }
; __device__ __forceinline__ float rinv_of(unsigned long long ss) { return rsqrtf((float)ss * (1.f / 16777216.f) * (1.f / DM) + 1e-6f); }
;   __device__ __forceinline__ void operator()(const f32x4 (&acc)[2][2][4][2], const Unit& u, const EpiCtx& x_, int wr, int wc, int fr, int fq) const {
;     ...
;     for (int ai = 0; ai < 2; ++ai)
; #pragma unroll
;       for (int m = 0; m < 4; ++m) {
;         const int row = (u.r0 + (ai ? x_.rdelta : 0)) + wr * 64 + m * 16 + fr;
;         bf16_t* rowp = (bf16_t*)u.C + (size_t)row * x_.ldc;
;         const float rs = (SCALE == 1) ? rinv_of(x_.ss[row]) : 1.f;
; #pragma unroll
;         for (int bj = 0; bj < 2; ++bj) {
;           const int cb = PERM ? (u.c0 + wc * 64 + bj * 32) : (u.c0 + bj * 128) + wc * 32;
;           f32x4 v0 = acc[ai][bj][m][0], v1 = acc[ai][bj][m][1];
;           if (SCALE == 1) { v0 *= rs; v1 *= rs; }
;           if (SCALE == 2) { v0 *= cs[bj][0]; v1 *= cs[bj][1]; }
;           if (PERM) {
;             uint4 o; o.x = cvt_pk_bf16(v0[0], v0[1]); o.y = cvt_pk_bf16(v0[2], v0[3]); o.z = cvt_pk_bf16(v1[0], v1[1]); o.w = cvt_pk_bf16(v1[2], v1[3]);
;             *(uint4*)(rowp + cb + 8 * fq) = o;
;           } else {
;             uint2 o0, o1; o0.x = cvt_pk_bf16(v0[0], v0[1]); o0.y = cvt_pk_bf16(v0[2], v0[3]); o1.x = cvt_pk_bf16(v1[0], v1[1]); o1.y = cvt_pk_bf16(v1[2], v1[3]);
;             *(uint2*)(rowp + cb + 4 * fq) = o0; *(uint2*)(rowp + cb + 16 + 4 * fq) = o1;
	s_waitcnt vmcnt(8)
	v_ffbh_u32_e32 v80, v167
	v_min_u32_e32 v80, 32, v80
	v_lshlrev_b64 v[0:1], v80, v[166:167]
	v_min_u32_e32 v0, 1, v0
	v_or_b32_e32 v0, v1, v0
	v_cvt_f32_u32_e32 v124, v0
	v_sub_u32_e32 v80, 32, v80
	v_lshl_add_u64 v[0:1], s[2:3], 0, v[122:123]
	v_lshl_add_u64 v[0:1], v[0:1], 0, v[134:135]
	v_ldexp_f32 v80, v124, v80
	v_mul_f32_e32 v80, 0x33800000, v80
	v_fmamk_f32 v80, v80, 0x3a000000, v234
	v_mul_f32_e32 v122, 0x4b800000, v80
	v_cmp_gt_f32_e32 vcc, s50, v80
	s_nop 1
	v_cndmask_b32_e32 v80, v80, v122, vcc
	v_rsq_f32_e32 v80, v80
	v_lshl_add_u64 v[122:123], v[0:1], 0, s[38:39]
	v_lshl_add_u64 v[0:1], v[0:1], 0, s[42:43]
	v_mul_f32_e32 v124, 0x45800000, v80
	v_cndmask_b32_e32 v80, v80, v124, vcc
	v_pk_mul_f32 v[116:117], v[116:117], v[80:81] op_sel_hi:[1,0]
	v_pk_mul_f32 v[114:115], v[114:115], v[80:81] op_sel_hi:[1,0]
	v_pk_mul_f32 v[112:113], v[112:113], v[80:81] op_sel_hi:[1,0]
	v_pk_mul_f32 v[110:111], v[110:111], v[80:81] op_sel_hi:[1,0]
	v_pk_mul_f32 v[108:109], v[108:109], v[80:81] op_sel_hi:[1,0]
	v_pk_mul_f32 v[106:107], v[106:107], v[80:81] op_sel_hi:[1,0]
	v_pk_mul_f32 v[124:125], v[104:105], v[80:81] op_sel_hi:[1,0]
	v_pk_mul_f32 v[126:127], v[102:103], v[80:81] op_sel_hi:[1,0]
	v_cvt_pk_bf16_f32 v102, v114, v115
	v_cvt_pk_bf16_f32 v103, v116, v117
	v_cvt_pk_bf16_f32 v104, v110, v111
	v_cvt_pk_bf16_f32 v105, v112, v113
	v_cvt_pk_bf16_f32 v106, v106, v107
	v_cvt_pk_bf16_f32 v107, v108, v109
	s_nop 0
	v_cvt_pk_bf16_f32 v108, v126, v127
	v_cvt_pk_bf16_f32 v109, v124, v125
	global_store_dwordx4 v[122:123], v[102:105], off nt
	global_store_dwordx4 v[0:1], v[106:109], off nt
	s_nop 0
	v_lshlrev_b64 v[104:105], 13, v[118:119]
	v_lshl_add_u64 v[104:105], s[2:3], 0, v[104:105]
	v_add_u32_e32 v0, s76, v152
	v_lshl_add_u64 v[104:105], v[104:105], 0, v[134:135]
	v_ashrrev_i32_e32 v1, 31, v0
	v_readfirstlane_b32 s76, v2
	s_waitcnt lgkmcnt(0)
	s_waitcnt vmcnt(9)
	v_ffbh_u32_e32 v80, v169
	v_min_u32_e32 v80, 32, v80
	v_lshlrev_b64 v[102:103], v80, v[168:169]
	v_min_u32_e32 v102, 1, v102
	v_or_b32_e32 v102, v103, v102
	v_cvt_f32_u32_e32 v106, v102
	v_sub_u32_e32 v80, 32, v80
	v_lshl_add_u64 v[102:103], v[0:1], 3, s[4:5]
	v_ldexp_f32 v80, v106, v80
	v_mul_f32_e32 v80, 0x33800000, v80
	v_fmamk_f32 v80, v80, 0x3a000000, v234
	v_mul_f32_e32 v106, 0x4b800000, v80
	v_cmp_gt_f32_e32 vcc, s50, v80
	s_nop 1
	v_cndmask_b32_e32 v80, v80, v106, vcc
	v_rsq_f32_e32 v80, v80
	v_lshl_add_u64 v[106:107], v[104:105], 0, s[38:39]
	v_lshl_add_u64 v[104:105], v[104:105], 0, s[42:43]
	v_mul_f32_e32 v108, 0x45800000, v80
	v_cndmask_b32_e32 v80, v80, v108, vcc
	v_pk_mul_f32 v[100:101], v[100:101], v[80:81] op_sel_hi:[1,0]
	v_pk_mul_f32 v[98:99], v[98:99], v[80:81] op_sel_hi:[1,0]
	v_pk_mul_f32 v[96:97], v[96:97], v[80:81] op_sel_hi:[1,0]
	v_pk_mul_f32 v[94:95], v[94:95], v[80:81] op_sel_hi:[1,0]
	v_pk_mul_f32 v[92:93], v[92:93], v[80:81] op_sel_hi:[1,0]
	v_pk_mul_f32 v[90:91], v[90:91], v[80:81] op_sel_hi:[1,0]
	v_pk_mul_f32 v[108:109], v[88:89], v[80:81] op_sel_hi:[1,0]
	v_pk_mul_f32 v[110:111], v[86:87], v[80:81] op_sel_hi:[1,0]
	v_cvt_pk_bf16_f32 v86, v98, v99
	v_cvt_pk_bf16_f32 v87, v100, v101
	v_cvt_pk_bf16_f32 v88, v94, v95
	v_cvt_pk_bf16_f32 v89, v96, v97
	v_cvt_pk_bf16_f32 v90, v90, v91
	v_cvt_pk_bf16_f32 v91, v92, v93
	s_nop 0
	v_cvt_pk_bf16_f32 v92, v110, v111
	v_cvt_pk_bf16_f32 v93, v108, v109
	global_store_dwordx4 v[106:107], v[86:89], off nt
	global_store_dwordx4 v[104:105], v[90:93], off nt
	s_nop 0
	s_waitcnt lgkmcnt(0)
	s_waitcnt vmcnt(10)
	v_ffbh_u32_e32 v80, v171
	v_min_u32_e32 v80, 32, v80
	v_lshlrev_b64 v[86:87], v80, v[170:171]
	v_min_u32_e32 v86, 1, v86
	v_or_b32_e32 v86, v87, v86
	v_cvt_f32_u32_e32 v88, v86
	v_lshlrev_b64 v[86:87], 13, v[0:1]
	v_sub_u32_e32 v1, 32, v80
	v_lshl_add_u64 v[86:87], s[2:3], 0, v[86:87]
	v_ldexp_f32 v1, v88, v1
	v_mul_f32_e32 v1, 0x33800000, v1
	v_fmamk_f32 v1, v1, 0x3a000000, v234
	v_mul_f32_e32 v80, 0x4b800000, v1
	v_cmp_gt_f32_e32 vcc, s50, v1
	v_lshl_add_u64 v[86:87], v[86:87], 0, v[134:135]
	v_lshl_add_u64 v[88:89], v[86:87], 0, s[38:39]
	v_cndmask_b32_e32 v1, v1, v80, vcc
	v_rsq_f32_e32 v1, v1
	v_lshl_add_u64 v[86:87], v[86:87], 0, s[42:43]
	v_add_u32_e32 v0, 0x80, v0
	v_mul_f32_e32 v80, 0x45800000, v1
	v_cndmask_b32_e32 v80, v1, v80, vcc
	v_pk_mul_f32 v[84:85], v[84:85], v[80:81] op_sel_hi:[1,0]
	v_pk_mul_f32 v[82:83], v[82:83], v[80:81] op_sel_hi:[1,0]
	v_pk_mul_f32 v[78:79], v[78:79], v[80:81] op_sel_hi:[1,0]
	v_pk_mul_f32 v[76:77], v[76:77], v[80:81] op_sel_hi:[1,0]
	v_pk_mul_f32 v[74:75], v[74:75], v[80:81] op_sel_hi:[1,0]
	v_pk_mul_f32 v[72:73], v[72:73], v[80:81] op_sel_hi:[1,0]
	v_pk_mul_f32 v[90:91], v[70:71], v[80:81] op_sel_hi:[1,0]
	v_pk_mul_f32 v[92:93], v[68:69], v[80:81] op_sel_hi:[1,0]
	v_cvt_pk_bf16_f32 v68, v82, v83
	v_cvt_pk_bf16_f32 v69, v84, v85
	v_cvt_pk_bf16_f32 v70, v76, v77
	v_cvt_pk_bf16_f32 v71, v78, v79
	v_cvt_pk_bf16_f32 v72, v72, v73
	v_cvt_pk_bf16_f32 v73, v74, v75
	s_nop 0
	v_cvt_pk_bf16_f32 v74, v92, v93
	v_cvt_pk_bf16_f32 v75, v90, v91
	global_store_dwordx4 v[88:89], v[68:71], off nt
	global_store_dwordx4 v[86:87], v[72:75], off nt
	s_nop 0
	v_add_u32_e32 v70, 0x80, v138
	v_ashrrev_i32_e32 v71, 31, v70
	s_waitcnt lgkmcnt(0)
	s_waitcnt vmcnt(11)
; __device__ __forceinline__ unsigned cvt_pk_bf16(float lo, float hi) { unsigned r; asm("v_cvt_pk_bf16_f32 %0, %1, %2" : "=v"(r) : "v"(lo), "v"(hi)); return r; }
; __device__ __forceinline__ float rinv_of(unsigned long long ss) { return rsqrtf((float)ss * (1.f / 16777216.f) * (1.f / DM) + 1e-6f); }
; #define G_WAIT_V(n) asm volatile("s_waitcnt vmcnt(" #n ")" ::: "memory")
; #define G_BAR __builtin_amdgcn_s_barrier()
;   __device__ __forceinline__ void operator()(const f32x4 (&acc)[2][2][4][2], const Unit& u, const EpiCtx& x_, int wr, int wc, int fr, int fq) const {
;     ...
;     for (int ai = 0; ai < 2; ++ai)
; #pragma unroll
;       for (int m = 0; m < 4; ++m) {
;         const int row = (u.r0 + (ai ? x_.rdelta : 0)) + wr * 64 + m * 16 + fr;
;         bf16_t* rowp = (bf16_t*)u.C + (size_t)row * x_.ldc;
;         const float rs = (SCALE == 1) ? rinv_of(x_.ss[row]) : 1.f;
; #pragma unroll
;         for (int bj = 0; bj < 2; ++bj) {
;           const int cb = PERM ? (u.c0 + wc * 64 + bj * 32) : (u.c0 + bj * 128) + wc * 32;
;           f32x4 v0 = acc[ai][bj][m][0], v1 = acc[ai][bj][m][1];
;           if (SCALE == 1) { v0 *= rs; v1 *= rs; }
;           if (SCALE == 2) { v0 *= cs[bj][0]; v1 *= cs[bj][1]; }
;           if (PERM) {
;             uint4 o; o.x = cvt_pk_bf16(v0[0], v0[1]); o.y = cvt_pk_bf16(v0[2], v0[3]); o.z = cvt_pk_bf16(v1[0], v1[1]); o.w = cvt_pk_bf16(v1[2], v1[3]);
;             *(uint4*)(rowp + cb + 8 * fq) = o;
;           } else {
;             uint2 o0, o1; o0.x = cvt_pk_bf16(v0[0], v0[1]); o0.y = cvt_pk_bf16(v0[2], v0[3]); o1.x = cvt_pk_bf16(v1[0], v1[1]); o1.y = cvt_pk_bf16(v1[2], v1[3]);
;             *(uint2*)(rowp + cb + 4 * fq) = o0; *(uint2*)(rowp + cb + 16 + 4 * fq) = o1;
; template <class Epi>
; __device__ __forceinline__ void gemm_phase(LAS unsigned char* lds, const int K, const unsigned lda_b, const unsigned ldb_b, const Map& M, const Epi& E) {
;     ...
;     if (!has_next) break;
; #pragma unroll
;     for (int a = 0; a < 2; ++a)
; #pragma unroll
;       for (int b = 0; b < 2; ++b)
; #pragma unroll
;         for (int m = 0; m < 4; ++m)
; #pragma unroll
;           for (int n = 0; n < 2; ++n) acc[a][b][m][n] = (f32x4){0.f, 0.f, 0.f, 0.f};
;     cur = nxt; ++ui;
;   }
;   G_WAIT_V(0);
;   if (wr == 0) G_BAR;
	v_ffbh_u32_e32 v1, v173
	v_min_u32_e32 v1, 32, v1
	v_lshlrev_b64 v[68:69], v1, v[172:173]
	v_min_u32_e32 v68, 1, v68
	v_or_b32_e32 v68, v69, v68
	v_cvt_f32_u32_e32 v72, v68
	v_sub_u32_e32 v1, 32, v1
	v_lshlrev_b64 v[68:69], 13, v[70:71]
	v_lshl_add_u64 v[68:69], s[2:3], 0, v[68:69]
	v_ldexp_f32 v1, v72, v1
	v_mul_f32_e32 v1, 0x33800000, v1
	v_fmamk_f32 v1, v1, 0x3a000000, v234
	v_mul_f32_e32 v70, 0x4b800000, v1
	v_cmp_gt_f32_e32 vcc, s50, v1
	v_lshl_add_u64 v[68:69], v[68:69], 0, v[134:135]
	s_nop 0
	v_cndmask_b32_e32 v1, v1, v70, vcc
	v_rsq_f32_e32 v1, v1
	v_lshl_add_u64 v[70:71], v[68:69], 0, s[38:39]
	v_lshl_add_u64 v[68:69], v[68:69], 0, s[42:43]
	v_mul_f32_e32 v72, 0x45800000, v1
	v_cndmask_b32_e32 v72, v1, v72, vcc
	v_pk_mul_f32 v[66:67], v[66:67], v[72:73] op_sel_hi:[1,0]
	v_pk_mul_f32 v[64:65], v[64:65], v[72:73] op_sel_hi:[1,0]
	v_pk_mul_f32 v[62:63], v[62:63], v[72:73] op_sel_hi:[1,0]
	v_pk_mul_f32 v[60:61], v[60:61], v[72:73] op_sel_hi:[1,0]
	v_pk_mul_f32 v[58:59], v[58:59], v[72:73] op_sel_hi:[1,0]
	v_pk_mul_f32 v[56:57], v[56:57], v[72:73] op_sel_hi:[1,0]
	v_pk_mul_f32 v[74:75], v[54:55], v[72:73] op_sel_hi:[1,0]
	v_pk_mul_f32 v[72:73], v[52:53], v[72:73] op_sel_hi:[1,0]
	v_cvt_pk_bf16_f32 v52, v64, v65
	v_cvt_pk_bf16_f32 v53, v66, v67
	v_cvt_pk_bf16_f32 v54, v60, v61
	v_cvt_pk_bf16_f32 v55, v62, v63
	v_cvt_pk_bf16_f32 v56, v56, v57
	v_cvt_pk_bf16_f32 v57, v58, v59
	s_nop 0
	v_cvt_pk_bf16_f32 v58, v72, v73
	v_cvt_pk_bf16_f32 v59, v74, v75
	global_store_dwordx4 v[70:71], v[52:55], off nt
	global_store_dwordx4 v[68:69], v[56:59], off nt
	s_nop 0
	v_add_u32_e32 v54, 0x80, v136
	v_ashrrev_i32_e32 v55, 31, v54
	s_waitcnt lgkmcnt(0)
	s_waitcnt vmcnt(12)
	v_ffbh_u32_e32 v1, v175
	v_min_u32_e32 v1, 32, v1
	v_lshlrev_b64 v[52:53], v1, v[174:175]
	v_min_u32_e32 v52, 1, v52
	v_or_b32_e32 v52, v53, v52
	v_cvt_f32_u32_e32 v56, v52
	v_sub_u32_e32 v1, 32, v1
	v_lshlrev_b64 v[52:53], 13, v[54:55]
	v_lshl_add_u64 v[52:53], s[2:3], 0, v[52:53]
	v_ldexp_f32 v1, v56, v1
	v_mul_f32_e32 v1, 0x33800000, v1
	v_fmamk_f32 v1, v1, 0x3a000000, v234
	v_mul_f32_e32 v54, 0x4b800000, v1
	v_cmp_gt_f32_e32 vcc, s50, v1
	v_lshl_add_u64 v[52:53], v[52:53], 0, v[134:135]
	s_nop 0
	v_cndmask_b32_e32 v1, v1, v54, vcc
	v_rsq_f32_e32 v1, v1
	v_lshl_add_u64 v[54:55], v[52:53], 0, s[38:39]
	v_lshl_add_u64 v[52:53], v[52:53], 0, s[42:43]
	v_mul_f32_e32 v56, 0x45800000, v1
	v_cndmask_b32_e32 v56, v1, v56, vcc
	v_pk_mul_f32 v[50:51], v[50:51], v[56:57] op_sel_hi:[1,0]
	v_pk_mul_f32 v[48:49], v[48:49], v[56:57] op_sel_hi:[1,0]
	v_pk_mul_f32 v[46:47], v[46:47], v[56:57] op_sel_hi:[1,0]
	v_pk_mul_f32 v[44:45], v[44:45], v[56:57] op_sel_hi:[1,0]
	v_pk_mul_f32 v[42:43], v[42:43], v[56:57] op_sel_hi:[1,0]
	v_pk_mul_f32 v[40:41], v[40:41], v[56:57] op_sel_hi:[1,0]
	v_pk_mul_f32 v[58:59], v[38:39], v[56:57] op_sel_hi:[1,0]
	v_pk_mul_f32 v[56:57], v[36:37], v[56:57] op_sel_hi:[1,0]
	v_cvt_pk_bf16_f32 v36, v48, v49
	v_cvt_pk_bf16_f32 v37, v50, v51
	v_cvt_pk_bf16_f32 v38, v44, v45
	v_cvt_pk_bf16_f32 v39, v46, v47
	v_cvt_pk_bf16_f32 v40, v40, v41
	v_cvt_pk_bf16_f32 v41, v42, v43
	s_nop 0
	v_cvt_pk_bf16_f32 v42, v56, v57
	v_cvt_pk_bf16_f32 v43, v58, v59
	global_store_dwordx4 v[54:55], v[36:39], off nt
	global_store_dwordx4 v[52:53], v[40:43], off nt
	s_nop 0
	v_add_u32_e32 v38, 0x80, v118
	v_ashrrev_i32_e32 v39, 31, v38
	s_waitcnt lgkmcnt(0)
	s_waitcnt vmcnt(13)
	v_ffbh_u32_e32 v1, v177
	v_min_u32_e32 v1, 32, v1
	v_lshlrev_b64 v[36:37], v1, v[176:177]
	v_min_u32_e32 v36, 1, v36
	v_or_b32_e32 v36, v37, v36
	v_cvt_f32_u32_e32 v40, v36
	v_sub_u32_e32 v1, 32, v1
	v_lshlrev_b64 v[36:37], 13, v[38:39]
	v_lshl_add_u64 v[36:37], s[2:3], 0, v[36:37]
	v_ldexp_f32 v1, v40, v1
	v_mul_f32_e32 v1, 0x33800000, v1
	v_fmamk_f32 v1, v1, 0x3a000000, v234
	v_mul_f32_e32 v38, 0x4b800000, v1
	v_cmp_gt_f32_e32 vcc, s50, v1
	v_lshl_add_u64 v[36:37], v[36:37], 0, v[134:135]
	s_nop 0
	v_cndmask_b32_e32 v1, v1, v38, vcc
	v_rsq_f32_e32 v1, v1
	v_lshl_add_u64 v[38:39], v[36:37], 0, s[38:39]
	v_lshl_add_u64 v[36:37], v[36:37], 0, s[42:43]
	v_mul_f32_e32 v40, 0x45800000, v1
	v_cndmask_b32_e32 v40, v1, v40, vcc
	v_pk_mul_f32 v[34:35], v[34:35], v[40:41] op_sel_hi:[1,0]
	v_pk_mul_f32 v[32:33], v[32:33], v[40:41] op_sel_hi:[1,0]
	v_pk_mul_f32 v[30:31], v[30:31], v[40:41] op_sel_hi:[1,0]
	v_pk_mul_f32 v[28:29], v[28:29], v[40:41] op_sel_hi:[1,0]
	v_pk_mul_f32 v[26:27], v[26:27], v[40:41] op_sel_hi:[1,0]
	v_pk_mul_f32 v[24:25], v[24:25], v[40:41] op_sel_hi:[1,0]
	v_pk_mul_f32 v[42:43], v[22:23], v[40:41] op_sel_hi:[1,0]
	v_pk_mul_f32 v[40:41], v[20:21], v[40:41] op_sel_hi:[1,0]
	v_cvt_pk_bf16_f32 v20, v32, v33
	v_cvt_pk_bf16_f32 v21, v34, v35
	v_cvt_pk_bf16_f32 v22, v28, v29
	v_cvt_pk_bf16_f32 v23, v30, v31
	v_cvt_pk_bf16_f32 v24, v24, v25
	v_cvt_pk_bf16_f32 v25, v26, v27
	s_nop 0
	v_cvt_pk_bf16_f32 v26, v40, v41
	v_cvt_pk_bf16_f32 v27, v42, v43
	global_store_dwordx4 v[38:39], v[20:23], off nt
	global_store_dwordx4 v[36:37], v[24:27], off nt
	s_nop 0
	v_ashrrev_i32_e32 v1, 31, v0
	v_lshlrev_b64 v[0:1], 13, v[0:1]
	v_lshl_add_u64 v[0:1], s[2:3], 0, v[0:1]
	v_lshl_add_u64 v[0:1], v[0:1], 0, v[134:135]
	s_mov_b64 s[2:3], s[6:7]
	s_waitcnt lgkmcnt(0)
	s_waitcnt vmcnt(14)
	v_ffbh_u32_e32 v2, v179
	v_min_u32_e32 v22, 32, v2
	v_lshlrev_b64 v[2:3], v22, v[178:179]
	v_min_u32_e32 v2, 1, v2
	v_or_b32_e32 v2, v3, v2
	v_cvt_f32_u32_e32 v2, v2
	v_sub_u32_e32 v3, 32, v22
	v_lshl_add_u64 v[20:21], v[0:1], 0, s[38:39]
	v_lshl_add_u64 v[22:23], v[0:1], 0, s[42:43]
	v_ldexp_f32 v2, v2, v3
	v_mul_f32_e32 v2, 0x33800000, v2
	v_fmamk_f32 v2, v2, 0x3a000000, v234
	v_mul_f32_e32 v3, 0x4b800000, v2
	v_cmp_gt_f32_e32 vcc, s50, v2
	s_nop 1
	v_cndmask_b32_e32 v2, v2, v3, vcc
	v_rsq_f32_e32 v2, v2
	s_nop 0
	v_mul_f32_e32 v0, 0x45800000, v2
	v_cndmask_b32_e32 v0, v2, v0, vcc
	v_pk_mul_f32 v[2:3], v[18:19], v[0:1] op_sel_hi:[1,0]
	v_pk_mul_f32 v[16:17], v[16:17], v[0:1] op_sel_hi:[1,0]
	v_pk_mul_f32 v[14:15], v[14:15], v[0:1] op_sel_hi:[1,0]
	v_pk_mul_f32 v[12:13], v[12:13], v[0:1] op_sel_hi:[1,0]
	v_pk_mul_f32 v[10:11], v[10:11], v[0:1] op_sel_hi:[1,0]
	v_pk_mul_f32 v[8:9], v[8:9], v[0:1] op_sel_hi:[1,0]
	v_pk_mul_f32 v[18:19], v[6:7], v[0:1] op_sel_hi:[1,0]
	v_pk_mul_f32 v[6:7], v[4:5], v[0:1] op_sel_hi:[1,0]
	v_cvt_pk_bf16_f32 v0, v16, v17
	v_cvt_pk_bf16_f32 v1, v2, v3
	v_cvt_pk_bf16_f32 v2, v12, v13
	v_cvt_pk_bf16_f32 v3, v14, v15
	v_cvt_pk_bf16_f32 v4, v8, v9
	v_cvt_pk_bf16_f32 v5, v10, v11
	s_nop 0
	v_cvt_pk_bf16_f32 v6, v6, v7
	v_cvt_pk_bf16_f32 v7, v18, v19
	global_store_dwordx4 v[20:21], v[0:3], off nt
	global_store_dwordx4 v[22:23], v[4:7], off nt
	s_cbranch_scc0 .LBB0_256
	s_waitcnt vmcnt(0)
	s_cmpk_gt_u32 s1, 0xff
	s_cbranch_scc1 .LBB0_261
	s_barrier

; #define G_STAGE(bufoff, gbase, voff) do { _Pragma("unroll") for (int _i = 0; _i < 2; ++_i) { unsigned _vo = (voff)[_i]; asm volatile("" : "+v"(_vo));   \
;     __builtin_amdgcn_global_load_lds((const unsigned*)((const char*)(gbase) + _vo), (LAS unsigned*)(lds + (bufoff) + ldsw + _i * 8192), 16, 0, 0); } } while (0)
; #define G_LDA(dst, b, h) do { _Pragma("unroll") for (int m = 0; m < 4; ++m) _Pragma("unroll") for (int k = 0; k < 2; ++k) dst[m][k] = *(const LAS bf16x8*)(lds + G_SA(b, h) + aoff + m * 2048 + k * 1024); } while (0)
; #define G_LDB(dst, b, h) do { _Pragma("unroll") for (int n = 0; n < 2; ++n) _Pragma("unroll") for (int k = 0; k < 2; ++k) dst[n][k] = *(const LAS bf16x8*)(lds + G_SB(b, h) + boff + n * 2048 + k * 1024); } while (0)
; template <class Epi>
; __device__ __forceinline__ void gemm_phase(LAS unsigned char* lds, const int K, const unsigned lda_b, const unsigned ldb_b, const Map& M, const Epi& E) {
;     ...
;     for (int t = 0; t < nt; t += 2) {
;       const bool last = (t == nt - 2);
;       const char* a1h1 = cur.a0 + a_h + (size_t)(t + 1) * kstep;
;       const char* a2h0 = last ? nxt.a0 : cur.a0 + (size_t)(t + 2) * kstep; const char* a2h1 = a2h0 + a_h;
;       const char* b2h0 = last ? nxt.b0 : cur.b0 + (size_t)(t + 2) * kstep; const char* b2h1 = last ? nxt.b1 : cur.b1 + (size_t)(t + 2) * kstep;
;       G_LDB(B0, 0, 0); G_SCHED; G_LDA(At, 0, 0); G_STAGE(G_SA(1, 1), a1h1, voffA);
;       G_WAIT_L(8); G_BAR; G_WAIT_L(0); G_MMA(0, 0, At, B0); G_BAR; G_SCHED;
;       G_LDB(B1, 0, 1); G_STAGE(G_SB(0, 0), b2h0, voffB);
;       G_BAR; G_WAIT_L(0); G_MMA(0, 1, At, B1); G_BAR;
;       G_LDA(At, 0, 1); G_STAGE(G_SA(0, 0), a2h0, voffA);
;       G_BAR; G_WAIT_L(0); G_MMA(1, 0, At, B0); G_BAR; G_SCHED;
;       G_STAGE(G_SB(0, 1), b2h1, voffB);
;       G_WAIT_V(6); G_BAR; G_MMA(1, 1, At, B1); G_BAR;
;       G_LDB(B0, 1, 0); G_SCHED; G_LDA(At, 1, 0); G_STAGE(G_SA(0, 1), a2h1, voffA);
;       G_WAIT_L(8); G_BAR; G_WAIT_L(0); G_MMA(0, 0, At, B0); G_BAR; G_SCHED;
;       G_LDB(B1, 1, 1); G_STAGE(G_SB(1, 0), b2h0 + kstep, voffB);
;       G_BAR; G_WAIT_L(0); G_MMA(0, 1, At, B1); G_BAR;
;       G_LDA(At, 1, 1); G_STAGE(G_SA(1, 0), a2h0 + kstep, voffA);
;       G_BAR; G_WAIT_L(0); G_MMA(1, 0, At, B0); G_BAR; G_SCHED;
;       G_STAGE(G_SB(1, 1), b2h1 + kstep, voffB);
;       G_WAIT_V(6); G_BAR; G_MMA(1, 1, At, B1); G_BAR;
.LBB0_408:
	s_add_i32 s30, s29, 2
	s_add_u32 s42, s38, 0x100
	s_addc_u32 s43, s39, 0
	s_add_i32 s22, 0, 0x10000
	v_add_u32_e32 v80, s22, v133
	ds_read_b128 v[146:149], v80
	ds_read_b128 v[150:153], v80 offset:1024
	ds_read_b128 v[154:157], v80 offset:2048
	ds_read_b128 v[164:167], v80 offset:3072
	s_cmp_eq_u32 s76, s29
	s_cselect_b32 s69, s5, s43
	s_cselect_b32 s68, s4, s42
	s_cselect_b32 s95, s7, s28
	s_cselect_b32 s94, s6, vcc_hi
	s_cselect_b32 s44, s8, s87
	s_cselect_b32 s45, s9, vcc_lo
	s_add_u32 s96, s68, s18
	s_addc_u32 s97, s69, 0
	v_mov_b32_e32 v80, v130
	s_add_u32 s34, s38, s82
	ds_read_b128 v[168:171], v144
	ds_read_b128 v[172:175], v144 offset:1024
	ds_read_b128 v[176:179], v144 offset:2048
	ds_read_b128 v[184:187], v144 offset:3072
	ds_read_b128 v[190:193], v144 offset:4096
	ds_read_b128 v[194:197], v144 offset:5120
	ds_read_b128 v[198:201], v144 offset:6144
	ds_read_b128 v[202:205], v144 offset:7168
	s_addc_u32 s35, s39, s83
	s_add_i32 m0, s46, 0xc000
	s_nop 0
	global_load_lds_dwordx4 v80, s[34:35]
	v_mov_b32_e32 v80, v134
	s_add_i32 m0, s46, 0xe000
	s_nop 0
	global_load_lds_dwordx4 v80, s[34:35]
	s_waitcnt lgkmcnt(8)
	s_barrier
	s_waitcnt lgkmcnt(0)
	s_setprio 1
	s_waitcnt lgkmcnt(0)
	v_mfma_f32_16x16x32_bf16 v[126:129], v[146:149], v[168:171], v[126:129]
	v_mfma_f32_16x16x32_bf16 v[122:125], v[154:157], v[168:171], v[122:125]
	v_mfma_f32_16x16x32_bf16 v[118:121], v[146:149], v[176:179], v[118:121]
	v_mfma_f32_16x16x32_bf16 v[114:117], v[154:157], v[176:179], v[114:117]
	v_mfma_f32_16x16x32_bf16 v[102:105], v[146:149], v[190:193], v[102:105]
	v_mfma_f32_16x16x32_bf16 v[98:101], v[154:157], v[190:193], v[98:101]
	v_mfma_f32_16x16x32_bf16 v[86:89], v[146:149], v[198:201], v[86:89]
	v_mfma_f32_16x16x32_bf16 v[82:85], v[154:157], v[198:201], v[82:85]
	v_mfma_f32_16x16x32_bf16 v[126:129], v[150:153], v[172:175], v[126:129]
	v_mfma_f32_16x16x32_bf16 v[122:125], v[164:167], v[172:175], v[122:125]
	v_mfma_f32_16x16x32_bf16 v[118:121], v[150:153], v[184:187], v[118:121]
	v_mfma_f32_16x16x32_bf16 v[114:117], v[164:167], v[184:187], v[114:117]
	v_mfma_f32_16x16x32_bf16 v[102:105], v[150:153], v[194:197], v[102:105]
	v_mfma_f32_16x16x32_bf16 v[98:101], v[164:167], v[194:197], v[98:101]
	v_mfma_f32_16x16x32_bf16 v[86:89], v[150:153], v[202:205], v[86:89]
	v_mfma_f32_16x16x32_bf16 v[82:85], v[164:167], v[202:205], v[82:85]
	s_setprio 0
	s_barrier
	s_add_i32 s31, 0, 0x14000
	v_add_u32_e32 v80, s31, v133
	ds_read_b128 v[206:209], v80
	ds_read_b128 v[210:213], v80 offset:1024
	ds_read_b128 v[214:217], v80 offset:2048
	ds_read_b128 v[218:221], v80 offset:3072
	v_mov_b32_e32 v80, v132
	s_add_i32 s22, s22, s41
	s_mov_b32 m0, s22
	s_nop 0
	global_load_lds_dwordx4 v80, s[94:95]
	v_mov_b32_e32 v80, v136
	s_add_i32 m0, s22, 0x2000
	s_nop 0
	global_load_lds_dwordx4 v80, s[94:95]
	s_barrier
	s_waitcnt lgkmcnt(0)
	s_setprio 1
	s_waitcnt lgkmcnt(0)
	v_mfma_f32_16x16x32_bf16 v[110:113], v[206:209], v[168:171], v[110:113]
	v_mfma_f32_16x16x32_bf16 v[106:109], v[214:217], v[168:171], v[106:109]
	v_mfma_f32_16x16x32_bf16 v[94:97], v[206:209], v[176:179], v[94:97]
	v_mfma_f32_16x16x32_bf16 v[90:93], v[214:217], v[176:179], v[90:93]
	v_mfma_f32_16x16x32_bf16 v[76:79], v[206:209], v[190:193], v[76:79]
	v_mfma_f32_16x16x32_bf16 v[72:75], v[214:217], v[190:193], v[72:75]
	v_mfma_f32_16x16x32_bf16 v[68:71], v[206:209], v[198:201], v[68:71]
	v_mfma_f32_16x16x32_bf16 v[64:67], v[214:217], v[198:201], v[64:67]
	v_mfma_f32_16x16x32_bf16 v[110:113], v[210:213], v[172:175], v[110:113]
	v_mfma_f32_16x16x32_bf16 v[106:109], v[218:221], v[172:175], v[106:109]
	v_mfma_f32_16x16x32_bf16 v[94:97], v[210:213], v[184:187], v[94:97]
	v_mfma_f32_16x16x32_bf16 v[90:93], v[218:221], v[184:187], v[90:93]
	v_mfma_f32_16x16x32_bf16 v[76:79], v[210:213], v[194:197], v[76:79]
	v_mfma_f32_16x16x32_bf16 v[72:75], v[218:221], v[194:197], v[72:75]
	v_mfma_f32_16x16x32_bf16 v[68:71], v[210:213], v[202:205], v[68:71]
	v_mfma_f32_16x16x32_bf16 v[64:67], v[218:221], v[202:205], v[64:67]
	s_setprio 0
	v_mov_b32_e32 v80, v130
	s_mov_b32 m0, s46
	s_barrier
	ds_read_b128 v[168:171], v144 offset:16384
	ds_read_b128 v[172:175], v144 offset:17408
	ds_read_b128 v[176:179], v144 offset:18432
	ds_read_b128 v[184:187], v144 offset:19456
	ds_read_b128 v[190:193], v144 offset:20480
	ds_read_b128 v[194:197], v144 offset:21504
	ds_read_b128 v[198:201], v144 offset:22528
	ds_read_b128 v[202:205], v144 offset:23552
	s_nop 0
	global_load_lds_dwordx4 v80, s[68:69]
	v_mov_b32_e32 v80, v134
	s_mov_b32 m0, s47
	s_nop 0
	global_load_lds_dwordx4 v80, s[68:69]
	s_barrier
	s_waitcnt lgkmcnt(0)
	s_setprio 1
	s_waitcnt lgkmcnt(0)
	v_mfma_f32_16x16x32_bf16 v[60:63], v[146:149], v[168:171], v[60:63]
	v_mfma_f32_16x16x32_bf16 v[56:59], v[154:157], v[168:171], v[56:59]
	v_mfma_f32_16x16x32_bf16 v[52:55], v[146:149], v[176:179], v[52:55]
	v_mfma_f32_16x16x32_bf16 v[48:51], v[154:157], v[176:179], v[48:51]
	v_mfma_f32_16x16x32_bf16 v[36:39], v[146:149], v[190:193], v[36:39]
	v_mfma_f32_16x16x32_bf16 v[32:35], v[154:157], v[190:193], v[32:35]
	v_mfma_f32_16x16x32_bf16 v[20:23], v[146:149], v[198:201], v[20:23]
	v_mfma_f32_16x16x32_bf16 v[16:19], v[154:157], v[198:201], v[16:19]
	v_mfma_f32_16x16x32_bf16 v[60:63], v[150:153], v[172:175], v[60:63]
	v_mfma_f32_16x16x32_bf16 v[56:59], v[164:167], v[172:175], v[56:59]
	v_mfma_f32_16x16x32_bf16 v[52:55], v[150:153], v[184:187], v[52:55]
	v_mfma_f32_16x16x32_bf16 v[48:51], v[164:167], v[184:187], v[48:51]
	v_mfma_f32_16x16x32_bf16 v[36:39], v[150:153], v[194:197], v[36:39]
	v_mfma_f32_16x16x32_bf16 v[32:35], v[164:167], v[194:197], v[32:35]
	v_mfma_f32_16x16x32_bf16 v[20:23], v[150:153], v[202:205], v[20:23]
	v_mfma_f32_16x16x32_bf16 v[16:19], v[164:167], v[202:205], v[16:19]
	s_setprio 0
	s_barrier
; #define G_STAGE(bufoff, gbase, voff) do { _Pragma("unroll") for (int _i = 0; _i < 2; ++_i) { unsigned _vo = (voff)[_i]; asm volatile("" : "+v"(_vo));   \
;     __builtin_amdgcn_global_load_lds((const unsigned*)((const char*)(gbase) + _vo), (LAS unsigned*)(lds + (bufoff) + ldsw + _i * 8192), 16, 0, 0); } } while (0)
; #define G_LDA(dst, b, h) do { _Pragma("unroll") for (int m = 0; m < 4; ++m) _Pragma("unroll") for (int k = 0; k < 2; ++k) dst[m][k] = *(const LAS bf16x8*)(lds + G_SA(b, h) + aoff + m * 2048 + k * 1024); } while (0)
; #define G_LDB(dst, b, h) do { _Pragma("unroll") for (int n = 0; n < 2; ++n) _Pragma("unroll") for (int k = 0; k < 2; ++k) dst[n][k] = *(const LAS bf16x8*)(lds + G_SB(b, h) + boff + n * 2048 + k * 1024); } while (0)
; #define G_MMA(ai, bj, At, Bt) do { __builtin_amdgcn_s_setprio(1); _Pragma("unroll") for (int m = 0; m < 4; ++m) _Pragma("unroll") for (int n = 0; n < 2; ++n) _Pragma("unroll") for (int k = 0; k < 2; ++k) \
;     acc[ai][bj][m][n] = __builtin_amdgcn_mfma_f32_16x16x32_bf16(Bt[n][k], At[m][k], acc[ai][bj][m][n], 0, 0, 0); __builtin_amdgcn_s_setprio(0); } while (0)
; #define G_WAIT_V(n) asm volatile("s_waitcnt vmcnt(" #n ")" ::: "memory")
; template <class Epi>
; __device__ __forceinline__ void gemm_phase(LAS unsigned char* lds, const int K, const unsigned lda_b, const unsigned ldb_b, const Map& M, const Epi& E) {
;     ...
;       G_LDB(B0, 0, 0); G_SCHED; G_LDA(At, 0, 0); G_STAGE(G_SA(1, 1), a1h1, voffA);
;       G_WAIT_L(8); G_BAR; G_WAIT_L(0); G_MMA(0, 0, At, B0); G_BAR; G_SCHED;
;       G_LDB(B1, 0, 1); G_STAGE(G_SB(0, 0), b2h0, voffB);
;       G_BAR; G_WAIT_L(0); G_MMA(0, 1, At, B1); G_BAR;
;       G_LDA(At, 0, 1); G_STAGE(G_SA(0, 0), a2h0, voffA);
;       G_BAR; G_WAIT_L(0); G_MMA(1, 0, At, B0); G_BAR; G_SCHED;
;       G_STAGE(G_SB(0, 1), b2h1, voffB);
;       G_WAIT_V(6); G_BAR; G_MMA(1, 1, At, B1); G_BAR;
;       G_LDB(B0, 1, 0); G_SCHED; G_LDA(At, 1, 0); G_STAGE(G_SA(0, 1), a2h1, voffA);
;       G_WAIT_L(8); G_BAR; G_WAIT_L(0); G_MMA(0, 0, At, B0); G_BAR; G_SCHED;
;       G_LDB(B1, 1, 1); G_STAGE(G_SB(1, 0), b2h0 + kstep, voffB);
;       G_BAR; G_WAIT_L(0); G_MMA(0, 1, At, B1); G_BAR;
;       G_LDA(At, 1, 1); G_STAGE(G_SA(1, 0), a2h0 + kstep, voffA);
;       G_BAR; G_WAIT_L(0); G_MMA(1, 0, At, B0); G_BAR; G_SCHED;
;       G_STAGE(G_SB(1, 1), b2h1 + kstep, voffB);
;       G_WAIT_V(6); G_BAR; G_MMA(1, 1, At, B1); G_BAR;
	v_mov_b32_e32 v80, v132
	s_add_i32 s22, s31, s41
	s_mov_b32 m0, s22
	s_nop 0
	global_load_lds_dwordx4 v80, s[44:45]
	v_mov_b32_e32 v80, v136
	s_add_i32 m0, s22, 0x2000
	s_nop 0
	global_load_lds_dwordx4 v80, s[44:45]
	s_waitcnt vmcnt(6)
	s_barrier
	s_setprio 1
	v_mfma_f32_16x16x32_bf16 v[44:47], v[206:209], v[168:171], v[44:47]
	v_mfma_f32_16x16x32_bf16 v[40:43], v[214:217], v[168:171], v[40:43]
	v_mfma_f32_16x16x32_bf16 v[28:31], v[206:209], v[176:179], v[28:31]
	v_mfma_f32_16x16x32_bf16 v[24:27], v[214:217], v[176:179], v[24:27]
	v_mfma_f32_16x16x32_bf16 v[12:15], v[206:209], v[190:193], v[12:15]
	v_mfma_f32_16x16x32_bf16 v[8:11], v[214:217], v[190:193], v[8:11]
	v_mfma_f32_16x16x32_bf16 v[4:7], v[206:209], v[198:201], v[4:7]
	v_mfma_f32_16x16x32_bf16 v[0:3], v[214:217], v[198:201], v[0:3]
	v_mfma_f32_16x16x32_bf16 v[44:47], v[210:213], v[172:175], v[44:47]
	v_mfma_f32_16x16x32_bf16 v[40:43], v[218:221], v[172:175], v[40:43]
	v_mfma_f32_16x16x32_bf16 v[28:31], v[210:213], v[184:187], v[28:31]
	v_mfma_f32_16x16x32_bf16 v[24:27], v[218:221], v[184:187], v[24:27]
	v_mfma_f32_16x16x32_bf16 v[12:15], v[210:213], v[194:197], v[12:15]
	v_mfma_f32_16x16x32_bf16 v[8:11], v[218:221], v[194:197], v[8:11]
	v_mfma_f32_16x16x32_bf16 v[4:7], v[210:213], v[202:205], v[4:7]
	v_mfma_f32_16x16x32_bf16 v[0:3], v[218:221], v[202:205], v[0:3]
	s_setprio 0
	s_add_i32 s22, 0, 0x18000
	v_add_u32_e32 v80, s22, v133
	s_barrier
	ds_read_b128 v[146:149], v80
	ds_read_b128 v[150:153], v80 offset:1024
	ds_read_b128 v[154:157], v80 offset:2048
	ds_read_b128 v[164:167], v80 offset:3072
	v_mov_b32_e32 v80, v130
	s_mov_b32 m0, s48
	ds_read_b128 v[168:171], v144 offset:32768
	ds_read_b128 v[172:175], v144 offset:33792
	ds_read_b128 v[176:179], v144 offset:34816
	ds_read_b128 v[184:187], v144 offset:35840
	ds_read_b128 v[190:193], v144 offset:36864
	ds_read_b128 v[194:197], v144 offset:37888
	ds_read_b128 v[198:201], v144 offset:38912
	ds_read_b128 v[202:205], v144 offset:39936
	s_nop 0
	global_load_lds_dwordx4 v80, s[96:97]
	v_mov_b32_e32 v80, v134
	s_mov_b32 m0, s49
	s_nop 0
	global_load_lds_dwordx4 v80, s[96:97]
	s_waitcnt lgkmcnt(8)
	s_barrier
	s_waitcnt lgkmcnt(0)
	s_setprio 1
	s_waitcnt lgkmcnt(0)
	v_mfma_f32_16x16x32_bf16 v[126:129], v[146:149], v[168:171], v[126:129]
	v_mfma_f32_16x16x32_bf16 v[122:125], v[154:157], v[168:171], v[122:125]
	v_mfma_f32_16x16x32_bf16 v[118:121], v[146:149], v[176:179], v[118:121]
	v_mfma_f32_16x16x32_bf16 v[114:117], v[154:157], v[176:179], v[114:117]
	v_mfma_f32_16x16x32_bf16 v[102:105], v[146:149], v[190:193], v[102:105]
	v_mfma_f32_16x16x32_bf16 v[98:101], v[154:157], v[190:193], v[98:101]
	v_mfma_f32_16x16x32_bf16 v[86:89], v[146:149], v[198:201], v[86:89]
	v_mfma_f32_16x16x32_bf16 v[82:85], v[154:157], v[198:201], v[82:85]
	v_mfma_f32_16x16x32_bf16 v[126:129], v[150:153], v[172:175], v[126:129]
	v_mfma_f32_16x16x32_bf16 v[122:125], v[164:167], v[172:175], v[122:125]
	v_mfma_f32_16x16x32_bf16 v[118:121], v[150:153], v[184:187], v[118:121]
	v_mfma_f32_16x16x32_bf16 v[114:117], v[164:167], v[184:187], v[114:117]
	v_mfma_f32_16x16x32_bf16 v[102:105], v[150:153], v[194:197], v[102:105]
	v_mfma_f32_16x16x32_bf16 v[98:101], v[164:167], v[194:197], v[98:101]
	v_mfma_f32_16x16x32_bf16 v[86:89], v[150:153], v[202:205], v[86:89]
	v_mfma_f32_16x16x32_bf16 v[82:85], v[164:167], v[202:205], v[82:85]
	s_setprio 0
	s_barrier
	s_add_i32 s31, 0, 0x1c000
	v_add_u32_e32 v80, s31, v133
	ds_read_b128 v[206:209], v80
	ds_read_b128 v[210:213], v80 offset:1024
	ds_read_b128 v[214:217], v80 offset:2048
	ds_read_b128 v[218:221], v80 offset:3072
	v_mov_b32_e32 v80, v132
	s_add_i32 s22, s22, s41
	s_add_i32 m0, s22, 0xffffff80
	v_mov_b32_e32 v80, v136
	global_load_lds_dwordx4 v132, s[94:95] offset:128
	s_add_i32 m0, s22, 0x1f80
	s_nop 0
	global_load_lds_dwordx4 v136, s[94:95] offset:128
	s_barrier
	s_waitcnt lgkmcnt(0)
	s_setprio 1
	s_waitcnt lgkmcnt(0)
	v_mfma_f32_16x16x32_bf16 v[110:113], v[206:209], v[168:171], v[110:113]
	v_mfma_f32_16x16x32_bf16 v[106:109], v[214:217], v[168:171], v[106:109]
	v_mfma_f32_16x16x32_bf16 v[94:97], v[206:209], v[176:179], v[94:97]
	v_mfma_f32_16x16x32_bf16 v[90:93], v[214:217], v[176:179], v[90:93]
	v_mfma_f32_16x16x32_bf16 v[76:79], v[206:209], v[190:193], v[76:79]
	v_mfma_f32_16x16x32_bf16 v[72:75], v[214:217], v[190:193], v[72:75]
	v_mfma_f32_16x16x32_bf16 v[68:71], v[206:209], v[198:201], v[68:71]
	v_mfma_f32_16x16x32_bf16 v[64:67], v[214:217], v[198:201], v[64:67]
	v_mfma_f32_16x16x32_bf16 v[110:113], v[210:213], v[172:175], v[110:113]
	v_mfma_f32_16x16x32_bf16 v[106:109], v[218:221], v[172:175], v[106:109]
	v_mfma_f32_16x16x32_bf16 v[94:97], v[210:213], v[184:187], v[94:97]
	v_mfma_f32_16x16x32_bf16 v[90:93], v[218:221], v[184:187], v[90:93]
	v_mfma_f32_16x16x32_bf16 v[76:79], v[210:213], v[194:197], v[76:79]
	v_mfma_f32_16x16x32_bf16 v[72:75], v[218:221], v[194:197], v[72:75]
	v_mfma_f32_16x16x32_bf16 v[68:71], v[210:213], v[202:205], v[68:71]
	v_mfma_f32_16x16x32_bf16 v[64:67], v[218:221], v[202:205], v[64:67]
	s_setprio 0
	v_mov_b32_e32 v80, v130
	s_barrier
	ds_read_b128 v[168:171], v144 offset:49152
	ds_read_b128 v[172:175], v144 offset:50176
	ds_read_b128 v[176:179], v144 offset:51200
	ds_read_b128 v[184:187], v144 offset:52224
	ds_read_b128 v[190:193], v144 offset:53248
	ds_read_b128 v[194:197], v144 offset:54272
	ds_read_b128 v[198:201], v144 offset:55296
	ds_read_b128 v[202:205], v144 offset:56320
	s_add_i32 m0, s66, 0xffffff80
	v_mov_b32_e32 v80, v134
	global_load_lds_dwordx4 v130, s[68:69] offset:128
	s_add_i32 m0, s75, 0xffffff80
	s_nop 0
	global_load_lds_dwordx4 v134, s[68:69] offset:128
	s_barrier
; #define G_STAGE(bufoff, gbase, voff) do { _Pragma("unroll") for (int _i = 0; _i < 2; ++_i) { unsigned _vo = (voff)[_i]; asm volatile("" : "+v"(_vo));   \
;     __builtin_amdgcn_global_load_lds((const unsigned*)((const char*)(gbase) + _vo), (LAS unsigned*)(lds + (bufoff) + ldsw + _i * 8192), 16, 0, 0); } } while (0)
; #define G_LDA(dst, b, h) do { _Pragma("unroll") for (int m = 0; m < 4; ++m) _Pragma("unroll") for (int k = 0; k < 2; ++k) dst[m][k] = *(const LAS bf16x8*)(lds + G_SA(b, h) + aoff + m * 2048 + k * 1024); } while (0)
; #define G_MMA(ai, bj, At, Bt) do { __builtin_amdgcn_s_setprio(1); _Pragma("unroll") for (int m = 0; m < 4; ++m) _Pragma("unroll") for (int n = 0; n < 2; ++n) _Pragma("unroll") for (int k = 0; k < 2; ++k) \
;     acc[ai][bj][m][n] = __builtin_amdgcn_mfma_f32_16x16x32_bf16(Bt[n][k], At[m][k], acc[ai][bj][m][n], 0, 0, 0); __builtin_amdgcn_s_setprio(0); } while (0)
; #define G_WAIT_V(n) asm volatile("s_waitcnt vmcnt(" #n ")" ::: "memory")
; #define G_WAIT_L(n) asm volatile("s_waitcnt lgkmcnt(" #n ")" ::: "memory")
; #define G_BAR __builtin_amdgcn_s_barrier()
; #define G_SCHED __builtin_amdgcn_sched_barrier(0)
; template <class Epi>
; __device__ __forceinline__ void gemm_phase(LAS unsigned char* lds, const int K, const unsigned lda_b, const unsigned ldb_b, const Map& M, const Epi& E) {
;     ...
;       G_BAR; G_WAIT_L(0); G_MMA(0, 1, At, B1); G_BAR;
;       G_LDA(At, 1, 1); G_STAGE(G_SA(1, 0), a2h0 + kstep, voffA);
;       G_BAR; G_WAIT_L(0); G_MMA(1, 0, At, B0); G_BAR; G_SCHED;
;       G_STAGE(G_SB(1, 1), b2h1 + kstep, voffB);
;       G_WAIT_V(6); G_BAR; G_MMA(1, 1, At, B1); G_BAR;
	s_waitcnt lgkmcnt(0)
	s_setprio 1
	s_waitcnt lgkmcnt(0)
	v_mfma_f32_16x16x32_bf16 v[60:63], v[146:149], v[168:171], v[60:63]
	v_mfma_f32_16x16x32_bf16 v[56:59], v[154:157], v[168:171], v[56:59]
	v_mfma_f32_16x16x32_bf16 v[52:55], v[146:149], v[176:179], v[52:55]
	v_mfma_f32_16x16x32_bf16 v[48:51], v[154:157], v[176:179], v[48:51]
	v_mfma_f32_16x16x32_bf16 v[36:39], v[146:149], v[190:193], v[36:39]
	v_mfma_f32_16x16x32_bf16 v[32:35], v[154:157], v[190:193], v[32:35]
	v_mfma_f32_16x16x32_bf16 v[20:23], v[146:149], v[198:201], v[20:23]
	v_mfma_f32_16x16x32_bf16 v[16:19], v[154:157], v[198:201], v[16:19]
	v_mfma_f32_16x16x32_bf16 v[60:63], v[150:153], v[172:175], v[60:63]
	v_mfma_f32_16x16x32_bf16 v[56:59], v[164:167], v[172:175], v[56:59]
	v_mfma_f32_16x16x32_bf16 v[52:55], v[150:153], v[184:187], v[52:55]
	v_mfma_f32_16x16x32_bf16 v[48:51], v[164:167], v[184:187], v[48:51]
	v_mfma_f32_16x16x32_bf16 v[36:39], v[150:153], v[194:197], v[36:39]
	v_mfma_f32_16x16x32_bf16 v[32:35], v[164:167], v[194:197], v[32:35]
	v_mfma_f32_16x16x32_bf16 v[20:23], v[150:153], v[202:205], v[20:23]
	v_mfma_f32_16x16x32_bf16 v[16:19], v[164:167], v[202:205], v[16:19]
	s_setprio 0
	s_barrier
	v_mov_b32_e32 v80, v132
	s_add_i32 s22, s31, s41
	s_add_i32 m0, s22, 0xffffff80
	v_mov_b32_e32 v80, v136
	global_load_lds_dwordx4 v132, s[44:45] offset:128
	s_add_i32 m0, s22, 0x1f80
	s_nop 0
	global_load_lds_dwordx4 v136, s[44:45] offset:128
	s_waitcnt vmcnt(6)
	s_barrier
	s_setprio 1
	v_mfma_f32_16x16x32_bf16 v[44:47], v[206:209], v[168:171], v[44:47]
	v_mfma_f32_16x16x32_bf16 v[40:43], v[214:217], v[168:171], v[40:43]
	v_mfma_f32_16x16x32_bf16 v[28:31], v[206:209], v[176:179], v[28:31]
	v_mfma_f32_16x16x32_bf16 v[24:27], v[214:217], v[176:179], v[24:27]
	v_mfma_f32_16x16x32_bf16 v[12:15], v[206:209], v[190:193], v[12:15]
	v_mfma_f32_16x16x32_bf16 v[8:11], v[214:217], v[190:193], v[8:11]
	v_mfma_f32_16x16x32_bf16 v[4:7], v[206:209], v[198:201], v[4:7]
	v_mfma_f32_16x16x32_bf16 v[0:3], v[214:217], v[198:201], v[0:3]
	v_mfma_f32_16x16x32_bf16 v[44:47], v[210:213], v[172:175], v[44:47]
	v_mfma_f32_16x16x32_bf16 v[40:43], v[218:221], v[172:175], v[40:43]
	v_mfma_f32_16x16x32_bf16 v[28:31], v[210:213], v[184:187], v[28:31]
	v_mfma_f32_16x16x32_bf16 v[24:27], v[218:221], v[184:187], v[24:27]
	v_mfma_f32_16x16x32_bf16 v[12:15], v[210:213], v[194:197], v[12:15]
	v_mfma_f32_16x16x32_bf16 v[8:11], v[218:221], v[194:197], v[8:11]
	v_mfma_f32_16x16x32_bf16 v[4:7], v[210:213], v[202:205], v[4:7]
	v_mfma_f32_16x16x32_bf16 v[0:3], v[218:221], v[202:205], v[0:3]
	s_setprio 0
	s_add_u32 s87, s87, 0x100
	s_addc_u32 vcc_lo, vcc_lo, 0
	s_add_u32 vcc_hi, vcc_hi, 0x100
	s_addc_u32 s28, s28, 0
	s_cmp_ge_u32 s29, s76
	s_mov_b64 s[38:39], s[42:43]
	s_mov_b32 s29, s30
	s_barrier
	s_cbranch_scc0 .LBB0_408
;   __device__ __forceinline__ void operator()(const f32x4 (&acc)[2][2][4][2], const Unit& u, const EpiCtx& x_, int wr, int wc, int fr, int fq) const {
; #pragma unroll
;     for (int ai = 0; ai < 2; ++ai)
; #pragma unroll
;       for (int m = 0; m < 4; ++m) {
;         const int row = (u.r0 + (ai ? x_.rdelta : 0)) + wr * 64 + m * 16 + fr;
;         float* rowp = (float*)u.C + (size_t)row * x_.ldc;
; #pragma unroll
;         for (int bj = 0; bj < 2; ++bj) {
;           const int cb = (u.c0 + bj * 128) + wc * 32 + 4 * fq;
;           *(f32x4*)(rowp + cb) = acc[ai][bj][m][0]; *(f32x4*)(rowp + cb + 16) = acc[ai][bj][m][1];
;         }
;       }
	v_readfirstlane_b32 s22, v138
	v_add_u32_e32 v138, s67, v131
	v_readfirstlane_b32 s28, v139
	v_ashrrev_i32_e32 v139, 31, v138
	v_add_u32_e32 v148, s79, v135
	v_lshlrev_b64 v[146:147], 14, v[138:139]
	v_ashrrev_i32_e32 v149, 31, v148
	v_lshl_add_u64 v[146:147], s[2:3], 0, v[146:147]
	v_lshlrev_b64 v[148:149], 2, v[148:149]
	v_lshl_add_u64 v[150:151], v[146:147], 0, v[148:149]
	global_store_dwordx4 v[150:151], v[126:129], off nt
	global_store_dwordx4 v[150:151], v[122:125], off offset:64 nt
	s_cmp_eq_u32 s86, s81
	s_mov_b64 s[38:39], s[4:5]
	v_add_u32_e32 v122, s79, v137
	v_ashrrev_i32_e32 v123, 31, v122
	v_lshlrev_b64 v[122:123], 2, v[122:123]
	v_lshl_add_u64 v[124:125], v[146:147], 0, v[122:123]
	global_store_dwordx4 v[124:125], v[110:113], off nt
	global_store_dwordx4 v[124:125], v[106:109], off offset:64 nt
	s_mov_b64 s[42:43], s[6:7]
	s_mov_b64 s[44:45], s[8:9]
	v_add_u32_e32 v106, s67, v141
	v_ashrrev_i32_e32 v107, 31, v106
	v_lshlrev_b64 v[106:107], 14, v[106:107]
	v_lshl_add_u64 v[106:107], s[2:3], 0, v[106:107]
	v_lshl_add_u64 v[108:109], v[106:107], 0, v[148:149]
	v_lshl_add_u64 v[106:107], v[106:107], 0, v[122:123]
	global_store_dwordx4 v[108:109], v[118:121], off nt
	global_store_dwordx4 v[108:109], v[114:117], off offset:64 nt
	global_store_dwordx4 v[106:107], v[94:97], off nt
	global_store_dwordx4 v[106:107], v[90:93], off offset:64 nt
	s_mov_b32 s79, s28
	s_nop 0
	v_add_u32_e32 v90, s67, v142
	v_ashrrev_i32_e32 v91, 31, v90
	v_lshlrev_b64 v[90:91], 14, v[90:91]
	v_lshl_add_u64 v[90:91], s[2:3], 0, v[90:91]
	v_lshl_add_u64 v[92:93], v[90:91], 0, v[148:149]
	v_lshl_add_u64 v[90:91], v[90:91], 0, v[122:123]
	global_store_dwordx4 v[92:93], v[102:105], off nt
	global_store_dwordx4 v[92:93], v[98:101], off offset:64 nt
	global_store_dwordx4 v[90:91], v[76:79], off nt
	global_store_dwordx4 v[90:91], v[72:75], off offset:64 nt
	s_nop 1
	v_add_u32_e32 v72, s67, v143
	v_ashrrev_i32_e32 v73, 31, v72
	v_lshlrev_b64 v[72:73], 14, v[72:73]
	v_lshl_add_u64 v[72:73], s[2:3], 0, v[72:73]
	v_lshl_add_u64 v[74:75], v[72:73], 0, v[148:149]
	v_lshl_add_u64 v[72:73], v[72:73], 0, v[122:123]
	global_store_dwordx4 v[74:75], v[86:89], off nt
	global_store_dwordx4 v[74:75], v[82:85], off offset:64 nt
	global_store_dwordx4 v[72:73], v[68:71], off nt
	global_store_dwordx4 v[72:73], v[64:67], off offset:64 nt
	s_mov_b32 s67, s22
	s_nop 0
	v_add_u32_e32 v64, 0x80, v138
	v_ashrrev_i32_e32 v65, 31, v64
	v_lshlrev_b64 v[64:65], 14, v[64:65]
	v_lshl_add_u64 v[64:65], s[2:3], 0, v[64:65]
	v_lshl_add_u64 v[66:67], v[64:65], 0, v[148:149]
	global_store_dwordx4 v[66:67], v[60:63], off nt
	global_store_dwordx4 v[66:67], v[56:59], off offset:64 nt
	s_nop 1
	v_lshl_add_u64 v[56:57], v[64:65], 0, v[122:123]
	global_store_dwordx4 v[56:57], v[44:47], off nt
	global_store_dwordx4 v[56:57], v[40:43], off offset:64 nt
	s_nop 1
	v_add_u32_e32 v40, 0x90, v138
	v_ashrrev_i32_e32 v41, 31, v40
	v_lshlrev_b64 v[40:41], 14, v[40:41]
	v_lshl_add_u64 v[40:41], s[2:3], 0, v[40:41]
	v_lshl_add_u64 v[42:43], v[40:41], 0, v[148:149]
	v_lshl_add_u64 v[40:41], v[40:41], 0, v[122:123]
	global_store_dwordx4 v[42:43], v[52:55], off nt
	global_store_dwordx4 v[42:43], v[48:51], off offset:64 nt
	global_store_dwordx4 v[40:41], v[28:31], off nt
	global_store_dwordx4 v[40:41], v[24:27], off offset:64 nt
	s_nop 1
	v_add_u32_e32 v24, 0xa0, v138
	v_ashrrev_i32_e32 v25, 31, v24
	v_lshlrev_b64 v[24:25], 14, v[24:25]
	v_lshl_add_u64 v[24:25], s[2:3], 0, v[24:25]
	v_lshl_add_u64 v[26:27], v[24:25], 0, v[148:149]
	v_lshl_add_u64 v[24:25], v[24:25], 0, v[122:123]
	global_store_dwordx4 v[26:27], v[36:39], off nt
	global_store_dwordx4 v[26:27], v[32:35], off offset:64 nt
	global_store_dwordx4 v[24:25], v[12:15], off nt
	global_store_dwordx4 v[24:25], v[8:11], off offset:64 nt
	s_nop 1
	v_add_u32_e32 v8, 0xb0, v138
	v_ashrrev_i32_e32 v9, 31, v8
	v_lshlrev_b64 v[8:9], 14, v[8:9]
	v_lshl_add_u64 v[8:9], s[2:3], 0, v[8:9]
	v_lshl_add_u64 v[10:11], v[8:9], 0, v[148:149]
	v_lshl_add_u64 v[8:9], v[8:9], 0, v[122:123]
	s_mov_b64 s[2:3], s[36:37]
	global_store_dwordx4 v[10:11], v[20:23], off nt
	global_store_dwordx4 v[10:11], v[16:19], off offset:64 nt
	global_store_dwordx4 v[8:9], v[4:7], off nt
	global_store_dwordx4 v[8:9], v[0:3], off offset:64 nt
	s_cbranch_scc0 .LBB0_407
	s_waitcnt vmcnt(0)
	s_cmpk_gt_u32 s19, 0xff
	s_mov_b32 s86, 0x7f800000
	s_brev_b32 s82, 1
	s_cbranch_scc1 .LBB0_412
	s_barrier

; #define G_STAGE(bufoff, gbase, voff) do { _Pragma("unroll") for (int _i = 0; _i < 2; ++_i) { unsigned _vo = (voff)[_i]; asm volatile("" : "+v"(_vo));   \
;     __builtin_amdgcn_global_load_lds((const unsigned*)((const char*)(gbase) + _vo), (LAS unsigned*)(lds + (bufoff) + ldsw + _i * 8192), 16, 0, 0); } } while (0)
; #define G_LDA(dst, b, h) do { _Pragma("unroll") for (int m = 0; m < 4; ++m) _Pragma("unroll") for (int k = 0; k < 2; ++k) dst[m][k] = *(const LAS bf16x8*)(lds + G_SA(b, h) + aoff + m * 2048 + k * 1024); } while (0)
; #define G_LDB(dst, b, h) do { _Pragma("unroll") for (int n = 0; n < 2; ++n) _Pragma("unroll") for (int k = 0; k < 2; ++k) dst[n][k] = *(const LAS bf16x8*)(lds + G_SB(b, h) + boff + n * 2048 + k * 1024); } while (0)
; template <class Epi>
; __device__ __forceinline__ void gemm_phase(LAS unsigned char* lds, const int K, const unsigned lda_b, const unsigned ldb_b, const Map& M, const Epi& E) {
;     ...
;     for (int t = 0; t < nt; t += 2) {
;       const bool last = (t == nt - 2);
;       const char* a1h1 = cur.a0 + a_h + (size_t)(t + 1) * kstep;
;       const char* a2h0 = last ? nxt.a0 : cur.a0 + (size_t)(t + 2) * kstep; const char* a2h1 = a2h0 + a_h;
;       const char* b2h0 = last ? nxt.b0 : cur.b0 + (size_t)(t + 2) * kstep; const char* b2h1 = last ? nxt.b1 : cur.b1 + (size_t)(t + 2) * kstep;
;       G_LDB(B0, 0, 0); G_SCHED; G_LDA(At, 0, 0); G_STAGE(G_SA(1, 1), a1h1, voffA);
;       G_WAIT_L(8); G_BAR; G_WAIT_L(0); G_MMA(0, 0, At, B0); G_BAR; G_SCHED;
;       G_LDB(B1, 0, 1); G_STAGE(G_SB(0, 0), b2h0, voffB);
;       G_BAR; G_WAIT_L(0); G_MMA(0, 1, At, B1); G_BAR;
;       G_LDA(At, 0, 1); G_STAGE(G_SA(0, 0), a2h0, voffA);
;       G_BAR; G_WAIT_L(0); G_MMA(1, 0, At, B0); G_BAR; G_SCHED;
;       G_STAGE(G_SB(0, 1), b2h1, voffB);
;       G_WAIT_V(6); G_BAR; G_MMA(1, 1, At, B1); G_BAR;
;       G_LDB(B0, 1, 0); G_SCHED; G_LDA(At, 1, 0); G_STAGE(G_SA(0, 1), a2h1, voffA);
;       G_WAIT_L(8); G_BAR; G_WAIT_L(0); G_MMA(0, 0, At, B0); G_BAR; G_SCHED;
;       G_LDB(B1, 1, 1); G_STAGE(G_SB(1, 0), b2h0 + kstep, voffB);
;       G_BAR; G_WAIT_L(0); G_MMA(0, 1, At, B1); G_BAR;
;       G_LDA(At, 1, 1); G_STAGE(G_SA(1, 0), a2h0 + kstep, voffA);
;       G_BAR; G_WAIT_L(0); G_MMA(1, 0, At, B0); G_BAR; G_SCHED;
;       G_STAGE(G_SB(1, 1), b2h1 + kstep, voffB);
;       G_WAIT_V(6); G_BAR; G_MMA(1, 1, At, B1); G_BAR;
.LBB0_554:
	s_add_u32 s22, s2, 0xfff00080
	s_addc_u32 s35, s3, -1
	s_add_u32 s38, s30, 0xfffc0000
	s_addc_u32 s39, s31, -1
	s_add_i32 s76, 0, 0x10000
	v_add_u32_e32 v80, s76, v139
	ds_read_b128 v[142:145], v80
	ds_read_b128 v[146:149], v80 offset:1024
	ds_read_b128 v[150:153], v80 offset:2048
	ds_read_b128 v[154:157], v80 offset:3072
	s_cmp_eq_u32 s34, 60
	s_cselect_b32 s43, s5, s35
	s_cselect_b32 s42, s4, s22
	s_cselect_b32 s45, s7, s39
	s_cselect_b32 s44, s6, s38
	v_mov_b32_e32 v80, v134
	s_cselect_b32 s39, s29, s31
	s_cselect_b32 s38, s28, s30
	s_add_u32 s68, s42, 0x100000
	ds_read_b128 v[164:167], v141
	ds_read_b128 v[168:171], v141 offset:1024
	ds_read_b128 v[172:175], v141 offset:2048
	ds_read_b128 v[176:179], v141 offset:3072
	ds_read_b128 v[184:187], v141 offset:4096
	ds_read_b128 v[190:193], v141 offset:5120
	ds_read_b128 v[194:197], v141 offset:6144
	ds_read_b128 v[198:201], v141 offset:7168
	s_addc_u32 s69, s43, 0
	s_add_i32 m0, s19, 0xc000
	s_nop 0
	global_load_lds_dwordx4 v80, s[2:3]
	v_mov_b32_e32 v80, v136
	s_add_i32 m0, s19, 0xe000
	s_nop 0
	global_load_lds_dwordx4 v80, s[2:3]
	s_waitcnt lgkmcnt(8)
	s_barrier
	s_waitcnt lgkmcnt(0)
	s_setprio 1
	s_waitcnt lgkmcnt(0)
	v_mfma_f32_16x16x32_bf16 v[126:129], v[142:145], v[164:167], v[126:129]
	v_mfma_f32_16x16x32_bf16 v[122:125], v[150:153], v[164:167], v[122:125]
	v_mfma_f32_16x16x32_bf16 v[110:113], v[142:145], v[172:175], v[110:113]
	v_mfma_f32_16x16x32_bf16 v[106:109], v[150:153], v[172:175], v[106:109]
	v_mfma_f32_16x16x32_bf16 v[94:97], v[142:145], v[184:187], v[94:97]
	v_mfma_f32_16x16x32_bf16 v[90:93], v[150:153], v[184:187], v[90:93]
	v_mfma_f32_16x16x32_bf16 v[76:79], v[142:145], v[194:197], v[76:79]
	v_mfma_f32_16x16x32_bf16 v[72:75], v[150:153], v[194:197], v[72:75]
	v_mfma_f32_16x16x32_bf16 v[126:129], v[146:149], v[168:171], v[126:129]
	v_mfma_f32_16x16x32_bf16 v[122:125], v[154:157], v[168:171], v[122:125]
	v_mfma_f32_16x16x32_bf16 v[110:113], v[146:149], v[176:179], v[110:113]
	v_mfma_f32_16x16x32_bf16 v[106:109], v[154:157], v[176:179], v[106:109]
	v_mfma_f32_16x16x32_bf16 v[94:97], v[146:149], v[190:193], v[94:97]
	v_mfma_f32_16x16x32_bf16 v[90:93], v[154:157], v[190:193], v[90:93]
	v_mfma_f32_16x16x32_bf16 v[76:79], v[146:149], v[198:201], v[76:79]
	v_mfma_f32_16x16x32_bf16 v[72:75], v[154:157], v[198:201], v[72:75]
	s_setprio 0
	s_barrier
	s_add_i32 s22, 0, 0x14000
	v_add_u32_e32 v80, s22, v139
	ds_read_b128 v[202:205], v80
	ds_read_b128 v[206:209], v80 offset:1024
	ds_read_b128 v[210:213], v80 offset:2048
	ds_read_b128 v[214:217], v80 offset:3072
	v_mov_b32_e32 v80, v135
	s_add_i32 s35, s76, s18
	s_mov_b32 m0, s35
	s_nop 0
	global_load_lds_dwordx4 v80, s[44:45]
	v_mov_b32_e32 v80, v137
	s_add_i32 m0, s35, 0x2000
	s_nop 0
	global_load_lds_dwordx4 v80, s[44:45]
	s_barrier
	s_waitcnt lgkmcnt(0)
	s_setprio 1
	s_waitcnt lgkmcnt(0)
	v_mfma_f32_16x16x32_bf16 v[118:121], v[202:205], v[164:167], v[118:121]
	v_mfma_f32_16x16x32_bf16 v[114:117], v[210:213], v[164:167], v[114:117]
	v_mfma_f32_16x16x32_bf16 v[102:105], v[202:205], v[172:175], v[102:105]
	v_mfma_f32_16x16x32_bf16 v[98:101], v[210:213], v[172:175], v[98:101]
	v_mfma_f32_16x16x32_bf16 v[86:89], v[202:205], v[184:187], v[86:89]
	v_mfma_f32_16x16x32_bf16 v[82:85], v[210:213], v[184:187], v[82:85]
	v_mfma_f32_16x16x32_bf16 v[68:71], v[202:205], v[194:197], v[68:71]
	v_mfma_f32_16x16x32_bf16 v[64:67], v[210:213], v[194:197], v[64:67]
	v_mfma_f32_16x16x32_bf16 v[118:121], v[206:209], v[168:171], v[118:121]
	v_mfma_f32_16x16x32_bf16 v[114:117], v[214:217], v[168:171], v[114:117]
	v_mfma_f32_16x16x32_bf16 v[102:105], v[206:209], v[176:179], v[102:105]
	v_mfma_f32_16x16x32_bf16 v[98:101], v[214:217], v[176:179], v[98:101]
	v_mfma_f32_16x16x32_bf16 v[86:89], v[206:209], v[190:193], v[86:89]
	v_mfma_f32_16x16x32_bf16 v[82:85], v[214:217], v[190:193], v[82:85]
	v_mfma_f32_16x16x32_bf16 v[68:71], v[206:209], v[198:201], v[68:71]
	v_mfma_f32_16x16x32_bf16 v[64:67], v[214:217], v[198:201], v[64:67]
	s_setprio 0
	v_mov_b32_e32 v80, v134
	s_mov_b32 m0, s19
	s_barrier
	ds_read_b128 v[164:167], v141 offset:16384
	ds_read_b128 v[168:171], v141 offset:17408
	ds_read_b128 v[172:175], v141 offset:18432
	ds_read_b128 v[176:179], v141 offset:19456
	ds_read_b128 v[184:187], v141 offset:20480
	ds_read_b128 v[190:193], v141 offset:21504
	ds_read_b128 v[194:197], v141 offset:22528
	ds_read_b128 v[198:201], v141 offset:23552
	s_nop 0
	global_load_lds_dwordx4 v80, s[42:43]
	v_mov_b32_e32 v80, v136
	s_mov_b32 m0, s46
	s_nop 0
	global_load_lds_dwordx4 v80, s[42:43]
	s_barrier
	s_waitcnt lgkmcnt(0)
	s_setprio 1
	s_waitcnt lgkmcnt(0)
	v_mfma_f32_16x16x32_bf16 v[60:63], v[142:145], v[164:167], v[60:63]
	v_mfma_f32_16x16x32_bf16 v[56:59], v[150:153], v[164:167], v[56:59]
	v_mfma_f32_16x16x32_bf16 v[44:47], v[142:145], v[172:175], v[44:47]
	v_mfma_f32_16x16x32_bf16 v[40:43], v[150:153], v[172:175], v[40:43]
	v_mfma_f32_16x16x32_bf16 v[28:31], v[142:145], v[184:187], v[28:31]
	v_mfma_f32_16x16x32_bf16 v[24:27], v[150:153], v[184:187], v[24:27]
	v_mfma_f32_16x16x32_bf16 v[12:15], v[142:145], v[194:197], v[12:15]
	v_mfma_f32_16x16x32_bf16 v[8:11], v[150:153], v[194:197], v[8:11]
	v_mfma_f32_16x16x32_bf16 v[60:63], v[146:149], v[168:171], v[60:63]
	v_mfma_f32_16x16x32_bf16 v[56:59], v[154:157], v[168:171], v[56:59]
	v_mfma_f32_16x16x32_bf16 v[44:47], v[146:149], v[176:179], v[44:47]
	v_mfma_f32_16x16x32_bf16 v[40:43], v[154:157], v[176:179], v[40:43]
	v_mfma_f32_16x16x32_bf16 v[28:31], v[146:149], v[190:193], v[28:31]
	v_mfma_f32_16x16x32_bf16 v[24:27], v[154:157], v[190:193], v[24:27]
	v_mfma_f32_16x16x32_bf16 v[12:15], v[146:149], v[198:201], v[12:15]
	v_mfma_f32_16x16x32_bf16 v[8:11], v[154:157], v[198:201], v[8:11]
	s_setprio 0
	s_barrier
; #define G_STAGE(bufoff, gbase, voff) do { _Pragma("unroll") for (int _i = 0; _i < 2; ++_i) { unsigned _vo = (voff)[_i]; asm volatile("" : "+v"(_vo));   \
;     __builtin_amdgcn_global_load_lds((const unsigned*)((const char*)(gbase) + _vo), (LAS unsigned*)(lds + (bufoff) + ldsw + _i * 8192), 16, 0, 0); } } while (0)
; #define G_LDA(dst, b, h) do { _Pragma("unroll") for (int m = 0; m < 4; ++m) _Pragma("unroll") for (int k = 0; k < 2; ++k) dst[m][k] = *(const LAS bf16x8*)(lds + G_SA(b, h) + aoff + m * 2048 + k * 1024); } while (0)
; #define G_LDB(dst, b, h) do { _Pragma("unroll") for (int n = 0; n < 2; ++n) _Pragma("unroll") for (int k = 0; k < 2; ++k) dst[n][k] = *(const LAS bf16x8*)(lds + G_SB(b, h) + boff + n * 2048 + k * 1024); } while (0)
; #define G_MMA(ai, bj, At, Bt) do { __builtin_amdgcn_s_setprio(1); _Pragma("unroll") for (int m = 0; m < 4; ++m) _Pragma("unroll") for (int n = 0; n < 2; ++n) _Pragma("unroll") for (int k = 0; k < 2; ++k) \
;     acc[ai][bj][m][n] = __builtin_amdgcn_mfma_f32_16x16x32_bf16(Bt[n][k], At[m][k], acc[ai][bj][m][n], 0, 0, 0); __builtin_amdgcn_s_setprio(0); } while (0)
; #define G_WAIT_V(n) asm volatile("s_waitcnt vmcnt(" #n ")" ::: "memory")
; template <class Epi>
; __device__ __forceinline__ void gemm_phase(LAS unsigned char* lds, const int K, const unsigned lda_b, const unsigned ldb_b, const Map& M, const Epi& E) {
;     ...
;       G_LDB(B0, 0, 0); G_SCHED; G_LDA(At, 0, 0); G_STAGE(G_SA(1, 1), a1h1, voffA);
;       G_WAIT_L(8); G_BAR; G_WAIT_L(0); G_MMA(0, 0, At, B0); G_BAR; G_SCHED;
;       G_LDB(B1, 0, 1); G_STAGE(G_SB(0, 0), b2h0, voffB);
;       G_BAR; G_WAIT_L(0); G_MMA(0, 1, At, B1); G_BAR;
;       G_LDA(At, 0, 1); G_STAGE(G_SA(0, 0), a2h0, voffA);
;       G_BAR; G_WAIT_L(0); G_MMA(1, 0, At, B0); G_BAR; G_SCHED;
;       G_STAGE(G_SB(0, 1), b2h1, voffB);
;       G_WAIT_V(6); G_BAR; G_MMA(1, 1, At, B1); G_BAR;
;       G_LDB(B0, 1, 0); G_SCHED; G_LDA(At, 1, 0); G_STAGE(G_SA(0, 1), a2h1, voffA);
;       G_WAIT_L(8); G_BAR; G_WAIT_L(0); G_MMA(0, 0, At, B0); G_BAR; G_SCHED;
;       G_LDB(B1, 1, 1); G_STAGE(G_SB(1, 0), b2h0 + kstep, voffB);
;       G_BAR; G_WAIT_L(0); G_MMA(0, 1, At, B1); G_BAR;
;       G_LDA(At, 1, 1); G_STAGE(G_SA(1, 0), a2h0 + kstep, voffA);
;       G_BAR; G_WAIT_L(0); G_MMA(1, 0, At, B0); G_BAR; G_SCHED;
;       G_STAGE(G_SB(1, 1), b2h1 + kstep, voffB);
;       G_WAIT_V(6); G_BAR; G_MMA(1, 1, At, B1); G_BAR;
	v_mov_b32_e32 v80, v135
	s_add_i32 s22, s22, s18
	s_mov_b32 m0, s22
	s_nop 0
	global_load_lds_dwordx4 v80, s[38:39]
	v_mov_b32_e32 v80, v137
	s_add_i32 m0, s22, 0x2000
	s_nop 0
	global_load_lds_dwordx4 v80, s[38:39]
	s_waitcnt vmcnt(6)
	s_barrier
	s_setprio 1
	v_mfma_f32_16x16x32_bf16 v[52:55], v[202:205], v[164:167], v[52:55]
	v_mfma_f32_16x16x32_bf16 v[48:51], v[210:213], v[164:167], v[48:51]
	v_mfma_f32_16x16x32_bf16 v[36:39], v[202:205], v[172:175], v[36:39]
	v_mfma_f32_16x16x32_bf16 v[32:35], v[210:213], v[172:175], v[32:35]
	v_mfma_f32_16x16x32_bf16 v[20:23], v[202:205], v[184:187], v[20:23]
	v_mfma_f32_16x16x32_bf16 v[16:19], v[210:213], v[184:187], v[16:19]
	v_mfma_f32_16x16x32_bf16 v[4:7], v[202:205], v[194:197], v[4:7]
	v_mfma_f32_16x16x32_bf16 v[0:3], v[210:213], v[194:197], v[0:3]
	v_mfma_f32_16x16x32_bf16 v[52:55], v[206:209], v[168:171], v[52:55]
	v_mfma_f32_16x16x32_bf16 v[48:51], v[214:217], v[168:171], v[48:51]
	v_mfma_f32_16x16x32_bf16 v[36:39], v[206:209], v[176:179], v[36:39]
	v_mfma_f32_16x16x32_bf16 v[32:35], v[214:217], v[176:179], v[32:35]
	v_mfma_f32_16x16x32_bf16 v[20:23], v[206:209], v[190:193], v[20:23]
	v_mfma_f32_16x16x32_bf16 v[16:19], v[214:217], v[190:193], v[16:19]
	v_mfma_f32_16x16x32_bf16 v[4:7], v[206:209], v[198:201], v[4:7]
	v_mfma_f32_16x16x32_bf16 v[0:3], v[214:217], v[198:201], v[0:3]
	s_setprio 0
	s_add_i32 s22, 0, 0x18000
	v_add_u32_e32 v80, s22, v139
	s_barrier
	ds_read_b128 v[142:145], v80
	ds_read_b128 v[146:149], v80 offset:1024
	ds_read_b128 v[150:153], v80 offset:2048
	ds_read_b128 v[154:157], v80 offset:3072
	v_mov_b32_e32 v80, v134
	s_mov_b32 m0, s47
	ds_read_b128 v[164:167], v141 offset:32768
	ds_read_b128 v[168:171], v141 offset:33792
	ds_read_b128 v[172:175], v141 offset:34816
	ds_read_b128 v[176:179], v141 offset:35840
	ds_read_b128 v[184:187], v141 offset:36864
	ds_read_b128 v[190:193], v141 offset:37888
	ds_read_b128 v[194:197], v141 offset:38912
	ds_read_b128 v[198:201], v141 offset:39936
	s_nop 0
	global_load_lds_dwordx4 v80, s[68:69]
	v_mov_b32_e32 v80, v136
	s_mov_b32 m0, s48
	s_nop 0
	global_load_lds_dwordx4 v80, s[68:69]
	s_waitcnt lgkmcnt(8)
	s_barrier
	s_waitcnt lgkmcnt(0)
	s_setprio 1
	s_waitcnt lgkmcnt(0)
	v_mfma_f32_16x16x32_bf16 v[126:129], v[142:145], v[164:167], v[126:129]
	v_mfma_f32_16x16x32_bf16 v[122:125], v[150:153], v[164:167], v[122:125]
	v_mfma_f32_16x16x32_bf16 v[110:113], v[142:145], v[172:175], v[110:113]
	v_mfma_f32_16x16x32_bf16 v[106:109], v[150:153], v[172:175], v[106:109]
	v_mfma_f32_16x16x32_bf16 v[94:97], v[142:145], v[184:187], v[94:97]
	v_mfma_f32_16x16x32_bf16 v[90:93], v[150:153], v[184:187], v[90:93]
	v_mfma_f32_16x16x32_bf16 v[76:79], v[142:145], v[194:197], v[76:79]
	v_mfma_f32_16x16x32_bf16 v[72:75], v[150:153], v[194:197], v[72:75]
	v_mfma_f32_16x16x32_bf16 v[126:129], v[146:149], v[168:171], v[126:129]
	v_mfma_f32_16x16x32_bf16 v[122:125], v[154:157], v[168:171], v[122:125]
	v_mfma_f32_16x16x32_bf16 v[110:113], v[146:149], v[176:179], v[110:113]
	v_mfma_f32_16x16x32_bf16 v[106:109], v[154:157], v[176:179], v[106:109]
	v_mfma_f32_16x16x32_bf16 v[94:97], v[146:149], v[190:193], v[94:97]
	v_mfma_f32_16x16x32_bf16 v[90:93], v[154:157], v[190:193], v[90:93]
	v_mfma_f32_16x16x32_bf16 v[76:79], v[146:149], v[198:201], v[76:79]
	v_mfma_f32_16x16x32_bf16 v[72:75], v[154:157], v[198:201], v[72:75]
	s_setprio 0
	s_barrier
	s_add_i32 s35, 0, 0x1c000
	v_add_u32_e32 v80, s35, v139
	ds_read_b128 v[202:205], v80
	ds_read_b128 v[206:209], v80 offset:1024
	ds_read_b128 v[210:213], v80 offset:2048
	ds_read_b128 v[214:217], v80 offset:3072
	v_mov_b32_e32 v80, v135
	s_add_i32 s22, s22, s18
	s_add_i32 m0, s22, 0xffffff80
	v_mov_b32_e32 v80, v137
	global_load_lds_dwordx4 v135, s[44:45] offset:128
	s_add_i32 m0, s22, 0x1f80
	s_nop 0
	global_load_lds_dwordx4 v137, s[44:45] offset:128
	s_barrier
	s_waitcnt lgkmcnt(0)
	s_setprio 1
	s_waitcnt lgkmcnt(0)
	v_mfma_f32_16x16x32_bf16 v[118:121], v[202:205], v[164:167], v[118:121]
	v_mfma_f32_16x16x32_bf16 v[114:117], v[210:213], v[164:167], v[114:117]
	v_mfma_f32_16x16x32_bf16 v[102:105], v[202:205], v[172:175], v[102:105]
	v_mfma_f32_16x16x32_bf16 v[98:101], v[210:213], v[172:175], v[98:101]
	v_mfma_f32_16x16x32_bf16 v[86:89], v[202:205], v[184:187], v[86:89]
	v_mfma_f32_16x16x32_bf16 v[82:85], v[210:213], v[184:187], v[82:85]
	v_mfma_f32_16x16x32_bf16 v[68:71], v[202:205], v[194:197], v[68:71]
	v_mfma_f32_16x16x32_bf16 v[64:67], v[210:213], v[194:197], v[64:67]
	v_mfma_f32_16x16x32_bf16 v[118:121], v[206:209], v[168:171], v[118:121]
	v_mfma_f32_16x16x32_bf16 v[114:117], v[214:217], v[168:171], v[114:117]
	v_mfma_f32_16x16x32_bf16 v[102:105], v[206:209], v[176:179], v[102:105]
	v_mfma_f32_16x16x32_bf16 v[98:101], v[214:217], v[176:179], v[98:101]
	v_mfma_f32_16x16x32_bf16 v[86:89], v[206:209], v[190:193], v[86:89]
	v_mfma_f32_16x16x32_bf16 v[82:85], v[214:217], v[190:193], v[82:85]
	v_mfma_f32_16x16x32_bf16 v[68:71], v[206:209], v[198:201], v[68:71]
	v_mfma_f32_16x16x32_bf16 v[64:67], v[214:217], v[198:201], v[64:67]
	s_setprio 0
	v_mov_b32_e32 v80, v134
	s_barrier
	ds_read_b128 v[164:167], v141 offset:49152
	ds_read_b128 v[168:171], v141 offset:50176
	ds_read_b128 v[172:175], v141 offset:51200
	ds_read_b128 v[176:179], v141 offset:52224
	ds_read_b128 v[184:187], v141 offset:53248
	ds_read_b128 v[190:193], v141 offset:54272
	ds_read_b128 v[194:197], v141 offset:55296
	ds_read_b128 v[198:201], v141 offset:56320
	s_add_i32 m0, s49, 0xffffff80
	v_mov_b32_e32 v80, v136
	global_load_lds_dwordx4 v134, s[42:43] offset:128
	s_add_i32 m0, s61, 0xffffff80
	s_nop 0
	global_load_lds_dwordx4 v136, s[42:43] offset:128
	s_barrier
; __device__ __forceinline__ unsigned cvt_pk_bf16(float lo, float hi) { unsigned r; asm("v_cvt_pk_bf16_f32 %0, %1, %2" : "=v"(r) : "v"(lo), "v"(hi)); return r; }
; __device__ __forceinline__ float bf_lo(unsigned u) { return __uint_as_float(u << 16); }
; __device__ __forceinline__ float bf_hi(unsigned u) { return __uint_as_float(u & 0xffff0000u); }
; __device__ __forceinline__ unsigned long long ss_fix(float s) { return (unsigned long long)(s * 16777216.f); }
; #define G_WAIT_V(n) asm volatile("s_waitcnt vmcnt(" #n ")" ::: "memory")
;   __device__ __forceinline__ void operator()(const f32x4 (&acc)[2][2][4][2], const Unit& u, const EpiCtx& x_, int wr, int wc, int fr, int fq) const {
;     ...
;     for (int ai = 0; ai < 2; ++ai)
; #pragma unroll
;       for (int m = 0; m < 4; ++m) {
;         const int row = (u.r0 + (ai ? x_.rdelta : 0)) + wr * 64 + m * 16 + fr;
;         const bf16_t* xin = (const bf16_t*)x_.aux + (size_t)row * DM;
;         bf16_t* xbp = x_.xb + (size_t)row * DM;
;         float sq = 0.f;
; #pragma unroll
;         for (int bj = 0; bj < 2; ++bj) {
;           const int cb = u.c0 + wc * 64 + bj * 32 + 8 * fq;
;           const uint4 xi = *(const uint4*)(xin + cb); const f32x4 a = acc[ai][bj][m][0], b = acc[ai][bj][m][1];
;           const float x0 = bf_lo(xi.x) + a[0], x1 = bf_hi(xi.x) + a[1], x2 = bf_lo(xi.y) + a[2], x3 = bf_hi(xi.y) + a[3];
;           const float x4 = bf_lo(xi.z) + b[0], x5 = bf_hi(xi.z) + b[1], x6 = bf_lo(xi.w) + b[2], x7 = bf_hi(xi.w) + b[3];
;           sq += x0 * x0 + x1 * x1 + x2 * x2 + x3 * x3 + x4 * x4 + x5 * x5 + x6 * x6 + x7 * x7;
;           uint4 o; o.x = cvt_pk_bf16(x0, x1); o.y = cvt_pk_bf16(x2, x3); o.z = cvt_pk_bf16(x4, x5); o.w = cvt_pk_bf16(x6, x7);
;           *(uint4*)(xbp + cb) = o;
;         }
;         sq += __shfl_xor(sq, 16); sq += __shfl_xor(sq, 32);
;         if (fq == 0) atomicAdd(x_.sso + row, ss_fix(sq));
; template <class Epi>
; __device__ __forceinline__ void gemm_phase(LAS unsigned char* lds, const int K, const unsigned lda_b, const unsigned ldb_b, const Map& M, const Epi& E) {
;     ...
;       G_BAR; G_WAIT_L(0); G_MMA(0, 1, At, B1); G_BAR;
;       G_LDA(At, 1, 1); G_STAGE(G_SA(1, 0), a2h0 + kstep, voffA);
;       G_BAR; G_WAIT_L(0); G_MMA(1, 0, At, B0); G_BAR; G_SCHED;
;       G_STAGE(G_SB(1, 1), b2h1 + kstep, voffB);
;       G_WAIT_V(6); G_BAR; G_MMA(1, 1, At, B1); G_BAR;
	s_waitcnt lgkmcnt(0)
	s_setprio 1
	s_waitcnt lgkmcnt(0)
	v_mfma_f32_16x16x32_bf16 v[60:63], v[142:145], v[164:167], v[60:63]
	v_mfma_f32_16x16x32_bf16 v[56:59], v[150:153], v[164:167], v[56:59]
	v_mfma_f32_16x16x32_bf16 v[44:47], v[142:145], v[172:175], v[44:47]
	v_mfma_f32_16x16x32_bf16 v[40:43], v[150:153], v[172:175], v[40:43]
	v_mfma_f32_16x16x32_bf16 v[28:31], v[142:145], v[184:187], v[28:31]
	v_mfma_f32_16x16x32_bf16 v[24:27], v[150:153], v[184:187], v[24:27]
	v_mfma_f32_16x16x32_bf16 v[12:15], v[142:145], v[194:197], v[12:15]
	v_mfma_f32_16x16x32_bf16 v[8:11], v[150:153], v[194:197], v[8:11]
	v_mfma_f32_16x16x32_bf16 v[60:63], v[146:149], v[168:171], v[60:63]
	v_mfma_f32_16x16x32_bf16 v[56:59], v[154:157], v[168:171], v[56:59]
	v_mfma_f32_16x16x32_bf16 v[44:47], v[146:149], v[176:179], v[44:47]
	v_mfma_f32_16x16x32_bf16 v[40:43], v[154:157], v[176:179], v[40:43]
	v_mfma_f32_16x16x32_bf16 v[28:31], v[146:149], v[190:193], v[28:31]
	v_mfma_f32_16x16x32_bf16 v[24:27], v[154:157], v[190:193], v[24:27]
	v_mfma_f32_16x16x32_bf16 v[12:15], v[146:149], v[198:201], v[12:15]
	v_mfma_f32_16x16x32_bf16 v[8:11], v[154:157], v[198:201], v[8:11]
	s_setprio 0
	s_barrier
	v_mov_b32_e32 v80, v135
	s_add_i32 s22, s35, s18
	s_add_i32 m0, s22, 0xffffff80
	v_mov_b32_e32 v80, v137
	global_load_lds_dwordx4 v135, s[38:39] offset:128
	s_add_i32 m0, s22, 0x1f80
	s_nop 0
	global_load_lds_dwordx4 v137, s[38:39] offset:128
	s_waitcnt vmcnt(6)
	s_barrier
	s_setprio 1
	v_mfma_f32_16x16x32_bf16 v[52:55], v[202:205], v[164:167], v[52:55]
	v_mfma_f32_16x16x32_bf16 v[48:51], v[210:213], v[164:167], v[48:51]
	v_mfma_f32_16x16x32_bf16 v[36:39], v[202:205], v[172:175], v[36:39]
	v_mfma_f32_16x16x32_bf16 v[32:35], v[210:213], v[172:175], v[32:35]
	v_mfma_f32_16x16x32_bf16 v[20:23], v[202:205], v[184:187], v[20:23]
	v_mfma_f32_16x16x32_bf16 v[16:19], v[210:213], v[184:187], v[16:19]
	v_mfma_f32_16x16x32_bf16 v[4:7], v[202:205], v[194:197], v[4:7]
	v_mfma_f32_16x16x32_bf16 v[0:3], v[210:213], v[194:197], v[0:3]
	v_mfma_f32_16x16x32_bf16 v[52:55], v[206:209], v[168:171], v[52:55]
	v_mfma_f32_16x16x32_bf16 v[48:51], v[214:217], v[168:171], v[48:51]
	v_mfma_f32_16x16x32_bf16 v[36:39], v[206:209], v[176:179], v[36:39]
	v_mfma_f32_16x16x32_bf16 v[32:35], v[214:217], v[176:179], v[32:35]
	v_mfma_f32_16x16x32_bf16 v[20:23], v[206:209], v[190:193], v[20:23]
	v_mfma_f32_16x16x32_bf16 v[16:19], v[214:217], v[190:193], v[16:19]
	v_mfma_f32_16x16x32_bf16 v[4:7], v[206:209], v[198:201], v[4:7]
	v_mfma_f32_16x16x32_bf16 v[0:3], v[214:217], v[198:201], v[0:3]
	s_setprio 0
	s_add_i32 s34, s34, 2
	s_add_u32 s30, s30, 0x100
	s_addc_u32 s31, s31, 0
	s_add_u32 s2, s2, 0x100
	s_addc_u32 s3, s3, 0
	s_cmp_gt_u32 s34, 61
	s_barrier
	s_cbranch_scc0 .LBB0_554
	s_nop 1
	v_add_u32_e32 v194, s75, v138
	v_add_u32_e32 v196, s0, v140
	v_ashrrev_i32_e32 v195, 31, v194
	v_lshlrev_b64 v[198:199], 12, v[194:195]
	v_ashrrev_i32_e32 v197, 31, v196
	v_lshl_add_u64 v[200:201], s[8:9], 0, v[198:199]
	v_lshlrev_b64 v[202:203], 1, v[196:197]
	v_lshl_add_u64 v[204:205], v[200:201], 0, v[202:203]
	global_load_dwordx4 v[150:153], v[204:205], off
	global_load_dwordx4 v[154:157], v[204:205], off offset:64
	v_add_u32_e32 v198, 16, v194
	v_ashrrev_i32_e32 v195, 31, v198
	v_mov_b32_e32 v200, v198
	v_mov_b32_e32 v201, v195
	v_lshlrev_b64 v[204:205], 12, v[200:201]
	v_lshl_add_u64 v[200:201], s[8:9], 0, v[204:205]
	v_lshl_add_u64 v[206:207], v[200:201], 0, v[202:203]
	global_load_dwordx4 v[164:167], v[206:207], off
	global_load_dwordx4 v[168:171], v[206:207], off offset:64
	v_add_u32_e32 v198, 32, v194
	v_ashrrev_i32_e32 v195, 31, v198
	v_mov_b32_e32 v200, v198
	v_mov_b32_e32 v201, v195
	v_lshlrev_b64 v[204:205], 12, v[200:201]
	v_lshl_add_u64 v[200:201], s[8:9], 0, v[204:205]
	v_lshl_add_u64 v[206:207], v[200:201], 0, v[202:203]
	global_load_dwordx4 v[172:175], v[206:207], off
	global_load_dwordx4 v[176:179], v[206:207], off offset:64
	v_add_u32_e32 v198, 48, v194
	v_ashrrev_i32_e32 v195, 31, v198
	v_mov_b32_e32 v200, v198
	v_mov_b32_e32 v201, v195
	v_lshlrev_b64 v[204:205], 12, v[200:201]
	v_lshl_add_u64 v[200:201], s[8:9], 0, v[204:205]
	v_lshl_add_u64 v[206:207], v[200:201], 0, v[202:203]
	global_load_dwordx4 v[184:187], v[206:207], off
	global_load_dwordx4 v[190:193], v[206:207], off offset:64
	v_add_u32_e32 v132, s75, v138
	v_readfirstlane_b32 s38, v130
	v_add_u32_e32 v130, s0, v140
	v_ashrrev_i32_e32 v133, 31, v132
	v_readfirstlane_b32 s39, v131
	v_lshlrev_b64 v[142:143], 12, v[132:133]
	v_ashrrev_i32_e32 v131, 31, v130
	v_lshl_add_u64 v[144:145], s[8:9], 0, v[142:143]
	v_lshlrev_b64 v[130:131], 1, v[130:131]
	v_lshl_add_u64 v[148:149], v[144:145], 0, v[130:131]
	v_lshl_add_u64 v[146:147], s[36:37], 0, v[142:143]
	s_nop 0
	s_nop 0
	s_waitcnt lgkmcnt(0)
	s_nop 0
	s_waitcnt vmcnt(7)
	v_lshlrev_b32_e32 v80, 16, v150
	v_add_f32_e32 v80, v126, v80
	v_and_b32_e32 v126, 0xffff0000, v150
	v_add_f32_e32 v126, v127, v126
	v_lshlrev_b32_e32 v127, 16, v151
	v_add_f32_e32 v127, v128, v127
	v_and_b32_e32 v128, 0xffff0000, v151
	v_add_f32_e32 v128, v129, v128
	v_lshlrev_b32_e32 v129, 16, v152
	v_add_f32_e32 v129, v122, v129
	v_and_b32_e32 v122, 0xffff0000, v152
	v_mul_f32_e32 v144, v126, v126
	v_fmac_f32_e32 v144, v80, v80
	v_fmac_f32_e32 v144, v127, v127
	v_fmac_f32_e32 v144, v128, v128
	v_add_f32_e32 v142, v123, v122
	v_lshlrev_b32_e32 v122, 16, v153
	v_fmac_f32_e32 v144, v129, v129
	v_add_f32_e32 v143, v124, v122
	v_and_b32_e32 v122, 0xffff0000, v153
	v_fmac_f32_e32 v144, v142, v142
	v_add_f32_e32 v125, v125, v122
	v_fmac_f32_e32 v144, v143, v143
	v_cvt_pk_bf16_f32 v122, v80, v126
	v_cvt_pk_bf16_f32 v123, v127, v128
	v_lshl_add_u64 v[126:127], v[146:147], 0, v[130:131]
	v_fmac_f32_e32 v144, v125, v125
	v_cvt_pk_bf16_f32 v124, v129, v142
	v_cvt_pk_bf16_f32 v125, v143, v125
	global_store_dwordx4 v[126:127], v[122:125], off nt
	s_nop 0
	s_waitcnt lgkmcnt(0)
; __device__ __forceinline__ unsigned cvt_pk_bf16(float lo, float hi) { unsigned r; asm("v_cvt_pk_bf16_f32 %0, %1, %2" : "=v"(r) : "v"(lo), "v"(hi)); return r; }
; __device__ __forceinline__ float bf_lo(unsigned u) { return __uint_as_float(u << 16); }
; __device__ __forceinline__ float bf_hi(unsigned u) { return __uint_as_float(u & 0xffff0000u); }
; __device__ __forceinline__ unsigned long long ss_fix(float s) { return (unsigned long long)(s * 16777216.f); }
;   __device__ __forceinline__ void operator()(const f32x4 (&acc)[2][2][4][2], const Unit& u, const EpiCtx& x_, int wr, int wc, int fr, int fq) const {
;     ...
;     for (int ai = 0; ai < 2; ++ai)
; #pragma unroll
;       for (int m = 0; m < 4; ++m) {
;         const int row = (u.r0 + (ai ? x_.rdelta : 0)) + wr * 64 + m * 16 + fr;
;         const bf16_t* xin = (const bf16_t*)x_.aux + (size_t)row * DM;
;         bf16_t* xbp = x_.xb + (size_t)row * DM;
;         float sq = 0.f;
; #pragma unroll
;         for (int bj = 0; bj < 2; ++bj) {
;           const int cb = u.c0 + wc * 64 + bj * 32 + 8 * fq;
;           const uint4 xi = *(const uint4*)(xin + cb); const f32x4 a = acc[ai][bj][m][0], b = acc[ai][bj][m][1];
;           const float x0 = bf_lo(xi.x) + a[0], x1 = bf_hi(xi.x) + a[1], x2 = bf_lo(xi.y) + a[2], x3 = bf_hi(xi.y) + a[3];
;           const float x4 = bf_lo(xi.z) + b[0], x5 = bf_hi(xi.z) + b[1], x6 = bf_lo(xi.w) + b[2], x7 = bf_hi(xi.w) + b[3];
;           sq += x0 * x0 + x1 * x1 + x2 * x2 + x3 * x3 + x4 * x4 + x5 * x5 + x6 * x6 + x7 * x7;
;           uint4 o; o.x = cvt_pk_bf16(x0, x1); o.y = cvt_pk_bf16(x2, x3); o.z = cvt_pk_bf16(x4, x5); o.w = cvt_pk_bf16(x6, x7);
;           *(uint4*)(xbp + cb) = o;
;         }
;         sq += __shfl_xor(sq, 16); sq += __shfl_xor(sq, 32);
;         if (fq == 0) atomicAdd(x_.sso + row, ss_fix(sq));
	s_nop 0
	s_waitcnt vmcnt(7)
	v_lshlrev_b32_e32 v80, 16, v154
	v_add_f32_e32 v80, v118, v80
	v_and_b32_e32 v118, 0xffff0000, v154
	v_add_f32_e32 v118, v119, v118
	v_lshlrev_b32_e32 v119, 16, v155
	v_add_f32_e32 v119, v120, v119
	v_and_b32_e32 v120, 0xffff0000, v155
	v_add_f32_e32 v120, v121, v120
	v_lshlrev_b32_e32 v121, 16, v156
	v_add_f32_e32 v121, v114, v121
	v_and_b32_e32 v114, 0xffff0000, v156
	v_add_f32_e32 v122, v115, v114
	v_lshlrev_b32_e32 v114, 16, v157
	v_add_f32_e32 v123, v116, v114
	v_and_b32_e32 v114, 0xffff0000, v157
	v_add_f32_e32 v117, v117, v114
	v_mul_f32_e32 v114, v118, v118
	v_fmac_f32_e32 v114, v80, v80
	v_fmac_f32_e32 v114, v119, v119
	v_fmac_f32_e32 v114, v120, v120
	v_fmac_f32_e32 v114, v121, v121
	v_fmac_f32_e32 v114, v122, v122
	v_fmac_f32_e32 v114, v123, v123
	v_fmac_f32_e32 v114, v117, v117
	v_add_f32_e32 v124, v144, v114
	v_cvt_pk_bf16_f32 v114, v80, v118
	v_cvt_pk_bf16_f32 v115, v119, v120
	v_cvt_pk_bf16_f32 v116, v121, v122
	v_cvt_pk_bf16_f32 v117, v123, v117
	global_store_dwordx4 v[126:127], v[114:117], off offset:64 nt
	v_xor_b32_e32 v80, 16, v189
	s_nop 0
	v_and_b32_e32 v114, 64, v189
	v_add_u32_e32 v115, 64, v114
	v_cmp_lt_i32_e64 s[2:3], v80, v115
	v_xor_b32_e32 v116, 32, v189
	s_nop 0
	v_cndmask_b32_e64 v80, v189, v80, s[2:3]
	v_lshlrev_b32_e32 v80, 2, v80
	ds_bpermute_b32 v114, v80, v124
	v_cmp_lt_i32_e64 s[2:3], v116, v115
	s_waitcnt lgkmcnt(0)
	v_add_f32_e32 v114, v124, v114
	v_cndmask_b32_e64 v115, v189, v116, s[2:3]
	v_lshlrev_b32_e32 v116, 2, v115
	ds_bpermute_b32 v115, v116, v114
	s_and_saveexec_b64 s[2:3], vcc
	s_cbranch_execz .LBB0_557
	s_waitcnt lgkmcnt(0)
	v_add_f32_e32 v114, v114, v115
	v_mul_f32_e32 v114, 0x4b800000, v114
	v_trunc_f32_e32 v114, v114
	v_mul_f32_e32 v115, 0x2f800000, v114
	v_floor_f32_e32 v115, v115
	v_fmac_f32_e32 v114, 0xcf800000, v115
	v_cvt_u32_f32_e32 v114, v114
	v_cvt_u32_f32_e32 v115, v115
	v_lshl_add_u64 v[118:119], v[132:133], 3, s[40:41]
	global_atomic_add_x2 v[118:119], v[114:115], off
.LBB0_557:
	s_or_b64 exec, exec, s[2:3]
	v_add_u32_e32 v114, 16, v132
	s_waitcnt lgkmcnt(0)
	v_ashrrev_i32_e32 v115, 31, v114
	v_lshlrev_b64 v[118:119], 12, v[114:115]
	v_lshl_add_u64 v[120:121], s[8:9], 0, v[118:119]
	v_lshl_add_u64 v[124:125], v[120:121], 0, v[130:131]
	v_lshl_add_u64 v[122:123], s[36:37], 0, v[118:119]
	s_nop 0
	s_waitcnt lgkmcnt(0)
	s_nop 0
	s_waitcnt vmcnt(7)
	v_lshlrev_b32_e32 v117, 16, v164
	v_add_f32_e32 v110, v110, v117
	v_and_b32_e32 v117, 0xffff0000, v164
	v_add_f32_e32 v111, v111, v117
	v_lshlrev_b32_e32 v117, 16, v165
	v_add_f32_e32 v112, v112, v117
	v_and_b32_e32 v117, 0xffff0000, v165
	v_add_f32_e32 v113, v113, v117
	v_lshlrev_b32_e32 v117, 16, v166
	v_add_f32_e32 v117, v106, v117
	v_and_b32_e32 v106, 0xffff0000, v166
	v_mul_f32_e32 v120, v111, v111
	v_fmac_f32_e32 v120, v110, v110
	v_fmac_f32_e32 v120, v112, v112
	v_fmac_f32_e32 v120, v113, v113
	v_add_f32_e32 v118, v107, v106
	v_lshlrev_b32_e32 v106, 16, v167
	v_fmac_f32_e32 v120, v117, v117
	v_add_f32_e32 v119, v108, v106
	v_and_b32_e32 v106, 0xffff0000, v167
	v_fmac_f32_e32 v120, v118, v118
	v_add_f32_e32 v109, v109, v106
	v_fmac_f32_e32 v120, v119, v119
	v_cvt_pk_bf16_f32 v106, v110, v111
	v_lshl_add_u64 v[110:111], v[122:123], 0, v[130:131]
	v_fmac_f32_e32 v120, v109, v109
	v_cvt_pk_bf16_f32 v107, v112, v113
	v_cvt_pk_bf16_f32 v108, v117, v118
	v_cvt_pk_bf16_f32 v109, v119, v109
	global_store_dwordx4 v[110:111], v[106:109], off nt
	s_nop 0
	s_waitcnt lgkmcnt(0)
	s_nop 0
	s_waitcnt vmcnt(7)
	v_lshlrev_b32_e32 v112, 16, v168
	v_and_b32_e32 v106, 0xffff0000, v168
	v_add_f32_e32 v103, v103, v106
	v_lshlrev_b32_e32 v106, 16, v169
	v_add_f32_e32 v104, v104, v106
	v_and_b32_e32 v106, 0xffff0000, v169
	v_add_f32_e32 v105, v105, v106
	v_lshlrev_b32_e32 v106, 16, v170
	v_add_f32_e32 v106, v98, v106
	v_and_b32_e32 v98, 0xffff0000, v170
	v_add_f32_e32 v107, v99, v98
	v_lshlrev_b32_e32 v98, 16, v171
	v_add_f32_e32 v108, v100, v98
	v_and_b32_e32 v98, 0xffff0000, v171
	v_add_f32_e32 v102, v102, v112
	v_add_f32_e32 v101, v101, v98
	v_mul_f32_e32 v98, v103, v103
	v_fmac_f32_e32 v98, v102, v102
	v_fmac_f32_e32 v98, v104, v104
	v_fmac_f32_e32 v98, v105, v105
	v_fmac_f32_e32 v98, v106, v106
	v_fmac_f32_e32 v98, v107, v107
	v_fmac_f32_e32 v98, v108, v108
	v_fmac_f32_e32 v98, v101, v101
	v_add_f32_e32 v109, v120, v98
	v_cvt_pk_bf16_f32 v98, v102, v103
	v_cvt_pk_bf16_f32 v99, v104, v105
	v_cvt_pk_bf16_f32 v100, v106, v107
	v_cvt_pk_bf16_f32 v101, v108, v101
	global_store_dwordx4 v[110:111], v[98:101], off offset:64 nt
	s_nop 1
	ds_bpermute_b32 v98, v80, v109
	s_waitcnt lgkmcnt(0)
	v_add_f32_e32 v98, v109, v98
	ds_bpermute_b32 v99, v116, v98
	s_and_saveexec_b64 s[2:3], vcc
	s_cbranch_execz .LBB0_559
	s_waitcnt lgkmcnt(0)
	v_add_f32_e32 v98, v98, v99
	v_mul_f32_e32 v98, 0x4b800000, v98
	v_trunc_f32_e32 v98, v98
	v_mul_f32_e32 v99, 0x2f800000, v98
	v_floor_f32_e32 v99, v99
	v_fmac_f32_e32 v98, 0xcf800000, v99
	v_cvt_u32_f32_e32 v98, v98
	v_cvt_u32_f32_e32 v99, v99
	v_lshl_add_u64 v[100:101], v[114:115], 3, s[40:41]
	global_atomic_add_x2 v[100:101], v[98:99], off
; __device__ __forceinline__ unsigned cvt_pk_bf16(float lo, float hi) { unsigned r; asm("v_cvt_pk_bf16_f32 %0, %1, %2" : "=v"(r) : "v"(lo), "v"(hi)); return r; }
; __device__ __forceinline__ float bf_lo(unsigned u) { return __uint_as_float(u << 16); }
; __device__ __forceinline__ float bf_hi(unsigned u) { return __uint_as_float(u & 0xffff0000u); }
; __device__ __forceinline__ unsigned long long ss_fix(float s) { return (unsigned long long)(s * 16777216.f); }
;   __device__ __forceinline__ void operator()(const f32x4 (&acc)[2][2][4][2], const Unit& u, const EpiCtx& x_, int wr, int wc, int fr, int fq) const {
;     ...
;     for (int ai = 0; ai < 2; ++ai)
; #pragma unroll
;       for (int m = 0; m < 4; ++m) {
;         const int row = (u.r0 + (ai ? x_.rdelta : 0)) + wr * 64 + m * 16 + fr;
;         const bf16_t* xin = (const bf16_t*)x_.aux + (size_t)row * DM;
;         bf16_t* xbp = x_.xb + (size_t)row * DM;
;         float sq = 0.f;
; #pragma unroll
;         for (int bj = 0; bj < 2; ++bj) {
;           const int cb = u.c0 + wc * 64 + bj * 32 + 8 * fq;
;           const uint4 xi = *(const uint4*)(xin + cb); const f32x4 a = acc[ai][bj][m][0], b = acc[ai][bj][m][1];
;           const float x0 = bf_lo(xi.x) + a[0], x1 = bf_hi(xi.x) + a[1], x2 = bf_lo(xi.y) + a[2], x3 = bf_hi(xi.y) + a[3];
;           const float x4 = bf_lo(xi.z) + b[0], x5 = bf_hi(xi.z) + b[1], x6 = bf_lo(xi.w) + b[2], x7 = bf_hi(xi.w) + b[3];
;           sq += x0 * x0 + x1 * x1 + x2 * x2 + x3 * x3 + x4 * x4 + x5 * x5 + x6 * x6 + x7 * x7;
;           uint4 o; o.x = cvt_pk_bf16(x0, x1); o.y = cvt_pk_bf16(x2, x3); o.z = cvt_pk_bf16(x4, x5); o.w = cvt_pk_bf16(x6, x7);
;           *(uint4*)(xbp + cb) = o;
;         }
;         sq += __shfl_xor(sq, 16); sq += __shfl_xor(sq, 32);
;         if (fq == 0) atomicAdd(x_.sso + row, ss_fix(sq));
.LBB0_559:
	s_or_b64 exec, exec, s[2:3]
	s_nop 1
	v_add_u32_e32 v210, 0x80, v132
	v_ashrrev_i32_e32 v211, 31, v210
	v_lshlrev_b64 v[212:213], 12, v[210:211]
	v_lshl_add_u64 v[214:215], s[8:9], 0, v[212:213]
	v_lshl_add_u64 v[216:217], v[214:215], 0, v[130:131]
	global_load_dwordx4 v[150:153], v[216:217], off
	global_load_dwordx4 v[154:157], v[216:217], off offset:64
	v_add_u32_e32 v210, 0x90, v132
	v_ashrrev_i32_e32 v211, 31, v210
	v_lshlrev_b64 v[212:213], 12, v[210:211]
	v_lshl_add_u64 v[214:215], s[8:9], 0, v[212:213]
	v_lshl_add_u64 v[216:217], v[214:215], 0, v[130:131]
	global_load_dwordx4 v[164:167], v[216:217], off
	global_load_dwordx4 v[168:171], v[216:217], off offset:64
	v_add_u32_e32 v210, 0xa0, v132
	v_ashrrev_i32_e32 v211, 31, v210
	v_lshlrev_b64 v[212:213], 12, v[210:211]
	v_lshl_add_u64 v[214:215], s[8:9], 0, v[212:213]
	v_lshl_add_u64 v[216:217], v[214:215], 0, v[130:131]
	global_load_dwordx4 v[194:197], v[216:217], off
	global_load_dwordx4 v[198:201], v[216:217], off offset:64
	v_add_u32_e32 v210, 0xb0, v132
	v_ashrrev_i32_e32 v211, 31, v210
	v_lshlrev_b64 v[212:213], 12, v[210:211]
	v_lshl_add_u64 v[214:215], s[8:9], 0, v[212:213]
	v_lshl_add_u64 v[216:217], v[214:215], 0, v[130:131]
	global_load_dwordx4 v[202:205], v[216:217], off
	global_load_dwordx4 v[206:209], v[216:217], off offset:64
	v_add_u32_e32 v98, 32, v132
	s_waitcnt lgkmcnt(0)
	v_ashrrev_i32_e32 v99, 31, v98
	v_lshlrev_b64 v[100:101], 12, v[98:99]
	v_lshl_add_u64 v[102:103], s[8:9], 0, v[100:101]
	v_lshl_add_u64 v[106:107], v[102:103], 0, v[130:131]
	v_lshl_add_u64 v[104:105], s[36:37], 0, v[100:101]
	s_nop 0
	s_waitcnt lgkmcnt(0)
	s_nop 0
	s_waitcnt vmcnt(15)
	v_lshlrev_b32_e32 v108, 16, v172
	v_and_b32_e32 v100, 0xffff0000, v172
	v_add_f32_e32 v95, v95, v100
	v_lshlrev_b32_e32 v100, 16, v173
	v_add_f32_e32 v96, v96, v100
	v_and_b32_e32 v100, 0xffff0000, v173
	v_add_f32_e32 v97, v97, v100
	v_lshlrev_b32_e32 v100, 16, v174
	v_add_f32_e32 v100, v90, v100
	v_and_b32_e32 v90, 0xffff0000, v174
	v_add_f32_e32 v101, v91, v90
	v_lshlrev_b32_e32 v90, 16, v175
	v_add_f32_e32 v94, v94, v108
	v_add_f32_e32 v102, v92, v90
	v_and_b32_e32 v90, 0xffff0000, v175
	v_mul_f32_e32 v103, v95, v95
	v_fmac_f32_e32 v103, v94, v94
	v_fmac_f32_e32 v103, v96, v96
	v_fmac_f32_e32 v103, v97, v97
	v_fmac_f32_e32 v103, v100, v100
	v_fmac_f32_e32 v103, v101, v101
	v_add_f32_e32 v93, v93, v90
	v_fmac_f32_e32 v103, v102, v102
	v_cvt_pk_bf16_f32 v90, v94, v95
	v_lshl_add_u64 v[94:95], v[104:105], 0, v[130:131]
	v_fmac_f32_e32 v103, v93, v93
	v_cvt_pk_bf16_f32 v91, v96, v97
	v_cvt_pk_bf16_f32 v92, v100, v101
	v_cvt_pk_bf16_f32 v93, v102, v93
	global_store_dwordx4 v[94:95], v[90:93], off nt
	s_nop 0
	s_waitcnt lgkmcnt(0)
	s_nop 0
	s_waitcnt vmcnt(15)
	v_lshlrev_b32_e32 v96, 16, v176
	v_and_b32_e32 v90, 0xffff0000, v176
	v_add_f32_e32 v87, v87, v90
	v_lshlrev_b32_e32 v90, 16, v177
	v_add_f32_e32 v88, v88, v90
	v_and_b32_e32 v90, 0xffff0000, v177
	v_add_f32_e32 v89, v89, v90
	v_lshlrev_b32_e32 v90, 16, v178
	v_add_f32_e32 v90, v82, v90
	v_and_b32_e32 v82, 0xffff0000, v178
	v_add_f32_e32 v91, v83, v82
	v_lshlrev_b32_e32 v82, 16, v179
	v_add_f32_e32 v92, v84, v82
	v_and_b32_e32 v82, 0xffff0000, v179
	v_add_f32_e32 v86, v86, v96
	v_add_f32_e32 v85, v85, v82
	v_mul_f32_e32 v82, v87, v87
	v_fmac_f32_e32 v82, v86, v86
	v_fmac_f32_e32 v82, v88, v88
	v_fmac_f32_e32 v82, v89, v89
	v_fmac_f32_e32 v82, v90, v90
	v_fmac_f32_e32 v82, v91, v91
	v_fmac_f32_e32 v82, v92, v92
	v_fmac_f32_e32 v82, v85, v85
	v_add_f32_e32 v93, v103, v82
	v_cvt_pk_bf16_f32 v82, v86, v87
	v_cvt_pk_bf16_f32 v83, v88, v89
	v_cvt_pk_bf16_f32 v84, v90, v91
	v_cvt_pk_bf16_f32 v85, v92, v85
	global_store_dwordx4 v[94:95], v[82:85], off offset:64 nt
	s_nop 1
	ds_bpermute_b32 v82, v80, v93
	s_waitcnt lgkmcnt(0)
	v_add_f32_e32 v82, v93, v82
	ds_bpermute_b32 v83, v116, v82
	s_and_saveexec_b64 s[2:3], vcc
	s_cbranch_execz .LBB0_561
	s_waitcnt lgkmcnt(0)
	v_add_f32_e32 v82, v82, v83
	v_mul_f32_e32 v82, 0x4b800000, v82
	v_trunc_f32_e32 v82, v82
	v_mul_f32_e32 v83, 0x2f800000, v82
	v_floor_f32_e32 v83, v83
	v_fmac_f32_e32 v82, 0xcf800000, v83
	v_cvt_u32_f32_e32 v82, v82
	v_cvt_u32_f32_e32 v83, v83
	v_lshl_add_u64 v[84:85], v[98:99], 3, s[40:41]
	global_atomic_add_x2 v[84:85], v[82:83], off
; __device__ __forceinline__ unsigned cvt_pk_bf16(float lo, float hi) { unsigned r; asm("v_cvt_pk_bf16_f32 %0, %1, %2" : "=v"(r) : "v"(lo), "v"(hi)); return r; }
; __device__ __forceinline__ float bf_lo(unsigned u) { return __uint_as_float(u << 16); }
; __device__ __forceinline__ float bf_hi(unsigned u) { return __uint_as_float(u & 0xffff0000u); }
; __device__ __forceinline__ unsigned long long ss_fix(float s) { return (unsigned long long)(s * 16777216.f); }
;   __device__ __forceinline__ void operator()(const f32x4 (&acc)[2][2][4][2], const Unit& u, const EpiCtx& x_, int wr, int wc, int fr, int fq) const {
;     ...
;     for (int ai = 0; ai < 2; ++ai)
; #pragma unroll
;       for (int m = 0; m < 4; ++m) {
;         const int row = (u.r0 + (ai ? x_.rdelta : 0)) + wr * 64 + m * 16 + fr;
;         const bf16_t* xin = (const bf16_t*)x_.aux + (size_t)row * DM;
;         bf16_t* xbp = x_.xb + (size_t)row * DM;
;         float sq = 0.f;
; #pragma unroll
;         for (int bj = 0; bj < 2; ++bj) {
;           const int cb = u.c0 + wc * 64 + bj * 32 + 8 * fq;
;           const uint4 xi = *(const uint4*)(xin + cb); const f32x4 a = acc[ai][bj][m][0], b = acc[ai][bj][m][1];
;           const float x0 = bf_lo(xi.x) + a[0], x1 = bf_hi(xi.x) + a[1], x2 = bf_lo(xi.y) + a[2], x3 = bf_hi(xi.y) + a[3];
;           const float x4 = bf_lo(xi.z) + b[0], x5 = bf_hi(xi.z) + b[1], x6 = bf_lo(xi.w) + b[2], x7 = bf_hi(xi.w) + b[3];
;           sq += x0 * x0 + x1 * x1 + x2 * x2 + x3 * x3 + x4 * x4 + x5 * x5 + x6 * x6 + x7 * x7;
;           uint4 o; o.x = cvt_pk_bf16(x0, x1); o.y = cvt_pk_bf16(x2, x3); o.z = cvt_pk_bf16(x4, x5); o.w = cvt_pk_bf16(x6, x7);
;           *(uint4*)(xbp + cb) = o;
;         }
;         sq += __shfl_xor(sq, 16); sq += __shfl_xor(sq, 32);
;         if (fq == 0) atomicAdd(x_.sso + row, ss_fix(sq));
.LBB0_561:
	s_or_b64 exec, exec, s[2:3]
	v_add_u32_e32 v82, 48, v132
	s_waitcnt lgkmcnt(0)
	v_ashrrev_i32_e32 v83, 31, v82
	v_lshlrev_b64 v[84:85], 12, v[82:83]
	v_lshl_add_u64 v[86:87], s[8:9], 0, v[84:85]
	v_lshl_add_u64 v[90:91], v[86:87], 0, v[130:131]
	v_lshl_add_u64 v[88:89], s[36:37], 0, v[84:85]
	s_nop 0
	s_waitcnt lgkmcnt(0)
	s_nop 0
	s_waitcnt vmcnt(15)
	v_lshlrev_b32_e32 v92, 16, v184
	v_and_b32_e32 v84, 0xffff0000, v184
	v_add_f32_e32 v77, v77, v84
	v_lshlrev_b32_e32 v84, 16, v185
	v_add_f32_e32 v78, v78, v84
	v_and_b32_e32 v84, 0xffff0000, v185
	v_add_f32_e32 v79, v79, v84
	v_lshlrev_b32_e32 v84, 16, v186
	v_add_f32_e32 v84, v72, v84
	v_and_b32_e32 v72, 0xffff0000, v186
	v_add_f32_e32 v85, v73, v72
	v_lshlrev_b32_e32 v72, 16, v187
	v_add_f32_e32 v76, v76, v92
	v_add_f32_e32 v86, v74, v72
	v_and_b32_e32 v72, 0xffff0000, v187
	v_mul_f32_e32 v87, v77, v77
	v_fmac_f32_e32 v87, v76, v76
	v_fmac_f32_e32 v87, v78, v78
	v_fmac_f32_e32 v87, v79, v79
	v_fmac_f32_e32 v87, v84, v84
	v_fmac_f32_e32 v87, v85, v85
	v_add_f32_e32 v75, v75, v72
	v_fmac_f32_e32 v87, v86, v86
	v_cvt_pk_bf16_f32 v72, v76, v77
	v_lshl_add_u64 v[76:77], v[88:89], 0, v[130:131]
	v_fmac_f32_e32 v87, v75, v75
	v_cvt_pk_bf16_f32 v73, v78, v79
	v_cvt_pk_bf16_f32 v74, v84, v85
	v_cvt_pk_bf16_f32 v75, v86, v75
	global_store_dwordx4 v[76:77], v[72:75], off nt
	s_nop 0
	s_waitcnt lgkmcnt(0)
	s_nop 0
	s_waitcnt vmcnt(15)
	v_lshlrev_b32_e32 v78, 16, v190
	v_and_b32_e32 v72, 0xffff0000, v190
	v_add_f32_e32 v69, v69, v72
	v_lshlrev_b32_e32 v72, 16, v191
	v_add_f32_e32 v70, v70, v72
	v_and_b32_e32 v72, 0xffff0000, v191
	v_add_f32_e32 v71, v71, v72
	v_lshlrev_b32_e32 v72, 16, v192
	v_add_f32_e32 v72, v64, v72
	v_and_b32_e32 v64, 0xffff0000, v192
	v_add_f32_e32 v73, v65, v64
	v_lshlrev_b32_e32 v64, 16, v193
	v_add_f32_e32 v74, v66, v64
	v_and_b32_e32 v64, 0xffff0000, v193
	v_add_f32_e32 v68, v68, v78
	v_add_f32_e32 v67, v67, v64
	v_mul_f32_e32 v64, v69, v69
	v_fmac_f32_e32 v64, v68, v68
	v_fmac_f32_e32 v64, v70, v70
	v_fmac_f32_e32 v64, v71, v71
	v_fmac_f32_e32 v64, v72, v72
	v_fmac_f32_e32 v64, v73, v73
	v_fmac_f32_e32 v64, v74, v74
	v_fmac_f32_e32 v64, v67, v67
	v_add_f32_e32 v75, v87, v64
	v_cvt_pk_bf16_f32 v64, v68, v69
	v_cvt_pk_bf16_f32 v65, v70, v71
	v_cvt_pk_bf16_f32 v66, v72, v73
	v_cvt_pk_bf16_f32 v67, v74, v67
	global_store_dwordx4 v[76:77], v[64:67], off offset:64 nt
	s_nop 1
	ds_bpermute_b32 v64, v80, v75
	s_waitcnt lgkmcnt(0)
	v_add_f32_e32 v64, v75, v64
	ds_bpermute_b32 v65, v116, v64
	s_and_saveexec_b64 s[2:3], vcc
	s_cbranch_execz .LBB0_563
	s_waitcnt lgkmcnt(0)
	v_add_f32_e32 v64, v64, v65
	v_mul_f32_e32 v64, 0x4b800000, v64
	v_trunc_f32_e32 v64, v64
	v_mul_f32_e32 v65, 0x2f800000, v64
	v_floor_f32_e32 v65, v65
	v_fmac_f32_e32 v64, 0xcf800000, v65
	v_cvt_u32_f32_e32 v64, v64
	v_cvt_u32_f32_e32 v65, v65
	v_lshl_add_u64 v[66:67], v[82:83], 3, s[40:41]
	global_atomic_add_x2 v[66:67], v[64:65], off
.LBB0_563:
	s_or_b64 exec, exec, s[2:3]
	v_add_u32_e32 v64, 0x80, v132
	s_waitcnt lgkmcnt(0)
	v_ashrrev_i32_e32 v65, 31, v64
	v_lshlrev_b64 v[66:67], 12, v[64:65]
	v_lshl_add_u64 v[68:69], s[8:9], 0, v[66:67]
	v_lshl_add_u64 v[72:73], v[68:69], 0, v[130:131]
	v_lshl_add_u64 v[70:71], s[36:37], 0, v[66:67]
	s_nop 0
	s_waitcnt lgkmcnt(0)
	s_nop 0
	s_waitcnt vmcnt(11)
	v_lshlrev_b32_e32 v74, 16, v150
	v_and_b32_e32 v66, 0xffff0000, v150
	v_add_f32_e32 v61, v61, v66
	v_lshlrev_b32_e32 v66, 16, v151
	v_add_f32_e32 v62, v62, v66
	v_and_b32_e32 v66, 0xffff0000, v151
	v_add_f32_e32 v63, v63, v66
	v_lshlrev_b32_e32 v66, 16, v152
	v_add_f32_e32 v66, v56, v66
	v_and_b32_e32 v56, 0xffff0000, v152
	v_add_f32_e32 v67, v57, v56
	v_lshlrev_b32_e32 v56, 16, v153
	v_add_f32_e32 v60, v60, v74
	v_add_f32_e32 v68, v58, v56
	v_and_b32_e32 v56, 0xffff0000, v153
	v_mul_f32_e32 v69, v61, v61
	v_fmac_f32_e32 v69, v60, v60
	v_fmac_f32_e32 v69, v62, v62
	v_fmac_f32_e32 v69, v63, v63
	v_fmac_f32_e32 v69, v66, v66
	v_fmac_f32_e32 v69, v67, v67
	v_add_f32_e32 v59, v59, v56
	v_fmac_f32_e32 v69, v68, v68
	v_cvt_pk_bf16_f32 v56, v60, v61
	v_lshl_add_u64 v[60:61], v[70:71], 0, v[130:131]
	v_fmac_f32_e32 v69, v59, v59
	v_cvt_pk_bf16_f32 v57, v62, v63
	v_cvt_pk_bf16_f32 v58, v66, v67
	v_cvt_pk_bf16_f32 v59, v68, v59
	global_store_dwordx4 v[60:61], v[56:59], off nt
	s_nop 1
	s_nop 0
	s_waitcnt lgkmcnt(0)
	s_nop 0
	s_waitcnt vmcnt(11)
	v_lshlrev_b32_e32 v62, 16, v154
	v_and_b32_e32 v56, 0xffff0000, v154
	v_add_f32_e32 v53, v53, v56
	v_lshlrev_b32_e32 v56, 16, v155
	v_add_f32_e32 v54, v54, v56
	v_and_b32_e32 v56, 0xffff0000, v155
	v_add_f32_e32 v55, v55, v56
	v_lshlrev_b32_e32 v56, 16, v156
	v_add_f32_e32 v56, v48, v56
	v_and_b32_e32 v48, 0xffff0000, v156
	v_add_f32_e32 v57, v49, v48
	v_lshlrev_b32_e32 v48, 16, v157
	v_add_f32_e32 v58, v50, v48
	v_and_b32_e32 v48, 0xffff0000, v157
	v_add_f32_e32 v52, v52, v62
	v_add_f32_e32 v51, v51, v48
	v_mul_f32_e32 v48, v53, v53
	v_fmac_f32_e32 v48, v52, v52
	v_fmac_f32_e32 v48, v54, v54
	v_fmac_f32_e32 v48, v55, v55
	v_fmac_f32_e32 v48, v56, v56
	v_fmac_f32_e32 v48, v57, v57
	v_fmac_f32_e32 v48, v58, v58
	v_fmac_f32_e32 v48, v51, v51
	v_add_f32_e32 v59, v69, v48
	v_cvt_pk_bf16_f32 v48, v52, v53
	v_cvt_pk_bf16_f32 v49, v54, v55
	v_cvt_pk_bf16_f32 v50, v56, v57
	v_cvt_pk_bf16_f32 v51, v58, v51
	global_store_dwordx4 v[60:61], v[48:51], off offset:64 nt
	s_nop 1
	ds_bpermute_b32 v48, v80, v59
	s_waitcnt lgkmcnt(0)
	v_add_f32_e32 v48, v59, v48
	ds_bpermute_b32 v49, v116, v48
	s_and_saveexec_b64 s[2:3], vcc
	s_cbranch_execz .LBB0_565
	s_waitcnt lgkmcnt(0)
	v_add_f32_e32 v48, v48, v49
	v_mul_f32_e32 v48, 0x4b800000, v48
	v_trunc_f32_e32 v48, v48
	v_mul_f32_e32 v49, 0x2f800000, v48
	v_floor_f32_e32 v49, v49
	v_fmac_f32_e32 v48, 0xcf800000, v49
	v_cvt_u32_f32_e32 v48, v48
	v_cvt_u32_f32_e32 v49, v49
	v_lshl_add_u64 v[50:51], v[64:65], 3, s[40:41]
	global_atomic_add_x2 v[50:51], v[48:49], off
; __device__ __forceinline__ unsigned cvt_pk_bf16(float lo, float hi) { unsigned r; asm("v_cvt_pk_bf16_f32 %0, %1, %2" : "=v"(r) : "v"(lo), "v"(hi)); return r; }
; __device__ __forceinline__ float bf_lo(unsigned u) { return __uint_as_float(u << 16); }
; __device__ __forceinline__ float bf_hi(unsigned u) { return __uint_as_float(u & 0xffff0000u); }
; __device__ __forceinline__ unsigned long long ss_fix(float s) { return (unsigned long long)(s * 16777216.f); }
;   __device__ __forceinline__ void operator()(const f32x4 (&acc)[2][2][4][2], const Unit& u, const EpiCtx& x_, int wr, int wc, int fr, int fq) const {
;     ...
;     for (int ai = 0; ai < 2; ++ai)
; #pragma unroll
;       for (int m = 0; m < 4; ++m) {
;         const int row = (u.r0 + (ai ? x_.rdelta : 0)) + wr * 64 + m * 16 + fr;
;         const bf16_t* xin = (const bf16_t*)x_.aux + (size_t)row * DM;
;         bf16_t* xbp = x_.xb + (size_t)row * DM;
;         float sq = 0.f;
; #pragma unroll
;         for (int bj = 0; bj < 2; ++bj) {
;           const int cb = u.c0 + wc * 64 + bj * 32 + 8 * fq;
;           const uint4 xi = *(const uint4*)(xin + cb); const f32x4 a = acc[ai][bj][m][0], b = acc[ai][bj][m][1];
;           const float x0 = bf_lo(xi.x) + a[0], x1 = bf_hi(xi.x) + a[1], x2 = bf_lo(xi.y) + a[2], x3 = bf_hi(xi.y) + a[3];
;           const float x4 = bf_lo(xi.z) + b[0], x5 = bf_hi(xi.z) + b[1], x6 = bf_lo(xi.w) + b[2], x7 = bf_hi(xi.w) + b[3];
;           sq += x0 * x0 + x1 * x1 + x2 * x2 + x3 * x3 + x4 * x4 + x5 * x5 + x6 * x6 + x7 * x7;
;           uint4 o; o.x = cvt_pk_bf16(x0, x1); o.y = cvt_pk_bf16(x2, x3); o.z = cvt_pk_bf16(x4, x5); o.w = cvt_pk_bf16(x6, x7);
;           *(uint4*)(xbp + cb) = o;
;         }
;         sq += __shfl_xor(sq, 16); sq += __shfl_xor(sq, 32);
;         if (fq == 0) atomicAdd(x_.sso + row, ss_fix(sq));
.LBB0_565:
	s_or_b64 exec, exec, s[2:3]
	v_add_u32_e32 v48, 0x90, v132
	s_waitcnt lgkmcnt(0)
	v_ashrrev_i32_e32 v49, 31, v48
	v_lshlrev_b64 v[50:51], 12, v[48:49]
	v_lshl_add_u64 v[52:53], s[8:9], 0, v[50:51]
	v_lshl_add_u64 v[56:57], v[52:53], 0, v[130:131]
	v_lshl_add_u64 v[54:55], s[36:37], 0, v[50:51]
	s_nop 0
	s_waitcnt lgkmcnt(0)
	s_nop 0
	s_waitcnt vmcnt(11)
	v_lshlrev_b32_e32 v58, 16, v164
	v_and_b32_e32 v50, 0xffff0000, v164
	v_add_f32_e32 v45, v45, v50
	v_lshlrev_b32_e32 v50, 16, v165
	v_add_f32_e32 v46, v46, v50
	v_and_b32_e32 v50, 0xffff0000, v165
	v_add_f32_e32 v47, v47, v50
	v_lshlrev_b32_e32 v50, 16, v166
	v_add_f32_e32 v50, v40, v50
	v_and_b32_e32 v40, 0xffff0000, v166
	v_add_f32_e32 v51, v41, v40
	v_lshlrev_b32_e32 v40, 16, v167
	v_add_f32_e32 v44, v44, v58
	v_add_f32_e32 v52, v42, v40
	v_and_b32_e32 v40, 0xffff0000, v167
	v_mul_f32_e32 v53, v45, v45
	v_fmac_f32_e32 v53, v44, v44
	v_fmac_f32_e32 v53, v46, v46
	v_fmac_f32_e32 v53, v47, v47
	v_fmac_f32_e32 v53, v50, v50
	v_fmac_f32_e32 v53, v51, v51
	v_add_f32_e32 v43, v43, v40
	v_fmac_f32_e32 v53, v52, v52
	v_cvt_pk_bf16_f32 v40, v44, v45
	v_lshl_add_u64 v[44:45], v[54:55], 0, v[130:131]
	v_fmac_f32_e32 v53, v43, v43
	v_cvt_pk_bf16_f32 v41, v46, v47
	v_cvt_pk_bf16_f32 v42, v50, v51
	v_cvt_pk_bf16_f32 v43, v52, v43
	global_store_dwordx4 v[44:45], v[40:43], off nt
	s_nop 1
	s_nop 0
	s_waitcnt lgkmcnt(0)
	s_nop 0
	s_waitcnt vmcnt(11)
	v_lshlrev_b32_e32 v46, 16, v168
	v_and_b32_e32 v40, 0xffff0000, v168
	v_add_f32_e32 v37, v37, v40
	v_lshlrev_b32_e32 v40, 16, v169
	v_add_f32_e32 v38, v38, v40
	v_and_b32_e32 v40, 0xffff0000, v169
	v_add_f32_e32 v39, v39, v40
	v_lshlrev_b32_e32 v40, 16, v170
	v_add_f32_e32 v40, v32, v40
	v_and_b32_e32 v32, 0xffff0000, v170
	v_add_f32_e32 v41, v33, v32
	v_lshlrev_b32_e32 v32, 16, v171
	v_add_f32_e32 v42, v34, v32
	v_and_b32_e32 v32, 0xffff0000, v171
	v_add_f32_e32 v36, v36, v46
	v_add_f32_e32 v35, v35, v32
	v_mul_f32_e32 v32, v37, v37
	v_fmac_f32_e32 v32, v36, v36
	v_fmac_f32_e32 v32, v38, v38
	v_fmac_f32_e32 v32, v39, v39
	v_fmac_f32_e32 v32, v40, v40
	v_fmac_f32_e32 v32, v41, v41
	v_fmac_f32_e32 v32, v42, v42
	v_fmac_f32_e32 v32, v35, v35
	v_add_f32_e32 v43, v53, v32
	v_cvt_pk_bf16_f32 v32, v36, v37
	v_cvt_pk_bf16_f32 v33, v38, v39
	v_cvt_pk_bf16_f32 v34, v40, v41
	v_cvt_pk_bf16_f32 v35, v42, v35
	global_store_dwordx4 v[44:45], v[32:35], off offset:64 nt
	s_nop 1
	ds_bpermute_b32 v32, v80, v43
	s_waitcnt lgkmcnt(0)
	v_add_f32_e32 v32, v43, v32
	ds_bpermute_b32 v33, v116, v32
	s_and_saveexec_b64 s[2:3], vcc
	s_cbranch_execz .LBB0_567
	s_waitcnt lgkmcnt(0)
	v_add_f32_e32 v32, v32, v33
	v_mul_f32_e32 v32, 0x4b800000, v32
	v_trunc_f32_e32 v32, v32
	v_mul_f32_e32 v33, 0x2f800000, v32
	v_floor_f32_e32 v33, v33
	v_fmac_f32_e32 v32, 0xcf800000, v33
	v_cvt_u32_f32_e32 v32, v32
	v_cvt_u32_f32_e32 v33, v33
	v_lshl_add_u64 v[34:35], v[48:49], 3, s[40:41]
	global_atomic_add_x2 v[34:35], v[32:33], off
; __device__ __forceinline__ unsigned cvt_pk_bf16(float lo, float hi) { unsigned r; asm("v_cvt_pk_bf16_f32 %0, %1, %2" : "=v"(r) : "v"(lo), "v"(hi)); return r; }
; __device__ __forceinline__ float bf_lo(unsigned u) { return __uint_as_float(u << 16); }
; __device__ __forceinline__ float bf_hi(unsigned u) { return __uint_as_float(u & 0xffff0000u); }
; __device__ __forceinline__ unsigned long long ss_fix(float s) { return (unsigned long long)(s * 16777216.f); }
;   __device__ __forceinline__ void operator()(const f32x4 (&acc)[2][2][4][2], const Unit& u, const EpiCtx& x_, int wr, int wc, int fr, int fq) const {
;     ...
;     for (int ai = 0; ai < 2; ++ai)
; #pragma unroll
;       for (int m = 0; m < 4; ++m) {
;         const int row = (u.r0 + (ai ? x_.rdelta : 0)) + wr * 64 + m * 16 + fr;
;         const bf16_t* xin = (const bf16_t*)x_.aux + (size_t)row * DM;
;         bf16_t* xbp = x_.xb + (size_t)row * DM;
;         float sq = 0.f;
; #pragma unroll
;         for (int bj = 0; bj < 2; ++bj) {
;           const int cb = u.c0 + wc * 64 + bj * 32 + 8 * fq;
;           const uint4 xi = *(const uint4*)(xin + cb); const f32x4 a = acc[ai][bj][m][0], b = acc[ai][bj][m][1];
;           const float x0 = bf_lo(xi.x) + a[0], x1 = bf_hi(xi.x) + a[1], x2 = bf_lo(xi.y) + a[2], x3 = bf_hi(xi.y) + a[3];
;           const float x4 = bf_lo(xi.z) + b[0], x5 = bf_hi(xi.z) + b[1], x6 = bf_lo(xi.w) + b[2], x7 = bf_hi(xi.w) + b[3];
;           sq += x0 * x0 + x1 * x1 + x2 * x2 + x3 * x3 + x4 * x4 + x5 * x5 + x6 * x6 + x7 * x7;
;           uint4 o; o.x = cvt_pk_bf16(x0, x1); o.y = cvt_pk_bf16(x2, x3); o.z = cvt_pk_bf16(x4, x5); o.w = cvt_pk_bf16(x6, x7);
;           *(uint4*)(xbp + cb) = o;
;         }
;         sq += __shfl_xor(sq, 16); sq += __shfl_xor(sq, 32);
;         if (fq == 0) atomicAdd(x_.sso + row, ss_fix(sq));
.LBB0_567:
	s_or_b64 exec, exec, s[2:3]
	v_add_u32_e32 v32, 0xa0, v132
	s_waitcnt lgkmcnt(0)
	v_ashrrev_i32_e32 v33, 31, v32
	v_lshlrev_b64 v[34:35], 12, v[32:33]
	v_lshl_add_u64 v[36:37], s[8:9], 0, v[34:35]
	v_lshl_add_u64 v[40:41], v[36:37], 0, v[130:131]
	v_lshl_add_u64 v[38:39], s[36:37], 0, v[34:35]
	s_nop 0
	s_waitcnt lgkmcnt(0)
	s_nop 0
	s_waitcnt vmcnt(11)
	v_lshlrev_b32_e32 v42, 16, v194
	v_and_b32_e32 v34, 0xffff0000, v194
	v_add_f32_e32 v29, v29, v34
	v_lshlrev_b32_e32 v34, 16, v195
	v_add_f32_e32 v30, v30, v34
	v_and_b32_e32 v34, 0xffff0000, v195
	v_add_f32_e32 v31, v31, v34
	v_lshlrev_b32_e32 v34, 16, v196
	v_add_f32_e32 v34, v24, v34
	v_and_b32_e32 v24, 0xffff0000, v196
	v_add_f32_e32 v35, v25, v24
	v_lshlrev_b32_e32 v24, 16, v197
	v_add_f32_e32 v28, v28, v42
	v_add_f32_e32 v36, v26, v24
	v_and_b32_e32 v24, 0xffff0000, v197
	v_mul_f32_e32 v37, v29, v29
	v_fmac_f32_e32 v37, v28, v28
	v_fmac_f32_e32 v37, v30, v30
	v_fmac_f32_e32 v37, v31, v31
	v_fmac_f32_e32 v37, v34, v34
	v_fmac_f32_e32 v37, v35, v35
	v_add_f32_e32 v27, v27, v24
	v_fmac_f32_e32 v37, v36, v36
	v_cvt_pk_bf16_f32 v24, v28, v29
	v_lshl_add_u64 v[28:29], v[38:39], 0, v[130:131]
	v_fmac_f32_e32 v37, v27, v27
	v_cvt_pk_bf16_f32 v25, v30, v31
	v_cvt_pk_bf16_f32 v26, v34, v35
	v_cvt_pk_bf16_f32 v27, v36, v27
	global_store_dwordx4 v[28:29], v[24:27], off nt
	s_nop 1
	s_nop 0
	s_waitcnt lgkmcnt(0)
	s_nop 0
	s_waitcnt vmcnt(11)
	v_lshlrev_b32_e32 v30, 16, v198
	v_and_b32_e32 v24, 0xffff0000, v198
	v_add_f32_e32 v21, v21, v24
	v_lshlrev_b32_e32 v24, 16, v199
	v_add_f32_e32 v22, v22, v24
	v_and_b32_e32 v24, 0xffff0000, v199
	v_add_f32_e32 v23, v23, v24
	v_lshlrev_b32_e32 v24, 16, v200
	v_add_f32_e32 v24, v16, v24
	v_and_b32_e32 v16, 0xffff0000, v200
	v_add_f32_e32 v25, v17, v16
	v_lshlrev_b32_e32 v16, 16, v201
	v_add_f32_e32 v26, v18, v16
	v_and_b32_e32 v16, 0xffff0000, v201
	v_add_f32_e32 v20, v20, v30
	v_add_f32_e32 v19, v19, v16
	v_mul_f32_e32 v16, v21, v21
	v_fmac_f32_e32 v16, v20, v20
	v_fmac_f32_e32 v16, v22, v22
	v_fmac_f32_e32 v16, v23, v23
	v_fmac_f32_e32 v16, v24, v24
	v_fmac_f32_e32 v16, v25, v25
	v_fmac_f32_e32 v16, v26, v26
	v_fmac_f32_e32 v16, v19, v19
	v_add_f32_e32 v27, v37, v16
	v_cvt_pk_bf16_f32 v16, v20, v21
	v_cvt_pk_bf16_f32 v17, v22, v23
	v_cvt_pk_bf16_f32 v18, v24, v25
	v_cvt_pk_bf16_f32 v19, v26, v19
	global_store_dwordx4 v[28:29], v[16:19], off offset:64 nt
	s_nop 1
	ds_bpermute_b32 v16, v80, v27
	s_waitcnt lgkmcnt(0)
	v_add_f32_e32 v16, v27, v16
	ds_bpermute_b32 v17, v116, v16
	s_and_saveexec_b64 s[2:3], vcc
	s_cbranch_execz .LBB0_569
	s_waitcnt lgkmcnt(0)
	v_add_f32_e32 v16, v16, v17
	v_mul_f32_e32 v16, 0x4b800000, v16
	v_trunc_f32_e32 v16, v16
	v_mul_f32_e32 v17, 0x2f800000, v16
	v_floor_f32_e32 v17, v17
	v_fmac_f32_e32 v16, 0xcf800000, v17
	v_cvt_u32_f32_e32 v16, v16
	v_cvt_u32_f32_e32 v17, v17
	v_lshl_add_u64 v[18:19], v[32:33], 3, s[40:41]
	global_atomic_add_x2 v[18:19], v[16:17], off
.LBB0_569:
	s_or_b64 exec, exec, s[2:3]
	v_add_u32_e32 v16, 0xb0, v132
	s_waitcnt lgkmcnt(0)
	v_ashrrev_i32_e32 v17, 31, v16
	v_lshlrev_b64 v[18:19], 12, v[16:17]
	v_lshl_add_u64 v[20:21], s[8:9], 0, v[18:19]
	v_lshl_add_u64 v[24:25], v[20:21], 0, v[130:131]
	v_lshl_add_u64 v[22:23], s[36:37], 0, v[18:19]
	s_nop 0
	s_waitcnt lgkmcnt(0)
	s_nop 0
	s_waitcnt vmcnt(11)
	v_lshlrev_b32_e32 v26, 16, v202
	v_and_b32_e32 v18, 0xffff0000, v202
	v_add_f32_e32 v13, v13, v18
	v_lshlrev_b32_e32 v18, 16, v203
	v_add_f32_e32 v14, v14, v18
	v_and_b32_e32 v18, 0xffff0000, v203
	v_add_f32_e32 v15, v15, v18
	v_lshlrev_b32_e32 v18, 16, v204
	v_add_f32_e32 v18, v8, v18
	v_and_b32_e32 v8, 0xffff0000, v204
	v_add_f32_e32 v19, v9, v8
	v_lshlrev_b32_e32 v8, 16, v205
	v_add_f32_e32 v12, v12, v26
	v_add_f32_e32 v20, v10, v8
	v_and_b32_e32 v8, 0xffff0000, v205
	v_mul_f32_e32 v21, v13, v13
	v_fmac_f32_e32 v21, v12, v12
	v_fmac_f32_e32 v21, v14, v14
	v_fmac_f32_e32 v21, v15, v15
	v_fmac_f32_e32 v21, v18, v18
	v_fmac_f32_e32 v21, v19, v19
	v_add_f32_e32 v11, v11, v8
	v_fmac_f32_e32 v21, v20, v20
	v_cvt_pk_bf16_f32 v8, v12, v13
	v_lshl_add_u64 v[12:13], v[22:23], 0, v[130:131]
	v_fmac_f32_e32 v21, v11, v11
	v_cvt_pk_bf16_f32 v9, v14, v15
	v_cvt_pk_bf16_f32 v10, v18, v19
	v_cvt_pk_bf16_f32 v11, v20, v11
	global_store_dwordx4 v[12:13], v[8:11], off nt
	s_nop 1
	s_nop 0
	s_waitcnt lgkmcnt(0)
	s_nop 0
	s_waitcnt vmcnt(11)
	v_lshlrev_b32_e32 v14, 16, v206
	v_and_b32_e32 v8, 0xffff0000, v206
	v_add_f32_e32 v5, v5, v8
	v_lshlrev_b32_e32 v8, 16, v207
	v_add_f32_e32 v6, v6, v8
	v_and_b32_e32 v8, 0xffff0000, v207
	v_add_f32_e32 v7, v7, v8
	v_lshlrev_b32_e32 v8, 16, v208
	v_add_f32_e32 v8, v0, v8
	v_and_b32_e32 v0, 0xffff0000, v208
	v_add_f32_e32 v9, v1, v0
	v_lshlrev_b32_e32 v0, 16, v209
	v_add_f32_e32 v10, v2, v0
	v_and_b32_e32 v0, 0xffff0000, v209
	v_add_f32_e32 v4, v4, v14
	v_add_f32_e32 v3, v3, v0
	v_mul_f32_e32 v0, v5, v5
	v_fmac_f32_e32 v0, v4, v4
	v_fmac_f32_e32 v0, v6, v6
	v_fmac_f32_e32 v0, v7, v7
	v_fmac_f32_e32 v0, v8, v8
	v_fmac_f32_e32 v0, v9, v9
	v_fmac_f32_e32 v0, v10, v10
	v_fmac_f32_e32 v0, v3, v3
	v_add_f32_e32 v11, v21, v0
	v_cvt_pk_bf16_f32 v0, v4, v5
	v_cvt_pk_bf16_f32 v1, v6, v7
	v_cvt_pk_bf16_f32 v2, v8, v9
	v_cvt_pk_bf16_f32 v3, v10, v3
	global_store_dwordx4 v[12:13], v[0:3], off offset:64 nt
	s_nop 1
	ds_bpermute_b32 v0, v80, v11
	s_waitcnt lgkmcnt(0)
	v_add_f32_e32 v0, v11, v0
	ds_bpermute_b32 v1, v116, v0
	s_and_saveexec_b64 s[2:3], vcc
	s_cbranch_execz .LBB0_552
	s_waitcnt lgkmcnt(0)
	v_add_f32_e32 v0, v0, v1
	v_mul_f32_e32 v0, 0x4b800000, v0
	v_trunc_f32_e32 v0, v0
	v_mul_f32_e32 v1, 0x2f800000, v0
	v_floor_f32_e32 v1, v1
	v_fmac_f32_e32 v0, 0xcf800000, v1
	v_cvt_u32_f32_e32 v0, v0
	v_cvt_u32_f32_e32 v1, v1
	v_lshl_add_u64 v[2:3], v[16:17], 3, s[40:41]
	global_atomic_add_x2 v[2:3], v[0:1], off
	s_branch .LBB0_552

; __device__ __forceinline__ unsigned cvt_pk_bf16(float lo, float hi) { unsigned r; asm("v_cvt_pk_bf16_f32 %0, %1, %2" : "=v"(r) : "v"(lo), "v"(hi)); return r; }
; __device__ __forceinline__ float rinv_of(unsigned long long ss) { return rsqrtf((float)ss * (1.f / 16777216.f) * (1.f / DM) + 1e-6f); }
;   __device__ __forceinline__ void operator()(const f32x4 (&acc)[2][2][4][2], const Unit& u, const EpiCtx& x_, int wr, int wc, int fr, int fq) const {
;     ...
;     const int g = (hq % 48) >> 4, lg = 2 * g, L = S >> lg;
;     const bool isq = hq < 48; const int hh = isq ? hq : hq - 48;
;     bf16_t* obase = (bf16_t*)(isq ? u.C : x_.C2) + (size_t)hh * TS * 128 + wh * 64 + 8 * fq;
;     const float* gbase = (const float*)(isq ? x_.aux : x_.aux2) + wh * 64 + 8 * fq;
; #pragma unroll
;     for (int ai = 0; ai < 2; ++ai)
; #pragma unroll
;       for (int m = 0; m < 4; ++m) {
;         const int t = u.r0 + ai * 128 + wr * 64 + m * 16 + fr;
;         const int seq = t / S, n = t % S, pos = seq * S + (n & ((1 << lg) - 1)) * L + (n >> lg);
;         const float rs = rinv_of(ssv[ai][m]);
;         const float* rp = (const float*)0; (void)rp;
;         const float r0 = red[((wr * 2 + hd) * 128 + ai * 64 + m * 16 + fr) * 2], r1 = red[((wr * 2 + hd) * 128 + ai * 64 + m * 16 + fr) * 2 + 1];
;         const float rinv = rs * rsqrtf((r0 + r1) * (rs * rs) * (1.f / 128.f) + 1e-6f);
; #pragma unroll
;         for (int bj = 0; bj < 2; ++bj) {
;           const f32x4 g0 = *(const f32x4*)(gbase + bj * 32), g1 = *(const f32x4*)(gbase + bj * 32 + 4);
;           const f32x4 v0 = acc[ai][bj][m][0] * rinv * g0, v1 = acc[ai][bj][m][1] * rinv * g1;
;           uint4 o; o.x = cvt_pk_bf16(v0[0], v0[1]); o.y = cvt_pk_bf16(v0[2], v0[3]); o.z = cvt_pk_bf16(v1[0], v1[1]); o.w = cvt_pk_bf16(v1[2], v1[3]);
;           *(uint4*)(obase + (size_t)pos * 128 + bj * 32) = o;
;         }
.LBB0_587:
	s_or_b64 exec, exec, s[2:3]
	s_ashr_i32 s1, s1, 7
	s_add_i32 s1, s1, s86
	s_mul_hi_i32 s2, s1, 0x2aaaaaab
	s_lshr_b32 s3, s2, 31
	s_lshr_b32 s2, s2, 3
	s_add_i32 s2, s2, s3
	s_mul_i32 s2, s2, 48
	s_sub_i32 s2, s1, s2
	s_ashr_i32 s2, s2, 3
	s_and_b32 s39, s2, -2
	s_lshr_b32 s42, s17, s39
	s_cmp_lt_i32 s1, 48
	s_cselect_b64 s[2:3], -1, 0
	s_sub_i32 s30, s1, 48
	s_and_b64 s[28:29], s[2:3], exec
	s_cselect_b32 s28, s1, s30
	s_cselect_b32 s1, s5, s87
	s_cselect_b32 s30, s4, s83
	s_ashr_i32 s29, s28, 31
	s_lshl_b64 s[4:5], s[28:29], 22
	s_add_u32 s4, s30, s4
	s_addc_u32 s1, s1, s5
	s_lshl_b32 s5, s61, 1
	s_add_u32 s4, s4, s5
	s_addc_u32 s5, s1, 0
	s_and_b64 s[2:3], s[2:3], exec
	s_cselect_b32 s2, s19, s47
	s_cselect_b32 s1, s18, s46
	s_add_u32 s2, s2, s84
	s_addc_u32 s1, s1, s85
	s_lshl_b32 s3, s61, 2
	v_lshlrev_b32_e32 v80, 1, v138
	s_add_u32 s2, s2, s3
	v_lshl_add_u64 v[146:147], s[4:5], 0, v[80:81]
	s_addc_u32 s3, s1, 0
	v_lshlrev_b32_e32 v80, 2, v138
	v_lshl_add_u64 v[142:143], s[2:3], 0, v[80:81]
	s_nop 1
	global_load_dwordx4 v[190:193], v[142:143], off
	global_load_dwordx4 v[194:197], v[142:143], off offset:16
	global_load_dwordx4 v[198:201], v[142:143], off offset:128
	global_load_dwordx4 v[202:205], v[142:143], off offset:144
	v_sub_u32_e32 v80, 0, v140
	v_max_i32_e32 v80, v140, v80
	v_mul_hi_u32 v130, v80, v172
	v_mul_lo_u32 v130, v130, s17
	v_sub_u32_e32 v80, v80, v130
	v_cmp_le_u32_e64 s[2:3], s17, v80
	v_subrev_u32_e32 v130, s17, v80
	s_lshl_b32 s43, -1, s39
	v_cndmask_b32_e64 v80, v80, v130, s[2:3]
	v_cmp_le_u32_e64 s[2:3], s17, v80
	v_subrev_u32_e32 v130, s17, v80
	s_waitcnt lgkmcnt(0)
	s_barrier
	v_cndmask_b32_e64 v80, v80, v130, s[2:3]
	v_xor_b32_e32 v80, v80, v141
	v_sub_u32_e32 v80, v80, v141
	v_bitop3_b32 v130, v80, s43, v80 bitop3:0x30
	v_mul_lo_u32 v130, v130, s42
	s_waitcnt lgkmcnt(0)
	v_ashrrev_i32_e32 v131, s39, v80
	v_sub_u32_e32 v80, v140, v80
	v_add3_u32 v130, v80, v131, v130
	s_waitcnt vmcnt(0)
	v_ffbh_u32_e32 v80, v133
	v_min_u32_e32 v80, 32, v80
	v_lshlrev_b64 v[132:133], v80, v[132:133]
	v_min_u32_e32 v131, 1, v132
	v_or_b32_e32 v131, v133, v131
	v_cvt_f32_u32_e32 v131, v131
	v_sub_u32_e32 v80, 32, v80
	v_add_u32_e32 v178, s0, v169
	v_ldexp_f32 v80, v131, v80
	v_mul_f32_e32 v80, 0x33800000, v80
	v_fmamk_f32 v80, v80, 0x3a000000, v234
	v_cmp_gt_f32_e64 s[2:3], s50, v80
	v_mul_f32_e32 v131, 0x4b800000, v80
	s_cmp_eq_u32 s75, s79
	v_cndmask_b32_e64 v80, v80, v131, s[2:3]
	v_rsq_f32_e32 v80, v80
	s_mov_b32 s1, s44
	v_mul_f32_e32 v131, 0x45800000, v80
	v_cndmask_b32_e64 v141, v80, v131, s[2:3]
	v_add_u32_e32 v80, 0, v168
	v_add_u32_e32 v80, 0x20800, v80
	ds_read_b64 v[132:133], v80
	v_ashrrev_i32_e32 v131, 31, v130
	v_lshlrev_b64 v[130:131], 8, v[130:131]
	v_lshl_add_u64 v[160:161], v[146:147], 0, v[130:131]
	v_mul_f32_e32 v177, v141, v141
	s_waitcnt lgkmcnt(0)
	v_pk_add_f32 v[174:175], v[132:133], v[132:133] op_sel_hi:[0,1]
	s_nop 0
	s_nop 0
	v_ffbh_u32_e32 v174, v151
	v_min_u32_e32 v174, 32, v174
	v_lshlrev_b64 v[150:151], v174, v[150:151]
	v_min_u32_e32 v150, 1, v150
	v_or_b32_e32 v150, v151, v150
	v_cvt_f32_u32_e32 v150, v150
	v_sub_u32_e32 v151, 32, v174
	v_mov_b32_e32 v181, v175
	v_ldexp_f32 v176, v150, v151
	v_pk_mul_f32 v[174:175], v[176:177], v[180:181]
	v_mov_b64_e32 v[150:151], s[62:63]
	v_pk_fma_f32 v[174:175], v[174:175], s[26:27], v[150:151] op_sel_hi:[1,1,0]
	s_nop 0
	v_mul_f32_e32 v176, 0x4b800000, v175
	v_cmp_gt_f32_e64 s[4:5], s50, v175
	v_cmp_gt_f32_e64 s[2:3], s50, v174
	s_nop 0
	v_cndmask_b32_e64 v175, v175, v176, s[4:5]
	v_rsq_f32_e32 v175, v175
	s_nop 0
	v_mul_f32_e32 v176, 0x45800000, v175
	v_cndmask_b32_e64 v175, v175, v176, s[4:5]
	v_mul_f32_e32 v176, v141, v175
	v_pk_mul_f32 v[122:123], v[122:123], v[176:177] op_sel_hi:[1,0]
	v_pk_mul_f32 v[124:125], v[124:125], v[176:177] op_sel_hi:[1,0]
	v_pk_mul_f32 v[126:127], v[126:127], v[176:177] op_sel_hi:[1,0]
	v_pk_mul_f32 v[128:129], v[128:129], v[176:177] op_sel_hi:[1,0]
	v_pk_mul_f32 v[118:119], v[118:119], v[176:177] op_sel_hi:[1,0]
	v_pk_mul_f32 v[120:121], v[120:121], v[176:177] op_sel_hi:[1,0]
	v_pk_mul_f32 v[114:115], v[114:115], v[176:177] op_sel_hi:[1,0]
	v_pk_mul_f32 v[116:117], v[116:117], v[176:177] op_sel_hi:[1,0]
	s_waitcnt lgkmcnt(0)
	v_pk_mul_f32 v[128:129], v[192:193], v[128:129]
	v_pk_mul_f32 v[132:133], v[196:197], v[124:125]
	v_pk_mul_f32 v[124:125], v[194:195], v[122:123]
	v_pk_mul_f32 v[126:127], v[190:191], v[126:127]
	v_cvt_pk_bf16_f32 v123, v128, v129
	v_cvt_pk_bf16_f32 v124, v124, v125
	v_cvt_pk_bf16_f32 v125, v132, v133
	v_add_u32_e32 v131, s0, v170
	v_cvt_pk_bf16_f32 v122, v126, v127
	global_store_dwordx4 v[160:161], v[122:125], off nt
	s_nop 0
	s_nop 0
	s_nop 0
	s_waitcnt lgkmcnt(0)
	v_pk_mul_f32 v[120:121], v[200:201], v[120:121]
	v_pk_mul_f32 v[118:119], v[198:199], v[118:119]
	v_pk_mul_f32 v[122:123], v[204:205], v[116:117]
	v_pk_mul_f32 v[116:117], v[202:203], v[114:115]
	v_cvt_pk_bf16_f32 v115, v120, v121
	v_cvt_pk_bf16_f32 v114, v118, v119
	s_nop 0
	v_cvt_pk_bf16_f32 v116, v116, v117
	v_cvt_pk_bf16_f32 v117, v122, v123
	global_store_dwordx4 v[160:161], v[114:117], off offset:64 nt
	s_nop 1
	v_sub_u32_e32 v115, 0, v178
	v_max_i32_e32 v115, v178, v115
	v_mul_hi_u32 v116, v115, v172
	v_mul_lo_u32 v116, v116, s17
	v_sub_u32_e32 v115, v115, v116
	v_cmp_le_u32_e64 s[4:5], s17, v115
	v_subrev_u32_e32 v116, s17, v115
	v_ashrrev_i32_e32 v114, 31, v178
	v_cndmask_b32_e64 v115, v115, v116, s[4:5]
	v_cmp_le_u32_e64 s[4:5], s17, v115
	v_subrev_u32_e32 v116, s17, v115
	s_nop 0
	v_cndmask_b32_e64 v115, v115, v116, s[4:5]
	v_xor_b32_e32 v115, v115, v114
	v_sub_u32_e32 v114, v115, v114
	v_bitop3_b32 v115, v114, s43, v114 bitop3:0x30
	v_mul_lo_u32 v115, v115, s42
	v_ashrrev_i32_e32 v116, s39, v114
	v_sub_u32_e32 v114, v178, v114
	v_add3_u32 v114, v114, v116, v115
	v_mul_f32_e32 v115, 0x4b800000, v174
	v_cndmask_b32_e64 v115, v174, v115, s[2:3]
	v_rsq_f32_e32 v115, v115
	s_nop 0
	v_mul_f32_e32 v116, 0x45800000, v115
	v_cndmask_b32_e64 v130, v115, v116, s[2:3]
	ds_read_b64 v[116:117], v80 offset:128
	s_nop 0
	s_nop 0
	v_mul_f32_e32 v119, v130, v130
	v_ashrrev_i32_e32 v115, 31, v114
	v_lshlrev_b64 v[114:115], 8, v[114:115]
	s_waitcnt lgkmcnt(0)
; __device__ __forceinline__ unsigned cvt_pk_bf16(float lo, float hi) { unsigned r; asm("v_cvt_pk_bf16_f32 %0, %1, %2" : "=v"(r) : "v"(lo), "v"(hi)); return r; }
; __device__ __forceinline__ float rinv_of(unsigned long long ss) { return rsqrtf((float)ss * (1.f / 16777216.f) * (1.f / DM) + 1e-6f); }
;   __device__ __forceinline__ void operator()(const f32x4 (&acc)[2][2][4][2], const Unit& u, const EpiCtx& x_, int wr, int wc, int fr, int fq) const {
;     ...
; #pragma unroll
;     for (int ai = 0; ai < 2; ++ai)
; #pragma unroll
;       for (int m = 0; m < 4; ++m) {
;         const int t = u.r0 + ai * 128 + wr * 64 + m * 16 + fr;
;         const int seq = t / S, n = t % S, pos = seq * S + (n & ((1 << lg) - 1)) * L + (n >> lg);
;         const float rs = rinv_of(ssv[ai][m]);
;         const float* rp = (const float*)0; (void)rp;
;         const float r0 = red[((wr * 2 + hd) * 128 + ai * 64 + m * 16 + fr) * 2], r1 = red[((wr * 2 + hd) * 128 + ai * 64 + m * 16 + fr) * 2 + 1];
;         const float rinv = rs * rsqrtf((r0 + r1) * (rs * rs) * (1.f / 128.f) + 1e-6f);
; #pragma unroll
;         for (int bj = 0; bj < 2; ++bj) {
;           const f32x4 g0 = *(const f32x4*)(gbase + bj * 32), g1 = *(const f32x4*)(gbase + bj * 32 + 4);
;           const f32x4 v0 = acc[ai][bj][m][0] * rinv * g0, v1 = acc[ai][bj][m][1] * rinv * g1;
;           uint4 o; o.x = cvt_pk_bf16(v0[0], v0[1]); o.y = cvt_pk_bf16(v0[2], v0[3]); o.z = cvt_pk_bf16(v1[0], v1[1]); o.w = cvt_pk_bf16(v1[2], v1[3]);
;           *(uint4*)(obase + (size_t)pos * 128 + bj * 32) = o;
;         }
;       }
	v_pk_add_f32 v[116:117], v[116:117], v[116:117] op_sel_hi:[0,1]
	v_ffbh_u32_e32 v116, v159
	v_min_u32_e32 v116, 32, v116
	v_lshlrev_b64 v[128:129], v116, v[158:159]
	v_min_u32_e32 v118, 1, v128
	v_or_b32_e32 v118, v129, v118
	v_cvt_f32_u32_e32 v118, v118
	v_sub_u32_e32 v116, 32, v116
	v_mov_b32_e32 v181, v117
	v_lshl_add_u64 v[114:115], v[146:147], 0, v[114:115]
	v_ldexp_f32 v118, v118, v116
	v_pk_mul_f32 v[116:117], v[118:119], v[180:181]
	s_nop 0
	v_pk_fma_f32 v[116:117], v[116:117], s[26:27], v[150:151] op_sel_hi:[1,1,0]
	s_nop 0
	v_mul_f32_e32 v118, 0x4b800000, v117
	v_cmp_gt_f32_e64 s[4:5], s50, v117
	v_cmp_gt_f32_e64 s[2:3], s50, v116
	s_nop 0
	v_cndmask_b32_e64 v117, v117, v118, s[4:5]
	v_rsq_f32_e32 v117, v117
	s_nop 0
	v_mul_f32_e32 v118, 0x45800000, v117
	v_cndmask_b32_e64 v117, v117, v118, s[4:5]
	v_mul_f32_e32 v118, v130, v117
	v_pk_mul_f32 v[110:111], v[110:111], v[118:119] op_sel_hi:[1,0]
	v_pk_mul_f32 v[106:107], v[106:107], v[118:119] op_sel_hi:[1,0]
	v_pk_mul_f32 v[108:109], v[108:109], v[118:119] op_sel_hi:[1,0]
	v_pk_mul_f32 v[112:113], v[112:113], v[118:119] op_sel_hi:[1,0]
	v_pk_mul_f32 v[102:103], v[102:103], v[118:119] op_sel_hi:[1,0]
	v_pk_mul_f32 v[104:105], v[104:105], v[118:119] op_sel_hi:[1,0]
	v_pk_mul_f32 v[98:99], v[98:99], v[118:119] op_sel_hi:[1,0]
	v_pk_mul_f32 v[100:101], v[100:101], v[118:119] op_sel_hi:[1,0]
	s_nop 0
	v_pk_mul_f32 v[110:111], v[190:191], v[110:111]
	v_pk_mul_f32 v[120:121], v[196:197], v[108:109]
	v_pk_mul_f32 v[108:109], v[194:195], v[106:107]
	v_pk_mul_f32 v[112:113], v[192:193], v[112:113]
	v_cvt_pk_bf16_f32 v106, v110, v111
	v_cvt_pk_bf16_f32 v108, v108, v109
	v_cvt_pk_bf16_f32 v109, v120, v121
	s_nop 0
	v_cvt_pk_bf16_f32 v107, v112, v113
	global_store_dwordx4 v[114:115], v[106:109], off nt
	s_nop 0
	s_nop 0
	s_nop 0
	s_waitcnt lgkmcnt(0)
	v_pk_mul_f32 v[104:105], v[200:201], v[104:105]
	v_pk_mul_f32 v[102:103], v[198:199], v[102:103]
	v_pk_mul_f32 v[106:107], v[204:205], v[100:101]
	v_pk_mul_f32 v[100:101], v[202:203], v[98:99]
	v_cvt_pk_bf16_f32 v99, v104, v105
	v_cvt_pk_bf16_f32 v98, v102, v103
	s_nop 0
	v_cvt_pk_bf16_f32 v100, v100, v101
	v_cvt_pk_bf16_f32 v101, v106, v107
	global_store_dwordx4 v[114:115], v[98:101], off offset:64 nt
	v_add_u32_e32 v115, s0, v171
	s_mov_b32 s0, s38
	v_sub_u32_e32 v99, 0, v131
	v_max_i32_e32 v99, v131, v99
	v_mul_hi_u32 v100, v99, v172
	v_mul_lo_u32 v100, v100, s17
	v_sub_u32_e32 v99, v99, v100
	v_cmp_le_u32_e64 s[4:5], s17, v99
	v_subrev_u32_e32 v100, s17, v99
	v_ashrrev_i32_e32 v98, 31, v131
	v_cndmask_b32_e64 v99, v99, v100, s[4:5]
	v_cmp_le_u32_e64 s[4:5], s17, v99
	v_subrev_u32_e32 v100, s17, v99
	s_nop 0
	v_cndmask_b32_e64 v99, v99, v100, s[4:5]
	v_xor_b32_e32 v99, v99, v98
	v_sub_u32_e32 v98, v99, v98
	v_bitop3_b32 v99, v98, s43, v98 bitop3:0x30
	v_mul_lo_u32 v99, v99, s42
	v_ashrrev_i32_e32 v100, s39, v98
	v_sub_u32_e32 v98, v131, v98
	v_add3_u32 v98, v98, v100, v99
	v_mul_f32_e32 v99, 0x4b800000, v116
	v_cndmask_b32_e64 v99, v116, v99, s[2:3]
	v_rsq_f32_e32 v99, v99
	s_nop 0
	v_mul_f32_e32 v100, 0x45800000, v99
	v_cndmask_b32_e64 v114, v99, v100, s[2:3]
	ds_read_b64 v[100:101], v80 offset:256
	s_nop 0
	s_nop 0
	v_mul_f32_e32 v103, v114, v114
	v_ashrrev_i32_e32 v99, 31, v98
	v_lshlrev_b64 v[98:99], 8, v[98:99]
	s_waitcnt lgkmcnt(0)
	v_pk_add_f32 v[100:101], v[100:101], v[100:101] op_sel_hi:[0,1]
	v_ffbh_u32_e32 v100, v157
	v_min_u32_e32 v100, 32, v100
	v_lshlrev_b64 v[112:113], v100, v[156:157]
	v_min_u32_e32 v102, 1, v112
	v_or_b32_e32 v102, v113, v102
	v_cvt_f32_u32_e32 v102, v102
	v_sub_u32_e32 v100, 32, v100
	v_mov_b32_e32 v181, v101
	v_lshl_add_u64 v[98:99], v[146:147], 0, v[98:99]
	v_ldexp_f32 v102, v102, v100
	v_pk_mul_f32 v[100:101], v[102:103], v[180:181]
	s_nop 0
	v_pk_fma_f32 v[100:101], v[100:101], s[26:27], v[150:151] op_sel_hi:[1,1,0]
	s_nop 0
	v_mul_f32_e32 v102, 0x4b800000, v101
	v_cmp_gt_f32_e64 s[4:5], s50, v101
	v_cmp_gt_f32_e64 s[2:3], s50, v100
	s_nop 0
	v_cndmask_b32_e64 v101, v101, v102, s[4:5]
	v_rsq_f32_e32 v101, v101
	s_nop 0
	v_mul_f32_e32 v102, 0x45800000, v101
	v_cndmask_b32_e64 v101, v101, v102, s[4:5]
	v_mul_f32_e32 v102, v114, v101
	v_pk_mul_f32 v[94:95], v[94:95], v[102:103] op_sel_hi:[1,0]
	v_pk_mul_f32 v[90:91], v[90:91], v[102:103] op_sel_hi:[1,0]
	v_pk_mul_f32 v[92:93], v[92:93], v[102:103] op_sel_hi:[1,0]
	v_pk_mul_f32 v[96:97], v[96:97], v[102:103] op_sel_hi:[1,0]
	v_pk_mul_f32 v[86:87], v[86:87], v[102:103] op_sel_hi:[1,0]
	v_pk_mul_f32 v[88:89], v[88:89], v[102:103] op_sel_hi:[1,0]
	v_pk_mul_f32 v[82:83], v[82:83], v[102:103] op_sel_hi:[1,0]
	v_pk_mul_f32 v[84:85], v[84:85], v[102:103] op_sel_hi:[1,0]
	s_nop 0
	v_pk_mul_f32 v[94:95], v[190:191], v[94:95]
	v_pk_mul_f32 v[104:105], v[196:197], v[92:93]
	v_pk_mul_f32 v[92:93], v[194:195], v[90:91]
	v_pk_mul_f32 v[96:97], v[192:193], v[96:97]
	v_cvt_pk_bf16_f32 v90, v94, v95
	v_cvt_pk_bf16_f32 v92, v92, v93
	v_cvt_pk_bf16_f32 v93, v104, v105
	s_nop 0
	v_cvt_pk_bf16_f32 v91, v96, v97
	global_store_dwordx4 v[98:99], v[90:93], off nt
	s_nop 0
	s_nop 0
	s_nop 0
	s_waitcnt lgkmcnt(0)
; __device__ __forceinline__ unsigned cvt_pk_bf16(float lo, float hi) { unsigned r; asm("v_cvt_pk_bf16_f32 %0, %1, %2" : "=v"(r) : "v"(lo), "v"(hi)); return r; }
; __device__ __forceinline__ float rinv_of(unsigned long long ss) { return rsqrtf((float)ss * (1.f / 16777216.f) * (1.f / DM) + 1e-6f); }
;   __device__ __forceinline__ void operator()(const f32x4 (&acc)[2][2][4][2], const Unit& u, const EpiCtx& x_, int wr, int wc, int fr, int fq) const {
;     ...
; #pragma unroll
;     for (int ai = 0; ai < 2; ++ai)
; #pragma unroll
;       for (int m = 0; m < 4; ++m) {
;         const int t = u.r0 + ai * 128 + wr * 64 + m * 16 + fr;
;         const int seq = t / S, n = t % S, pos = seq * S + (n & ((1 << lg) - 1)) * L + (n >> lg);
;         const float rs = rinv_of(ssv[ai][m]);
;         const float* rp = (const float*)0; (void)rp;
;         const float r0 = red[((wr * 2 + hd) * 128 + ai * 64 + m * 16 + fr) * 2], r1 = red[((wr * 2 + hd) * 128 + ai * 64 + m * 16 + fr) * 2 + 1];
;         const float rinv = rs * rsqrtf((r0 + r1) * (rs * rs) * (1.f / 128.f) + 1e-6f);
; #pragma unroll
;         for (int bj = 0; bj < 2; ++bj) {
;           const f32x4 g0 = *(const f32x4*)(gbase + bj * 32), g1 = *(const f32x4*)(gbase + bj * 32 + 4);
;           const f32x4 v0 = acc[ai][bj][m][0] * rinv * g0, v1 = acc[ai][bj][m][1] * rinv * g1;
;           uint4 o; o.x = cvt_pk_bf16(v0[0], v0[1]); o.y = cvt_pk_bf16(v0[2], v0[3]); o.z = cvt_pk_bf16(v1[0], v1[1]); o.w = cvt_pk_bf16(v1[2], v1[3]);
;           *(uint4*)(obase + (size_t)pos * 128 + bj * 32) = o;
;         }
;       }
	v_pk_mul_f32 v[88:89], v[200:201], v[88:89]
	v_pk_mul_f32 v[86:87], v[198:199], v[86:87]
	v_pk_mul_f32 v[90:91], v[204:205], v[84:85]
	v_pk_mul_f32 v[84:85], v[202:203], v[82:83]
	v_cvt_pk_bf16_f32 v83, v88, v89
	v_cvt_pk_bf16_f32 v82, v86, v87
	s_nop 0
	v_cvt_pk_bf16_f32 v84, v84, v85
	v_cvt_pk_bf16_f32 v85, v90, v91
	global_store_dwordx4 v[98:99], v[82:85], off offset:64 nt
	v_add_u32_e32 v99, 0x80, v140
	s_nop 0
	v_sub_u32_e32 v83, 0, v115
	v_max_i32_e32 v83, v115, v83
	v_mul_hi_u32 v84, v83, v172
	v_mul_lo_u32 v84, v84, s17
	v_sub_u32_e32 v83, v83, v84
	v_cmp_le_u32_e64 s[4:5], s17, v83
	v_subrev_u32_e32 v84, s17, v83
	v_ashrrev_i32_e32 v82, 31, v115
	v_cndmask_b32_e64 v83, v83, v84, s[4:5]
	v_cmp_le_u32_e64 s[4:5], s17, v83
	v_subrev_u32_e32 v84, s17, v83
	s_nop 0
	v_cndmask_b32_e64 v83, v83, v84, s[4:5]
	v_xor_b32_e32 v83, v83, v82
	v_sub_u32_e32 v82, v83, v82
	v_bitop3_b32 v83, v82, s43, v82 bitop3:0x30
	v_mul_lo_u32 v83, v83, s42
	v_ashrrev_i32_e32 v84, s39, v82
	v_sub_u32_e32 v82, v115, v82
	v_add3_u32 v82, v82, v84, v83
	v_mul_f32_e32 v83, 0x4b800000, v100
	v_cndmask_b32_e64 v83, v100, v83, s[2:3]
	v_rsq_f32_e32 v83, v83
	s_nop 0
	v_mul_f32_e32 v84, 0x45800000, v83
	v_cndmask_b32_e64 v98, v83, v84, s[2:3]
	ds_read_b64 v[84:85], v80 offset:384
	s_nop 0
	s_nop 0
	v_mul_f32_e32 v87, v98, v98
	v_ashrrev_i32_e32 v83, 31, v82
	v_lshlrev_b64 v[82:83], 8, v[82:83]
	s_waitcnt lgkmcnt(0)
	v_pk_add_f32 v[84:85], v[84:85], v[84:85] op_sel_hi:[0,1]
	v_ffbh_u32_e32 v84, v155
	v_min_u32_e32 v84, 32, v84
	v_lshlrev_b64 v[96:97], v84, v[154:155]
	v_min_u32_e32 v86, 1, v96
	v_or_b32_e32 v86, v97, v86
	v_cvt_f32_u32_e32 v86, v86
	v_sub_u32_e32 v84, 32, v84
	v_mov_b32_e32 v181, v85
	v_lshl_add_u64 v[82:83], v[146:147], 0, v[82:83]
	v_ldexp_f32 v86, v86, v84
	v_pk_mul_f32 v[84:85], v[86:87], v[180:181]
	s_nop 0
	v_pk_fma_f32 v[84:85], v[84:85], s[26:27], v[150:151] op_sel_hi:[1,1,0]
	s_nop 0
	v_mul_f32_e32 v86, 0x4b800000, v85
	v_cmp_gt_f32_e64 s[4:5], s50, v85
	v_cmp_gt_f32_e64 s[2:3], s50, v84
	s_nop 0
	v_cndmask_b32_e64 v85, v85, v86, s[4:5]
	v_rsq_f32_e32 v85, v85
	s_nop 0
	v_mul_f32_e32 v86, 0x45800000, v85
	v_cndmask_b32_e64 v85, v85, v86, s[4:5]
	v_mul_f32_e32 v86, v98, v85
	v_pk_mul_f32 v[76:77], v[76:77], v[86:87] op_sel_hi:[1,0]
	v_pk_mul_f32 v[72:73], v[72:73], v[86:87] op_sel_hi:[1,0]
	v_pk_mul_f32 v[74:75], v[74:75], v[86:87] op_sel_hi:[1,0]
	v_pk_mul_f32 v[78:79], v[78:79], v[86:87] op_sel_hi:[1,0]
	v_pk_mul_f32 v[68:69], v[68:69], v[86:87] op_sel_hi:[1,0]
	v_pk_mul_f32 v[70:71], v[70:71], v[86:87] op_sel_hi:[1,0]
	v_pk_mul_f32 v[64:65], v[64:65], v[86:87] op_sel_hi:[1,0]
	v_pk_mul_f32 v[66:67], v[66:67], v[86:87] op_sel_hi:[1,0]
	s_nop 0
	v_pk_mul_f32 v[76:77], v[190:191], v[76:77]
	v_pk_mul_f32 v[88:89], v[196:197], v[74:75]
	v_pk_mul_f32 v[74:75], v[194:195], v[72:73]
	v_pk_mul_f32 v[78:79], v[192:193], v[78:79]
	v_cvt_pk_bf16_f32 v72, v76, v77
	v_cvt_pk_bf16_f32 v74, v74, v75
	v_cvt_pk_bf16_f32 v75, v88, v89
	s_nop 0
	v_cvt_pk_bf16_f32 v73, v78, v79
	global_store_dwordx4 v[82:83], v[72:75], off nt
	s_nop 0
	s_nop 0
	s_nop 0
	s_waitcnt lgkmcnt(0)
	v_pk_mul_f32 v[70:71], v[200:201], v[70:71]
	v_pk_mul_f32 v[68:69], v[198:199], v[68:69]
	v_pk_mul_f32 v[72:73], v[204:205], v[66:67]
	v_pk_mul_f32 v[66:67], v[202:203], v[64:65]
	v_cvt_pk_bf16_f32 v65, v70, v71
	v_cvt_pk_bf16_f32 v64, v68, v69
	s_nop 0
	v_cvt_pk_bf16_f32 v66, v66, v67
	v_cvt_pk_bf16_f32 v67, v72, v73
	global_store_dwordx4 v[82:83], v[64:67], off offset:64 nt
	v_add_u32_e32 v83, 0x90, v140
	s_nop 0
	v_sub_u32_e32 v65, 0xffffff80, v140
	v_max_i32_e32 v65, v99, v65
	v_mul_hi_u32 v66, v65, v172
	v_mul_lo_u32 v66, v66, s17
	v_sub_u32_e32 v65, v65, v66
	v_cmp_le_u32_e64 s[4:5], s17, v65
	v_subrev_u32_e32 v66, s17, v65
	v_ashrrev_i32_e32 v64, 31, v99
	v_cndmask_b32_e64 v65, v65, v66, s[4:5]
	v_cmp_le_u32_e64 s[4:5], s17, v65
	v_subrev_u32_e32 v66, s17, v65
	s_nop 0
	v_cndmask_b32_e64 v65, v65, v66, s[4:5]
	v_xor_b32_e32 v65, v65, v64
	v_sub_u32_e32 v64, v65, v64
	v_bitop3_b32 v65, v64, s43, v64 bitop3:0x30
	v_mul_lo_u32 v65, v65, s42
	v_ashrrev_i32_e32 v66, s39, v64
	v_sub_u32_e32 v64, v99, v64
	v_add3_u32 v64, v64, v66, v65
	v_mul_f32_e32 v65, 0x4b800000, v84
	v_cndmask_b32_e64 v65, v84, v65, s[2:3]
	v_rsq_f32_e32 v65, v65
	s_nop 0
	v_mul_f32_e32 v66, 0x45800000, v65
	v_cndmask_b32_e64 v82, v65, v66, s[2:3]
	ds_read_b64 v[66:67], v80 offset:512
	s_nop 0
	s_nop 0
	v_mul_f32_e32 v69, v82, v82
	v_ashrrev_i32_e32 v65, 31, v64
	v_lshlrev_b64 v[64:65], 8, v[64:65]
	s_waitcnt lgkmcnt(0)
	v_pk_add_f32 v[66:67], v[66:67], v[66:67] op_sel_hi:[0,1]
	v_ffbh_u32_e32 v66, v153
	v_min_u32_e32 v66, 32, v66
	v_lshlrev_b64 v[78:79], v66, v[152:153]
	v_min_u32_e32 v68, 1, v78
	v_or_b32_e32 v68, v79, v68
	v_cvt_f32_u32_e32 v68, v68
	v_sub_u32_e32 v66, 32, v66
	v_mov_b32_e32 v181, v67
	v_lshl_add_u64 v[64:65], v[146:147], 0, v[64:65]
	v_ldexp_f32 v68, v68, v66
	v_pk_mul_f32 v[66:67], v[68:69], v[180:181]
	s_nop 0
	v_pk_fma_f32 v[66:67], v[66:67], s[26:27], v[150:151] op_sel_hi:[1,1,0]
	s_nop 0
	v_mul_f32_e32 v68, 0x4b800000, v67
	v_cmp_gt_f32_e64 s[4:5], s50, v67
	v_cmp_gt_f32_e64 s[2:3], s50, v66
	s_nop 0
	v_cndmask_b32_e64 v67, v67, v68, s[4:5]
	v_rsq_f32_e32 v67, v67
	s_nop 0
	v_mul_f32_e32 v68, 0x45800000, v67
	v_cndmask_b32_e64 v67, v67, v68, s[4:5]
	v_mul_f32_e32 v68, v82, v67
	v_pk_mul_f32 v[60:61], v[60:61], v[68:69] op_sel_hi:[1,0]
	v_pk_mul_f32 v[56:57], v[56:57], v[68:69] op_sel_hi:[1,0]
	v_pk_mul_f32 v[58:59], v[58:59], v[68:69] op_sel_hi:[1,0]
	v_pk_mul_f32 v[62:63], v[62:63], v[68:69] op_sel_hi:[1,0]
	v_pk_mul_f32 v[52:53], v[52:53], v[68:69] op_sel_hi:[1,0]
	v_pk_mul_f32 v[54:55], v[54:55], v[68:69] op_sel_hi:[1,0]
	v_pk_mul_f32 v[48:49], v[48:49], v[68:69] op_sel_hi:[1,0]
	v_pk_mul_f32 v[50:51], v[50:51], v[68:69] op_sel_hi:[1,0]
	s_nop 0
	v_pk_mul_f32 v[60:61], v[190:191], v[60:61]
	v_pk_mul_f32 v[70:71], v[196:197], v[58:59]
	v_pk_mul_f32 v[58:59], v[194:195], v[56:57]
	v_pk_mul_f32 v[62:63], v[192:193], v[62:63]
	v_cvt_pk_bf16_f32 v56, v60, v61
	v_cvt_pk_bf16_f32 v58, v58, v59
	v_cvt_pk_bf16_f32 v59, v70, v71
	s_nop 0
	v_cvt_pk_bf16_f32 v57, v62, v63
	global_store_dwordx4 v[64:65], v[56:59], off nt
	s_nop 0
	s_nop 0
	s_nop 0
	s_waitcnt lgkmcnt(0)
; __device__ __forceinline__ unsigned cvt_pk_bf16(float lo, float hi) { unsigned r; asm("v_cvt_pk_bf16_f32 %0, %1, %2" : "=v"(r) : "v"(lo), "v"(hi)); return r; }
; __device__ __forceinline__ float rinv_of(unsigned long long ss) { return rsqrtf((float)ss * (1.f / 16777216.f) * (1.f / DM) + 1e-6f); }
;   __device__ __forceinline__ void operator()(const f32x4 (&acc)[2][2][4][2], const Unit& u, const EpiCtx& x_, int wr, int wc, int fr, int fq) const {
;     ...
; #pragma unroll
;     for (int ai = 0; ai < 2; ++ai)
; #pragma unroll
;       for (int m = 0; m < 4; ++m) {
;         const int t = u.r0 + ai * 128 + wr * 64 + m * 16 + fr;
;         const int seq = t / S, n = t % S, pos = seq * S + (n & ((1 << lg) - 1)) * L + (n >> lg);
;         const float rs = rinv_of(ssv[ai][m]);
;         const float* rp = (const float*)0; (void)rp;
;         const float r0 = red[((wr * 2 + hd) * 128 + ai * 64 + m * 16 + fr) * 2], r1 = red[((wr * 2 + hd) * 128 + ai * 64 + m * 16 + fr) * 2 + 1];
;         const float rinv = rs * rsqrtf((r0 + r1) * (rs * rs) * (1.f / 128.f) + 1e-6f);
; #pragma unroll
;         for (int bj = 0; bj < 2; ++bj) {
;           const f32x4 g0 = *(const f32x4*)(gbase + bj * 32), g1 = *(const f32x4*)(gbase + bj * 32 + 4);
;           const f32x4 v0 = acc[ai][bj][m][0] * rinv * g0, v1 = acc[ai][bj][m][1] * rinv * g1;
;           uint4 o; o.x = cvt_pk_bf16(v0[0], v0[1]); o.y = cvt_pk_bf16(v0[2], v0[3]); o.z = cvt_pk_bf16(v1[0], v1[1]); o.w = cvt_pk_bf16(v1[2], v1[3]);
;           *(uint4*)(obase + (size_t)pos * 128 + bj * 32) = o;
;         }
;       }
	v_pk_mul_f32 v[54:55], v[200:201], v[54:55]
	v_pk_mul_f32 v[52:53], v[198:199], v[52:53]
	v_pk_mul_f32 v[56:57], v[204:205], v[50:51]
	v_pk_mul_f32 v[50:51], v[202:203], v[48:49]
	v_cvt_pk_bf16_f32 v49, v54, v55
	v_cvt_pk_bf16_f32 v48, v52, v53
	s_nop 0
	v_cvt_pk_bf16_f32 v50, v50, v51
	v_cvt_pk_bf16_f32 v51, v56, v57
	global_store_dwordx4 v[64:65], v[48:51], off offset:64 nt
	v_add_u32_e32 v65, 0xa0, v140
	s_nop 0
	v_sub_u32_e32 v49, 0xffffff70, v140
	v_max_i32_e32 v49, v83, v49
	v_mul_hi_u32 v50, v49, v172
	v_mul_lo_u32 v50, v50, s17
	v_sub_u32_e32 v49, v49, v50
	v_cmp_le_u32_e64 s[4:5], s17, v49
	v_subrev_u32_e32 v50, s17, v49
	v_ashrrev_i32_e32 v48, 31, v83
	v_cndmask_b32_e64 v49, v49, v50, s[4:5]
	v_cmp_le_u32_e64 s[4:5], s17, v49
	v_subrev_u32_e32 v50, s17, v49
	s_nop 0
	v_cndmask_b32_e64 v49, v49, v50, s[4:5]
	v_xor_b32_e32 v49, v49, v48
	v_sub_u32_e32 v48, v49, v48
	v_bitop3_b32 v49, v48, s43, v48 bitop3:0x30
	v_mul_lo_u32 v49, v49, s42
	v_ashrrev_i32_e32 v50, s39, v48
	v_sub_u32_e32 v48, v83, v48
	v_add3_u32 v48, v48, v50, v49
	v_mul_f32_e32 v49, 0x4b800000, v66
	v_cndmask_b32_e64 v49, v66, v49, s[2:3]
	v_rsq_f32_e32 v49, v49
	s_nop 0
	v_mul_f32_e32 v50, 0x45800000, v49
	v_cndmask_b32_e64 v64, v49, v50, s[2:3]
	ds_read_b64 v[50:51], v80 offset:640
	s_nop 0
	s_nop 0
	v_mul_f32_e32 v53, v64, v64
	v_ashrrev_i32_e32 v49, 31, v48
	v_lshlrev_b64 v[48:49], 8, v[48:49]
	s_waitcnt lgkmcnt(0)
	v_pk_add_f32 v[50:51], v[50:51], v[50:51] op_sel_hi:[0,1]
	v_ffbh_u32_e32 v50, v149
	v_min_u32_e32 v50, 32, v50
	v_lshlrev_b64 v[62:63], v50, v[148:149]
	v_min_u32_e32 v52, 1, v62
	v_or_b32_e32 v52, v63, v52
	v_cvt_f32_u32_e32 v52, v52
	v_sub_u32_e32 v50, 32, v50
	v_mov_b32_e32 v181, v51
	v_lshl_add_u64 v[48:49], v[146:147], 0, v[48:49]
	v_ldexp_f32 v52, v52, v50
	v_pk_mul_f32 v[50:51], v[52:53], v[180:181]
	s_nop 0
	v_pk_fma_f32 v[50:51], v[50:51], s[26:27], v[150:151] op_sel_hi:[1,1,0]
	s_nop 0
	v_mul_f32_e32 v52, 0x4b800000, v51
	v_cmp_gt_f32_e64 s[4:5], s50, v51
	v_cmp_gt_f32_e64 s[2:3], s50, v50
	s_nop 0
	v_cndmask_b32_e64 v51, v51, v52, s[4:5]
	v_rsq_f32_e32 v51, v51
	s_nop 0
	v_mul_f32_e32 v52, 0x45800000, v51
	v_cndmask_b32_e64 v51, v51, v52, s[4:5]
	v_mul_f32_e32 v52, v64, v51
	v_pk_mul_f32 v[44:45], v[44:45], v[52:53] op_sel_hi:[1,0]
	v_pk_mul_f32 v[40:41], v[40:41], v[52:53] op_sel_hi:[1,0]
	v_pk_mul_f32 v[42:43], v[42:43], v[52:53] op_sel_hi:[1,0]
	v_pk_mul_f32 v[46:47], v[46:47], v[52:53] op_sel_hi:[1,0]
	v_pk_mul_f32 v[36:37], v[36:37], v[52:53] op_sel_hi:[1,0]
	v_pk_mul_f32 v[38:39], v[38:39], v[52:53] op_sel_hi:[1,0]
	v_pk_mul_f32 v[32:33], v[32:33], v[52:53] op_sel_hi:[1,0]
	v_pk_mul_f32 v[34:35], v[34:35], v[52:53] op_sel_hi:[1,0]
	s_nop 0
	v_pk_mul_f32 v[44:45], v[190:191], v[44:45]
	v_pk_mul_f32 v[54:55], v[196:197], v[42:43]
	v_pk_mul_f32 v[42:43], v[194:195], v[40:41]
	v_pk_mul_f32 v[46:47], v[192:193], v[46:47]
	v_cvt_pk_bf16_f32 v40, v44, v45
	v_cvt_pk_bf16_f32 v42, v42, v43
	v_cvt_pk_bf16_f32 v43, v54, v55
	s_nop 0
	v_cvt_pk_bf16_f32 v41, v46, v47
	global_store_dwordx4 v[48:49], v[40:43], off nt
	s_nop 0
	s_nop 0
	s_nop 0
	s_waitcnt lgkmcnt(0)
	v_pk_mul_f32 v[38:39], v[200:201], v[38:39]
	v_pk_mul_f32 v[36:37], v[198:199], v[36:37]
	v_pk_mul_f32 v[40:41], v[204:205], v[34:35]
	v_pk_mul_f32 v[34:35], v[202:203], v[32:33]
	v_cvt_pk_bf16_f32 v33, v38, v39
	v_cvt_pk_bf16_f32 v32, v36, v37
	s_nop 0
	v_cvt_pk_bf16_f32 v34, v34, v35
	v_cvt_pk_bf16_f32 v35, v40, v41
	global_store_dwordx4 v[48:49], v[32:35], off offset:64 nt
	v_add_u32_e32 v49, 0xb0, v140
	s_nop 0
	v_sub_u32_e32 v33, 0xffffff60, v140
	v_max_i32_e32 v33, v65, v33
	v_mul_hi_u32 v34, v33, v172
	v_mul_lo_u32 v34, v34, s17
	v_sub_u32_e32 v33, v33, v34
	v_cmp_le_u32_e64 s[4:5], s17, v33
	v_subrev_u32_e32 v34, s17, v33
	v_ashrrev_i32_e32 v32, 31, v65
	v_cndmask_b32_e64 v33, v33, v34, s[4:5]
	v_cmp_le_u32_e64 s[4:5], s17, v33
	v_subrev_u32_e32 v34, s17, v33
	s_nop 0
	v_cndmask_b32_e64 v33, v33, v34, s[4:5]
	v_xor_b32_e32 v33, v33, v32
	v_sub_u32_e32 v32, v33, v32
	v_bitop3_b32 v33, v32, s43, v32 bitop3:0x30
	v_mul_lo_u32 v33, v33, s42
	v_ashrrev_i32_e32 v34, s39, v32
	v_sub_u32_e32 v32, v65, v32
	v_add3_u32 v32, v32, v34, v33
	v_mul_f32_e32 v33, 0x4b800000, v50
	v_cndmask_b32_e64 v33, v50, v33, s[2:3]
	v_rsq_f32_e32 v33, v33
	s_nop 0
	v_mul_f32_e32 v34, 0x45800000, v33
	v_cndmask_b32_e64 v48, v33, v34, s[2:3]
	ds_read_b64 v[34:35], v80 offset:768
	s_nop 0
	s_nop 0
	v_mul_f32_e32 v37, v48, v48
	v_ashrrev_i32_e32 v33, 31, v32
	v_lshlrev_b64 v[32:33], 8, v[32:33]
	s_waitcnt lgkmcnt(0)
; __device__ __forceinline__ unsigned cvt_pk_bf16(float lo, float hi) { unsigned r; asm("v_cvt_pk_bf16_f32 %0, %1, %2" : "=v"(r) : "v"(lo), "v"(hi)); return r; }
; __device__ __forceinline__ float rinv_of(unsigned long long ss) { return rsqrtf((float)ss * (1.f / 16777216.f) * (1.f / DM) + 1e-6f); }
;   __device__ __forceinline__ void operator()(const f32x4 (&acc)[2][2][4][2], const Unit& u, const EpiCtx& x_, int wr, int wc, int fr, int fq) const {
;     ...
; #pragma unroll
;     for (int ai = 0; ai < 2; ++ai)
; #pragma unroll
;       for (int m = 0; m < 4; ++m) {
;         const int t = u.r0 + ai * 128 + wr * 64 + m * 16 + fr;
;         const int seq = t / S, n = t % S, pos = seq * S + (n & ((1 << lg) - 1)) * L + (n >> lg);
;         const float rs = rinv_of(ssv[ai][m]);
;         const float* rp = (const float*)0; (void)rp;
;         const float r0 = red[((wr * 2 + hd) * 128 + ai * 64 + m * 16 + fr) * 2], r1 = red[((wr * 2 + hd) * 128 + ai * 64 + m * 16 + fr) * 2 + 1];
;         const float rinv = rs * rsqrtf((r0 + r1) * (rs * rs) * (1.f / 128.f) + 1e-6f);
; #pragma unroll
;         for (int bj = 0; bj < 2; ++bj) {
;           const f32x4 g0 = *(const f32x4*)(gbase + bj * 32), g1 = *(const f32x4*)(gbase + bj * 32 + 4);
;           const f32x4 v0 = acc[ai][bj][m][0] * rinv * g0, v1 = acc[ai][bj][m][1] * rinv * g1;
;           uint4 o; o.x = cvt_pk_bf16(v0[0], v0[1]); o.y = cvt_pk_bf16(v0[2], v0[3]); o.z = cvt_pk_bf16(v1[0], v1[1]); o.w = cvt_pk_bf16(v1[2], v1[3]);
;           *(uint4*)(obase + (size_t)pos * 128 + bj * 32) = o;
;         }
;       }
	v_pk_add_f32 v[34:35], v[34:35], v[34:35] op_sel_hi:[0,1]
	v_ffbh_u32_e32 v34, v145
	v_min_u32_e32 v34, 32, v34
	v_lshlrev_b64 v[46:47], v34, v[144:145]
	v_min_u32_e32 v36, 1, v46
	v_or_b32_e32 v36, v47, v36
	v_cvt_f32_u32_e32 v36, v36
	v_sub_u32_e32 v34, 32, v34
	v_mov_b32_e32 v181, v35
	v_lshl_add_u64 v[32:33], v[146:147], 0, v[32:33]
	v_ldexp_f32 v36, v36, v34
	v_pk_mul_f32 v[34:35], v[36:37], v[180:181]
	s_nop 0
	v_pk_fma_f32 v[34:35], v[34:35], s[26:27], v[150:151] op_sel_hi:[1,1,0]
	s_nop 0
	v_mul_f32_e32 v36, 0x4b800000, v35
	v_cmp_gt_f32_e64 s[4:5], s50, v35
	v_cmp_gt_f32_e64 s[2:3], s50, v34
	s_nop 0
	v_cndmask_b32_e64 v35, v35, v36, s[4:5]
	v_rsq_f32_e32 v35, v35
	s_nop 0
	v_mul_f32_e32 v36, 0x45800000, v35
	v_cndmask_b32_e64 v35, v35, v36, s[4:5]
	v_mul_f32_e32 v36, v48, v35
	v_pk_mul_f32 v[28:29], v[28:29], v[36:37] op_sel_hi:[1,0]
	v_pk_mul_f32 v[24:25], v[24:25], v[36:37] op_sel_hi:[1,0]
	v_pk_mul_f32 v[26:27], v[26:27], v[36:37] op_sel_hi:[1,0]
	v_pk_mul_f32 v[30:31], v[30:31], v[36:37] op_sel_hi:[1,0]
	v_pk_mul_f32 v[20:21], v[20:21], v[36:37] op_sel_hi:[1,0]
	v_pk_mul_f32 v[22:23], v[22:23], v[36:37] op_sel_hi:[1,0]
	v_pk_mul_f32 v[16:17], v[16:17], v[36:37] op_sel_hi:[1,0]
	v_pk_mul_f32 v[18:19], v[18:19], v[36:37] op_sel_hi:[1,0]
	s_nop 0
	v_pk_mul_f32 v[28:29], v[190:191], v[28:29]
	v_pk_mul_f32 v[38:39], v[196:197], v[26:27]
	v_pk_mul_f32 v[26:27], v[194:195], v[24:25]
	v_pk_mul_f32 v[30:31], v[192:193], v[30:31]
	v_cvt_pk_bf16_f32 v24, v28, v29
	v_cvt_pk_bf16_f32 v26, v26, v27
	v_cvt_pk_bf16_f32 v27, v38, v39
	s_nop 0
	v_cvt_pk_bf16_f32 v25, v30, v31
	global_store_dwordx4 v[32:33], v[24:27], off nt
	s_nop 0
	s_nop 0
	s_nop 0
	s_waitcnt lgkmcnt(0)
	v_pk_mul_f32 v[22:23], v[200:201], v[22:23]
	v_pk_mul_f32 v[20:21], v[198:199], v[20:21]
	v_pk_mul_f32 v[24:25], v[204:205], v[18:19]
	v_pk_mul_f32 v[18:19], v[202:203], v[16:17]
	v_cvt_pk_bf16_f32 v17, v22, v23
	v_cvt_pk_bf16_f32 v16, v20, v21
	s_nop 0
	v_cvt_pk_bf16_f32 v18, v18, v19
	v_cvt_pk_bf16_f32 v19, v24, v25
	global_store_dwordx4 v[32:33], v[16:19], off offset:64 nt
	s_nop 1
	v_sub_u32_e32 v17, 0xffffff50, v140
	v_max_i32_e32 v17, v49, v17
	v_mul_hi_u32 v18, v17, v172
	v_mul_lo_u32 v18, v18, s17
	v_sub_u32_e32 v17, v17, v18
	v_cmp_le_u32_e64 s[4:5], s17, v17
	v_subrev_u32_e32 v18, s17, v17
	v_ashrrev_i32_e32 v16, 31, v49
	v_cndmask_b32_e64 v17, v17, v18, s[4:5]
	v_cmp_le_u32_e64 s[4:5], s17, v17
	v_subrev_u32_e32 v18, s17, v17
	s_nop 0
	v_cndmask_b32_e64 v17, v17, v18, s[4:5]
	v_xor_b32_e32 v17, v17, v16
	v_sub_u32_e32 v16, v17, v16
	v_bitop3_b32 v17, v16, s43, v16 bitop3:0x30
	v_mul_lo_u32 v17, v17, s42
	v_ashrrev_i32_e32 v18, s39, v16
	v_sub_u32_e32 v16, v49, v16
	v_add3_u32 v16, v16, v18, v17
	v_mul_f32_e32 v17, 0x4b800000, v34
	v_cndmask_b32_e64 v17, v34, v17, s[2:3]
	v_rsq_f32_e32 v17, v17
	s_mov_b64 s[4:5], s[94:95]
	v_mul_f32_e32 v18, 0x45800000, v17
	v_cndmask_b32_e64 v17, v17, v18, s[2:3]
	ds_read_b64 v[18:19], v80 offset:896
	s_nop 0
	s_nop 0
	s_waitcnt lgkmcnt(0)
	v_add_f32_e32 v18, v18, v19
	v_mul_f32_e32 v19, v17, v17
	v_mul_f32_e32 v18, v19, v18
	v_fmamk_f32 v18, v18, 0x3c000000, v234
	v_cmp_gt_f32_e64 s[2:3], s50, v18
	v_mul_f32_e32 v19, 0x4b800000, v18
	s_nop 0
	v_cndmask_b32_e64 v18, v18, v19, s[2:3]
	v_rsq_f32_e32 v18, v18
	s_nop 0
	v_mul_f32_e32 v19, 0x45800000, v18
	v_cndmask_b32_e64 v18, v18, v19, s[2:3]
	v_mul_f32_e32 v18, v17, v18
	v_ashrrev_i32_e32 v17, 31, v16
	v_lshlrev_b64 v[16:17], 8, v[16:17]
	v_pk_mul_f32 v[12:13], v[12:13], v[18:19] op_sel_hi:[1,0]
	v_pk_mul_f32 v[8:9], v[8:9], v[18:19] op_sel_hi:[1,0]
	v_pk_mul_f32 v[10:11], v[10:11], v[18:19] op_sel_hi:[1,0]
	v_lshl_add_u64 v[16:17], v[146:147], 0, v[16:17]
	v_pk_mul_f32 v[14:15], v[14:15], v[18:19] op_sel_hi:[1,0]
	v_pk_mul_f32 v[4:5], v[4:5], v[18:19] op_sel_hi:[1,0]
	v_pk_mul_f32 v[0:1], v[0:1], v[18:19] op_sel_hi:[1,0]
	v_pk_mul_f32 v[2:3], v[2:3], v[18:19] op_sel_hi:[1,0]
	v_pk_mul_f32 v[6:7], v[6:7], v[18:19] op_sel_hi:[1,0]
	s_nop 0
	v_pk_mul_f32 v[12:13], v[190:191], v[12:13]
	v_pk_mul_f32 v[20:21], v[196:197], v[10:11]
	v_pk_mul_f32 v[10:11], v[194:195], v[8:9]
	v_pk_mul_f32 v[14:15], v[192:193], v[14:15]
	v_cvt_pk_bf16_f32 v8, v12, v13
	v_cvt_pk_bf16_f32 v10, v10, v11
	v_cvt_pk_bf16_f32 v11, v20, v21
	s_nop 0
	v_cvt_pk_bf16_f32 v9, v14, v15
	global_store_dwordx4 v[16:17], v[8:11], off nt
	s_nop 0
	s_nop 0
	s_nop 0
	s_waitcnt lgkmcnt(0)
	v_pk_mul_f32 v[4:5], v[198:199], v[4:5]
	v_pk_mul_f32 v[8:9], v[204:205], v[2:3]
	v_pk_mul_f32 v[2:3], v[202:203], v[0:1]
	v_pk_mul_f32 v[6:7], v[200:201], v[6:7]
	v_cvt_pk_bf16_f32 v0, v4, v5
	v_cvt_pk_bf16_f32 v2, v2, v3
	v_cvt_pk_bf16_f32 v3, v8, v9
	s_nop 0
	v_cvt_pk_bf16_f32 v1, v6, v7
	global_store_dwordx4 v[16:17], v[0:3], off offset:64 nt
	s_cbranch_scc1 .LBB0_606

; #define G_STAGE(bufoff, gbase, voff) do { _Pragma("unroll") for (int _i = 0; _i < 2; ++_i) { unsigned _vo = (voff)[_i]; asm volatile("" : "+v"(_vo));   \
;     __builtin_amdgcn_global_load_lds((const unsigned*)((const char*)(gbase) + _vo), (LAS unsigned*)(lds + (bufoff) + ldsw + _i * 8192), 16, 0, 0); } } while (0)
; #define G_LDA(dst, b, h) do { _Pragma("unroll") for (int m = 0; m < 4; ++m) _Pragma("unroll") for (int k = 0; k < 2; ++k) dst[m][k] = *(const LAS bf16x8*)(lds + G_SA(b, h) + aoff + m * 2048 + k * 1024); } while (0)
; #define G_LDB(dst, b, h) do { _Pragma("unroll") for (int n = 0; n < 2; ++n) _Pragma("unroll") for (int k = 0; k < 2; ++k) dst[n][k] = *(const LAS bf16x8*)(lds + G_SB(b, h) + boff + n * 2048 + k * 1024); } while (0)
; #define G_MMA(ai, bj, At, Bt) do { __builtin_amdgcn_s_setprio(1); _Pragma("unroll") for (int m = 0; m < 4; ++m) _Pragma("unroll") for (int n = 0; n < 2; ++n) _Pragma("unroll") for (int k = 0; k < 2; ++k) \
;     acc[ai][bj][m][n] = __builtin_amdgcn_mfma_f32_16x16x32_bf16(Bt[n][k], At[m][k], acc[ai][bj][m][n], 0, 0, 0); __builtin_amdgcn_s_setprio(0); } while (0)
; template <class Epi>
; __device__ __forceinline__ void gemm_phase(LAS unsigned char* lds, const int K, const unsigned lda_b, const unsigned ldb_b, const Map& M, const Epi& E) {
;     ...
;     for (int t = 0; t < nt; t += 2) {
;       const bool last = (t == nt - 2);
;       const char* a1h1 = cur.a0 + a_h + (size_t)(t + 1) * kstep;
;       const char* a2h0 = last ? nxt.a0 : cur.a0 + (size_t)(t + 2) * kstep; const char* a2h1 = a2h0 + a_h;
;       const char* b2h0 = last ? nxt.b0 : cur.b0 + (size_t)(t + 2) * kstep; const char* b2h1 = last ? nxt.b1 : cur.b1 + (size_t)(t + 2) * kstep;
;       G_LDB(B0, 0, 0); G_SCHED; G_LDA(At, 0, 0); G_STAGE(G_SA(1, 1), a1h1, voffA);
;       G_WAIT_L(8); G_BAR; G_WAIT_L(0); G_MMA(0, 0, At, B0); G_BAR; G_SCHED;
;       G_LDB(B1, 0, 1); G_STAGE(G_SB(0, 0), b2h0, voffB);
;       G_BAR; G_WAIT_L(0); G_MMA(0, 1, At, B1); G_BAR;
;       G_LDA(At, 0, 1); G_STAGE(G_SA(0, 0), a2h0, voffA);
;       G_BAR; G_WAIT_L(0); G_MMA(1, 0, At, B0); G_BAR; G_SCHED;
;       G_STAGE(G_SB(0, 1), b2h1, voffB);
;       G_WAIT_V(6); G_BAR; G_MMA(1, 1, At, B1); G_BAR;
;       G_LDB(B0, 1, 0); G_SCHED; G_LDA(At, 1, 0); G_STAGE(G_SA(0, 1), a2h1, voffA);
;       G_WAIT_L(8); G_BAR; G_WAIT_L(0); G_MMA(0, 0, At, B0); G_BAR; G_SCHED;
.LBB0_626:
	s_add_u32 s22, s38, 0xfff80080
	s_addc_u32 s35, s39, -1
	s_add_u32 s42, s30, 0xfffe0000
	s_addc_u32 s43, s31, -1
	s_add_i32 s81, 0, 0x10000
	v_add_u32_e32 v0, s81, v149
	ds_read_b128 v[136:139], v0
	ds_read_b128 v[140:143], v0 offset:1024
	ds_read_b128 v[154:157], v0 offset:2048
	ds_read_b128 v[158:161], v0 offset:3072
	s_cmp_eq_u32 s34, 28
	s_cselect_b32 s45, s37, s35
	s_cselect_b32 s44, s36, s22
	s_cselect_b32 s69, s41, s43
	s_cselect_b32 s68, s40, s42
	v_mov_b32_e32 v0, v144
	s_cselect_b32 s43, s29, s31
	s_cselect_b32 s42, s28, s30
	s_add_u32 s94, s44, 0x80000
	ds_read_b128 v[164:167], v153
	ds_read_b128 v[168:171], v153 offset:1024
	ds_read_b128 v[172:175], v153 offset:2048
	ds_read_b128 v[190:193], v153 offset:3072
	ds_read_b128 v[194:197], v153 offset:4096
	ds_read_b128 v[198:201], v153 offset:5120
	ds_read_b128 v[202:205], v153 offset:6144
	ds_read_b128 v[206:209], v153 offset:7168
	s_addc_u32 s95, s45, 0
	s_add_i32 m0, s18, 0xc000
	s_nop 0
	global_load_lds_dwordx4 v0, s[38:39]
	v_mov_b32_e32 v0, v146
	s_add_i32 m0, s18, 0xe000
	s_nop 0
	global_load_lds_dwordx4 v0, s[38:39]
	s_waitcnt lgkmcnt(8)
	s_barrier
	s_waitcnt lgkmcnt(0)
	s_setprio 1
	s_waitcnt lgkmcnt(0)
	v_mfma_f32_16x16x32_bf16 v[130:133], v[136:139], v[164:167], v[130:133]
	v_mfma_f32_16x16x32_bf16 v[126:129], v[154:157], v[164:167], v[126:129]
	v_mfma_f32_16x16x32_bf16 v[114:117], v[136:139], v[172:175], v[114:117]
	v_mfma_f32_16x16x32_bf16 v[110:113], v[154:157], v[172:175], v[110:113]
	v_mfma_f32_16x16x32_bf16 v[98:101], v[136:139], v[194:197], v[98:101]
	v_mfma_f32_16x16x32_bf16 v[94:97], v[154:157], v[194:197], v[94:97]
	v_mfma_f32_16x16x32_bf16 v[82:85], v[136:139], v[202:205], v[82:85]
	v_mfma_f32_16x16x32_bf16 v[76:79], v[154:157], v[202:205], v[76:79]
	v_mfma_f32_16x16x32_bf16 v[130:133], v[140:143], v[168:171], v[130:133]
	v_mfma_f32_16x16x32_bf16 v[126:129], v[158:161], v[168:171], v[126:129]
	v_mfma_f32_16x16x32_bf16 v[114:117], v[140:143], v[190:193], v[114:117]
	v_mfma_f32_16x16x32_bf16 v[110:113], v[158:161], v[190:193], v[110:113]
	v_mfma_f32_16x16x32_bf16 v[98:101], v[140:143], v[198:201], v[98:101]
	v_mfma_f32_16x16x32_bf16 v[94:97], v[158:161], v[198:201], v[94:97]
	v_mfma_f32_16x16x32_bf16 v[82:85], v[140:143], v[206:209], v[82:85]
	v_mfma_f32_16x16x32_bf16 v[76:79], v[158:161], v[206:209], v[76:79]
	s_setprio 0
	s_barrier
	s_add_i32 s22, 0, 0x14000
	v_add_u32_e32 v0, s22, v149
	ds_read_b128 v[210:213], v0
	ds_read_b128 v[214:217], v0 offset:1024
	ds_read_b128 v[238:241], v0 offset:2048
	ds_read_b128 v[242:245], v0 offset:3072
	v_mov_b32_e32 v0, v145
	s_add_i32 s35, s81, s13
	s_mov_b32 m0, s35
	s_nop 0
	global_load_lds_dwordx4 v0, s[68:69]
	v_mov_b32_e32 v0, v147
	s_add_i32 m0, s35, 0x2000
	s_nop 0
	global_load_lds_dwordx4 v0, s[68:69]
	s_barrier
	s_waitcnt lgkmcnt(0)
	s_setprio 1
	s_waitcnt lgkmcnt(0)
	v_mfma_f32_16x16x32_bf16 v[122:125], v[210:213], v[164:167], v[122:125]
	v_mfma_f32_16x16x32_bf16 v[118:121], v[238:241], v[164:167], v[118:121]
	v_mfma_f32_16x16x32_bf16 v[106:109], v[210:213], v[172:175], v[106:109]
	v_mfma_f32_16x16x32_bf16 v[102:105], v[238:241], v[172:175], v[102:105]
	v_mfma_f32_16x16x32_bf16 v[90:93], v[210:213], v[194:197], v[90:93]
	v_mfma_f32_16x16x32_bf16 v[86:89], v[238:241], v[194:197], v[86:89]
	v_mfma_f32_16x16x32_bf16 v[72:75], v[210:213], v[202:205], v[72:75]
	v_mfma_f32_16x16x32_bf16 v[68:71], v[238:241], v[202:205], v[68:71]
	v_mfma_f32_16x16x32_bf16 v[122:125], v[214:217], v[168:171], v[122:125]
	v_mfma_f32_16x16x32_bf16 v[118:121], v[242:245], v[168:171], v[118:121]
	v_mfma_f32_16x16x32_bf16 v[106:109], v[214:217], v[190:193], v[106:109]
	v_mfma_f32_16x16x32_bf16 v[102:105], v[242:245], v[190:193], v[102:105]
	v_mfma_f32_16x16x32_bf16 v[90:93], v[214:217], v[198:201], v[90:93]
	v_mfma_f32_16x16x32_bf16 v[86:89], v[242:245], v[198:201], v[86:89]
	v_mfma_f32_16x16x32_bf16 v[72:75], v[214:217], v[206:209], v[72:75]
	v_mfma_f32_16x16x32_bf16 v[68:71], v[242:245], v[206:209], v[68:71]
	s_setprio 0
	v_mov_b32_e32 v0, v144
	s_mov_b32 m0, s18
	s_barrier
	ds_read_b128 v[164:167], v153 offset:16384
	ds_read_b128 v[168:171], v153 offset:17408
	ds_read_b128 v[172:175], v153 offset:18432
	ds_read_b128 v[190:193], v153 offset:19456
	ds_read_b128 v[194:197], v153 offset:20480
	ds_read_b128 v[198:201], v153 offset:21504
	ds_read_b128 v[202:205], v153 offset:22528
	ds_read_b128 v[206:209], v153 offset:23552
	s_nop 0
	global_load_lds_dwordx4 v0, s[44:45]
	v_mov_b32_e32 v0, v146
	s_mov_b32 m0, s19
	s_nop 0
	global_load_lds_dwordx4 v0, s[44:45]
	s_barrier
	s_waitcnt lgkmcnt(0)
	s_setprio 1
	s_waitcnt lgkmcnt(0)
	v_mfma_f32_16x16x32_bf16 v[64:67], v[136:139], v[164:167], v[64:67]
	v_mfma_f32_16x16x32_bf16 v[60:63], v[154:157], v[164:167], v[60:63]
	v_mfma_f32_16x16x32_bf16 v[48:51], v[136:139], v[172:175], v[48:51]
	v_mfma_f32_16x16x32_bf16 v[44:47], v[154:157], v[172:175], v[44:47]
	v_mfma_f32_16x16x32_bf16 v[32:35], v[136:139], v[194:197], v[32:35]
	v_mfma_f32_16x16x32_bf16 v[28:31], v[154:157], v[194:197], v[28:31]
	v_mfma_f32_16x16x32_bf16 v[16:19], v[136:139], v[202:205], v[16:19]
	v_mfma_f32_16x16x32_bf16 v[12:15], v[154:157], v[202:205], v[12:15]
	v_mfma_f32_16x16x32_bf16 v[64:67], v[140:143], v[168:171], v[64:67]
	v_mfma_f32_16x16x32_bf16 v[60:63], v[158:161], v[168:171], v[60:63]
	v_mfma_f32_16x16x32_bf16 v[48:51], v[140:143], v[190:193], v[48:51]
	v_mfma_f32_16x16x32_bf16 v[44:47], v[158:161], v[190:193], v[44:47]
	v_mfma_f32_16x16x32_bf16 v[32:35], v[140:143], v[198:201], v[32:35]
	v_mfma_f32_16x16x32_bf16 v[28:31], v[158:161], v[198:201], v[28:31]
	v_mfma_f32_16x16x32_bf16 v[16:19], v[140:143], v[206:209], v[16:19]
	v_mfma_f32_16x16x32_bf16 v[12:15], v[158:161], v[206:209], v[12:15]
	s_setprio 0
	s_barrier
; #define G_STAGE(bufoff, gbase, voff) do { _Pragma("unroll") for (int _i = 0; _i < 2; ++_i) { unsigned _vo = (voff)[_i]; asm volatile("" : "+v"(_vo));   \
;     __builtin_amdgcn_global_load_lds((const unsigned*)((const char*)(gbase) + _vo), (LAS unsigned*)(lds + (bufoff) + ldsw + _i * 8192), 16, 0, 0); } } while (0)
; #define G_LDA(dst, b, h) do { _Pragma("unroll") for (int m = 0; m < 4; ++m) _Pragma("unroll") for (int k = 0; k < 2; ++k) dst[m][k] = *(const LAS bf16x8*)(lds + G_SA(b, h) + aoff + m * 2048 + k * 1024); } while (0)
; #define G_LDB(dst, b, h) do { _Pragma("unroll") for (int n = 0; n < 2; ++n) _Pragma("unroll") for (int k = 0; k < 2; ++k) dst[n][k] = *(const LAS bf16x8*)(lds + G_SB(b, h) + boff + n * 2048 + k * 1024); } while (0)
; #define G_MMA(ai, bj, At, Bt) do { __builtin_amdgcn_s_setprio(1); _Pragma("unroll") for (int m = 0; m < 4; ++m) _Pragma("unroll") for (int n = 0; n < 2; ++n) _Pragma("unroll") for (int k = 0; k < 2; ++k) \
;     acc[ai][bj][m][n] = __builtin_amdgcn_mfma_f32_16x16x32_bf16(Bt[n][k], At[m][k], acc[ai][bj][m][n], 0, 0, 0); __builtin_amdgcn_s_setprio(0); } while (0)
; #define G_WAIT_V(n) asm volatile("s_waitcnt vmcnt(" #n ")" ::: "memory")
; #define G_WAIT_L(n) asm volatile("s_waitcnt lgkmcnt(" #n ")" ::: "memory")
; template <class Epi>
; __device__ __forceinline__ void gemm_phase(LAS unsigned char* lds, const int K, const unsigned lda_b, const unsigned ldb_b, const Map& M, const Epi& E) {
;     ...
;       G_LDB(B0, 0, 0); G_SCHED; G_LDA(At, 0, 0); G_STAGE(G_SA(1, 1), a1h1, voffA);
;       G_WAIT_L(8); G_BAR; G_WAIT_L(0); G_MMA(0, 0, At, B0); G_BAR; G_SCHED;
;       G_LDB(B1, 0, 1); G_STAGE(G_SB(0, 0), b2h0, voffB);
;       G_BAR; G_WAIT_L(0); G_MMA(0, 1, At, B1); G_BAR;
;       G_LDA(At, 0, 1); G_STAGE(G_SA(0, 0), a2h0, voffA);
;       G_BAR; G_WAIT_L(0); G_MMA(1, 0, At, B0); G_BAR; G_SCHED;
;       G_STAGE(G_SB(0, 1), b2h1, voffB);
;       G_WAIT_V(6); G_BAR; G_MMA(1, 1, At, B1); G_BAR;
;       G_LDB(B0, 1, 0); G_SCHED; G_LDA(At, 1, 0); G_STAGE(G_SA(0, 1), a2h1, voffA);
;       G_WAIT_L(8); G_BAR; G_WAIT_L(0); G_MMA(0, 0, At, B0); G_BAR; G_SCHED;
;       G_LDB(B1, 1, 1); G_STAGE(G_SB(1, 0), b2h0 + kstep, voffB);
;       G_BAR; G_WAIT_L(0); G_MMA(0, 1, At, B1); G_BAR;
;       G_LDA(At, 1, 1); G_STAGE(G_SA(1, 0), a2h0 + kstep, voffA);
;       G_BAR; G_WAIT_L(0); G_MMA(1, 0, At, B0); G_BAR; G_SCHED;
	v_mov_b32_e32 v0, v145
	s_add_i32 s22, s22, s13
	s_mov_b32 m0, s22
	s_nop 0
	global_load_lds_dwordx4 v0, s[42:43]
	v_mov_b32_e32 v0, v147
	s_add_i32 m0, s22, 0x2000
	s_nop 0
	global_load_lds_dwordx4 v0, s[42:43]
	s_waitcnt vmcnt(6)
	s_barrier
	s_setprio 1
	v_mfma_f32_16x16x32_bf16 v[56:59], v[210:213], v[164:167], v[56:59]
	v_mfma_f32_16x16x32_bf16 v[52:55], v[238:241], v[164:167], v[52:55]
	v_mfma_f32_16x16x32_bf16 v[40:43], v[210:213], v[172:175], v[40:43]
	v_mfma_f32_16x16x32_bf16 v[36:39], v[238:241], v[172:175], v[36:39]
	v_mfma_f32_16x16x32_bf16 v[24:27], v[210:213], v[194:197], v[24:27]
	v_mfma_f32_16x16x32_bf16 v[20:23], v[238:241], v[194:197], v[20:23]
	v_mfma_f32_16x16x32_bf16 v[8:11], v[210:213], v[202:205], v[8:11]
	v_mfma_f32_16x16x32_bf16 v[4:7], v[238:241], v[202:205], v[4:7]
	v_mfma_f32_16x16x32_bf16 v[56:59], v[214:217], v[168:171], v[56:59]
	v_mfma_f32_16x16x32_bf16 v[52:55], v[242:245], v[168:171], v[52:55]
	v_mfma_f32_16x16x32_bf16 v[40:43], v[214:217], v[190:193], v[40:43]
	v_mfma_f32_16x16x32_bf16 v[36:39], v[242:245], v[190:193], v[36:39]
	v_mfma_f32_16x16x32_bf16 v[24:27], v[214:217], v[198:201], v[24:27]
	v_mfma_f32_16x16x32_bf16 v[20:23], v[242:245], v[198:201], v[20:23]
	v_mfma_f32_16x16x32_bf16 v[8:11], v[214:217], v[206:209], v[8:11]
	v_mfma_f32_16x16x32_bf16 v[4:7], v[242:245], v[206:209], v[4:7]
	s_setprio 0
	s_add_i32 s22, 0, 0x18000
	v_add_u32_e32 v0, s22, v149
	s_barrier
	ds_read_b128 v[136:139], v0
	ds_read_b128 v[140:143], v0 offset:1024
	ds_read_b128 v[154:157], v0 offset:2048
	ds_read_b128 v[158:161], v0 offset:3072
	v_mov_b32_e32 v0, v144
	s_mov_b32 m0, s46
	ds_read_b128 v[164:167], v153 offset:32768
	ds_read_b128 v[168:171], v153 offset:33792
	ds_read_b128 v[172:175], v153 offset:34816
	ds_read_b128 v[190:193], v153 offset:35840
	ds_read_b128 v[194:197], v153 offset:36864
	ds_read_b128 v[198:201], v153 offset:37888
	ds_read_b128 v[202:205], v153 offset:38912
	ds_read_b128 v[206:209], v153 offset:39936
	s_nop 0
	global_load_lds_dwordx4 v0, s[94:95]
	v_mov_b32_e32 v0, v146
	s_mov_b32 m0, s47
	s_nop 0
	global_load_lds_dwordx4 v0, s[94:95]
	s_waitcnt lgkmcnt(8)
	s_barrier
	s_waitcnt lgkmcnt(0)
	s_setprio 1
	s_waitcnt lgkmcnt(0)
	v_mfma_f32_16x16x32_bf16 v[130:133], v[136:139], v[164:167], v[130:133]
	v_mfma_f32_16x16x32_bf16 v[126:129], v[154:157], v[164:167], v[126:129]
	v_mfma_f32_16x16x32_bf16 v[114:117], v[136:139], v[172:175], v[114:117]
	v_mfma_f32_16x16x32_bf16 v[110:113], v[154:157], v[172:175], v[110:113]
	v_mfma_f32_16x16x32_bf16 v[98:101], v[136:139], v[194:197], v[98:101]
	v_mfma_f32_16x16x32_bf16 v[94:97], v[154:157], v[194:197], v[94:97]
	v_mfma_f32_16x16x32_bf16 v[82:85], v[136:139], v[202:205], v[82:85]
	v_mfma_f32_16x16x32_bf16 v[76:79], v[154:157], v[202:205], v[76:79]
	v_mfma_f32_16x16x32_bf16 v[130:133], v[140:143], v[168:171], v[130:133]
	v_mfma_f32_16x16x32_bf16 v[126:129], v[158:161], v[168:171], v[126:129]
	v_mfma_f32_16x16x32_bf16 v[114:117], v[140:143], v[190:193], v[114:117]
	v_mfma_f32_16x16x32_bf16 v[110:113], v[158:161], v[190:193], v[110:113]
	v_mfma_f32_16x16x32_bf16 v[98:101], v[140:143], v[198:201], v[98:101]
	v_mfma_f32_16x16x32_bf16 v[94:97], v[158:161], v[198:201], v[94:97]
	v_mfma_f32_16x16x32_bf16 v[82:85], v[140:143], v[206:209], v[82:85]
	v_mfma_f32_16x16x32_bf16 v[76:79], v[158:161], v[206:209], v[76:79]
	s_setprio 0
	s_barrier
	s_add_i32 s35, 0, 0x1c000
	v_add_u32_e32 v0, s35, v149
	v_mov_b32_e32 v80, v145
	ds_read_b128 v[210:213], v0
	ds_read_b128 v[214:217], v0 offset:1024
	ds_read_b128 v[238:241], v0 offset:2048
	ds_read_b128 v[242:245], v0 offset:3072
	s_add_i32 s22, s22, s13
	s_add_i32 m0, s22, 0xffffff80
	v_mov_b32_e32 v80, v147
	global_load_lds_dwordx4 v145, s[68:69] offset:128
	s_add_i32 m0, s22, 0x1f80
	s_nop 0
	global_load_lds_dwordx4 v147, s[68:69] offset:128
	s_barrier
	s_waitcnt lgkmcnt(0)
	s_setprio 1
	s_waitcnt lgkmcnt(0)
	v_mfma_f32_16x16x32_bf16 v[122:125], v[210:213], v[164:167], v[122:125]
	v_mfma_f32_16x16x32_bf16 v[118:121], v[238:241], v[164:167], v[118:121]
	v_mfma_f32_16x16x32_bf16 v[106:109], v[210:213], v[172:175], v[106:109]
	v_mfma_f32_16x16x32_bf16 v[102:105], v[238:241], v[172:175], v[102:105]
	v_mfma_f32_16x16x32_bf16 v[90:93], v[210:213], v[194:197], v[90:93]
	v_mfma_f32_16x16x32_bf16 v[86:89], v[238:241], v[194:197], v[86:89]
	v_mfma_f32_16x16x32_bf16 v[72:75], v[210:213], v[202:205], v[72:75]
	v_mfma_f32_16x16x32_bf16 v[68:71], v[238:241], v[202:205], v[68:71]
	v_mfma_f32_16x16x32_bf16 v[122:125], v[214:217], v[168:171], v[122:125]
	v_mfma_f32_16x16x32_bf16 v[118:121], v[242:245], v[168:171], v[118:121]
	v_mfma_f32_16x16x32_bf16 v[106:109], v[214:217], v[190:193], v[106:109]
	v_mfma_f32_16x16x32_bf16 v[102:105], v[242:245], v[190:193], v[102:105]
	v_mfma_f32_16x16x32_bf16 v[90:93], v[214:217], v[198:201], v[90:93]
	v_mfma_f32_16x16x32_bf16 v[86:89], v[242:245], v[198:201], v[86:89]
	v_mfma_f32_16x16x32_bf16 v[72:75], v[214:217], v[206:209], v[72:75]
	v_mfma_f32_16x16x32_bf16 v[68:71], v[242:245], v[206:209], v[68:71]
	s_setprio 0
	v_mov_b32_e32 v80, v144
	s_barrier
	ds_read_b128 v[164:167], v153 offset:49152
	ds_read_b128 v[168:171], v153 offset:50176
	ds_read_b128 v[172:175], v153 offset:51200
	ds_read_b128 v[190:193], v153 offset:52224
	ds_read_b128 v[194:197], v153 offset:53248
	ds_read_b128 v[198:201], v153 offset:54272
	ds_read_b128 v[202:205], v153 offset:55296
	ds_read_b128 v[206:209], v153 offset:56320
	s_add_i32 m0, s48, 0xffffff80
	v_mov_b32_e32 v80, v146
	global_load_lds_dwordx4 v144, s[44:45] offset:128
	s_add_i32 m0, s49, 0xffffff80
	s_nop 0
	global_load_lds_dwordx4 v146, s[44:45] offset:128
	s_barrier
; __device__ __forceinline__ unsigned cvt_pk_bf16(float lo, float hi) { unsigned r; asm("v_cvt_pk_bf16_f32 %0, %1, %2" : "=v"(r) : "v"(lo), "v"(hi)); return r; }
; __device__ __forceinline__ float rinv_of(unsigned long long ss) { return rsqrtf((float)ss * (1.f / 16777216.f) * (1.f / DM) + 1e-6f); }
; #define G_LDA(dst, b, h) do { _Pragma("unroll") for (int m = 0; m < 4; ++m) _Pragma("unroll") for (int k = 0; k < 2; ++k) dst[m][k] = *(const LAS bf16x8*)(lds + G_SA(b, h) + aoff + m * 2048 + k * 1024); } while (0)
; #define G_WAIT_V(n) asm volatile("s_waitcnt vmcnt(" #n ")" ::: "memory")
;   __device__ __forceinline__ void operator()(const f32x4 (&acc)[2][2][4][2], const Unit& u, const EpiCtx& x_, int wr, int wc, int fr, int fq) const {
;     ...
; #pragma unroll
;     for (int ai = 0; ai < 2; ++ai)
; #pragma unroll
;       for (int m = 0; m < 4; ++m) {
;         const int row = (u.r0 + (ai ? x_.rdelta : 0)) + wr * 64 + m * 16 + fr;
;         bf16_t* rowp = (bf16_t*)u.C + (size_t)row * x_.ldc;
;         const float rs = (SCALE == 1) ? rinv_of(x_.ss[row]) : 1.f;
; #pragma unroll
;         for (int bj = 0; bj < 2; ++bj) {
;           const int cb = PERM ? (u.c0 + wc * 64 + bj * 32) : (u.c0 + bj * 128) + wc * 32;
;           f32x4 v0 = acc[ai][bj][m][0], v1 = acc[ai][bj][m][1];
;           if (SCALE == 1) { v0 *= rs; v1 *= rs; }
;           if (SCALE == 2) { v0 *= cs[bj][0]; v1 *= cs[bj][1]; }
;           if (PERM) {
;             uint4 o; o.x = cvt_pk_bf16(v0[0], v0[1]); o.y = cvt_pk_bf16(v0[2], v0[3]); o.z = cvt_pk_bf16(v1[0], v1[1]); o.w = cvt_pk_bf16(v1[2], v1[3]);
;             *(uint4*)(rowp + cb + 8 * fq) = o;
; template <class Epi>
; __device__ __forceinline__ void gemm_phase(LAS unsigned char* lds, const int K, const unsigned lda_b, const unsigned ldb_b, const Map& M, const Epi& E) {
;     ...
;       G_WAIT_V(6); G_BAR; G_MMA(1, 1, At, B1); G_BAR;
;       G_LDB(B0, 1, 0); G_SCHED; G_LDA(At, 1, 0); G_STAGE(G_SA(0, 1), a2h1, voffA);
;       G_WAIT_L(8); G_BAR; G_WAIT_L(0); G_MMA(0, 0, At, B0); G_BAR; G_SCHED;
;       G_LDB(B1, 1, 1); G_STAGE(G_SB(1, 0), b2h0 + kstep, voffB);
;       G_BAR; G_WAIT_L(0); G_MMA(0, 1, At, B1); G_BAR;
;       G_LDA(At, 1, 1); G_STAGE(G_SA(1, 0), a2h0 + kstep, voffA);
;       G_BAR; G_WAIT_L(0); G_MMA(1, 0, At, B0); G_BAR; G_SCHED;
;       G_STAGE(G_SB(1, 1), b2h1 + kstep, voffB);
;       G_WAIT_V(6); G_BAR; G_MMA(1, 1, At, B1); G_BAR;
	s_waitcnt lgkmcnt(0)
	s_setprio 1
	s_waitcnt lgkmcnt(0)
	v_mfma_f32_16x16x32_bf16 v[64:67], v[136:139], v[164:167], v[64:67]
	v_mfma_f32_16x16x32_bf16 v[60:63], v[154:157], v[164:167], v[60:63]
	v_mfma_f32_16x16x32_bf16 v[48:51], v[136:139], v[172:175], v[48:51]
	v_mfma_f32_16x16x32_bf16 v[44:47], v[154:157], v[172:175], v[44:47]
	v_mfma_f32_16x16x32_bf16 v[32:35], v[136:139], v[194:197], v[32:35]
	v_mfma_f32_16x16x32_bf16 v[28:31], v[154:157], v[194:197], v[28:31]
	v_mfma_f32_16x16x32_bf16 v[16:19], v[136:139], v[202:205], v[16:19]
	v_mfma_f32_16x16x32_bf16 v[12:15], v[154:157], v[202:205], v[12:15]
	v_mfma_f32_16x16x32_bf16 v[64:67], v[140:143], v[168:171], v[64:67]
	v_mfma_f32_16x16x32_bf16 v[60:63], v[158:161], v[168:171], v[60:63]
	v_mfma_f32_16x16x32_bf16 v[48:51], v[140:143], v[190:193], v[48:51]
	v_mfma_f32_16x16x32_bf16 v[44:47], v[158:161], v[190:193], v[44:47]
	v_mfma_f32_16x16x32_bf16 v[32:35], v[140:143], v[198:201], v[32:35]
	v_mfma_f32_16x16x32_bf16 v[28:31], v[158:161], v[198:201], v[28:31]
	v_mfma_f32_16x16x32_bf16 v[16:19], v[140:143], v[206:209], v[16:19]
	v_mfma_f32_16x16x32_bf16 v[12:15], v[158:161], v[206:209], v[12:15]
	s_setprio 0
	s_barrier
	v_mov_b32_e32 v80, v145
	s_add_i32 s22, s35, s13
	s_add_i32 m0, s22, 0xffffff80
	v_mov_b32_e32 v80, v147
	global_load_lds_dwordx4 v145, s[42:43] offset:128
	s_add_i32 m0, s22, 0x1f80
	s_nop 0
	global_load_lds_dwordx4 v147, s[42:43] offset:128
	s_waitcnt vmcnt(6)
	s_barrier
	s_setprio 1
	v_mfma_f32_16x16x32_bf16 v[56:59], v[210:213], v[164:167], v[56:59]
	v_mfma_f32_16x16x32_bf16 v[52:55], v[238:241], v[164:167], v[52:55]
	v_mfma_f32_16x16x32_bf16 v[40:43], v[210:213], v[172:175], v[40:43]
	v_mfma_f32_16x16x32_bf16 v[36:39], v[238:241], v[172:175], v[36:39]
	v_mfma_f32_16x16x32_bf16 v[24:27], v[210:213], v[194:197], v[24:27]
	v_mfma_f32_16x16x32_bf16 v[20:23], v[238:241], v[194:197], v[20:23]
	v_mfma_f32_16x16x32_bf16 v[8:11], v[210:213], v[202:205], v[8:11]
	v_mfma_f32_16x16x32_bf16 v[4:7], v[238:241], v[202:205], v[4:7]
	v_mfma_f32_16x16x32_bf16 v[56:59], v[214:217], v[168:171], v[56:59]
	v_mfma_f32_16x16x32_bf16 v[52:55], v[242:245], v[168:171], v[52:55]
	v_mfma_f32_16x16x32_bf16 v[40:43], v[214:217], v[190:193], v[40:43]
	v_mfma_f32_16x16x32_bf16 v[36:39], v[242:245], v[190:193], v[36:39]
	v_mfma_f32_16x16x32_bf16 v[24:27], v[214:217], v[198:201], v[24:27]
	v_mfma_f32_16x16x32_bf16 v[20:23], v[242:245], v[198:201], v[20:23]
	v_mfma_f32_16x16x32_bf16 v[8:11], v[214:217], v[206:209], v[8:11]
	v_mfma_f32_16x16x32_bf16 v[4:7], v[242:245], v[206:209], v[4:7]
	s_setprio 0
	s_add_i32 s34, s34, 2
	s_add_u32 s30, s30, 0x100
	s_addc_u32 s31, s31, 0
	s_add_u32 s38, s38, 0x100
	s_addc_u32 s39, s39, 0
	s_cmp_gt_u32 s34, 29
	s_barrier
	s_cbranch_scc0 .LBB0_626
	s_nop 1
	v_add_u32_e32 v192, s76, v148
	v_ashrrev_i32_e32 v193, 31, v192
	v_lshl_add_u64 v[194:195], v[192:193], 3, s[4:5]
	global_load_dwordx2 v[160:161], v[194:195], off
	v_add_u32_e32 v196, s76, v150
	v_ashrrev_i32_e32 v197, 31, v196
	v_lshl_add_u64 v[198:199], v[196:197], 3, s[4:5]
	global_load_dwordx2 v[164:165], v[198:199], off
	v_add_u32_e32 v200, s76, v151
	v_ashrrev_i32_e32 v201, 31, v200
	v_lshl_add_u64 v[202:203], v[200:201], 3, s[4:5]
	global_load_dwordx2 v[166:167], v[202:203], off
	v_add_u32_e32 v204, s76, v152
	v_ashrrev_i32_e32 v205, 31, v204
	v_lshl_add_u64 v[206:207], v[204:205], 3, s[4:5]
	global_load_dwordx2 v[168:169], v[206:207], off
	global_load_dwordx2 v[170:171], v[194:195], off offset:1024
	global_load_dwordx2 v[172:173], v[198:199], off offset:1024
	global_load_dwordx2 v[174:175], v[202:203], off offset:1024
	global_load_dwordx2 v[190:191], v[206:207], off offset:1024
	v_add_u32_e32 v138, s76, v148
	v_ashrrev_i32_e32 v139, 31, v138
	v_lshl_add_u64 v[140:141], v[138:139], 3, s[4:5]
	s_nop 0
	v_lshlrev_b64 v[154:155], 12, v[138:139]
	s_add_i32 s28, s79, s61
	v_mov_b32_e32 v135, v81
	s_add_i32 s30, s66, s79
	s_ashr_i32 s29, s28, 31
	v_add_u32_e32 v136, s76, v150
	s_ashr_i32 s31, s30, 31
	s_lshl_b64 s[38:39], s[28:29], 1
	v_ashrrev_i32_e32 v137, 31, v136
	s_lshl_b64 s[42:43], s[30:31], 1
	v_lshl_add_u64 v[142:143], v[136:137], 3, s[4:5]
	v_readfirstlane_b32 s79, v3
	s_mov_b64 s[44:45], s[36:37]
	s_mov_b64 s[68:69], s[40:41]
	s_cmp_eq_u32 s75, s67
	s_waitcnt lgkmcnt(0)
	s_waitcnt vmcnt(7)
	v_ffbh_u32_e32 v80, v161
	v_min_u32_e32 v80, 32, v80
	v_lshlrev_b64 v[0:1], v80, v[160:161]
	v_min_u32_e32 v0, 1, v0
	v_or_b32_e32 v0, v1, v0
	v_cvt_f32_u32_e32 v139, v0
	v_sub_u32_e32 v80, 32, v80
	v_lshl_add_u64 v[0:1], s[2:3], 0, v[154:155]
	v_lshl_add_u64 v[0:1], v[0:1], 0, v[134:135]
	v_ldexp_f32 v80, v139, v80
	v_mul_f32_e32 v80, 0x33800000, v80
	v_fmamk_f32 v80, v80, 0x3a000000, v234
	v_mul_f32_e32 v139, 0x4b800000, v80
	v_cmp_gt_f32_e32 vcc, s50, v80
	v_lshl_add_u64 v[154:155], v[0:1], 0, s[38:39]
	v_lshl_add_u64 v[0:1], v[0:1], 0, s[42:43]
	v_cndmask_b32_e32 v80, v80, v139, vcc
	v_rsq_f32_e32 v80, v80
	s_nop 0
	v_mul_f32_e32 v139, 0x45800000, v80
	v_cndmask_b32_e32 v80, v80, v139, vcc
	v_pk_mul_f32 v[132:133], v[132:133], v[80:81] op_sel_hi:[1,0]
	v_pk_mul_f32 v[130:131], v[130:131], v[80:81] op_sel_hi:[1,0]
	v_pk_mul_f32 v[128:129], v[128:129], v[80:81] op_sel_hi:[1,0]
	v_pk_mul_f32 v[126:127], v[126:127], v[80:81] op_sel_hi:[1,0]
	v_pk_mul_f32 v[124:125], v[124:125], v[80:81] op_sel_hi:[1,0]
	v_pk_mul_f32 v[122:123], v[122:123], v[80:81] op_sel_hi:[1,0]
	v_pk_mul_f32 v[156:157], v[120:121], v[80:81] op_sel_hi:[1,0]
	v_pk_mul_f32 v[158:159], v[118:119], v[80:81] op_sel_hi:[1,0]
	v_cvt_pk_bf16_f32 v118, v130, v131
	v_cvt_pk_bf16_f32 v119, v132, v133
	v_cvt_pk_bf16_f32 v120, v126, v127
	v_cvt_pk_bf16_f32 v121, v128, v129
	v_cvt_pk_bf16_f32 v122, v122, v123
	v_cvt_pk_bf16_f32 v123, v124, v125
	s_nop 0
	v_cvt_pk_bf16_f32 v124, v158, v159
	v_cvt_pk_bf16_f32 v125, v156, v157
	global_store_dwordx4 v[154:155], v[118:121], off nt
	global_store_dwordx4 v[0:1], v[122:125], off nt
	s_nop 0
	v_add_u32_e32 v118, s76, v151
	v_lshlrev_b64 v[122:123], 12, v[136:137]
	v_ashrrev_i32_e32 v119, 31, v118
	v_lshl_add_u64 v[120:121], v[118:119], 3, s[4:5]
	s_waitcnt lgkmcnt(0)
; __device__ __forceinline__ unsigned cvt_pk_bf16(float lo, float hi) { unsigned r; asm("v_cvt_pk_bf16_f32 %0, %1, %2" : "=v"(r) : "v"(lo), "v"(hi)); return r; }
; __device__ __forceinline__ float rinv_of(unsigned long long ss) { return rsqrtf((float)ss * (1.f / 16777216.f) * (1.f / DM) + 1e-6f); }
;   __device__ __forceinline__ void operator()(const f32x4 (&acc)[2][2][4][2], const Unit& u, const EpiCtx& x_, int wr, int wc, int fr, int fq) const {
;     ...
; #pragma unroll
;     for (int ai = 0; ai < 2; ++ai)
; #pragma unroll
;       for (int m = 0; m < 4; ++m) {
;         const int row = (u.r0 + (ai ? x_.rdelta : 0)) + wr * 64 + m * 16 + fr;
;         bf16_t* rowp = (bf16_t*)u.C + (size_t)row * x_.ldc;
;         const float rs = (SCALE == 1) ? rinv_of(x_.ss[row]) : 1.f;
; #pragma unroll
;         for (int bj = 0; bj < 2; ++bj) {
;           const int cb = PERM ? (u.c0 + wc * 64 + bj * 32) : (u.c0 + bj * 128) + wc * 32;
;           f32x4 v0 = acc[ai][bj][m][0], v1 = acc[ai][bj][m][1];
;           if (SCALE == 1) { v0 *= rs; v1 *= rs; }
;           if (SCALE == 2) { v0 *= cs[bj][0]; v1 *= cs[bj][1]; }
;           if (PERM) {
;             uint4 o; o.x = cvt_pk_bf16(v0[0], v0[1]); o.y = cvt_pk_bf16(v0[2], v0[3]); o.z = cvt_pk_bf16(v1[0], v1[1]); o.w = cvt_pk_bf16(v1[2], v1[3]);
;             *(uint4*)(rowp + cb + 8 * fq) = o;
	s_waitcnt vmcnt(8)
	v_ffbh_u32_e32 v80, v165
	v_min_u32_e32 v80, 32, v80
	v_lshlrev_b64 v[0:1], v80, v[164:165]
	v_min_u32_e32 v0, 1, v0
	v_or_b32_e32 v0, v1, v0
	v_cvt_f32_u32_e32 v124, v0
	v_sub_u32_e32 v80, 32, v80
	v_lshl_add_u64 v[0:1], s[2:3], 0, v[122:123]
	v_lshl_add_u64 v[0:1], v[0:1], 0, v[134:135]
	v_ldexp_f32 v80, v124, v80
	v_mul_f32_e32 v80, 0x33800000, v80
	v_fmamk_f32 v80, v80, 0x3a000000, v234
	v_mul_f32_e32 v122, 0x4b800000, v80
	v_cmp_gt_f32_e32 vcc, s50, v80
	s_nop 1
	v_cndmask_b32_e32 v80, v80, v122, vcc
	v_rsq_f32_e32 v80, v80
	v_lshl_add_u64 v[122:123], v[0:1], 0, s[38:39]
	v_lshl_add_u64 v[0:1], v[0:1], 0, s[42:43]
	v_mul_f32_e32 v124, 0x45800000, v80
	v_cndmask_b32_e32 v80, v80, v124, vcc
	v_pk_mul_f32 v[116:117], v[116:117], v[80:81] op_sel_hi:[1,0]
	v_pk_mul_f32 v[114:115], v[114:115], v[80:81] op_sel_hi:[1,0]
	v_pk_mul_f32 v[112:113], v[112:113], v[80:81] op_sel_hi:[1,0]
	v_pk_mul_f32 v[110:111], v[110:111], v[80:81] op_sel_hi:[1,0]
	v_pk_mul_f32 v[108:109], v[108:109], v[80:81] op_sel_hi:[1,0]
	v_pk_mul_f32 v[106:107], v[106:107], v[80:81] op_sel_hi:[1,0]
	v_pk_mul_f32 v[124:125], v[104:105], v[80:81] op_sel_hi:[1,0]
	v_pk_mul_f32 v[126:127], v[102:103], v[80:81] op_sel_hi:[1,0]
	v_cvt_pk_bf16_f32 v102, v114, v115
	v_cvt_pk_bf16_f32 v103, v116, v117
	v_cvt_pk_bf16_f32 v104, v110, v111
	v_cvt_pk_bf16_f32 v105, v112, v113
	v_cvt_pk_bf16_f32 v106, v106, v107
	v_cvt_pk_bf16_f32 v107, v108, v109
	s_nop 0
	v_cvt_pk_bf16_f32 v108, v126, v127
	v_cvt_pk_bf16_f32 v109, v124, v125
	global_store_dwordx4 v[122:123], v[102:105], off nt
	global_store_dwordx4 v[0:1], v[106:109], off nt
	s_nop 0
	v_lshlrev_b64 v[104:105], 12, v[118:119]
	v_lshl_add_u64 v[104:105], s[2:3], 0, v[104:105]
	v_add_u32_e32 v0, s76, v152
	v_lshl_add_u64 v[104:105], v[104:105], 0, v[134:135]
	v_ashrrev_i32_e32 v1, 31, v0
	v_readfirstlane_b32 s76, v2
	s_waitcnt lgkmcnt(0)
	s_waitcnt vmcnt(9)
	v_ffbh_u32_e32 v80, v167
	v_min_u32_e32 v80, 32, v80
	v_lshlrev_b64 v[102:103], v80, v[166:167]
	v_min_u32_e32 v102, 1, v102
	v_or_b32_e32 v102, v103, v102
	v_cvt_f32_u32_e32 v106, v102
	v_sub_u32_e32 v80, 32, v80
	v_lshl_add_u64 v[102:103], v[0:1], 3, s[4:5]
	v_ldexp_f32 v80, v106, v80
	v_mul_f32_e32 v80, 0x33800000, v80
	v_fmamk_f32 v80, v80, 0x3a000000, v234
	v_mul_f32_e32 v106, 0x4b800000, v80
	v_cmp_gt_f32_e32 vcc, s50, v80
	s_nop 1
	v_cndmask_b32_e32 v80, v80, v106, vcc
	v_rsq_f32_e32 v80, v80
	v_lshl_add_u64 v[106:107], v[104:105], 0, s[38:39]
	v_lshl_add_u64 v[104:105], v[104:105], 0, s[42:43]
	v_mul_f32_e32 v108, 0x45800000, v80
	v_cndmask_b32_e32 v80, v80, v108, vcc
	v_pk_mul_f32 v[100:101], v[100:101], v[80:81] op_sel_hi:[1,0]
	v_pk_mul_f32 v[98:99], v[98:99], v[80:81] op_sel_hi:[1,0]
	v_pk_mul_f32 v[96:97], v[96:97], v[80:81] op_sel_hi:[1,0]
	v_pk_mul_f32 v[94:95], v[94:95], v[80:81] op_sel_hi:[1,0]
	v_pk_mul_f32 v[92:93], v[92:93], v[80:81] op_sel_hi:[1,0]
	v_pk_mul_f32 v[90:91], v[90:91], v[80:81] op_sel_hi:[1,0]
	v_pk_mul_f32 v[108:109], v[88:89], v[80:81] op_sel_hi:[1,0]
	v_pk_mul_f32 v[110:111], v[86:87], v[80:81] op_sel_hi:[1,0]
	v_cvt_pk_bf16_f32 v86, v98, v99
	v_cvt_pk_bf16_f32 v87, v100, v101
	v_cvt_pk_bf16_f32 v88, v94, v95
	v_cvt_pk_bf16_f32 v89, v96, v97
	v_cvt_pk_bf16_f32 v90, v90, v91
	v_cvt_pk_bf16_f32 v91, v92, v93
	s_nop 0
	v_cvt_pk_bf16_f32 v92, v110, v111
	v_cvt_pk_bf16_f32 v93, v108, v109
	global_store_dwordx4 v[106:107], v[86:89], off nt
	global_store_dwordx4 v[104:105], v[90:93], off nt
	s_nop 0
	s_waitcnt lgkmcnt(0)
	s_waitcnt vmcnt(10)
	v_ffbh_u32_e32 v80, v169
	v_min_u32_e32 v80, 32, v80
	v_lshlrev_b64 v[86:87], v80, v[168:169]
	v_min_u32_e32 v86, 1, v86
	v_or_b32_e32 v86, v87, v86
	v_cvt_f32_u32_e32 v88, v86
	v_lshlrev_b64 v[86:87], 12, v[0:1]
	v_sub_u32_e32 v1, 32, v80
	v_lshl_add_u64 v[86:87], s[2:3], 0, v[86:87]
	v_ldexp_f32 v1, v88, v1
	v_mul_f32_e32 v1, 0x33800000, v1
	v_fmamk_f32 v1, v1, 0x3a000000, v234
	v_mul_f32_e32 v80, 0x4b800000, v1
	v_cmp_gt_f32_e32 vcc, s50, v1
	v_lshl_add_u64 v[86:87], v[86:87], 0, v[134:135]
	v_lshl_add_u64 v[88:89], v[86:87], 0, s[38:39]
	v_cndmask_b32_e32 v1, v1, v80, vcc
	v_rsq_f32_e32 v1, v1
	v_lshl_add_u64 v[86:87], v[86:87], 0, s[42:43]
	v_add_u32_e32 v0, 0x80, v0
	v_mul_f32_e32 v80, 0x45800000, v1
	v_cndmask_b32_e32 v80, v1, v80, vcc
	v_pk_mul_f32 v[84:85], v[84:85], v[80:81] op_sel_hi:[1,0]
	v_pk_mul_f32 v[82:83], v[82:83], v[80:81] op_sel_hi:[1,0]
	v_pk_mul_f32 v[78:79], v[78:79], v[80:81] op_sel_hi:[1,0]
	v_pk_mul_f32 v[76:77], v[76:77], v[80:81] op_sel_hi:[1,0]
	v_pk_mul_f32 v[74:75], v[74:75], v[80:81] op_sel_hi:[1,0]
	v_pk_mul_f32 v[72:73], v[72:73], v[80:81] op_sel_hi:[1,0]
	v_pk_mul_f32 v[90:91], v[70:71], v[80:81] op_sel_hi:[1,0]
	v_pk_mul_f32 v[92:93], v[68:69], v[80:81] op_sel_hi:[1,0]
	v_cvt_pk_bf16_f32 v68, v82, v83
	v_cvt_pk_bf16_f32 v69, v84, v85
	v_cvt_pk_bf16_f32 v70, v76, v77
	v_cvt_pk_bf16_f32 v71, v78, v79
	v_cvt_pk_bf16_f32 v72, v72, v73
	v_cvt_pk_bf16_f32 v73, v74, v75
	s_nop 0
	v_cvt_pk_bf16_f32 v74, v92, v93
	v_cvt_pk_bf16_f32 v75, v90, v91
	global_store_dwordx4 v[88:89], v[68:71], off nt
	global_store_dwordx4 v[86:87], v[72:75], off nt
	s_nop 0
	v_add_u32_e32 v70, 0x80, v138
	v_ashrrev_i32_e32 v71, 31, v70
	s_waitcnt lgkmcnt(0)
	s_waitcnt vmcnt(11)
; __device__ __forceinline__ unsigned cvt_pk_bf16(float lo, float hi) { unsigned r; asm("v_cvt_pk_bf16_f32 %0, %1, %2" : "=v"(r) : "v"(lo), "v"(hi)); return r; }
; __device__ __forceinline__ float rinv_of(unsigned long long ss) { return rsqrtf((float)ss * (1.f / 16777216.f) * (1.f / DM) + 1e-6f); }
; #define G_WAIT_V(n) asm volatile("s_waitcnt vmcnt(" #n ")" ::: "memory")
; #define G_BAR __builtin_amdgcn_s_barrier()
;   __device__ __forceinline__ void operator()(const f32x4 (&acc)[2][2][4][2], const Unit& u, const EpiCtx& x_, int wr, int wc, int fr, int fq) const {
;     ...
;       for (int m = 0; m < 4; ++m) {
;         const int row = (u.r0 + (ai ? x_.rdelta : 0)) + wr * 64 + m * 16 + fr;
;         bf16_t* rowp = (bf16_t*)u.C + (size_t)row * x_.ldc;
;         const float rs = (SCALE == 1) ? rinv_of(x_.ss[row]) : 1.f;
; #pragma unroll
;         for (int bj = 0; bj < 2; ++bj) {
;           const int cb = PERM ? (u.c0 + wc * 64 + bj * 32) : (u.c0 + bj * 128) + wc * 32;
;           f32x4 v0 = acc[ai][bj][m][0], v1 = acc[ai][bj][m][1];
;           if (SCALE == 1) { v0 *= rs; v1 *= rs; }
;           if (SCALE == 2) { v0 *= cs[bj][0]; v1 *= cs[bj][1]; }
;           if (PERM) {
;             uint4 o; o.x = cvt_pk_bf16(v0[0], v0[1]); o.y = cvt_pk_bf16(v0[2], v0[3]); o.z = cvt_pk_bf16(v1[0], v1[1]); o.w = cvt_pk_bf16(v1[2], v1[3]);
;             *(uint4*)(rowp + cb + 8 * fq) = o;
;           } else {
;             uint2 o0, o1; o0.x = cvt_pk_bf16(v0[0], v0[1]); o0.y = cvt_pk_bf16(v0[2], v0[3]); o1.x = cvt_pk_bf16(v1[0], v1[1]); o1.y = cvt_pk_bf16(v1[2], v1[3]);
;             *(uint2*)(rowp + cb + 4 * fq) = o0; *(uint2*)(rowp + cb + 16 + 4 * fq) = o1;
;           }
;         }
; template <class Epi>
; __device__ __forceinline__ void gemm_phase(LAS unsigned char* lds, const int K, const unsigned lda_b, const unsigned ldb_b, const Map& M, const Epi& E) {
;     ...
;     cur = nxt; ++ui;
;   }
;   G_WAIT_V(0);
;   if (wr == 0) G_BAR;
;   G_BAR;
	v_ffbh_u32_e32 v1, v171
	v_min_u32_e32 v1, 32, v1
	v_lshlrev_b64 v[68:69], v1, v[170:171]
	v_min_u32_e32 v68, 1, v68
	v_or_b32_e32 v68, v69, v68
	v_cvt_f32_u32_e32 v72, v68
	v_sub_u32_e32 v1, 32, v1
	v_lshlrev_b64 v[68:69], 12, v[70:71]
	v_lshl_add_u64 v[68:69], s[2:3], 0, v[68:69]
	v_ldexp_f32 v1, v72, v1
	v_mul_f32_e32 v1, 0x33800000, v1
	v_fmamk_f32 v1, v1, 0x3a000000, v234
	v_mul_f32_e32 v70, 0x4b800000, v1
	v_cmp_gt_f32_e32 vcc, s50, v1
	v_lshl_add_u64 v[68:69], v[68:69], 0, v[134:135]
	s_nop 0
	v_cndmask_b32_e32 v1, v1, v70, vcc
	v_rsq_f32_e32 v1, v1
	v_lshl_add_u64 v[70:71], v[68:69], 0, s[38:39]
	v_lshl_add_u64 v[68:69], v[68:69], 0, s[42:43]
	v_mul_f32_e32 v72, 0x45800000, v1
	v_cndmask_b32_e32 v72, v1, v72, vcc
	v_pk_mul_f32 v[66:67], v[66:67], v[72:73] op_sel_hi:[1,0]
	v_pk_mul_f32 v[64:65], v[64:65], v[72:73] op_sel_hi:[1,0]
	v_pk_mul_f32 v[62:63], v[62:63], v[72:73] op_sel_hi:[1,0]
	v_pk_mul_f32 v[60:61], v[60:61], v[72:73] op_sel_hi:[1,0]
	v_pk_mul_f32 v[58:59], v[58:59], v[72:73] op_sel_hi:[1,0]
	v_pk_mul_f32 v[56:57], v[56:57], v[72:73] op_sel_hi:[1,0]
	v_pk_mul_f32 v[74:75], v[54:55], v[72:73] op_sel_hi:[1,0]
	v_pk_mul_f32 v[72:73], v[52:53], v[72:73] op_sel_hi:[1,0]
	v_cvt_pk_bf16_f32 v52, v64, v65
	v_cvt_pk_bf16_f32 v53, v66, v67
	v_cvt_pk_bf16_f32 v54, v60, v61
	v_cvt_pk_bf16_f32 v55, v62, v63
	v_cvt_pk_bf16_f32 v56, v56, v57
	v_cvt_pk_bf16_f32 v57, v58, v59
	s_nop 0
	v_cvt_pk_bf16_f32 v58, v72, v73
	v_cvt_pk_bf16_f32 v59, v74, v75
	global_store_dwordx4 v[70:71], v[52:55], off nt
	global_store_dwordx4 v[68:69], v[56:59], off nt
	s_nop 0
	v_add_u32_e32 v54, 0x80, v136
	v_ashrrev_i32_e32 v55, 31, v54
	s_waitcnt lgkmcnt(0)
	s_waitcnt vmcnt(12)
	v_ffbh_u32_e32 v1, v173
	v_min_u32_e32 v1, 32, v1
	v_lshlrev_b64 v[52:53], v1, v[172:173]
	v_min_u32_e32 v52, 1, v52
	v_or_b32_e32 v52, v53, v52
	v_cvt_f32_u32_e32 v56, v52
	v_sub_u32_e32 v1, 32, v1
	v_lshlrev_b64 v[52:53], 12, v[54:55]
	v_lshl_add_u64 v[52:53], s[2:3], 0, v[52:53]
	v_ldexp_f32 v1, v56, v1
	v_mul_f32_e32 v1, 0x33800000, v1
	v_fmamk_f32 v1, v1, 0x3a000000, v234
	v_mul_f32_e32 v54, 0x4b800000, v1
	v_cmp_gt_f32_e32 vcc, s50, v1
	v_lshl_add_u64 v[52:53], v[52:53], 0, v[134:135]
	s_nop 0
	v_cndmask_b32_e32 v1, v1, v54, vcc
	v_rsq_f32_e32 v1, v1
	v_lshl_add_u64 v[54:55], v[52:53], 0, s[38:39]
	v_lshl_add_u64 v[52:53], v[52:53], 0, s[42:43]
	v_mul_f32_e32 v56, 0x45800000, v1
	v_cndmask_b32_e32 v56, v1, v56, vcc
	v_pk_mul_f32 v[50:51], v[50:51], v[56:57] op_sel_hi:[1,0]
	v_pk_mul_f32 v[48:49], v[48:49], v[56:57] op_sel_hi:[1,0]
	v_pk_mul_f32 v[46:47], v[46:47], v[56:57] op_sel_hi:[1,0]
	v_pk_mul_f32 v[44:45], v[44:45], v[56:57] op_sel_hi:[1,0]
	v_pk_mul_f32 v[42:43], v[42:43], v[56:57] op_sel_hi:[1,0]
	v_pk_mul_f32 v[40:41], v[40:41], v[56:57] op_sel_hi:[1,0]
	v_pk_mul_f32 v[58:59], v[38:39], v[56:57] op_sel_hi:[1,0]
	v_pk_mul_f32 v[56:57], v[36:37], v[56:57] op_sel_hi:[1,0]
	v_cvt_pk_bf16_f32 v36, v48, v49
	v_cvt_pk_bf16_f32 v37, v50, v51
	v_cvt_pk_bf16_f32 v38, v44, v45
	v_cvt_pk_bf16_f32 v39, v46, v47
	v_cvt_pk_bf16_f32 v40, v40, v41
	v_cvt_pk_bf16_f32 v41, v42, v43
	s_nop 0
	v_cvt_pk_bf16_f32 v42, v56, v57
	v_cvt_pk_bf16_f32 v43, v58, v59
	global_store_dwordx4 v[54:55], v[36:39], off nt
	global_store_dwordx4 v[52:53], v[40:43], off nt
	s_nop 0
	v_add_u32_e32 v38, 0x80, v118
	v_ashrrev_i32_e32 v39, 31, v38
	s_waitcnt lgkmcnt(0)
	s_waitcnt vmcnt(13)
	v_ffbh_u32_e32 v1, v175
	v_min_u32_e32 v1, 32, v1
	v_lshlrev_b64 v[36:37], v1, v[174:175]
	v_min_u32_e32 v36, 1, v36
	v_or_b32_e32 v36, v37, v36
	v_cvt_f32_u32_e32 v40, v36
	v_sub_u32_e32 v1, 32, v1
	v_lshlrev_b64 v[36:37], 12, v[38:39]
	v_lshl_add_u64 v[36:37], s[2:3], 0, v[36:37]
	v_ldexp_f32 v1, v40, v1
	v_mul_f32_e32 v1, 0x33800000, v1
	v_fmamk_f32 v1, v1, 0x3a000000, v234
	v_mul_f32_e32 v38, 0x4b800000, v1
	v_cmp_gt_f32_e32 vcc, s50, v1
	v_lshl_add_u64 v[36:37], v[36:37], 0, v[134:135]
	s_nop 0
	v_cndmask_b32_e32 v1, v1, v38, vcc
	v_rsq_f32_e32 v1, v1
	v_lshl_add_u64 v[38:39], v[36:37], 0, s[38:39]
	v_lshl_add_u64 v[36:37], v[36:37], 0, s[42:43]
	v_mul_f32_e32 v40, 0x45800000, v1
	v_cndmask_b32_e32 v40, v1, v40, vcc
	v_pk_mul_f32 v[34:35], v[34:35], v[40:41] op_sel_hi:[1,0]
	v_pk_mul_f32 v[32:33], v[32:33], v[40:41] op_sel_hi:[1,0]
	v_pk_mul_f32 v[30:31], v[30:31], v[40:41] op_sel_hi:[1,0]
	v_pk_mul_f32 v[28:29], v[28:29], v[40:41] op_sel_hi:[1,0]
	v_pk_mul_f32 v[26:27], v[26:27], v[40:41] op_sel_hi:[1,0]
	v_pk_mul_f32 v[24:25], v[24:25], v[40:41] op_sel_hi:[1,0]
	v_pk_mul_f32 v[42:43], v[22:23], v[40:41] op_sel_hi:[1,0]
	v_pk_mul_f32 v[40:41], v[20:21], v[40:41] op_sel_hi:[1,0]
	v_cvt_pk_bf16_f32 v20, v32, v33
	v_cvt_pk_bf16_f32 v21, v34, v35
	v_cvt_pk_bf16_f32 v22, v28, v29
	v_cvt_pk_bf16_f32 v23, v30, v31
	v_cvt_pk_bf16_f32 v24, v24, v25
	v_cvt_pk_bf16_f32 v25, v26, v27
	s_nop 0
	v_cvt_pk_bf16_f32 v26, v40, v41
	v_cvt_pk_bf16_f32 v27, v42, v43
	global_store_dwordx4 v[38:39], v[20:23], off nt
	global_store_dwordx4 v[36:37], v[24:27], off nt
	s_nop 0
	v_ashrrev_i32_e32 v1, 31, v0
	v_lshlrev_b64 v[0:1], 12, v[0:1]
	v_lshl_add_u64 v[0:1], s[2:3], 0, v[0:1]
	v_lshl_add_u64 v[0:1], v[0:1], 0, v[134:135]
	s_mov_b64 s[2:3], s[8:9]
	s_waitcnt lgkmcnt(0)
	s_waitcnt vmcnt(14)
	v_ffbh_u32_e32 v2, v191
	v_min_u32_e32 v22, 32, v2
	v_lshlrev_b64 v[2:3], v22, v[190:191]
	v_min_u32_e32 v2, 1, v2
	v_or_b32_e32 v2, v3, v2
	v_cvt_f32_u32_e32 v2, v2
	v_sub_u32_e32 v3, 32, v22
	v_lshl_add_u64 v[20:21], v[0:1], 0, s[38:39]
	v_lshl_add_u64 v[22:23], v[0:1], 0, s[42:43]
	v_ldexp_f32 v2, v2, v3
	v_mul_f32_e32 v2, 0x33800000, v2
	v_fmamk_f32 v2, v2, 0x3a000000, v234
	v_mul_f32_e32 v3, 0x4b800000, v2
	v_cmp_gt_f32_e32 vcc, s50, v2
	s_nop 1
	v_cndmask_b32_e32 v2, v2, v3, vcc
	v_rsq_f32_e32 v2, v2
	s_nop 0
	v_mul_f32_e32 v0, 0x45800000, v2
	v_cndmask_b32_e32 v0, v2, v0, vcc
	v_pk_mul_f32 v[2:3], v[18:19], v[0:1] op_sel_hi:[1,0]
	v_pk_mul_f32 v[16:17], v[16:17], v[0:1] op_sel_hi:[1,0]
	v_pk_mul_f32 v[14:15], v[14:15], v[0:1] op_sel_hi:[1,0]
	v_pk_mul_f32 v[12:13], v[12:13], v[0:1] op_sel_hi:[1,0]
	v_pk_mul_f32 v[10:11], v[10:11], v[0:1] op_sel_hi:[1,0]
	v_pk_mul_f32 v[8:9], v[8:9], v[0:1] op_sel_hi:[1,0]
	v_pk_mul_f32 v[18:19], v[6:7], v[0:1] op_sel_hi:[1,0]
	v_pk_mul_f32 v[6:7], v[4:5], v[0:1] op_sel_hi:[1,0]
	v_cvt_pk_bf16_f32 v0, v16, v17
	v_cvt_pk_bf16_f32 v1, v2, v3
	v_cvt_pk_bf16_f32 v2, v12, v13
	v_cvt_pk_bf16_f32 v3, v14, v15
	v_cvt_pk_bf16_f32 v4, v8, v9
	v_cvt_pk_bf16_f32 v5, v10, v11
	s_nop 0
	v_cvt_pk_bf16_f32 v6, v6, v7
	v_cvt_pk_bf16_f32 v7, v18, v19
	global_store_dwordx4 v[20:21], v[0:3], off nt
	global_store_dwordx4 v[22:23], v[4:7], off nt
	s_cbranch_scc0 .LBB0_625
	s_waitcnt vmcnt(0)
	s_cmpk_gt_u32 s1, 0xff
	s_cbranch_scc1 .LBB0_630
	s_barrier

; #define G_STAGE(bufoff, gbase, voff) do { _Pragma("unroll") for (int _i = 0; _i < 2; ++_i) { unsigned _vo = (voff)[_i]; asm volatile("" : "+v"(_vo));   \
;     __builtin_amdgcn_global_load_lds((const unsigned*)((const char*)(gbase) + _vo), (LAS unsigned*)(lds + (bufoff) + ldsw + _i * 8192), 16, 0, 0); } } while (0)
; #define G_LDA(dst, b, h) do { _Pragma("unroll") for (int m = 0; m < 4; ++m) _Pragma("unroll") for (int k = 0; k < 2; ++k) dst[m][k] = *(const LAS bf16x8*)(lds + G_SA(b, h) + aoff + m * 2048 + k * 1024); } while (0)
; #define G_LDB(dst, b, h) do { _Pragma("unroll") for (int n = 0; n < 2; ++n) _Pragma("unroll") for (int k = 0; k < 2; ++k) dst[n][k] = *(const LAS bf16x8*)(lds + G_SB(b, h) + boff + n * 2048 + k * 1024); } while (0)
; #define G_MMA(ai, bj, At, Bt) do { __builtin_amdgcn_s_setprio(1); _Pragma("unroll") for (int m = 0; m < 4; ++m) _Pragma("unroll") for (int n = 0; n < 2; ++n) _Pragma("unroll") for (int k = 0; k < 2; ++k) \
;     acc[ai][bj][m][n] = __builtin_amdgcn_mfma_f32_16x16x32_bf16(Bt[n][k], At[m][k], acc[ai][bj][m][n], 0, 0, 0); __builtin_amdgcn_s_setprio(0); } while (0)
; template <class Epi>
; __device__ __forceinline__ void gemm_phase(LAS unsigned char* lds, const int K, const unsigned lda_b, const unsigned ldb_b, const Map& M, const Epi& E) {
;     ...
;     for (int t = 0; t < nt; t += 2) {
;       const bool last = (t == nt - 2);
;       const char* a1h1 = cur.a0 + a_h + (size_t)(t + 1) * kstep;
;       const char* a2h0 = last ? nxt.a0 : cur.a0 + (size_t)(t + 2) * kstep; const char* a2h1 = a2h0 + a_h;
;       const char* b2h0 = last ? nxt.b0 : cur.b0 + (size_t)(t + 2) * kstep; const char* b2h1 = last ? nxt.b1 : cur.b1 + (size_t)(t + 2) * kstep;
;       G_LDB(B0, 0, 0); G_SCHED; G_LDA(At, 0, 0); G_STAGE(G_SA(1, 1), a1h1, voffA);
;       G_WAIT_L(8); G_BAR; G_WAIT_L(0); G_MMA(0, 0, At, B0); G_BAR; G_SCHED;
;       G_LDB(B1, 0, 1); G_STAGE(G_SB(0, 0), b2h0, voffB);
;       G_BAR; G_WAIT_L(0); G_MMA(0, 1, At, B1); G_BAR;
;       G_LDA(At, 0, 1); G_STAGE(G_SA(0, 0), a2h0, voffA);
;       G_BAR; G_WAIT_L(0); G_MMA(1, 0, At, B0); G_BAR; G_SCHED;
;       G_STAGE(G_SB(0, 1), b2h1, voffB);
;       G_WAIT_V(6); G_BAR; G_MMA(1, 1, At, B1); G_BAR;
;       G_LDB(B0, 1, 0); G_SCHED; G_LDA(At, 1, 0); G_STAGE(G_SA(0, 1), a2h1, voffA);
;       G_WAIT_L(8); G_BAR; G_WAIT_L(0); G_MMA(0, 0, At, B0); G_BAR; G_SCHED;
.LBB0_651:
	s_add_u32 s22, s2, 0xfff80080
	s_addc_u32 s34, s3, -1
	s_add_u32 s35, s29, s46
	s_addc_u32 s38, s30, 0
	s_add_i32 vcc_lo, 0, 0x10000
	v_add_u32_e32 v80, vcc_lo, v158
	ds_read_b128 v[132:135], v80
	ds_read_b128 v[136:139], v80 offset:1024
	ds_read_b128 v[140:143], v80 offset:2048
	ds_read_b128 v[144:147], v80 offset:3072
	s_cmp_eq_u32 s31, 28
	s_cselect_b32 s43, s9, s34
	s_cselect_b32 s42, s8, s22
	s_cselect_b32 s45, s37, s30
	s_cselect_b32 s44, s36, s29
	v_mov_b32_e32 v80, v153
	s_cselect_b32 s39, s28, s38
	s_cselect_b32 s38, s0, s35
	s_add_u32 s68, s42, 0x80000
	ds_read_b128 v[148:151], v170
	ds_read_b128 v[172:175], v170 offset:1024
	ds_read_b128 v[190:193], v170 offset:2048
	ds_read_b128 v[194:197], v170 offset:3072
	ds_read_b128 v[198:201], v170 offset:4096
	ds_read_b128 v[202:205], v170 offset:5120
	ds_read_b128 v[206:209], v170 offset:6144
	ds_read_b128 v[210:213], v170 offset:7168
	s_addc_u32 s69, s43, 0
	s_add_i32 m0, s48, 0xc000
	s_nop 0
	global_load_lds_dwordx4 v80, s[2:3]
	v_mov_b32_e32 v80, v155
	s_add_i32 m0, s48, 0xe000
	s_nop 0
	global_load_lds_dwordx4 v80, s[2:3]
	s_waitcnt lgkmcnt(8)
	s_barrier
	s_waitcnt lgkmcnt(0)
	s_setprio 1
	s_waitcnt lgkmcnt(0)
	v_mfma_f32_16x16x32_bf16 v[126:129], v[132:135], v[148:151], v[126:129]
	v_mfma_f32_16x16x32_bf16 v[122:125], v[140:143], v[148:151], v[122:125]
	v_mfma_f32_16x16x32_bf16 v[110:113], v[132:135], v[190:193], v[110:113]
	v_mfma_f32_16x16x32_bf16 v[106:109], v[140:143], v[190:193], v[106:109]
	v_mfma_f32_16x16x32_bf16 v[94:97], v[132:135], v[198:201], v[94:97]
	v_mfma_f32_16x16x32_bf16 v[90:93], v[140:143], v[198:201], v[90:93]
	v_mfma_f32_16x16x32_bf16 v[76:79], v[132:135], v[206:209], v[76:79]
	v_mfma_f32_16x16x32_bf16 v[72:75], v[140:143], v[206:209], v[72:75]
	v_mfma_f32_16x16x32_bf16 v[126:129], v[136:139], v[172:175], v[126:129]
	v_mfma_f32_16x16x32_bf16 v[122:125], v[144:147], v[172:175], v[122:125]
	v_mfma_f32_16x16x32_bf16 v[110:113], v[136:139], v[194:197], v[110:113]
	v_mfma_f32_16x16x32_bf16 v[106:109], v[144:147], v[194:197], v[106:109]
	v_mfma_f32_16x16x32_bf16 v[94:97], v[136:139], v[202:205], v[94:97]
	v_mfma_f32_16x16x32_bf16 v[90:93], v[144:147], v[202:205], v[90:93]
	v_mfma_f32_16x16x32_bf16 v[76:79], v[136:139], v[210:213], v[76:79]
	v_mfma_f32_16x16x32_bf16 v[72:75], v[144:147], v[210:213], v[72:75]
	s_setprio 0
	s_barrier
	s_add_i32 s22, 0, 0x14000
	v_add_u32_e32 v80, s22, v158
	ds_read_b128 v[214:217], v80
	ds_read_b128 v[226:229], v80 offset:1024
	ds_read_b128 v[238:241], v80 offset:2048
	ds_read_b128 v[242:245], v80 offset:3072
	v_mov_b32_e32 v80, v154
	s_add_i32 s34, vcc_lo, s47
	s_mov_b32 m0, s34
	s_nop 0
	global_load_lds_dwordx4 v80, s[44:45]
	v_mov_b32_e32 v80, v156
	s_add_i32 m0, s34, 0x2000
	s_nop 0
	global_load_lds_dwordx4 v80, s[44:45]
	s_barrier
	s_waitcnt lgkmcnt(0)
	s_setprio 1
	s_waitcnt lgkmcnt(0)
	v_mfma_f32_16x16x32_bf16 v[118:121], v[214:217], v[148:151], v[118:121]
	v_mfma_f32_16x16x32_bf16 v[114:117], v[238:241], v[148:151], v[114:117]
	v_mfma_f32_16x16x32_bf16 v[102:105], v[214:217], v[190:193], v[102:105]
	v_mfma_f32_16x16x32_bf16 v[98:101], v[238:241], v[190:193], v[98:101]
	v_mfma_f32_16x16x32_bf16 v[86:89], v[214:217], v[198:201], v[86:89]
	v_mfma_f32_16x16x32_bf16 v[82:85], v[238:241], v[198:201], v[82:85]
	v_mfma_f32_16x16x32_bf16 v[68:71], v[214:217], v[206:209], v[68:71]
	v_mfma_f32_16x16x32_bf16 v[64:67], v[238:241], v[206:209], v[64:67]
	v_mfma_f32_16x16x32_bf16 v[118:121], v[226:229], v[172:175], v[118:121]
	v_mfma_f32_16x16x32_bf16 v[114:117], v[242:245], v[172:175], v[114:117]
	v_mfma_f32_16x16x32_bf16 v[102:105], v[226:229], v[194:197], v[102:105]
	v_mfma_f32_16x16x32_bf16 v[98:101], v[242:245], v[194:197], v[98:101]
	v_mfma_f32_16x16x32_bf16 v[86:89], v[226:229], v[202:205], v[86:89]
	v_mfma_f32_16x16x32_bf16 v[82:85], v[242:245], v[202:205], v[82:85]
	v_mfma_f32_16x16x32_bf16 v[68:71], v[226:229], v[210:213], v[68:71]
	v_mfma_f32_16x16x32_bf16 v[64:67], v[242:245], v[210:213], v[64:67]
	s_setprio 0
	v_mov_b32_e32 v80, v153
	s_mov_b32 m0, s48
	s_barrier
	ds_read_b128 v[148:151], v170 offset:16384
	ds_read_b128 v[172:175], v170 offset:17408
	ds_read_b128 v[190:193], v170 offset:18432
	ds_read_b128 v[194:197], v170 offset:19456
	ds_read_b128 v[198:201], v170 offset:20480
	ds_read_b128 v[202:205], v170 offset:21504
	ds_read_b128 v[206:209], v170 offset:22528
	ds_read_b128 v[210:213], v170 offset:23552
	s_nop 0
	global_load_lds_dwordx4 v80, s[42:43]
	v_mov_b32_e32 v80, v155
	s_mov_b32 m0, s49
	s_nop 0
	global_load_lds_dwordx4 v80, s[42:43]
	s_barrier
	s_waitcnt lgkmcnt(0)
	s_setprio 1
	s_waitcnt lgkmcnt(0)
	v_mfma_f32_16x16x32_bf16 v[60:63], v[132:135], v[148:151], v[60:63]
	v_mfma_f32_16x16x32_bf16 v[56:59], v[140:143], v[148:151], v[56:59]
	v_mfma_f32_16x16x32_bf16 v[44:47], v[132:135], v[190:193], v[44:47]
	v_mfma_f32_16x16x32_bf16 v[40:43], v[140:143], v[190:193], v[40:43]
	v_mfma_f32_16x16x32_bf16 v[28:31], v[132:135], v[198:201], v[28:31]
	v_mfma_f32_16x16x32_bf16 v[24:27], v[140:143], v[198:201], v[24:27]
	v_mfma_f32_16x16x32_bf16 v[12:15], v[132:135], v[206:209], v[12:15]
	v_mfma_f32_16x16x32_bf16 v[8:11], v[140:143], v[206:209], v[8:11]
	v_mfma_f32_16x16x32_bf16 v[60:63], v[136:139], v[172:175], v[60:63]
	v_mfma_f32_16x16x32_bf16 v[56:59], v[144:147], v[172:175], v[56:59]
	v_mfma_f32_16x16x32_bf16 v[44:47], v[136:139], v[194:197], v[44:47]
	v_mfma_f32_16x16x32_bf16 v[40:43], v[144:147], v[194:197], v[40:43]
	v_mfma_f32_16x16x32_bf16 v[28:31], v[136:139], v[202:205], v[28:31]
	v_mfma_f32_16x16x32_bf16 v[24:27], v[144:147], v[202:205], v[24:27]
	v_mfma_f32_16x16x32_bf16 v[12:15], v[136:139], v[210:213], v[12:15]
	v_mfma_f32_16x16x32_bf16 v[8:11], v[144:147], v[210:213], v[8:11]
	s_setprio 0
	s_barrier
; #define G_STAGE(bufoff, gbase, voff) do { _Pragma("unroll") for (int _i = 0; _i < 2; ++_i) { unsigned _vo = (voff)[_i]; asm volatile("" : "+v"(_vo));   \
;     __builtin_amdgcn_global_load_lds((const unsigned*)((const char*)(gbase) + _vo), (LAS unsigned*)(lds + (bufoff) + ldsw + _i * 8192), 16, 0, 0); } } while (0)
; #define G_LDA(dst, b, h) do { _Pragma("unroll") for (int m = 0; m < 4; ++m) _Pragma("unroll") for (int k = 0; k < 2; ++k) dst[m][k] = *(const LAS bf16x8*)(lds + G_SA(b, h) + aoff + m * 2048 + k * 1024); } while (0)
; #define G_LDB(dst, b, h) do { _Pragma("unroll") for (int n = 0; n < 2; ++n) _Pragma("unroll") for (int k = 0; k < 2; ++k) dst[n][k] = *(const LAS bf16x8*)(lds + G_SB(b, h) + boff + n * 2048 + k * 1024); } while (0)
; #define G_MMA(ai, bj, At, Bt) do { __builtin_amdgcn_s_setprio(1); _Pragma("unroll") for (int m = 0; m < 4; ++m) _Pragma("unroll") for (int n = 0; n < 2; ++n) _Pragma("unroll") for (int k = 0; k < 2; ++k) \
;     acc[ai][bj][m][n] = __builtin_amdgcn_mfma_f32_16x16x32_bf16(Bt[n][k], At[m][k], acc[ai][bj][m][n], 0, 0, 0); __builtin_amdgcn_s_setprio(0); } while (0)
; #define G_WAIT_V(n) asm volatile("s_waitcnt vmcnt(" #n ")" ::: "memory")
; #define G_WAIT_L(n) asm volatile("s_waitcnt lgkmcnt(" #n ")" ::: "memory")
; template <class Epi>
; __device__ __forceinline__ void gemm_phase(LAS unsigned char* lds, const int K, const unsigned lda_b, const unsigned ldb_b, const Map& M, const Epi& E) {
;     ...
;       G_LDB(B0, 0, 0); G_SCHED; G_LDA(At, 0, 0); G_STAGE(G_SA(1, 1), a1h1, voffA);
;       G_WAIT_L(8); G_BAR; G_WAIT_L(0); G_MMA(0, 0, At, B0); G_BAR; G_SCHED;
;       G_LDB(B1, 0, 1); G_STAGE(G_SB(0, 0), b2h0, voffB);
;       G_BAR; G_WAIT_L(0); G_MMA(0, 1, At, B1); G_BAR;
;       G_LDA(At, 0, 1); G_STAGE(G_SA(0, 0), a2h0, voffA);
;       G_BAR; G_WAIT_L(0); G_MMA(1, 0, At, B0); G_BAR; G_SCHED;
;       G_STAGE(G_SB(0, 1), b2h1, voffB);
;       G_WAIT_V(6); G_BAR; G_MMA(1, 1, At, B1); G_BAR;
;       G_LDB(B0, 1, 0); G_SCHED; G_LDA(At, 1, 0); G_STAGE(G_SA(0, 1), a2h1, voffA);
;       G_WAIT_L(8); G_BAR; G_WAIT_L(0); G_MMA(0, 0, At, B0); G_BAR; G_SCHED;
;       G_LDB(B1, 1, 1); G_STAGE(G_SB(1, 0), b2h0 + kstep, voffB);
;       G_BAR; G_WAIT_L(0); G_MMA(0, 1, At, B1); G_BAR;
;       G_LDA(At, 1, 1); G_STAGE(G_SA(1, 0), a2h0 + kstep, voffA);
;       G_BAR; G_WAIT_L(0); G_MMA(1, 0, At, B0); G_BAR; G_SCHED;
	v_mov_b32_e32 v80, v154
	s_add_i32 s22, s22, s47
	s_mov_b32 m0, s22
	s_nop 0
	global_load_lds_dwordx4 v80, s[38:39]
	v_mov_b32_e32 v80, v156
	s_add_i32 m0, s22, 0x2000
	s_nop 0
	global_load_lds_dwordx4 v80, s[38:39]
	s_waitcnt vmcnt(6)
	s_barrier
	s_setprio 1
	v_mfma_f32_16x16x32_bf16 v[52:55], v[214:217], v[148:151], v[52:55]
	v_mfma_f32_16x16x32_bf16 v[48:51], v[238:241], v[148:151], v[48:51]
	v_mfma_f32_16x16x32_bf16 v[36:39], v[214:217], v[190:193], v[36:39]
	v_mfma_f32_16x16x32_bf16 v[32:35], v[238:241], v[190:193], v[32:35]
	v_mfma_f32_16x16x32_bf16 v[20:23], v[214:217], v[198:201], v[20:23]
	v_mfma_f32_16x16x32_bf16 v[16:19], v[238:241], v[198:201], v[16:19]
	v_mfma_f32_16x16x32_bf16 v[4:7], v[214:217], v[206:209], v[4:7]
	v_mfma_f32_16x16x32_bf16 v[0:3], v[238:241], v[206:209], v[0:3]
	v_mfma_f32_16x16x32_bf16 v[52:55], v[226:229], v[172:175], v[52:55]
	v_mfma_f32_16x16x32_bf16 v[48:51], v[242:245], v[172:175], v[48:51]
	v_mfma_f32_16x16x32_bf16 v[36:39], v[226:229], v[194:197], v[36:39]
	v_mfma_f32_16x16x32_bf16 v[32:35], v[242:245], v[194:197], v[32:35]
	v_mfma_f32_16x16x32_bf16 v[20:23], v[226:229], v[202:205], v[20:23]
	v_mfma_f32_16x16x32_bf16 v[16:19], v[242:245], v[202:205], v[16:19]
	v_mfma_f32_16x16x32_bf16 v[4:7], v[226:229], v[210:213], v[4:7]
	v_mfma_f32_16x16x32_bf16 v[0:3], v[242:245], v[210:213], v[0:3]
	s_setprio 0
	s_add_i32 s22, 0, 0x18000
	v_add_u32_e32 v80, s22, v158
	s_barrier
	ds_read_b128 v[132:135], v80
	ds_read_b128 v[136:139], v80 offset:1024
	ds_read_b128 v[140:143], v80 offset:2048
	ds_read_b128 v[144:147], v80 offset:3072
	v_mov_b32_e32 v80, v153
	s_mov_b32 m0, s61
	ds_read_b128 v[148:151], v170 offset:32768
	ds_read_b128 v[172:175], v170 offset:33792
	ds_read_b128 v[190:193], v170 offset:34816
	ds_read_b128 v[194:197], v170 offset:35840
	ds_read_b128 v[198:201], v170 offset:36864
	ds_read_b128 v[202:205], v170 offset:37888
	ds_read_b128 v[206:209], v170 offset:38912
	ds_read_b128 v[210:213], v170 offset:39936
	s_nop 0
	global_load_lds_dwordx4 v80, s[68:69]
	v_mov_b32_e32 v80, v155
	s_mov_b32 m0, s66
	s_nop 0
	global_load_lds_dwordx4 v80, s[68:69]
	s_waitcnt lgkmcnt(8)
	s_barrier
	s_waitcnt lgkmcnt(0)
	s_setprio 1
	s_waitcnt lgkmcnt(0)
	v_mfma_f32_16x16x32_bf16 v[126:129], v[132:135], v[148:151], v[126:129]
	v_mfma_f32_16x16x32_bf16 v[122:125], v[140:143], v[148:151], v[122:125]
	v_mfma_f32_16x16x32_bf16 v[110:113], v[132:135], v[190:193], v[110:113]
	v_mfma_f32_16x16x32_bf16 v[106:109], v[140:143], v[190:193], v[106:109]
	v_mfma_f32_16x16x32_bf16 v[94:97], v[132:135], v[198:201], v[94:97]
	v_mfma_f32_16x16x32_bf16 v[90:93], v[140:143], v[198:201], v[90:93]
	v_mfma_f32_16x16x32_bf16 v[76:79], v[132:135], v[206:209], v[76:79]
	v_mfma_f32_16x16x32_bf16 v[72:75], v[140:143], v[206:209], v[72:75]
	v_mfma_f32_16x16x32_bf16 v[126:129], v[136:139], v[172:175], v[126:129]
	v_mfma_f32_16x16x32_bf16 v[122:125], v[144:147], v[172:175], v[122:125]
	v_mfma_f32_16x16x32_bf16 v[110:113], v[136:139], v[194:197], v[110:113]
	v_mfma_f32_16x16x32_bf16 v[106:109], v[144:147], v[194:197], v[106:109]
	v_mfma_f32_16x16x32_bf16 v[94:97], v[136:139], v[202:205], v[94:97]
	v_mfma_f32_16x16x32_bf16 v[90:93], v[144:147], v[202:205], v[90:93]
	v_mfma_f32_16x16x32_bf16 v[76:79], v[136:139], v[210:213], v[76:79]
	v_mfma_f32_16x16x32_bf16 v[72:75], v[144:147], v[210:213], v[72:75]
	s_setprio 0
	s_barrier
	s_add_i32 s34, 0, 0x1c000
	v_add_u32_e32 v80, s34, v158
	ds_read_b128 v[214:217], v80
	ds_read_b128 v[226:229], v80 offset:1024
	ds_read_b128 v[238:241], v80 offset:2048
	ds_read_b128 v[242:245], v80 offset:3072
	v_mov_b32_e32 v80, v154
	s_add_i32 s22, s22, s47
	s_add_i32 m0, s22, 0xffffff80
	v_mov_b32_e32 v80, v156
	global_load_lds_dwordx4 v154, s[44:45] offset:128
	s_add_i32 m0, s22, 0x1f80
	s_nop 0
	global_load_lds_dwordx4 v156, s[44:45] offset:128
	s_barrier
	s_waitcnt lgkmcnt(0)
	s_setprio 1
	s_waitcnt lgkmcnt(0)
	v_mfma_f32_16x16x32_bf16 v[118:121], v[214:217], v[148:151], v[118:121]
	v_mfma_f32_16x16x32_bf16 v[114:117], v[238:241], v[148:151], v[114:117]
	v_mfma_f32_16x16x32_bf16 v[102:105], v[214:217], v[190:193], v[102:105]
	v_mfma_f32_16x16x32_bf16 v[98:101], v[238:241], v[190:193], v[98:101]
	v_mfma_f32_16x16x32_bf16 v[86:89], v[214:217], v[198:201], v[86:89]
	v_mfma_f32_16x16x32_bf16 v[82:85], v[238:241], v[198:201], v[82:85]
	v_mfma_f32_16x16x32_bf16 v[68:71], v[214:217], v[206:209], v[68:71]
	v_mfma_f32_16x16x32_bf16 v[64:67], v[238:241], v[206:209], v[64:67]
	v_mfma_f32_16x16x32_bf16 v[118:121], v[226:229], v[172:175], v[118:121]
	v_mfma_f32_16x16x32_bf16 v[114:117], v[242:245], v[172:175], v[114:117]
	v_mfma_f32_16x16x32_bf16 v[102:105], v[226:229], v[194:197], v[102:105]
	v_mfma_f32_16x16x32_bf16 v[98:101], v[242:245], v[194:197], v[98:101]
	v_mfma_f32_16x16x32_bf16 v[86:89], v[226:229], v[202:205], v[86:89]
	v_mfma_f32_16x16x32_bf16 v[82:85], v[242:245], v[202:205], v[82:85]
	v_mfma_f32_16x16x32_bf16 v[68:71], v[226:229], v[210:213], v[68:71]
	v_mfma_f32_16x16x32_bf16 v[64:67], v[242:245], v[210:213], v[64:67]
	s_setprio 0
	v_mov_b32_e32 v80, v153
	s_barrier
	ds_read_b128 v[148:151], v170 offset:49152
	ds_read_b128 v[172:175], v170 offset:50176
	ds_read_b128 v[190:193], v170 offset:51200
	ds_read_b128 v[194:197], v170 offset:52224
	ds_read_b128 v[198:201], v170 offset:53248
	ds_read_b128 v[202:205], v170 offset:54272
	ds_read_b128 v[206:209], v170 offset:55296
	ds_read_b128 v[210:213], v170 offset:56320
	s_add_i32 m0, s67, 0xffffff80
	v_mov_b32_e32 v80, v155
	global_load_lds_dwordx4 v153, s[42:43] offset:128
	s_add_i32 m0, s76, 0xffffff80
	s_nop 0
	global_load_lds_dwordx4 v155, s[42:43] offset:128
	s_barrier
; __device__ __forceinline__ float rinv_of(unsigned long long ss) { return rsqrtf((float)ss * (1.f / 16777216.f) * (1.f / DM) + 1e-6f); }
; #define G_STAGE(bufoff, gbase, voff) do { _Pragma("unroll") for (int _i = 0; _i < 2; ++_i) { unsigned _vo = (voff)[_i]; asm volatile("" : "+v"(_vo));   \
;     __builtin_amdgcn_global_load_lds((const unsigned*)((const char*)(gbase) + _vo), (LAS unsigned*)(lds + (bufoff) + ldsw + _i * 8192), 16, 0, 0); } } while (0)
; #define G_LDA(dst, b, h) do { _Pragma("unroll") for (int m = 0; m < 4; ++m) _Pragma("unroll") for (int k = 0; k < 2; ++k) dst[m][k] = *(const LAS bf16x8*)(lds + G_SA(b, h) + aoff + m * 2048 + k * 1024); } while (0)
; #define G_LDB(dst, b, h) do { _Pragma("unroll") for (int n = 0; n < 2; ++n) _Pragma("unroll") for (int k = 0; k < 2; ++k) dst[n][k] = *(const LAS bf16x8*)(lds + G_SB(b, h) + boff + n * 2048 + k * 1024); } while (0)
; #define G_WAIT_V(n) asm volatile("s_waitcnt vmcnt(" #n ")" ::: "memory")
; #define G_WAIT_L(n) asm volatile("s_waitcnt lgkmcnt(" #n ")" ::: "memory")
; #define G_BAR __builtin_amdgcn_s_barrier()
; #define G_SCHED __builtin_amdgcn_sched_barrier(0)
;   __device__ __forceinline__ void operator()(const f32x4 (&acc)[2][2][4][2], const Unit& u, const EpiCtx& x_, int wr, int wc, int fr, int fq) const {
;     ...
;     { const int lg = x_.p0, S = x_.p1, L = S >> lg;
; #pragma unroll
;       for (int bj = 0; bj < 2; ++bj) {
;         const int col = u.c0 + wc * 64 + bj * 32 + 8 * fq, seq = col / S, rem = col % S, r = rem / L, m0 = rem % L;
;         const unsigned long long* sp = x_.ss + (size_t)seq * S + r;
; #pragma unroll
;         for (int i = 0; i < 8; ++i) cs[bj][i >> 2][i & 3] = rinv_of(sp[(size_t)(m0 + i) << lg]);
;       } }
; template <class Epi>
; __device__ __forceinline__ void gemm_phase(LAS unsigned char* lds, const int K, const unsigned lda_b, const unsigned ldb_b, const Map& M, const Epi& E) {
;     ...
;       G_WAIT_L(8); G_BAR; G_WAIT_L(0); G_MMA(0, 0, At, B0); G_BAR; G_SCHED;
;       G_LDB(B1, 1, 1); G_STAGE(G_SB(1, 0), b2h0 + kstep, voffB);
;       G_BAR; G_WAIT_L(0); G_MMA(0, 1, At, B1); G_BAR;
;       G_LDA(At, 1, 1); G_STAGE(G_SA(1, 0), a2h0 + kstep, voffA);
;       G_BAR; G_WAIT_L(0); G_MMA(1, 0, At, B0); G_BAR; G_SCHED;
;       G_STAGE(G_SB(1, 1), b2h1 + kstep, voffB);
;       G_WAIT_V(6); G_BAR; G_MMA(1, 1, At, B1); G_BAR;
	s_waitcnt lgkmcnt(0)
	s_setprio 1
	s_waitcnt lgkmcnt(0)
	v_mfma_f32_16x16x32_bf16 v[60:63], v[132:135], v[148:151], v[60:63]
	v_mfma_f32_16x16x32_bf16 v[56:59], v[140:143], v[148:151], v[56:59]
	v_mfma_f32_16x16x32_bf16 v[44:47], v[132:135], v[190:193], v[44:47]
	v_mfma_f32_16x16x32_bf16 v[40:43], v[140:143], v[190:193], v[40:43]
	v_mfma_f32_16x16x32_bf16 v[28:31], v[132:135], v[198:201], v[28:31]
	v_mfma_f32_16x16x32_bf16 v[24:27], v[140:143], v[198:201], v[24:27]
	v_mfma_f32_16x16x32_bf16 v[12:15], v[132:135], v[206:209], v[12:15]
	v_mfma_f32_16x16x32_bf16 v[8:11], v[140:143], v[206:209], v[8:11]
	v_mfma_f32_16x16x32_bf16 v[60:63], v[136:139], v[172:175], v[60:63]
	v_mfma_f32_16x16x32_bf16 v[56:59], v[144:147], v[172:175], v[56:59]
	v_mfma_f32_16x16x32_bf16 v[44:47], v[136:139], v[194:197], v[44:47]
	v_mfma_f32_16x16x32_bf16 v[40:43], v[144:147], v[194:197], v[40:43]
	v_mfma_f32_16x16x32_bf16 v[28:31], v[136:139], v[202:205], v[28:31]
	v_mfma_f32_16x16x32_bf16 v[24:27], v[144:147], v[202:205], v[24:27]
	v_mfma_f32_16x16x32_bf16 v[12:15], v[136:139], v[210:213], v[12:15]
	v_mfma_f32_16x16x32_bf16 v[8:11], v[144:147], v[210:213], v[8:11]
	s_setprio 0
	s_barrier
	v_mov_b32_e32 v80, v154
	s_add_i32 s22, s34, s47
	s_add_i32 m0, s22, 0xffffff80
	v_mov_b32_e32 v80, v156
	global_load_lds_dwordx4 v154, s[38:39] offset:128
	s_add_i32 m0, s22, 0x1f80
	s_nop 0
	global_load_lds_dwordx4 v156, s[38:39] offset:128
	s_waitcnt vmcnt(6)
	s_barrier
	s_setprio 1
	v_mfma_f32_16x16x32_bf16 v[52:55], v[214:217], v[148:151], v[52:55]
	v_mfma_f32_16x16x32_bf16 v[48:51], v[238:241], v[148:151], v[48:51]
	v_mfma_f32_16x16x32_bf16 v[36:39], v[214:217], v[190:193], v[36:39]
	v_mfma_f32_16x16x32_bf16 v[32:35], v[238:241], v[190:193], v[32:35]
	v_mfma_f32_16x16x32_bf16 v[20:23], v[214:217], v[198:201], v[20:23]
	v_mfma_f32_16x16x32_bf16 v[16:19], v[238:241], v[198:201], v[16:19]
	v_mfma_f32_16x16x32_bf16 v[4:7], v[214:217], v[206:209], v[4:7]
	v_mfma_f32_16x16x32_bf16 v[0:3], v[238:241], v[206:209], v[0:3]
	v_mfma_f32_16x16x32_bf16 v[52:55], v[226:229], v[172:175], v[52:55]
	v_mfma_f32_16x16x32_bf16 v[48:51], v[242:245], v[172:175], v[48:51]
	v_mfma_f32_16x16x32_bf16 v[36:39], v[226:229], v[194:197], v[36:39]
	v_mfma_f32_16x16x32_bf16 v[32:35], v[242:245], v[194:197], v[32:35]
	v_mfma_f32_16x16x32_bf16 v[20:23], v[226:229], v[202:205], v[20:23]
	v_mfma_f32_16x16x32_bf16 v[16:19], v[242:245], v[202:205], v[16:19]
	v_mfma_f32_16x16x32_bf16 v[4:7], v[226:229], v[210:213], v[4:7]
	v_mfma_f32_16x16x32_bf16 v[0:3], v[242:245], v[210:213], v[0:3]
	s_setprio 0
	s_add_i32 s31, s31, 2
	s_add_u32 s29, s29, 0x100
	s_addc_u32 s30, s30, 0
	s_add_u32 s2, s2, 0x100
	s_addc_u32 s3, s3, 0
	s_cmp_gt_u32 s31, 29
	s_barrier
	s_cbranch_scc0 .LBB0_651
	v_add_u32_e32 v171, s97, v159
	v_readfirstlane_b32 s0, v130
	v_sub_u32_e32 v130, 0, v171
	v_max_i32_e32 v130, v171, v130
	v_readfirstlane_b32 s42, v131
	v_mul_hi_u32 v131, v130, v152
	v_mul_lo_u32 v132, v131, s17
	v_sub_u32_e32 v130, v130, v132
	v_cmp_le_u32_e32 vcc, s17, v130
	v_add_u32_e32 v132, 1, v131
	v_ashrrev_i32_e32 v80, 31, v171
	v_cndmask_b32_e32 v131, v131, v132, vcc
	v_subrev_u32_e32 v132, s17, v130
	v_cndmask_b32_e32 v130, v130, v132, vcc
	v_cmp_le_u32_e32 vcc, s17, v130
	v_add_u32_e32 v130, 1, v131
	v_mov_b64_e32 v[136:137], s[62:63]
	v_cndmask_b32_e32 v130, v131, v130, vcc
	v_xor_b32_e32 v130, v130, v80
	v_sub_u32_e32 v130, v130, v80
	v_mul_lo_u32 v80, v130, s17
	v_sub_u32_e32 v80, v171, v80
	v_sub_u32_e32 v132, 0, v80
	v_max_i32_e32 v132, v80, v132
	v_mul_hi_u32 v133, v132, v169
	v_mul_lo_u32 v134, v133, s83
	v_sub_u32_e32 v132, v132, v134
	v_cmp_le_u32_e32 vcc, s83, v132
	v_add_u32_e32 v134, 1, v133
	v_ashrrev_i32_e32 v131, 31, v80
	v_cndmask_b32_e32 v133, v133, v134, vcc
	v_subrev_u32_e32 v134, s83, v132
	v_cndmask_b32_e32 v132, v132, v134, vcc
	v_cmp_le_u32_e32 vcc, s83, v132
	v_add_u32_e32 v132, 1, v133
	v_xor_b32_e32 v131, s87, v131
	v_cndmask_b32_e32 v132, v133, v132, vcc
	v_xor_b32_e32 v132, v132, v131
	v_sub_u32_e32 v132, v132, v131
	v_mul_lo_u32 v131, v132, s79
	v_sub_u32_e32 v138, v80, v131
	v_ashrrev_i32_e32 v131, 31, v130
	v_lshlrev_b64 v[130:131], s81, v[130:131]
	v_lshl_add_u64 v[130:131], v[130:131], 3, s[4:5]
	v_ashrrev_i32_e32 v133, 31, v132
	v_ashrrev_i32_e32 v139, 31, v138
	v_lshl_add_u64 v[140:141], v[132:133], 3, v[130:131]
	s_nop 1
	v_lshlrev_b64 v[202:203], s18, v[138:139]
	v_lshl_add_u64 v[204:205], v[202:203], 3, v[140:141]
	global_load_dwordx2 v[172:173], v[204:205], off
	v_add_u32_e32 v202, 1, v138
	v_ashrrev_i32_e32 v203, 31, v202
	v_lshlrev_b64 v[204:205], s18, v[202:203]
	v_lshl_add_u64 v[202:203], v[204:205], 3, v[140:141]
	global_load_dwordx2 v[174:175], v[202:203], off
	v_add_u32_e32 v202, 3, v138
	v_ashrrev_i32_e32 v203, 31, v202
	v_lshlrev_b64 v[204:205], s18, v[202:203]
	v_lshl_add_u64 v[202:203], v[204:205], 3, v[140:141]
	global_load_dwordx2 v[190:191], v[202:203], off
	v_add_u32_e32 v202, 5, v138
	v_ashrrev_i32_e32 v203, 31, v202
	v_lshlrev_b64 v[204:205], s18, v[202:203]
	v_lshl_add_u64 v[202:203], v[204:205], 3, v[140:141]
	global_load_dwordx2 v[192:193], v[202:203], off
	v_add_u32_e32 v202, 2, v138
	v_ashrrev_i32_e32 v203, 31, v202
	v_lshlrev_b64 v[204:205], s18, v[202:203]
	v_lshl_add_u64 v[202:203], v[204:205], 3, v[140:141]
	global_load_dwordx2 v[194:195], v[202:203], off
	v_add_u32_e32 v202, 4, v138
	v_ashrrev_i32_e32 v203, 31, v202
	v_lshlrev_b64 v[204:205], s18, v[202:203]
	v_lshl_add_u64 v[202:203], v[204:205], 3, v[140:141]
	global_load_dwordx2 v[196:197], v[202:203], off
	v_add_u32_e32 v202, 6, v138
	v_ashrrev_i32_e32 v203, 31, v202
	v_lshlrev_b64 v[204:205], s18, v[202:203]
	v_lshl_add_u64 v[202:203], v[204:205], 3, v[140:141]
	global_load_dwordx2 v[198:199], v[202:203], off
	v_add_u32_e32 v202, 7, v138
	v_ashrrev_i32_e32 v203, 31, v202
	v_lshlrev_b64 v[204:205], s18, v[202:203]
	v_lshl_add_u64 v[202:203], v[204:205], 3, v[140:141]
	global_load_dwordx2 v[200:201], v[202:203], off
	v_lshlrev_b64 v[130:131], s18, v[138:139]
	v_lshl_add_u64 v[130:131], v[130:131], 3, v[140:141]
	s_nop 0
	v_add_u32_e32 v132, 1, v138
	v_ashrrev_i32_e32 v133, 31, v132
	v_lshlrev_b64 v[132:133], s18, v[132:133]
	v_lshl_add_u64 v[132:133], v[132:133], 3, v[140:141]
	s_nop 0
	v_add_u32_e32 v134, 3, v138
	v_ashrrev_i32_e32 v135, 31, v134
	v_lshlrev_b64 v[134:135], s18, v[134:135]
	v_lshl_add_u64 v[134:135], v[134:135], 3, v[140:141]
	s_nop 0
	v_add_u32_e32 v142, 5, v138
	v_ashrrev_i32_e32 v143, 31, v142
	v_lshlrev_b64 v[142:143], s18, v[142:143]
	v_lshl_add_u64 v[142:143], v[142:143], 3, v[140:141]
	s_cmp_eq_u32 s96, s86
	s_mov_b64 s[38:39], s[36:37]
	s_nop 0
	s_waitcnt lgkmcnt(0)
; __device__ __forceinline__ unsigned cvt_pk_bf16(float lo, float hi) { unsigned r; asm("v_cvt_pk_bf16_f32 %0, %1, %2" : "=v"(r) : "v"(lo), "v"(hi)); return r; }
; __device__ __forceinline__ float rinv_of(unsigned long long ss) { return rsqrtf((float)ss * (1.f / 16777216.f) * (1.f / DM) + 1e-6f); }
;   __device__ __forceinline__ void operator()(const f32x4 (&acc)[2][2][4][2], const Unit& u, const EpiCtx& x_, int wr, int wc, int fr, int fq) const {
;     ...
;     { const int lg = x_.p0, S = x_.p1, L = S >> lg;
; #pragma unroll
;       for (int bj = 0; bj < 2; ++bj) {
;         const int col = u.c0 + wc * 64 + bj * 32 + 8 * fq, seq = col / S, rem = col % S, r = rem / L, m0 = rem % L;
;         const unsigned long long* sp = x_.ss + (size_t)seq * S + r;
; #pragma unroll
;         for (int i = 0; i < 8; ++i) cs[bj][i >> 2][i & 3] = rinv_of(sp[(size_t)(m0 + i) << lg]);
;       } }
; #pragma unroll
;     for (int ai = 0; ai < 2; ++ai)
; #pragma unroll
;       for (int m = 0; m < 4; ++m) {
;         const int row = u.r0 + ai * 128 + wr * 64 + m * 16 + fr, hh = (x_.p0 >> 1) * 16 + (row >> 7), d = row & 127;
; #pragma unroll
;         for (int bj = 0; bj < 2; ++bj) {
;           const int col = u.c0 + wc * 64 + bj * 32 + 8 * fq;
;           const f32x4 v0 = acc[ai][bj][m][0] * cs[bj][0], v1 = acc[ai][bj][m][1] * cs[bj][1];
;           uint4 o; o.x = cvt_pk_bf16(v0[0], v0[1]); o.y = cvt_pk_bf16(v0[2], v0[3]); o.z = cvt_pk_bf16(v1[0], v1[1]); o.w = cvt_pk_bf16(v1[2], v1[3]);
	s_nop 0
	s_waitcnt vmcnt(7)
	v_ffbh_u32_e32 v80, v173
	v_min_u32_e32 v80, 32, v80
	v_lshlrev_b64 v[130:131], v80, v[172:173]
	v_min_u32_e32 v130, 1, v130
	v_or_b32_e32 v130, v131, v130
	v_cvt_f32_u32_e32 v130, v130
	v_sub_u32_e32 v80, 32, v80
	v_ldexp_f32 v130, v130, v80
	s_nop 0
	s_waitcnt vmcnt(6)
	v_ffbh_u32_e32 v80, v175
	v_min_u32_e32 v80, 32, v80
	v_lshlrev_b64 v[132:133], v80, v[174:175]
	v_min_u32_e32 v131, 1, v132
	v_or_b32_e32 v131, v133, v131
	v_cvt_f32_u32_e32 v131, v131
	v_sub_u32_e32 v80, 32, v80
	v_ldexp_f32 v131, v131, v80
	v_pk_mul_f32 v[130:131], v[130:131], s[60:61] op_sel_hi:[1,0]
	s_nop 0
	v_pk_fma_f32 v[130:131], v[130:131], s[26:27], v[136:137] op_sel_hi:[1,0,0]
	s_nop 0
	v_mul_f32_e32 v80, 0x4b800000, v130
	v_cmp_gt_f32_e64 s[2:3], s50, v130
	v_cmp_gt_f32_e32 vcc, s50, v131
	s_nop 0
	v_cndmask_b32_e64 v80, v130, v80, s[2:3]
	v_rsq_f32_e32 v130, v80
	v_mul_f32_e32 v80, 0x4b800000, v131
	v_cndmask_b32_e32 v80, v131, v80, vcc
	v_rsq_f32_e32 v131, v80
	s_nop 0
	s_waitcnt vmcnt(5)
	v_ffbh_u32_e32 v80, v191
	v_min_u32_e32 v80, 32, v80
	v_lshlrev_b64 v[134:135], v80, v[190:191]
	v_pk_mul_f32 v[132:133], v[130:131], s[64:65] op_sel_hi:[1,0]
	v_min_u32_e32 v134, 1, v134
	v_cndmask_b32_e64 v130, v130, v132, s[2:3]
	v_add_u32_e32 v132, 2, v138
	v_cndmask_b32_e32 v131, v131, v133, vcc
	v_ashrrev_i32_e32 v133, 31, v132
	v_lshlrev_b64 v[132:133], s18, v[132:133]
	v_lshl_add_u64 v[132:133], v[132:133], 3, v[140:141]
	s_nop 0
	v_or_b32_e32 v134, v135, v134
	v_cvt_f32_u32_e32 v134, v134
	v_sub_u32_e32 v80, 32, v80
	v_pk_mul_f32 v[126:127], v[126:127], v[130:131]
	v_pk_mul_f32 v[110:111], v[110:111], v[130:131]
	v_ldexp_f32 v135, v134, v80
	v_cvt_pk_bf16_f32 v126, v126, v127
	v_pk_mul_f32 v[94:95], v[94:95], v[130:131]
	v_pk_mul_f32 v[76:77], v[76:77], v[130:131]
	v_pk_mul_f32 v[60:61], v[60:61], v[130:131]
	v_pk_mul_f32 v[44:45], v[44:45], v[130:131]
	v_pk_mul_f32 v[28:29], v[28:29], v[130:131]
	v_pk_mul_f32 v[12:13], v[12:13], v[130:131]
	s_waitcnt lgkmcnt(0)
	s_nop 0
	s_waitcnt vmcnt(3)
	v_ffbh_u32_e32 v80, v195
	v_min_u32_e32 v80, 32, v80
	v_lshlrev_b64 v[132:133], v80, v[194:195]
	v_min_u32_e32 v132, 1, v132
	v_or_b32_e32 v132, v133, v132
	v_cvt_f32_u32_e32 v132, v132
	v_sub_u32_e32 v80, 32, v80
	v_ldexp_f32 v134, v132, v80
	v_pk_mul_f32 v[132:133], v[134:135], s[60:61] op_sel_hi:[1,0]
	s_nop 0
	v_pk_fma_f32 v[132:133], v[132:133], s[26:27], v[136:137] op_sel_hi:[1,0,0]
	s_nop 0
	v_mul_f32_e32 v80, 0x4b800000, v132
	v_cmp_gt_f32_e64 s[2:3], s50, v132
	v_cmp_gt_f32_e32 vcc, s50, v133
	s_nop 0
	v_cndmask_b32_e64 v80, v132, v80, s[2:3]
	v_rsq_f32_e32 v132, v80
	v_mul_f32_e32 v80, 0x4b800000, v133
	v_cndmask_b32_e32 v80, v133, v80, vcc
	v_rsq_f32_e32 v133, v80
	v_ffbh_u32_e32 v80, v193
	v_min_u32_e32 v80, 32, v80
	v_lshlrev_b64 v[142:143], v80, v[192:193]
	v_pk_mul_f32 v[134:135], v[132:133], s[64:65] op_sel_hi:[1,0]
	v_min_u32_e32 v139, 1, v142
	v_cndmask_b32_e64 v132, v132, v134, s[2:3]
	v_add_u32_e32 v134, 4, v138
	v_cndmask_b32_e32 v133, v133, v135, vcc
	v_ashrrev_i32_e32 v135, 31, v134
	v_lshlrev_b64 v[134:135], s18, v[134:135]
	v_lshl_add_u64 v[134:135], v[134:135], 3, v[140:141]
	s_nop 0
	v_or_b32_e32 v139, v143, v139
	v_cvt_f32_u32_e32 v139, v139
	v_sub_u32_e32 v80, 32, v80
	v_pk_mul_f32 v[128:129], v[128:129], v[132:133]
	v_pk_mul_f32 v[112:113], v[112:113], v[132:133]
	v_ldexp_f32 v143, v139, v80
	v_cvt_pk_bf16_f32 v127, v128, v129
	v_pk_mul_f32 v[96:97], v[96:97], v[132:133]
	v_pk_mul_f32 v[78:79], v[78:79], v[132:133]
	v_pk_mul_f32 v[62:63], v[62:63], v[132:133]
	v_pk_mul_f32 v[46:47], v[46:47], v[132:133]
	v_pk_mul_f32 v[30:31], v[30:31], v[132:133]
	v_pk_mul_f32 v[14:15], v[14:15], v[132:133]
	s_waitcnt lgkmcnt(0)
	s_nop 0
	s_waitcnt vmcnt(2)
	v_ffbh_u32_e32 v80, v197
	v_min_u32_e32 v80, 32, v80
	v_lshlrev_b64 v[134:135], v80, v[196:197]
	v_min_u32_e32 v134, 1, v134
	v_or_b32_e32 v134, v135, v134
	v_cvt_f32_u32_e32 v134, v134
	v_sub_u32_e32 v80, 32, v80
	v_ldexp_f32 v142, v134, v80
	v_pk_mul_f32 v[134:135], v[142:143], s[60:61] op_sel_hi:[1,0]
	s_nop 0
	v_pk_fma_f32 v[134:135], v[134:135], s[26:27], v[136:137] op_sel_hi:[1,0,0]
	s_nop 0
	v_mul_f32_e32 v80, 0x4b800000, v134
	v_cmp_gt_f32_e64 s[2:3], s50, v134
	v_cmp_gt_f32_e32 vcc, s50, v135
	s_nop 0
	v_cndmask_b32_e64 v80, v134, v80, s[2:3]
	v_rsq_f32_e32 v134, v80
	v_mul_f32_e32 v80, 0x4b800000, v135
	v_cndmask_b32_e32 v80, v135, v80, vcc
	v_rsq_f32_e32 v135, v80
	s_nop 0
	v_pk_mul_f32 v[142:143], v[134:135], s[64:65] op_sel_hi:[1,0]
	s_nop 0
	v_cndmask_b32_e64 v134, v134, v142, s[2:3]
	v_add_u32_e32 v142, 6, v138
	v_add_u32_e32 v138, 7, v138
	v_cndmask_b32_e32 v135, v135, v143, vcc
	v_ashrrev_i32_e32 v143, 31, v142
	v_ashrrev_i32_e32 v139, 31, v138
	v_lshlrev_b64 v[142:143], s18, v[142:143]
	v_lshlrev_b64 v[138:139], s18, v[138:139]
	v_lshl_add_u64 v[142:143], v[142:143], 3, v[140:141]
	v_lshl_add_u64 v[138:139], v[138:139], 3, v[140:141]
	s_nop 0
	v_pk_mul_f32 v[122:123], v[122:123], v[134:135]
	s_nop 0
	v_cvt_pk_bf16_f32 v128, v122, v123
	v_ashrrev_i32_e32 v122, 5, v171
	v_ashrrev_i32_e32 v123, 31, v122
	v_lshlrev_b64 v[122:123], 13, v[122:123]
	v_lshl_add_u64 v[122:123], s[94:95], 0, v[122:123]
	s_waitcnt lgkmcnt(0)
	s_nop 0
	s_waitcnt vmcnt(0)
; __device__ __forceinline__ float rinv_of(unsigned long long ss) { return rsqrtf((float)ss * (1.f / 16777216.f) * (1.f / DM) + 1e-6f); }
;   __device__ __forceinline__ void operator()(const f32x4 (&acc)[2][2][4][2], const Unit& u, const EpiCtx& x_, int wr, int wc, int fr, int fq) const {
;     ...
;     { const int lg = x_.p0, S = x_.p1, L = S >> lg;
; #pragma unroll
;       for (int bj = 0; bj < 2; ++bj) {
;         const int col = u.c0 + wc * 64 + bj * 32 + 8 * fq, seq = col / S, rem = col % S, r = rem / L, m0 = rem % L;
;         const unsigned long long* sp = x_.ss + (size_t)seq * S + r;
; #pragma unroll
;         for (int i = 0; i < 8; ++i) cs[bj][i >> 2][i & 3] = rinv_of(sp[(size_t)(m0 + i) << lg]);
;       } }
; #pragma unroll
;     for (int ai = 0; ai < 2; ++ai)
; #pragma unroll
;       for (int m = 0; m < 4; ++m) {
;         const int row = u.r0 + ai * 128 + wr * 64 + m * 16 + fr, hh = (x_.p0 >> 1) * 16 + (row >> 7), d = row & 127;
; #pragma unroll
;         for (int bj = 0; bj < 2; ++bj) {
;           const int col = u.c0 + wc * 64 + bj * 32 + 8 * fq;
;           const f32x4 v0 = acc[ai][bj][m][0] * cs[bj][0], v1 = acc[ai][bj][m][1] * cs[bj][1];
	v_ffbh_u32_e32 v80, v201
	v_min_u32_e32 v80, 32, v80
	v_lshlrev_b64 v[138:139], v80, v[200:201]
	v_min_u32_e32 v138, 1, v138
	v_or_b32_e32 v138, v139, v138
	v_cvt_f32_u32_e32 v138, v138
	v_sub_u32_e32 v80, 32, v80
	v_ldexp_f32 v139, v138, v80
	v_ffbh_u32_e32 v80, v199
	v_min_u32_e32 v80, 32, v80
	v_lshlrev_b64 v[140:141], v80, v[198:199]
	v_min_u32_e32 v138, 1, v140
	v_or_b32_e32 v138, v141, v138
	v_cvt_f32_u32_e32 v138, v138
	v_sub_u32_e32 v80, 32, v80
	v_ldexp_f32 v138, v138, v80
	v_pk_mul_f32 v[138:139], v[138:139], s[60:61] op_sel_hi:[1,0]
	s_nop 0
	v_pk_fma_f32 v[138:139], v[138:139], s[26:27], v[136:137] op_sel_hi:[1,0,0]
	s_nop 0
	v_mul_f32_e32 v80, 0x4b800000, v138
	v_cmp_gt_f32_e64 s[2:3], s50, v138
	v_cmp_gt_f32_e32 vcc, s50, v139
	s_nop 0
	v_cndmask_b32_e64 v80, v138, v80, s[2:3]
	v_rsq_f32_e32 v138, v80
	v_mul_f32_e32 v80, 0x4b800000, v139
	v_cndmask_b32_e32 v80, v139, v80, vcc
	v_rsq_f32_e32 v139, v80
	v_add_u32_e32 v80, 32, v171
	v_pk_mul_f32 v[140:141], v[138:139], s[64:65] op_sel_hi:[1,0]
	s_nop 0
	v_cndmask_b32_e32 v139, v139, v141, vcc
	v_sub_u32_e32 v141, 0xffffffe0, v171
	v_max_i32_e32 v141, v80, v141
	v_mul_hi_u32 v142, v141, v152
	v_mul_lo_u32 v143, v142, s17
	v_sub_u32_e32 v141, v141, v143
	v_cmp_le_u32_e32 vcc, s17, v141
	v_add_u32_e32 v143, 1, v142
	v_cndmask_b32_e64 v138, v138, v140, s[2:3]
	v_cndmask_b32_e32 v142, v142, v143, vcc
	v_subrev_u32_e32 v143, s17, v141
	v_cndmask_b32_e32 v141, v141, v143, vcc
	v_cmp_le_u32_e32 vcc, s17, v141
	v_add_u32_e32 v141, 1, v142
	v_ashrrev_i32_e32 v140, 31, v80
	v_cndmask_b32_e32 v141, v142, v141, vcc
	v_xor_b32_e32 v141, v141, v140
	v_sub_u32_e32 v140, v141, v140
	v_mul_lo_u32 v141, v140, s17
	v_sub_u32_e32 v80, v80, v141
	v_sub_u32_e32 v142, 0, v80
	v_max_i32_e32 v142, v80, v142
	v_mul_hi_u32 v143, v142, v169
	v_mul_lo_u32 v144, v143, s83
	v_sub_u32_e32 v142, v142, v144
	v_cmp_le_u32_e32 vcc, s83, v142
	v_add_u32_e32 v144, 1, v143
	v_ashrrev_i32_e32 v141, 31, v80
	v_cndmask_b32_e32 v143, v143, v144, vcc
	v_subrev_u32_e32 v144, s83, v142
	v_cndmask_b32_e32 v142, v142, v144, vcc
	v_cmp_le_u32_e32 vcc, s83, v142
	v_add_u32_e32 v142, 1, v143
	v_xor_b32_e32 v141, s87, v141
	v_cndmask_b32_e32 v142, v143, v142, vcc
	v_xor_b32_e32 v142, v142, v141
	v_sub_u32_e32 v142, v142, v141
	v_mul_lo_u32 v141, v142, s79
	v_sub_u32_e32 v146, v80, v141
	v_ashrrev_i32_e32 v141, 31, v140
	v_lshlrev_b64 v[140:141], s81, v[140:141]
	v_lshl_add_u64 v[140:141], v[140:141], 3, s[4:5]
	v_ashrrev_i32_e32 v143, 31, v142
	v_ashrrev_i32_e32 v147, 31, v146
	v_lshl_add_u64 v[148:149], v[142:143], 3, v[140:141]
	v_lshlrev_b64 v[140:141], s18, v[146:147]
	v_lshl_add_u64 v[140:141], v[140:141], 3, v[148:149]
	s_nop 1
	global_load_dwordx2 v[172:173], v[140:141], off
	v_add_u32_e32 v202, 1, v146
	v_ashrrev_i32_e32 v203, 31, v202
	v_lshlrev_b64 v[204:205], s18, v[202:203]
	v_lshl_add_u64 v[202:203], v[204:205], 3, v[148:149]
	global_load_dwordx2 v[174:175], v[202:203], off
	v_add_u32_e32 v202, 3, v146
	v_ashrrev_i32_e32 v203, 31, v202
	v_lshlrev_b64 v[204:205], s18, v[202:203]
	v_lshl_add_u64 v[202:203], v[204:205], 3, v[148:149]
	global_load_dwordx2 v[190:191], v[202:203], off
	v_add_u32_e32 v202, 5, v146
	v_ashrrev_i32_e32 v203, 31, v202
	v_lshlrev_b64 v[204:205], s18, v[202:203]
	v_lshl_add_u64 v[202:203], v[204:205], 3, v[148:149]
	global_load_dwordx2 v[192:193], v[202:203], off
	v_add_u32_e32 v202, 2, v146
	v_ashrrev_i32_e32 v203, 31, v202
	v_lshlrev_b64 v[204:205], s18, v[202:203]
	v_lshl_add_u64 v[202:203], v[204:205], 3, v[148:149]
	global_load_dwordx2 v[194:195], v[202:203], off
	v_add_u32_e32 v202, 4, v146
	v_ashrrev_i32_e32 v203, 31, v202
	v_lshlrev_b64 v[204:205], s18, v[202:203]
	v_lshl_add_u64 v[202:203], v[204:205], 3, v[148:149]
	global_load_dwordx2 v[196:197], v[202:203], off
	v_add_u32_e32 v202, 6, v146
	v_ashrrev_i32_e32 v203, 31, v202
	v_lshlrev_b64 v[204:205], s18, v[202:203]
	v_lshl_add_u64 v[202:203], v[204:205], 3, v[148:149]
	global_load_dwordx2 v[198:199], v[202:203], off
	v_add_u32_e32 v202, 7, v146
	v_ashrrev_i32_e32 v203, 31, v202
	v_lshlrev_b64 v[204:205], s18, v[202:203]
	v_lshl_add_u64 v[202:203], v[204:205], 3, v[148:149]
	global_load_dwordx2 v[200:201], v[202:203], off
	s_nop 0
	v_add_u32_e32 v142, 1, v146
	v_ashrrev_i32_e32 v143, 31, v142
	v_lshlrev_b64 v[142:143], s18, v[142:143]
	v_lshl_add_u64 v[142:143], v[142:143], 3, v[148:149]
	s_nop 0
	v_add_u32_e32 v144, 3, v146
	v_ashrrev_i32_e32 v145, 31, v144
	v_lshlrev_b64 v[144:145], s18, v[144:145]
	v_lshl_add_u64 v[144:145], v[144:145], 3, v[148:149]
	s_nop 0
	v_add_u32_e32 v150, 5, v146
	v_ashrrev_i32_e32 v151, 31, v150
	v_lshlrev_b64 v[150:151], s18, v[150:151]
	v_lshl_add_u64 v[150:151], v[150:151], 3, v[148:149]
	v_pk_mul_f32 v[124:125], v[124:125], v[138:139]
	s_nop 0
	v_cvt_pk_bf16_f32 v129, v124, v125
	s_waitcnt lgkmcnt(0)
	s_nop 0
	s_waitcnt vmcnt(7)
	v_ffbh_u32_e32 v80, v173
	v_min_u32_e32 v80, 32, v80
	v_lshlrev_b64 v[140:141], v80, v[172:173]
	v_min_u32_e32 v140, 1, v140
	v_or_b32_e32 v140, v141, v140
	v_cvt_f32_u32_e32 v140, v140
	v_sub_u32_e32 v80, 32, v80
	v_ldexp_f32 v140, v140, v80
	s_nop 0
	s_waitcnt vmcnt(6)
	v_ffbh_u32_e32 v80, v175
	v_min_u32_e32 v80, 32, v80
	v_lshlrev_b64 v[142:143], v80, v[174:175]
	v_min_u32_e32 v141, 1, v142
	v_or_b32_e32 v141, v143, v141
	v_cvt_f32_u32_e32 v141, v141
	v_sub_u32_e32 v80, 32, v80
	v_ldexp_f32 v141, v141, v80
	v_pk_mul_f32 v[140:141], v[140:141], s[60:61] op_sel_hi:[1,0]
	s_nop 0
	v_pk_fma_f32 v[140:141], v[140:141], s[26:27], v[136:137] op_sel_hi:[1,0,0]
	s_nop 0
	v_mul_f32_e32 v80, 0x4b800000, v140
	v_cmp_gt_f32_e64 s[2:3], s50, v140
	v_cmp_gt_f32_e32 vcc, s50, v141
	s_nop 0
	v_cndmask_b32_e64 v80, v140, v80, s[2:3]
	v_rsq_f32_e32 v140, v80
	v_mul_f32_e32 v80, 0x4b800000, v141
	v_cndmask_b32_e32 v80, v141, v80, vcc
	v_rsq_f32_e32 v141, v80
	s_nop 0
	s_waitcnt vmcnt(5)
; __device__ __forceinline__ unsigned cvt_pk_bf16(float lo, float hi) { unsigned r; asm("v_cvt_pk_bf16_f32 %0, %1, %2" : "=v"(r) : "v"(lo), "v"(hi)); return r; }
; __device__ __forceinline__ float rinv_of(unsigned long long ss) { return rsqrtf((float)ss * (1.f / 16777216.f) * (1.f / DM) + 1e-6f); }
;   __device__ __forceinline__ void operator()(const f32x4 (&acc)[2][2][4][2], const Unit& u, const EpiCtx& x_, int wr, int wc, int fr, int fq) const {
;     ...
;         for (int i = 0; i < 8; ++i) cs[bj][i >> 2][i & 3] = rinv_of(sp[(size_t)(m0 + i) << lg]);
;       } }
; #pragma unroll
;     for (int ai = 0; ai < 2; ++ai)
; #pragma unroll
;       for (int m = 0; m < 4; ++m) {
;         const int row = u.r0 + ai * 128 + wr * 64 + m * 16 + fr, hh = (x_.p0 >> 1) * 16 + (row >> 7), d = row & 127;
; #pragma unroll
;         for (int bj = 0; bj < 2; ++bj) {
;           const int col = u.c0 + wc * 64 + bj * 32 + 8 * fq;
;           const f32x4 v0 = acc[ai][bj][m][0] * cs[bj][0], v1 = acc[ai][bj][m][1] * cs[bj][1];
;           uint4 o; o.x = cvt_pk_bf16(v0[0], v0[1]); o.y = cvt_pk_bf16(v0[2], v0[3]); o.z = cvt_pk_bf16(v1[0], v1[1]); o.w = cvt_pk_bf16(v1[2], v1[3]);
;           *(uint4*)((bf16_t*)u.C + (((size_t)hh * (TS / 32) + (col >> 5)) * 128 + d) * 32 + (col & 31)) = o;
	v_ffbh_u32_e32 v80, v191
	v_min_u32_e32 v80, 32, v80
	v_lshlrev_b64 v[144:145], v80, v[190:191]
	v_pk_mul_f32 v[142:143], v[140:141], s[64:65] op_sel_hi:[1,0]
	v_min_u32_e32 v144, 1, v144
	v_cndmask_b32_e64 v140, v140, v142, s[2:3]
	v_add_u32_e32 v142, 2, v146
	v_cndmask_b32_e32 v141, v141, v143, vcc
	v_ashrrev_i32_e32 v143, 31, v142
	v_lshlrev_b64 v[142:143], s18, v[142:143]
	v_lshl_add_u64 v[142:143], v[142:143], 3, v[148:149]
	s_nop 0
	v_or_b32_e32 v144, v145, v144
	v_cvt_f32_u32_e32 v144, v144
	v_sub_u32_e32 v80, 32, v80
	v_pk_mul_f32 v[118:119], v[118:119], v[140:141]
	v_pk_mul_f32 v[102:103], v[102:103], v[140:141]
	v_ldexp_f32 v145, v144, v80
	v_pk_mul_f32 v[86:87], v[86:87], v[140:141]
	v_pk_mul_f32 v[68:69], v[68:69], v[140:141]
	v_pk_mul_f32 v[52:53], v[52:53], v[140:141]
	v_pk_mul_f32 v[36:37], v[36:37], v[140:141]
	v_pk_mul_f32 v[20:21], v[20:21], v[140:141]
	v_pk_mul_f32 v[4:5], v[4:5], v[140:141]
	s_waitcnt lgkmcnt(0)
	s_nop 0
	s_waitcnt vmcnt(3)
	v_ffbh_u32_e32 v80, v195
	v_min_u32_e32 v80, 32, v80
	v_lshlrev_b64 v[142:143], v80, v[194:195]
	v_min_u32_e32 v142, 1, v142
	v_or_b32_e32 v142, v143, v142
	v_cvt_f32_u32_e32 v142, v142
	v_sub_u32_e32 v80, 32, v80
	v_ldexp_f32 v144, v142, v80
	v_pk_mul_f32 v[142:143], v[144:145], s[60:61] op_sel_hi:[1,0]
	s_nop 0
	v_pk_fma_f32 v[142:143], v[142:143], s[26:27], v[136:137] op_sel_hi:[1,0,0]
	s_nop 0
	v_mul_f32_e32 v80, 0x4b800000, v142
	v_cmp_gt_f32_e64 s[2:3], s50, v142
	v_cmp_gt_f32_e32 vcc, s50, v143
	s_nop 0
	v_cndmask_b32_e64 v80, v142, v80, s[2:3]
	v_rsq_f32_e32 v142, v80
	v_mul_f32_e32 v80, 0x4b800000, v143
	v_cndmask_b32_e32 v80, v143, v80, vcc
	v_rsq_f32_e32 v143, v80
	v_ffbh_u32_e32 v80, v193
	v_min_u32_e32 v80, 32, v80
	v_lshlrev_b64 v[150:151], v80, v[192:193]
	v_pk_mul_f32 v[144:145], v[142:143], s[64:65] op_sel_hi:[1,0]
	v_min_u32_e32 v147, 1, v150
	v_cndmask_b32_e64 v142, v142, v144, s[2:3]
	v_add_u32_e32 v144, 4, v146
	v_cndmask_b32_e32 v143, v143, v145, vcc
	v_ashrrev_i32_e32 v145, 31, v144
	v_lshlrev_b64 v[144:145], s18, v[144:145]
	v_lshl_add_u64 v[144:145], v[144:145], 3, v[148:149]
	s_nop 0
	v_or_b32_e32 v147, v151, v147
	v_cvt_f32_u32_e32 v147, v147
	v_sub_u32_e32 v80, 32, v80
	v_pk_mul_f32 v[120:121], v[120:121], v[142:143]
	v_pk_mul_f32 v[104:105], v[104:105], v[142:143]
	v_ldexp_f32 v151, v147, v80
	v_pk_mul_f32 v[88:89], v[88:89], v[142:143]
	v_pk_mul_f32 v[70:71], v[70:71], v[142:143]
	v_pk_mul_f32 v[54:55], v[54:55], v[142:143]
	v_pk_mul_f32 v[38:39], v[38:39], v[142:143]
	v_pk_mul_f32 v[22:23], v[22:23], v[142:143]
	v_pk_mul_f32 v[6:7], v[6:7], v[142:143]
	s_waitcnt lgkmcnt(0)
	s_nop 0
	s_waitcnt vmcnt(2)
	v_ffbh_u32_e32 v80, v197
	v_min_u32_e32 v80, 32, v80
	v_lshlrev_b64 v[144:145], v80, v[196:197]
	v_min_u32_e32 v144, 1, v144
	v_or_b32_e32 v144, v145, v144
	v_cvt_f32_u32_e32 v144, v144
	v_sub_u32_e32 v80, 32, v80
	v_ldexp_f32 v150, v144, v80
	v_pk_mul_f32 v[144:145], v[150:151], s[60:61] op_sel_hi:[1,0]
	s_nop 0
	v_pk_fma_f32 v[144:145], v[144:145], s[26:27], v[136:137] op_sel_hi:[1,0,0]
	s_nop 0
	v_mul_f32_e32 v80, 0x4b800000, v144
	v_cmp_gt_f32_e64 s[2:3], s50, v144
	v_cmp_gt_f32_e32 vcc, s50, v145
	s_nop 0
	v_cndmask_b32_e64 v80, v144, v80, s[2:3]
	v_rsq_f32_e32 v144, v80
	v_mul_f32_e32 v80, 0x4b800000, v145
	v_cndmask_b32_e32 v80, v145, v80, vcc
	v_rsq_f32_e32 v145, v80
	s_nop 0
	v_pk_mul_f32 v[150:151], v[144:145], s[64:65] op_sel_hi:[1,0]
	s_nop 0
	v_cndmask_b32_e64 v144, v144, v150, s[2:3]
	v_add_u32_e32 v150, 6, v146
	v_add_u32_e32 v146, 7, v146
	v_cndmask_b32_e32 v145, v145, v151, vcc
	v_ashrrev_i32_e32 v151, 31, v150
	v_ashrrev_i32_e32 v147, 31, v146
	v_lshlrev_b64 v[150:151], s18, v[150:151]
	v_lshlrev_b64 v[146:147], s18, v[146:147]
	v_lshl_add_u64 v[150:151], v[150:151], 3, v[148:149]
	v_lshl_add_u64 v[146:147], v[146:147], 3, v[148:149]
	s_nop 0
	v_pk_mul_f32 v[114:115], v[114:115], v[144:145]
	s_nop 0
	s_waitcnt lgkmcnt(0)
	s_nop 0
	s_waitcnt vmcnt(0)
	v_ffbh_u32_e32 v80, v201
	v_min_u32_e32 v80, 32, v80
	v_lshlrev_b64 v[146:147], v80, v[200:201]
	v_min_u32_e32 v146, 1, v146
	v_or_b32_e32 v146, v147, v146
	v_cvt_f32_u32_e32 v146, v146
	v_sub_u32_e32 v80, 32, v80
	v_ldexp_f32 v147, v146, v80
	v_ffbh_u32_e32 v80, v199
	v_min_u32_e32 v80, 32, v80
	v_lshlrev_b64 v[148:149], v80, v[198:199]
	v_min_u32_e32 v146, 1, v148
	v_or_b32_e32 v146, v149, v146
	v_cvt_f32_u32_e32 v146, v146
	v_sub_u32_e32 v80, 32, v80
	v_ldexp_f32 v146, v146, v80
	v_pk_mul_f32 v[146:147], v[146:147], s[60:61] op_sel_hi:[1,0]
	s_nop 0
	v_pk_fma_f32 v[136:137], v[146:147], s[26:27], v[136:137] op_sel_hi:[1,0,0]
	s_nop 0
	v_mul_f32_e32 v80, 0x4b800000, v136
	v_cmp_gt_f32_e64 s[2:3], s50, v136
	v_cmp_gt_f32_e32 vcc, s50, v137
	s_nop 0
	v_cndmask_b32_e64 v80, v136, v80, s[2:3]
	v_rsq_f32_e32 v136, v80
	v_mul_f32_e32 v80, 0x4b800000, v137
	v_cndmask_b32_e32 v80, v137, v80, vcc
	v_rsq_f32_e32 v137, v80
	v_add_u32_e32 v80, s75, v157
	v_pk_mul_f32 v[146:147], v[136:137], s[64:65] op_sel_hi:[1,0]
	s_nop 0
	v_cndmask_b32_e64 v136, v136, v146, s[2:3]
	v_ashrrev_i32_e32 v146, 7, v80
	v_add_u32_e32 v146, s82, v146
	v_cndmask_b32_e32 v137, v137, v147, vcc
	v_ashrrev_i32_e32 v147, 31, v146
	v_lshlrev_b64 v[146:147], 22, v[146:147]
	v_lshlrev_b32_e32 v80, 6, v80
	v_and_b32_e32 v80, 0x1fc0, v80
	v_lshl_add_u64 v[124:125], v[122:123], 0, v[146:147]
	v_lshl_add_u64 v[148:149], v[124:125], 0, v[80:81]
	v_and_b32_e32 v124, 31, v171
	v_lshlrev_b32_e32 v124, 1, v124
	v_mov_b32_e32 v125, v81
	v_lshl_add_u64 v[148:149], v[148:149], 0, v[124:125]
	global_store_dwordx4 v[148:149], v[126:129], off nt
	s_mov_b64 s[2:3], s[8:9]
	s_nop 0
	v_add_u32_e32 v128, s97, v160
	v_pk_mul_f32 v[126:127], v[116:117], v[136:137]
; __device__ __forceinline__ unsigned cvt_pk_bf16(float lo, float hi) { unsigned r; asm("v_cvt_pk_bf16_f32 %0, %1, %2" : "=v"(r) : "v"(lo), "v"(hi)); return r; }
;   __device__ __forceinline__ void operator()(const f32x4 (&acc)[2][2][4][2], const Unit& u, const EpiCtx& x_, int wr, int wc, int fr, int fq) const {
;     ...
; #pragma unroll
;     for (int ai = 0; ai < 2; ++ai)
; #pragma unroll
;       for (int m = 0; m < 4; ++m) {
;         const int row = u.r0 + ai * 128 + wr * 64 + m * 16 + fr, hh = (x_.p0 >> 1) * 16 + (row >> 7), d = row & 127;
; #pragma unroll
;         for (int bj = 0; bj < 2; ++bj) {
;           const int col = u.c0 + wc * 64 + bj * 32 + 8 * fq;
;           const f32x4 v0 = acc[ai][bj][m][0] * cs[bj][0], v1 = acc[ai][bj][m][1] * cs[bj][1];
;           uint4 o; o.x = cvt_pk_bf16(v0[0], v0[1]); o.y = cvt_pk_bf16(v0[2], v0[3]); o.z = cvt_pk_bf16(v1[0], v1[1]); o.w = cvt_pk_bf16(v1[2], v1[3]);
;           *(uint4*)((bf16_t*)u.C + (((size_t)hh * (TS / 32) + (col >> 5)) * 128 + d) * 32 + (col & 31)) = o;
;         }
;       }
	v_cvt_pk_bf16_f32 v116, v118, v119
	v_cvt_pk_bf16_f32 v118, v114, v115
	v_ashrrev_i32_e32 v114, 5, v128
	v_ashrrev_i32_e32 v115, 31, v114
	v_lshlrev_b64 v[114:115], 13, v[114:115]
	v_lshl_add_u64 v[114:115], s[94:95], 0, v[114:115]
	v_cvt_pk_bf16_f32 v117, v120, v121
	v_lshl_add_u64 v[120:121], v[114:115], 0, v[146:147]
	v_lshl_add_u64 v[120:121], v[120:121], 0, v[80:81]
	v_and_b32_e32 v80, 31, v128
	v_lshlrev_b32_e32 v80, 1, v80
	v_lshl_add_u64 v[120:121], v[120:121], 0, v[80:81]
	v_cvt_pk_bf16_f32 v119, v126, v127
	global_store_dwordx4 v[120:121], v[116:119], off nt
	v_add_u32_e32 v120, s75, v161
	s_mov_b64 s[94:95], s[40:41]
	v_ashrrev_i32_e32 v116, 7, v120
	v_add_u32_e32 v116, s82, v116
	v_ashrrev_i32_e32 v117, 31, v116
	v_pk_mul_f32 v[118:119], v[108:109], v[138:139]
	v_pk_mul_f32 v[108:109], v[106:107], v[134:135]
	v_cvt_pk_bf16_f32 v106, v110, v111
	v_cvt_pk_bf16_f32 v107, v112, v113
	v_lshlrev_b64 v[110:111], 22, v[116:117]
	v_lshlrev_b32_e32 v112, 6, v120
	v_and_b32_e32 v112, 0x1fc0, v112
	v_mov_b32_e32 v113, v81
	v_lshl_add_u64 v[116:117], v[122:123], 0, v[110:111]
	v_lshl_add_u64 v[116:117], v[116:117], 0, v[112:113]
	v_lshl_add_u64 v[116:117], v[116:117], 0, v[124:125]
	v_cvt_pk_bf16_f32 v108, v108, v109
	v_cvt_pk_bf16_f32 v109, v118, v119
	global_store_dwordx4 v[116:117], v[106:109], off nt
	s_mov_b32 s97, s42
	s_nop 0
	v_pk_mul_f32 v[106:107], v[100:101], v[136:137]
	v_pk_mul_f32 v[100:101], v[98:99], v[144:145]
	v_cvt_pk_bf16_f32 v98, v102, v103
	v_lshl_add_u64 v[102:103], v[114:115], 0, v[110:111]
	v_lshl_add_u64 v[102:103], v[102:103], 0, v[112:113]
	v_lshl_add_u64 v[102:103], v[102:103], 0, v[80:81]
	v_cvt_pk_bf16_f32 v99, v104, v105
	v_cvt_pk_bf16_f32 v100, v100, v101
	v_cvt_pk_bf16_f32 v101, v106, v107
	global_store_dwordx4 v[102:103], v[98:101], off nt
	v_add_u32_e32 v102, s75, v163
	s_nop 0
	v_ashrrev_i32_e32 v98, 7, v102
	v_add_u32_e32 v98, s82, v98
	v_ashrrev_i32_e32 v99, 31, v98
	v_pk_mul_f32 v[100:101], v[92:93], v[138:139]
	v_pk_mul_f32 v[92:93], v[90:91], v[134:135]
	v_cvt_pk_bf16_f32 v90, v94, v95
	v_cvt_pk_bf16_f32 v91, v96, v97
	v_lshlrev_b64 v[94:95], 22, v[98:99]
	v_lshlrev_b32_e32 v96, 6, v102
	v_and_b32_e32 v96, 0x1fc0, v96
	v_mov_b32_e32 v97, v81
	v_lshl_add_u64 v[98:99], v[122:123], 0, v[94:95]
	v_lshl_add_u64 v[98:99], v[98:99], 0, v[96:97]
	v_lshl_add_u64 v[98:99], v[98:99], 0, v[124:125]
	v_cvt_pk_bf16_f32 v92, v92, v93
	v_cvt_pk_bf16_f32 v93, v100, v101
	global_store_dwordx4 v[98:99], v[90:93], off nt
	s_nop 1
	v_pk_mul_f32 v[90:91], v[84:85], v[136:137]
	v_pk_mul_f32 v[84:85], v[82:83], v[144:145]
	v_cvt_pk_bf16_f32 v82, v86, v87
	v_lshl_add_u64 v[86:87], v[114:115], 0, v[94:95]
	v_lshl_add_u64 v[86:87], v[86:87], 0, v[96:97]
	v_lshl_add_u64 v[86:87], v[86:87], 0, v[80:81]
	v_cvt_pk_bf16_f32 v83, v88, v89
	v_cvt_pk_bf16_f32 v84, v84, v85
	v_cvt_pk_bf16_f32 v85, v90, v91
	global_store_dwordx4 v[86:87], v[82:85], off nt
	v_add_u32_e32 v86, s75, v164
	s_nop 0
	v_ashrrev_i32_e32 v82, 7, v86
	v_add_u32_e32 v82, s82, v82
	v_ashrrev_i32_e32 v83, 31, v82
	v_pk_mul_f32 v[84:85], v[74:75], v[138:139]
	v_pk_mul_f32 v[74:75], v[72:73], v[134:135]
	v_cvt_pk_bf16_f32 v72, v76, v77
	v_cvt_pk_bf16_f32 v73, v78, v79
	v_lshlrev_b64 v[76:77], 22, v[82:83]
	v_lshlrev_b32_e32 v78, 6, v86
	v_and_b32_e32 v78, 0x1fc0, v78
	v_mov_b32_e32 v79, v81
	v_lshl_add_u64 v[82:83], v[122:123], 0, v[76:77]
	v_lshl_add_u64 v[82:83], v[82:83], 0, v[78:79]
	v_lshl_add_u64 v[82:83], v[82:83], 0, v[124:125]
	v_cvt_pk_bf16_f32 v74, v74, v75
	v_cvt_pk_bf16_f32 v75, v84, v85
	global_store_dwordx4 v[82:83], v[72:75], off nt
	s_nop 1
	v_pk_mul_f32 v[72:73], v[66:67], v[136:137]
	v_pk_mul_f32 v[66:67], v[64:65], v[144:145]
	v_cvt_pk_bf16_f32 v64, v68, v69
	v_lshl_add_u64 v[68:69], v[114:115], 0, v[76:77]
	v_lshl_add_u64 v[68:69], v[68:69], 0, v[78:79]
	v_lshl_add_u64 v[68:69], v[68:69], 0, v[80:81]
	v_cvt_pk_bf16_f32 v65, v70, v71
	v_cvt_pk_bf16_f32 v66, v66, v67
	v_cvt_pk_bf16_f32 v67, v72, v73
	global_store_dwordx4 v[68:69], v[64:67], off nt
	v_add_u32_e32 v68, s75, v165
	s_nop 0
	v_ashrrev_i32_e32 v64, 7, v68
	v_add_u32_e32 v64, s82, v64
	v_ashrrev_i32_e32 v65, 31, v64
	v_pk_mul_f32 v[66:67], v[58:59], v[138:139]
	v_pk_mul_f32 v[58:59], v[56:57], v[134:135]
	v_cvt_pk_bf16_f32 v56, v60, v61
; __device__ __forceinline__ unsigned cvt_pk_bf16(float lo, float hi) { unsigned r; asm("v_cvt_pk_bf16_f32 %0, %1, %2" : "=v"(r) : "v"(lo), "v"(hi)); return r; }
;   __device__ __forceinline__ void operator()(const f32x4 (&acc)[2][2][4][2], const Unit& u, const EpiCtx& x_, int wr, int wc, int fr, int fq) const {
;     ...
; #pragma unroll
;     for (int ai = 0; ai < 2; ++ai)
; #pragma unroll
;       for (int m = 0; m < 4; ++m) {
;         const int row = u.r0 + ai * 128 + wr * 64 + m * 16 + fr, hh = (x_.p0 >> 1) * 16 + (row >> 7), d = row & 127;
; #pragma unroll
;         for (int bj = 0; bj < 2; ++bj) {
;           const int col = u.c0 + wc * 64 + bj * 32 + 8 * fq;
;           const f32x4 v0 = acc[ai][bj][m][0] * cs[bj][0], v1 = acc[ai][bj][m][1] * cs[bj][1];
;           uint4 o; o.x = cvt_pk_bf16(v0[0], v0[1]); o.y = cvt_pk_bf16(v0[2], v0[3]); o.z = cvt_pk_bf16(v1[0], v1[1]); o.w = cvt_pk_bf16(v1[2], v1[3]);
;           *(uint4*)((bf16_t*)u.C + (((size_t)hh * (TS / 32) + (col >> 5)) * 128 + d) * 32 + (col & 31)) = o;
;         }
;       }
	v_cvt_pk_bf16_f32 v57, v62, v63
	v_lshlrev_b64 v[60:61], 22, v[64:65]
	v_lshlrev_b32_e32 v62, 6, v68
	v_and_b32_e32 v62, 0x1fc0, v62
	v_mov_b32_e32 v63, v81
	v_lshl_add_u64 v[64:65], v[122:123], 0, v[60:61]
	v_lshl_add_u64 v[64:65], v[64:65], 0, v[62:63]
	v_lshl_add_u64 v[64:65], v[64:65], 0, v[124:125]
	v_cvt_pk_bf16_f32 v58, v58, v59
	v_cvt_pk_bf16_f32 v59, v66, v67
	global_store_dwordx4 v[64:65], v[56:59], off nt
	s_nop 1
	v_pk_mul_f32 v[56:57], v[50:51], v[136:137]
	v_pk_mul_f32 v[50:51], v[48:49], v[144:145]
	v_cvt_pk_bf16_f32 v48, v52, v53
	v_lshl_add_u64 v[52:53], v[114:115], 0, v[60:61]
	v_lshl_add_u64 v[52:53], v[52:53], 0, v[62:63]
	v_lshl_add_u64 v[52:53], v[52:53], 0, v[80:81]
	v_cvt_pk_bf16_f32 v49, v54, v55
	v_cvt_pk_bf16_f32 v50, v50, v51
	v_cvt_pk_bf16_f32 v51, v56, v57
	global_store_dwordx4 v[52:53], v[48:51], off nt
	v_add_u32_e32 v52, s75, v166
	s_nop 0
	v_ashrrev_i32_e32 v48, 7, v52
	v_add_u32_e32 v48, s82, v48
	v_ashrrev_i32_e32 v49, 31, v48
	v_pk_mul_f32 v[50:51], v[42:43], v[138:139]
	v_pk_mul_f32 v[42:43], v[40:41], v[134:135]
	v_cvt_pk_bf16_f32 v40, v44, v45
	v_cvt_pk_bf16_f32 v41, v46, v47
	v_lshlrev_b64 v[44:45], 22, v[48:49]
	v_lshlrev_b32_e32 v46, 6, v52
	v_and_b32_e32 v46, 0x1fc0, v46
	v_mov_b32_e32 v47, v81
	v_lshl_add_u64 v[48:49], v[122:123], 0, v[44:45]
	v_lshl_add_u64 v[48:49], v[48:49], 0, v[46:47]
	v_lshl_add_u64 v[48:49], v[48:49], 0, v[124:125]
	v_cvt_pk_bf16_f32 v42, v42, v43
	v_cvt_pk_bf16_f32 v43, v50, v51
	global_store_dwordx4 v[48:49], v[40:43], off nt
	s_nop 1
	v_pk_mul_f32 v[40:41], v[34:35], v[136:137]
	v_pk_mul_f32 v[34:35], v[32:33], v[144:145]
	v_cvt_pk_bf16_f32 v32, v36, v37
	v_lshl_add_u64 v[36:37], v[114:115], 0, v[44:45]
	v_lshl_add_u64 v[36:37], v[36:37], 0, v[46:47]
	v_lshl_add_u64 v[36:37], v[36:37], 0, v[80:81]
	v_cvt_pk_bf16_f32 v33, v38, v39
	v_cvt_pk_bf16_f32 v34, v34, v35
	v_cvt_pk_bf16_f32 v35, v40, v41
	global_store_dwordx4 v[36:37], v[32:35], off nt
	v_add_u32_e32 v36, s75, v167
	s_nop 0
	v_ashrrev_i32_e32 v32, 7, v36
	v_add_u32_e32 v32, s82, v32
	v_ashrrev_i32_e32 v33, 31, v32
	v_pk_mul_f32 v[34:35], v[26:27], v[138:139]
	v_pk_mul_f32 v[26:27], v[24:25], v[134:135]
	v_cvt_pk_bf16_f32 v24, v28, v29
	v_cvt_pk_bf16_f32 v25, v30, v31
	v_lshlrev_b64 v[28:29], 22, v[32:33]
	v_lshlrev_b32_e32 v30, 6, v36
	v_and_b32_e32 v30, 0x1fc0, v30
	v_mov_b32_e32 v31, v81
	v_lshl_add_u64 v[32:33], v[122:123], 0, v[28:29]
	v_lshl_add_u64 v[32:33], v[32:33], 0, v[30:31]
	v_lshl_add_u64 v[32:33], v[32:33], 0, v[124:125]
	v_cvt_pk_bf16_f32 v26, v26, v27
	v_cvt_pk_bf16_f32 v27, v34, v35
	global_store_dwordx4 v[32:33], v[24:27], off nt
	s_nop 1
	v_pk_mul_f32 v[24:25], v[18:19], v[136:137]
	v_pk_mul_f32 v[18:19], v[16:17], v[144:145]
	v_cvt_pk_bf16_f32 v16, v20, v21
	v_lshl_add_u64 v[20:21], v[114:115], 0, v[28:29]
	v_lshl_add_u64 v[20:21], v[20:21], 0, v[30:31]
	v_lshl_add_u64 v[20:21], v[20:21], 0, v[80:81]
	v_cvt_pk_bf16_f32 v17, v22, v23
	v_cvt_pk_bf16_f32 v18, v18, v19
	v_cvt_pk_bf16_f32 v19, v24, v25
	global_store_dwordx4 v[20:21], v[16:19], off nt
	v_add_u32_e32 v20, s75, v168
	s_mov_b32 s75, s0
	v_ashrrev_i32_e32 v16, 7, v20
	v_add_u32_e32 v16, s82, v16
	v_ashrrev_i32_e32 v17, 31, v16
	v_pk_mul_f32 v[18:19], v[10:11], v[138:139]
	v_pk_mul_f32 v[10:11], v[8:9], v[134:135]
	v_cvt_pk_bf16_f32 v8, v12, v13
	v_cvt_pk_bf16_f32 v9, v14, v15
	v_lshlrev_b64 v[12:13], 22, v[16:17]
	v_lshlrev_b32_e32 v14, 6, v20
	v_and_b32_e32 v14, 0x1fc0, v14
	v_mov_b32_e32 v15, v81
	v_lshl_add_u64 v[16:17], v[122:123], 0, v[12:13]
	v_lshl_add_u64 v[16:17], v[16:17], 0, v[14:15]
	v_lshl_add_u64 v[16:17], v[16:17], 0, v[124:125]
	v_cvt_pk_bf16_f32 v10, v10, v11
	v_cvt_pk_bf16_f32 v11, v18, v19
	global_store_dwordx4 v[16:17], v[8:11], off nt
	s_nop 1
	v_pk_mul_f32 v[8:9], v[2:3], v[136:137]
	v_pk_mul_f32 v[2:3], v[0:1], v[144:145]
	v_cvt_pk_bf16_f32 v0, v4, v5
	v_lshl_add_u64 v[4:5], v[114:115], 0, v[12:13]
	v_lshl_add_u64 v[4:5], v[4:5], 0, v[14:15]
	v_lshl_add_u64 v[4:5], v[4:5], 0, v[80:81]
	v_cvt_pk_bf16_f32 v1, v6, v7
	v_cvt_pk_bf16_f32 v2, v2, v3
	v_cvt_pk_bf16_f32 v3, v8, v9
	global_store_dwordx4 v[4:5], v[0:3], off nt
	s_cbranch_scc0 .LBB0_650
	s_waitcnt vmcnt(0)
	s_cmpk_gt_u32 s19, 0xff
	s_mov_b32 s86, 0x7f800000
	s_brev_b32 s82, 1
	s_cbranch_scc1 .LBB0_632
	s_barrier
	s_branch .LBB0_632

; #define G_STAGE(bufoff, gbase, voff) do { _Pragma("unroll") for (int _i = 0; _i < 2; ++_i) { unsigned _vo = (voff)[_i]; asm volatile("" : "+v"(_vo));   \
;     __builtin_amdgcn_global_load_lds((const unsigned*)((const char*)(gbase) + _vo), (LAS unsigned*)(lds + (bufoff) + ldsw + _i * 8192), 16, 0, 0); } } while (0)
; #define G_LDA(dst, b, h) do { _Pragma("unroll") for (int m = 0; m < 4; ++m) _Pragma("unroll") for (int k = 0; k < 2; ++k) dst[m][k] = *(const LAS bf16x8*)(lds + G_SA(b, h) + aoff + m * 2048 + k * 1024); } while (0)
; #define G_LDB(dst, b, h) do { _Pragma("unroll") for (int n = 0; n < 2; ++n) _Pragma("unroll") for (int k = 0; k < 2; ++k) dst[n][k] = *(const LAS bf16x8*)(lds + G_SB(b, h) + boff + n * 2048 + k * 1024); } while (0)
; #define G_MMA(ai, bj, At, Bt) do { __builtin_amdgcn_s_setprio(1); _Pragma("unroll") for (int m = 0; m < 4; ++m) _Pragma("unroll") for (int n = 0; n < 2; ++n) _Pragma("unroll") for (int k = 0; k < 2; ++k) \
;     acc[ai][bj][m][n] = __builtin_amdgcn_mfma_f32_16x16x32_bf16(Bt[n][k], At[m][k], acc[ai][bj][m][n], 0, 0, 0); __builtin_amdgcn_s_setprio(0); } while (0)
; template <class Epi>
; __device__ __forceinline__ void gemm_phase(LAS unsigned char* lds, const int K, const unsigned lda_b, const unsigned ldb_b, const Map& M, const Epi& E) {
;     ...
;     for (int t = 0; t < nt; t += 2) {
;       const bool last = (t == nt - 2);
;       const char* a1h1 = cur.a0 + a_h + (size_t)(t + 1) * kstep;
;       const char* a2h0 = last ? nxt.a0 : cur.a0 + (size_t)(t + 2) * kstep; const char* a2h1 = a2h0 + a_h;
;       const char* b2h0 = last ? nxt.b0 : cur.b0 + (size_t)(t + 2) * kstep; const char* b2h1 = last ? nxt.b1 : cur.b1 + (size_t)(t + 2) * kstep;
;       G_LDB(B0, 0, 0); G_SCHED; G_LDA(At, 0, 0); G_STAGE(G_SA(1, 1), a1h1, voffA);
;       G_WAIT_L(8); G_BAR; G_WAIT_L(0); G_MMA(0, 0, At, B0); G_BAR; G_SCHED;
;       G_LDB(B1, 0, 1); G_STAGE(G_SB(0, 0), b2h0, voffB);
;       G_BAR; G_WAIT_L(0); G_MMA(0, 1, At, B1); G_BAR;
;       G_LDA(At, 0, 1); G_STAGE(G_SA(0, 0), a2h0, voffA);
;       G_BAR; G_WAIT_L(0); G_MMA(1, 0, At, B0); G_BAR; G_SCHED;
;       G_STAGE(G_SB(0, 1), b2h1, voffB);
;       G_WAIT_V(6); G_BAR; G_MMA(1, 1, At, B1); G_BAR;
;       G_LDB(B0, 1, 0); G_SCHED; G_LDA(At, 1, 0); G_STAGE(G_SA(0, 1), a2h1, voffA);
;       G_WAIT_L(8); G_BAR; G_WAIT_L(0); G_MMA(0, 0, At, B0); G_BAR; G_SCHED;
.LBB0_844:
	s_add_u32 s22, s2, 0xfff80080
	s_addc_u32 s35, s3, -1
	s_add_u32 s38, s30, 0xfffe0000
	s_addc_u32 s39, s31, -1
	s_add_i32 s75, 0, 0x10000
	v_add_u32_e32 v80, s75, v139
	ds_read_b128 v[142:145], v80
	ds_read_b128 v[146:149], v80 offset:1024
	ds_read_b128 v[150:153], v80 offset:2048
	ds_read_b128 v[154:157], v80 offset:3072
	s_cmp_eq_u32 s34, 28
	s_cselect_b32 s43, s5, s35
	s_cselect_b32 s42, s4, s22
	s_cselect_b32 s45, s7, s39
	s_cselect_b32 s44, s6, s38
	v_mov_b32_e32 v80, v134
	s_cselect_b32 s39, s29, s31
	s_cselect_b32 s38, s28, s30
	s_add_u32 s68, s42, 0x80000
	ds_read_b128 v[158:161], v141
	ds_read_b128 v[162:165], v141 offset:1024
	ds_read_b128 v[166:169], v141 offset:2048
	ds_read_b128 v[170:173], v141 offset:3072
	ds_read_b128 v[174:177], v141 offset:4096
	ds_read_b128 v[190:193], v141 offset:5120
	ds_read_b128 v[194:197], v141 offset:6144
	ds_read_b128 v[198:201], v141 offset:7168
	s_addc_u32 s69, s43, 0
	s_add_i32 m0, s18, 0xc000
	s_nop 0
	global_load_lds_dwordx4 v80, s[2:3]
	v_mov_b32_e32 v80, v136
	s_add_i32 m0, s18, 0xe000
	s_nop 0
	global_load_lds_dwordx4 v80, s[2:3]
	s_waitcnt lgkmcnt(8)
	s_barrier
	s_waitcnt lgkmcnt(0)
	s_setprio 1
	s_waitcnt lgkmcnt(0)
	v_mfma_f32_16x16x32_bf16 v[126:129], v[142:145], v[158:161], v[126:129]
	v_mfma_f32_16x16x32_bf16 v[122:125], v[150:153], v[158:161], v[122:125]
	v_mfma_f32_16x16x32_bf16 v[110:113], v[142:145], v[166:169], v[110:113]
	v_mfma_f32_16x16x32_bf16 v[106:109], v[150:153], v[166:169], v[106:109]
	v_mfma_f32_16x16x32_bf16 v[94:97], v[142:145], v[174:177], v[94:97]
	v_mfma_f32_16x16x32_bf16 v[90:93], v[150:153], v[174:177], v[90:93]
	v_mfma_f32_16x16x32_bf16 v[76:79], v[142:145], v[194:197], v[76:79]
	v_mfma_f32_16x16x32_bf16 v[72:75], v[150:153], v[194:197], v[72:75]
	v_mfma_f32_16x16x32_bf16 v[126:129], v[146:149], v[162:165], v[126:129]
	v_mfma_f32_16x16x32_bf16 v[122:125], v[154:157], v[162:165], v[122:125]
	v_mfma_f32_16x16x32_bf16 v[110:113], v[146:149], v[170:173], v[110:113]
	v_mfma_f32_16x16x32_bf16 v[106:109], v[154:157], v[170:173], v[106:109]
	v_mfma_f32_16x16x32_bf16 v[94:97], v[146:149], v[190:193], v[94:97]
	v_mfma_f32_16x16x32_bf16 v[90:93], v[154:157], v[190:193], v[90:93]
	v_mfma_f32_16x16x32_bf16 v[76:79], v[146:149], v[198:201], v[76:79]
	v_mfma_f32_16x16x32_bf16 v[72:75], v[154:157], v[198:201], v[72:75]
	s_setprio 0
	s_barrier
	s_add_i32 s22, 0, 0x14000
	v_add_u32_e32 v80, s22, v139
	ds_read_b128 v[202:205], v80
	ds_read_b128 v[206:209], v80 offset:1024
	ds_read_b128 v[210:213], v80 offset:2048
	ds_read_b128 v[214:217], v80 offset:3072
	v_mov_b32_e32 v80, v135
	s_add_i32 s35, s75, s17
	s_mov_b32 m0, s35
	s_nop 0
	global_load_lds_dwordx4 v80, s[44:45]
	v_mov_b32_e32 v80, v137
	s_add_i32 m0, s35, 0x2000
	s_nop 0
	global_load_lds_dwordx4 v80, s[44:45]
	s_barrier
	s_waitcnt lgkmcnt(0)
	s_setprio 1
	s_waitcnt lgkmcnt(0)
	v_mfma_f32_16x16x32_bf16 v[118:121], v[202:205], v[158:161], v[118:121]
	v_mfma_f32_16x16x32_bf16 v[114:117], v[210:213], v[158:161], v[114:117]
	v_mfma_f32_16x16x32_bf16 v[102:105], v[202:205], v[166:169], v[102:105]
	v_mfma_f32_16x16x32_bf16 v[98:101], v[210:213], v[166:169], v[98:101]
	v_mfma_f32_16x16x32_bf16 v[86:89], v[202:205], v[174:177], v[86:89]
	v_mfma_f32_16x16x32_bf16 v[82:85], v[210:213], v[174:177], v[82:85]
	v_mfma_f32_16x16x32_bf16 v[68:71], v[202:205], v[194:197], v[68:71]
	v_mfma_f32_16x16x32_bf16 v[64:67], v[210:213], v[194:197], v[64:67]
	v_mfma_f32_16x16x32_bf16 v[118:121], v[206:209], v[162:165], v[118:121]
	v_mfma_f32_16x16x32_bf16 v[114:117], v[214:217], v[162:165], v[114:117]
	v_mfma_f32_16x16x32_bf16 v[102:105], v[206:209], v[170:173], v[102:105]
	v_mfma_f32_16x16x32_bf16 v[98:101], v[214:217], v[170:173], v[98:101]
	v_mfma_f32_16x16x32_bf16 v[86:89], v[206:209], v[190:193], v[86:89]
	v_mfma_f32_16x16x32_bf16 v[82:85], v[214:217], v[190:193], v[82:85]
	v_mfma_f32_16x16x32_bf16 v[68:71], v[206:209], v[198:201], v[68:71]
	v_mfma_f32_16x16x32_bf16 v[64:67], v[214:217], v[198:201], v[64:67]
	s_setprio 0
	v_mov_b32_e32 v80, v134
	s_mov_b32 m0, s18
	s_barrier
	ds_read_b128 v[158:161], v141 offset:16384
	ds_read_b128 v[162:165], v141 offset:17408
	ds_read_b128 v[166:169], v141 offset:18432
	ds_read_b128 v[170:173], v141 offset:19456
	ds_read_b128 v[174:177], v141 offset:20480
	ds_read_b128 v[190:193], v141 offset:21504
	ds_read_b128 v[194:197], v141 offset:22528
	ds_read_b128 v[198:201], v141 offset:23552
	s_nop 0
	global_load_lds_dwordx4 v80, s[42:43]
	v_mov_b32_e32 v80, v136
	s_mov_b32 m0, s19
	s_nop 0
	global_load_lds_dwordx4 v80, s[42:43]
	s_barrier
	s_waitcnt lgkmcnt(0)
	s_setprio 1
	s_waitcnt lgkmcnt(0)
	v_mfma_f32_16x16x32_bf16 v[60:63], v[142:145], v[158:161], v[60:63]
	v_mfma_f32_16x16x32_bf16 v[56:59], v[150:153], v[158:161], v[56:59]
	v_mfma_f32_16x16x32_bf16 v[44:47], v[142:145], v[166:169], v[44:47]
	v_mfma_f32_16x16x32_bf16 v[40:43], v[150:153], v[166:169], v[40:43]
	v_mfma_f32_16x16x32_bf16 v[28:31], v[142:145], v[174:177], v[28:31]
	v_mfma_f32_16x16x32_bf16 v[24:27], v[150:153], v[174:177], v[24:27]
	v_mfma_f32_16x16x32_bf16 v[12:15], v[142:145], v[194:197], v[12:15]
	v_mfma_f32_16x16x32_bf16 v[8:11], v[150:153], v[194:197], v[8:11]
	v_mfma_f32_16x16x32_bf16 v[60:63], v[146:149], v[162:165], v[60:63]
	v_mfma_f32_16x16x32_bf16 v[56:59], v[154:157], v[162:165], v[56:59]
	v_mfma_f32_16x16x32_bf16 v[44:47], v[146:149], v[170:173], v[44:47]
	v_mfma_f32_16x16x32_bf16 v[40:43], v[154:157], v[170:173], v[40:43]
	v_mfma_f32_16x16x32_bf16 v[28:31], v[146:149], v[190:193], v[28:31]
	v_mfma_f32_16x16x32_bf16 v[24:27], v[154:157], v[190:193], v[24:27]
	v_mfma_f32_16x16x32_bf16 v[12:15], v[146:149], v[198:201], v[12:15]
	v_mfma_f32_16x16x32_bf16 v[8:11], v[154:157], v[198:201], v[8:11]
	s_setprio 0
	s_barrier
; #define G_STAGE(bufoff, gbase, voff) do { _Pragma("unroll") for (int _i = 0; _i < 2; ++_i) { unsigned _vo = (voff)[_i]; asm volatile("" : "+v"(_vo));   \
;     __builtin_amdgcn_global_load_lds((const unsigned*)((const char*)(gbase) + _vo), (LAS unsigned*)(lds + (bufoff) + ldsw + _i * 8192), 16, 0, 0); } } while (0)
; #define G_LDA(dst, b, h) do { _Pragma("unroll") for (int m = 0; m < 4; ++m) _Pragma("unroll") for (int k = 0; k < 2; ++k) dst[m][k] = *(const LAS bf16x8*)(lds + G_SA(b, h) + aoff + m * 2048 + k * 1024); } while (0)
; #define G_LDB(dst, b, h) do { _Pragma("unroll") for (int n = 0; n < 2; ++n) _Pragma("unroll") for (int k = 0; k < 2; ++k) dst[n][k] = *(const LAS bf16x8*)(lds + G_SB(b, h) + boff + n * 2048 + k * 1024); } while (0)
; #define G_MMA(ai, bj, At, Bt) do { __builtin_amdgcn_s_setprio(1); _Pragma("unroll") for (int m = 0; m < 4; ++m) _Pragma("unroll") for (int n = 0; n < 2; ++n) _Pragma("unroll") for (int k = 0; k < 2; ++k) \
;     acc[ai][bj][m][n] = __builtin_amdgcn_mfma_f32_16x16x32_bf16(Bt[n][k], At[m][k], acc[ai][bj][m][n], 0, 0, 0); __builtin_amdgcn_s_setprio(0); } while (0)
; #define G_WAIT_V(n) asm volatile("s_waitcnt vmcnt(" #n ")" ::: "memory")
; #define G_WAIT_L(n) asm volatile("s_waitcnt lgkmcnt(" #n ")" ::: "memory")
; template <class Epi>
; __device__ __forceinline__ void gemm_phase(LAS unsigned char* lds, const int K, const unsigned lda_b, const unsigned ldb_b, const Map& M, const Epi& E) {
;     ...
;       G_LDB(B0, 0, 0); G_SCHED; G_LDA(At, 0, 0); G_STAGE(G_SA(1, 1), a1h1, voffA);
;       G_WAIT_L(8); G_BAR; G_WAIT_L(0); G_MMA(0, 0, At, B0); G_BAR; G_SCHED;
;       G_LDB(B1, 0, 1); G_STAGE(G_SB(0, 0), b2h0, voffB);
;       G_BAR; G_WAIT_L(0); G_MMA(0, 1, At, B1); G_BAR;
;       G_LDA(At, 0, 1); G_STAGE(G_SA(0, 0), a2h0, voffA);
;       G_BAR; G_WAIT_L(0); G_MMA(1, 0, At, B0); G_BAR; G_SCHED;
;       G_STAGE(G_SB(0, 1), b2h1, voffB);
;       G_WAIT_V(6); G_BAR; G_MMA(1, 1, At, B1); G_BAR;
;       G_LDB(B0, 1, 0); G_SCHED; G_LDA(At, 1, 0); G_STAGE(G_SA(0, 1), a2h1, voffA);
;       G_WAIT_L(8); G_BAR; G_WAIT_L(0); G_MMA(0, 0, At, B0); G_BAR; G_SCHED;
;       G_LDB(B1, 1, 1); G_STAGE(G_SB(1, 0), b2h0 + kstep, voffB);
;       G_BAR; G_WAIT_L(0); G_MMA(0, 1, At, B1); G_BAR;
;       G_LDA(At, 1, 1); G_STAGE(G_SA(1, 0), a2h0 + kstep, voffA);
;       G_BAR; G_WAIT_L(0); G_MMA(1, 0, At, B0); G_BAR; G_SCHED;
	v_mov_b32_e32 v80, v135
	s_add_i32 s22, s22, s17
	s_mov_b32 m0, s22
	s_nop 0
	global_load_lds_dwordx4 v80, s[38:39]
	v_mov_b32_e32 v80, v137
	s_add_i32 m0, s22, 0x2000
	s_nop 0
	global_load_lds_dwordx4 v80, s[38:39]
	s_waitcnt vmcnt(6)
	s_barrier
	s_setprio 1
	v_mfma_f32_16x16x32_bf16 v[52:55], v[202:205], v[158:161], v[52:55]
	v_mfma_f32_16x16x32_bf16 v[48:51], v[210:213], v[158:161], v[48:51]
	v_mfma_f32_16x16x32_bf16 v[36:39], v[202:205], v[166:169], v[36:39]
	v_mfma_f32_16x16x32_bf16 v[32:35], v[210:213], v[166:169], v[32:35]
	v_mfma_f32_16x16x32_bf16 v[20:23], v[202:205], v[174:177], v[20:23]
	v_mfma_f32_16x16x32_bf16 v[16:19], v[210:213], v[174:177], v[16:19]
	v_mfma_f32_16x16x32_bf16 v[4:7], v[202:205], v[194:197], v[4:7]
	v_mfma_f32_16x16x32_bf16 v[0:3], v[210:213], v[194:197], v[0:3]
	v_mfma_f32_16x16x32_bf16 v[52:55], v[206:209], v[162:165], v[52:55]
	v_mfma_f32_16x16x32_bf16 v[48:51], v[214:217], v[162:165], v[48:51]
	v_mfma_f32_16x16x32_bf16 v[36:39], v[206:209], v[170:173], v[36:39]
	v_mfma_f32_16x16x32_bf16 v[32:35], v[214:217], v[170:173], v[32:35]
	v_mfma_f32_16x16x32_bf16 v[20:23], v[206:209], v[190:193], v[20:23]
	v_mfma_f32_16x16x32_bf16 v[16:19], v[214:217], v[190:193], v[16:19]
	v_mfma_f32_16x16x32_bf16 v[4:7], v[206:209], v[198:201], v[4:7]
	v_mfma_f32_16x16x32_bf16 v[0:3], v[214:217], v[198:201], v[0:3]
	s_setprio 0
	s_add_i32 s22, 0, 0x18000
	v_add_u32_e32 v80, s22, v139
	s_barrier
	ds_read_b128 v[142:145], v80
	ds_read_b128 v[146:149], v80 offset:1024
	ds_read_b128 v[150:153], v80 offset:2048
	ds_read_b128 v[154:157], v80 offset:3072
	v_mov_b32_e32 v80, v134
	s_mov_b32 m0, s46
	ds_read_b128 v[158:161], v141 offset:32768
	ds_read_b128 v[162:165], v141 offset:33792
	ds_read_b128 v[166:169], v141 offset:34816
	ds_read_b128 v[170:173], v141 offset:35840
	ds_read_b128 v[174:177], v141 offset:36864
	ds_read_b128 v[190:193], v141 offset:37888
	ds_read_b128 v[194:197], v141 offset:38912
	ds_read_b128 v[198:201], v141 offset:39936
	s_nop 0
	global_load_lds_dwordx4 v80, s[68:69]
	v_mov_b32_e32 v80, v136
	s_mov_b32 m0, s47
	s_nop 0
	global_load_lds_dwordx4 v80, s[68:69]
	s_waitcnt lgkmcnt(8)
	s_barrier
	s_waitcnt lgkmcnt(0)
	s_setprio 1
	s_waitcnt lgkmcnt(0)
	v_mfma_f32_16x16x32_bf16 v[126:129], v[142:145], v[158:161], v[126:129]
	v_mfma_f32_16x16x32_bf16 v[122:125], v[150:153], v[158:161], v[122:125]
	v_mfma_f32_16x16x32_bf16 v[110:113], v[142:145], v[166:169], v[110:113]
	v_mfma_f32_16x16x32_bf16 v[106:109], v[150:153], v[166:169], v[106:109]
	v_mfma_f32_16x16x32_bf16 v[94:97], v[142:145], v[174:177], v[94:97]
	v_mfma_f32_16x16x32_bf16 v[90:93], v[150:153], v[174:177], v[90:93]
	v_mfma_f32_16x16x32_bf16 v[76:79], v[142:145], v[194:197], v[76:79]
	v_mfma_f32_16x16x32_bf16 v[72:75], v[150:153], v[194:197], v[72:75]
	v_mfma_f32_16x16x32_bf16 v[126:129], v[146:149], v[162:165], v[126:129]
	v_mfma_f32_16x16x32_bf16 v[122:125], v[154:157], v[162:165], v[122:125]
	v_mfma_f32_16x16x32_bf16 v[110:113], v[146:149], v[170:173], v[110:113]
	v_mfma_f32_16x16x32_bf16 v[106:109], v[154:157], v[170:173], v[106:109]
	v_mfma_f32_16x16x32_bf16 v[94:97], v[146:149], v[190:193], v[94:97]
	v_mfma_f32_16x16x32_bf16 v[90:93], v[154:157], v[190:193], v[90:93]
	v_mfma_f32_16x16x32_bf16 v[76:79], v[146:149], v[198:201], v[76:79]
	v_mfma_f32_16x16x32_bf16 v[72:75], v[154:157], v[198:201], v[72:75]
	s_setprio 0
	s_barrier
	s_add_i32 s35, 0, 0x1c000
	v_add_u32_e32 v80, s35, v139
	ds_read_b128 v[202:205], v80
	ds_read_b128 v[206:209], v80 offset:1024
	ds_read_b128 v[210:213], v80 offset:2048
	ds_read_b128 v[214:217], v80 offset:3072
	v_mov_b32_e32 v80, v135
	s_add_i32 s22, s22, s17
	s_add_i32 m0, s22, 0xffffff80
	v_mov_b32_e32 v80, v137
	global_load_lds_dwordx4 v135, s[44:45] offset:128
	s_add_i32 m0, s22, 0x1f80
	s_nop 0
	global_load_lds_dwordx4 v137, s[44:45] offset:128
	s_barrier
	s_waitcnt lgkmcnt(0)
	s_setprio 1
	s_waitcnt lgkmcnt(0)
	v_mfma_f32_16x16x32_bf16 v[118:121], v[202:205], v[158:161], v[118:121]
	v_mfma_f32_16x16x32_bf16 v[114:117], v[210:213], v[158:161], v[114:117]
	v_mfma_f32_16x16x32_bf16 v[102:105], v[202:205], v[166:169], v[102:105]
	v_mfma_f32_16x16x32_bf16 v[98:101], v[210:213], v[166:169], v[98:101]
	v_mfma_f32_16x16x32_bf16 v[86:89], v[202:205], v[174:177], v[86:89]
	v_mfma_f32_16x16x32_bf16 v[82:85], v[210:213], v[174:177], v[82:85]
	v_mfma_f32_16x16x32_bf16 v[68:71], v[202:205], v[194:197], v[68:71]
	v_mfma_f32_16x16x32_bf16 v[64:67], v[210:213], v[194:197], v[64:67]
	v_mfma_f32_16x16x32_bf16 v[118:121], v[206:209], v[162:165], v[118:121]
	v_mfma_f32_16x16x32_bf16 v[114:117], v[214:217], v[162:165], v[114:117]
	v_mfma_f32_16x16x32_bf16 v[102:105], v[206:209], v[170:173], v[102:105]
	v_mfma_f32_16x16x32_bf16 v[98:101], v[214:217], v[170:173], v[98:101]
	v_mfma_f32_16x16x32_bf16 v[86:89], v[206:209], v[190:193], v[86:89]
	v_mfma_f32_16x16x32_bf16 v[82:85], v[214:217], v[190:193], v[82:85]
	v_mfma_f32_16x16x32_bf16 v[68:71], v[206:209], v[198:201], v[68:71]
	v_mfma_f32_16x16x32_bf16 v[64:67], v[214:217], v[198:201], v[64:67]
	s_setprio 0
	v_mov_b32_e32 v80, v134
	s_barrier
	ds_read_b128 v[158:161], v141 offset:49152
	ds_read_b128 v[162:165], v141 offset:50176
	ds_read_b128 v[166:169], v141 offset:51200
	ds_read_b128 v[170:173], v141 offset:52224
	ds_read_b128 v[174:177], v141 offset:53248
	ds_read_b128 v[190:193], v141 offset:54272
	ds_read_b128 v[194:197], v141 offset:55296
	ds_read_b128 v[198:201], v141 offset:56320
	s_add_i32 m0, s48, 0xffffff80
	v_mov_b32_e32 v80, v136
	global_load_lds_dwordx4 v134, s[42:43] offset:128
	s_add_i32 m0, s49, 0xffffff80
	s_nop 0
	global_load_lds_dwordx4 v136, s[42:43] offset:128
	s_barrier
; __device__ __forceinline__ unsigned cvt_pk_bf16(float lo, float hi) { unsigned r; asm("v_cvt_pk_bf16_f32 %0, %1, %2" : "=v"(r) : "v"(lo), "v"(hi)); return r; }
; __device__ __forceinline__ float bf_lo(unsigned u) { return __uint_as_float(u << 16); }
; __device__ __forceinline__ float bf_hi(unsigned u) { return __uint_as_float(u & 0xffff0000u); }
; #define G_WAIT_V(n) asm volatile("s_waitcnt vmcnt(" #n ")" ::: "memory")
; #define G_WAIT_L(n) asm volatile("s_waitcnt lgkmcnt(" #n ")" ::: "memory")
;   __device__ __forceinline__ void operator()(const f32x4 (&acc)[2][2][4][2], const Unit& u, const EpiCtx& x_, int wr, int wc, int fr, int fq) const {
; #pragma unroll
;     for (int ai = 0; ai < 2; ++ai)
; #pragma unroll
;       for (int m = 0; m < 4; ++m) {
;         const int row = (u.r0 + (ai ? x_.rdelta : 0)) + wr * 64 + m * 16 + fr;
;         const bf16_t* xin = (const bf16_t*)x_.aux + (size_t)row * DM;
;         bf16_t* xbp = x_.xb + (size_t)row * DM;
;         float sq = 0.f;
; #pragma unroll
;         for (int bj = 0; bj < 2; ++bj) {
;           const int cb = u.c0 + wc * 64 + bj * 32 + 8 * fq;
;           const uint4 xi = *(const uint4*)(xin + cb); const f32x4 a = acc[ai][bj][m][0], b = acc[ai][bj][m][1];
;           const float x0 = bf_lo(xi.x) + a[0], x1 = bf_hi(xi.x) + a[1], x2 = bf_lo(xi.y) + a[2], x3 = bf_hi(xi.y) + a[3];
;           const float x4 = bf_lo(xi.z) + b[0], x5 = bf_hi(xi.z) + b[1], x6 = bf_lo(xi.w) + b[2], x7 = bf_hi(xi.w) + b[3];
;           sq += x0 * x0 + x1 * x1 + x2 * x2 + x3 * x3 + x4 * x4 + x5 * x5 + x6 * x6 + x7 * x7;
;           uint4 o; o.x = cvt_pk_bf16(x0, x1); o.y = cvt_pk_bf16(x2, x3); o.z = cvt_pk_bf16(x4, x5); o.w = cvt_pk_bf16(x6, x7);
;           *(uint4*)(xbp + cb) = o;
; template <class Epi>
; __device__ __forceinline__ void gemm_phase(LAS unsigned char* lds, const int K, const unsigned lda_b, const unsigned ldb_b, const Map& M, const Epi& E) {
;     ...
;       G_WAIT_L(8); G_BAR; G_WAIT_L(0); G_MMA(0, 0, At, B0); G_BAR; G_SCHED;
;       G_LDB(B1, 1, 1); G_STAGE(G_SB(1, 0), b2h0 + kstep, voffB);
;       G_BAR; G_WAIT_L(0); G_MMA(0, 1, At, B1); G_BAR;
;       G_LDA(At, 1, 1); G_STAGE(G_SA(1, 0), a2h0 + kstep, voffA);
;       G_BAR; G_WAIT_L(0); G_MMA(1, 0, At, B0); G_BAR; G_SCHED;
;       G_STAGE(G_SB(1, 1), b2h1 + kstep, voffB);
;       G_WAIT_V(6); G_BAR; G_MMA(1, 1, At, B1); G_BAR;
	s_waitcnt lgkmcnt(0)
	s_setprio 1
	s_waitcnt lgkmcnt(0)
	v_mfma_f32_16x16x32_bf16 v[60:63], v[142:145], v[158:161], v[60:63]
	v_mfma_f32_16x16x32_bf16 v[56:59], v[150:153], v[158:161], v[56:59]
	v_mfma_f32_16x16x32_bf16 v[44:47], v[142:145], v[166:169], v[44:47]
	v_mfma_f32_16x16x32_bf16 v[40:43], v[150:153], v[166:169], v[40:43]
	v_mfma_f32_16x16x32_bf16 v[28:31], v[142:145], v[174:177], v[28:31]
	v_mfma_f32_16x16x32_bf16 v[24:27], v[150:153], v[174:177], v[24:27]
	v_mfma_f32_16x16x32_bf16 v[12:15], v[142:145], v[194:197], v[12:15]
	v_mfma_f32_16x16x32_bf16 v[8:11], v[150:153], v[194:197], v[8:11]
	v_mfma_f32_16x16x32_bf16 v[60:63], v[146:149], v[162:165], v[60:63]
	v_mfma_f32_16x16x32_bf16 v[56:59], v[154:157], v[162:165], v[56:59]
	v_mfma_f32_16x16x32_bf16 v[44:47], v[146:149], v[170:173], v[44:47]
	v_mfma_f32_16x16x32_bf16 v[40:43], v[154:157], v[170:173], v[40:43]
	v_mfma_f32_16x16x32_bf16 v[28:31], v[146:149], v[190:193], v[28:31]
	v_mfma_f32_16x16x32_bf16 v[24:27], v[154:157], v[190:193], v[24:27]
	v_mfma_f32_16x16x32_bf16 v[12:15], v[146:149], v[198:201], v[12:15]
	v_mfma_f32_16x16x32_bf16 v[8:11], v[154:157], v[198:201], v[8:11]
	s_setprio 0
	s_barrier
	v_mov_b32_e32 v80, v135
	s_add_i32 s22, s35, s17
	s_add_i32 m0, s22, 0xffffff80
	v_mov_b32_e32 v80, v137
	global_load_lds_dwordx4 v135, s[38:39] offset:128
	s_add_i32 m0, s22, 0x1f80
	s_nop 0
	global_load_lds_dwordx4 v137, s[38:39] offset:128
	s_waitcnt vmcnt(6)
	s_barrier
	s_setprio 1
	v_mfma_f32_16x16x32_bf16 v[52:55], v[202:205], v[158:161], v[52:55]
	v_mfma_f32_16x16x32_bf16 v[48:51], v[210:213], v[158:161], v[48:51]
	v_mfma_f32_16x16x32_bf16 v[36:39], v[202:205], v[166:169], v[36:39]
	v_mfma_f32_16x16x32_bf16 v[32:35], v[210:213], v[166:169], v[32:35]
	v_mfma_f32_16x16x32_bf16 v[20:23], v[202:205], v[174:177], v[20:23]
	v_mfma_f32_16x16x32_bf16 v[16:19], v[210:213], v[174:177], v[16:19]
	v_mfma_f32_16x16x32_bf16 v[4:7], v[202:205], v[194:197], v[4:7]
	v_mfma_f32_16x16x32_bf16 v[0:3], v[210:213], v[194:197], v[0:3]
	v_mfma_f32_16x16x32_bf16 v[52:55], v[206:209], v[162:165], v[52:55]
	v_mfma_f32_16x16x32_bf16 v[48:51], v[214:217], v[162:165], v[48:51]
	v_mfma_f32_16x16x32_bf16 v[36:39], v[206:209], v[170:173], v[36:39]
	v_mfma_f32_16x16x32_bf16 v[32:35], v[214:217], v[170:173], v[32:35]
	v_mfma_f32_16x16x32_bf16 v[20:23], v[206:209], v[190:193], v[20:23]
	v_mfma_f32_16x16x32_bf16 v[16:19], v[214:217], v[190:193], v[16:19]
	v_mfma_f32_16x16x32_bf16 v[4:7], v[206:209], v[198:201], v[4:7]
	v_mfma_f32_16x16x32_bf16 v[0:3], v[214:217], v[198:201], v[0:3]
	s_setprio 0
	s_add_i32 s34, s34, 2
	s_add_u32 s30, s30, 0x100
	s_addc_u32 s31, s31, 0
	s_add_u32 s2, s2, 0x100
	s_addc_u32 s3, s3, 0
	s_cmp_gt_u32 s34, 29
	s_barrier
	s_cbranch_scc0 .LBB0_844
	s_nop 1
	v_add_u32_e32 v194, s67, v138
	v_add_u32_e32 v196, s0, v140
	v_ashrrev_i32_e32 v195, 31, v194
	v_lshlrev_b64 v[198:199], 12, v[194:195]
	v_ashrrev_i32_e32 v197, 31, v196
	v_lshl_add_u64 v[200:201], s[8:9], 0, v[198:199]
	v_lshlrev_b64 v[202:203], 1, v[196:197]
	v_lshl_add_u64 v[204:205], v[200:201], 0, v[202:203]
	global_load_dwordx4 v[150:153], v[204:205], off
	global_load_dwordx4 v[154:157], v[204:205], off offset:64
	v_add_u32_e32 v198, 16, v194
	v_ashrrev_i32_e32 v195, 31, v198
	v_mov_b32_e32 v200, v198
	v_mov_b32_e32 v201, v195
	v_lshlrev_b64 v[204:205], 12, v[200:201]
	v_lshl_add_u64 v[200:201], s[8:9], 0, v[204:205]
	v_lshl_add_u64 v[206:207], v[200:201], 0, v[202:203]
	global_load_dwordx4 v[158:161], v[206:207], off
	global_load_dwordx4 v[162:165], v[206:207], off offset:64
	v_add_u32_e32 v198, 32, v194
	v_ashrrev_i32_e32 v195, 31, v198
	v_mov_b32_e32 v200, v198
	v_mov_b32_e32 v201, v195
	v_lshlrev_b64 v[204:205], 12, v[200:201]
	v_lshl_add_u64 v[200:201], s[8:9], 0, v[204:205]
	v_lshl_add_u64 v[206:207], v[200:201], 0, v[202:203]
	global_load_dwordx4 v[166:169], v[206:207], off
	global_load_dwordx4 v[170:173], v[206:207], off offset:64
	v_add_u32_e32 v198, 48, v194
	v_ashrrev_i32_e32 v195, 31, v198
	v_mov_b32_e32 v200, v198
	v_mov_b32_e32 v201, v195
	v_lshlrev_b64 v[204:205], 12, v[200:201]
	v_lshl_add_u64 v[200:201], s[8:9], 0, v[204:205]
	v_lshl_add_u64 v[206:207], v[200:201], 0, v[202:203]
	global_load_dwordx4 v[174:177], v[206:207], off
	global_load_dwordx4 v[190:193], v[206:207], off offset:64
	v_add_u32_e32 v132, s67, v138
	v_readfirstlane_b32 s38, v130
	v_add_u32_e32 v130, s0, v140
	v_ashrrev_i32_e32 v133, 31, v132
	v_readfirstlane_b32 s39, v131
	v_lshlrev_b64 v[142:143], 12, v[132:133]
	v_ashrrev_i32_e32 v131, 31, v130
	v_lshl_add_u64 v[144:145], s[8:9], 0, v[142:143]
	v_lshlrev_b64 v[130:131], 1, v[130:131]
	v_lshl_add_u64 v[148:149], v[144:145], 0, v[130:131]
	v_lshl_add_u64 v[146:147], s[36:37], 0, v[142:143]
	s_nop 0
	s_nop 0
	s_waitcnt lgkmcnt(0)
	s_nop 0
	s_waitcnt vmcnt(7)
	v_lshlrev_b32_e32 v80, 16, v150
	v_add_f32_e32 v80, v126, v80
	v_and_b32_e32 v126, 0xffff0000, v150
	v_add_f32_e32 v126, v127, v126
	v_lshlrev_b32_e32 v127, 16, v151
	v_add_f32_e32 v127, v128, v127
	v_and_b32_e32 v128, 0xffff0000, v151
	v_add_f32_e32 v128, v129, v128
	v_lshlrev_b32_e32 v129, 16, v152
	v_add_f32_e32 v129, v122, v129
	v_and_b32_e32 v122, 0xffff0000, v152
	v_mul_f32_e32 v144, v126, v126
	v_fmac_f32_e32 v144, v80, v80
	v_fmac_f32_e32 v144, v127, v127
	v_fmac_f32_e32 v144, v128, v128
	v_add_f32_e32 v142, v123, v122
	v_lshlrev_b32_e32 v122, 16, v153
	v_fmac_f32_e32 v144, v129, v129
	v_add_f32_e32 v143, v124, v122
	v_and_b32_e32 v122, 0xffff0000, v153
	v_fmac_f32_e32 v144, v142, v142
	v_add_f32_e32 v125, v125, v122
	v_fmac_f32_e32 v144, v143, v143
	v_cvt_pk_bf16_f32 v122, v80, v126
	v_cvt_pk_bf16_f32 v123, v127, v128
	v_lshl_add_u64 v[126:127], v[146:147], 0, v[130:131]
	v_fmac_f32_e32 v144, v125, v125
	v_cvt_pk_bf16_f32 v124, v129, v142
	v_cvt_pk_bf16_f32 v125, v143, v125
	global_store_dwordx4 v[126:127], v[122:125], off nt
	s_nop 0
	s_waitcnt lgkmcnt(0)
; __device__ __forceinline__ unsigned cvt_pk_bf16(float lo, float hi) { unsigned r; asm("v_cvt_pk_bf16_f32 %0, %1, %2" : "=v"(r) : "v"(lo), "v"(hi)); return r; }
; __device__ __forceinline__ float bf_lo(unsigned u) { return __uint_as_float(u << 16); }
; __device__ __forceinline__ float bf_hi(unsigned u) { return __uint_as_float(u & 0xffff0000u); }
; __device__ __forceinline__ unsigned long long ss_fix(float s) { return (unsigned long long)(s * 16777216.f); }
;   __device__ __forceinline__ void operator()(const f32x4 (&acc)[2][2][4][2], const Unit& u, const EpiCtx& x_, int wr, int wc, int fr, int fq) const {
;     ...
; #pragma unroll
;         for (int bj = 0; bj < 2; ++bj) {
;           const int cb = u.c0 + wc * 64 + bj * 32 + 8 * fq;
;           const uint4 xi = *(const uint4*)(xin + cb); const f32x4 a = acc[ai][bj][m][0], b = acc[ai][bj][m][1];
;           const float x0 = bf_lo(xi.x) + a[0], x1 = bf_hi(xi.x) + a[1], x2 = bf_lo(xi.y) + a[2], x3 = bf_hi(xi.y) + a[3];
;           const float x4 = bf_lo(xi.z) + b[0], x5 = bf_hi(xi.z) + b[1], x6 = bf_lo(xi.w) + b[2], x7 = bf_hi(xi.w) + b[3];
;           sq += x0 * x0 + x1 * x1 + x2 * x2 + x3 * x3 + x4 * x4 + x5 * x5 + x6 * x6 + x7 * x7;
;           uint4 o; o.x = cvt_pk_bf16(x0, x1); o.y = cvt_pk_bf16(x2, x3); o.z = cvt_pk_bf16(x4, x5); o.w = cvt_pk_bf16(x6, x7);
;           *(uint4*)(xbp + cb) = o;
;         }
;         sq += __shfl_xor(sq, 16); sq += __shfl_xor(sq, 32);
;         if (fq == 0) atomicAdd(x_.sso + row, ss_fix(sq));
	s_nop 0
	s_waitcnt vmcnt(7)
	v_lshlrev_b32_e32 v80, 16, v154
	v_add_f32_e32 v80, v118, v80
	v_and_b32_e32 v118, 0xffff0000, v154
	v_add_f32_e32 v118, v119, v118
	v_lshlrev_b32_e32 v119, 16, v155
	v_add_f32_e32 v119, v120, v119
	v_and_b32_e32 v120, 0xffff0000, v155
	v_add_f32_e32 v120, v121, v120
	v_lshlrev_b32_e32 v121, 16, v156
	v_add_f32_e32 v121, v114, v121
	v_and_b32_e32 v114, 0xffff0000, v156
	v_add_f32_e32 v122, v115, v114
	v_lshlrev_b32_e32 v114, 16, v157
	v_add_f32_e32 v123, v116, v114
	v_and_b32_e32 v114, 0xffff0000, v157
	v_add_f32_e32 v117, v117, v114
	v_mul_f32_e32 v114, v118, v118
	v_fmac_f32_e32 v114, v80, v80
	v_fmac_f32_e32 v114, v119, v119
	v_fmac_f32_e32 v114, v120, v120
	v_fmac_f32_e32 v114, v121, v121
	v_fmac_f32_e32 v114, v122, v122
	v_fmac_f32_e32 v114, v123, v123
	v_fmac_f32_e32 v114, v117, v117
	v_add_f32_e32 v124, v144, v114
	v_cvt_pk_bf16_f32 v114, v80, v118
	v_cvt_pk_bf16_f32 v115, v119, v120
	v_cvt_pk_bf16_f32 v116, v121, v122
	v_cvt_pk_bf16_f32 v117, v123, v117
	global_store_dwordx4 v[126:127], v[114:117], off offset:64 nt
	v_xor_b32_e32 v80, 16, v189
	s_nop 0
	v_and_b32_e32 v114, 64, v189
	v_add_u32_e32 v115, 64, v114
	v_cmp_lt_i32_e64 s[2:3], v80, v115
	v_xor_b32_e32 v116, 32, v189
	s_nop 0
	v_cndmask_b32_e64 v80, v189, v80, s[2:3]
	v_lshlrev_b32_e32 v80, 2, v80
	ds_bpermute_b32 v114, v80, v124
	v_cmp_lt_i32_e64 s[2:3], v116, v115
	s_waitcnt lgkmcnt(0)
	v_add_f32_e32 v114, v124, v114
	v_cndmask_b32_e64 v115, v189, v116, s[2:3]
	v_lshlrev_b32_e32 v116, 2, v115
	ds_bpermute_b32 v115, v116, v114
	s_and_saveexec_b64 s[2:3], vcc
	s_cbranch_execz .LBB0_847
	s_waitcnt lgkmcnt(0)
	v_add_f32_e32 v114, v114, v115
	v_mul_f32_e32 v114, 0x4b800000, v114
	v_trunc_f32_e32 v114, v114
	v_mul_f32_e32 v115, 0x2f800000, v114
	v_floor_f32_e32 v115, v115
	v_fmac_f32_e32 v114, 0xcf800000, v115
	v_cvt_u32_f32_e32 v114, v114
	v_cvt_u32_f32_e32 v115, v115
	v_lshl_add_u64 v[118:119], v[132:133], 3, s[40:41]
	global_atomic_add_x2 v[118:119], v[114:115], off
.LBB0_847:
	s_or_b64 exec, exec, s[2:3]
	v_add_u32_e32 v114, 16, v132
	s_waitcnt lgkmcnt(0)
	v_ashrrev_i32_e32 v115, 31, v114
	v_lshlrev_b64 v[118:119], 12, v[114:115]
	v_lshl_add_u64 v[120:121], s[8:9], 0, v[118:119]
	v_lshl_add_u64 v[124:125], v[120:121], 0, v[130:131]
	v_lshl_add_u64 v[122:123], s[36:37], 0, v[118:119]
	s_nop 0
	s_waitcnt lgkmcnt(0)
	s_nop 0
	s_waitcnt vmcnt(7)
	v_lshlrev_b32_e32 v117, 16, v158
	v_add_f32_e32 v110, v110, v117
	v_and_b32_e32 v117, 0xffff0000, v158
	v_add_f32_e32 v111, v111, v117
	v_lshlrev_b32_e32 v117, 16, v159
	v_add_f32_e32 v112, v112, v117
	v_and_b32_e32 v117, 0xffff0000, v159
	v_add_f32_e32 v113, v113, v117
	v_lshlrev_b32_e32 v117, 16, v160
	v_add_f32_e32 v117, v106, v117
	v_and_b32_e32 v106, 0xffff0000, v160
	v_mul_f32_e32 v120, v111, v111
	v_fmac_f32_e32 v120, v110, v110
	v_fmac_f32_e32 v120, v112, v112
	v_fmac_f32_e32 v120, v113, v113
	v_add_f32_e32 v118, v107, v106
	v_lshlrev_b32_e32 v106, 16, v161
	v_fmac_f32_e32 v120, v117, v117
	v_add_f32_e32 v119, v108, v106
	v_and_b32_e32 v106, 0xffff0000, v161
	v_fmac_f32_e32 v120, v118, v118
	v_add_f32_e32 v109, v109, v106
	v_fmac_f32_e32 v120, v119, v119
	v_cvt_pk_bf16_f32 v106, v110, v111
	v_lshl_add_u64 v[110:111], v[122:123], 0, v[130:131]
	v_fmac_f32_e32 v120, v109, v109
	v_cvt_pk_bf16_f32 v107, v112, v113
	v_cvt_pk_bf16_f32 v108, v117, v118
	v_cvt_pk_bf16_f32 v109, v119, v109
	global_store_dwordx4 v[110:111], v[106:109], off nt
	s_nop 0
	s_waitcnt lgkmcnt(0)
	s_nop 0
	s_waitcnt vmcnt(7)
	v_lshlrev_b32_e32 v112, 16, v162
	v_and_b32_e32 v106, 0xffff0000, v162
	v_add_f32_e32 v103, v103, v106
	v_lshlrev_b32_e32 v106, 16, v163
	v_add_f32_e32 v104, v104, v106
	v_and_b32_e32 v106, 0xffff0000, v163
	v_add_f32_e32 v105, v105, v106
	v_lshlrev_b32_e32 v106, 16, v164
	v_add_f32_e32 v106, v98, v106
	v_and_b32_e32 v98, 0xffff0000, v164
	v_add_f32_e32 v107, v99, v98
	v_lshlrev_b32_e32 v98, 16, v165
	v_add_f32_e32 v108, v100, v98
	v_and_b32_e32 v98, 0xffff0000, v165
	v_add_f32_e32 v102, v102, v112
	v_add_f32_e32 v101, v101, v98
	v_mul_f32_e32 v98, v103, v103
	v_fmac_f32_e32 v98, v102, v102
	v_fmac_f32_e32 v98, v104, v104
	v_fmac_f32_e32 v98, v105, v105
	v_fmac_f32_e32 v98, v106, v106
	v_fmac_f32_e32 v98, v107, v107
	v_fmac_f32_e32 v98, v108, v108
	v_fmac_f32_e32 v98, v101, v101
	v_add_f32_e32 v109, v120, v98
	v_cvt_pk_bf16_f32 v98, v102, v103
	v_cvt_pk_bf16_f32 v99, v104, v105
	v_cvt_pk_bf16_f32 v100, v106, v107
	v_cvt_pk_bf16_f32 v101, v108, v101
	global_store_dwordx4 v[110:111], v[98:101], off offset:64 nt
	s_nop 1
	ds_bpermute_b32 v98, v80, v109
	s_waitcnt lgkmcnt(0)
	v_add_f32_e32 v98, v109, v98
	ds_bpermute_b32 v99, v116, v98
	s_and_saveexec_b64 s[2:3], vcc
	s_cbranch_execz .LBB0_849
	s_waitcnt lgkmcnt(0)
	v_add_f32_e32 v98, v98, v99
	v_mul_f32_e32 v98, 0x4b800000, v98
	v_trunc_f32_e32 v98, v98
	v_mul_f32_e32 v99, 0x2f800000, v98
	v_floor_f32_e32 v99, v99
	v_fmac_f32_e32 v98, 0xcf800000, v99
	v_cvt_u32_f32_e32 v98, v98
	v_cvt_u32_f32_e32 v99, v99
	v_lshl_add_u64 v[100:101], v[114:115], 3, s[40:41]
	global_atomic_add_x2 v[100:101], v[98:99], off
; __device__ __forceinline__ unsigned cvt_pk_bf16(float lo, float hi) { unsigned r; asm("v_cvt_pk_bf16_f32 %0, %1, %2" : "=v"(r) : "v"(lo), "v"(hi)); return r; }
; __device__ __forceinline__ float bf_lo(unsigned u) { return __uint_as_float(u << 16); }
; __device__ __forceinline__ float bf_hi(unsigned u) { return __uint_as_float(u & 0xffff0000u); }
; __device__ __forceinline__ unsigned long long ss_fix(float s) { return (unsigned long long)(s * 16777216.f); }
;   __device__ __forceinline__ void operator()(const f32x4 (&acc)[2][2][4][2], const Unit& u, const EpiCtx& x_, int wr, int wc, int fr, int fq) const {
;     ...
;     for (int ai = 0; ai < 2; ++ai)
; #pragma unroll
;       for (int m = 0; m < 4; ++m) {
;         const int row = (u.r0 + (ai ? x_.rdelta : 0)) + wr * 64 + m * 16 + fr;
;         const bf16_t* xin = (const bf16_t*)x_.aux + (size_t)row * DM;
;         bf16_t* xbp = x_.xb + (size_t)row * DM;
;         float sq = 0.f;
; #pragma unroll
;         for (int bj = 0; bj < 2; ++bj) {
;           const int cb = u.c0 + wc * 64 + bj * 32 + 8 * fq;
;           const uint4 xi = *(const uint4*)(xin + cb); const f32x4 a = acc[ai][bj][m][0], b = acc[ai][bj][m][1];
;           const float x0 = bf_lo(xi.x) + a[0], x1 = bf_hi(xi.x) + a[1], x2 = bf_lo(xi.y) + a[2], x3 = bf_hi(xi.y) + a[3];
;           const float x4 = bf_lo(xi.z) + b[0], x5 = bf_hi(xi.z) + b[1], x6 = bf_lo(xi.w) + b[2], x7 = bf_hi(xi.w) + b[3];
;           sq += x0 * x0 + x1 * x1 + x2 * x2 + x3 * x3 + x4 * x4 + x5 * x5 + x6 * x6 + x7 * x7;
;           uint4 o; o.x = cvt_pk_bf16(x0, x1); o.y = cvt_pk_bf16(x2, x3); o.z = cvt_pk_bf16(x4, x5); o.w = cvt_pk_bf16(x6, x7);
;           *(uint4*)(xbp + cb) = o;
;         }
;         sq += __shfl_xor(sq, 16); sq += __shfl_xor(sq, 32);
;         if (fq == 0) atomicAdd(x_.sso + row, ss_fix(sq));
.LBB0_849:
	s_or_b64 exec, exec, s[2:3]
	s_nop 1
	v_add_u32_e32 v210, 0x80, v132
	v_ashrrev_i32_e32 v211, 31, v210
	v_lshlrev_b64 v[212:213], 12, v[210:211]
	v_lshl_add_u64 v[214:215], s[8:9], 0, v[212:213]
	v_lshl_add_u64 v[216:217], v[214:215], 0, v[130:131]
	global_load_dwordx4 v[150:153], v[216:217], off
	global_load_dwordx4 v[154:157], v[216:217], off offset:64
	v_add_u32_e32 v210, 0x90, v132
	v_ashrrev_i32_e32 v211, 31, v210
	v_lshlrev_b64 v[212:213], 12, v[210:211]
	v_lshl_add_u64 v[214:215], s[8:9], 0, v[212:213]
	v_lshl_add_u64 v[216:217], v[214:215], 0, v[130:131]
	global_load_dwordx4 v[158:161], v[216:217], off
	global_load_dwordx4 v[162:165], v[216:217], off offset:64
	v_add_u32_e32 v210, 0xa0, v132
	v_ashrrev_i32_e32 v211, 31, v210
	v_lshlrev_b64 v[212:213], 12, v[210:211]
	v_lshl_add_u64 v[214:215], s[8:9], 0, v[212:213]
	v_lshl_add_u64 v[216:217], v[214:215], 0, v[130:131]
	global_load_dwordx4 v[194:197], v[216:217], off
	global_load_dwordx4 v[198:201], v[216:217], off offset:64
	v_add_u32_e32 v210, 0xb0, v132
	v_ashrrev_i32_e32 v211, 31, v210
	v_lshlrev_b64 v[212:213], 12, v[210:211]
	v_lshl_add_u64 v[214:215], s[8:9], 0, v[212:213]
	v_lshl_add_u64 v[216:217], v[214:215], 0, v[130:131]
	global_load_dwordx4 v[202:205], v[216:217], off
	global_load_dwordx4 v[206:209], v[216:217], off offset:64
	v_add_u32_e32 v98, 32, v132
	s_waitcnt lgkmcnt(0)
	v_ashrrev_i32_e32 v99, 31, v98
	v_lshlrev_b64 v[100:101], 12, v[98:99]
	v_lshl_add_u64 v[102:103], s[8:9], 0, v[100:101]
	v_lshl_add_u64 v[106:107], v[102:103], 0, v[130:131]
	v_lshl_add_u64 v[104:105], s[36:37], 0, v[100:101]
	s_nop 0
	s_waitcnt lgkmcnt(0)
	s_nop 0
	s_waitcnt vmcnt(15)
	v_lshlrev_b32_e32 v108, 16, v166
	v_and_b32_e32 v100, 0xffff0000, v166
	v_add_f32_e32 v95, v95, v100
	v_lshlrev_b32_e32 v100, 16, v167
	v_add_f32_e32 v96, v96, v100
	v_and_b32_e32 v100, 0xffff0000, v167
	v_add_f32_e32 v97, v97, v100
	v_lshlrev_b32_e32 v100, 16, v168
	v_add_f32_e32 v100, v90, v100
	v_and_b32_e32 v90, 0xffff0000, v168
	v_add_f32_e32 v101, v91, v90
	v_lshlrev_b32_e32 v90, 16, v169
	v_add_f32_e32 v94, v94, v108
	v_add_f32_e32 v102, v92, v90
	v_and_b32_e32 v90, 0xffff0000, v169
	v_mul_f32_e32 v103, v95, v95
	v_fmac_f32_e32 v103, v94, v94
	v_fmac_f32_e32 v103, v96, v96
	v_fmac_f32_e32 v103, v97, v97
	v_fmac_f32_e32 v103, v100, v100
	v_fmac_f32_e32 v103, v101, v101
	v_add_f32_e32 v93, v93, v90
	v_fmac_f32_e32 v103, v102, v102
	v_cvt_pk_bf16_f32 v90, v94, v95
	v_lshl_add_u64 v[94:95], v[104:105], 0, v[130:131]
	v_fmac_f32_e32 v103, v93, v93
	v_cvt_pk_bf16_f32 v91, v96, v97
	v_cvt_pk_bf16_f32 v92, v100, v101
	v_cvt_pk_bf16_f32 v93, v102, v93
	global_store_dwordx4 v[94:95], v[90:93], off nt
	s_nop 0
	s_waitcnt lgkmcnt(0)
	s_nop 0
	s_waitcnt vmcnt(15)
	v_lshlrev_b32_e32 v96, 16, v170
	v_and_b32_e32 v90, 0xffff0000, v170
	v_add_f32_e32 v87, v87, v90
	v_lshlrev_b32_e32 v90, 16, v171
	v_add_f32_e32 v88, v88, v90
	v_and_b32_e32 v90, 0xffff0000, v171
	v_add_f32_e32 v89, v89, v90
	v_lshlrev_b32_e32 v90, 16, v172
	v_add_f32_e32 v90, v82, v90
	v_and_b32_e32 v82, 0xffff0000, v172
	v_add_f32_e32 v91, v83, v82
	v_lshlrev_b32_e32 v82, 16, v173
	v_add_f32_e32 v92, v84, v82
	v_and_b32_e32 v82, 0xffff0000, v173
	v_add_f32_e32 v86, v86, v96
	v_add_f32_e32 v85, v85, v82
	v_mul_f32_e32 v82, v87, v87
	v_fmac_f32_e32 v82, v86, v86
	v_fmac_f32_e32 v82, v88, v88
	v_fmac_f32_e32 v82, v89, v89
	v_fmac_f32_e32 v82, v90, v90
	v_fmac_f32_e32 v82, v91, v91
	v_fmac_f32_e32 v82, v92, v92
	v_fmac_f32_e32 v82, v85, v85
	v_add_f32_e32 v93, v103, v82
	v_cvt_pk_bf16_f32 v82, v86, v87
	v_cvt_pk_bf16_f32 v83, v88, v89
	v_cvt_pk_bf16_f32 v84, v90, v91
	v_cvt_pk_bf16_f32 v85, v92, v85
	global_store_dwordx4 v[94:95], v[82:85], off offset:64 nt
	s_nop 1
	ds_bpermute_b32 v82, v80, v93
	s_waitcnt lgkmcnt(0)
	v_add_f32_e32 v82, v93, v82
	ds_bpermute_b32 v83, v116, v82
	s_and_saveexec_b64 s[2:3], vcc
	s_cbranch_execz .LBB0_851
	s_waitcnt lgkmcnt(0)
	v_add_f32_e32 v82, v82, v83
	v_mul_f32_e32 v82, 0x4b800000, v82
	v_trunc_f32_e32 v82, v82
	v_mul_f32_e32 v83, 0x2f800000, v82
	v_floor_f32_e32 v83, v83
	v_fmac_f32_e32 v82, 0xcf800000, v83
	v_cvt_u32_f32_e32 v82, v82
	v_cvt_u32_f32_e32 v83, v83
	v_lshl_add_u64 v[84:85], v[98:99], 3, s[40:41]
	global_atomic_add_x2 v[84:85], v[82:83], off
; __device__ __forceinline__ unsigned cvt_pk_bf16(float lo, float hi) { unsigned r; asm("v_cvt_pk_bf16_f32 %0, %1, %2" : "=v"(r) : "v"(lo), "v"(hi)); return r; }
; __device__ __forceinline__ float bf_lo(unsigned u) { return __uint_as_float(u << 16); }
; __device__ __forceinline__ float bf_hi(unsigned u) { return __uint_as_float(u & 0xffff0000u); }
; __device__ __forceinline__ unsigned long long ss_fix(float s) { return (unsigned long long)(s * 16777216.f); }
;   __device__ __forceinline__ void operator()(const f32x4 (&acc)[2][2][4][2], const Unit& u, const EpiCtx& x_, int wr, int wc, int fr, int fq) const {
;     ...
;         const int row = (u.r0 + (ai ? x_.rdelta : 0)) + wr * 64 + m * 16 + fr;
;         const bf16_t* xin = (const bf16_t*)x_.aux + (size_t)row * DM;
;         bf16_t* xbp = x_.xb + (size_t)row * DM;
;         float sq = 0.f;
; #pragma unroll
;         for (int bj = 0; bj < 2; ++bj) {
;           const int cb = u.c0 + wc * 64 + bj * 32 + 8 * fq;
;           const uint4 xi = *(const uint4*)(xin + cb); const f32x4 a = acc[ai][bj][m][0], b = acc[ai][bj][m][1];
;           const float x0 = bf_lo(xi.x) + a[0], x1 = bf_hi(xi.x) + a[1], x2 = bf_lo(xi.y) + a[2], x3 = bf_hi(xi.y) + a[3];
;           const float x4 = bf_lo(xi.z) + b[0], x5 = bf_hi(xi.z) + b[1], x6 = bf_lo(xi.w) + b[2], x7 = bf_hi(xi.w) + b[3];
;           sq += x0 * x0 + x1 * x1 + x2 * x2 + x3 * x3 + x4 * x4 + x5 * x5 + x6 * x6 + x7 * x7;
;           uint4 o; o.x = cvt_pk_bf16(x0, x1); o.y = cvt_pk_bf16(x2, x3); o.z = cvt_pk_bf16(x4, x5); o.w = cvt_pk_bf16(x6, x7);
;           *(uint4*)(xbp + cb) = o;
;         }
;         sq += __shfl_xor(sq, 16); sq += __shfl_xor(sq, 32);
;         if (fq == 0) atomicAdd(x_.sso + row, ss_fix(sq));
.LBB0_851:
	s_or_b64 exec, exec, s[2:3]
	v_add_u32_e32 v82, 48, v132
	s_waitcnt lgkmcnt(0)
	v_ashrrev_i32_e32 v83, 31, v82
	v_lshlrev_b64 v[84:85], 12, v[82:83]
	v_lshl_add_u64 v[86:87], s[8:9], 0, v[84:85]
	v_lshl_add_u64 v[90:91], v[86:87], 0, v[130:131]
	v_lshl_add_u64 v[88:89], s[36:37], 0, v[84:85]
	s_nop 0
	s_waitcnt lgkmcnt(0)
	s_nop 0
	s_waitcnt vmcnt(15)
	v_lshlrev_b32_e32 v92, 16, v174
	v_and_b32_e32 v84, 0xffff0000, v174
	v_add_f32_e32 v77, v77, v84
	v_lshlrev_b32_e32 v84, 16, v175
	v_add_f32_e32 v78, v78, v84
	v_and_b32_e32 v84, 0xffff0000, v175
	v_add_f32_e32 v79, v79, v84
	v_lshlrev_b32_e32 v84, 16, v176
	v_add_f32_e32 v84, v72, v84
	v_and_b32_e32 v72, 0xffff0000, v176
	v_add_f32_e32 v85, v73, v72
	v_lshlrev_b32_e32 v72, 16, v177
	v_add_f32_e32 v76, v76, v92
	v_add_f32_e32 v86, v74, v72
	v_and_b32_e32 v72, 0xffff0000, v177
	v_mul_f32_e32 v87, v77, v77
	v_fmac_f32_e32 v87, v76, v76
	v_fmac_f32_e32 v87, v78, v78
	v_fmac_f32_e32 v87, v79, v79
	v_fmac_f32_e32 v87, v84, v84
	v_fmac_f32_e32 v87, v85, v85
	v_add_f32_e32 v75, v75, v72
	v_fmac_f32_e32 v87, v86, v86
	v_cvt_pk_bf16_f32 v72, v76, v77
	v_lshl_add_u64 v[76:77], v[88:89], 0, v[130:131]
	v_fmac_f32_e32 v87, v75, v75
	v_cvt_pk_bf16_f32 v73, v78, v79
	v_cvt_pk_bf16_f32 v74, v84, v85
	v_cvt_pk_bf16_f32 v75, v86, v75
	global_store_dwordx4 v[76:77], v[72:75], off nt
	s_nop 0
	s_waitcnt lgkmcnt(0)
	s_nop 0
	s_waitcnt vmcnt(15)
	v_lshlrev_b32_e32 v78, 16, v190
	v_and_b32_e32 v72, 0xffff0000, v190
	v_add_f32_e32 v69, v69, v72
	v_lshlrev_b32_e32 v72, 16, v191
	v_add_f32_e32 v70, v70, v72
	v_and_b32_e32 v72, 0xffff0000, v191
	v_add_f32_e32 v71, v71, v72
	v_lshlrev_b32_e32 v72, 16, v192
	v_add_f32_e32 v72, v64, v72
	v_and_b32_e32 v64, 0xffff0000, v192
	v_add_f32_e32 v73, v65, v64
	v_lshlrev_b32_e32 v64, 16, v193
	v_add_f32_e32 v74, v66, v64
	v_and_b32_e32 v64, 0xffff0000, v193
	v_add_f32_e32 v68, v68, v78
	v_add_f32_e32 v67, v67, v64
	v_mul_f32_e32 v64, v69, v69
	v_fmac_f32_e32 v64, v68, v68
	v_fmac_f32_e32 v64, v70, v70
	v_fmac_f32_e32 v64, v71, v71
	v_fmac_f32_e32 v64, v72, v72
	v_fmac_f32_e32 v64, v73, v73
	v_fmac_f32_e32 v64, v74, v74
	v_fmac_f32_e32 v64, v67, v67
	v_add_f32_e32 v75, v87, v64
	v_cvt_pk_bf16_f32 v64, v68, v69
	v_cvt_pk_bf16_f32 v65, v70, v71
	v_cvt_pk_bf16_f32 v66, v72, v73
	v_cvt_pk_bf16_f32 v67, v74, v67
	global_store_dwordx4 v[76:77], v[64:67], off offset:64 nt
	s_nop 1
	ds_bpermute_b32 v64, v80, v75
	s_waitcnt lgkmcnt(0)
	v_add_f32_e32 v64, v75, v64
	ds_bpermute_b32 v65, v116, v64
	s_and_saveexec_b64 s[2:3], vcc
	s_cbranch_execz .LBB0_853
	s_waitcnt lgkmcnt(0)
	v_add_f32_e32 v64, v64, v65
	v_mul_f32_e32 v64, 0x4b800000, v64
	v_trunc_f32_e32 v64, v64
	v_mul_f32_e32 v65, 0x2f800000, v64
	v_floor_f32_e32 v65, v65
	v_fmac_f32_e32 v64, 0xcf800000, v65
	v_cvt_u32_f32_e32 v64, v64
	v_cvt_u32_f32_e32 v65, v65
	v_lshl_add_u64 v[66:67], v[82:83], 3, s[40:41]
	global_atomic_add_x2 v[66:67], v[64:65], off

; __device__ __forceinline__ unsigned cvt_pk_bf16(float lo, float hi) { unsigned r; asm("v_cvt_pk_bf16_f32 %0, %1, %2" : "=v"(r) : "v"(lo), "v"(hi)); return r; }
; __device__ __forceinline__ float bf_lo(unsigned u) { return __uint_as_float(u << 16); }
; __device__ __forceinline__ float bf_hi(unsigned u) { return __uint_as_float(u & 0xffff0000u); }
; __device__ __forceinline__ unsigned long long ss_fix(float s) { return (unsigned long long)(s * 16777216.f); }
;   __device__ __forceinline__ void operator()(const f32x4 (&acc)[2][2][4][2], const Unit& u, const EpiCtx& x_, int wr, int wc, int fr, int fq) const {
;     ...
;         const int row = (u.r0 + (ai ? x_.rdelta : 0)) + wr * 64 + m * 16 + fr;
;         const bf16_t* xin = (const bf16_t*)x_.aux + (size_t)row * DM;
;         bf16_t* xbp = x_.xb + (size_t)row * DM;
;         float sq = 0.f;
; #pragma unroll
;         for (int bj = 0; bj < 2; ++bj) {
;           const int cb = u.c0 + wc * 64 + bj * 32 + 8 * fq;
;           const uint4 xi = *(const uint4*)(xin + cb); const f32x4 a = acc[ai][bj][m][0], b = acc[ai][bj][m][1];
;           const float x0 = bf_lo(xi.x) + a[0], x1 = bf_hi(xi.x) + a[1], x2 = bf_lo(xi.y) + a[2], x3 = bf_hi(xi.y) + a[3];
;           const float x4 = bf_lo(xi.z) + b[0], x5 = bf_hi(xi.z) + b[1], x6 = bf_lo(xi.w) + b[2], x7 = bf_hi(xi.w) + b[3];
;           sq += x0 * x0 + x1 * x1 + x2 * x2 + x3 * x3 + x4 * x4 + x5 * x5 + x6 * x6 + x7 * x7;
;           uint4 o; o.x = cvt_pk_bf16(x0, x1); o.y = cvt_pk_bf16(x2, x3); o.z = cvt_pk_bf16(x4, x5); o.w = cvt_pk_bf16(x6, x7);
;           *(uint4*)(xbp + cb) = o;
;         }
;         sq += __shfl_xor(sq, 16); sq += __shfl_xor(sq, 32);
;         if (fq == 0) atomicAdd(x_.sso + row, ss_fix(sq));
.LBB0_855:
	s_or_b64 exec, exec, s[2:3]
	v_add_u32_e32 v48, 0x90, v132
	s_waitcnt lgkmcnt(0)
	v_ashrrev_i32_e32 v49, 31, v48
	v_lshlrev_b64 v[50:51], 12, v[48:49]
	v_lshl_add_u64 v[52:53], s[8:9], 0, v[50:51]
	v_lshl_add_u64 v[56:57], v[52:53], 0, v[130:131]
	v_lshl_add_u64 v[54:55], s[36:37], 0, v[50:51]
	s_nop 0
	s_waitcnt lgkmcnt(0)
	s_nop 0
	s_waitcnt vmcnt(11)
	v_lshlrev_b32_e32 v58, 16, v158
	v_and_b32_e32 v50, 0xffff0000, v158
	v_add_f32_e32 v45, v45, v50
	v_lshlrev_b32_e32 v50, 16, v159
	v_add_f32_e32 v46, v46, v50
	v_and_b32_e32 v50, 0xffff0000, v159
	v_add_f32_e32 v47, v47, v50
	v_lshlrev_b32_e32 v50, 16, v160
	v_add_f32_e32 v50, v40, v50
	v_and_b32_e32 v40, 0xffff0000, v160
	v_add_f32_e32 v51, v41, v40
	v_lshlrev_b32_e32 v40, 16, v161
	v_add_f32_e32 v44, v44, v58
	v_add_f32_e32 v52, v42, v40
	v_and_b32_e32 v40, 0xffff0000, v161
	v_mul_f32_e32 v53, v45, v45
	v_fmac_f32_e32 v53, v44, v44
	v_fmac_f32_e32 v53, v46, v46
	v_fmac_f32_e32 v53, v47, v47
	v_fmac_f32_e32 v53, v50, v50
	v_fmac_f32_e32 v53, v51, v51
	v_add_f32_e32 v43, v43, v40
	v_fmac_f32_e32 v53, v52, v52
	v_cvt_pk_bf16_f32 v40, v44, v45
	v_lshl_add_u64 v[44:45], v[54:55], 0, v[130:131]
	v_fmac_f32_e32 v53, v43, v43
	v_cvt_pk_bf16_f32 v41, v46, v47
	v_cvt_pk_bf16_f32 v42, v50, v51
	v_cvt_pk_bf16_f32 v43, v52, v43
	global_store_dwordx4 v[44:45], v[40:43], off nt
	s_nop 1
	s_nop 0
	s_waitcnt lgkmcnt(0)
	s_nop 0
	s_waitcnt vmcnt(11)
	v_lshlrev_b32_e32 v46, 16, v162
	v_and_b32_e32 v40, 0xffff0000, v162
	v_add_f32_e32 v37, v37, v40
	v_lshlrev_b32_e32 v40, 16, v163
	v_add_f32_e32 v38, v38, v40
	v_and_b32_e32 v40, 0xffff0000, v163
	v_add_f32_e32 v39, v39, v40
	v_lshlrev_b32_e32 v40, 16, v164
	v_add_f32_e32 v40, v32, v40
	v_and_b32_e32 v32, 0xffff0000, v164
	v_add_f32_e32 v41, v33, v32
	v_lshlrev_b32_e32 v32, 16, v165
	v_add_f32_e32 v42, v34, v32
	v_and_b32_e32 v32, 0xffff0000, v165
	v_add_f32_e32 v36, v36, v46
	v_add_f32_e32 v35, v35, v32
	v_mul_f32_e32 v32, v37, v37
	v_fmac_f32_e32 v32, v36, v36
	v_fmac_f32_e32 v32, v38, v38
	v_fmac_f32_e32 v32, v39, v39
	v_fmac_f32_e32 v32, v40, v40
	v_fmac_f32_e32 v32, v41, v41
	v_fmac_f32_e32 v32, v42, v42
	v_fmac_f32_e32 v32, v35, v35
	v_add_f32_e32 v43, v53, v32
	v_cvt_pk_bf16_f32 v32, v36, v37
	v_cvt_pk_bf16_f32 v33, v38, v39
	v_cvt_pk_bf16_f32 v34, v40, v41
	v_cvt_pk_bf16_f32 v35, v42, v35
	global_store_dwordx4 v[44:45], v[32:35], off offset:64 nt
	s_nop 1
	ds_bpermute_b32 v32, v80, v43
	s_waitcnt lgkmcnt(0)
	v_add_f32_e32 v32, v43, v32
	ds_bpermute_b32 v33, v116, v32
	s_and_saveexec_b64 s[2:3], vcc
	s_cbranch_execz .LBB0_857
	s_waitcnt lgkmcnt(0)
	v_add_f32_e32 v32, v32, v33
	v_mul_f32_e32 v32, 0x4b800000, v32
	v_trunc_f32_e32 v32, v32
	v_mul_f32_e32 v33, 0x2f800000, v32
	v_floor_f32_e32 v33, v33
	v_fmac_f32_e32 v32, 0xcf800000, v33
	v_cvt_u32_f32_e32 v32, v32
	v_cvt_u32_f32_e32 v33, v33
	v_lshl_add_u64 v[34:35], v[48:49], 3, s[40:41]
	global_atomic_add_x2 v[34:35], v[32:33], off

; #define G_STAGE(bufoff, gbase, voff) do { _Pragma("unroll") for (int _i = 0; _i < 2; ++_i) { unsigned _vo = (voff)[_i]; asm volatile("" : "+v"(_vo));   \
;     __builtin_amdgcn_global_load_lds((const unsigned*)((const char*)(gbase) + _vo), (LAS unsigned*)(lds + (bufoff) + ldsw + _i * 8192), 16, 0, 0); } } while (0)
; #define G_LDA(dst, b, h) do { _Pragma("unroll") for (int m = 0; m < 4; ++m) _Pragma("unroll") for (int k = 0; k < 2; ++k) dst[m][k] = *(const LAS bf16x8*)(lds + G_SA(b, h) + aoff + m * 2048 + k * 1024); } while (0)
; #define G_LDB(dst, b, h) do { _Pragma("unroll") for (int n = 0; n < 2; ++n) _Pragma("unroll") for (int k = 0; k < 2; ++k) dst[n][k] = *(const LAS bf16x8*)(lds + G_SB(b, h) + boff + n * 2048 + k * 1024); } while (0)
; #define G_MMA(ai, bj, At, Bt) do { __builtin_amdgcn_s_setprio(1); _Pragma("unroll") for (int m = 0; m < 4; ++m) _Pragma("unroll") for (int n = 0; n < 2; ++n) _Pragma("unroll") for (int k = 0; k < 2; ++k) \
;     acc[ai][bj][m][n] = __builtin_amdgcn_mfma_f32_16x16x32_bf16(Bt[n][k], At[m][k], acc[ai][bj][m][n], 0, 0, 0); __builtin_amdgcn_s_setprio(0); } while (0)
; #define G_WAIT_V(n) asm volatile("s_waitcnt vmcnt(" #n ")" ::: "memory")
; #define G_WAIT_L(n) asm volatile("s_waitcnt lgkmcnt(" #n ")" ::: "memory")
; #define G_BAR __builtin_amdgcn_s_barrier()
; template <class Epi>
; __device__ __forceinline__ void gemm_phase(LAS unsigned char* lds, const int K, const unsigned lda_b, const unsigned ldb_b, const Map& M, const Epi& E) {
;     ...
;     for (int t = 0; t < nt; t += 2) {
;       const bool last = (t == nt - 2);
;       const char* a1h1 = cur.a0 + a_h + (size_t)(t + 1) * kstep;
;       const char* a2h0 = last ? nxt.a0 : cur.a0 + (size_t)(t + 2) * kstep; const char* a2h1 = a2h0 + a_h;
;       const char* b2h0 = last ? nxt.b0 : cur.b0 + (size_t)(t + 2) * kstep; const char* b2h1 = last ? nxt.b1 : cur.b1 + (size_t)(t + 2) * kstep;
;       G_LDB(B0, 0, 0); G_SCHED; G_LDA(At, 0, 0); G_STAGE(G_SA(1, 1), a1h1, voffA);
;       G_WAIT_L(8); G_BAR; G_WAIT_L(0); G_MMA(0, 0, At, B0); G_BAR; G_SCHED;
;       G_LDB(B1, 0, 1); G_STAGE(G_SB(0, 0), b2h0, voffB);
;       G_BAR; G_WAIT_L(0); G_MMA(0, 1, At, B1); G_BAR;
;       G_LDA(At, 0, 1); G_STAGE(G_SA(0, 0), a2h0, voffA);
;       G_BAR; G_WAIT_L(0); G_MMA(1, 0, At, B0); G_BAR; G_SCHED;
;       G_STAGE(G_SB(0, 1), b2h1, voffB);
;       G_WAIT_V(6); G_BAR; G_MMA(1, 1, At, B1); G_BAR;
.LBB0_958:
	s_add_u32 s22, s4, 0xfff80080
	s_addc_u32 s30, s5, -1
	s_add_u32 s31, s19, 0xfffe0000
	s_addc_u32 s34, s28, -1
	s_add_i32 s35, 0, 0x10000
	v_add_u32_e32 v80, s35, v165
	ds_read_b128 v[132:135], v80
	ds_read_b128 v[136:139], v80 offset:1024
	ds_read_b128 v[140:143], v80 offset:2048
	ds_read_b128 v[144:147], v80 offset:3072
	s_cmp_eq_u32 s29, 28
	s_cselect_b32 s43, s7, s30
	s_cselect_b32 s42, s6, s22
	s_cselect_b32 s45, s9, s34
	s_cselect_b32 s44, s8, s31
	v_mov_b32_e32 v80, v160
	s_cselect_b32 s39, s18, s28
	s_cselect_b32 s38, s1, s19
	s_add_u32 s68, s42, 0x80000
	ds_read_b128 v[148:151], v171
	ds_read_b128 v[152:155], v171 offset:1024
	ds_read_b128 v[172:175], v171 offset:2048
	ds_read_b128 v[176:179], v171 offset:3072
	ds_read_b128 v[184:187], v171 offset:4096
	ds_read_b128 v[190:193], v171 offset:5120
	ds_read_b128 v[194:197], v171 offset:6144
	ds_read_b128 v[198:201], v171 offset:7168
	s_addc_u32 s69, s43, 0
	s_add_i32 m0, s47, 0xc000
	s_nop 0
	global_load_lds_dwordx4 v80, s[4:5]
	v_mov_b32_e32 v80, v162
	s_add_i32 m0, s47, 0xe000
	s_nop 0
	global_load_lds_dwordx4 v80, s[4:5]
	s_waitcnt lgkmcnt(8)
	s_barrier
	s_waitcnt lgkmcnt(0)
	s_setprio 1
	s_waitcnt lgkmcnt(0)
	v_mfma_f32_16x16x32_bf16 v[128:131], v[132:135], v[148:151], v[128:131]
	v_mfma_f32_16x16x32_bf16 v[124:127], v[140:143], v[148:151], v[124:127]
	v_mfma_f32_16x16x32_bf16 v[110:113], v[132:135], v[172:175], v[110:113]
	v_mfma_f32_16x16x32_bf16 v[106:109], v[140:143], v[172:175], v[106:109]
	v_mfma_f32_16x16x32_bf16 v[94:97], v[132:135], v[184:187], v[94:97]
	v_mfma_f32_16x16x32_bf16 v[90:93], v[140:143], v[184:187], v[90:93]
	v_mfma_f32_16x16x32_bf16 v[76:79], v[132:135], v[194:197], v[76:79]
	v_mfma_f32_16x16x32_bf16 v[72:75], v[140:143], v[194:197], v[72:75]
	v_mfma_f32_16x16x32_bf16 v[128:131], v[136:139], v[152:155], v[128:131]
	v_mfma_f32_16x16x32_bf16 v[124:127], v[144:147], v[152:155], v[124:127]
	v_mfma_f32_16x16x32_bf16 v[110:113], v[136:139], v[176:179], v[110:113]
	v_mfma_f32_16x16x32_bf16 v[106:109], v[144:147], v[176:179], v[106:109]
	v_mfma_f32_16x16x32_bf16 v[94:97], v[136:139], v[190:193], v[94:97]
	v_mfma_f32_16x16x32_bf16 v[90:93], v[144:147], v[190:193], v[90:93]
	v_mfma_f32_16x16x32_bf16 v[76:79], v[136:139], v[198:201], v[76:79]
	v_mfma_f32_16x16x32_bf16 v[72:75], v[144:147], v[198:201], v[72:75]
	s_setprio 0
	s_barrier
	s_add_i32 s22, 0, 0x14000
	v_add_u32_e32 v80, s22, v165
	ds_read_b128 v[202:205], v80
	ds_read_b128 v[206:209], v80 offset:1024
	ds_read_b128 v[210:213], v80 offset:2048
	ds_read_b128 v[214:217], v80 offset:3072
	v_mov_b32_e32 v80, v161
	s_add_i32 s30, s35, s46
	s_mov_b32 m0, s30
	s_nop 0
	global_load_lds_dwordx4 v80, s[44:45]
	v_mov_b32_e32 v80, v163
	s_add_i32 m0, s30, 0x2000
	s_nop 0
	global_load_lds_dwordx4 v80, s[44:45]
	s_barrier
	s_waitcnt lgkmcnt(0)
	s_setprio 1
	s_waitcnt lgkmcnt(0)
	v_mfma_f32_16x16x32_bf16 v[118:121], v[202:205], v[148:151], v[118:121]
	v_mfma_f32_16x16x32_bf16 v[114:117], v[210:213], v[148:151], v[114:117]
	v_mfma_f32_16x16x32_bf16 v[102:105], v[202:205], v[172:175], v[102:105]
	v_mfma_f32_16x16x32_bf16 v[98:101], v[210:213], v[172:175], v[98:101]
	v_mfma_f32_16x16x32_bf16 v[86:89], v[202:205], v[184:187], v[86:89]
	v_mfma_f32_16x16x32_bf16 v[82:85], v[210:213], v[184:187], v[82:85]
	v_mfma_f32_16x16x32_bf16 v[68:71], v[202:205], v[194:197], v[68:71]
	v_mfma_f32_16x16x32_bf16 v[64:67], v[210:213], v[194:197], v[64:67]
	v_mfma_f32_16x16x32_bf16 v[118:121], v[206:209], v[152:155], v[118:121]
	v_mfma_f32_16x16x32_bf16 v[114:117], v[214:217], v[152:155], v[114:117]
	v_mfma_f32_16x16x32_bf16 v[102:105], v[206:209], v[176:179], v[102:105]
	v_mfma_f32_16x16x32_bf16 v[98:101], v[214:217], v[176:179], v[98:101]
	v_mfma_f32_16x16x32_bf16 v[86:89], v[206:209], v[190:193], v[86:89]
	v_mfma_f32_16x16x32_bf16 v[82:85], v[214:217], v[190:193], v[82:85]
	v_mfma_f32_16x16x32_bf16 v[68:71], v[206:209], v[198:201], v[68:71]
	v_mfma_f32_16x16x32_bf16 v[64:67], v[214:217], v[198:201], v[64:67]
	s_setprio 0
	v_mov_b32_e32 v80, v160
	s_mov_b32 m0, s47
	s_barrier
	ds_read_b128 v[148:151], v171 offset:16384
	ds_read_b128 v[152:155], v171 offset:17408
	ds_read_b128 v[172:175], v171 offset:18432
	ds_read_b128 v[176:179], v171 offset:19456
	ds_read_b128 v[184:187], v171 offset:20480
	ds_read_b128 v[190:193], v171 offset:21504
	ds_read_b128 v[194:197], v171 offset:22528
	ds_read_b128 v[198:201], v171 offset:23552
	s_nop 0
	global_load_lds_dwordx4 v80, s[42:43]
	v_mov_b32_e32 v80, v162
	s_mov_b32 m0, s48
	s_nop 0
	global_load_lds_dwordx4 v80, s[42:43]
	s_barrier
	s_waitcnt lgkmcnt(0)
	s_setprio 1
	s_waitcnt lgkmcnt(0)
	v_mfma_f32_16x16x32_bf16 v[60:63], v[132:135], v[148:151], v[60:63]
	v_mfma_f32_16x16x32_bf16 v[56:59], v[140:143], v[148:151], v[56:59]
	v_mfma_f32_16x16x32_bf16 v[44:47], v[132:135], v[172:175], v[44:47]
	v_mfma_f32_16x16x32_bf16 v[40:43], v[140:143], v[172:175], v[40:43]
	v_mfma_f32_16x16x32_bf16 v[28:31], v[132:135], v[184:187], v[28:31]
	v_mfma_f32_16x16x32_bf16 v[24:27], v[140:143], v[184:187], v[24:27]
	v_mfma_f32_16x16x32_bf16 v[12:15], v[132:135], v[194:197], v[12:15]
	v_mfma_f32_16x16x32_bf16 v[8:11], v[140:143], v[194:197], v[8:11]
	v_mfma_f32_16x16x32_bf16 v[60:63], v[136:139], v[152:155], v[60:63]
	v_mfma_f32_16x16x32_bf16 v[56:59], v[144:147], v[152:155], v[56:59]
	v_mfma_f32_16x16x32_bf16 v[44:47], v[136:139], v[176:179], v[44:47]
	v_mfma_f32_16x16x32_bf16 v[40:43], v[144:147], v[176:179], v[40:43]
	v_mfma_f32_16x16x32_bf16 v[28:31], v[136:139], v[190:193], v[28:31]
	v_mfma_f32_16x16x32_bf16 v[24:27], v[144:147], v[190:193], v[24:27]
	v_mfma_f32_16x16x32_bf16 v[12:15], v[136:139], v[198:201], v[12:15]
	v_mfma_f32_16x16x32_bf16 v[8:11], v[144:147], v[198:201], v[8:11]
	s_setprio 0
	s_barrier
; #define G_STAGE(bufoff, gbase, voff) do { _Pragma("unroll") for (int _i = 0; _i < 2; ++_i) { unsigned _vo = (voff)[_i]; asm volatile("" : "+v"(_vo));   \
;     __builtin_amdgcn_global_load_lds((const unsigned*)((const char*)(gbase) + _vo), (LAS unsigned*)(lds + (bufoff) + ldsw + _i * 8192), 16, 0, 0); } } while (0)
; #define G_LDA(dst, b, h) do { _Pragma("unroll") for (int m = 0; m < 4; ++m) _Pragma("unroll") for (int k = 0; k < 2; ++k) dst[m][k] = *(const LAS bf16x8*)(lds + G_SA(b, h) + aoff + m * 2048 + k * 1024); } while (0)
; #define G_LDB(dst, b, h) do { _Pragma("unroll") for (int n = 0; n < 2; ++n) _Pragma("unroll") for (int k = 0; k < 2; ++k) dst[n][k] = *(const LAS bf16x8*)(lds + G_SB(b, h) + boff + n * 2048 + k * 1024); } while (0)
; #define G_MMA(ai, bj, At, Bt) do { __builtin_amdgcn_s_setprio(1); _Pragma("unroll") for (int m = 0; m < 4; ++m) _Pragma("unroll") for (int n = 0; n < 2; ++n) _Pragma("unroll") for (int k = 0; k < 2; ++k) \
;     acc[ai][bj][m][n] = __builtin_amdgcn_mfma_f32_16x16x32_bf16(Bt[n][k], At[m][k], acc[ai][bj][m][n], 0, 0, 0); __builtin_amdgcn_s_setprio(0); } while (0)
; #define G_WAIT_V(n) asm volatile("s_waitcnt vmcnt(" #n ")" ::: "memory")
; #define G_WAIT_L(n) asm volatile("s_waitcnt lgkmcnt(" #n ")" ::: "memory")
; #define G_BAR __builtin_amdgcn_s_barrier()
; #define G_SCHED __builtin_amdgcn_sched_barrier(0)
; template <class Epi>
; __device__ __forceinline__ void gemm_phase(LAS unsigned char* lds, const int K, const unsigned lda_b, const unsigned ldb_b, const Map& M, const Epi& E) {
;     ...
;       G_WAIT_V(6); G_BAR; G_MMA(1, 1, At, B1); G_BAR;
;       G_LDB(B0, 1, 0); G_SCHED; G_LDA(At, 1, 0); G_STAGE(G_SA(0, 1), a2h1, voffA);
;       G_WAIT_L(8); G_BAR; G_WAIT_L(0); G_MMA(0, 0, At, B0); G_BAR; G_SCHED;
;       G_LDB(B1, 1, 1); G_STAGE(G_SB(1, 0), b2h0 + kstep, voffB);
;       G_BAR; G_WAIT_L(0); G_MMA(0, 1, At, B1); G_BAR;
;       G_LDA(At, 1, 1); G_STAGE(G_SA(1, 0), a2h0 + kstep, voffA);
;       G_BAR; G_WAIT_L(0); G_MMA(1, 0, At, B0); G_BAR; G_SCHED;
	v_mov_b32_e32 v80, v161
	s_add_i32 s22, s22, s46
	s_mov_b32 m0, s22
	s_nop 0
	global_load_lds_dwordx4 v80, s[38:39]
	v_mov_b32_e32 v80, v163
	s_add_i32 m0, s22, 0x2000
	s_nop 0
	global_load_lds_dwordx4 v80, s[38:39]
	s_waitcnt vmcnt(6)
	s_barrier
	s_setprio 1
	v_mfma_f32_16x16x32_bf16 v[52:55], v[202:205], v[148:151], v[52:55]
	v_mfma_f32_16x16x32_bf16 v[48:51], v[210:213], v[148:151], v[48:51]
	v_mfma_f32_16x16x32_bf16 v[36:39], v[202:205], v[172:175], v[36:39]
	v_mfma_f32_16x16x32_bf16 v[32:35], v[210:213], v[172:175], v[32:35]
	v_mfma_f32_16x16x32_bf16 v[20:23], v[202:205], v[184:187], v[20:23]
	v_mfma_f32_16x16x32_bf16 v[16:19], v[210:213], v[184:187], v[16:19]
	v_mfma_f32_16x16x32_bf16 v[4:7], v[202:205], v[194:197], v[4:7]
	v_mfma_f32_16x16x32_bf16 v[0:3], v[210:213], v[194:197], v[0:3]
	v_mfma_f32_16x16x32_bf16 v[52:55], v[206:209], v[152:155], v[52:55]
	v_mfma_f32_16x16x32_bf16 v[48:51], v[214:217], v[152:155], v[48:51]
	v_mfma_f32_16x16x32_bf16 v[36:39], v[206:209], v[176:179], v[36:39]
	v_mfma_f32_16x16x32_bf16 v[32:35], v[214:217], v[176:179], v[32:35]
	v_mfma_f32_16x16x32_bf16 v[20:23], v[206:209], v[190:193], v[20:23]
	v_mfma_f32_16x16x32_bf16 v[16:19], v[214:217], v[190:193], v[16:19]
	v_mfma_f32_16x16x32_bf16 v[4:7], v[206:209], v[198:201], v[4:7]
	v_mfma_f32_16x16x32_bf16 v[0:3], v[214:217], v[198:201], v[0:3]
	s_setprio 0
	s_add_i32 s22, 0, 0x18000
	v_add_u32_e32 v80, s22, v165
	s_barrier
	ds_read_b128 v[132:135], v80
	ds_read_b128 v[136:139], v80 offset:1024
	ds_read_b128 v[140:143], v80 offset:2048
	ds_read_b128 v[144:147], v80 offset:3072
	v_mov_b32_e32 v80, v160
	s_mov_b32 m0, s49
	ds_read_b128 v[148:151], v171 offset:32768
	ds_read_b128 v[152:155], v171 offset:33792
	ds_read_b128 v[172:175], v171 offset:34816
	ds_read_b128 v[176:179], v171 offset:35840
	ds_read_b128 v[184:187], v171 offset:36864
	ds_read_b128 v[190:193], v171 offset:37888
	ds_read_b128 v[194:197], v171 offset:38912
	ds_read_b128 v[198:201], v171 offset:39936
	s_nop 0
	global_load_lds_dwordx4 v80, s[68:69]
	v_mov_b32_e32 v80, v162
	s_mov_b32 m0, s66
	s_nop 0
	global_load_lds_dwordx4 v80, s[68:69]
	s_waitcnt lgkmcnt(8)
	s_barrier
	s_waitcnt lgkmcnt(0)
	s_setprio 1
	s_waitcnt lgkmcnt(0)
	v_mfma_f32_16x16x32_bf16 v[128:131], v[132:135], v[148:151], v[128:131]
	v_mfma_f32_16x16x32_bf16 v[124:127], v[140:143], v[148:151], v[124:127]
	v_mfma_f32_16x16x32_bf16 v[110:113], v[132:135], v[172:175], v[110:113]
	v_mfma_f32_16x16x32_bf16 v[106:109], v[140:143], v[172:175], v[106:109]
	v_mfma_f32_16x16x32_bf16 v[94:97], v[132:135], v[184:187], v[94:97]
	v_mfma_f32_16x16x32_bf16 v[90:93], v[140:143], v[184:187], v[90:93]
	v_mfma_f32_16x16x32_bf16 v[76:79], v[132:135], v[194:197], v[76:79]
	v_mfma_f32_16x16x32_bf16 v[72:75], v[140:143], v[194:197], v[72:75]
	v_mfma_f32_16x16x32_bf16 v[128:131], v[136:139], v[152:155], v[128:131]
	v_mfma_f32_16x16x32_bf16 v[124:127], v[144:147], v[152:155], v[124:127]
	v_mfma_f32_16x16x32_bf16 v[110:113], v[136:139], v[176:179], v[110:113]
	v_mfma_f32_16x16x32_bf16 v[106:109], v[144:147], v[176:179], v[106:109]
	v_mfma_f32_16x16x32_bf16 v[94:97], v[136:139], v[190:193], v[94:97]
	v_mfma_f32_16x16x32_bf16 v[90:93], v[144:147], v[190:193], v[90:93]
	v_mfma_f32_16x16x32_bf16 v[76:79], v[136:139], v[198:201], v[76:79]
	v_mfma_f32_16x16x32_bf16 v[72:75], v[144:147], v[198:201], v[72:75]
	s_setprio 0
	s_barrier
	s_add_i32 s30, 0, 0x1c000
	v_add_u32_e32 v80, s30, v165
	ds_read_b128 v[202:205], v80
	ds_read_b128 v[206:209], v80 offset:1024
	ds_read_b128 v[210:213], v80 offset:2048
	ds_read_b128 v[214:217], v80 offset:3072
	v_mov_b32_e32 v80, v161
	s_add_i32 s22, s22, s46
	s_add_i32 m0, s22, 0xffffff80
	v_mov_b32_e32 v80, v163
	global_load_lds_dwordx4 v161, s[44:45] offset:128
	s_add_i32 m0, s22, 0x1f80
	s_nop 0
	global_load_lds_dwordx4 v163, s[44:45] offset:128
	s_barrier
	s_waitcnt lgkmcnt(0)
	s_setprio 1
	s_waitcnt lgkmcnt(0)
	v_mfma_f32_16x16x32_bf16 v[118:121], v[202:205], v[148:151], v[118:121]
	v_mfma_f32_16x16x32_bf16 v[114:117], v[210:213], v[148:151], v[114:117]
	v_mfma_f32_16x16x32_bf16 v[102:105], v[202:205], v[172:175], v[102:105]
	v_mfma_f32_16x16x32_bf16 v[98:101], v[210:213], v[172:175], v[98:101]
	v_mfma_f32_16x16x32_bf16 v[86:89], v[202:205], v[184:187], v[86:89]
	v_mfma_f32_16x16x32_bf16 v[82:85], v[210:213], v[184:187], v[82:85]
	v_mfma_f32_16x16x32_bf16 v[68:71], v[202:205], v[194:197], v[68:71]
	v_mfma_f32_16x16x32_bf16 v[64:67], v[210:213], v[194:197], v[64:67]
	v_mfma_f32_16x16x32_bf16 v[118:121], v[206:209], v[152:155], v[118:121]
	v_mfma_f32_16x16x32_bf16 v[114:117], v[214:217], v[152:155], v[114:117]
	v_mfma_f32_16x16x32_bf16 v[102:105], v[206:209], v[176:179], v[102:105]
	v_mfma_f32_16x16x32_bf16 v[98:101], v[214:217], v[176:179], v[98:101]
	v_mfma_f32_16x16x32_bf16 v[86:89], v[206:209], v[190:193], v[86:89]
	v_mfma_f32_16x16x32_bf16 v[82:85], v[214:217], v[190:193], v[82:85]
	v_mfma_f32_16x16x32_bf16 v[68:71], v[206:209], v[198:201], v[68:71]
	v_mfma_f32_16x16x32_bf16 v[64:67], v[214:217], v[198:201], v[64:67]
	s_setprio 0
	v_mov_b32_e32 v80, v160
	s_barrier
	ds_read_b128 v[148:151], v171 offset:49152
	ds_read_b128 v[152:155], v171 offset:50176
	ds_read_b128 v[172:175], v171 offset:51200
	ds_read_b128 v[176:179], v171 offset:52224
	ds_read_b128 v[184:187], v171 offset:53248
	ds_read_b128 v[190:193], v171 offset:54272
	ds_read_b128 v[194:197], v171 offset:55296
	ds_read_b128 v[198:201], v171 offset:56320
	s_add_i32 m0, s67, 0xffffff80
	v_mov_b32_e32 v80, v162
	global_load_lds_dwordx4 v160, s[42:43] offset:128
	s_add_i32 m0, s81, 0xffffff80
	s_nop 0
	global_load_lds_dwordx4 v162, s[42:43] offset:128
	s_barrier
; __device__ __forceinline__ float bf_lo(unsigned u) { return __uint_as_float(u << 16); }
; __device__ __forceinline__ float bf_hi(unsigned u) { return __uint_as_float(u & 0xffff0000u); }
; __device__ __forceinline__ float sigmoidf_(float x) { return 1.f / (1.f + __expf(-x)); }
; __device__ __forceinline__ float rinv_of(unsigned long long ss) { return rsqrtf((float)ss * (1.f / 16777216.f) * (1.f / DM) + 1e-6f); }
; #define G_LDA(dst, b, h) do { _Pragma("unroll") for (int m = 0; m < 4; ++m) _Pragma("unroll") for (int k = 0; k < 2; ++k) dst[m][k] = *(const LAS bf16x8*)(lds + G_SA(b, h) + aoff + m * 2048 + k * 1024); } while (0)
; #define G_BAR __builtin_amdgcn_s_barrier()
;   __device__ __forceinline__ void operator()(const f32x4 (&acc)[2][2][4][2], const Unit& u, const EpiCtx& x_, int wr, int wc, int fr, int fq) const {
;     ...
;         const int row = (u.r0 + (ai ? x_.rdelta : 0)) + wr * 64 + m * 16 + fr;
;         const bf16_t* pep = (const bf16_t*)x_.aux + (size_t)row * DM;
;         const bf16_t* xin = (const bf16_t*)x_.aux2 + (size_t)row * DM;
;         bf16_t* xbp = x_.xb + (size_t)row * DM;
;         const float rs = rinv_of(x_.ss[row]);
;         float sq = 0.f;
; #pragma unroll
;         for (int bj = 0; bj < 2; ++bj) {
;           const int cb = u.c0 + wc * 64 + bj * 32 + 8 * fq;
;           const uint4 pe = *(const uint4*)(pep + cb), xi = *(const uint4*)(xin + cb);
;           const f32x4 a = acc[ai][bj][m][0] * rs, b = acc[ai][bj][m][1] * rs;
;           f32x4 xa, xc;
;           xa[0] = bf_lo(xi.x) + bf_lo(pe.x) * sigmoidf_(a[0]); xa[1] = bf_hi(xi.x) + bf_hi(pe.x) * sigmoidf_(a[1]);
; template <class Epi>
; __device__ __forceinline__ void gemm_phase(LAS unsigned char* lds, const int K, const unsigned lda_b, const unsigned ldb_b, const Map& M, const Epi& E) {
;     ...
;       G_WAIT_V(6); G_BAR; G_MMA(1, 1, At, B1); G_BAR;
;       G_LDB(B0, 1, 0); G_SCHED; G_LDA(At, 1, 0); G_STAGE(G_SA(0, 1), a2h1, voffA);
;       G_WAIT_L(8); G_BAR; G_WAIT_L(0); G_MMA(0, 0, At, B0); G_BAR; G_SCHED;
;       G_LDB(B1, 1, 1); G_STAGE(G_SB(1, 0), b2h0 + kstep, voffB);
;       G_BAR; G_WAIT_L(0); G_MMA(0, 1, At, B1); G_BAR;
;       G_LDA(At, 1, 1); G_STAGE(G_SA(1, 0), a2h0 + kstep, voffA);
;       G_BAR; G_WAIT_L(0); G_MMA(1, 0, At, B0); G_BAR; G_SCHED;
;       G_STAGE(G_SB(1, 1), b2h1 + kstep, voffB);
;       G_WAIT_V(6); G_BAR; G_MMA(1, 1, At, B1); G_BAR;
	s_waitcnt lgkmcnt(0)
	s_setprio 1
	s_waitcnt lgkmcnt(0)
	v_mfma_f32_16x16x32_bf16 v[60:63], v[132:135], v[148:151], v[60:63]
	v_mfma_f32_16x16x32_bf16 v[56:59], v[140:143], v[148:151], v[56:59]
	v_mfma_f32_16x16x32_bf16 v[44:47], v[132:135], v[172:175], v[44:47]
	v_mfma_f32_16x16x32_bf16 v[40:43], v[140:143], v[172:175], v[40:43]
	v_mfma_f32_16x16x32_bf16 v[28:31], v[132:135], v[184:187], v[28:31]
	v_mfma_f32_16x16x32_bf16 v[24:27], v[140:143], v[184:187], v[24:27]
	v_mfma_f32_16x16x32_bf16 v[12:15], v[132:135], v[194:197], v[12:15]
	v_mfma_f32_16x16x32_bf16 v[8:11], v[140:143], v[194:197], v[8:11]
	v_mfma_f32_16x16x32_bf16 v[60:63], v[136:139], v[152:155], v[60:63]
	v_mfma_f32_16x16x32_bf16 v[56:59], v[144:147], v[152:155], v[56:59]
	v_mfma_f32_16x16x32_bf16 v[44:47], v[136:139], v[176:179], v[44:47]
	v_mfma_f32_16x16x32_bf16 v[40:43], v[144:147], v[176:179], v[40:43]
	v_mfma_f32_16x16x32_bf16 v[28:31], v[136:139], v[190:193], v[28:31]
	v_mfma_f32_16x16x32_bf16 v[24:27], v[144:147], v[190:193], v[24:27]
	v_mfma_f32_16x16x32_bf16 v[12:15], v[136:139], v[198:201], v[12:15]
	v_mfma_f32_16x16x32_bf16 v[8:11], v[144:147], v[198:201], v[8:11]
	s_setprio 0
	s_barrier
	v_mov_b32_e32 v80, v161
	s_add_i32 s22, s30, s46
	s_add_i32 m0, s22, 0xffffff80
	v_mov_b32_e32 v80, v163
	global_load_lds_dwordx4 v161, s[38:39] offset:128
	s_add_i32 m0, s22, 0x1f80
	s_nop 0
	global_load_lds_dwordx4 v163, s[38:39] offset:128
	s_waitcnt vmcnt(6)
	s_barrier
	s_setprio 1
	v_mfma_f32_16x16x32_bf16 v[52:55], v[202:205], v[148:151], v[52:55]
	v_mfma_f32_16x16x32_bf16 v[48:51], v[210:213], v[148:151], v[48:51]
	v_mfma_f32_16x16x32_bf16 v[36:39], v[202:205], v[172:175], v[36:39]
	v_mfma_f32_16x16x32_bf16 v[32:35], v[210:213], v[172:175], v[32:35]
	v_mfma_f32_16x16x32_bf16 v[20:23], v[202:205], v[184:187], v[20:23]
	v_mfma_f32_16x16x32_bf16 v[16:19], v[210:213], v[184:187], v[16:19]
	v_mfma_f32_16x16x32_bf16 v[4:7], v[202:205], v[194:197], v[4:7]
	v_mfma_f32_16x16x32_bf16 v[0:3], v[210:213], v[194:197], v[0:3]
	v_mfma_f32_16x16x32_bf16 v[52:55], v[206:209], v[152:155], v[52:55]
	v_mfma_f32_16x16x32_bf16 v[48:51], v[214:217], v[152:155], v[48:51]
	v_mfma_f32_16x16x32_bf16 v[36:39], v[206:209], v[176:179], v[36:39]
	v_mfma_f32_16x16x32_bf16 v[32:35], v[214:217], v[176:179], v[32:35]
	v_mfma_f32_16x16x32_bf16 v[20:23], v[206:209], v[190:193], v[20:23]
	v_mfma_f32_16x16x32_bf16 v[16:19], v[214:217], v[190:193], v[16:19]
	v_mfma_f32_16x16x32_bf16 v[4:7], v[206:209], v[198:201], v[4:7]
	v_mfma_f32_16x16x32_bf16 v[0:3], v[214:217], v[198:201], v[0:3]
	s_setprio 0
	s_add_i32 s29, s29, 2
	s_add_u32 s19, s19, 0x100
	s_addc_u32 s28, s28, 0
	s_add_u32 s4, s4, 0x100
	s_addc_u32 s5, s5, 0
	s_cmp_gt_u32 s29, 29
	s_barrier
	s_cbranch_scc0 .LBB0_958
	s_nop 1
	v_add_u32_e32 v198, s87, v164
	v_ashrrev_i32_e32 v199, 31, v198
	v_lshl_add_u64 v[200:201], v[198:199], 3, s[96:97]
	global_load_dwordx2 v[174:175], v[200:201], off
	v_lshlrev_b64 v[200:201], 12, v[198:199]
	v_lshl_add_u64 v[202:203], s[92:93], 0, v[200:201]
	v_add_u32_e32 v204, s0, v166
	v_ashrrev_i32_e32 v205, 31, v204
	v_lshlrev_b64 v[206:207], 1, v[204:205]
	v_lshl_add_u64 v[208:209], v[202:203], 0, v[206:207]
	global_load_dwordx4 v[176:179], v[208:209], off
	v_lshl_add_u64 v[208:209], s[94:95], 0, v[200:201]
	v_lshl_add_u64 v[210:211], v[208:209], 0, v[206:207]
	global_load_dwordx4 v[184:187], v[210:211], off
	v_add_u32_e32 v204, s0, v167
	v_ashrrev_i32_e32 v205, 31, v204
	v_lshlrev_b64 v[206:207], 1, v[204:205]
	v_lshl_add_u64 v[210:211], v[202:203], 0, v[206:207]
	global_load_dwordx4 v[190:193], v[210:211], off
	v_lshl_add_u64 v[202:203], v[208:209], 0, v[206:207]
	global_load_dwordx4 v[194:197], v[202:203], off
	v_add_u32_e32 v146, s87, v164
	v_ashrrev_i32_e32 v147, 31, v146
	v_readfirstlane_b32 s42, v122
	v_readfirstlane_b32 s43, v123
	v_lshlrev_b64 v[122:123], 12, v[146:147]
	v_lshl_add_u64 v[152:153], s[92:93], 0, v[122:123]
	v_lshl_add_u64 v[150:151], s[94:95], 0, v[122:123]
	v_lshl_add_u64 v[148:149], s[90:91], 0, v[122:123]
	v_lshl_add_u64 v[122:123], v[146:147], 3, s[96:97]
	s_nop 0
	v_add_u32_e32 v140, s0, v166
	v_ashrrev_i32_e32 v141, 31, v140
	v_lshlrev_b64 v[142:143], 1, v[140:141]
	s_cmp_lg_u64 s[36:37], 0
	v_lshlrev_b64 v[144:145], 11, v[146:147]
	s_cselect_b64 s[38:39], -1, 0
	s_cmp_eq_u64 s[36:37], 0
	s_waitcnt lgkmcnt(0)
	s_nop 0
	s_nop 0
	s_nop 0
	s_nop 0
	s_nop 0
	s_nop 0
	s_nop 0
	s_nop 0
	s_nop 0
	s_nop 0
	s_nop 0
	s_nop 0
	s_nop 0
	s_nop 0
	s_waitcnt vmcnt(4)
	v_ffbh_u32_e32 v80, v175
	v_min_u32_e32 v80, 32, v80
	v_lshlrev_b64 v[122:123], v80, v[174:175]
	v_min_u32_e32 v122, 1, v122
	v_or_b32_e32 v122, v123, v122
	v_cvt_f32_u32_e32 v122, v122
	v_sub_u32_e32 v80, 32, v80
	v_ldexp_f32 v80, v122, v80
	v_mul_f32_e32 v80, 0x33800000, v80
	v_fmamk_f32 v80, v80, 0x3a000000, v234
	v_cmp_gt_f32_e32 vcc, s50, v80
	v_mul_f32_e32 v122, 0x4b800000, v80
	s_nop 0
	v_cndmask_b32_e32 v80, v80, v122, vcc
	v_rsq_f32_e32 v80, v80
	s_nop 0
	v_mul_f32_e32 v122, 0x45800000, v80
	v_cndmask_b32_e32 v154, v80, v122, vcc
	v_lshl_add_u64 v[122:123], v[152:153], 0, v[142:143]
	s_nop 0
	v_lshl_add_u64 v[122:123], v[150:151], 0, v[142:143]
	s_nop 0
	v_pk_mul_f32 v[122:123], v[128:129], v[154:155] op_sel_hi:[1,0]
	v_pk_mul_f32 v[128:129], v[126:127], v[154:155] op_sel_hi:[1,0]
	v_mul_f32_e32 v80, 0xbfb8aa3b, v122
	v_exp_f32_e32 v122, v80
	v_mul_f32_e32 v80, 0xbfb8aa3b, v123
	v_exp_f32_e32 v123, v80
	v_pk_mul_f32 v[126:127], v[124:125], v[154:155] op_sel_hi:[1,0]
	v_pk_mul_f32 v[130:131], v[130:131], v[154:155] op_sel_hi:[1,0]
	v_pk_add_f32 v[122:123], v[122:123], 1.0 op_sel_hi:[1,0]
	s_nop 0
	v_div_scale_f32 v80, s[4:5], v123, v123, 1.0
	s_waitcnt lgkmcnt(0)
; __device__ __forceinline__ unsigned cvt_pk_bf16(float lo, float hi) { unsigned r; asm("v_cvt_pk_bf16_f32 %0, %1, %2" : "=v"(r) : "v"(lo), "v"(hi)); return r; }
; __device__ __forceinline__ float bf_lo(unsigned u) { return __uint_as_float(u << 16); }
; __device__ __forceinline__ float bf_hi(unsigned u) { return __uint_as_float(u & 0xffff0000u); }
; __device__ __forceinline__ float sigmoidf_(float x) { return 1.f / (1.f + __expf(-x)); }
; __device__ __forceinline__ float rinv_of(unsigned long long ss) { return rsqrtf((float)ss * (1.f / 16777216.f) * (1.f / DM) + 1e-6f); }
;   __device__ __forceinline__ void operator()(const f32x4 (&acc)[2][2][4][2], const Unit& u, const EpiCtx& x_, int wr, int wc, int fr, int fq) const {
;     ...
;         const float rs = rinv_of(x_.ss[row]);
;         float sq = 0.f;
; #pragma unroll
;         for (int bj = 0; bj < 2; ++bj) {
;           const int cb = u.c0 + wc * 64 + bj * 32 + 8 * fq;
;           const uint4 pe = *(const uint4*)(pep + cb), xi = *(const uint4*)(xin + cb);
;           const f32x4 a = acc[ai][bj][m][0] * rs, b = acc[ai][bj][m][1] * rs;
;           f32x4 xa, xc;
;           xa[0] = bf_lo(xi.x) + bf_lo(pe.x) * sigmoidf_(a[0]); xa[1] = bf_hi(xi.x) + bf_hi(pe.x) * sigmoidf_(a[1]);
;           xa[2] = bf_lo(xi.y) + bf_lo(pe.y) * sigmoidf_(a[2]); xa[3] = bf_hi(xi.y) + bf_hi(pe.y) * sigmoidf_(a[3]);
;           xc[0] = bf_lo(xi.z) + bf_lo(pe.z) * sigmoidf_(b[0]); xc[1] = bf_hi(xi.z) + bf_hi(pe.z) * sigmoidf_(b[1]);
;           xc[2] = bf_lo(xi.w) + bf_lo(pe.w) * sigmoidf_(b[2]); xc[3] = bf_hi(xi.w) + bf_hi(pe.w) * sigmoidf_(b[3]);
;           sq += xa[0] * xa[0] + xa[1] * xa[1] + xa[2] * xa[2] + xa[3] * xa[3] + xc[0] * xc[0] + xc[1] * xc[1] + xc[2] * xc[2] + xc[3] * xc[3];
;           uint4 o; o.x = cvt_pk_bf16(xa[0], xa[1]); o.y = cvt_pk_bf16(xa[2], xa[3]); o.z = cvt_pk_bf16(xc[0], xc[1]); o.w = cvt_pk_bf16(xc[2], xc[3]);
;           *(uint4*)(xbp + cb) = o;
;           if (last) { float* op = (float*)u.C + (size_t)row * DM + cb; *(f32x4*)op = xa; *(f32x4*)(op + 4) = xc; }
	s_nop 0
	s_nop 0
	s_nop 0
	s_nop 0
	s_nop 0
	s_nop 0
	s_nop 0
	s_nop 0
	s_nop 0
	s_nop 0
	s_nop 0
	s_nop 0
	s_nop 0
	s_nop 0
	s_waitcnt vmcnt(3)
	v_lshlrev_b32_e32 v156, 16, v176
	v_and_b32_e32 v157, 0xffff0000, v176
	v_rcp_f32_e32 v132, v80
	s_nop 0
	s_nop 0
	s_nop 0
	s_nop 0
	s_nop 0
	s_nop 0
	s_nop 0
	s_nop 0
	s_nop 0
	s_nop 0
	s_nop 0
	s_nop 0
	s_nop 0
	s_nop 0
	s_waitcnt vmcnt(2)
	v_lshlrev_b32_e32 v124, 16, v184
	v_and_b32_e32 v125, 0xffff0000, v184
	v_fma_f32 v136, -v80, v132, 1.0
	v_fmac_f32_e32 v132, v136, v132
	v_div_scale_f32 v136, vcc, 1.0, v123, 1.0
	v_mul_f32_e32 v155, v136, v132
	v_fma_f32 v172, -v80, v155, v136
	v_fmac_f32_e32 v155, v172, v132
	v_fma_f32 v80, -v80, v155, v136
	v_div_fmas_f32 v80, v80, v132, v155
	v_div_fixup_f32 v123, v80, v123, 1.0
	v_div_scale_f32 v80, s[4:5], v122, v122, 1.0
	v_rcp_f32_e32 v132, v80
	s_nop 0
	v_fma_f32 v136, -v80, v132, 1.0
	v_fmac_f32_e32 v132, v136, v132
	v_div_scale_f32 v136, vcc, 1.0, v122, 1.0
	v_mul_f32_e32 v155, v136, v132
	v_fma_f32 v172, -v80, v155, v136
	v_fmac_f32_e32 v155, v172, v132
	v_fma_f32 v80, -v80, v155, v136
	v_div_fmas_f32 v80, v80, v132, v155
	v_div_fixup_f32 v122, v80, v122, 1.0
	v_mul_f32_e32 v80, 0xbfb8aa3b, v130
	v_exp_f32_e32 v130, v80
	v_mul_f32_e32 v80, 0xbfb8aa3b, v131
	v_exp_f32_e32 v131, v80
	v_pk_fma_f32 v[122:123], v[122:123], v[156:157], v[124:125]
	v_lshlrev_b32_e32 v124, 16, v185
	v_and_b32_e32 v125, 0xffff0000, v185
	v_pk_add_f32 v[130:131], v[130:131], 1.0 op_sel_hi:[1,0]
	v_lshlrev_b32_e32 v132, 16, v177
	v_div_scale_f32 v80, s[4:5], v131, v131, 1.0
	v_rcp_f32_e32 v136, v80
	v_and_b32_e32 v133, 0xffff0000, v177
	v_fma_f32 v137, -v80, v136, 1.0
	v_fmac_f32_e32 v136, v137, v136
	v_div_scale_f32 v137, vcc, 1.0, v131, 1.0
	v_mul_f32_e32 v155, v137, v136
	v_fma_f32 v156, -v80, v155, v137
	v_fmac_f32_e32 v155, v156, v136
	v_fma_f32 v80, -v80, v155, v137
	v_div_fmas_f32 v80, v80, v136, v155
	v_div_fixup_f32 v131, v80, v131, 1.0
	v_div_scale_f32 v80, s[4:5], v130, v130, 1.0
	v_rcp_f32_e32 v136, v80
	s_nop 0
	v_fma_f32 v137, -v80, v136, 1.0
	v_fmac_f32_e32 v136, v137, v136
	v_div_scale_f32 v137, vcc, 1.0, v130, 1.0
	v_mul_f32_e32 v155, v137, v136
	v_fma_f32 v156, -v80, v155, v137
	v_fmac_f32_e32 v155, v156, v136
	v_fma_f32 v80, -v80, v155, v137
	v_div_fmas_f32 v80, v80, v136, v155
	v_div_fixup_f32 v130, v80, v130, 1.0
	v_mul_f32_e32 v80, 0xbfb8aa3b, v126
	v_exp_f32_e32 v126, v80
	v_mul_f32_e32 v80, 0xbfb8aa3b, v127
	v_exp_f32_e32 v127, v80
	v_pk_fma_f32 v[124:125], v[130:131], v[132:133], v[124:125]
	v_lshlrev_b32_e32 v132, 16, v178
	v_and_b32_e32 v133, 0xffff0000, v178
	v_pk_add_f32 v[126:127], v[126:127], 1.0 op_sel_hi:[1,0]
	v_lshlrev_b32_e32 v130, 16, v186
	v_div_scale_f32 v80, s[4:5], v127, v127, 1.0
	v_rcp_f32_e32 v134, v80
	v_and_b32_e32 v131, 0xffff0000, v186
	v_lshl_add_u64 v[156:157], v[144:145], 2, s[36:37]
	v_fma_f32 v136, -v80, v134, 1.0
	v_fmac_f32_e32 v134, v136, v134
	v_div_scale_f32 v136, vcc, 1.0, v127, 1.0
	v_mul_f32_e32 v137, v136, v134
	v_fma_f32 v138, -v80, v137, v136
	v_fmac_f32_e32 v137, v138, v134
	v_fma_f32 v80, -v80, v137, v136
	v_div_fmas_f32 v80, v80, v134, v137
	v_div_fixup_f32 v127, v80, v127, 1.0
	v_div_scale_f32 v80, s[4:5], v126, v126, 1.0
	v_rcp_f32_e32 v134, v80
	s_nop 0
	v_fma_f32 v136, -v80, v134, 1.0
	v_fmac_f32_e32 v134, v136, v134
	v_div_scale_f32 v136, vcc, 1.0, v126, 1.0
	v_mul_f32_e32 v137, v136, v134
	v_fma_f32 v138, -v80, v137, v136
	v_fmac_f32_e32 v137, v138, v134
	v_fma_f32 v80, -v80, v137, v136
	v_div_fmas_f32 v80, v80, v134, v137
	v_div_fixup_f32 v126, v80, v126, 1.0
	v_mul_f32_e32 v80, 0xbfb8aa3b, v128
	v_exp_f32_e32 v128, v80
	v_mul_f32_e32 v80, 0xbfb8aa3b, v129
	v_exp_f32_e32 v129, v80
	v_pk_fma_f32 v[126:127], v[126:127], v[132:133], v[130:131]
	v_lshlrev_b32_e32 v132, 16, v179
	v_and_b32_e32 v133, 0xffff0000, v179
	v_pk_add_f32 v[128:129], v[128:129], 1.0 op_sel_hi:[1,0]
	v_lshlrev_b32_e32 v130, 16, v187
	v_div_scale_f32 v80, s[4:5], v129, v129, 1.0
	v_rcp_f32_e32 v134, v80
	v_and_b32_e32 v131, 0xffff0000, v187
	v_fma_f32 v135, -v80, v134, 1.0
	v_fmac_f32_e32 v134, v135, v134
	v_div_scale_f32 v135, vcc, 1.0, v129, 1.0
	v_mul_f32_e32 v136, v135, v134
	v_fma_f32 v137, -v80, v136, v135
	v_fmac_f32_e32 v136, v137, v134
	v_fma_f32 v80, -v80, v136, v135
	v_div_fmas_f32 v80, v80, v134, v136
	v_div_fixup_f32 v129, v80, v129, 1.0
	v_div_scale_f32 v80, s[4:5], v128, v128, 1.0
	v_rcp_f32_e32 v134, v80
	s_nop 0
	v_fma_f32 v135, -v80, v134, 1.0
	v_fmac_f32_e32 v134, v135, v134
	v_div_scale_f32 v135, vcc, 1.0, v128, 1.0
	v_mul_f32_e32 v136, v135, v134
	v_fma_f32 v137, -v80, v136, v135
	v_fmac_f32_e32 v136, v137, v134
	v_fma_f32 v80, -v80, v136, v135
	v_div_fmas_f32 v80, v80, v134, v136
	v_div_fixup_f32 v128, v80, v128, 1.0
	v_pk_fma_f32 v[128:129], v[128:129], v[132:133], v[130:131]
	v_lshl_add_u64 v[134:135], v[148:149], 0, v[142:143]
	v_cvt_pk_bf16_f32 v130, v122, v123
	v_cvt_pk_bf16_f32 v131, v124, v125
	v_cvt_pk_bf16_f32 v132, v126, v127
	v_cvt_pk_bf16_f32 v133, v128, v129
	global_store_dwordx4 v[134:135], v[130:133], off nt
	s_cbranch_scc1 .LBB0_961
	s_nop 0
	v_lshl_add_u64 v[130:131], v[140:141], 2, v[156:157]
	global_store_dwordx4 v[130:131], v[122:125], off nt
	global_store_dwordx4 v[130:131], v[126:129], off offset:16 nt
; __device__ __forceinline__ unsigned cvt_pk_bf16(float lo, float hi) { unsigned r; asm("v_cvt_pk_bf16_f32 %0, %1, %2" : "=v"(r) : "v"(lo), "v"(hi)); return r; }
; __device__ __forceinline__ float bf_lo(unsigned u) { return __uint_as_float(u << 16); }
; __device__ __forceinline__ float bf_hi(unsigned u) { return __uint_as_float(u & 0xffff0000u); }
; __device__ __forceinline__ float sigmoidf_(float x) { return 1.f / (1.f + __expf(-x)); }
;   __device__ __forceinline__ void operator()(const f32x4 (&acc)[2][2][4][2], const Unit& u, const EpiCtx& x_, int wr, int wc, int fr, int fq) const {
;     ...
;         for (int bj = 0; bj < 2; ++bj) {
;           const int cb = u.c0 + wc * 64 + bj * 32 + 8 * fq;
;           const uint4 pe = *(const uint4*)(pep + cb), xi = *(const uint4*)(xin + cb);
;           const f32x4 a = acc[ai][bj][m][0] * rs, b = acc[ai][bj][m][1] * rs;
;           f32x4 xa, xc;
;           xa[0] = bf_lo(xi.x) + bf_lo(pe.x) * sigmoidf_(a[0]); xa[1] = bf_hi(xi.x) + bf_hi(pe.x) * sigmoidf_(a[1]);
;           xa[2] = bf_lo(xi.y) + bf_lo(pe.y) * sigmoidf_(a[2]); xa[3] = bf_hi(xi.y) + bf_hi(pe.y) * sigmoidf_(a[3]);
;           xc[0] = bf_lo(xi.z) + bf_lo(pe.z) * sigmoidf_(b[0]); xc[1] = bf_hi(xi.z) + bf_hi(pe.z) * sigmoidf_(b[1]);
;           xc[2] = bf_lo(xi.w) + bf_lo(pe.w) * sigmoidf_(b[2]); xc[3] = bf_hi(xi.w) + bf_hi(pe.w) * sigmoidf_(b[3]);
;           sq += xa[0] * xa[0] + xa[1] * xa[1] + xa[2] * xa[2] + xa[3] * xa[3] + xc[0] * xc[0] + xc[1] * xc[1] + xc[2] * xc[2] + xc[3] * xc[3];
;           uint4 o; o.x = cvt_pk_bf16(xa[0], xa[1]); o.y = cvt_pk_bf16(xa[2], xa[3]); o.z = cvt_pk_bf16(xc[0], xc[1]); o.w = cvt_pk_bf16(xc[2], xc[3]);
;           *(uint4*)(xbp + cb) = o;
;           if (last) { float* op = (float*)u.C + (size_t)row * DM + cb; *(f32x4*)op = xa; *(f32x4*)(op + 4) = xc; }
.LBB0_961:
	s_nop 1
	v_add_u32_e32 v198, s87, v168
	v_ashrrev_i32_e32 v199, 31, v198
	v_lshl_add_u64 v[200:201], v[198:199], 3, s[96:97]
	global_load_dwordx2 v[174:175], v[200:201], off
	v_lshlrev_b64 v[200:201], 12, v[198:199]
	v_lshl_add_u64 v[202:203], s[94:95], 0, v[200:201]
	v_lshl_add_u64 v[204:205], v[202:203], 0, v[142:143]
	global_load_dwordx4 v[176:179], v[204:205], off
	v_lshl_add_u64 v[202:203], s[92:93], 0, v[200:201]
	v_lshl_add_u64 v[204:205], v[202:203], 0, v[142:143]
	global_load_dwordx4 v[184:187], v[204:205], off
	v_add_u32_e32 v138, s0, v167
	v_ashrrev_i32_e32 v139, 31, v138
	v_lshlrev_b64 v[144:145], 1, v[138:139]
	v_lshl_add_u64 v[130:131], v[152:153], 0, v[144:145]
	s_nop 0
	v_lshl_add_u64 v[134:135], v[150:151], 0, v[144:145]
	s_nop 0
	v_mov_b32_e32 v155, v154
	v_pk_mul_f32 v[172:173], v[118:119], v[154:155]
	v_mov_b32_e32 v150, v154
	v_mov_b32_e32 v151, v154
	v_mul_f32_e32 v80, 0xbfb8aa3b, v172
	v_pk_mul_f32 v[152:153], v[120:121], v[150:151]
	v_pk_mul_f32 v[120:121], v[116:117], v[150:151]
	v_exp_f32_e32 v150, v80
	v_mul_f32_e32 v80, 0xbfb8aa3b, v173
	v_exp_f32_e32 v151, v80
	v_pk_mul_f32 v[118:119], v[114:115], v[154:155]
	v_pk_add_f32 v[150:151], v[150:151], 1.0 op_sel_hi:[1,0]
	s_nop 0
	v_div_scale_f32 v80, s[0:1], v151, v151, 1.0
	s_waitcnt lgkmcnt(0)
	s_nop 0
	s_nop 0
	s_nop 0
	s_nop 0
	s_nop 0
	s_nop 0
	s_nop 0
	s_nop 0
	s_nop 0
	s_nop 0
	s_nop 0
	s_nop 0
	s_nop 0
	s_nop 0
	s_waitcnt vmcnt(5)
	v_lshlrev_b32_e32 v116, 16, v190
	v_and_b32_e32 v117, 0xffff0000, v190
	v_rcp_f32_e32 v130, v80
	s_nop 0
	s_nop 0
	s_nop 0
	s_nop 0
	s_nop 0
	s_nop 0
	s_nop 0
	s_nop 0
	s_nop 0
	s_nop 0
	s_nop 0
	s_nop 0
	s_nop 0
	s_nop 0
	s_waitcnt vmcnt(4)
	v_lshlrev_b32_e32 v114, 16, v194
	v_and_b32_e32 v115, 0xffff0000, v194
	v_fma_f32 v134, -v80, v130, 1.0
	v_fmac_f32_e32 v130, v134, v130
	v_div_scale_f32 v134, vcc, 1.0, v151, 1.0
	v_mul_f32_e32 v154, v134, v130
	v_fma_f32 v155, -v80, v154, v134
	v_fmac_f32_e32 v154, v155, v130
	v_fma_f32 v80, -v80, v154, v134
	v_div_fmas_f32 v80, v80, v130, v154
	v_div_fixup_f32 v151, v80, v151, 1.0
	v_div_scale_f32 v80, s[0:1], v150, v150, 1.0
	v_rcp_f32_e32 v130, v80
	s_nop 0
	v_fma_f32 v134, -v80, v130, 1.0
	v_fmac_f32_e32 v130, v134, v130
	v_div_scale_f32 v134, vcc, 1.0, v150, 1.0
	v_mul_f32_e32 v154, v134, v130
	v_fma_f32 v155, -v80, v154, v134
	v_fmac_f32_e32 v154, v155, v130
	v_fma_f32 v80, -v80, v154, v134
	v_div_fmas_f32 v80, v80, v130, v154
	v_div_fixup_f32 v150, v80, v150, 1.0
	v_mul_f32_e32 v80, 0xbfb8aa3b, v152
	v_exp_f32_e32 v134, v80
	v_mul_f32_e32 v80, 0xbfb8aa3b, v153
	v_pk_fma_f32 v[114:115], v[150:151], v[116:117], v[114:115]
	v_lshlrev_b32_e32 v116, 16, v195
	v_and_b32_e32 v117, 0xffff0000, v195
	v_exp_f32_e32 v135, v80
	v_lshlrev_b32_e32 v130, 16, v191
	v_and_b32_e32 v131, 0xffff0000, v191
	v_pk_add_f32 v[134:135], v[134:135], 1.0 op_sel_hi:[1,0]
	s_nop 0
	v_div_scale_f32 v80, s[0:1], v135, v135, 1.0
	v_rcp_f32_e32 v150, v80
	s_nop 0
	v_fma_f32 v151, -v80, v150, 1.0
	v_fmac_f32_e32 v150, v151, v150
	v_div_scale_f32 v151, vcc, 1.0, v135, 1.0
	v_mul_f32_e32 v152, v151, v150
	v_fma_f32 v153, -v80, v152, v151
	v_fmac_f32_e32 v152, v153, v150
	v_fma_f32 v80, -v80, v152, v151
	v_div_fmas_f32 v80, v80, v150, v152
	v_div_fixup_f32 v135, v80, v135, 1.0
	v_div_scale_f32 v80, s[0:1], v134, v134, 1.0
	v_rcp_f32_e32 v150, v80
	s_nop 0
	v_fma_f32 v151, -v80, v150, 1.0
	v_fmac_f32_e32 v150, v151, v150
	v_div_scale_f32 v151, vcc, 1.0, v134, 1.0
	v_mul_f32_e32 v152, v151, v150
	v_fma_f32 v153, -v80, v152, v151
	v_fmac_f32_e32 v152, v153, v150
	v_fma_f32 v80, -v80, v152, v151
	v_div_fmas_f32 v80, v80, v150, v152
	v_div_fixup_f32 v134, v80, v134, 1.0
	v_mul_f32_e32 v80, 0xbfb8aa3b, v118
	v_exp_f32_e32 v118, v80
	v_mul_f32_e32 v80, 0xbfb8aa3b, v119
	v_exp_f32_e32 v119, v80
	v_pk_fma_f32 v[116:117], v[134:135], v[130:131], v[116:117]
	v_lshlrev_b32_e32 v134, 16, v192
	v_and_b32_e32 v135, 0xffff0000, v192
	v_pk_add_f32 v[118:119], v[118:119], 1.0 op_sel_hi:[1,0]
	v_lshlrev_b32_e32 v130, 16, v196
	v_div_scale_f32 v80, s[0:1], v119, v119, 1.0
	v_rcp_f32_e32 v132, v80
	v_and_b32_e32 v131, 0xffff0000, v196
	v_fma_f32 v136, -v80, v132, 1.0
	v_fmac_f32_e32 v132, v136, v132
	v_div_scale_f32 v136, vcc, 1.0, v119, 1.0
	v_mul_f32_e32 v150, v136, v132
	v_fma_f32 v151, -v80, v150, v136
	v_fmac_f32_e32 v150, v151, v132
	v_fma_f32 v80, -v80, v150, v136
	v_div_fmas_f32 v80, v80, v132, v150
	v_div_fixup_f32 v119, v80, v119, 1.0
	v_div_scale_f32 v80, s[0:1], v118, v118, 1.0
	v_rcp_f32_e32 v132, v80
	s_nop 0
	v_fma_f32 v136, -v80, v132, 1.0
	v_fmac_f32_e32 v132, v136, v132
	v_div_scale_f32 v136, vcc, 1.0, v118, 1.0
	v_mul_f32_e32 v150, v136, v132
	v_fma_f32 v151, -v80, v150, v136
	v_fmac_f32_e32 v150, v151, v132
	v_fma_f32 v80, -v80, v150, v136
	v_div_fmas_f32 v80, v80, v132, v150
	v_div_fixup_f32 v118, v80, v118, 1.0
	v_mul_f32_e32 v80, 0xbfb8aa3b, v120
	v_exp_f32_e32 v120, v80
	v_mul_f32_e32 v80, 0xbfb8aa3b, v121
	v_exp_f32_e32 v121, v80
	v_pk_fma_f32 v[118:119], v[118:119], v[134:135], v[130:131]
	v_lshlrev_b32_e32 v130, 16, v197
	v_and_b32_e32 v131, 0xffff0000, v197
	v_pk_add_f32 v[120:121], v[120:121], 1.0 op_sel_hi:[1,0]
	v_lshlrev_b32_e32 v132, 16, v193
	v_div_scale_f32 v80, s[0:1], v121, v121, 1.0
	v_rcp_f32_e32 v134, v80
	v_and_b32_e32 v133, 0xffff0000, v193
	v_fma_f32 v135, -v80, v134, 1.0
	v_fmac_f32_e32 v134, v135, v134
	v_div_scale_f32 v135, vcc, 1.0, v121, 1.0
	v_mul_f32_e32 v136, v135, v134
	v_fma_f32 v137, -v80, v136, v135
	v_fmac_f32_e32 v136, v137, v134
	v_fma_f32 v80, -v80, v136, v135
	v_div_fmas_f32 v80, v80, v134, v136
	v_div_fixup_f32 v121, v80, v121, 1.0
	v_div_scale_f32 v80, s[0:1], v120, v120, 1.0
	v_rcp_f32_e32 v134, v80
	s_nop 0
	v_fma_f32 v135, -v80, v134, 1.0
	v_fmac_f32_e32 v134, v135, v134
	v_div_scale_f32 v135, vcc, 1.0, v120, 1.0
	v_mul_f32_e32 v136, v135, v134
	v_fma_f32 v137, -v80, v136, v135
	v_fmac_f32_e32 v136, v137, v134
	v_fma_f32 v80, -v80, v136, v135
	v_div_fmas_f32 v80, v80, v134, v136
	v_div_fixup_f32 v120, v80, v120, 1.0
	v_cndmask_b32_e64 v80, 0, 1, s[38:39]
	v_pk_fma_f32 v[120:121], v[120:121], v[132:133], v[130:131]
	v_lshl_add_u64 v[134:135], v[148:149], 0, v[144:145]
	v_cmp_ne_u32_e64 s[4:5], 1, v80
	s_andn2_b64 vcc, exec, s[38:39]
	v_cvt_pk_bf16_f32 v130, v114, v115
	v_cvt_pk_bf16_f32 v131, v116, v117
	v_cvt_pk_bf16_f32 v132, v118, v119
	v_cvt_pk_bf16_f32 v133, v120, v121
	global_store_dwordx4 v[134:135], v[130:133], off nt
	s_cbranch_vccnz .LBB0_963
	s_nop 0
	v_lshl_add_u64 v[130:131], v[138:139], 2, v[156:157]
	global_store_dwordx4 v[130:131], v[114:117], off nt
	global_store_dwordx4 v[130:131], v[118:121], off offset:16 nt

; __device__ __forceinline__ float bf_lo(unsigned u) { return __uint_as_float(u << 16); }
; __device__ __forceinline__ float bf_hi(unsigned u) { return __uint_as_float(u & 0xffff0000u); }
; __device__ __forceinline__ float sigmoidf_(float x) { return 1.f / (1.f + __expf(-x)); }
; __device__ __forceinline__ float rinv_of(unsigned long long ss) { return rsqrtf((float)ss * (1.f / 16777216.f) * (1.f / DM) + 1e-6f); }
;   __device__ __forceinline__ void operator()(const f32x4 (&acc)[2][2][4][2], const Unit& u, const EpiCtx& x_, int wr, int wc, int fr, int fq) const {
;     ...
;         const int row = (u.r0 + (ai ? x_.rdelta : 0)) + wr * 64 + m * 16 + fr;
;         const bf16_t* pep = (const bf16_t*)x_.aux + (size_t)row * DM;
;         const bf16_t* xin = (const bf16_t*)x_.aux2 + (size_t)row * DM;
;         bf16_t* xbp = x_.xb + (size_t)row * DM;
;         const float rs = rinv_of(x_.ss[row]);
;         float sq = 0.f;
; #pragma unroll
;         for (int bj = 0; bj < 2; ++bj) {
;           const int cb = u.c0 + wc * 64 + bj * 32 + 8 * fq;
;           const uint4 pe = *(const uint4*)(pep + cb), xi = *(const uint4*)(xin + cb);
;           const f32x4 a = acc[ai][bj][m][0] * rs, b = acc[ai][bj][m][1] * rs;
;           f32x4 xa, xc;
;           xa[0] = bf_lo(xi.x) + bf_lo(pe.x) * sigmoidf_(a[0]); xa[1] = bf_hi(xi.x) + bf_hi(pe.x) * sigmoidf_(a[1]);
.LBB0_965:
	s_or_b64 exec, exec, s[18:19]
	s_nop 1
	v_add_u32_e32 v198, s87, v168
	v_ashrrev_i32_e32 v199, 31, v198
	v_lshlrev_b64 v[200:201], 12, v[198:199]
	v_lshl_add_u64 v[202:203], s[92:93], 0, v[200:201]
	v_lshl_add_u64 v[204:205], v[202:203], 0, v[144:145]
	global_load_dwordx4 v[190:193], v[204:205], off
	v_lshl_add_u64 v[202:203], s[94:95], 0, v[200:201]
	v_lshl_add_u64 v[204:205], v[202:203], 0, v[144:145]
	global_load_dwordx4 v[194:197], v[204:205], off
	v_add_u32_e32 v124, s87, v168
	v_ashrrev_i32_e32 v125, 31, v124
	s_waitcnt lgkmcnt(0)
	v_lshlrev_b64 v[114:115], 12, v[124:125]
	v_lshl_add_u64 v[130:131], s[92:93], 0, v[114:115]
	v_lshl_add_u64 v[128:129], s[94:95], 0, v[114:115]
	v_lshl_add_u64 v[126:127], s[90:91], 0, v[114:115]
	v_lshl_add_u64 v[114:115], v[124:125], 3, s[96:97]
	s_nop 0
	v_lshl_add_u64 v[118:119], v[128:129], 0, v[142:143]
	s_nop 0
	v_lshlrev_b64 v[134:135], 11, v[124:125]
	v_lshl_add_u64 v[134:135], v[134:135], 2, s[36:37]
	s_waitcnt lgkmcnt(0)
	s_nop 0
	s_nop 0
	s_nop 0
	s_nop 0
	s_nop 0
	s_nop 0
	s_nop 0
	s_nop 0
	s_nop 0
	s_nop 0
	s_nop 0
	s_nop 0
	s_nop 0
	s_nop 0
	s_waitcnt vmcnt(5)
	v_ffbh_u32_e32 v116, v175
	v_min_u32_e32 v116, 32, v116
	v_lshlrev_b64 v[114:115], v116, v[174:175]
	v_min_u32_e32 v114, 1, v114
	v_or_b32_e32 v114, v115, v114
	v_cvt_f32_u32_e32 v114, v114
	v_sub_u32_e32 v115, 32, v116
	v_ldexp_f32 v114, v114, v115
	v_mul_f32_e32 v114, 0x33800000, v114
	v_fmamk_f32 v114, v114, 0x3a000000, v234
	v_cmp_gt_f32_e32 vcc, s50, v114
	v_mul_f32_e32 v115, 0x4b800000, v114
	s_nop 0
	v_cndmask_b32_e32 v114, v114, v115, vcc
	v_rsq_f32_e32 v114, v114
	s_nop 0
	v_mul_f32_e32 v115, 0x45800000, v114
	v_cndmask_b32_e32 v132, v114, v115, vcc
	v_lshl_add_u64 v[114:115], v[130:131], 0, v[142:143]
	s_nop 0
	v_pk_mul_f32 v[150:151], v[110:111], v[132:133] op_sel_hi:[1,0]
	v_pk_mul_f32 v[148:149], v[112:113], v[132:133] op_sel_hi:[1,0]
	v_pk_mul_f32 v[112:113], v[108:109], v[132:133] op_sel_hi:[1,0]
	v_pk_mul_f32 v[110:111], v[106:107], v[132:133] op_sel_hi:[1,0]
	v_mul_f32_e32 v107, 0xbfb8aa3b, v150
	v_exp_f32_e32 v150, v107
	s_nop 0
	s_nop 0
	s_nop 0
	s_nop 0
	s_nop 0
	s_nop 0
	s_nop 0
	s_nop 0
	s_nop 0
	s_nop 0
	s_nop 0
	s_nop 0
	s_nop 0
	s_nop 0
	s_waitcnt vmcnt(4)
	v_lshlrev_b32_e32 v106, 16, v176
	v_and_b32_e32 v107, 0xffff0000, v176
	v_mul_f32_e32 v110, 0xbfb8aa3b, v110
	v_mul_f32_e32 v111, 0xbfb8aa3b, v111
	v_exp_f32_e32 v110, v110
	v_exp_f32_e32 v111, v111
	v_mul_f32_e32 v112, 0xbfb8aa3b, v112
	v_mul_f32_e32 v113, 0xbfb8aa3b, v113
	v_exp_f32_e32 v112, v112
	v_pk_add_f32 v[110:111], v[110:111], 1.0 op_sel_hi:[1,0]
	v_exp_f32_e32 v113, v113
	s_waitcnt lgkmcnt(0)
	s_nop 0
	s_nop 0
	s_nop 0
	s_nop 0
	s_nop 0
	s_nop 0
	s_nop 0
	s_nop 0
	s_nop 0
	s_nop 0
	s_nop 0
	s_nop 0
	s_nop 0
	s_nop 0
	s_waitcnt vmcnt(3)
	v_lshlrev_b32_e32 v108, 16, v184
	v_and_b32_e32 v109, 0xffff0000, v184
	v_mul_f32_e32 v114, 0xbfb8aa3b, v151
	v_exp_f32_e32 v151, v114
	v_pk_add_f32 v[112:113], v[112:113], 1.0 op_sel_hi:[1,0]
	v_pk_add_f32 v[150:151], v[150:151], 1.0 op_sel_hi:[1,0]
	s_nop 0
	v_div_scale_f32 v114, s[0:1], v151, v151, 1.0
	v_rcp_f32_e32 v118, v114
	s_nop 0
	v_fma_f32 v133, -v114, v118, 1.0
	v_fmac_f32_e32 v118, v133, v118
	v_div_scale_f32 v133, vcc, 1.0, v151, 1.0
	v_mul_f32_e32 v137, v133, v118
	v_fma_f32 v147, -v114, v137, v133
	v_fmac_f32_e32 v137, v147, v118
	v_fma_f32 v114, -v114, v137, v133
	v_div_fmas_f32 v114, v114, v118, v137
	v_div_fixup_f32 v151, v114, v151, 1.0
	v_div_scale_f32 v114, s[0:1], v150, v150, 1.0
	v_rcp_f32_e32 v118, v114
	s_nop 0
	v_fma_f32 v133, -v114, v118, 1.0
	v_fmac_f32_e32 v118, v133, v118
	v_div_scale_f32 v133, vcc, 1.0, v150, 1.0
	v_mul_f32_e32 v137, v133, v118
	v_fma_f32 v147, -v114, v137, v133
	v_fmac_f32_e32 v137, v147, v118
	v_fma_f32 v114, -v114, v137, v133
	v_div_fmas_f32 v114, v114, v118, v137
	v_div_fixup_f32 v150, v114, v150, 1.0
	v_pk_fma_f32 v[106:107], v[150:151], v[108:109], v[106:107]
	v_mul_f32_e32 v109, 0xbfb8aa3b, v148
	v_lshlrev_b32_e32 v108, 16, v177
	v_exp_f32_e32 v118, v109
	v_and_b32_e32 v109, 0xffff0000, v177
	v_mul_f32_e32 v119, 0xbfb8aa3b, v149
	v_exp_f32_e32 v119, v119
	v_lshlrev_b32_e32 v114, 16, v185
	v_and_b32_e32 v115, 0xffff0000, v185
	v_pk_add_f32 v[118:119], v[118:119], 1.0 op_sel_hi:[1,0]
	s_nop 0
	v_div_scale_f32 v133, s[0:1], v119, v119, 1.0
	v_rcp_f32_e32 v137, v133
	s_nop 0
	v_fma_f32 v147, -v133, v137, 1.0
	v_fmac_f32_e32 v137, v147, v137
	v_div_scale_f32 v147, vcc, 1.0, v119, 1.0
	v_mul_f32_e32 v148, v147, v137
	v_fma_f32 v149, -v133, v148, v147
	v_fmac_f32_e32 v148, v149, v137
	v_fma_f32 v133, -v133, v148, v147
	v_div_fmas_f32 v133, v133, v137, v148
	v_div_fixup_f32 v119, v133, v119, 1.0
	v_div_scale_f32 v133, s[0:1], v118, v118, 1.0
	v_rcp_f32_e32 v137, v133
	s_nop 0
	v_fma_f32 v147, -v133, v137, 1.0
	v_fmac_f32_e32 v137, v147, v137
	v_div_scale_f32 v147, vcc, 1.0, v118, 1.0
	v_mul_f32_e32 v148, v147, v137
	v_fma_f32 v149, -v133, v148, v147
	v_fmac_f32_e32 v148, v149, v137
	v_fma_f32 v133, -v133, v148, v147
	v_div_fmas_f32 v133, v133, v137, v148
	v_div_fixup_f32 v118, v133, v118, 1.0
	v_pk_fma_f32 v[108:109], v[118:119], v[114:115], v[108:109]
	v_lshlrev_b32_e32 v118, 16, v186
	v_and_b32_e32 v119, 0xffff0000, v186
	v_div_scale_f32 v116, s[0:1], v111, v111, 1.0
	v_lshlrev_b32_e32 v114, 16, v178
	v_and_b32_e32 v115, 0xffff0000, v178
	v_rcp_f32_e32 v120, v116
	s_nop 0
	v_fma_f32 v133, -v116, v120, 1.0
	v_fmac_f32_e32 v120, v133, v120
	v_div_scale_f32 v133, vcc, 1.0, v111, 1.0
	v_mul_f32_e32 v137, v133, v120
	v_fma_f32 v147, -v116, v137, v133
	v_fmac_f32_e32 v137, v147, v120
	v_fma_f32 v116, -v116, v137, v133
	v_div_fmas_f32 v116, v116, v120, v137
; __device__ __forceinline__ unsigned cvt_pk_bf16(float lo, float hi) { unsigned r; asm("v_cvt_pk_bf16_f32 %0, %1, %2" : "=v"(r) : "v"(lo), "v"(hi)); return r; }
; __device__ __forceinline__ float bf_lo(unsigned u) { return __uint_as_float(u << 16); }
; __device__ __forceinline__ float bf_hi(unsigned u) { return __uint_as_float(u & 0xffff0000u); }
; __device__ __forceinline__ float sigmoidf_(float x) { return 1.f / (1.f + __expf(-x)); }
;   __device__ __forceinline__ void operator()(const f32x4 (&acc)[2][2][4][2], const Unit& u, const EpiCtx& x_, int wr, int wc, int fr, int fq) const {
;     ...
;           const f32x4 a = acc[ai][bj][m][0] * rs, b = acc[ai][bj][m][1] * rs;
;           f32x4 xa, xc;
;           xa[0] = bf_lo(xi.x) + bf_lo(pe.x) * sigmoidf_(a[0]); xa[1] = bf_hi(xi.x) + bf_hi(pe.x) * sigmoidf_(a[1]);
;           xa[2] = bf_lo(xi.y) + bf_lo(pe.y) * sigmoidf_(a[2]); xa[3] = bf_hi(xi.y) + bf_hi(pe.y) * sigmoidf_(a[3]);
;           xc[0] = bf_lo(xi.z) + bf_lo(pe.z) * sigmoidf_(b[0]); xc[1] = bf_hi(xi.z) + bf_hi(pe.z) * sigmoidf_(b[1]);
;           xc[2] = bf_lo(xi.w) + bf_lo(pe.w) * sigmoidf_(b[2]); xc[3] = bf_hi(xi.w) + bf_hi(pe.w) * sigmoidf_(b[3]);
;           sq += xa[0] * xa[0] + xa[1] * xa[1] + xa[2] * xa[2] + xa[3] * xa[3] + xc[0] * xc[0] + xc[1] * xc[1] + xc[2] * xc[2] + xc[3] * xc[3];
;           uint4 o; o.x = cvt_pk_bf16(xa[0], xa[1]); o.y = cvt_pk_bf16(xa[2], xa[3]); o.z = cvt_pk_bf16(xc[0], xc[1]); o.w = cvt_pk_bf16(xc[2], xc[3]);
;           *(uint4*)(xbp + cb) = o;
;           if (last) { float* op = (float*)u.C + (size_t)row * DM + cb; *(f32x4*)op = xa; *(f32x4*)(op + 4) = xc; }
	v_div_fixup_f32 v111, v116, v111, 1.0
	v_div_scale_f32 v116, s[0:1], v110, v110, 1.0
	v_rcp_f32_e32 v120, v116
	s_nop 0
	v_fma_f32 v133, -v116, v120, 1.0
	v_fmac_f32_e32 v120, v133, v120
	v_div_scale_f32 v133, vcc, 1.0, v110, 1.0
	v_mul_f32_e32 v137, v133, v120
	v_fma_f32 v147, -v116, v137, v133
	v_fmac_f32_e32 v137, v147, v120
	v_fma_f32 v116, -v116, v137, v133
	v_div_fmas_f32 v116, v116, v120, v137
	v_div_fixup_f32 v110, v116, v110, 1.0
	v_pk_fma_f32 v[110:111], v[110:111], v[118:119], v[114:115]
	v_div_scale_f32 v118, s[0:1], v113, v113, 1.0
	v_rcp_f32_e32 v119, v118
	v_lshlrev_b32_e32 v114, 16, v179
	v_and_b32_e32 v115, 0xffff0000, v179
	v_lshlrev_b32_e32 v116, 16, v187
	v_fma_f32 v120, -v118, v119, 1.0
	v_fmac_f32_e32 v119, v120, v119
	v_div_scale_f32 v120, vcc, 1.0, v113, 1.0
	v_mul_f32_e32 v121, v120, v119
	v_fma_f32 v133, -v118, v121, v120
	v_fmac_f32_e32 v121, v133, v119
	v_fma_f32 v118, -v118, v121, v120
	v_div_fmas_f32 v118, v118, v119, v121
	v_div_fixup_f32 v113, v118, v113, 1.0
	v_div_scale_f32 v118, s[0:1], v112, v112, 1.0
	v_rcp_f32_e32 v119, v118
	v_and_b32_e32 v117, 0xffff0000, v187
	v_fma_f32 v120, -v118, v119, 1.0
	v_fmac_f32_e32 v119, v120, v119
	v_div_scale_f32 v120, vcc, 1.0, v112, 1.0
	v_mul_f32_e32 v121, v120, v119
	v_fma_f32 v133, -v118, v121, v120
	v_fmac_f32_e32 v121, v133, v119
	v_fma_f32 v118, -v118, v121, v120
	v_div_fmas_f32 v118, v118, v119, v121
	v_div_fixup_f32 v112, v118, v112, 1.0
	v_pk_fma_f32 v[112:113], v[112:113], v[116:117], v[114:115]
	v_lshl_add_u64 v[118:119], v[126:127], 0, v[142:143]
	s_and_b64 vcc, exec, s[4:5]
	v_cvt_pk_bf16_f32 v114, v106, v107
	v_cvt_pk_bf16_f32 v115, v108, v109
	v_cvt_pk_bf16_f32 v116, v110, v111
	v_cvt_pk_bf16_f32 v117, v112, v113
	global_store_dwordx4 v[118:119], v[114:117], off nt
	s_cbranch_vccnz .LBB0_967
	s_nop 0
	v_lshl_add_u64 v[114:115], v[140:141], 2, v[134:135]
	global_store_dwordx4 v[114:115], v[106:109], off nt
	global_store_dwordx4 v[114:115], v[110:113], off offset:16 nt
; __device__ __forceinline__ unsigned cvt_pk_bf16(float lo, float hi) { unsigned r; asm("v_cvt_pk_bf16_f32 %0, %1, %2" : "=v"(r) : "v"(lo), "v"(hi)); return r; }
; __device__ __forceinline__ float bf_lo(unsigned u) { return __uint_as_float(u << 16); }
; __device__ __forceinline__ float bf_hi(unsigned u) { return __uint_as_float(u & 0xffff0000u); }
; __device__ __forceinline__ float sigmoidf_(float x) { return 1.f / (1.f + __expf(-x)); }
;   __device__ __forceinline__ void operator()(const f32x4 (&acc)[2][2][4][2], const Unit& u, const EpiCtx& x_, int wr, int wc, int fr, int fq) const {
;     ...
;         for (int bj = 0; bj < 2; ++bj) {
;           const int cb = u.c0 + wc * 64 + bj * 32 + 8 * fq;
;           const uint4 pe = *(const uint4*)(pep + cb), xi = *(const uint4*)(xin + cb);
;           const f32x4 a = acc[ai][bj][m][0] * rs, b = acc[ai][bj][m][1] * rs;
;           f32x4 xa, xc;
;           xa[0] = bf_lo(xi.x) + bf_lo(pe.x) * sigmoidf_(a[0]); xa[1] = bf_hi(xi.x) + bf_hi(pe.x) * sigmoidf_(a[1]);
;           xa[2] = bf_lo(xi.y) + bf_lo(pe.y) * sigmoidf_(a[2]); xa[3] = bf_hi(xi.y) + bf_hi(pe.y) * sigmoidf_(a[3]);
;           xc[0] = bf_lo(xi.z) + bf_lo(pe.z) * sigmoidf_(b[0]); xc[1] = bf_hi(xi.z) + bf_hi(pe.z) * sigmoidf_(b[1]);
;           xc[2] = bf_lo(xi.w) + bf_lo(pe.w) * sigmoidf_(b[2]); xc[3] = bf_hi(xi.w) + bf_hi(pe.w) * sigmoidf_(b[3]);
;           sq += xa[0] * xa[0] + xa[1] * xa[1] + xa[2] * xa[2] + xa[3] * xa[3] + xc[0] * xc[0] + xc[1] * xc[1] + xc[2] * xc[2] + xc[3] * xc[3];
;           uint4 o; o.x = cvt_pk_bf16(xa[0], xa[1]); o.y = cvt_pk_bf16(xa[2], xa[3]); o.z = cvt_pk_bf16(xc[0], xc[1]); o.w = cvt_pk_bf16(xc[2], xc[3]);
;           *(uint4*)(xbp + cb) = o;
;           if (last) { float* op = (float*)u.C + (size_t)row * DM + cb; *(f32x4*)op = xa; *(f32x4*)(op + 4) = xc; }
.LBB0_967:
	s_nop 1
	v_add_u32_e32 v198, s87, v169
	v_ashrrev_i32_e32 v199, 31, v198
	v_lshl_add_u64 v[200:201], v[198:199], 3, s[96:97]
	global_load_dwordx2 v[174:175], v[200:201], off
	v_lshlrev_b64 v[200:201], 12, v[198:199]
	v_lshl_add_u64 v[202:203], s[94:95], 0, v[200:201]
	v_lshl_add_u64 v[204:205], v[202:203], 0, v[142:143]
	global_load_dwordx4 v[176:179], v[204:205], off
	v_lshl_add_u64 v[202:203], s[92:93], 0, v[200:201]
	v_lshl_add_u64 v[204:205], v[202:203], 0, v[142:143]
	global_load_dwordx4 v[184:187], v[204:205], off
	s_nop 0
	v_lshl_add_u64 v[114:115], v[130:131], 0, v[144:145]
	s_nop 0
	v_lshl_add_u64 v[118:119], v[128:129], 0, v[144:145]
	s_nop 0
	v_mov_b32_e32 v133, v132
	v_mov_b32_e32 v128, v132
	v_mov_b32_e32 v129, v132
	v_pk_mul_f32 v[148:149], v[102:103], v[132:133]
	v_pk_mul_f32 v[130:131], v[104:105], v[128:129]
	v_pk_mul_f32 v[104:105], v[100:101], v[128:129]
	v_pk_mul_f32 v[102:103], v[98:99], v[132:133]
	v_mul_f32_e32 v99, 0xbfb8aa3b, v148
	v_exp_f32_e32 v128, v99
	v_mul_f32_e32 v102, 0xbfb8aa3b, v102
	v_mul_f32_e32 v103, 0xbfb8aa3b, v103
	v_exp_f32_e32 v102, v102
	v_exp_f32_e32 v103, v103
	v_mul_f32_e32 v104, 0xbfb8aa3b, v104
	v_mul_f32_e32 v105, 0xbfb8aa3b, v105
	v_exp_f32_e32 v104, v104
	v_pk_add_f32 v[102:103], v[102:103], 1.0 op_sel_hi:[1,0]
	v_exp_f32_e32 v105, v105
	s_waitcnt lgkmcnt(0)
	s_nop 0
	s_nop 0
	s_nop 0
	s_nop 0
	s_nop 0
	s_nop 0
	s_nop 0
	s_nop 0
	s_nop 0
	s_nop 0
	s_nop 0
	s_nop 0
	s_nop 0
	s_nop 0
	s_waitcnt vmcnt(5)
	v_lshlrev_b32_e32 v100, 16, v190
	v_and_b32_e32 v101, 0xffff0000, v190
	v_mul_f32_e32 v114, 0xbfb8aa3b, v149
	v_exp_f32_e32 v129, v114
	s_nop 0
	s_nop 0
	s_nop 0
	s_nop 0
	s_nop 0
	s_nop 0
	s_nop 0
	s_nop 0
	s_nop 0
	s_nop 0
	s_nop 0
	s_nop 0
	s_nop 0
	s_nop 0
	s_waitcnt vmcnt(4)
	v_lshlrev_b32_e32 v98, 16, v194
	v_and_b32_e32 v99, 0xffff0000, v194
	v_pk_add_f32 v[104:105], v[104:105], 1.0 op_sel_hi:[1,0]
	v_pk_add_f32 v[128:129], v[128:129], 1.0 op_sel_hi:[1,0]
	s_nop 0
	v_div_scale_f32 v114, s[0:1], v129, v129, 1.0
	v_rcp_f32_e32 v118, v114
	s_nop 0
	v_fma_f32 v132, -v114, v118, 1.0
	v_fmac_f32_e32 v118, v132, v118
	v_div_scale_f32 v132, vcc, 1.0, v129, 1.0
	v_mul_f32_e32 v133, v132, v118
	v_fma_f32 v137, -v114, v133, v132
	v_fmac_f32_e32 v133, v137, v118
	v_fma_f32 v114, -v114, v133, v132
	v_div_fmas_f32 v114, v114, v118, v133
	v_div_fixup_f32 v129, v114, v129, 1.0
	v_div_scale_f32 v114, s[0:1], v128, v128, 1.0
	v_rcp_f32_e32 v118, v114
	s_nop 0
	v_fma_f32 v132, -v114, v118, 1.0
	v_fmac_f32_e32 v118, v132, v118
	v_div_scale_f32 v132, vcc, 1.0, v128, 1.0
	v_mul_f32_e32 v133, v132, v118
	v_fma_f32 v137, -v114, v133, v132
	v_fmac_f32_e32 v133, v137, v118
	v_fma_f32 v114, -v114, v133, v132
	v_div_fmas_f32 v114, v114, v118, v133
	v_div_fixup_f32 v128, v114, v128, 1.0
	v_pk_fma_f32 v[98:99], v[128:129], v[100:101], v[98:99]
	v_mul_f32_e32 v101, 0xbfb8aa3b, v130
	v_lshlrev_b32_e32 v100, 16, v195
	v_exp_f32_e32 v118, v101
	v_and_b32_e32 v101, 0xffff0000, v195
	v_mul_f32_e32 v119, 0xbfb8aa3b, v131
	v_exp_f32_e32 v119, v119
	v_lshlrev_b32_e32 v114, 16, v191
	v_and_b32_e32 v115, 0xffff0000, v191
	v_pk_add_f32 v[118:119], v[118:119], 1.0 op_sel_hi:[1,0]
	s_nop 0
	v_div_scale_f32 v128, s[0:1], v119, v119, 1.0
	v_rcp_f32_e32 v129, v128
	s_nop 0
	v_fma_f32 v130, -v128, v129, 1.0
	v_fmac_f32_e32 v129, v130, v129
	v_div_scale_f32 v130, vcc, 1.0, v119, 1.0
	v_mul_f32_e32 v131, v130, v129
	v_fma_f32 v132, -v128, v131, v130
	v_fmac_f32_e32 v131, v132, v129
	v_fma_f32 v128, -v128, v131, v130
	v_div_fmas_f32 v128, v128, v129, v131
	v_div_fixup_f32 v119, v128, v119, 1.0
	v_div_scale_f32 v128, s[0:1], v118, v118, 1.0
	v_rcp_f32_e32 v129, v128
	s_nop 0
	v_fma_f32 v130, -v128, v129, 1.0
	v_fmac_f32_e32 v129, v130, v129
	v_div_scale_f32 v130, vcc, 1.0, v118, 1.0
	v_mul_f32_e32 v131, v130, v129
	v_fma_f32 v132, -v128, v131, v130
	v_fmac_f32_e32 v131, v132, v129
	v_fma_f32 v128, -v128, v131, v130
	v_div_fmas_f32 v128, v128, v129, v131
	v_div_fixup_f32 v118, v128, v118, 1.0
	v_pk_fma_f32 v[100:101], v[118:119], v[114:115], v[100:101]
	v_lshlrev_b32_e32 v118, 16, v192
	v_and_b32_e32 v119, 0xffff0000, v192
	v_div_scale_f32 v116, s[0:1], v103, v103, 1.0
	v_lshlrev_b32_e32 v114, 16, v196
	v_and_b32_e32 v115, 0xffff0000, v196
	v_rcp_f32_e32 v120, v116
	s_nop 0
	v_fma_f32 v128, -v116, v120, 1.0
	v_fmac_f32_e32 v120, v128, v120
	v_div_scale_f32 v128, vcc, 1.0, v103, 1.0
	v_mul_f32_e32 v129, v128, v120
	v_fma_f32 v130, -v116, v129, v128
	v_fmac_f32_e32 v129, v130, v120
	v_fma_f32 v116, -v116, v129, v128
	v_div_fmas_f32 v116, v116, v120, v129
	v_div_fixup_f32 v103, v116, v103, 1.0
	v_div_scale_f32 v116, s[0:1], v102, v102, 1.0
	v_rcp_f32_e32 v120, v116
	s_nop 0
	v_fma_f32 v128, -v116, v120, 1.0
	v_fmac_f32_e32 v120, v128, v120
	v_div_scale_f32 v128, vcc, 1.0, v102, 1.0
	v_mul_f32_e32 v129, v128, v120
	v_fma_f32 v130, -v116, v129, v128
	v_fmac_f32_e32 v129, v130, v120
	v_fma_f32 v116, -v116, v129, v128
	v_div_fmas_f32 v116, v116, v120, v129
	v_div_fixup_f32 v102, v116, v102, 1.0
	v_pk_fma_f32 v[102:103], v[102:103], v[118:119], v[114:115]
	v_div_scale_f32 v118, s[0:1], v105, v105, 1.0
	v_rcp_f32_e32 v119, v118
	v_lshlrev_b32_e32 v114, 16, v197
	v_and_b32_e32 v115, 0xffff0000, v197
	v_lshlrev_b32_e32 v116, 16, v193
	v_fma_f32 v120, -v118, v119, 1.0
	v_fmac_f32_e32 v119, v120, v119
	v_div_scale_f32 v120, vcc, 1.0, v105, 1.0
	v_mul_f32_e32 v121, v120, v119
	v_fma_f32 v128, -v118, v121, v120
	v_fmac_f32_e32 v121, v128, v119
	v_fma_f32 v118, -v118, v121, v120
	v_div_fmas_f32 v118, v118, v119, v121
	v_div_fixup_f32 v105, v118, v105, 1.0
	v_div_scale_f32 v118, s[0:1], v104, v104, 1.0
	v_rcp_f32_e32 v119, v118
	v_and_b32_e32 v117, 0xffff0000, v193
	v_fma_f32 v120, -v118, v119, 1.0
	v_fmac_f32_e32 v119, v120, v119
	v_div_scale_f32 v120, vcc, 1.0, v104, 1.0
	v_mul_f32_e32 v121, v120, v119
	v_fma_f32 v128, -v118, v121, v120
	v_fmac_f32_e32 v121, v128, v119
	v_fma_f32 v118, -v118, v121, v120
	v_div_fmas_f32 v118, v118, v119, v121
	v_div_fixup_f32 v104, v118, v104, 1.0
	v_pk_fma_f32 v[104:105], v[104:105], v[116:117], v[114:115]
	v_lshl_add_u64 v[118:119], v[126:127], 0, v[144:145]
	s_and_b64 vcc, exec, s[4:5]
	v_cvt_pk_bf16_f32 v114, v98, v99
	v_cvt_pk_bf16_f32 v115, v100, v101
	v_cvt_pk_bf16_f32 v116, v102, v103
	v_cvt_pk_bf16_f32 v117, v104, v105
	global_store_dwordx4 v[118:119], v[114:117], off nt
	s_cbranch_vccnz .LBB0_969
	s_nop 0
	v_lshl_add_u64 v[114:115], v[138:139], 2, v[134:135]
	global_store_dwordx4 v[114:115], v[98:101], off nt
	global_store_dwordx4 v[114:115], v[102:105], off offset:16 nt

; __device__ __forceinline__ float bf_lo(unsigned u) { return __uint_as_float(u << 16); }
; __device__ __forceinline__ float bf_hi(unsigned u) { return __uint_as_float(u & 0xffff0000u); }
; __device__ __forceinline__ float sigmoidf_(float x) { return 1.f / (1.f + __expf(-x)); }
; __device__ __forceinline__ float rinv_of(unsigned long long ss) { return rsqrtf((float)ss * (1.f / 16777216.f) * (1.f / DM) + 1e-6f); }
;   __device__ __forceinline__ void operator()(const f32x4 (&acc)[2][2][4][2], const Unit& u, const EpiCtx& x_, int wr, int wc, int fr, int fq) const {
;     ...
;         const int row = (u.r0 + (ai ? x_.rdelta : 0)) + wr * 64 + m * 16 + fr;
;         const bf16_t* pep = (const bf16_t*)x_.aux + (size_t)row * DM;
;         const bf16_t* xin = (const bf16_t*)x_.aux2 + (size_t)row * DM;
;         bf16_t* xbp = x_.xb + (size_t)row * DM;
;         const float rs = rinv_of(x_.ss[row]);
;         float sq = 0.f;
; #pragma unroll
;         for (int bj = 0; bj < 2; ++bj) {
;           const int cb = u.c0 + wc * 64 + bj * 32 + 8 * fq;
;           const uint4 pe = *(const uint4*)(pep + cb), xi = *(const uint4*)(xin + cb);
;           const f32x4 a = acc[ai][bj][m][0] * rs, b = acc[ai][bj][m][1] * rs;
;           f32x4 xa, xc;
;           xa[0] = bf_lo(xi.x) + bf_lo(pe.x) * sigmoidf_(a[0]); xa[1] = bf_hi(xi.x) + bf_hi(pe.x) * sigmoidf_(a[1]);
.LBB0_971:
	s_or_b64 exec, exec, s[18:19]
	s_nop 1
	v_add_u32_e32 v198, s87, v169
	v_ashrrev_i32_e32 v199, 31, v198
	v_lshlrev_b64 v[200:201], 12, v[198:199]
	v_lshl_add_u64 v[202:203], s[92:93], 0, v[200:201]
	v_lshl_add_u64 v[204:205], v[202:203], 0, v[144:145]
	global_load_dwordx4 v[190:193], v[204:205], off
	v_lshl_add_u64 v[202:203], s[94:95], 0, v[200:201]
	v_lshl_add_u64 v[204:205], v[202:203], 0, v[144:145]
	global_load_dwordx4 v[194:197], v[204:205], off
	v_add_u32_e32 v108, s87, v169
	v_ashrrev_i32_e32 v109, 31, v108
	s_waitcnt lgkmcnt(0)
	v_lshlrev_b64 v[98:99], 12, v[108:109]
	v_lshl_add_u64 v[114:115], s[92:93], 0, v[98:99]
	v_lshl_add_u64 v[112:113], s[94:95], 0, v[98:99]
	v_lshl_add_u64 v[110:111], s[90:91], 0, v[98:99]
	v_lshl_add_u64 v[98:99], v[108:109], 3, s[96:97]
	s_nop 0
	v_lshl_add_u64 v[102:103], v[112:113], 0, v[142:143]
	s_nop 0
	v_lshlrev_b64 v[118:119], 11, v[108:109]
	v_lshl_add_u64 v[118:119], v[118:119], 2, s[36:37]
	s_waitcnt lgkmcnt(0)
	s_nop 0
	s_nop 0
	s_nop 0
	s_nop 0
	s_nop 0
	s_nop 0
	s_nop 0
	s_nop 0
	s_nop 0
	s_nop 0
	s_nop 0
	s_nop 0
	s_nop 0
	s_nop 0
	s_waitcnt vmcnt(5)
	v_ffbh_u32_e32 v100, v175
	v_min_u32_e32 v100, 32, v100
	v_lshlrev_b64 v[98:99], v100, v[174:175]
	v_min_u32_e32 v98, 1, v98
	v_or_b32_e32 v98, v99, v98
	v_cvt_f32_u32_e32 v98, v98
	v_sub_u32_e32 v99, 32, v100
	v_ldexp_f32 v98, v98, v99
	v_mul_f32_e32 v98, 0x33800000, v98
	v_fmamk_f32 v98, v98, 0x3a000000, v234
	v_cmp_gt_f32_e32 vcc, s50, v98
	v_mul_f32_e32 v99, 0x4b800000, v98
	s_nop 0
	v_cndmask_b32_e32 v98, v98, v99, vcc
	v_rsq_f32_e32 v98, v98
	s_nop 0
	v_mul_f32_e32 v99, 0x45800000, v98
	v_cndmask_b32_e32 v116, v98, v99, vcc
	v_lshl_add_u64 v[98:99], v[114:115], 0, v[142:143]
	s_nop 0
	v_pk_mul_f32 v[126:127], v[94:95], v[116:117] op_sel_hi:[1,0]
	v_pk_mul_f32 v[120:121], v[96:97], v[116:117] op_sel_hi:[1,0]
	v_pk_mul_f32 v[96:97], v[92:93], v[116:117] op_sel_hi:[1,0]
	v_pk_mul_f32 v[94:95], v[90:91], v[116:117] op_sel_hi:[1,0]
	v_mul_f32_e32 v91, 0xbfb8aa3b, v126
	v_exp_f32_e32 v126, v91
	s_nop 0
	s_nop 0
	s_nop 0
	s_nop 0
	s_nop 0
	s_nop 0
	s_nop 0
	s_nop 0
	s_nop 0
	s_nop 0
	s_nop 0
	s_nop 0
	s_nop 0
	s_nop 0
	s_waitcnt vmcnt(4)
	v_lshlrev_b32_e32 v90, 16, v176
	v_and_b32_e32 v91, 0xffff0000, v176
	v_mul_f32_e32 v94, 0xbfb8aa3b, v94
	v_mul_f32_e32 v95, 0xbfb8aa3b, v95
	v_exp_f32_e32 v94, v94
	v_exp_f32_e32 v95, v95
	v_mul_f32_e32 v96, 0xbfb8aa3b, v96
	v_mul_f32_e32 v97, 0xbfb8aa3b, v97
	v_exp_f32_e32 v96, v96
	v_pk_add_f32 v[94:95], v[94:95], 1.0 op_sel_hi:[1,0]
	v_exp_f32_e32 v97, v97
	s_waitcnt lgkmcnt(0)
	s_nop 0
	s_nop 0
	s_nop 0
	s_nop 0
	s_nop 0
	s_nop 0
	s_nop 0
	s_nop 0
	s_nop 0
	s_nop 0
	s_nop 0
	s_nop 0
	s_nop 0
	s_nop 0
	s_waitcnt vmcnt(3)
	v_lshlrev_b32_e32 v92, 16, v184
	v_and_b32_e32 v93, 0xffff0000, v184
	v_mul_f32_e32 v98, 0xbfb8aa3b, v127
	v_exp_f32_e32 v127, v98
	v_pk_add_f32 v[96:97], v[96:97], 1.0 op_sel_hi:[1,0]
	v_pk_add_f32 v[126:127], v[126:127], 1.0 op_sel_hi:[1,0]
	s_nop 0
	v_div_scale_f32 v98, s[0:1], v127, v127, 1.0
	v_rcp_f32_e32 v102, v98
	s_nop 0
	v_fma_f32 v117, -v98, v102, 1.0
	v_fmac_f32_e32 v102, v117, v102
	v_div_scale_f32 v117, vcc, 1.0, v127, 1.0
	v_mul_f32_e32 v125, v117, v102
	v_fma_f32 v128, -v98, v125, v117
	v_fmac_f32_e32 v125, v128, v102
	v_fma_f32 v98, -v98, v125, v117
	v_div_fmas_f32 v98, v98, v102, v125
	v_div_fixup_f32 v127, v98, v127, 1.0
	v_div_scale_f32 v98, s[0:1], v126, v126, 1.0
	v_rcp_f32_e32 v102, v98
	s_nop 0
	v_fma_f32 v117, -v98, v102, 1.0
	v_fmac_f32_e32 v102, v117, v102
	v_div_scale_f32 v117, vcc, 1.0, v126, 1.0
	v_mul_f32_e32 v125, v117, v102
	v_fma_f32 v128, -v98, v125, v117
	v_fmac_f32_e32 v125, v128, v102
	v_fma_f32 v98, -v98, v125, v117
	v_div_fmas_f32 v98, v98, v102, v125
	v_div_fixup_f32 v126, v98, v126, 1.0
	v_pk_fma_f32 v[90:91], v[126:127], v[92:93], v[90:91]
	v_mul_f32_e32 v93, 0xbfb8aa3b, v120
	v_lshlrev_b32_e32 v92, 16, v177
	v_exp_f32_e32 v102, v93
	v_and_b32_e32 v93, 0xffff0000, v177
	v_mul_f32_e32 v103, 0xbfb8aa3b, v121
	v_exp_f32_e32 v103, v103
	v_lshlrev_b32_e32 v98, 16, v185
	v_and_b32_e32 v99, 0xffff0000, v185
	v_pk_add_f32 v[102:103], v[102:103], 1.0 op_sel_hi:[1,0]
	s_nop 0
	v_div_scale_f32 v117, s[0:1], v103, v103, 1.0
	v_rcp_f32_e32 v120, v117
	s_nop 0
	v_fma_f32 v121, -v117, v120, 1.0
	v_fmac_f32_e32 v120, v121, v120
	v_div_scale_f32 v121, vcc, 1.0, v103, 1.0
	v_mul_f32_e32 v125, v121, v120
	v_fma_f32 v126, -v117, v125, v121
	v_fmac_f32_e32 v125, v126, v120
	v_fma_f32 v117, -v117, v125, v121
	v_div_fmas_f32 v117, v117, v120, v125
	v_div_fixup_f32 v103, v117, v103, 1.0
	v_div_scale_f32 v117, s[0:1], v102, v102, 1.0
	v_rcp_f32_e32 v120, v117
	s_nop 0
	v_fma_f32 v121, -v117, v120, 1.0
	v_fmac_f32_e32 v120, v121, v120
	v_div_scale_f32 v121, vcc, 1.0, v102, 1.0
	v_mul_f32_e32 v125, v121, v120
	v_fma_f32 v126, -v117, v125, v121
	v_fmac_f32_e32 v125, v126, v120
	v_fma_f32 v117, -v117, v125, v121
	v_div_fmas_f32 v117, v117, v120, v125
	v_div_fixup_f32 v102, v117, v102, 1.0
	v_pk_fma_f32 v[92:93], v[102:103], v[98:99], v[92:93]
	v_lshlrev_b32_e32 v102, 16, v186
	v_and_b32_e32 v103, 0xffff0000, v186
	v_div_scale_f32 v100, s[0:1], v95, v95, 1.0
	v_lshlrev_b32_e32 v98, 16, v178
	v_and_b32_e32 v99, 0xffff0000, v178
	v_rcp_f32_e32 v104, v100
	s_nop 0
	v_fma_f32 v117, -v100, v104, 1.0
	v_fmac_f32_e32 v104, v117, v104
	v_div_scale_f32 v117, vcc, 1.0, v95, 1.0
	v_mul_f32_e32 v120, v117, v104
	v_fma_f32 v121, -v100, v120, v117
	v_fmac_f32_e32 v120, v121, v104
	v_fma_f32 v100, -v100, v120, v117
	v_div_fmas_f32 v100, v100, v104, v120
	v_div_fixup_f32 v95, v100, v95, 1.0
	v_div_scale_f32 v100, s[0:1], v94, v94, 1.0
	v_rcp_f32_e32 v104, v100
	s_nop 0
; __device__ __forceinline__ unsigned cvt_pk_bf16(float lo, float hi) { unsigned r; asm("v_cvt_pk_bf16_f32 %0, %1, %2" : "=v"(r) : "v"(lo), "v"(hi)); return r; }
; __device__ __forceinline__ float bf_lo(unsigned u) { return __uint_as_float(u << 16); }
; __device__ __forceinline__ float bf_hi(unsigned u) { return __uint_as_float(u & 0xffff0000u); }
; __device__ __forceinline__ float sigmoidf_(float x) { return 1.f / (1.f + __expf(-x)); }
;   __device__ __forceinline__ void operator()(const f32x4 (&acc)[2][2][4][2], const Unit& u, const EpiCtx& x_, int wr, int wc, int fr, int fq) const {
;     ...
;           const f32x4 a = acc[ai][bj][m][0] * rs, b = acc[ai][bj][m][1] * rs;
;           f32x4 xa, xc;
;           xa[0] = bf_lo(xi.x) + bf_lo(pe.x) * sigmoidf_(a[0]); xa[1] = bf_hi(xi.x) + bf_hi(pe.x) * sigmoidf_(a[1]);
;           xa[2] = bf_lo(xi.y) + bf_lo(pe.y) * sigmoidf_(a[2]); xa[3] = bf_hi(xi.y) + bf_hi(pe.y) * sigmoidf_(a[3]);
;           xc[0] = bf_lo(xi.z) + bf_lo(pe.z) * sigmoidf_(b[0]); xc[1] = bf_hi(xi.z) + bf_hi(pe.z) * sigmoidf_(b[1]);
;           xc[2] = bf_lo(xi.w) + bf_lo(pe.w) * sigmoidf_(b[2]); xc[3] = bf_hi(xi.w) + bf_hi(pe.w) * sigmoidf_(b[3]);
;           sq += xa[0] * xa[0] + xa[1] * xa[1] + xa[2] * xa[2] + xa[3] * xa[3] + xc[0] * xc[0] + xc[1] * xc[1] + xc[2] * xc[2] + xc[3] * xc[3];
;           uint4 o; o.x = cvt_pk_bf16(xa[0], xa[1]); o.y = cvt_pk_bf16(xa[2], xa[3]); o.z = cvt_pk_bf16(xc[0], xc[1]); o.w = cvt_pk_bf16(xc[2], xc[3]);
;           *(uint4*)(xbp + cb) = o;
;           if (last) { float* op = (float*)u.C + (size_t)row * DM + cb; *(f32x4*)op = xa; *(f32x4*)(op + 4) = xc; }
	v_fma_f32 v117, -v100, v104, 1.0
	v_fmac_f32_e32 v104, v117, v104
	v_div_scale_f32 v117, vcc, 1.0, v94, 1.0
	v_mul_f32_e32 v120, v117, v104
	v_fma_f32 v121, -v100, v120, v117
	v_fmac_f32_e32 v120, v121, v104
	v_fma_f32 v100, -v100, v120, v117
	v_div_fmas_f32 v100, v100, v104, v120
	v_div_fixup_f32 v94, v100, v94, 1.0
	v_pk_fma_f32 v[94:95], v[94:95], v[102:103], v[98:99]
	v_div_scale_f32 v102, s[0:1], v97, v97, 1.0
	v_rcp_f32_e32 v103, v102
	v_lshlrev_b32_e32 v98, 16, v179
	v_and_b32_e32 v99, 0xffff0000, v179
	v_lshlrev_b32_e32 v100, 16, v187
	v_fma_f32 v104, -v102, v103, 1.0
	v_fmac_f32_e32 v103, v104, v103
	v_div_scale_f32 v104, vcc, 1.0, v97, 1.0
	v_mul_f32_e32 v105, v104, v103
	v_fma_f32 v117, -v102, v105, v104
	v_fmac_f32_e32 v105, v117, v103
	v_fma_f32 v102, -v102, v105, v104
	v_div_fmas_f32 v102, v102, v103, v105
	v_div_fixup_f32 v97, v102, v97, 1.0
	v_div_scale_f32 v102, s[0:1], v96, v96, 1.0
	v_rcp_f32_e32 v103, v102
	v_and_b32_e32 v101, 0xffff0000, v187
	v_fma_f32 v104, -v102, v103, 1.0
	v_fmac_f32_e32 v103, v104, v103
	v_div_scale_f32 v104, vcc, 1.0, v96, 1.0
	v_mul_f32_e32 v105, v104, v103
	v_fma_f32 v117, -v102, v105, v104
	v_fmac_f32_e32 v105, v117, v103
	v_fma_f32 v102, -v102, v105, v104
	v_div_fmas_f32 v102, v102, v103, v105
	v_div_fixup_f32 v96, v102, v96, 1.0
	v_pk_fma_f32 v[96:97], v[96:97], v[100:101], v[98:99]
	v_lshl_add_u64 v[102:103], v[110:111], 0, v[142:143]
	s_and_b64 vcc, exec, s[4:5]
	v_cvt_pk_bf16_f32 v98, v90, v91
	v_cvt_pk_bf16_f32 v99, v92, v93
	v_cvt_pk_bf16_f32 v100, v94, v95
	v_cvt_pk_bf16_f32 v101, v96, v97
	global_store_dwordx4 v[102:103], v[98:101], off nt
	s_cbranch_vccnz .LBB0_973
	s_nop 0
	v_lshl_add_u64 v[98:99], v[140:141], 2, v[118:119]
	global_store_dwordx4 v[98:99], v[90:93], off nt
	global_store_dwordx4 v[98:99], v[94:97], off offset:16 nt
; __device__ __forceinline__ unsigned cvt_pk_bf16(float lo, float hi) { unsigned r; asm("v_cvt_pk_bf16_f32 %0, %1, %2" : "=v"(r) : "v"(lo), "v"(hi)); return r; }
; __device__ __forceinline__ float bf_lo(unsigned u) { return __uint_as_float(u << 16); }
; __device__ __forceinline__ float bf_hi(unsigned u) { return __uint_as_float(u & 0xffff0000u); }
; __device__ __forceinline__ float sigmoidf_(float x) { return 1.f / (1.f + __expf(-x)); }
;   __device__ __forceinline__ void operator()(const f32x4 (&acc)[2][2][4][2], const Unit& u, const EpiCtx& x_, int wr, int wc, int fr, int fq) const {
;     ...
;         for (int bj = 0; bj < 2; ++bj) {
;           const int cb = u.c0 + wc * 64 + bj * 32 + 8 * fq;
;           const uint4 pe = *(const uint4*)(pep + cb), xi = *(const uint4*)(xin + cb);
;           const f32x4 a = acc[ai][bj][m][0] * rs, b = acc[ai][bj][m][1] * rs;
;           f32x4 xa, xc;
;           xa[0] = bf_lo(xi.x) + bf_lo(pe.x) * sigmoidf_(a[0]); xa[1] = bf_hi(xi.x) + bf_hi(pe.x) * sigmoidf_(a[1]);
;           xa[2] = bf_lo(xi.y) + bf_lo(pe.y) * sigmoidf_(a[2]); xa[3] = bf_hi(xi.y) + bf_hi(pe.y) * sigmoidf_(a[3]);
;           xc[0] = bf_lo(xi.z) + bf_lo(pe.z) * sigmoidf_(b[0]); xc[1] = bf_hi(xi.z) + bf_hi(pe.z) * sigmoidf_(b[1]);
;           xc[2] = bf_lo(xi.w) + bf_lo(pe.w) * sigmoidf_(b[2]); xc[3] = bf_hi(xi.w) + bf_hi(pe.w) * sigmoidf_(b[3]);
;           sq += xa[0] * xa[0] + xa[1] * xa[1] + xa[2] * xa[2] + xa[3] * xa[3] + xc[0] * xc[0] + xc[1] * xc[1] + xc[2] * xc[2] + xc[3] * xc[3];
;           uint4 o; o.x = cvt_pk_bf16(xa[0], xa[1]); o.y = cvt_pk_bf16(xa[2], xa[3]); o.z = cvt_pk_bf16(xc[0], xc[1]); o.w = cvt_pk_bf16(xc[2], xc[3]);
;           *(uint4*)(xbp + cb) = o;
;           if (last) { float* op = (float*)u.C + (size_t)row * DM + cb; *(f32x4*)op = xa; *(f32x4*)(op + 4) = xc; }
.LBB0_973:
	s_nop 1
	v_add_u32_e32 v198, s87, v170
	v_ashrrev_i32_e32 v199, 31, v198
	v_lshl_add_u64 v[200:201], v[198:199], 3, s[96:97]
	global_load_dwordx2 v[174:175], v[200:201], off
	v_lshlrev_b64 v[200:201], 12, v[198:199]
	v_lshl_add_u64 v[202:203], s[94:95], 0, v[200:201]
	v_lshl_add_u64 v[204:205], v[202:203], 0, v[142:143]
	global_load_dwordx4 v[176:179], v[204:205], off
	v_lshl_add_u64 v[202:203], s[92:93], 0, v[200:201]
	v_lshl_add_u64 v[204:205], v[202:203], 0, v[142:143]
	global_load_dwordx4 v[184:187], v[204:205], off
	s_nop 0
	v_lshl_add_u64 v[98:99], v[114:115], 0, v[144:145]
	s_nop 0
	v_lshl_add_u64 v[102:103], v[112:113], 0, v[144:145]
	s_nop 0
	v_mov_b32_e32 v117, v116
	v_mov_b32_e32 v112, v116
	v_mov_b32_e32 v113, v116
	v_pk_mul_f32 v[120:121], v[86:87], v[116:117]
	v_pk_mul_f32 v[114:115], v[88:89], v[112:113]
	v_pk_mul_f32 v[88:89], v[84:85], v[112:113]
	v_pk_mul_f32 v[86:87], v[82:83], v[116:117]
	v_mul_f32_e32 v83, 0xbfb8aa3b, v120
	v_exp_f32_e32 v112, v83
	v_mul_f32_e32 v86, 0xbfb8aa3b, v86
	v_mul_f32_e32 v87, 0xbfb8aa3b, v87
	v_exp_f32_e32 v86, v86
	v_exp_f32_e32 v87, v87
	v_mul_f32_e32 v88, 0xbfb8aa3b, v88
	v_mul_f32_e32 v89, 0xbfb8aa3b, v89
	v_exp_f32_e32 v88, v88
	v_pk_add_f32 v[86:87], v[86:87], 1.0 op_sel_hi:[1,0]
	v_exp_f32_e32 v89, v89
	s_waitcnt lgkmcnt(0)
	s_nop 0
	s_nop 0
	s_nop 0
	s_nop 0
	s_nop 0
	s_nop 0
	s_nop 0
	s_nop 0
	s_nop 0
	s_nop 0
	s_nop 0
	s_nop 0
	s_nop 0
	s_nop 0
	s_waitcnt vmcnt(5)
	v_lshlrev_b32_e32 v84, 16, v190
	v_and_b32_e32 v85, 0xffff0000, v190
	v_mul_f32_e32 v98, 0xbfb8aa3b, v121
	v_exp_f32_e32 v113, v98
	s_nop 0
	s_nop 0
	s_nop 0
	s_nop 0
	s_nop 0
	s_nop 0
	s_nop 0
	s_nop 0
	s_nop 0
	s_nop 0
	s_nop 0
	s_nop 0
	s_nop 0
	s_nop 0
	s_waitcnt vmcnt(4)
	v_lshlrev_b32_e32 v82, 16, v194
	v_and_b32_e32 v83, 0xffff0000, v194
	v_pk_add_f32 v[88:89], v[88:89], 1.0 op_sel_hi:[1,0]
	v_pk_add_f32 v[112:113], v[112:113], 1.0 op_sel_hi:[1,0]
	s_nop 0
	v_div_scale_f32 v98, s[0:1], v113, v113, 1.0
	v_rcp_f32_e32 v102, v98
	s_nop 0
	v_fma_f32 v116, -v98, v102, 1.0
	v_fmac_f32_e32 v102, v116, v102
	v_div_scale_f32 v116, vcc, 1.0, v113, 1.0
	v_mul_f32_e32 v117, v116, v102
	v_fma_f32 v120, -v98, v117, v116
	v_fmac_f32_e32 v117, v120, v102
	v_fma_f32 v98, -v98, v117, v116
	v_div_fmas_f32 v98, v98, v102, v117
	v_div_fixup_f32 v113, v98, v113, 1.0
	v_div_scale_f32 v98, s[0:1], v112, v112, 1.0
	v_rcp_f32_e32 v102, v98
	s_nop 0
	v_fma_f32 v116, -v98, v102, 1.0
	v_fmac_f32_e32 v102, v116, v102
	v_div_scale_f32 v116, vcc, 1.0, v112, 1.0
	v_mul_f32_e32 v117, v116, v102
	v_fma_f32 v120, -v98, v117, v116
	v_fmac_f32_e32 v117, v120, v102
	v_fma_f32 v98, -v98, v117, v116
	v_div_fmas_f32 v98, v98, v102, v117
	v_div_fixup_f32 v112, v98, v112, 1.0
	v_pk_fma_f32 v[82:83], v[112:113], v[84:85], v[82:83]
	v_mul_f32_e32 v85, 0xbfb8aa3b, v114
	v_lshlrev_b32_e32 v84, 16, v195
	v_exp_f32_e32 v102, v85
	v_and_b32_e32 v85, 0xffff0000, v195
	v_mul_f32_e32 v103, 0xbfb8aa3b, v115
	v_exp_f32_e32 v103, v103
	v_lshlrev_b32_e32 v98, 16, v191
	v_and_b32_e32 v99, 0xffff0000, v191
	v_pk_add_f32 v[102:103], v[102:103], 1.0 op_sel_hi:[1,0]
	s_nop 0
	v_div_scale_f32 v112, s[0:1], v103, v103, 1.0
	v_rcp_f32_e32 v113, v112
	s_nop 0
	v_fma_f32 v114, -v112, v113, 1.0
	v_fmac_f32_e32 v113, v114, v113
	v_div_scale_f32 v114, vcc, 1.0, v103, 1.0
	v_mul_f32_e32 v115, v114, v113
	v_fma_f32 v116, -v112, v115, v114
	v_fmac_f32_e32 v115, v116, v113
	v_fma_f32 v112, -v112, v115, v114
	v_div_fmas_f32 v112, v112, v113, v115
	v_div_fixup_f32 v103, v112, v103, 1.0
	v_div_scale_f32 v112, s[0:1], v102, v102, 1.0
	v_rcp_f32_e32 v113, v112
	s_nop 0
	v_fma_f32 v114, -v112, v113, 1.0
	v_fmac_f32_e32 v113, v114, v113
	v_div_scale_f32 v114, vcc, 1.0, v102, 1.0
	v_mul_f32_e32 v115, v114, v113
	v_fma_f32 v116, -v112, v115, v114
	v_fmac_f32_e32 v115, v116, v113
	v_fma_f32 v112, -v112, v115, v114
	v_div_fmas_f32 v112, v112, v113, v115
	v_div_fixup_f32 v102, v112, v102, 1.0
	v_pk_fma_f32 v[84:85], v[102:103], v[98:99], v[84:85]
	v_lshlrev_b32_e32 v102, 16, v192
	v_and_b32_e32 v103, 0xffff0000, v192
	v_div_scale_f32 v100, s[0:1], v87, v87, 1.0
	v_lshlrev_b32_e32 v98, 16, v196
	v_and_b32_e32 v99, 0xffff0000, v196
	v_rcp_f32_e32 v104, v100
	s_nop 0
	v_fma_f32 v112, -v100, v104, 1.0
	v_fmac_f32_e32 v104, v112, v104
	v_div_scale_f32 v112, vcc, 1.0, v87, 1.0
	v_mul_f32_e32 v113, v112, v104
	v_fma_f32 v114, -v100, v113, v112
	v_fmac_f32_e32 v113, v114, v104
	v_fma_f32 v100, -v100, v113, v112
	v_div_fmas_f32 v100, v100, v104, v113
	v_div_fixup_f32 v87, v100, v87, 1.0
	v_div_scale_f32 v100, s[0:1], v86, v86, 1.0
	v_rcp_f32_e32 v104, v100
	s_nop 0
	v_fma_f32 v112, -v100, v104, 1.0
	v_fmac_f32_e32 v104, v112, v104
	v_div_scale_f32 v112, vcc, 1.0, v86, 1.0
	v_mul_f32_e32 v113, v112, v104
	v_fma_f32 v114, -v100, v113, v112
	v_fmac_f32_e32 v113, v114, v104
	v_fma_f32 v100, -v100, v113, v112
	v_div_fmas_f32 v100, v100, v104, v113
	v_div_fixup_f32 v86, v100, v86, 1.0
	v_pk_fma_f32 v[86:87], v[86:87], v[102:103], v[98:99]
	v_div_scale_f32 v102, s[0:1], v89, v89, 1.0
	v_rcp_f32_e32 v103, v102
	v_lshlrev_b32_e32 v98, 16, v197
	v_and_b32_e32 v99, 0xffff0000, v197
	v_lshlrev_b32_e32 v100, 16, v193
	v_fma_f32 v104, -v102, v103, 1.0
	v_fmac_f32_e32 v103, v104, v103
	v_div_scale_f32 v104, vcc, 1.0, v89, 1.0
	v_mul_f32_e32 v105, v104, v103
	v_fma_f32 v112, -v102, v105, v104
	v_fmac_f32_e32 v105, v112, v103
	v_fma_f32 v102, -v102, v105, v104
	v_div_fmas_f32 v102, v102, v103, v105
	v_div_fixup_f32 v89, v102, v89, 1.0
	v_div_scale_f32 v102, s[0:1], v88, v88, 1.0
	v_rcp_f32_e32 v103, v102
	v_and_b32_e32 v101, 0xffff0000, v193
	v_fma_f32 v104, -v102, v103, 1.0
	v_fmac_f32_e32 v103, v104, v103
	v_div_scale_f32 v104, vcc, 1.0, v88, 1.0
	v_mul_f32_e32 v105, v104, v103
	v_fma_f32 v112, -v102, v105, v104
	v_fmac_f32_e32 v105, v112, v103
	v_fma_f32 v102, -v102, v105, v104
	v_div_fmas_f32 v102, v102, v103, v105
	v_div_fixup_f32 v88, v102, v88, 1.0
	v_pk_fma_f32 v[88:89], v[88:89], v[100:101], v[98:99]
	v_lshl_add_u64 v[102:103], v[110:111], 0, v[144:145]
	s_and_b64 vcc, exec, s[4:5]
	v_cvt_pk_bf16_f32 v98, v82, v83
	v_cvt_pk_bf16_f32 v99, v84, v85
	v_cvt_pk_bf16_f32 v100, v86, v87
	v_cvt_pk_bf16_f32 v101, v88, v89
	global_store_dwordx4 v[102:103], v[98:101], off nt
	s_cbranch_vccnz .LBB0_975
	s_nop 0
	v_lshl_add_u64 v[98:99], v[138:139], 2, v[118:119]
	global_store_dwordx4 v[98:99], v[82:85], off nt
	global_store_dwordx4 v[98:99], v[86:89], off offset:16 nt

; __device__ __forceinline__ float bf_lo(unsigned u) { return __uint_as_float(u << 16); }
; __device__ __forceinline__ float bf_hi(unsigned u) { return __uint_as_float(u & 0xffff0000u); }
; __device__ __forceinline__ float sigmoidf_(float x) { return 1.f / (1.f + __expf(-x)); }
; __device__ __forceinline__ float rinv_of(unsigned long long ss) { return rsqrtf((float)ss * (1.f / 16777216.f) * (1.f / DM) + 1e-6f); }
;   __device__ __forceinline__ void operator()(const f32x4 (&acc)[2][2][4][2], const Unit& u, const EpiCtx& x_, int wr, int wc, int fr, int fq) const {
;     ...
;         const int row = (u.r0 + (ai ? x_.rdelta : 0)) + wr * 64 + m * 16 + fr;
;         const bf16_t* pep = (const bf16_t*)x_.aux + (size_t)row * DM;
;         const bf16_t* xin = (const bf16_t*)x_.aux2 + (size_t)row * DM;
;         bf16_t* xbp = x_.xb + (size_t)row * DM;
;         const float rs = rinv_of(x_.ss[row]);
;         float sq = 0.f;
; #pragma unroll
;         for (int bj = 0; bj < 2; ++bj) {
;           const int cb = u.c0 + wc * 64 + bj * 32 + 8 * fq;
;           const uint4 pe = *(const uint4*)(pep + cb), xi = *(const uint4*)(xin + cb);
;           const f32x4 a = acc[ai][bj][m][0] * rs, b = acc[ai][bj][m][1] * rs;
;           f32x4 xa, xc;
;           xa[0] = bf_lo(xi.x) + bf_lo(pe.x) * sigmoidf_(a[0]); xa[1] = bf_hi(xi.x) + bf_hi(pe.x) * sigmoidf_(a[1]);
.LBB0_977:
	s_or_b64 exec, exec, s[18:19]
	s_nop 1
	v_add_u32_e32 v198, s87, v170
	v_ashrrev_i32_e32 v199, 31, v198
	v_lshlrev_b64 v[200:201], 12, v[198:199]
	v_lshl_add_u64 v[202:203], s[92:93], 0, v[200:201]
	v_lshl_add_u64 v[204:205], v[202:203], 0, v[144:145]
	global_load_dwordx4 v[190:193], v[204:205], off
	v_lshl_add_u64 v[202:203], s[94:95], 0, v[200:201]
	v_lshl_add_u64 v[204:205], v[202:203], 0, v[144:145]
	global_load_dwordx4 v[194:197], v[204:205], off
	v_add_u32_e32 v92, s87, v170
	v_ashrrev_i32_e32 v93, 31, v92
	s_waitcnt lgkmcnt(0)
	v_lshlrev_b64 v[82:83], 12, v[92:93]
	v_lshl_add_u64 v[98:99], s[92:93], 0, v[82:83]
	v_lshl_add_u64 v[96:97], s[94:95], 0, v[82:83]
	v_lshl_add_u64 v[94:95], s[90:91], 0, v[82:83]
	v_lshl_add_u64 v[82:83], v[92:93], 3, s[96:97]
	s_nop 0
	v_lshl_add_u64 v[86:87], v[96:97], 0, v[142:143]
	s_nop 0
	v_lshlrev_b64 v[102:103], 11, v[92:93]
	v_lshl_add_u64 v[102:103], v[102:103], 2, s[36:37]
	s_waitcnt lgkmcnt(0)
	s_nop 0
	s_nop 0
	s_nop 0
	s_nop 0
	s_nop 0
	s_nop 0
	s_nop 0
	s_nop 0
	s_nop 0
	s_nop 0
	s_nop 0
	s_nop 0
	s_nop 0
	s_nop 0
	s_waitcnt vmcnt(5)
	v_ffbh_u32_e32 v84, v175
	v_min_u32_e32 v84, 32, v84
	v_lshlrev_b64 v[82:83], v84, v[174:175]
	v_min_u32_e32 v82, 1, v82
	v_or_b32_e32 v82, v83, v82
	v_cvt_f32_u32_e32 v82, v82
	v_sub_u32_e32 v83, 32, v84
	v_ldexp_f32 v82, v82, v83
	v_mul_f32_e32 v82, 0x33800000, v82
	v_fmamk_f32 v82, v82, 0x3a000000, v234
	v_cmp_gt_f32_e32 vcc, s50, v82
	v_mul_f32_e32 v83, 0x4b800000, v82
	s_nop 0
	v_cndmask_b32_e32 v82, v82, v83, vcc
	v_rsq_f32_e32 v82, v82
	s_nop 0
	v_mul_f32_e32 v83, 0x45800000, v82
	v_cndmask_b32_e32 v100, v82, v83, vcc
	v_lshl_add_u64 v[82:83], v[98:99], 0, v[142:143]
	s_nop 0
	v_pk_mul_f32 v[110:111], v[76:77], v[100:101] op_sel_hi:[1,0]
	v_pk_mul_f32 v[104:105], v[78:79], v[100:101] op_sel_hi:[1,0]
	v_pk_mul_f32 v[78:79], v[74:75], v[100:101] op_sel_hi:[1,0]
	v_pk_mul_f32 v[76:77], v[72:73], v[100:101] op_sel_hi:[1,0]
	v_mul_f32_e32 v73, 0xbfb8aa3b, v110
	v_exp_f32_e32 v110, v73
	s_nop 0
	s_nop 0
	s_nop 0
	s_nop 0
	s_nop 0
	s_nop 0
	s_nop 0
	s_nop 0
	s_nop 0
	s_nop 0
	s_nop 0
	s_nop 0
	s_nop 0
	s_nop 0
	s_waitcnt vmcnt(4)
	v_lshlrev_b32_e32 v72, 16, v176
	v_and_b32_e32 v73, 0xffff0000, v176
	v_mul_f32_e32 v76, 0xbfb8aa3b, v76
	v_mul_f32_e32 v77, 0xbfb8aa3b, v77
	v_exp_f32_e32 v76, v76
	v_exp_f32_e32 v77, v77
	v_mul_f32_e32 v78, 0xbfb8aa3b, v78
	v_mul_f32_e32 v79, 0xbfb8aa3b, v79
	v_exp_f32_e32 v78, v78
	v_pk_add_f32 v[76:77], v[76:77], 1.0 op_sel_hi:[1,0]
	v_exp_f32_e32 v79, v79
	s_waitcnt lgkmcnt(0)
	s_nop 0
	s_nop 0
	s_nop 0
	s_nop 0
	s_nop 0
	s_nop 0
	s_nop 0
	s_nop 0
	s_nop 0
	s_nop 0
	s_nop 0
	s_nop 0
	s_nop 0
	s_nop 0
	s_waitcnt vmcnt(3)
	v_lshlrev_b32_e32 v74, 16, v184
	v_and_b32_e32 v75, 0xffff0000, v184
	v_mul_f32_e32 v82, 0xbfb8aa3b, v111
	v_exp_f32_e32 v111, v82
	v_pk_add_f32 v[78:79], v[78:79], 1.0 op_sel_hi:[1,0]
	v_pk_add_f32 v[110:111], v[110:111], 1.0 op_sel_hi:[1,0]
	s_nop 0
	v_div_scale_f32 v82, s[0:1], v111, v111, 1.0
	v_rcp_f32_e32 v86, v82
	s_nop 0
	v_fma_f32 v101, -v82, v86, 1.0
	v_fmac_f32_e32 v86, v101, v86
	v_div_scale_f32 v101, vcc, 1.0, v111, 1.0
	v_mul_f32_e32 v109, v101, v86
	v_fma_f32 v112, -v82, v109, v101
	v_fmac_f32_e32 v109, v112, v86
	v_fma_f32 v82, -v82, v109, v101
	v_div_fmas_f32 v82, v82, v86, v109
	v_div_fixup_f32 v111, v82, v111, 1.0
	v_div_scale_f32 v82, s[0:1], v110, v110, 1.0
	v_rcp_f32_e32 v86, v82
	s_nop 0
	v_fma_f32 v101, -v82, v86, 1.0
	v_fmac_f32_e32 v86, v101, v86
	v_div_scale_f32 v101, vcc, 1.0, v110, 1.0
	v_mul_f32_e32 v109, v101, v86
	v_fma_f32 v112, -v82, v109, v101
	v_fmac_f32_e32 v109, v112, v86
	v_fma_f32 v82, -v82, v109, v101
	v_div_fmas_f32 v82, v82, v86, v109
	v_div_fixup_f32 v110, v82, v110, 1.0
	v_pk_fma_f32 v[72:73], v[110:111], v[74:75], v[72:73]
	v_mul_f32_e32 v75, 0xbfb8aa3b, v104
	v_lshlrev_b32_e32 v74, 16, v177
	v_exp_f32_e32 v86, v75
	v_and_b32_e32 v75, 0xffff0000, v177
	v_mul_f32_e32 v87, 0xbfb8aa3b, v105
	v_exp_f32_e32 v87, v87
	v_lshlrev_b32_e32 v82, 16, v185
	v_and_b32_e32 v83, 0xffff0000, v185
	v_pk_add_f32 v[86:87], v[86:87], 1.0 op_sel_hi:[1,0]
	s_nop 0
	v_div_scale_f32 v101, s[0:1], v87, v87, 1.0
	v_rcp_f32_e32 v104, v101
	s_nop 0
	v_fma_f32 v105, -v101, v104, 1.0
	v_fmac_f32_e32 v104, v105, v104
	v_div_scale_f32 v105, vcc, 1.0, v87, 1.0
	v_mul_f32_e32 v109, v105, v104
	v_fma_f32 v110, -v101, v109, v105
	v_fmac_f32_e32 v109, v110, v104
	v_fma_f32 v101, -v101, v109, v105
	v_div_fmas_f32 v101, v101, v104, v109
	v_div_fixup_f32 v87, v101, v87, 1.0
	v_div_scale_f32 v101, s[0:1], v86, v86, 1.0
	v_rcp_f32_e32 v104, v101
	s_nop 0
	v_fma_f32 v105, -v101, v104, 1.0
	v_fmac_f32_e32 v104, v105, v104
	v_div_scale_f32 v105, vcc, 1.0, v86, 1.0
	v_mul_f32_e32 v109, v105, v104
	v_fma_f32 v110, -v101, v109, v105
	v_fmac_f32_e32 v109, v110, v104
	v_fma_f32 v101, -v101, v109, v105
	v_div_fmas_f32 v101, v101, v104, v109
	v_div_fixup_f32 v86, v101, v86, 1.0
	v_pk_fma_f32 v[74:75], v[86:87], v[82:83], v[74:75]
	v_lshlrev_b32_e32 v86, 16, v186
	v_and_b32_e32 v87, 0xffff0000, v186
	v_div_scale_f32 v84, s[0:1], v77, v77, 1.0
	v_lshlrev_b32_e32 v82, 16, v178
	v_and_b32_e32 v83, 0xffff0000, v178
	v_rcp_f32_e32 v88, v84
	s_nop 0
	v_fma_f32 v101, -v84, v88, 1.0
	v_fmac_f32_e32 v88, v101, v88
	v_div_scale_f32 v101, vcc, 1.0, v77, 1.0
	v_mul_f32_e32 v104, v101, v88
	v_fma_f32 v105, -v84, v104, v101
	v_fmac_f32_e32 v104, v105, v88
	v_fma_f32 v84, -v84, v104, v101
	v_div_fmas_f32 v84, v84, v88, v104
	v_div_fixup_f32 v77, v84, v77, 1.0
	v_div_scale_f32 v84, s[0:1], v76, v76, 1.0
	v_rcp_f32_e32 v88, v84
	s_nop 0
	v_fma_f32 v101, -v84, v88, 1.0
	v_fmac_f32_e32 v88, v101, v88
	v_div_scale_f32 v101, vcc, 1.0, v76, 1.0
; __device__ __forceinline__ unsigned cvt_pk_bf16(float lo, float hi) { unsigned r; asm("v_cvt_pk_bf16_f32 %0, %1, %2" : "=v"(r) : "v"(lo), "v"(hi)); return r; }
; __device__ __forceinline__ float bf_lo(unsigned u) { return __uint_as_float(u << 16); }
; __device__ __forceinline__ float bf_hi(unsigned u) { return __uint_as_float(u & 0xffff0000u); }
; __device__ __forceinline__ float sigmoidf_(float x) { return 1.f / (1.f + __expf(-x)); }
;   __device__ __forceinline__ void operator()(const f32x4 (&acc)[2][2][4][2], const Unit& u, const EpiCtx& x_, int wr, int wc, int fr, int fq) const {
;     ...
;           const f32x4 a = acc[ai][bj][m][0] * rs, b = acc[ai][bj][m][1] * rs;
;           f32x4 xa, xc;
;           xa[0] = bf_lo(xi.x) + bf_lo(pe.x) * sigmoidf_(a[0]); xa[1] = bf_hi(xi.x) + bf_hi(pe.x) * sigmoidf_(a[1]);
;           xa[2] = bf_lo(xi.y) + bf_lo(pe.y) * sigmoidf_(a[2]); xa[3] = bf_hi(xi.y) + bf_hi(pe.y) * sigmoidf_(a[3]);
;           xc[0] = bf_lo(xi.z) + bf_lo(pe.z) * sigmoidf_(b[0]); xc[1] = bf_hi(xi.z) + bf_hi(pe.z) * sigmoidf_(b[1]);
;           xc[2] = bf_lo(xi.w) + bf_lo(pe.w) * sigmoidf_(b[2]); xc[3] = bf_hi(xi.w) + bf_hi(pe.w) * sigmoidf_(b[3]);
;           sq += xa[0] * xa[0] + xa[1] * xa[1] + xa[2] * xa[2] + xa[3] * xa[3] + xc[0] * xc[0] + xc[1] * xc[1] + xc[2] * xc[2] + xc[3] * xc[3];
;           uint4 o; o.x = cvt_pk_bf16(xa[0], xa[1]); o.y = cvt_pk_bf16(xa[2], xa[3]); o.z = cvt_pk_bf16(xc[0], xc[1]); o.w = cvt_pk_bf16(xc[2], xc[3]);
;           *(uint4*)(xbp + cb) = o;
;           if (last) { float* op = (float*)u.C + (size_t)row * DM + cb; *(f32x4*)op = xa; *(f32x4*)(op + 4) = xc; }
	v_mul_f32_e32 v104, v101, v88
	v_fma_f32 v105, -v84, v104, v101
	v_fmac_f32_e32 v104, v105, v88
	v_fma_f32 v84, -v84, v104, v101
	v_div_fmas_f32 v84, v84, v88, v104
	v_div_fixup_f32 v76, v84, v76, 1.0
	v_pk_fma_f32 v[76:77], v[76:77], v[86:87], v[82:83]
	v_div_scale_f32 v86, s[0:1], v79, v79, 1.0
	v_rcp_f32_e32 v87, v86
	v_lshlrev_b32_e32 v82, 16, v179
	v_and_b32_e32 v83, 0xffff0000, v179
	v_lshlrev_b32_e32 v84, 16, v187
	v_fma_f32 v88, -v86, v87, 1.0
	v_fmac_f32_e32 v87, v88, v87
	v_div_scale_f32 v88, vcc, 1.0, v79, 1.0
	v_mul_f32_e32 v89, v88, v87
	v_fma_f32 v101, -v86, v89, v88
	v_fmac_f32_e32 v89, v101, v87
	v_fma_f32 v86, -v86, v89, v88
	v_div_fmas_f32 v86, v86, v87, v89
	v_div_fixup_f32 v79, v86, v79, 1.0
	v_div_scale_f32 v86, s[0:1], v78, v78, 1.0
	v_rcp_f32_e32 v87, v86
	v_and_b32_e32 v85, 0xffff0000, v187
	v_fma_f32 v88, -v86, v87, 1.0
	v_fmac_f32_e32 v87, v88, v87
	v_div_scale_f32 v88, vcc, 1.0, v78, 1.0
	v_mul_f32_e32 v89, v88, v87
	v_fma_f32 v101, -v86, v89, v88
	v_fmac_f32_e32 v89, v101, v87
	v_fma_f32 v86, -v86, v89, v88
	v_div_fmas_f32 v86, v86, v87, v89
	v_div_fixup_f32 v78, v86, v78, 1.0
	v_pk_fma_f32 v[78:79], v[78:79], v[84:85], v[82:83]
	v_lshl_add_u64 v[86:87], v[94:95], 0, v[142:143]
	s_and_b64 vcc, exec, s[4:5]
	v_cvt_pk_bf16_f32 v82, v72, v73
	v_cvt_pk_bf16_f32 v83, v74, v75
	v_cvt_pk_bf16_f32 v84, v76, v77
	v_cvt_pk_bf16_f32 v85, v78, v79
	global_store_dwordx4 v[86:87], v[82:85], off nt
	s_cbranch_vccnz .LBB0_979
	s_nop 0
	v_lshl_add_u64 v[82:83], v[140:141], 2, v[102:103]
	global_store_dwordx4 v[82:83], v[72:75], off nt
	global_store_dwordx4 v[82:83], v[76:79], off offset:16 nt
; __device__ __forceinline__ unsigned cvt_pk_bf16(float lo, float hi) { unsigned r; asm("v_cvt_pk_bf16_f32 %0, %1, %2" : "=v"(r) : "v"(lo), "v"(hi)); return r; }
; __device__ __forceinline__ float bf_lo(unsigned u) { return __uint_as_float(u << 16); }
; __device__ __forceinline__ float bf_hi(unsigned u) { return __uint_as_float(u & 0xffff0000u); }
; __device__ __forceinline__ float sigmoidf_(float x) { return 1.f / (1.f + __expf(-x)); }
;   __device__ __forceinline__ void operator()(const f32x4 (&acc)[2][2][4][2], const Unit& u, const EpiCtx& x_, int wr, int wc, int fr, int fq) const {
;     ...
;         for (int bj = 0; bj < 2; ++bj) {
;           const int cb = u.c0 + wc * 64 + bj * 32 + 8 * fq;
;           const uint4 pe = *(const uint4*)(pep + cb), xi = *(const uint4*)(xin + cb);
;           const f32x4 a = acc[ai][bj][m][0] * rs, b = acc[ai][bj][m][1] * rs;
;           f32x4 xa, xc;
;           xa[0] = bf_lo(xi.x) + bf_lo(pe.x) * sigmoidf_(a[0]); xa[1] = bf_hi(xi.x) + bf_hi(pe.x) * sigmoidf_(a[1]);
;           xa[2] = bf_lo(xi.y) + bf_lo(pe.y) * sigmoidf_(a[2]); xa[3] = bf_hi(xi.y) + bf_hi(pe.y) * sigmoidf_(a[3]);
;           xc[0] = bf_lo(xi.z) + bf_lo(pe.z) * sigmoidf_(b[0]); xc[1] = bf_hi(xi.z) + bf_hi(pe.z) * sigmoidf_(b[1]);
;           xc[2] = bf_lo(xi.w) + bf_lo(pe.w) * sigmoidf_(b[2]); xc[3] = bf_hi(xi.w) + bf_hi(pe.w) * sigmoidf_(b[3]);
;           sq += xa[0] * xa[0] + xa[1] * xa[1] + xa[2] * xa[2] + xa[3] * xa[3] + xc[0] * xc[0] + xc[1] * xc[1] + xc[2] * xc[2] + xc[3] * xc[3];
;           uint4 o; o.x = cvt_pk_bf16(xa[0], xa[1]); o.y = cvt_pk_bf16(xa[2], xa[3]); o.z = cvt_pk_bf16(xc[0], xc[1]); o.w = cvt_pk_bf16(xc[2], xc[3]);
;           *(uint4*)(xbp + cb) = o;
;           if (last) { float* op = (float*)u.C + (size_t)row * DM + cb; *(f32x4*)op = xa; *(f32x4*)(op + 4) = xc; }
.LBB0_979:
	s_nop 1
	v_add_u32_e32 v198, 0x80, v146
	v_ashrrev_i32_e32 v199, 31, v198
	v_lshl_add_u64 v[200:201], v[198:199], 3, s[96:97]
	global_load_dwordx2 v[174:175], v[200:201], off
	v_lshlrev_b64 v[200:201], 12, v[198:199]
	v_lshl_add_u64 v[202:203], s[94:95], 0, v[200:201]
	v_lshl_add_u64 v[204:205], v[202:203], 0, v[142:143]
	global_load_dwordx4 v[176:179], v[204:205], off
	v_lshl_add_u64 v[202:203], s[92:93], 0, v[200:201]
	v_lshl_add_u64 v[204:205], v[202:203], 0, v[142:143]
	global_load_dwordx4 v[184:187], v[204:205], off
	s_nop 0
	v_lshl_add_u64 v[82:83], v[98:99], 0, v[144:145]
	s_nop 0
	v_lshl_add_u64 v[86:87], v[96:97], 0, v[144:145]
	s_nop 0
	v_mov_b32_e32 v101, v100
	v_mov_b32_e32 v96, v100
	v_mov_b32_e32 v97, v100
	v_pk_mul_f32 v[104:105], v[68:69], v[100:101]
	v_pk_mul_f32 v[98:99], v[70:71], v[96:97]
	v_pk_mul_f32 v[70:71], v[66:67], v[96:97]
	v_pk_mul_f32 v[68:69], v[64:65], v[100:101]
	v_mul_f32_e32 v65, 0xbfb8aa3b, v104
	v_exp_f32_e32 v96, v65
	v_mul_f32_e32 v68, 0xbfb8aa3b, v68
	v_mul_f32_e32 v69, 0xbfb8aa3b, v69
	v_exp_f32_e32 v68, v68
	v_exp_f32_e32 v69, v69
	v_mul_f32_e32 v70, 0xbfb8aa3b, v70
	v_mul_f32_e32 v71, 0xbfb8aa3b, v71
	v_exp_f32_e32 v70, v70
	v_pk_add_f32 v[68:69], v[68:69], 1.0 op_sel_hi:[1,0]
	v_exp_f32_e32 v71, v71
	s_waitcnt lgkmcnt(0)
	s_nop 0
	s_nop 0
	s_nop 0
	s_nop 0
	s_nop 0
	s_nop 0
	s_nop 0
	s_nop 0
	s_nop 0
	s_nop 0
	s_nop 0
	s_nop 0
	s_nop 0
	s_nop 0
	s_waitcnt vmcnt(5)
	v_lshlrev_b32_e32 v66, 16, v190
	v_and_b32_e32 v67, 0xffff0000, v190
	v_mul_f32_e32 v82, 0xbfb8aa3b, v105
	v_exp_f32_e32 v97, v82
	s_nop 0
	s_nop 0
	s_nop 0
	s_nop 0
	s_nop 0
	s_nop 0
	s_nop 0
	s_nop 0
	s_nop 0
	s_nop 0
	s_nop 0
	s_nop 0
	s_nop 0
	s_nop 0
	s_waitcnt vmcnt(4)
	v_lshlrev_b32_e32 v64, 16, v194
	v_and_b32_e32 v65, 0xffff0000, v194
	v_pk_add_f32 v[70:71], v[70:71], 1.0 op_sel_hi:[1,0]
	v_pk_add_f32 v[96:97], v[96:97], 1.0 op_sel_hi:[1,0]
	s_nop 0
	v_div_scale_f32 v82, s[0:1], v97, v97, 1.0
	v_rcp_f32_e32 v86, v82
	s_nop 0
	v_fma_f32 v100, -v82, v86, 1.0
	v_fmac_f32_e32 v86, v100, v86
	v_div_scale_f32 v100, vcc, 1.0, v97, 1.0
	v_mul_f32_e32 v101, v100, v86
	v_fma_f32 v104, -v82, v101, v100
	v_fmac_f32_e32 v101, v104, v86
	v_fma_f32 v82, -v82, v101, v100
	v_div_fmas_f32 v82, v82, v86, v101
	v_div_fixup_f32 v97, v82, v97, 1.0
	v_div_scale_f32 v82, s[0:1], v96, v96, 1.0
	v_rcp_f32_e32 v86, v82
	s_nop 0
	v_fma_f32 v100, -v82, v86, 1.0
	v_fmac_f32_e32 v86, v100, v86
	v_div_scale_f32 v100, vcc, 1.0, v96, 1.0
	v_mul_f32_e32 v101, v100, v86
	v_fma_f32 v104, -v82, v101, v100
	v_fmac_f32_e32 v101, v104, v86
	v_fma_f32 v82, -v82, v101, v100
	v_div_fmas_f32 v82, v82, v86, v101
	v_div_fixup_f32 v96, v82, v96, 1.0
	v_pk_fma_f32 v[64:65], v[96:97], v[66:67], v[64:65]
	v_mul_f32_e32 v67, 0xbfb8aa3b, v98
	v_lshlrev_b32_e32 v66, 16, v195
	v_exp_f32_e32 v86, v67
	v_and_b32_e32 v67, 0xffff0000, v195
	v_mul_f32_e32 v87, 0xbfb8aa3b, v99
	v_exp_f32_e32 v87, v87
	v_lshlrev_b32_e32 v82, 16, v191
	v_and_b32_e32 v83, 0xffff0000, v191
	v_pk_add_f32 v[86:87], v[86:87], 1.0 op_sel_hi:[1,0]
	s_nop 0
	v_div_scale_f32 v96, s[0:1], v87, v87, 1.0
	v_rcp_f32_e32 v97, v96
	s_nop 0
	v_fma_f32 v98, -v96, v97, 1.0
	v_fmac_f32_e32 v97, v98, v97
	v_div_scale_f32 v98, vcc, 1.0, v87, 1.0
	v_mul_f32_e32 v99, v98, v97
	v_fma_f32 v100, -v96, v99, v98
	v_fmac_f32_e32 v99, v100, v97
	v_fma_f32 v96, -v96, v99, v98
	v_div_fmas_f32 v96, v96, v97, v99
	v_div_fixup_f32 v87, v96, v87, 1.0
	v_div_scale_f32 v96, s[0:1], v86, v86, 1.0
	v_rcp_f32_e32 v97, v96
	s_nop 0
	v_fma_f32 v98, -v96, v97, 1.0
	v_fmac_f32_e32 v97, v98, v97
	v_div_scale_f32 v98, vcc, 1.0, v86, 1.0
	v_mul_f32_e32 v99, v98, v97
	v_fma_f32 v100, -v96, v99, v98
	v_fmac_f32_e32 v99, v100, v97
	v_fma_f32 v96, -v96, v99, v98
	v_div_fmas_f32 v96, v96, v97, v99
	v_div_fixup_f32 v86, v96, v86, 1.0
	v_pk_fma_f32 v[66:67], v[86:87], v[82:83], v[66:67]
	v_lshlrev_b32_e32 v86, 16, v192
	v_and_b32_e32 v87, 0xffff0000, v192
	v_div_scale_f32 v84, s[0:1], v69, v69, 1.0
	v_lshlrev_b32_e32 v82, 16, v196
	v_and_b32_e32 v83, 0xffff0000, v196
	v_rcp_f32_e32 v88, v84
	s_nop 0
	v_fma_f32 v96, -v84, v88, 1.0
	v_fmac_f32_e32 v88, v96, v88
	v_div_scale_f32 v96, vcc, 1.0, v69, 1.0
	v_mul_f32_e32 v97, v96, v88
	v_fma_f32 v98, -v84, v97, v96
	v_fmac_f32_e32 v97, v98, v88
	v_fma_f32 v84, -v84, v97, v96
	v_div_fmas_f32 v84, v84, v88, v97
	v_div_fixup_f32 v69, v84, v69, 1.0
	v_div_scale_f32 v84, s[0:1], v68, v68, 1.0
	v_rcp_f32_e32 v88, v84
	s_nop 0
	v_fma_f32 v96, -v84, v88, 1.0
	v_fmac_f32_e32 v88, v96, v88
	v_div_scale_f32 v96, vcc, 1.0, v68, 1.0
	v_mul_f32_e32 v97, v96, v88
	v_fma_f32 v98, -v84, v97, v96
	v_fmac_f32_e32 v97, v98, v88
	v_fma_f32 v84, -v84, v97, v96
	v_div_fmas_f32 v84, v84, v88, v97
	v_div_fixup_f32 v68, v84, v68, 1.0
	v_pk_fma_f32 v[68:69], v[68:69], v[86:87], v[82:83]
	v_div_scale_f32 v86, s[0:1], v71, v71, 1.0
	v_rcp_f32_e32 v87, v86
	v_lshlrev_b32_e32 v82, 16, v197
	v_and_b32_e32 v83, 0xffff0000, v197
	v_lshlrev_b32_e32 v84, 16, v193
	v_fma_f32 v88, -v86, v87, 1.0
	v_fmac_f32_e32 v87, v88, v87
	v_div_scale_f32 v88, vcc, 1.0, v71, 1.0
	v_mul_f32_e32 v89, v88, v87
	v_fma_f32 v96, -v86, v89, v88
	v_fmac_f32_e32 v89, v96, v87
	v_fma_f32 v86, -v86, v89, v88
	v_div_fmas_f32 v86, v86, v87, v89
	v_div_fixup_f32 v71, v86, v71, 1.0
	v_div_scale_f32 v86, s[0:1], v70, v70, 1.0
	v_rcp_f32_e32 v87, v86
	v_and_b32_e32 v85, 0xffff0000, v193
	v_fma_f32 v88, -v86, v87, 1.0
	v_fmac_f32_e32 v87, v88, v87
	v_div_scale_f32 v88, vcc, 1.0, v70, 1.0
	v_mul_f32_e32 v89, v88, v87
	v_fma_f32 v96, -v86, v89, v88
	v_fmac_f32_e32 v89, v96, v87
	v_fma_f32 v86, -v86, v89, v88
	v_div_fmas_f32 v86, v86, v87, v89
	v_div_fixup_f32 v70, v86, v70, 1.0
	v_pk_fma_f32 v[70:71], v[70:71], v[84:85], v[82:83]
	v_lshl_add_u64 v[86:87], v[94:95], 0, v[144:145]
	s_and_b64 vcc, exec, s[4:5]
	v_cvt_pk_bf16_f32 v82, v64, v65
	v_cvt_pk_bf16_f32 v83, v66, v67
	v_cvt_pk_bf16_f32 v84, v68, v69
	v_cvt_pk_bf16_f32 v85, v70, v71
	global_store_dwordx4 v[86:87], v[82:85], off nt
	s_cbranch_vccnz .LBB0_981
	s_nop 0
	v_lshl_add_u64 v[82:83], v[138:139], 2, v[102:103]
	global_store_dwordx4 v[82:83], v[64:67], off nt
	global_store_dwordx4 v[82:83], v[68:71], off offset:16 nt

; __device__ __forceinline__ unsigned cvt_pk_bf16(float lo, float hi) { unsigned r; asm("v_cvt_pk_bf16_f32 %0, %1, %2" : "=v"(r) : "v"(lo), "v"(hi)); return r; }
; __device__ __forceinline__ float bf_lo(unsigned u) { return __uint_as_float(u << 16); }
; __device__ __forceinline__ float bf_hi(unsigned u) { return __uint_as_float(u & 0xffff0000u); }
; __device__ __forceinline__ float sigmoidf_(float x) { return 1.f / (1.f + __expf(-x)); }
; __device__ __forceinline__ float rinv_of(unsigned long long ss) { return rsqrtf((float)ss * (1.f / 16777216.f) * (1.f / DM) + 1e-6f); }
;   __device__ __forceinline__ void operator()(const f32x4 (&acc)[2][2][4][2], const Unit& u, const EpiCtx& x_, int wr, int wc, int fr, int fq) const {
;     ...
;         const int row = (u.r0 + (ai ? x_.rdelta : 0)) + wr * 64 + m * 16 + fr;
;         const bf16_t* pep = (const bf16_t*)x_.aux + (size_t)row * DM;
;         const bf16_t* xin = (const bf16_t*)x_.aux2 + (size_t)row * DM;
;         bf16_t* xbp = x_.xb + (size_t)row * DM;
;         const float rs = rinv_of(x_.ss[row]);
;         float sq = 0.f;
; #pragma unroll
;         for (int bj = 0; bj < 2; ++bj) {
;           const int cb = u.c0 + wc * 64 + bj * 32 + 8 * fq;
;           const uint4 pe = *(const uint4*)(pep + cb), xi = *(const uint4*)(xin + cb);
;           const f32x4 a = acc[ai][bj][m][0] * rs, b = acc[ai][bj][m][1] * rs;
;           f32x4 xa, xc;
;           xa[0] = bf_lo(xi.x) + bf_lo(pe.x) * sigmoidf_(a[0]); xa[1] = bf_hi(xi.x) + bf_hi(pe.x) * sigmoidf_(a[1]);
;           xa[2] = bf_lo(xi.y) + bf_lo(pe.y) * sigmoidf_(a[2]); xa[3] = bf_hi(xi.y) + bf_hi(pe.y) * sigmoidf_(a[3]);
;           xc[0] = bf_lo(xi.z) + bf_lo(pe.z) * sigmoidf_(b[0]); xc[1] = bf_hi(xi.z) + bf_hi(pe.z) * sigmoidf_(b[1]);
;           xc[2] = bf_lo(xi.w) + bf_lo(pe.w) * sigmoidf_(b[2]); xc[3] = bf_hi(xi.w) + bf_hi(pe.w) * sigmoidf_(b[3]);
;           sq += xa[0] * xa[0] + xa[1] * xa[1] + xa[2] * xa[2] + xa[3] * xa[3] + xc[0] * xc[0] + xc[1] * xc[1] + xc[2] * xc[2] + xc[3] * xc[3];
;           uint4 o; o.x = cvt_pk_bf16(xa[0], xa[1]); o.y = cvt_pk_bf16(xa[2], xa[3]); o.z = cvt_pk_bf16(xc[0], xc[1]); o.w = cvt_pk_bf16(xc[2], xc[3]);
;           *(uint4*)(xbp + cb) = o;
;           if (last) { float* op = (float*)u.C + (size_t)row * DM + cb; *(f32x4*)op = xa; *(f32x4*)(op + 4) = xc; }
.LBB0_983:
	s_or_b64 exec, exec, s[18:19]
	s_nop 1
	v_add_u32_e32 v198, 0x80, v146
	v_ashrrev_i32_e32 v199, 31, v198
	v_lshlrev_b64 v[200:201], 12, v[198:199]
	v_lshl_add_u64 v[202:203], s[92:93], 0, v[200:201]
	v_lshl_add_u64 v[204:205], v[202:203], 0, v[144:145]
	global_load_dwordx4 v[190:193], v[204:205], off
	v_lshl_add_u64 v[202:203], s[94:95], 0, v[200:201]
	v_lshl_add_u64 v[204:205], v[202:203], 0, v[144:145]
	global_load_dwordx4 v[194:197], v[204:205], off
	v_add_u32_e32 v64, 0x80, v146
	s_waitcnt lgkmcnt(0)
	v_ashrrev_i32_e32 v65, 31, v64
	v_lshlrev_b64 v[84:85], 11, v[64:65]
	v_lshlrev_b64 v[66:67], 12, v[64:65]
	v_lshl_add_u64 v[64:65], v[64:65], 3, s[96:97]
	s_nop 0
	v_lshl_add_u64 v[78:79], s[92:93], 0, v[66:67]
	v_lshl_add_u64 v[76:77], s[94:95], 0, v[66:67]
	v_lshl_add_u64 v[74:75], s[90:91], 0, v[66:67]
	v_lshl_add_u64 v[68:69], v[76:77], 0, v[142:143]
	s_nop 0
	v_lshl_add_u64 v[84:85], v[84:85], 2, s[36:37]
	s_waitcnt lgkmcnt(0)
	s_nop 0
	s_nop 0
	s_nop 0
	s_nop 0
	s_nop 0
	s_nop 0
	s_nop 0
	s_nop 0
	s_nop 0
	s_nop 0
	s_nop 0
	s_nop 0
	s_nop 0
	s_nop 0
	s_waitcnt vmcnt(5)
	v_ffbh_u32_e32 v66, v175
	v_min_u32_e32 v66, 32, v66
	v_lshlrev_b64 v[64:65], v66, v[174:175]
	v_min_u32_e32 v64, 1, v64
	v_or_b32_e32 v64, v65, v64
	v_cvt_f32_u32_e32 v64, v64
	v_sub_u32_e32 v65, 32, v66
	v_ldexp_f32 v64, v64, v65
	v_mul_f32_e32 v64, 0x33800000, v64
	v_fmamk_f32 v64, v64, 0x3a000000, v234
	v_cmp_gt_f32_e32 vcc, s50, v64
	v_mul_f32_e32 v65, 0x4b800000, v64
	s_nop 0
	v_cndmask_b32_e32 v64, v64, v65, vcc
	v_rsq_f32_e32 v64, v64
	s_nop 0
	v_mul_f32_e32 v65, 0x45800000, v64
	v_cndmask_b32_e32 v82, v64, v65, vcc
	v_lshl_add_u64 v[64:65], v[78:79], 0, v[142:143]
	s_nop 0
	v_pk_mul_f32 v[88:89], v[60:61], v[82:83] op_sel_hi:[1,0]
	v_pk_mul_f32 v[86:87], v[62:63], v[82:83] op_sel_hi:[1,0]
	v_pk_mul_f32 v[62:63], v[58:59], v[82:83] op_sel_hi:[1,0]
	v_pk_mul_f32 v[60:61], v[56:57], v[82:83] op_sel_hi:[1,0]
	v_mul_f32_e32 v57, 0xbfb8aa3b, v88
	v_exp_f32_e32 v88, v57
	s_nop 0
	s_nop 0
	s_nop 0
	s_nop 0
	s_nop 0
	s_nop 0
	s_nop 0
	s_nop 0
	s_nop 0
	s_nop 0
	s_nop 0
	s_nop 0
	s_nop 0
	s_nop 0
	s_waitcnt vmcnt(4)
	v_lshlrev_b32_e32 v56, 16, v176
	v_and_b32_e32 v57, 0xffff0000, v176
	v_mul_f32_e32 v60, 0xbfb8aa3b, v60
	v_mul_f32_e32 v61, 0xbfb8aa3b, v61
	v_exp_f32_e32 v60, v60
	v_exp_f32_e32 v61, v61
	v_mul_f32_e32 v62, 0xbfb8aa3b, v62
	v_mul_f32_e32 v63, 0xbfb8aa3b, v63
	v_exp_f32_e32 v62, v62
	v_pk_add_f32 v[60:61], v[60:61], 1.0 op_sel_hi:[1,0]
	v_exp_f32_e32 v63, v63
	s_waitcnt lgkmcnt(0)
	s_nop 0
	s_nop 0
	s_nop 0
	s_nop 0
	s_nop 0
	s_nop 0
	s_nop 0
	s_nop 0
	s_nop 0
	s_nop 0
	s_nop 0
	s_nop 0
	s_nop 0
	s_nop 0
	s_waitcnt vmcnt(3)
	v_lshlrev_b32_e32 v58, 16, v184
	v_and_b32_e32 v59, 0xffff0000, v184
	v_mul_f32_e32 v64, 0xbfb8aa3b, v89
	v_exp_f32_e32 v89, v64
	v_pk_add_f32 v[62:63], v[62:63], 1.0 op_sel_hi:[1,0]
	v_pk_add_f32 v[88:89], v[88:89], 1.0 op_sel_hi:[1,0]
	s_nop 0
	v_div_scale_f32 v64, s[0:1], v89, v89, 1.0
	v_rcp_f32_e32 v68, v64
	s_nop 0
	v_fma_f32 v83, -v64, v68, 1.0
	v_fmac_f32_e32 v68, v83, v68
	v_div_scale_f32 v83, vcc, 1.0, v89, 1.0
	v_mul_f32_e32 v93, v83, v68
	v_fma_f32 v94, -v64, v93, v83
	v_fmac_f32_e32 v93, v94, v68
	v_fma_f32 v64, -v64, v93, v83
	v_div_fmas_f32 v64, v64, v68, v93
	v_div_fixup_f32 v89, v64, v89, 1.0
	v_div_scale_f32 v64, s[0:1], v88, v88, 1.0
	v_rcp_f32_e32 v68, v64
	s_nop 0
	v_fma_f32 v83, -v64, v68, 1.0
	v_fmac_f32_e32 v68, v83, v68
	v_div_scale_f32 v83, vcc, 1.0, v88, 1.0
	v_mul_f32_e32 v93, v83, v68
	v_fma_f32 v94, -v64, v93, v83
	v_fmac_f32_e32 v93, v94, v68
	v_fma_f32 v64, -v64, v93, v83
	v_div_fmas_f32 v64, v64, v68, v93
	v_div_fixup_f32 v88, v64, v88, 1.0
	v_pk_fma_f32 v[56:57], v[88:89], v[58:59], v[56:57]
	v_mul_f32_e32 v59, 0xbfb8aa3b, v86
	v_lshlrev_b32_e32 v58, 16, v177
	v_exp_f32_e32 v68, v59
	v_and_b32_e32 v59, 0xffff0000, v177
	v_mul_f32_e32 v69, 0xbfb8aa3b, v87
	v_exp_f32_e32 v69, v69
	v_lshlrev_b32_e32 v64, 16, v185
	v_and_b32_e32 v65, 0xffff0000, v185
	v_pk_add_f32 v[68:69], v[68:69], 1.0 op_sel_hi:[1,0]
	s_nop 0
	v_div_scale_f32 v83, s[0:1], v69, v69, 1.0
	v_rcp_f32_e32 v86, v83
	s_nop 0
	v_fma_f32 v87, -v83, v86, 1.0
	v_fmac_f32_e32 v86, v87, v86
	v_div_scale_f32 v87, vcc, 1.0, v69, 1.0
	v_mul_f32_e32 v88, v87, v86
	v_fma_f32 v89, -v83, v88, v87
	v_fmac_f32_e32 v88, v89, v86
	v_fma_f32 v83, -v83, v88, v87
	v_div_fmas_f32 v83, v83, v86, v88
	v_div_fixup_f32 v69, v83, v69, 1.0
	v_div_scale_f32 v83, s[0:1], v68, v68, 1.0
	v_rcp_f32_e32 v86, v83
	s_nop 0
	v_fma_f32 v87, -v83, v86, 1.0
	v_fmac_f32_e32 v86, v87, v86
	v_div_scale_f32 v87, vcc, 1.0, v68, 1.0
	v_mul_f32_e32 v88, v87, v86
	v_fma_f32 v89, -v83, v88, v87
	v_fmac_f32_e32 v88, v89, v86
	v_fma_f32 v83, -v83, v88, v87
	v_div_fmas_f32 v83, v83, v86, v88
	v_div_fixup_f32 v68, v83, v68, 1.0
	v_pk_fma_f32 v[58:59], v[68:69], v[64:65], v[58:59]
	v_lshlrev_b32_e32 v68, 16, v186
	v_and_b32_e32 v69, 0xffff0000, v186
	v_div_scale_f32 v66, s[0:1], v61, v61, 1.0
	v_lshlrev_b32_e32 v64, 16, v178
	v_and_b32_e32 v65, 0xffff0000, v178
	v_rcp_f32_e32 v70, v66
	s_nop 0
	v_fma_f32 v83, -v66, v70, 1.0
	v_fmac_f32_e32 v70, v83, v70
	v_div_scale_f32 v83, vcc, 1.0, v61, 1.0
	v_mul_f32_e32 v86, v83, v70
	v_fma_f32 v87, -v66, v86, v83
	v_fmac_f32_e32 v86, v87, v70
	v_fma_f32 v66, -v66, v86, v83
	v_div_fmas_f32 v66, v66, v70, v86
	v_div_fixup_f32 v61, v66, v61, 1.0
	v_div_scale_f32 v66, s[0:1], v60, v60, 1.0
	v_rcp_f32_e32 v70, v66
	s_nop 0
	v_fma_f32 v83, -v66, v70, 1.0
	v_fmac_f32_e32 v70, v83, v70
	v_div_scale_f32 v83, vcc, 1.0, v60, 1.0
	v_mul_f32_e32 v86, v83, v70
	v_fma_f32 v87, -v66, v86, v83
	v_fmac_f32_e32 v86, v87, v70
	v_fma_f32 v66, -v66, v86, v83
	v_div_fmas_f32 v66, v66, v70, v86
	v_div_fixup_f32 v60, v66, v60, 1.0
	v_pk_fma_f32 v[60:61], v[60:61], v[68:69], v[64:65]
	v_div_scale_f32 v68, s[0:1], v63, v63, 1.0
	v_rcp_f32_e32 v69, v68
	v_lshlrev_b32_e32 v64, 16, v179
	v_and_b32_e32 v65, 0xffff0000, v179
	v_lshlrev_b32_e32 v66, 16, v187
	v_fma_f32 v70, -v68, v69, 1.0
	v_fmac_f32_e32 v69, v70, v69
	v_div_scale_f32 v70, vcc, 1.0, v63, 1.0
	v_mul_f32_e32 v71, v70, v69
	v_fma_f32 v83, -v68, v71, v70
	v_fmac_f32_e32 v71, v83, v69
	v_fma_f32 v68, -v68, v71, v70
	v_div_fmas_f32 v68, v68, v69, v71
	v_div_fixup_f32 v63, v68, v63, 1.0
	v_div_scale_f32 v68, s[0:1], v62, v62, 1.0
	v_rcp_f32_e32 v69, v68
	v_and_b32_e32 v67, 0xffff0000, v187
	v_fma_f32 v70, -v68, v69, 1.0
	v_fmac_f32_e32 v69, v70, v69
	v_div_scale_f32 v70, vcc, 1.0, v62, 1.0
	v_mul_f32_e32 v71, v70, v69
	v_fma_f32 v83, -v68, v71, v70
	v_fmac_f32_e32 v71, v83, v69
	v_fma_f32 v68, -v68, v71, v70
	v_div_fmas_f32 v68, v68, v69, v71
	v_div_fixup_f32 v62, v68, v62, 1.0
	v_pk_fma_f32 v[62:63], v[62:63], v[66:67], v[64:65]
	v_lshl_add_u64 v[68:69], v[74:75], 0, v[142:143]
	s_and_b64 vcc, exec, s[4:5]
	v_cvt_pk_bf16_f32 v64, v56, v57
	v_cvt_pk_bf16_f32 v65, v58, v59
	v_cvt_pk_bf16_f32 v66, v60, v61
	v_cvt_pk_bf16_f32 v67, v62, v63
	global_store_dwordx4 v[68:69], v[64:67], off nt
	s_cbranch_vccnz .LBB0_985
; __device__ __forceinline__ unsigned cvt_pk_bf16(float lo, float hi) { unsigned r; asm("v_cvt_pk_bf16_f32 %0, %1, %2" : "=v"(r) : "v"(lo), "v"(hi)); return r; }
; __device__ __forceinline__ float bf_lo(unsigned u) { return __uint_as_float(u << 16); }
; __device__ __forceinline__ float bf_hi(unsigned u) { return __uint_as_float(u & 0xffff0000u); }
; __device__ __forceinline__ float sigmoidf_(float x) { return 1.f / (1.f + __expf(-x)); }
;   __device__ __forceinline__ void operator()(const f32x4 (&acc)[2][2][4][2], const Unit& u, const EpiCtx& x_, int wr, int wc, int fr, int fq) const {
;     ...
;         for (int bj = 0; bj < 2; ++bj) {
;           const int cb = u.c0 + wc * 64 + bj * 32 + 8 * fq;
;           const uint4 pe = *(const uint4*)(pep + cb), xi = *(const uint4*)(xin + cb);
;           const f32x4 a = acc[ai][bj][m][0] * rs, b = acc[ai][bj][m][1] * rs;
;           f32x4 xa, xc;
;           xa[0] = bf_lo(xi.x) + bf_lo(pe.x) * sigmoidf_(a[0]); xa[1] = bf_hi(xi.x) + bf_hi(pe.x) * sigmoidf_(a[1]);
;           xa[2] = bf_lo(xi.y) + bf_lo(pe.y) * sigmoidf_(a[2]); xa[3] = bf_hi(xi.y) + bf_hi(pe.y) * sigmoidf_(a[3]);
;           xc[0] = bf_lo(xi.z) + bf_lo(pe.z) * sigmoidf_(b[0]); xc[1] = bf_hi(xi.z) + bf_hi(pe.z) * sigmoidf_(b[1]);
;           xc[2] = bf_lo(xi.w) + bf_lo(pe.w) * sigmoidf_(b[2]); xc[3] = bf_hi(xi.w) + bf_hi(pe.w) * sigmoidf_(b[3]);
;           sq += xa[0] * xa[0] + xa[1] * xa[1] + xa[2] * xa[2] + xa[3] * xa[3] + xc[0] * xc[0] + xc[1] * xc[1] + xc[2] * xc[2] + xc[3] * xc[3];
;           uint4 o; o.x = cvt_pk_bf16(xa[0], xa[1]); o.y = cvt_pk_bf16(xa[2], xa[3]); o.z = cvt_pk_bf16(xc[0], xc[1]); o.w = cvt_pk_bf16(xc[2], xc[3]);
;           *(uint4*)(xbp + cb) = o;
;           if (last) { float* op = (float*)u.C + (size_t)row * DM + cb; *(f32x4*)op = xa; *(f32x4*)(op + 4) = xc; }
	s_nop 0
	v_lshl_add_u64 v[64:65], v[140:141], 2, v[84:85]
	global_store_dwordx4 v[64:65], v[56:59], off nt
	global_store_dwordx4 v[64:65], v[60:63], off offset:16 nt
.LBB0_985:
	s_nop 1
	v_add_u32_e32 v198, 0x80, v124
	v_ashrrev_i32_e32 v199, 31, v198
	v_lshl_add_u64 v[200:201], v[198:199], 3, s[96:97]
	global_load_dwordx2 v[174:175], v[200:201], off
	v_lshlrev_b64 v[200:201], 12, v[198:199]
	v_lshl_add_u64 v[202:203], s[94:95], 0, v[200:201]
	v_lshl_add_u64 v[204:205], v[202:203], 0, v[142:143]
	global_load_dwordx4 v[176:179], v[204:205], off
	v_lshl_add_u64 v[202:203], s[92:93], 0, v[200:201]
	v_lshl_add_u64 v[204:205], v[202:203], 0, v[142:143]
	global_load_dwordx4 v[184:187], v[204:205], off
	s_nop 0
	v_lshl_add_u64 v[64:65], v[78:79], 0, v[144:145]
	s_nop 0
	v_lshl_add_u64 v[68:69], v[76:77], 0, v[144:145]
	s_nop 0
	v_mov_b32_e32 v83, v82
	v_mov_b32_e32 v76, v82
	v_mov_b32_e32 v77, v82
	v_pk_mul_f32 v[86:87], v[52:53], v[82:83]
	v_pk_mul_f32 v[78:79], v[54:55], v[76:77]
	v_pk_mul_f32 v[54:55], v[50:51], v[76:77]
	v_pk_mul_f32 v[52:53], v[48:49], v[82:83]
	v_mul_f32_e32 v49, 0xbfb8aa3b, v86
	v_exp_f32_e32 v76, v49
	v_mul_f32_e32 v52, 0xbfb8aa3b, v52
	v_mul_f32_e32 v53, 0xbfb8aa3b, v53
	v_exp_f32_e32 v52, v52
	v_exp_f32_e32 v53, v53
	v_mul_f32_e32 v54, 0xbfb8aa3b, v54
	v_mul_f32_e32 v55, 0xbfb8aa3b, v55
	v_exp_f32_e32 v54, v54
	v_pk_add_f32 v[52:53], v[52:53], 1.0 op_sel_hi:[1,0]
	v_exp_f32_e32 v55, v55
	s_waitcnt lgkmcnt(0)
	s_nop 0
	s_nop 0
	s_nop 0
	s_nop 0
	s_nop 0
	s_nop 0
	s_nop 0
	s_nop 0
	s_nop 0
	s_nop 0
	s_nop 0
	s_nop 0
	s_nop 0
	s_nop 0
	s_waitcnt vmcnt(5)
	v_lshlrev_b32_e32 v50, 16, v190
	v_and_b32_e32 v51, 0xffff0000, v190
	v_mul_f32_e32 v64, 0xbfb8aa3b, v87
	v_exp_f32_e32 v77, v64
	s_nop 0
	s_nop 0
	s_nop 0
	s_nop 0
	s_nop 0
	s_nop 0
	s_nop 0
	s_nop 0
	s_nop 0
	s_nop 0
	s_nop 0
	s_nop 0
	s_nop 0
	s_nop 0
	s_waitcnt vmcnt(4)
	v_lshlrev_b32_e32 v48, 16, v194
	v_and_b32_e32 v49, 0xffff0000, v194
	v_pk_add_f32 v[54:55], v[54:55], 1.0 op_sel_hi:[1,0]
	v_pk_add_f32 v[76:77], v[76:77], 1.0 op_sel_hi:[1,0]
	s_nop 0
	v_div_scale_f32 v64, s[0:1], v77, v77, 1.0
	v_rcp_f32_e32 v68, v64
	s_nop 0
	v_fma_f32 v82, -v64, v68, 1.0
	v_fmac_f32_e32 v68, v82, v68
	v_div_scale_f32 v82, vcc, 1.0, v77, 1.0
	v_mul_f32_e32 v83, v82, v68
	v_fma_f32 v86, -v64, v83, v82
	v_fmac_f32_e32 v83, v86, v68
	v_fma_f32 v64, -v64, v83, v82
	v_div_fmas_f32 v64, v64, v68, v83
	v_div_fixup_f32 v77, v64, v77, 1.0
	v_div_scale_f32 v64, s[0:1], v76, v76, 1.0
	v_rcp_f32_e32 v68, v64
	s_nop 0
	v_fma_f32 v82, -v64, v68, 1.0
	v_fmac_f32_e32 v68, v82, v68
	v_div_scale_f32 v82, vcc, 1.0, v76, 1.0
	v_mul_f32_e32 v83, v82, v68
	v_fma_f32 v86, -v64, v83, v82
	v_fmac_f32_e32 v83, v86, v68
	v_fma_f32 v64, -v64, v83, v82
	v_div_fmas_f32 v64, v64, v68, v83
	v_div_fixup_f32 v76, v64, v76, 1.0
	v_pk_fma_f32 v[48:49], v[76:77], v[50:51], v[48:49]
	v_mul_f32_e32 v51, 0xbfb8aa3b, v78
	v_lshlrev_b32_e32 v50, 16, v195
	v_exp_f32_e32 v68, v51
	v_and_b32_e32 v51, 0xffff0000, v195
	v_mul_f32_e32 v69, 0xbfb8aa3b, v79
	v_exp_f32_e32 v69, v69
	v_lshlrev_b32_e32 v64, 16, v191
	v_and_b32_e32 v65, 0xffff0000, v191
	v_pk_add_f32 v[68:69], v[68:69], 1.0 op_sel_hi:[1,0]
	s_nop 0
	v_div_scale_f32 v76, s[0:1], v69, v69, 1.0
	v_rcp_f32_e32 v77, v76
	s_nop 0
	v_fma_f32 v78, -v76, v77, 1.0
	v_fmac_f32_e32 v77, v78, v77
	v_div_scale_f32 v78, vcc, 1.0, v69, 1.0
	v_mul_f32_e32 v79, v78, v77
	v_fma_f32 v82, -v76, v79, v78
	v_fmac_f32_e32 v79, v82, v77
	v_fma_f32 v76, -v76, v79, v78
	v_div_fmas_f32 v76, v76, v77, v79
	v_div_fixup_f32 v69, v76, v69, 1.0
	v_div_scale_f32 v76, s[0:1], v68, v68, 1.0
	v_rcp_f32_e32 v77, v76
	s_nop 0
	v_fma_f32 v78, -v76, v77, 1.0
	v_fmac_f32_e32 v77, v78, v77
	v_div_scale_f32 v78, vcc, 1.0, v68, 1.0
	v_mul_f32_e32 v79, v78, v77
	v_fma_f32 v82, -v76, v79, v78
	v_fmac_f32_e32 v79, v82, v77
	v_fma_f32 v76, -v76, v79, v78
	v_div_fmas_f32 v76, v76, v77, v79
	v_div_fixup_f32 v68, v76, v68, 1.0
	v_pk_fma_f32 v[50:51], v[68:69], v[64:65], v[50:51]
	v_lshlrev_b32_e32 v68, 16, v192
	v_and_b32_e32 v69, 0xffff0000, v192
	v_div_scale_f32 v66, s[0:1], v53, v53, 1.0
	v_lshlrev_b32_e32 v64, 16, v196
	v_and_b32_e32 v65, 0xffff0000, v196
	v_rcp_f32_e32 v70, v66
	s_nop 0
	v_fma_f32 v76, -v66, v70, 1.0
	v_fmac_f32_e32 v70, v76, v70
	v_div_scale_f32 v76, vcc, 1.0, v53, 1.0
	v_mul_f32_e32 v77, v76, v70
	v_fma_f32 v78, -v66, v77, v76
	v_fmac_f32_e32 v77, v78, v70
	v_fma_f32 v66, -v66, v77, v76
	v_div_fmas_f32 v66, v66, v70, v77
	v_div_fixup_f32 v53, v66, v53, 1.0
	v_div_scale_f32 v66, s[0:1], v52, v52, 1.0
	v_rcp_f32_e32 v70, v66
	s_nop 0
	v_fma_f32 v76, -v66, v70, 1.0
	v_fmac_f32_e32 v70, v76, v70
	v_div_scale_f32 v76, vcc, 1.0, v52, 1.0
	v_mul_f32_e32 v77, v76, v70
	v_fma_f32 v78, -v66, v77, v76
	v_fmac_f32_e32 v77, v78, v70
	v_fma_f32 v66, -v66, v77, v76
	v_div_fmas_f32 v66, v66, v70, v77
	v_div_fixup_f32 v52, v66, v52, 1.0
	v_pk_fma_f32 v[52:53], v[52:53], v[68:69], v[64:65]
	v_div_scale_f32 v68, s[0:1], v55, v55, 1.0
	v_rcp_f32_e32 v69, v68
	v_lshlrev_b32_e32 v64, 16, v197
	v_and_b32_e32 v65, 0xffff0000, v197
	v_lshlrev_b32_e32 v66, 16, v193
	v_fma_f32 v70, -v68, v69, 1.0
	v_fmac_f32_e32 v69, v70, v69
	v_div_scale_f32 v70, vcc, 1.0, v55, 1.0
	v_mul_f32_e32 v71, v70, v69
	v_fma_f32 v76, -v68, v71, v70
	v_fmac_f32_e32 v71, v76, v69
	v_fma_f32 v68, -v68, v71, v70
	v_div_fmas_f32 v68, v68, v69, v71
	v_div_fixup_f32 v55, v68, v55, 1.0
	v_div_scale_f32 v68, s[0:1], v54, v54, 1.0
	v_rcp_f32_e32 v69, v68
	v_and_b32_e32 v67, 0xffff0000, v193
	v_fma_f32 v70, -v68, v69, 1.0
	v_fmac_f32_e32 v69, v70, v69
	v_div_scale_f32 v70, vcc, 1.0, v54, 1.0
	v_mul_f32_e32 v71, v70, v69
	v_fma_f32 v76, -v68, v71, v70
	v_fmac_f32_e32 v71, v76, v69
	v_fma_f32 v68, -v68, v71, v70
	v_div_fmas_f32 v68, v68, v69, v71
	v_div_fixup_f32 v54, v68, v54, 1.0
	v_pk_fma_f32 v[54:55], v[54:55], v[66:67], v[64:65]
	v_lshl_add_u64 v[68:69], v[74:75], 0, v[144:145]
	s_and_b64 vcc, exec, s[4:5]
	v_cvt_pk_bf16_f32 v64, v48, v49
	v_cvt_pk_bf16_f32 v65, v50, v51
	v_cvt_pk_bf16_f32 v66, v52, v53
	v_cvt_pk_bf16_f32 v67, v54, v55
	global_store_dwordx4 v[68:69], v[64:67], off nt
	s_cbranch_vccnz .LBB0_987
	s_nop 0
	v_lshl_add_u64 v[64:65], v[138:139], 2, v[84:85]
	global_store_dwordx4 v[64:65], v[48:51], off nt
	global_store_dwordx4 v[64:65], v[52:55], off offset:16 nt

; __device__ __forceinline__ unsigned cvt_pk_bf16(float lo, float hi) { unsigned r; asm("v_cvt_pk_bf16_f32 %0, %1, %2" : "=v"(r) : "v"(lo), "v"(hi)); return r; }
; __device__ __forceinline__ float bf_lo(unsigned u) { return __uint_as_float(u << 16); }
; __device__ __forceinline__ float bf_hi(unsigned u) { return __uint_as_float(u & 0xffff0000u); }
; __device__ __forceinline__ float sigmoidf_(float x) { return 1.f / (1.f + __expf(-x)); }
; __device__ __forceinline__ float rinv_of(unsigned long long ss) { return rsqrtf((float)ss * (1.f / 16777216.f) * (1.f / DM) + 1e-6f); }
;   __device__ __forceinline__ void operator()(const f32x4 (&acc)[2][2][4][2], const Unit& u, const EpiCtx& x_, int wr, int wc, int fr, int fq) const {
;     ...
;         const int row = (u.r0 + (ai ? x_.rdelta : 0)) + wr * 64 + m * 16 + fr;
;         const bf16_t* pep = (const bf16_t*)x_.aux + (size_t)row * DM;
;         const bf16_t* xin = (const bf16_t*)x_.aux2 + (size_t)row * DM;
;         bf16_t* xbp = x_.xb + (size_t)row * DM;
;         const float rs = rinv_of(x_.ss[row]);
;         float sq = 0.f;
; #pragma unroll
;         for (int bj = 0; bj < 2; ++bj) {
;           const int cb = u.c0 + wc * 64 + bj * 32 + 8 * fq;
;           const uint4 pe = *(const uint4*)(pep + cb), xi = *(const uint4*)(xin + cb);
;           const f32x4 a = acc[ai][bj][m][0] * rs, b = acc[ai][bj][m][1] * rs;
;           f32x4 xa, xc;
;           xa[0] = bf_lo(xi.x) + bf_lo(pe.x) * sigmoidf_(a[0]); xa[1] = bf_hi(xi.x) + bf_hi(pe.x) * sigmoidf_(a[1]);
;           xa[2] = bf_lo(xi.y) + bf_lo(pe.y) * sigmoidf_(a[2]); xa[3] = bf_hi(xi.y) + bf_hi(pe.y) * sigmoidf_(a[3]);
;           xc[0] = bf_lo(xi.z) + bf_lo(pe.z) * sigmoidf_(b[0]); xc[1] = bf_hi(xi.z) + bf_hi(pe.z) * sigmoidf_(b[1]);
;           xc[2] = bf_lo(xi.w) + bf_lo(pe.w) * sigmoidf_(b[2]); xc[3] = bf_hi(xi.w) + bf_hi(pe.w) * sigmoidf_(b[3]);
;           sq += xa[0] * xa[0] + xa[1] * xa[1] + xa[2] * xa[2] + xa[3] * xa[3] + xc[0] * xc[0] + xc[1] * xc[1] + xc[2] * xc[2] + xc[3] * xc[3];
;           uint4 o; o.x = cvt_pk_bf16(xa[0], xa[1]); o.y = cvt_pk_bf16(xa[2], xa[3]); o.z = cvt_pk_bf16(xc[0], xc[1]); o.w = cvt_pk_bf16(xc[2], xc[3]);
;           *(uint4*)(xbp + cb) = o;
;           if (last) { float* op = (float*)u.C + (size_t)row * DM + cb; *(f32x4*)op = xa; *(f32x4*)(op + 4) = xc; }
.LBB0_989:
	s_or_b64 exec, exec, s[18:19]
	s_nop 1
	v_add_u32_e32 v198, 0x80, v124
	v_ashrrev_i32_e32 v199, 31, v198
	v_lshlrev_b64 v[200:201], 12, v[198:199]
	v_lshl_add_u64 v[202:203], s[92:93], 0, v[200:201]
	v_lshl_add_u64 v[204:205], v[202:203], 0, v[144:145]
	global_load_dwordx4 v[190:193], v[204:205], off
	v_lshl_add_u64 v[202:203], s[94:95], 0, v[200:201]
	v_lshl_add_u64 v[204:205], v[202:203], 0, v[144:145]
	global_load_dwordx4 v[194:197], v[204:205], off
	v_add_u32_e32 v48, 0x80, v124
	s_waitcnt lgkmcnt(0)
	v_ashrrev_i32_e32 v49, 31, v48
	v_lshlrev_b64 v[64:65], 11, v[48:49]
	v_lshlrev_b64 v[50:51], 12, v[48:49]
	v_lshl_add_u64 v[48:49], v[48:49], 3, s[96:97]
	s_nop 0
	v_lshl_add_u64 v[60:61], s[92:93], 0, v[50:51]
	v_lshl_add_u64 v[58:59], s[94:95], 0, v[50:51]
	v_lshl_add_u64 v[56:57], s[90:91], 0, v[50:51]
	v_lshl_add_u64 v[52:53], v[58:59], 0, v[142:143]
	s_nop 0
	v_lshl_add_u64 v[64:65], v[64:65], 2, s[36:37]
	s_waitcnt lgkmcnt(0)
	s_nop 0
	s_nop 0
	s_nop 0
	s_nop 0
	s_nop 0
	s_nop 0
	s_nop 0
	s_nop 0
	s_nop 0
	s_nop 0
	s_nop 0
	s_nop 0
	s_nop 0
	s_nop 0
	s_waitcnt vmcnt(5)
	v_ffbh_u32_e32 v50, v175
	v_min_u32_e32 v50, 32, v50
	v_lshlrev_b64 v[48:49], v50, v[174:175]
	v_min_u32_e32 v48, 1, v48
	v_or_b32_e32 v48, v49, v48
	v_cvt_f32_u32_e32 v48, v48
	v_sub_u32_e32 v49, 32, v50
	v_ldexp_f32 v48, v48, v49
	v_mul_f32_e32 v48, 0x33800000, v48
	v_fmamk_f32 v48, v48, 0x3a000000, v234
	v_cmp_gt_f32_e32 vcc, s50, v48
	v_mul_f32_e32 v49, 0x4b800000, v48
	s_nop 0
	v_cndmask_b32_e32 v48, v48, v49, vcc
	v_rsq_f32_e32 v48, v48
	s_nop 0
	v_mul_f32_e32 v49, 0x45800000, v48
	v_cndmask_b32_e32 v62, v48, v49, vcc
	v_lshl_add_u64 v[48:49], v[60:61], 0, v[142:143]
	s_nop 0
	v_pk_mul_f32 v[68:69], v[44:45], v[62:63] op_sel_hi:[1,0]
	v_pk_mul_f32 v[66:67], v[46:47], v[62:63] op_sel_hi:[1,0]
	v_pk_mul_f32 v[46:47], v[42:43], v[62:63] op_sel_hi:[1,0]
	v_pk_mul_f32 v[44:45], v[40:41], v[62:63] op_sel_hi:[1,0]
	v_mul_f32_e32 v41, 0xbfb8aa3b, v68
	v_exp_f32_e32 v68, v41
	s_nop 0
	s_nop 0
	s_nop 0
	s_nop 0
	s_nop 0
	s_nop 0
	s_nop 0
	s_nop 0
	s_nop 0
	s_nop 0
	s_nop 0
	s_nop 0
	s_nop 0
	s_nop 0
	s_waitcnt vmcnt(4)
	v_lshlrev_b32_e32 v40, 16, v176
	v_and_b32_e32 v41, 0xffff0000, v176
	v_mul_f32_e32 v44, 0xbfb8aa3b, v44
	v_mul_f32_e32 v45, 0xbfb8aa3b, v45
	v_exp_f32_e32 v44, v44
	v_exp_f32_e32 v45, v45
	v_mul_f32_e32 v46, 0xbfb8aa3b, v46
	v_mul_f32_e32 v47, 0xbfb8aa3b, v47
	v_exp_f32_e32 v46, v46
	v_pk_add_f32 v[44:45], v[44:45], 1.0 op_sel_hi:[1,0]
	v_exp_f32_e32 v47, v47
	s_waitcnt lgkmcnt(0)
	s_nop 0
	s_nop 0
	s_nop 0
	s_nop 0
	s_nop 0
	s_nop 0
	s_nop 0
	s_nop 0
	s_nop 0
	s_nop 0
	s_nop 0
	s_nop 0
	s_nop 0
	s_nop 0
	s_waitcnt vmcnt(3)
	v_lshlrev_b32_e32 v42, 16, v184
	v_and_b32_e32 v43, 0xffff0000, v184
	v_mul_f32_e32 v48, 0xbfb8aa3b, v69
	v_exp_f32_e32 v69, v48
	v_pk_add_f32 v[46:47], v[46:47], 1.0 op_sel_hi:[1,0]
	v_pk_add_f32 v[68:69], v[68:69], 1.0 op_sel_hi:[1,0]
	s_nop 0
	v_div_scale_f32 v48, s[0:1], v69, v69, 1.0
	v_rcp_f32_e32 v52, v48
	s_nop 0
	v_fma_f32 v63, -v48, v52, 1.0
	v_fmac_f32_e32 v52, v63, v52
	v_div_scale_f32 v63, vcc, 1.0, v69, 1.0
	v_mul_f32_e32 v70, v63, v52
	v_fma_f32 v71, -v48, v70, v63
	v_fmac_f32_e32 v70, v71, v52
	v_fma_f32 v48, -v48, v70, v63
	v_div_fmas_f32 v48, v48, v52, v70
	v_div_fixup_f32 v69, v48, v69, 1.0
	v_div_scale_f32 v48, s[0:1], v68, v68, 1.0
	v_rcp_f32_e32 v52, v48
	s_nop 0
	v_fma_f32 v63, -v48, v52, 1.0
	v_fmac_f32_e32 v52, v63, v52
	v_div_scale_f32 v63, vcc, 1.0, v68, 1.0
	v_mul_f32_e32 v70, v63, v52
	v_fma_f32 v71, -v48, v70, v63
	v_fmac_f32_e32 v70, v71, v52
	v_fma_f32 v48, -v48, v70, v63
	v_div_fmas_f32 v48, v48, v52, v70
	v_div_fixup_f32 v68, v48, v68, 1.0
	v_pk_fma_f32 v[40:41], v[68:69], v[42:43], v[40:41]
	v_mul_f32_e32 v43, 0xbfb8aa3b, v66
	v_lshlrev_b32_e32 v42, 16, v177
	v_exp_f32_e32 v52, v43
	v_and_b32_e32 v43, 0xffff0000, v177
	v_mul_f32_e32 v53, 0xbfb8aa3b, v67
	v_exp_f32_e32 v53, v53
	v_lshlrev_b32_e32 v48, 16, v185
	v_and_b32_e32 v49, 0xffff0000, v185
	v_pk_add_f32 v[52:53], v[52:53], 1.0 op_sel_hi:[1,0]
	s_nop 0
	v_div_scale_f32 v63, s[0:1], v53, v53, 1.0
	v_rcp_f32_e32 v66, v63
	s_nop 0
	v_fma_f32 v67, -v63, v66, 1.0
	v_fmac_f32_e32 v66, v67, v66
	v_div_scale_f32 v67, vcc, 1.0, v53, 1.0
	v_mul_f32_e32 v68, v67, v66
	v_fma_f32 v69, -v63, v68, v67
	v_fmac_f32_e32 v68, v69, v66
	v_fma_f32 v63, -v63, v68, v67
	v_div_fmas_f32 v63, v63, v66, v68
	v_div_fixup_f32 v53, v63, v53, 1.0
	v_div_scale_f32 v63, s[0:1], v52, v52, 1.0
	v_rcp_f32_e32 v66, v63
	s_nop 0
	v_fma_f32 v67, -v63, v66, 1.0
	v_fmac_f32_e32 v66, v67, v66
	v_div_scale_f32 v67, vcc, 1.0, v52, 1.0
	v_mul_f32_e32 v68, v67, v66
	v_fma_f32 v69, -v63, v68, v67
	v_fmac_f32_e32 v68, v69, v66
	v_fma_f32 v63, -v63, v68, v67
	v_div_fmas_f32 v63, v63, v66, v68
	v_div_fixup_f32 v52, v63, v52, 1.0
	v_pk_fma_f32 v[42:43], v[52:53], v[48:49], v[42:43]
	v_lshlrev_b32_e32 v52, 16, v186
	v_and_b32_e32 v53, 0xffff0000, v186
	v_div_scale_f32 v50, s[0:1], v45, v45, 1.0
	v_lshlrev_b32_e32 v48, 16, v178
	v_and_b32_e32 v49, 0xffff0000, v178
	v_rcp_f32_e32 v54, v50
	s_nop 0
	v_fma_f32 v63, -v50, v54, 1.0
	v_fmac_f32_e32 v54, v63, v54
	v_div_scale_f32 v63, vcc, 1.0, v45, 1.0
	v_mul_f32_e32 v66, v63, v54
	v_fma_f32 v67, -v50, v66, v63
	v_fmac_f32_e32 v66, v67, v54
	v_fma_f32 v50, -v50, v66, v63
	v_div_fmas_f32 v50, v50, v54, v66
	v_div_fixup_f32 v45, v50, v45, 1.0
	v_div_scale_f32 v50, s[0:1], v44, v44, 1.0
	v_rcp_f32_e32 v54, v50
	s_nop 0
	v_fma_f32 v63, -v50, v54, 1.0
	v_fmac_f32_e32 v54, v63, v54
	v_div_scale_f32 v63, vcc, 1.0, v44, 1.0
	v_mul_f32_e32 v66, v63, v54
	v_fma_f32 v67, -v50, v66, v63
	v_fmac_f32_e32 v66, v67, v54
	v_fma_f32 v50, -v50, v66, v63
	v_div_fmas_f32 v50, v50, v54, v66
	v_div_fixup_f32 v44, v50, v44, 1.0
	v_pk_fma_f32 v[44:45], v[44:45], v[52:53], v[48:49]
	v_div_scale_f32 v52, s[0:1], v47, v47, 1.0
	v_rcp_f32_e32 v53, v52
	v_lshlrev_b32_e32 v48, 16, v179
	v_and_b32_e32 v49, 0xffff0000, v179
	v_lshlrev_b32_e32 v50, 16, v187
	v_fma_f32 v54, -v52, v53, 1.0
	v_fmac_f32_e32 v53, v54, v53
	v_div_scale_f32 v54, vcc, 1.0, v47, 1.0
	v_mul_f32_e32 v55, v54, v53
	v_fma_f32 v63, -v52, v55, v54
	v_fmac_f32_e32 v55, v63, v53
	v_fma_f32 v52, -v52, v55, v54
	v_div_fmas_f32 v52, v52, v53, v55
	v_div_fixup_f32 v47, v52, v47, 1.0
	v_div_scale_f32 v52, s[0:1], v46, v46, 1.0
	v_rcp_f32_e32 v53, v52
	v_and_b32_e32 v51, 0xffff0000, v187
	v_fma_f32 v54, -v52, v53, 1.0
	v_fmac_f32_e32 v53, v54, v53
	v_div_scale_f32 v54, vcc, 1.0, v46, 1.0
	v_mul_f32_e32 v55, v54, v53
	v_fma_f32 v63, -v52, v55, v54
	v_fmac_f32_e32 v55, v63, v53
	v_fma_f32 v52, -v52, v55, v54
	v_div_fmas_f32 v52, v52, v53, v55
	v_div_fixup_f32 v46, v52, v46, 1.0
	v_pk_fma_f32 v[46:47], v[46:47], v[50:51], v[48:49]
	v_lshl_add_u64 v[52:53], v[56:57], 0, v[142:143]
	s_and_b64 vcc, exec, s[4:5]
	v_cvt_pk_bf16_f32 v48, v40, v41
	v_cvt_pk_bf16_f32 v49, v42, v43
	v_cvt_pk_bf16_f32 v50, v44, v45
	v_cvt_pk_bf16_f32 v51, v46, v47
	global_store_dwordx4 v[52:53], v[48:51], off nt
	s_cbranch_vccnz .LBB0_991
; __device__ __forceinline__ unsigned cvt_pk_bf16(float lo, float hi) { unsigned r; asm("v_cvt_pk_bf16_f32 %0, %1, %2" : "=v"(r) : "v"(lo), "v"(hi)); return r; }
; __device__ __forceinline__ float bf_lo(unsigned u) { return __uint_as_float(u << 16); }
; __device__ __forceinline__ float bf_hi(unsigned u) { return __uint_as_float(u & 0xffff0000u); }
; __device__ __forceinline__ float sigmoidf_(float x) { return 1.f / (1.f + __expf(-x)); }
;   __device__ __forceinline__ void operator()(const f32x4 (&acc)[2][2][4][2], const Unit& u, const EpiCtx& x_, int wr, int wc, int fr, int fq) const {
;     ...
;         for (int bj = 0; bj < 2; ++bj) {
;           const int cb = u.c0 + wc * 64 + bj * 32 + 8 * fq;
;           const uint4 pe = *(const uint4*)(pep + cb), xi = *(const uint4*)(xin + cb);
;           const f32x4 a = acc[ai][bj][m][0] * rs, b = acc[ai][bj][m][1] * rs;
;           f32x4 xa, xc;
;           xa[0] = bf_lo(xi.x) + bf_lo(pe.x) * sigmoidf_(a[0]); xa[1] = bf_hi(xi.x) + bf_hi(pe.x) * sigmoidf_(a[1]);
;           xa[2] = bf_lo(xi.y) + bf_lo(pe.y) * sigmoidf_(a[2]); xa[3] = bf_hi(xi.y) + bf_hi(pe.y) * sigmoidf_(a[3]);
;           xc[0] = bf_lo(xi.z) + bf_lo(pe.z) * sigmoidf_(b[0]); xc[1] = bf_hi(xi.z) + bf_hi(pe.z) * sigmoidf_(b[1]);
;           xc[2] = bf_lo(xi.w) + bf_lo(pe.w) * sigmoidf_(b[2]); xc[3] = bf_hi(xi.w) + bf_hi(pe.w) * sigmoidf_(b[3]);
;           sq += xa[0] * xa[0] + xa[1] * xa[1] + xa[2] * xa[2] + xa[3] * xa[3] + xc[0] * xc[0] + xc[1] * xc[1] + xc[2] * xc[2] + xc[3] * xc[3];
;           uint4 o; o.x = cvt_pk_bf16(xa[0], xa[1]); o.y = cvt_pk_bf16(xa[2], xa[3]); o.z = cvt_pk_bf16(xc[0], xc[1]); o.w = cvt_pk_bf16(xc[2], xc[3]);
;           *(uint4*)(xbp + cb) = o;
;           if (last) { float* op = (float*)u.C + (size_t)row * DM + cb; *(f32x4*)op = xa; *(f32x4*)(op + 4) = xc; }
	s_nop 0
	v_lshl_add_u64 v[48:49], v[140:141], 2, v[64:65]
	global_store_dwordx4 v[48:49], v[40:43], off nt
	global_store_dwordx4 v[48:49], v[44:47], off offset:16 nt
.LBB0_991:
	s_nop 1
	v_add_u32_e32 v198, 0x80, v108
	v_ashrrev_i32_e32 v199, 31, v198
	v_lshl_add_u64 v[200:201], v[198:199], 3, s[96:97]
	global_load_dwordx2 v[174:175], v[200:201], off
	v_lshlrev_b64 v[200:201], 12, v[198:199]
	v_lshl_add_u64 v[202:203], s[94:95], 0, v[200:201]
	v_lshl_add_u64 v[204:205], v[202:203], 0, v[142:143]
	global_load_dwordx4 v[176:179], v[204:205], off
	v_lshl_add_u64 v[202:203], s[92:93], 0, v[200:201]
	v_lshl_add_u64 v[204:205], v[202:203], 0, v[142:143]
	global_load_dwordx4 v[184:187], v[204:205], off
	s_nop 0
	v_lshl_add_u64 v[48:49], v[60:61], 0, v[144:145]
	s_nop 0
	v_lshl_add_u64 v[52:53], v[58:59], 0, v[144:145]
	s_nop 0
	v_mov_b32_e32 v63, v62
	v_mov_b32_e32 v58, v62
	v_mov_b32_e32 v59, v62
	v_pk_mul_f32 v[66:67], v[36:37], v[62:63]
	v_pk_mul_f32 v[60:61], v[38:39], v[58:59]
	v_pk_mul_f32 v[38:39], v[34:35], v[58:59]
	v_pk_mul_f32 v[36:37], v[32:33], v[62:63]
	v_mul_f32_e32 v33, 0xbfb8aa3b, v66
	v_exp_f32_e32 v58, v33
	v_mul_f32_e32 v36, 0xbfb8aa3b, v36
	v_mul_f32_e32 v37, 0xbfb8aa3b, v37
	v_exp_f32_e32 v36, v36
	v_exp_f32_e32 v37, v37
	v_mul_f32_e32 v38, 0xbfb8aa3b, v38
	v_mul_f32_e32 v39, 0xbfb8aa3b, v39
	v_exp_f32_e32 v38, v38
	v_pk_add_f32 v[36:37], v[36:37], 1.0 op_sel_hi:[1,0]
	v_exp_f32_e32 v39, v39
	s_waitcnt lgkmcnt(0)
	s_nop 0
	s_nop 0
	s_nop 0
	s_nop 0
	s_nop 0
	s_nop 0
	s_nop 0
	s_nop 0
	s_nop 0
	s_nop 0
	s_nop 0
	s_nop 0
	s_nop 0
	s_nop 0
	s_waitcnt vmcnt(5)
	v_lshlrev_b32_e32 v34, 16, v190
	v_and_b32_e32 v35, 0xffff0000, v190
	v_mul_f32_e32 v48, 0xbfb8aa3b, v67
	v_exp_f32_e32 v59, v48
	s_nop 0
	s_nop 0
	s_nop 0
	s_nop 0
	s_nop 0
	s_nop 0
	s_nop 0
	s_nop 0
	s_nop 0
	s_nop 0
	s_nop 0
	s_nop 0
	s_nop 0
	s_nop 0
	s_waitcnt vmcnt(4)
	v_lshlrev_b32_e32 v32, 16, v194
	v_and_b32_e32 v33, 0xffff0000, v194
	v_pk_add_f32 v[38:39], v[38:39], 1.0 op_sel_hi:[1,0]
	v_pk_add_f32 v[58:59], v[58:59], 1.0 op_sel_hi:[1,0]
	s_nop 0
	v_div_scale_f32 v48, s[0:1], v59, v59, 1.0
	v_rcp_f32_e32 v52, v48
	s_nop 0
	v_fma_f32 v62, -v48, v52, 1.0
	v_fmac_f32_e32 v52, v62, v52
	v_div_scale_f32 v62, vcc, 1.0, v59, 1.0
	v_mul_f32_e32 v63, v62, v52
	v_fma_f32 v66, -v48, v63, v62
	v_fmac_f32_e32 v63, v66, v52
	v_fma_f32 v48, -v48, v63, v62
	v_div_fmas_f32 v48, v48, v52, v63
	v_div_fixup_f32 v59, v48, v59, 1.0
	v_div_scale_f32 v48, s[0:1], v58, v58, 1.0
	v_rcp_f32_e32 v52, v48
	s_nop 0
	v_fma_f32 v62, -v48, v52, 1.0
	v_fmac_f32_e32 v52, v62, v52
	v_div_scale_f32 v62, vcc, 1.0, v58, 1.0
	v_mul_f32_e32 v63, v62, v52
	v_fma_f32 v66, -v48, v63, v62
	v_fmac_f32_e32 v63, v66, v52
	v_fma_f32 v48, -v48, v63, v62
	v_div_fmas_f32 v48, v48, v52, v63
	v_div_fixup_f32 v58, v48, v58, 1.0
	v_pk_fma_f32 v[32:33], v[58:59], v[34:35], v[32:33]
	v_mul_f32_e32 v35, 0xbfb8aa3b, v60
	v_lshlrev_b32_e32 v34, 16, v195
	v_exp_f32_e32 v52, v35
	v_and_b32_e32 v35, 0xffff0000, v195
	v_mul_f32_e32 v53, 0xbfb8aa3b, v61
	v_exp_f32_e32 v53, v53
	v_lshlrev_b32_e32 v48, 16, v191
	v_and_b32_e32 v49, 0xffff0000, v191
	v_pk_add_f32 v[52:53], v[52:53], 1.0 op_sel_hi:[1,0]
	s_nop 0
	v_div_scale_f32 v58, s[0:1], v53, v53, 1.0
	v_rcp_f32_e32 v59, v58
	s_nop 0
	v_fma_f32 v60, -v58, v59, 1.0
	v_fmac_f32_e32 v59, v60, v59
	v_div_scale_f32 v60, vcc, 1.0, v53, 1.0
	v_mul_f32_e32 v61, v60, v59
	v_fma_f32 v62, -v58, v61, v60
	v_fmac_f32_e32 v61, v62, v59
	v_fma_f32 v58, -v58, v61, v60
	v_div_fmas_f32 v58, v58, v59, v61
	v_div_fixup_f32 v53, v58, v53, 1.0
	v_div_scale_f32 v58, s[0:1], v52, v52, 1.0
	v_rcp_f32_e32 v59, v58
	s_nop 0
	v_fma_f32 v60, -v58, v59, 1.0
	v_fmac_f32_e32 v59, v60, v59
	v_div_scale_f32 v60, vcc, 1.0, v52, 1.0
	v_mul_f32_e32 v61, v60, v59
	v_fma_f32 v62, -v58, v61, v60
	v_fmac_f32_e32 v61, v62, v59
	v_fma_f32 v58, -v58, v61, v60
	v_div_fmas_f32 v58, v58, v59, v61
	v_div_fixup_f32 v52, v58, v52, 1.0
	v_pk_fma_f32 v[34:35], v[52:53], v[48:49], v[34:35]
	v_lshlrev_b32_e32 v52, 16, v192
	v_and_b32_e32 v53, 0xffff0000, v192
	v_div_scale_f32 v50, s[0:1], v37, v37, 1.0
	v_lshlrev_b32_e32 v48, 16, v196
	v_and_b32_e32 v49, 0xffff0000, v196
	v_rcp_f32_e32 v54, v50
	s_nop 0
	v_fma_f32 v58, -v50, v54, 1.0
	v_fmac_f32_e32 v54, v58, v54
	v_div_scale_f32 v58, vcc, 1.0, v37, 1.0
	v_mul_f32_e32 v59, v58, v54
	v_fma_f32 v60, -v50, v59, v58
	v_fmac_f32_e32 v59, v60, v54
	v_fma_f32 v50, -v50, v59, v58
	v_div_fmas_f32 v50, v50, v54, v59
	v_div_fixup_f32 v37, v50, v37, 1.0
	v_div_scale_f32 v50, s[0:1], v36, v36, 1.0
	v_rcp_f32_e32 v54, v50
	s_nop 0
	v_fma_f32 v58, -v50, v54, 1.0
	v_fmac_f32_e32 v54, v58, v54
	v_div_scale_f32 v58, vcc, 1.0, v36, 1.0
	v_mul_f32_e32 v59, v58, v54
	v_fma_f32 v60, -v50, v59, v58
	v_fmac_f32_e32 v59, v60, v54
	v_fma_f32 v50, -v50, v59, v58
	v_div_fmas_f32 v50, v50, v54, v59
	v_div_fixup_f32 v36, v50, v36, 1.0
	v_pk_fma_f32 v[36:37], v[36:37], v[52:53], v[48:49]
	v_div_scale_f32 v52, s[0:1], v39, v39, 1.0
	v_rcp_f32_e32 v53, v52
	v_lshlrev_b32_e32 v48, 16, v197
	v_and_b32_e32 v49, 0xffff0000, v197
	v_lshlrev_b32_e32 v50, 16, v193
	v_fma_f32 v54, -v52, v53, 1.0
	v_fmac_f32_e32 v53, v54, v53
	v_div_scale_f32 v54, vcc, 1.0, v39, 1.0
	v_mul_f32_e32 v55, v54, v53
	v_fma_f32 v58, -v52, v55, v54
	v_fmac_f32_e32 v55, v58, v53
	v_fma_f32 v52, -v52, v55, v54
	v_div_fmas_f32 v52, v52, v53, v55
	v_div_fixup_f32 v39, v52, v39, 1.0
	v_div_scale_f32 v52, s[0:1], v38, v38, 1.0
	v_rcp_f32_e32 v53, v52
	v_and_b32_e32 v51, 0xffff0000, v193
	v_fma_f32 v54, -v52, v53, 1.0
	v_fmac_f32_e32 v53, v54, v53
	v_div_scale_f32 v54, vcc, 1.0, v38, 1.0
	v_mul_f32_e32 v55, v54, v53
	v_fma_f32 v58, -v52, v55, v54
	v_fmac_f32_e32 v55, v58, v53
	v_fma_f32 v52, -v52, v55, v54
	v_div_fmas_f32 v52, v52, v53, v55
	v_div_fixup_f32 v38, v52, v38, 1.0
	v_pk_fma_f32 v[38:39], v[38:39], v[50:51], v[48:49]
	v_lshl_add_u64 v[52:53], v[56:57], 0, v[144:145]
	s_and_b64 vcc, exec, s[4:5]
	v_cvt_pk_bf16_f32 v48, v32, v33
	v_cvt_pk_bf16_f32 v49, v34, v35
	v_cvt_pk_bf16_f32 v50, v36, v37
	v_cvt_pk_bf16_f32 v51, v38, v39
	global_store_dwordx4 v[52:53], v[48:51], off nt
	s_cbranch_vccnz .LBB0_993
	s_nop 0
	v_lshl_add_u64 v[48:49], v[138:139], 2, v[64:65]
	global_store_dwordx4 v[48:49], v[32:35], off nt
	global_store_dwordx4 v[48:49], v[36:39], off offset:16 nt

; __device__ __forceinline__ unsigned cvt_pk_bf16(float lo, float hi) { unsigned r; asm("v_cvt_pk_bf16_f32 %0, %1, %2" : "=v"(r) : "v"(lo), "v"(hi)); return r; }
; __device__ __forceinline__ float bf_lo(unsigned u) { return __uint_as_float(u << 16); }
; __device__ __forceinline__ float bf_hi(unsigned u) { return __uint_as_float(u & 0xffff0000u); }
; __device__ __forceinline__ float sigmoidf_(float x) { return 1.f / (1.f + __expf(-x)); }
; __device__ __forceinline__ float rinv_of(unsigned long long ss) { return rsqrtf((float)ss * (1.f / 16777216.f) * (1.f / DM) + 1e-6f); }
;   __device__ __forceinline__ void operator()(const f32x4 (&acc)[2][2][4][2], const Unit& u, const EpiCtx& x_, int wr, int wc, int fr, int fq) const {
;     ...
;         const int row = (u.r0 + (ai ? x_.rdelta : 0)) + wr * 64 + m * 16 + fr;
;         const bf16_t* pep = (const bf16_t*)x_.aux + (size_t)row * DM;
;         const bf16_t* xin = (const bf16_t*)x_.aux2 + (size_t)row * DM;
;         bf16_t* xbp = x_.xb + (size_t)row * DM;
;         const float rs = rinv_of(x_.ss[row]);
;         float sq = 0.f;
; #pragma unroll
;         for (int bj = 0; bj < 2; ++bj) {
;           const int cb = u.c0 + wc * 64 + bj * 32 + 8 * fq;
;           const uint4 pe = *(const uint4*)(pep + cb), xi = *(const uint4*)(xin + cb);
;           const f32x4 a = acc[ai][bj][m][0] * rs, b = acc[ai][bj][m][1] * rs;
;           f32x4 xa, xc;
;           xa[0] = bf_lo(xi.x) + bf_lo(pe.x) * sigmoidf_(a[0]); xa[1] = bf_hi(xi.x) + bf_hi(pe.x) * sigmoidf_(a[1]);
;           xa[2] = bf_lo(xi.y) + bf_lo(pe.y) * sigmoidf_(a[2]); xa[3] = bf_hi(xi.y) + bf_hi(pe.y) * sigmoidf_(a[3]);
;           xc[0] = bf_lo(xi.z) + bf_lo(pe.z) * sigmoidf_(b[0]); xc[1] = bf_hi(xi.z) + bf_hi(pe.z) * sigmoidf_(b[1]);
;           xc[2] = bf_lo(xi.w) + bf_lo(pe.w) * sigmoidf_(b[2]); xc[3] = bf_hi(xi.w) + bf_hi(pe.w) * sigmoidf_(b[3]);
;           sq += xa[0] * xa[0] + xa[1] * xa[1] + xa[2] * xa[2] + xa[3] * xa[3] + xc[0] * xc[0] + xc[1] * xc[1] + xc[2] * xc[2] + xc[3] * xc[3];
;           uint4 o; o.x = cvt_pk_bf16(xa[0], xa[1]); o.y = cvt_pk_bf16(xa[2], xa[3]); o.z = cvt_pk_bf16(xc[0], xc[1]); o.w = cvt_pk_bf16(xc[2], xc[3]);
;           *(uint4*)(xbp + cb) = o;
;           if (last) { float* op = (float*)u.C + (size_t)row * DM + cb; *(f32x4*)op = xa; *(f32x4*)(op + 4) = xc; }
.LBB0_995:
	s_or_b64 exec, exec, s[18:19]
	s_nop 1
	v_add_u32_e32 v198, 0x80, v108
	v_ashrrev_i32_e32 v199, 31, v198
	v_lshlrev_b64 v[200:201], 12, v[198:199]
	v_lshl_add_u64 v[202:203], s[92:93], 0, v[200:201]
	v_lshl_add_u64 v[204:205], v[202:203], 0, v[144:145]
	global_load_dwordx4 v[190:193], v[204:205], off
	v_lshl_add_u64 v[202:203], s[94:95], 0, v[200:201]
	v_lshl_add_u64 v[204:205], v[202:203], 0, v[144:145]
	global_load_dwordx4 v[194:197], v[204:205], off
	v_add_u32_e32 v32, 0x80, v108
	s_waitcnt lgkmcnt(0)
	v_ashrrev_i32_e32 v33, 31, v32
	v_lshlrev_b64 v[48:49], 11, v[32:33]
	v_lshlrev_b64 v[34:35], 12, v[32:33]
	v_lshl_add_u64 v[32:33], v[32:33], 3, s[96:97]
	s_nop 0
	v_lshl_add_u64 v[44:45], s[92:93], 0, v[34:35]
	v_lshl_add_u64 v[42:43], s[94:95], 0, v[34:35]
	v_lshl_add_u64 v[40:41], s[90:91], 0, v[34:35]
	v_lshl_add_u64 v[36:37], v[42:43], 0, v[142:143]
	s_nop 0
	v_lshl_add_u64 v[48:49], v[48:49], 2, s[36:37]
	s_waitcnt lgkmcnt(0)
	s_nop 0
	s_nop 0
	s_nop 0
	s_nop 0
	s_nop 0
	s_nop 0
	s_nop 0
	s_nop 0
	s_nop 0
	s_nop 0
	s_nop 0
	s_nop 0
	s_nop 0
	s_nop 0
	s_waitcnt vmcnt(5)
	v_ffbh_u32_e32 v34, v175
	v_min_u32_e32 v34, 32, v34
	v_lshlrev_b64 v[32:33], v34, v[174:175]
	v_min_u32_e32 v32, 1, v32
	v_or_b32_e32 v32, v33, v32
	v_cvt_f32_u32_e32 v32, v32
	v_sub_u32_e32 v33, 32, v34
	v_ldexp_f32 v32, v32, v33
	v_mul_f32_e32 v32, 0x33800000, v32
	v_fmamk_f32 v32, v32, 0x3a000000, v234
	v_cmp_gt_f32_e32 vcc, s50, v32
	v_mul_f32_e32 v33, 0x4b800000, v32
	s_nop 0
	v_cndmask_b32_e32 v32, v32, v33, vcc
	v_rsq_f32_e32 v32, v32
	s_nop 0
	v_mul_f32_e32 v33, 0x45800000, v32
	v_cndmask_b32_e32 v46, v32, v33, vcc
	v_lshl_add_u64 v[32:33], v[44:45], 0, v[142:143]
	s_nop 0
	v_pk_mul_f32 v[52:53], v[28:29], v[46:47] op_sel_hi:[1,0]
	v_pk_mul_f32 v[50:51], v[30:31], v[46:47] op_sel_hi:[1,0]
	v_pk_mul_f32 v[30:31], v[26:27], v[46:47] op_sel_hi:[1,0]
	v_pk_mul_f32 v[28:29], v[24:25], v[46:47] op_sel_hi:[1,0]
	v_mul_f32_e32 v25, 0xbfb8aa3b, v52
	v_exp_f32_e32 v52, v25
	s_nop 0
	s_nop 0
	s_nop 0
	s_nop 0
	s_nop 0
	s_nop 0
	s_nop 0
	s_nop 0
	s_nop 0
	s_nop 0
	s_nop 0
	s_nop 0
	s_nop 0
	s_nop 0
	s_waitcnt vmcnt(4)
	v_lshlrev_b32_e32 v24, 16, v176
	v_and_b32_e32 v25, 0xffff0000, v176
	v_mul_f32_e32 v28, 0xbfb8aa3b, v28
	v_mul_f32_e32 v29, 0xbfb8aa3b, v29
	v_exp_f32_e32 v28, v28
	v_exp_f32_e32 v29, v29
	v_mul_f32_e32 v30, 0xbfb8aa3b, v30
	v_mul_f32_e32 v31, 0xbfb8aa3b, v31
	v_exp_f32_e32 v30, v30
	v_pk_add_f32 v[28:29], v[28:29], 1.0 op_sel_hi:[1,0]
	v_exp_f32_e32 v31, v31
	s_waitcnt lgkmcnt(0)
	s_nop 0
	s_nop 0
	s_nop 0
	s_nop 0
	s_nop 0
	s_nop 0
	s_nop 0
	s_nop 0
	s_nop 0
	s_nop 0
	s_nop 0
	s_nop 0
	s_nop 0
	s_nop 0
	s_waitcnt vmcnt(3)
	v_lshlrev_b32_e32 v26, 16, v184
	v_and_b32_e32 v27, 0xffff0000, v184
	v_mul_f32_e32 v32, 0xbfb8aa3b, v53
	v_exp_f32_e32 v53, v32
	v_pk_add_f32 v[30:31], v[30:31], 1.0 op_sel_hi:[1,0]
	v_pk_add_f32 v[52:53], v[52:53], 1.0 op_sel_hi:[1,0]
	s_nop 0
	v_div_scale_f32 v32, s[0:1], v53, v53, 1.0
	v_rcp_f32_e32 v36, v32
	s_nop 0
	v_fma_f32 v47, -v32, v36, 1.0
	v_fmac_f32_e32 v36, v47, v36
	v_div_scale_f32 v47, vcc, 1.0, v53, 1.0
	v_mul_f32_e32 v54, v47, v36
	v_fma_f32 v55, -v32, v54, v47
	v_fmac_f32_e32 v54, v55, v36
	v_fma_f32 v32, -v32, v54, v47
	v_div_fmas_f32 v32, v32, v36, v54
	v_div_fixup_f32 v53, v32, v53, 1.0
	v_div_scale_f32 v32, s[0:1], v52, v52, 1.0
	v_rcp_f32_e32 v36, v32
	s_nop 0
	v_fma_f32 v47, -v32, v36, 1.0
	v_fmac_f32_e32 v36, v47, v36
	v_div_scale_f32 v47, vcc, 1.0, v52, 1.0
	v_mul_f32_e32 v54, v47, v36
	v_fma_f32 v55, -v32, v54, v47
	v_fmac_f32_e32 v54, v55, v36
	v_fma_f32 v32, -v32, v54, v47
	v_div_fmas_f32 v32, v32, v36, v54
	v_div_fixup_f32 v52, v32, v52, 1.0
	v_pk_fma_f32 v[24:25], v[52:53], v[26:27], v[24:25]
	v_mul_f32_e32 v27, 0xbfb8aa3b, v50
	v_lshlrev_b32_e32 v26, 16, v177
	v_exp_f32_e32 v36, v27
	v_and_b32_e32 v27, 0xffff0000, v177
	v_mul_f32_e32 v37, 0xbfb8aa3b, v51
	v_exp_f32_e32 v37, v37
	v_lshlrev_b32_e32 v32, 16, v185
	v_and_b32_e32 v33, 0xffff0000, v185
	v_pk_add_f32 v[36:37], v[36:37], 1.0 op_sel_hi:[1,0]
	s_nop 0
	v_div_scale_f32 v47, s[0:1], v37, v37, 1.0
	v_rcp_f32_e32 v50, v47
	s_nop 0
	v_fma_f32 v51, -v47, v50, 1.0
	v_fmac_f32_e32 v50, v51, v50
	v_div_scale_f32 v51, vcc, 1.0, v37, 1.0
	v_mul_f32_e32 v52, v51, v50
	v_fma_f32 v53, -v47, v52, v51
	v_fmac_f32_e32 v52, v53, v50
	v_fma_f32 v47, -v47, v52, v51
	v_div_fmas_f32 v47, v47, v50, v52
	v_div_fixup_f32 v37, v47, v37, 1.0
	v_div_scale_f32 v47, s[0:1], v36, v36, 1.0
	v_rcp_f32_e32 v50, v47
	s_nop 0
	v_fma_f32 v51, -v47, v50, 1.0
	v_fmac_f32_e32 v50, v51, v50
	v_div_scale_f32 v51, vcc, 1.0, v36, 1.0
	v_mul_f32_e32 v52, v51, v50
	v_fma_f32 v53, -v47, v52, v51
	v_fmac_f32_e32 v52, v53, v50
	v_fma_f32 v47, -v47, v52, v51
	v_div_fmas_f32 v47, v47, v50, v52
	v_div_fixup_f32 v36, v47, v36, 1.0
	v_pk_fma_f32 v[26:27], v[36:37], v[32:33], v[26:27]
	v_lshlrev_b32_e32 v36, 16, v186
	v_and_b32_e32 v37, 0xffff0000, v186
	v_div_scale_f32 v34, s[0:1], v29, v29, 1.0
	v_lshlrev_b32_e32 v32, 16, v178
	v_and_b32_e32 v33, 0xffff0000, v178
	v_rcp_f32_e32 v38, v34
	s_nop 0
	v_fma_f32 v47, -v34, v38, 1.0
	v_fmac_f32_e32 v38, v47, v38
	v_div_scale_f32 v47, vcc, 1.0, v29, 1.0
	v_mul_f32_e32 v50, v47, v38
	v_fma_f32 v51, -v34, v50, v47
	v_fmac_f32_e32 v50, v51, v38
	v_fma_f32 v34, -v34, v50, v47
	v_div_fmas_f32 v34, v34, v38, v50
	v_div_fixup_f32 v29, v34, v29, 1.0
	v_div_scale_f32 v34, s[0:1], v28, v28, 1.0
	v_rcp_f32_e32 v38, v34
	s_nop 0
	v_fma_f32 v47, -v34, v38, 1.0
	v_fmac_f32_e32 v38, v47, v38
	v_div_scale_f32 v47, vcc, 1.0, v28, 1.0
	v_mul_f32_e32 v50, v47, v38
	v_fma_f32 v51, -v34, v50, v47
	v_fmac_f32_e32 v50, v51, v38
	v_fma_f32 v34, -v34, v50, v47
	v_div_fmas_f32 v34, v34, v38, v50
	v_div_fixup_f32 v28, v34, v28, 1.0
	v_pk_fma_f32 v[28:29], v[28:29], v[36:37], v[32:33]
	v_div_scale_f32 v36, s[0:1], v31, v31, 1.0
	v_rcp_f32_e32 v37, v36
	v_lshlrev_b32_e32 v32, 16, v179
	v_and_b32_e32 v33, 0xffff0000, v179
	v_lshlrev_b32_e32 v34, 16, v187
	v_fma_f32 v38, -v36, v37, 1.0
	v_fmac_f32_e32 v37, v38, v37
	v_div_scale_f32 v38, vcc, 1.0, v31, 1.0
	v_mul_f32_e32 v39, v38, v37
	v_fma_f32 v47, -v36, v39, v38
	v_fmac_f32_e32 v39, v47, v37
	v_fma_f32 v36, -v36, v39, v38
	v_div_fmas_f32 v36, v36, v37, v39
	v_div_fixup_f32 v31, v36, v31, 1.0
	v_div_scale_f32 v36, s[0:1], v30, v30, 1.0
	v_rcp_f32_e32 v37, v36
	v_and_b32_e32 v35, 0xffff0000, v187
	v_fma_f32 v38, -v36, v37, 1.0
	v_fmac_f32_e32 v37, v38, v37
	v_div_scale_f32 v38, vcc, 1.0, v30, 1.0
	v_mul_f32_e32 v39, v38, v37
	v_fma_f32 v47, -v36, v39, v38
	v_fmac_f32_e32 v39, v47, v37
	v_fma_f32 v36, -v36, v39, v38
	v_div_fmas_f32 v36, v36, v37, v39
	v_div_fixup_f32 v30, v36, v30, 1.0
	v_pk_fma_f32 v[30:31], v[30:31], v[34:35], v[32:33]
	v_lshl_add_u64 v[36:37], v[40:41], 0, v[142:143]
	s_and_b64 vcc, exec, s[4:5]
	v_cvt_pk_bf16_f32 v32, v24, v25
	v_cvt_pk_bf16_f32 v33, v26, v27
	v_cvt_pk_bf16_f32 v34, v28, v29
	v_cvt_pk_bf16_f32 v35, v30, v31
	global_store_dwordx4 v[36:37], v[32:35], off nt
	s_cbranch_vccnz .LBB0_997
; __device__ __forceinline__ unsigned cvt_pk_bf16(float lo, float hi) { unsigned r; asm("v_cvt_pk_bf16_f32 %0, %1, %2" : "=v"(r) : "v"(lo), "v"(hi)); return r; }
; __device__ __forceinline__ float bf_lo(unsigned u) { return __uint_as_float(u << 16); }
; __device__ __forceinline__ float bf_hi(unsigned u) { return __uint_as_float(u & 0xffff0000u); }
; __device__ __forceinline__ float sigmoidf_(float x) { return 1.f / (1.f + __expf(-x)); }
;   __device__ __forceinline__ void operator()(const f32x4 (&acc)[2][2][4][2], const Unit& u, const EpiCtx& x_, int wr, int wc, int fr, int fq) const {
;     ...
;         for (int bj = 0; bj < 2; ++bj) {
;           const int cb = u.c0 + wc * 64 + bj * 32 + 8 * fq;
;           const uint4 pe = *(const uint4*)(pep + cb), xi = *(const uint4*)(xin + cb);
;           const f32x4 a = acc[ai][bj][m][0] * rs, b = acc[ai][bj][m][1] * rs;
;           f32x4 xa, xc;
;           xa[0] = bf_lo(xi.x) + bf_lo(pe.x) * sigmoidf_(a[0]); xa[1] = bf_hi(xi.x) + bf_hi(pe.x) * sigmoidf_(a[1]);
;           xa[2] = bf_lo(xi.y) + bf_lo(pe.y) * sigmoidf_(a[2]); xa[3] = bf_hi(xi.y) + bf_hi(pe.y) * sigmoidf_(a[3]);
;           xc[0] = bf_lo(xi.z) + bf_lo(pe.z) * sigmoidf_(b[0]); xc[1] = bf_hi(xi.z) + bf_hi(pe.z) * sigmoidf_(b[1]);
;           xc[2] = bf_lo(xi.w) + bf_lo(pe.w) * sigmoidf_(b[2]); xc[3] = bf_hi(xi.w) + bf_hi(pe.w) * sigmoidf_(b[3]);
;           sq += xa[0] * xa[0] + xa[1] * xa[1] + xa[2] * xa[2] + xa[3] * xa[3] + xc[0] * xc[0] + xc[1] * xc[1] + xc[2] * xc[2] + xc[3] * xc[3];
;           uint4 o; o.x = cvt_pk_bf16(xa[0], xa[1]); o.y = cvt_pk_bf16(xa[2], xa[3]); o.z = cvt_pk_bf16(xc[0], xc[1]); o.w = cvt_pk_bf16(xc[2], xc[3]);
;           *(uint4*)(xbp + cb) = o;
;           if (last) { float* op = (float*)u.C + (size_t)row * DM + cb; *(f32x4*)op = xa; *(f32x4*)(op + 4) = xc; }
	s_nop 0
	v_lshl_add_u64 v[32:33], v[140:141], 2, v[48:49]
	global_store_dwordx4 v[32:33], v[24:27], off nt
	global_store_dwordx4 v[32:33], v[28:31], off offset:16 nt
.LBB0_997:
	s_nop 1
	v_add_u32_e32 v198, 0x80, v92
	v_ashrrev_i32_e32 v199, 31, v198
	v_lshl_add_u64 v[200:201], v[198:199], 3, s[96:97]
	global_load_dwordx2 v[174:175], v[200:201], off
	v_lshlrev_b64 v[200:201], 12, v[198:199]
	v_lshl_add_u64 v[202:203], s[94:95], 0, v[200:201]
	v_lshl_add_u64 v[204:205], v[202:203], 0, v[142:143]
	global_load_dwordx4 v[176:179], v[204:205], off
	v_lshl_add_u64 v[202:203], s[92:93], 0, v[200:201]
	v_lshl_add_u64 v[204:205], v[202:203], 0, v[142:143]
	global_load_dwordx4 v[184:187], v[204:205], off
	s_nop 0
	v_lshl_add_u64 v[32:33], v[44:45], 0, v[144:145]
	s_nop 0
	v_lshl_add_u64 v[36:37], v[42:43], 0, v[144:145]
	s_nop 0
	v_mov_b32_e32 v47, v46
	v_mov_b32_e32 v42, v46
	v_mov_b32_e32 v43, v46
	v_pk_mul_f32 v[50:51], v[20:21], v[46:47]
	v_pk_mul_f32 v[44:45], v[22:23], v[42:43]
	v_pk_mul_f32 v[22:23], v[18:19], v[42:43]
	v_pk_mul_f32 v[20:21], v[16:17], v[46:47]
	v_mul_f32_e32 v17, 0xbfb8aa3b, v50
	v_exp_f32_e32 v42, v17
	v_mul_f32_e32 v20, 0xbfb8aa3b, v20
	v_mul_f32_e32 v21, 0xbfb8aa3b, v21
	v_exp_f32_e32 v20, v20
	v_exp_f32_e32 v21, v21
	v_mul_f32_e32 v22, 0xbfb8aa3b, v22
	v_mul_f32_e32 v23, 0xbfb8aa3b, v23
	v_exp_f32_e32 v22, v22
	v_pk_add_f32 v[20:21], v[20:21], 1.0 op_sel_hi:[1,0]
	v_exp_f32_e32 v23, v23
	s_waitcnt lgkmcnt(0)
	s_nop 0
	s_nop 0
	s_nop 0
	s_nop 0
	s_nop 0
	s_nop 0
	s_nop 0
	s_nop 0
	s_nop 0
	s_nop 0
	s_nop 0
	s_nop 0
	s_nop 0
	s_nop 0
	s_waitcnt vmcnt(5)
	v_lshlrev_b32_e32 v18, 16, v190
	v_and_b32_e32 v19, 0xffff0000, v190
	v_mul_f32_e32 v32, 0xbfb8aa3b, v51
	v_exp_f32_e32 v43, v32
	s_nop 0
	s_nop 0
	s_nop 0
	s_nop 0
	s_nop 0
	s_nop 0
	s_nop 0
	s_nop 0
	s_nop 0
	s_nop 0
	s_nop 0
	s_nop 0
	s_nop 0
	s_nop 0
	s_waitcnt vmcnt(4)
	v_lshlrev_b32_e32 v16, 16, v194
	v_and_b32_e32 v17, 0xffff0000, v194
	v_pk_add_f32 v[22:23], v[22:23], 1.0 op_sel_hi:[1,0]
	v_pk_add_f32 v[42:43], v[42:43], 1.0 op_sel_hi:[1,0]
	s_nop 0
	v_div_scale_f32 v32, s[0:1], v43, v43, 1.0
	v_rcp_f32_e32 v36, v32
	s_nop 0
	v_fma_f32 v46, -v32, v36, 1.0
	v_fmac_f32_e32 v36, v46, v36
	v_div_scale_f32 v46, vcc, 1.0, v43, 1.0
	v_mul_f32_e32 v47, v46, v36
	v_fma_f32 v50, -v32, v47, v46
	v_fmac_f32_e32 v47, v50, v36
	v_fma_f32 v32, -v32, v47, v46
	v_div_fmas_f32 v32, v32, v36, v47
	v_div_fixup_f32 v43, v32, v43, 1.0
	v_div_scale_f32 v32, s[0:1], v42, v42, 1.0
	v_rcp_f32_e32 v36, v32
	s_nop 0
	v_fma_f32 v46, -v32, v36, 1.0
	v_fmac_f32_e32 v36, v46, v36
	v_div_scale_f32 v46, vcc, 1.0, v42, 1.0
	v_mul_f32_e32 v47, v46, v36
	v_fma_f32 v50, -v32, v47, v46
	v_fmac_f32_e32 v47, v50, v36
	v_fma_f32 v32, -v32, v47, v46
	v_div_fmas_f32 v32, v32, v36, v47
	v_div_fixup_f32 v42, v32, v42, 1.0
	v_pk_fma_f32 v[16:17], v[42:43], v[18:19], v[16:17]
	v_mul_f32_e32 v19, 0xbfb8aa3b, v44
	v_lshlrev_b32_e32 v18, 16, v195
	v_exp_f32_e32 v36, v19
	v_and_b32_e32 v19, 0xffff0000, v195
	v_mul_f32_e32 v37, 0xbfb8aa3b, v45
	v_exp_f32_e32 v37, v37
	v_lshlrev_b32_e32 v32, 16, v191
	v_and_b32_e32 v33, 0xffff0000, v191
	v_pk_add_f32 v[36:37], v[36:37], 1.0 op_sel_hi:[1,0]
	s_nop 0
	v_div_scale_f32 v42, s[0:1], v37, v37, 1.0
	v_rcp_f32_e32 v43, v42
	s_nop 0
	v_fma_f32 v44, -v42, v43, 1.0
	v_fmac_f32_e32 v43, v44, v43
	v_div_scale_f32 v44, vcc, 1.0, v37, 1.0
	v_mul_f32_e32 v45, v44, v43
	v_fma_f32 v46, -v42, v45, v44
	v_fmac_f32_e32 v45, v46, v43
	v_fma_f32 v42, -v42, v45, v44
	v_div_fmas_f32 v42, v42, v43, v45
	v_div_fixup_f32 v37, v42, v37, 1.0
	v_div_scale_f32 v42, s[0:1], v36, v36, 1.0
	v_rcp_f32_e32 v43, v42
	s_nop 0
	v_fma_f32 v44, -v42, v43, 1.0
	v_fmac_f32_e32 v43, v44, v43
	v_div_scale_f32 v44, vcc, 1.0, v36, 1.0
	v_mul_f32_e32 v45, v44, v43
	v_fma_f32 v46, -v42, v45, v44
	v_fmac_f32_e32 v45, v46, v43
	v_fma_f32 v42, -v42, v45, v44
	v_div_fmas_f32 v42, v42, v43, v45
	v_div_fixup_f32 v36, v42, v36, 1.0
	v_pk_fma_f32 v[18:19], v[36:37], v[32:33], v[18:19]
	v_lshlrev_b32_e32 v36, 16, v192
	v_and_b32_e32 v37, 0xffff0000, v192
	v_div_scale_f32 v34, s[0:1], v21, v21, 1.0
	v_lshlrev_b32_e32 v32, 16, v196
	v_and_b32_e32 v33, 0xffff0000, v196
	v_rcp_f32_e32 v38, v34
	s_nop 0
	v_fma_f32 v42, -v34, v38, 1.0
	v_fmac_f32_e32 v38, v42, v38
	v_div_scale_f32 v42, vcc, 1.0, v21, 1.0
	v_mul_f32_e32 v43, v42, v38
	v_fma_f32 v44, -v34, v43, v42
	v_fmac_f32_e32 v43, v44, v38
	v_fma_f32 v34, -v34, v43, v42
	v_div_fmas_f32 v34, v34, v38, v43
	v_div_fixup_f32 v21, v34, v21, 1.0
	v_div_scale_f32 v34, s[0:1], v20, v20, 1.0
	v_rcp_f32_e32 v38, v34
	s_nop 0
	v_fma_f32 v42, -v34, v38, 1.0
	v_fmac_f32_e32 v38, v42, v38
	v_div_scale_f32 v42, vcc, 1.0, v20, 1.0
	v_mul_f32_e32 v43, v42, v38
	v_fma_f32 v44, -v34, v43, v42
	v_fmac_f32_e32 v43, v44, v38
	v_fma_f32 v34, -v34, v43, v42
	v_div_fmas_f32 v34, v34, v38, v43
	v_div_fixup_f32 v20, v34, v20, 1.0
	v_pk_fma_f32 v[20:21], v[20:21], v[36:37], v[32:33]
	v_div_scale_f32 v36, s[0:1], v23, v23, 1.0
	v_rcp_f32_e32 v37, v36
	v_lshlrev_b32_e32 v32, 16, v197
	v_and_b32_e32 v33, 0xffff0000, v197
	v_lshlrev_b32_e32 v34, 16, v193
	v_fma_f32 v38, -v36, v37, 1.0
	v_fmac_f32_e32 v37, v38, v37
	v_div_scale_f32 v38, vcc, 1.0, v23, 1.0
	v_mul_f32_e32 v39, v38, v37
	v_fma_f32 v42, -v36, v39, v38
	v_fmac_f32_e32 v39, v42, v37
	v_fma_f32 v36, -v36, v39, v38
	v_div_fmas_f32 v36, v36, v37, v39
	v_div_fixup_f32 v23, v36, v23, 1.0
	v_div_scale_f32 v36, s[0:1], v22, v22, 1.0
	v_rcp_f32_e32 v37, v36
	v_and_b32_e32 v35, 0xffff0000, v193
	v_fma_f32 v38, -v36, v37, 1.0
	v_fmac_f32_e32 v37, v38, v37
	v_div_scale_f32 v38, vcc, 1.0, v22, 1.0
	v_mul_f32_e32 v39, v38, v37
	v_fma_f32 v42, -v36, v39, v38
	v_fmac_f32_e32 v39, v42, v37
	v_fma_f32 v36, -v36, v39, v38
	v_div_fmas_f32 v36, v36, v37, v39
	v_div_fixup_f32 v22, v36, v22, 1.0
	v_pk_fma_f32 v[22:23], v[22:23], v[34:35], v[32:33]
	v_lshl_add_u64 v[36:37], v[40:41], 0, v[144:145]
	s_and_b64 vcc, exec, s[4:5]
	v_cvt_pk_bf16_f32 v32, v16, v17
	v_cvt_pk_bf16_f32 v33, v18, v19
	v_cvt_pk_bf16_f32 v34, v20, v21
	v_cvt_pk_bf16_f32 v35, v22, v23
	global_store_dwordx4 v[36:37], v[32:35], off nt
	s_cbranch_vccnz .LBB0_999
	s_nop 0
	v_lshl_add_u64 v[32:33], v[138:139], 2, v[48:49]
	global_store_dwordx4 v[32:33], v[16:19], off nt
	global_store_dwordx4 v[32:33], v[20:23], off offset:16 nt

; __device__ __forceinline__ unsigned cvt_pk_bf16(float lo, float hi) { unsigned r; asm("v_cvt_pk_bf16_f32 %0, %1, %2" : "=v"(r) : "v"(lo), "v"(hi)); return r; }
; __device__ __forceinline__ float bf_lo(unsigned u) { return __uint_as_float(u << 16); }
; __device__ __forceinline__ float bf_hi(unsigned u) { return __uint_as_float(u & 0xffff0000u); }
; __device__ __forceinline__ float sigmoidf_(float x) { return 1.f / (1.f + __expf(-x)); }
; __device__ __forceinline__ float rinv_of(unsigned long long ss) { return rsqrtf((float)ss * (1.f / 16777216.f) * (1.f / DM) + 1e-6f); }
;   __device__ __forceinline__ void operator()(const f32x4 (&acc)[2][2][4][2], const Unit& u, const EpiCtx& x_, int wr, int wc, int fr, int fq) const {
;     ...
;         const int row = (u.r0 + (ai ? x_.rdelta : 0)) + wr * 64 + m * 16 + fr;
;         const bf16_t* pep = (const bf16_t*)x_.aux + (size_t)row * DM;
;         const bf16_t* xin = (const bf16_t*)x_.aux2 + (size_t)row * DM;
;         bf16_t* xbp = x_.xb + (size_t)row * DM;
;         const float rs = rinv_of(x_.ss[row]);
;         float sq = 0.f;
; #pragma unroll
;         for (int bj = 0; bj < 2; ++bj) {
;           const int cb = u.c0 + wc * 64 + bj * 32 + 8 * fq;
;           const uint4 pe = *(const uint4*)(pep + cb), xi = *(const uint4*)(xin + cb);
;           const f32x4 a = acc[ai][bj][m][0] * rs, b = acc[ai][bj][m][1] * rs;
;           f32x4 xa, xc;
;           xa[0] = bf_lo(xi.x) + bf_lo(pe.x) * sigmoidf_(a[0]); xa[1] = bf_hi(xi.x) + bf_hi(pe.x) * sigmoidf_(a[1]);
;           xa[2] = bf_lo(xi.y) + bf_lo(pe.y) * sigmoidf_(a[2]); xa[3] = bf_hi(xi.y) + bf_hi(pe.y) * sigmoidf_(a[3]);
;           xc[0] = bf_lo(xi.z) + bf_lo(pe.z) * sigmoidf_(b[0]); xc[1] = bf_hi(xi.z) + bf_hi(pe.z) * sigmoidf_(b[1]);
;           xc[2] = bf_lo(xi.w) + bf_lo(pe.w) * sigmoidf_(b[2]); xc[3] = bf_hi(xi.w) + bf_hi(pe.w) * sigmoidf_(b[3]);
;           sq += xa[0] * xa[0] + xa[1] * xa[1] + xa[2] * xa[2] + xa[3] * xa[3] + xc[0] * xc[0] + xc[1] * xc[1] + xc[2] * xc[2] + xc[3] * xc[3];
;           uint4 o; o.x = cvt_pk_bf16(xa[0], xa[1]); o.y = cvt_pk_bf16(xa[2], xa[3]); o.z = cvt_pk_bf16(xc[0], xc[1]); o.w = cvt_pk_bf16(xc[2], xc[3]);
;           *(uint4*)(xbp + cb) = o;
.LBB0_1001:
	s_or_b64 exec, exec, s[18:19]
	s_nop 1
	v_add_u32_e32 v198, 0x80, v92
	v_ashrrev_i32_e32 v199, 31, v198
	v_lshlrev_b64 v[200:201], 12, v[198:199]
	v_lshl_add_u64 v[202:203], s[92:93], 0, v[200:201]
	v_lshl_add_u64 v[204:205], v[202:203], 0, v[144:145]
	global_load_dwordx4 v[190:193], v[204:205], off
	v_lshl_add_u64 v[202:203], s[94:95], 0, v[200:201]
	v_lshl_add_u64 v[204:205], v[202:203], 0, v[144:145]
	global_load_dwordx4 v[194:197], v[204:205], off
	v_add_u32_e32 v16, 0x80, v92
	s_waitcnt lgkmcnt(0)
	v_ashrrev_i32_e32 v17, 31, v16
	v_lshlrev_b64 v[32:33], 11, v[16:17]
	v_lshlrev_b64 v[18:19], 12, v[16:17]
	v_lshl_add_u64 v[16:17], v[16:17], 3, s[96:97]
	s_nop 0
	v_lshl_add_u64 v[28:29], s[92:93], 0, v[18:19]
	v_lshl_add_u64 v[26:27], s[94:95], 0, v[18:19]
	v_lshl_add_u64 v[24:25], s[90:91], 0, v[18:19]
	v_lshl_add_u64 v[20:21], v[26:27], 0, v[142:143]
	s_nop 0
	v_lshl_add_u64 v[32:33], v[32:33], 2, s[36:37]
	s_waitcnt lgkmcnt(0)
	s_nop 0
	s_nop 0
	s_nop 0
	s_nop 0
	s_nop 0
	s_nop 0
	s_nop 0
	s_nop 0
	s_nop 0
	s_nop 0
	s_nop 0
	s_nop 0
	s_nop 0
	s_nop 0
	s_waitcnt vmcnt(5)
	v_ffbh_u32_e32 v18, v175
	v_min_u32_e32 v18, 32, v18
	v_lshlrev_b64 v[16:17], v18, v[174:175]
	v_min_u32_e32 v16, 1, v16
	v_or_b32_e32 v16, v17, v16
	v_cvt_f32_u32_e32 v16, v16
	v_sub_u32_e32 v17, 32, v18
	v_ldexp_f32 v16, v16, v17
	v_mul_f32_e32 v16, 0x33800000, v16
	v_fmamk_f32 v16, v16, 0x3a000000, v234
	v_cmp_gt_f32_e32 vcc, s50, v16
	v_mul_f32_e32 v17, 0x4b800000, v16
	s_nop 0
	v_cndmask_b32_e32 v16, v16, v17, vcc
	v_rsq_f32_e32 v16, v16
	s_nop 0
	v_mul_f32_e32 v17, 0x45800000, v16
	v_cndmask_b32_e32 v30, v16, v17, vcc
	v_lshl_add_u64 v[16:17], v[28:29], 0, v[142:143]
	s_nop 0
	v_pk_mul_f32 v[36:37], v[12:13], v[30:31] op_sel_hi:[1,0]
	v_pk_mul_f32 v[34:35], v[14:15], v[30:31] op_sel_hi:[1,0]
	v_pk_mul_f32 v[14:15], v[10:11], v[30:31] op_sel_hi:[1,0]
	v_pk_mul_f32 v[12:13], v[8:9], v[30:31] op_sel_hi:[1,0]
	v_mul_f32_e32 v9, 0xbfb8aa3b, v36
	v_exp_f32_e32 v36, v9
	s_nop 0
	s_nop 0
	s_nop 0
	s_nop 0
	s_nop 0
	s_nop 0
	s_nop 0
	s_nop 0
	s_nop 0
	s_nop 0
	s_nop 0
	s_nop 0
	s_nop 0
	s_nop 0
	s_waitcnt vmcnt(4)
	v_lshlrev_b32_e32 v8, 16, v176
	v_and_b32_e32 v9, 0xffff0000, v176
	v_mul_f32_e32 v12, 0xbfb8aa3b, v12
	v_mul_f32_e32 v13, 0xbfb8aa3b, v13
	v_exp_f32_e32 v12, v12
	v_exp_f32_e32 v13, v13
	v_mul_f32_e32 v14, 0xbfb8aa3b, v14
	v_mul_f32_e32 v15, 0xbfb8aa3b, v15
	v_exp_f32_e32 v14, v14
	v_pk_add_f32 v[12:13], v[12:13], 1.0 op_sel_hi:[1,0]
	v_exp_f32_e32 v15, v15
	s_waitcnt lgkmcnt(0)
	s_nop 0
	s_nop 0
	s_nop 0
	s_nop 0
	s_nop 0
	s_nop 0
	s_nop 0
	s_nop 0
	s_nop 0
	s_nop 0
	s_nop 0
	s_nop 0
	s_nop 0
	s_nop 0
	s_waitcnt vmcnt(3)
	v_lshlrev_b32_e32 v10, 16, v184
	v_and_b32_e32 v11, 0xffff0000, v184
	v_mul_f32_e32 v16, 0xbfb8aa3b, v37
	v_exp_f32_e32 v37, v16
	v_pk_add_f32 v[14:15], v[14:15], 1.0 op_sel_hi:[1,0]
	v_pk_add_f32 v[36:37], v[36:37], 1.0 op_sel_hi:[1,0]
	s_nop 0
	v_div_scale_f32 v16, s[0:1], v37, v37, 1.0
	v_rcp_f32_e32 v20, v16
	s_nop 0
	v_fma_f32 v31, -v16, v20, 1.0
	v_fmac_f32_e32 v20, v31, v20
	v_div_scale_f32 v31, vcc, 1.0, v37, 1.0
	v_mul_f32_e32 v38, v31, v20
	v_fma_f32 v39, -v16, v38, v31
	v_fmac_f32_e32 v38, v39, v20
	v_fma_f32 v16, -v16, v38, v31
	v_div_fmas_f32 v16, v16, v20, v38
	v_div_fixup_f32 v37, v16, v37, 1.0
	v_div_scale_f32 v16, s[0:1], v36, v36, 1.0
	v_rcp_f32_e32 v20, v16
	s_nop 0
	v_fma_f32 v31, -v16, v20, 1.0
	v_fmac_f32_e32 v20, v31, v20
	v_div_scale_f32 v31, vcc, 1.0, v36, 1.0
	v_mul_f32_e32 v38, v31, v20
	v_fma_f32 v39, -v16, v38, v31
	v_fmac_f32_e32 v38, v39, v20
	v_fma_f32 v16, -v16, v38, v31
	v_div_fmas_f32 v16, v16, v20, v38
	v_div_fixup_f32 v36, v16, v36, 1.0
	v_pk_fma_f32 v[8:9], v[36:37], v[10:11], v[8:9]
	v_mul_f32_e32 v11, 0xbfb8aa3b, v34
	v_lshlrev_b32_e32 v10, 16, v177
	v_exp_f32_e32 v20, v11
	v_and_b32_e32 v11, 0xffff0000, v177
	v_mul_f32_e32 v21, 0xbfb8aa3b, v35
	v_exp_f32_e32 v21, v21
	v_lshlrev_b32_e32 v16, 16, v185
	v_and_b32_e32 v17, 0xffff0000, v185
	v_pk_add_f32 v[20:21], v[20:21], 1.0 op_sel_hi:[1,0]
	s_nop 0
	v_div_scale_f32 v31, s[0:1], v21, v21, 1.0
	v_rcp_f32_e32 v34, v31
	s_nop 0
	v_fma_f32 v35, -v31, v34, 1.0
	v_fmac_f32_e32 v34, v35, v34
	v_div_scale_f32 v35, vcc, 1.0, v21, 1.0
	v_mul_f32_e32 v36, v35, v34
	v_fma_f32 v37, -v31, v36, v35
	v_fmac_f32_e32 v36, v37, v34
	v_fma_f32 v31, -v31, v36, v35
	v_div_fmas_f32 v31, v31, v34, v36
	v_div_fixup_f32 v21, v31, v21, 1.0
	v_div_scale_f32 v31, s[0:1], v20, v20, 1.0
	v_rcp_f32_e32 v34, v31
	s_nop 0
	v_fma_f32 v35, -v31, v34, 1.0
	v_fmac_f32_e32 v34, v35, v34
	v_div_scale_f32 v35, vcc, 1.0, v20, 1.0
	v_mul_f32_e32 v36, v35, v34
	v_fma_f32 v37, -v31, v36, v35
	v_fmac_f32_e32 v36, v37, v34
	v_fma_f32 v31, -v31, v36, v35
	v_div_fmas_f32 v31, v31, v34, v36
	v_div_fixup_f32 v20, v31, v20, 1.0
	v_pk_fma_f32 v[10:11], v[20:21], v[16:17], v[10:11]
	v_lshlrev_b32_e32 v20, 16, v186
	v_and_b32_e32 v21, 0xffff0000, v186
	v_div_scale_f32 v18, s[0:1], v13, v13, 1.0
	v_lshlrev_b32_e32 v16, 16, v178
	v_and_b32_e32 v17, 0xffff0000, v178
	v_rcp_f32_e32 v22, v18
	s_nop 0
	v_fma_f32 v31, -v18, v22, 1.0
	v_fmac_f32_e32 v22, v31, v22
	v_div_scale_f32 v31, vcc, 1.0, v13, 1.0
	v_mul_f32_e32 v34, v31, v22
	v_fma_f32 v35, -v18, v34, v31
	v_fmac_f32_e32 v34, v35, v22
	v_fma_f32 v18, -v18, v34, v31
	v_div_fmas_f32 v18, v18, v22, v34
	v_div_fixup_f32 v13, v18, v13, 1.0
	v_div_scale_f32 v18, s[0:1], v12, v12, 1.0
	v_rcp_f32_e32 v22, v18
	s_nop 0
	v_fma_f32 v31, -v18, v22, 1.0
	v_fmac_f32_e32 v22, v31, v22
	v_div_scale_f32 v31, vcc, 1.0, v12, 1.0
	v_mul_f32_e32 v34, v31, v22
	v_fma_f32 v35, -v18, v34, v31
	v_fmac_f32_e32 v34, v35, v22
	v_fma_f32 v18, -v18, v34, v31
	v_div_fmas_f32 v18, v18, v22, v34
	v_div_fixup_f32 v12, v18, v12, 1.0
	v_pk_fma_f32 v[12:13], v[12:13], v[20:21], v[16:17]
	v_div_scale_f32 v20, s[0:1], v15, v15, 1.0
	v_rcp_f32_e32 v21, v20
	v_lshlrev_b32_e32 v16, 16, v179
	v_and_b32_e32 v17, 0xffff0000, v179
	v_lshlrev_b32_e32 v18, 16, v187
	v_fma_f32 v22, -v20, v21, 1.0
	v_fmac_f32_e32 v21, v22, v21
	v_div_scale_f32 v22, vcc, 1.0, v15, 1.0
	v_mul_f32_e32 v23, v22, v21
	v_fma_f32 v31, -v20, v23, v22
	v_fmac_f32_e32 v23, v31, v21
	v_fma_f32 v20, -v20, v23, v22
	v_div_fmas_f32 v20, v20, v21, v23
	v_div_fixup_f32 v15, v20, v15, 1.0
	v_div_scale_f32 v20, s[0:1], v14, v14, 1.0
	v_rcp_f32_e32 v21, v20
	v_and_b32_e32 v19, 0xffff0000, v187
	v_fma_f32 v22, -v20, v21, 1.0
	v_fmac_f32_e32 v21, v22, v21
	v_div_scale_f32 v22, vcc, 1.0, v14, 1.0
	v_mul_f32_e32 v23, v22, v21
	v_fma_f32 v31, -v20, v23, v22
	v_fmac_f32_e32 v23, v31, v21
	v_fma_f32 v20, -v20, v23, v22
	v_div_fmas_f32 v20, v20, v21, v23
	v_div_fixup_f32 v14, v20, v14, 1.0
	v_pk_fma_f32 v[14:15], v[14:15], v[18:19], v[16:17]
	v_lshl_add_u64 v[20:21], v[24:25], 0, v[142:143]
	s_and_b64 vcc, exec, s[4:5]
	v_cvt_pk_bf16_f32 v16, v8, v9
	v_cvt_pk_bf16_f32 v17, v10, v11
	v_cvt_pk_bf16_f32 v18, v12, v13
	v_cvt_pk_bf16_f32 v19, v14, v15
	global_store_dwordx4 v[20:21], v[16:19], off nt
	s_cbranch_vccnz .LBB0_1003
; __device__ __forceinline__ unsigned cvt_pk_bf16(float lo, float hi) { unsigned r; asm("v_cvt_pk_bf16_f32 %0, %1, %2" : "=v"(r) : "v"(lo), "v"(hi)); return r; }
; __device__ __forceinline__ float bf_lo(unsigned u) { return __uint_as_float(u << 16); }
; __device__ __forceinline__ float bf_hi(unsigned u) { return __uint_as_float(u & 0xffff0000u); }
; __device__ __forceinline__ float sigmoidf_(float x) { return 1.f / (1.f + __expf(-x)); }
; __device__ __forceinline__ unsigned long long ss_fix(float s) { return (unsigned long long)(s * 16777216.f); }
;   __device__ __forceinline__ void operator()(const f32x4 (&acc)[2][2][4][2], const Unit& u, const EpiCtx& x_, int wr, int wc, int fr, int fq) const {
;     ...
;           const int cb = u.c0 + wc * 64 + bj * 32 + 8 * fq;
;           const uint4 pe = *(const uint4*)(pep + cb), xi = *(const uint4*)(xin + cb);
;           const f32x4 a = acc[ai][bj][m][0] * rs, b = acc[ai][bj][m][1] * rs;
;           f32x4 xa, xc;
;           xa[0] = bf_lo(xi.x) + bf_lo(pe.x) * sigmoidf_(a[0]); xa[1] = bf_hi(xi.x) + bf_hi(pe.x) * sigmoidf_(a[1]);
;           xa[2] = bf_lo(xi.y) + bf_lo(pe.y) * sigmoidf_(a[2]); xa[3] = bf_hi(xi.y) + bf_hi(pe.y) * sigmoidf_(a[3]);
;           xc[0] = bf_lo(xi.z) + bf_lo(pe.z) * sigmoidf_(b[0]); xc[1] = bf_hi(xi.z) + bf_hi(pe.z) * sigmoidf_(b[1]);
;           xc[2] = bf_lo(xi.w) + bf_lo(pe.w) * sigmoidf_(b[2]); xc[3] = bf_hi(xi.w) + bf_hi(pe.w) * sigmoidf_(b[3]);
;           sq += xa[0] * xa[0] + xa[1] * xa[1] + xa[2] * xa[2] + xa[3] * xa[3] + xc[0] * xc[0] + xc[1] * xc[1] + xc[2] * xc[2] + xc[3] * xc[3];
;           uint4 o; o.x = cvt_pk_bf16(xa[0], xa[1]); o.y = cvt_pk_bf16(xa[2], xa[3]); o.z = cvt_pk_bf16(xc[0], xc[1]); o.w = cvt_pk_bf16(xc[2], xc[3]);
;           *(uint4*)(xbp + cb) = o;
;           if (last) { float* op = (float*)u.C + (size_t)row * DM + cb; *(f32x4*)op = xa; *(f32x4*)(op + 4) = xc; }
;         }
;         sq += __shfl_xor(sq, 16); sq += __shfl_xor(sq, 32);
;         if (fq == 0) atomicAdd(x_.sso + row, ss_fix(sq));
	s_nop 0
	v_lshl_add_u64 v[16:17], v[140:141], 2, v[32:33]
	global_store_dwordx4 v[16:17], v[8:11], off nt
	global_store_dwordx4 v[16:17], v[12:15], off offset:16 nt
.LBB0_1003:
	s_nop 0
	v_lshl_add_u64 v[16:17], v[28:29], 0, v[144:145]
	s_nop 0
	v_lshl_add_u64 v[20:21], v[26:27], 0, v[144:145]
	s_nop 0
	v_mov_b32_e32 v31, v30
	v_mov_b32_e32 v26, v30
	v_mov_b32_e32 v27, v30
	v_pk_mul_f32 v[34:35], v[4:5], v[30:31]
	v_pk_mul_f32 v[28:29], v[6:7], v[26:27]
	v_pk_mul_f32 v[6:7], v[2:3], v[26:27]
	v_pk_mul_f32 v[4:5], v[0:1], v[30:31]
	v_mul_f32_e32 v1, 0xbfb8aa3b, v34
	v_exp_f32_e32 v26, v1
	v_mul_f32_e32 v4, 0xbfb8aa3b, v4
	v_mul_f32_e32 v5, 0xbfb8aa3b, v5
	v_exp_f32_e32 v4, v4
	v_exp_f32_e32 v5, v5
	v_mul_f32_e32 v6, 0xbfb8aa3b, v6
	v_mul_f32_e32 v7, 0xbfb8aa3b, v7
	v_exp_f32_e32 v6, v6
	v_pk_add_f32 v[4:5], v[4:5], 1.0 op_sel_hi:[1,0]
	v_exp_f32_e32 v7, v7
	s_waitcnt lgkmcnt(0)
	s_nop 0
	s_nop 0
	s_nop 0
	s_nop 0
	s_nop 0
	s_nop 0
	s_nop 0
	s_nop 0
	s_nop 0
	s_nop 0
	s_nop 0
	s_nop 0
	s_nop 0
	s_nop 0
	s_waitcnt vmcnt(2)
	v_lshlrev_b32_e32 v2, 16, v190
	v_and_b32_e32 v3, 0xffff0000, v190
	v_mul_f32_e32 v16, 0xbfb8aa3b, v35
	v_exp_f32_e32 v27, v16
	s_nop 0
	s_nop 0
	s_nop 0
	s_nop 0
	s_nop 0
	s_nop 0
	s_nop 0
	s_nop 0
	s_nop 0
	s_nop 0
	s_nop 0
	s_nop 0
	s_nop 0
	s_nop 0
	s_waitcnt vmcnt(1)
	v_lshlrev_b32_e32 v0, 16, v194
	v_and_b32_e32 v1, 0xffff0000, v194
	v_pk_add_f32 v[6:7], v[6:7], 1.0 op_sel_hi:[1,0]
	v_pk_add_f32 v[26:27], v[26:27], 1.0 op_sel_hi:[1,0]
	s_nop 0
	v_div_scale_f32 v16, s[0:1], v27, v27, 1.0
	v_rcp_f32_e32 v20, v16
	s_nop 0
	v_fma_f32 v30, -v16, v20, 1.0
	v_fmac_f32_e32 v20, v30, v20
	v_div_scale_f32 v30, vcc, 1.0, v27, 1.0
	v_mul_f32_e32 v31, v30, v20
	v_fma_f32 v34, -v16, v31, v30
	v_fmac_f32_e32 v31, v34, v20
	v_fma_f32 v16, -v16, v31, v30
	v_div_fmas_f32 v16, v16, v20, v31
	v_div_fixup_f32 v27, v16, v27, 1.0
	v_div_scale_f32 v16, s[0:1], v26, v26, 1.0
	v_rcp_f32_e32 v20, v16
	s_nop 0
	v_fma_f32 v30, -v16, v20, 1.0
	v_fmac_f32_e32 v20, v30, v20
	v_div_scale_f32 v30, vcc, 1.0, v26, 1.0
	v_mul_f32_e32 v31, v30, v20
	v_fma_f32 v34, -v16, v31, v30
	v_fmac_f32_e32 v31, v34, v20
	v_fma_f32 v16, -v16, v31, v30
	v_div_fmas_f32 v16, v16, v20, v31
	v_div_fixup_f32 v26, v16, v26, 1.0
	v_pk_fma_f32 v[0:1], v[26:27], v[2:3], v[0:1]
	v_mul_f32_e32 v3, 0xbfb8aa3b, v28
	v_lshlrev_b32_e32 v2, 16, v195
	v_exp_f32_e32 v20, v3
	v_and_b32_e32 v3, 0xffff0000, v195
	v_mul_f32_e32 v21, 0xbfb8aa3b, v29
	v_exp_f32_e32 v21, v21
	v_lshlrev_b32_e32 v16, 16, v191
	v_and_b32_e32 v17, 0xffff0000, v191
	v_pk_add_f32 v[20:21], v[20:21], 1.0 op_sel_hi:[1,0]
	s_nop 0
	v_div_scale_f32 v26, s[0:1], v21, v21, 1.0
	v_rcp_f32_e32 v27, v26
	s_nop 0
	v_fma_f32 v28, -v26, v27, 1.0
	v_fmac_f32_e32 v27, v28, v27
	v_div_scale_f32 v28, vcc, 1.0, v21, 1.0
	v_mul_f32_e32 v29, v28, v27
	v_fma_f32 v30, -v26, v29, v28
	v_fmac_f32_e32 v29, v30, v27
	v_fma_f32 v26, -v26, v29, v28
	v_div_fmas_f32 v26, v26, v27, v29
	v_div_fixup_f32 v21, v26, v21, 1.0
	v_div_scale_f32 v26, s[0:1], v20, v20, 1.0
	v_rcp_f32_e32 v27, v26
	s_nop 0
	v_fma_f32 v28, -v26, v27, 1.0
	v_fmac_f32_e32 v27, v28, v27
	v_div_scale_f32 v28, vcc, 1.0, v20, 1.0
	v_mul_f32_e32 v29, v28, v27
	v_fma_f32 v30, -v26, v29, v28
	v_fmac_f32_e32 v29, v30, v27
	v_fma_f32 v26, -v26, v29, v28
	v_div_fmas_f32 v26, v26, v27, v29
	v_div_fixup_f32 v20, v26, v20, 1.0
	v_pk_fma_f32 v[2:3], v[20:21], v[16:17], v[2:3]
	v_lshlrev_b32_e32 v20, 16, v192
	v_and_b32_e32 v21, 0xffff0000, v192
	v_div_scale_f32 v18, s[0:1], v5, v5, 1.0
	v_lshlrev_b32_e32 v16, 16, v196
	v_and_b32_e32 v17, 0xffff0000, v196
	v_rcp_f32_e32 v22, v18
	s_nop 0
	v_fma_f32 v26, -v18, v22, 1.0
	v_fmac_f32_e32 v22, v26, v22
	v_div_scale_f32 v26, vcc, 1.0, v5, 1.0
	v_mul_f32_e32 v27, v26, v22
	v_fma_f32 v28, -v18, v27, v26
	v_fmac_f32_e32 v27, v28, v22
	v_fma_f32 v18, -v18, v27, v26
	v_div_fmas_f32 v18, v18, v22, v27
	v_div_fixup_f32 v5, v18, v5, 1.0
	v_div_scale_f32 v18, s[0:1], v4, v4, 1.0
	v_rcp_f32_e32 v22, v18
	s_nop 0
	v_fma_f32 v26, -v18, v22, 1.0
	v_fmac_f32_e32 v22, v26, v22
	v_div_scale_f32 v26, vcc, 1.0, v4, 1.0
	v_mul_f32_e32 v27, v26, v22
	v_fma_f32 v28, -v18, v27, v26
	v_fmac_f32_e32 v27, v28, v22
	v_fma_f32 v18, -v18, v27, v26
	v_div_fmas_f32 v18, v18, v22, v27
	v_div_fixup_f32 v4, v18, v4, 1.0
	v_pk_fma_f32 v[4:5], v[4:5], v[20:21], v[16:17]
	v_div_scale_f32 v20, s[0:1], v7, v7, 1.0
	v_rcp_f32_e32 v21, v20
	v_lshlrev_b32_e32 v16, 16, v197
	v_and_b32_e32 v17, 0xffff0000, v197
	v_lshlrev_b32_e32 v18, 16, v193
	v_fma_f32 v22, -v20, v21, 1.0
	v_fmac_f32_e32 v21, v22, v21
	v_div_scale_f32 v22, vcc, 1.0, v7, 1.0
	v_mul_f32_e32 v23, v22, v21
	v_fma_f32 v26, -v20, v23, v22
	v_fmac_f32_e32 v23, v26, v21
	v_fma_f32 v20, -v20, v23, v22
	v_div_fmas_f32 v20, v20, v21, v23
	v_div_fixup_f32 v7, v20, v7, 1.0
	v_div_scale_f32 v20, s[0:1], v6, v6, 1.0
	v_rcp_f32_e32 v21, v20
	v_and_b32_e32 v19, 0xffff0000, v193
	v_fma_f32 v22, -v20, v21, 1.0
	v_fmac_f32_e32 v21, v22, v21
	v_div_scale_f32 v22, vcc, 1.0, v6, 1.0
	v_mul_f32_e32 v23, v22, v21
	v_fma_f32 v26, -v20, v23, v22
	v_fmac_f32_e32 v23, v26, v21
	v_fma_f32 v20, -v20, v23, v22
	v_div_fmas_f32 v20, v20, v21, v23
	v_div_fixup_f32 v6, v20, v6, 1.0
	v_pk_fma_f32 v[6:7], v[6:7], v[18:19], v[16:17]
	v_lshl_add_u64 v[20:21], v[24:25], 0, v[144:145]
	s_and_b64 vcc, exec, s[4:5]
	v_cvt_pk_bf16_f32 v16, v0, v1
	v_cvt_pk_bf16_f32 v17, v2, v3
	v_cvt_pk_bf16_f32 v18, v4, v5
	v_cvt_pk_bf16_f32 v19, v6, v7
	global_store_dwordx4 v[20:21], v[16:19], off nt
	s_cbranch_vccnz .LBB0_1005
	s_nop 0
	v_lshl_add_u64 v[16:17], v[138:139], 2, v[32:33]
	global_store_dwordx4 v[16:17], v[0:3], off nt
	global_store_dwordx4 v[16:17], v[4:7], off offset:16 nt
